# outproj: tile pairs (mt, mt+64) share the weight K-tiles: 4 LDS units (A0, A1 single-buffered, B double-buffered), 25% less L2->LDS traffic per MFMA
# speedup vs baseline: 1.0031x; 1.0031x over previous
.LBB0_313:
	s_or_b64 exec, exec, s[0:1]
	s_cmpk_lt_i32 s2, 0x400
	s_cselect_b64 s[16:17], -1, 0
	s_cmpk_gt_i32 s2, 0x3ff
	s_waitcnt lgkmcnt(0)
	s_barrier
	s_cbranch_scc1 .LBB0_318
	v_lshrrev_b32_e32 v141, 4, v129
	v_and_b32_e32 v64, 15, v141
	v_bfe_u32 v65, v141, 4, 2
	v_bfe_u32 v66, v141, 1, 3
	v_xor_b32_e32 v66, v65, v66
	v_lshlrev_b32_e32 v66, 4, v66
	v_lshl_or_b32 v67, v64, 7, v66
	v_bfe_u32 v68, v141, 7, 1
	v_bfe_u32 v69, v141, 6, 1
	v_lshl_add_u32 v151, v68, 13, v67
	v_xor_b32_e32 v220, 64, v151
	v_lshl_add_u32 v222, v69, 13, v67
	v_xor_b32_e32 v224, 64, v222
	v_bfe_u32 v70, v141, 4, 3
	v_and_b32_e32 v71, 7, v141
	v_xor_b32_e32 v70, v70, v71
	v_lshlrev_b32_e32 v70, 4, v70
	v_lshrrev_b32_e32 v72, 3, v141
	v_lshl_or_b32 v226, v72, 12, v70
	v_add_u32_e32 v228, 131072, v226
	v_add_u32_e32 v244, 262144, v226
	v_add_u32_e32 v245, 393216, v226
	v_bfe_u32 v73, v141, 3, 3
	v_lshlrev_b32_e32 v74, 8, v69
	v_lshl_add_u32 v148, v71, 5, v74
	v_lshl_add_u32 v74, v68, 6, v73
	v_lshl_add_u32 v150, v74, 12, v148
	v_lshrrev_b32_e32 v74, 6, v141
	v_lshlrev_b32_e32 v74, 13, v74
	v_lshl_add_u32 v75, v65, 10, v74
	v_add_u32_e32 v76, 0, v65
	v_and_b32_e32 v76, 3, v76
	v_lshl_add_u32 v76, v76, 4, v64
	v_lshl_add_u32 v248, v76, 2, v75
	v_add_u32_e32 v76, 1, v65
	v_and_b32_e32 v76, 3, v76
	v_lshl_add_u32 v76, v76, 4, v64
	v_lshl_add_u32 v249, v76, 2, v75
	v_add_u32_e32 v76, 2, v65
	v_and_b32_e32 v76, 3, v76
	v_lshl_add_u32 v76, v76, 4, v64
	v_lshl_add_u32 v250, v76, 2, v75
	v_add_u32_e32 v76, 3, v65
	v_and_b32_e32 v76, 3, v76
	v_lshl_add_u32 v76, v76, 4, v64
	v_lshl_add_u32 v251, v76, 2, v75
	v_lshl_add_u32 v75, v73, 8, v74
	v_lshrrev_b32_e32 v77, 2, v73
	v_lshlrev_b32_e32 v78, 3, v71
	v_add_u32_e32 v76, 0, v77
	v_and_b32_e32 v76, 3, v76
	v_lshl_add_u32 v76, v76, 4, v78
	v_and_b32_e32 v76, 63, v76
	v_lshl_add_u32 v252, v76, 2, v75
	v_add_u32_e32 v76, 2, v77
	v_and_b32_e32 v76, 3, v76
	v_lshl_add_u32 v76, v76, 4, v78
	v_and_b32_e32 v76, 63, v76
	v_lshl_add_u32 v253, v76, 2, v75
	v_add_u32_e32 v253, 2048, v253
	v_add_u32_e32 v76, 4, v77
	v_and_b32_e32 v76, 3, v76
	v_lshl_add_u32 v76, v76, 4, v78
	v_and_b32_e32 v76, 63, v76
	v_lshl_add_u32 v254, v76, 2, v75
	v_add_u32_e32 v254, 4096, v254
	v_add_u32_e32 v76, 6, v77
	v_and_b32_e32 v76, 3, v76
	v_lshl_add_u32 v76, v76, 4, v78
	v_and_b32_e32 v76, 63, v76
	v_lshl_add_u32 v255, v76, 2, v75
	v_add_u32_e32 v255, 6144, v255
	v_readfirstlane_b32 s38, v129
	s_mov_b32 s52, s2
	s_cmpk_ge_i32 s52, 0x200
	s_cbranch_scc1 .Lmy_op0_end
.Lmy_op0_tile:
	s_and_b32 s20, s52, 7
	s_lshl_b32 s20, s20, 3
	s_bfe_u32 s21, s52, 0x30003
	s_or_b32 s22, s20, s21
	s_bfe_u32 s23, s52, 0x30006
	s_lshl_b32 s20, s22, 19
	s_add_u32 s98, s50, s20
	s_addc_u32 s99, s51, 0
	s_add_u32 s98, s98, 0x5a00000
	s_addc_u32 s99, s99, 0
	s_add_u32 s100, s98, 0x2000000
	s_addc_u32 s101, s99, 0
	s_lshl_b32 s21, s23, 19
	s_add_u32 s4, s50, s21
	s_addc_u32 s5, s51, 0
	s_add_u32 s4, s4, 0x2800000
	s_addc_u32 s5, s5, 0
	s_lshr_b32 s21, s22, 5
	s_mul_i32 s21, s21, 0x3000
	s_lshl_b32 s24, s23, 9
	s_add_i32 s21, s21, s24
	s_add_i32 s21, s21, 0x10c2000
	s_add_u32 s6, s50, s21
	s_addc_u32 s7, s51, 0
	s_add_u32 s8, s6, 0x6000
	s_addc_u32 s9, s7, 0
	s_add_i32 s20, s20, s24
	s_add_u32 s10, s68, s20
	s_addc_u32 s11, s69, 0
	s_add_u32 s12, s48, s20
	s_addc_u32 s13, s49, 0
	global_load_dwordx4 v[0:3], v148, s[6:7]
	global_load_dwordx4 v[4:7], v148, s[6:7] offset:16
	s_add_u32 s6, s6, 0xc000
	s_addc_u32 s7, s7, 0
	global_load_dwordx4 v[8:11], v148, s[6:7]
	global_load_dwordx4 v[12:15], v148, s[6:7] offset:16
	s_add_u32 s6, s6, 0xc000
	s_addc_u32 s7, s7, 0
	global_load_dwordx4 v[16:19], v148, s[6:7]
	global_load_dwordx4 v[20:23], v148, s[6:7] offset:16
	s_add_u32 s6, s6, 0xc000
	s_addc_u32 s7, s7, 0
	global_load_dwordx4 v[24:27], v148, s[6:7]
	global_load_dwordx4 v[28:31], v148, s[6:7] offset:16
	s_add_u32 s6, s6, 0xc000
	s_addc_u32 s7, s7, 0
	global_load_dwordx4 v[32:35], v148, s[6:7]
	global_load_dwordx4 v[36:39], v148, s[6:7] offset:16
	s_add_u32 s6, s6, 0xc000
	s_addc_u32 s7, s7, 0
	global_load_dwordx4 v[40:43], v148, s[6:7]
	global_load_dwordx4 v[44:47], v148, s[6:7] offset:16
	s_add_u32 s6, s6, 0xc000
	s_addc_u32 s7, s7, 0
	global_load_dwordx4 v[48:51], v148, s[6:7]
	global_load_dwordx4 v[52:55], v148, s[6:7] offset:16
	s_add_u32 s6, s6, 0xc000
	s_addc_u32 s7, s7, 0
	global_load_dwordx4 v[56:59], v148, s[6:7]
	global_load_dwordx4 v[60:63], v148, s[6:7] offset:16
	global_load_dwordx4 v[160:163], v148, s[8:9]
	global_load_dwordx4 v[164:167], v148, s[8:9] offset:16
	s_add_u32 s8, s8, 0xc000
	s_addc_u32 s9, s9, 0
	global_load_dwordx4 v[168:171], v148, s[8:9]
	global_load_dwordx4 v[172:175], v148, s[8:9] offset:16
	s_add_u32 s8, s8, 0xc000
	s_addc_u32 s9, s9, 0
	global_load_dwordx4 v[176:179], v148, s[8:9]
	global_load_dwordx4 v[180:183], v148, s[8:9] offset:16
	s_add_u32 s8, s8, 0xc000
	s_addc_u32 s9, s9, 0
	global_load_dwordx4 v[184:187], v148, s[8:9]
	global_load_dwordx4 v[188:191], v148, s[8:9] offset:16
	s_add_u32 s8, s8, 0xc000
	s_addc_u32 s9, s9, 0
	global_load_dwordx4 v[192:195], v148, s[8:9]
	global_load_dwordx4 v[196:199], v148, s[8:9] offset:16
	s_add_u32 s8, s8, 0xc000
	s_addc_u32 s9, s9, 0
	global_load_dwordx4 v[200:203], v148, s[8:9]
	global_load_dwordx4 v[204:207], v148, s[8:9] offset:16
	s_add_u32 s8, s8, 0xc000
	s_addc_u32 s9, s9, 0
	global_load_dwordx4 v[208:211], v148, s[8:9]
	global_load_dwordx4 v[212:215], v148, s[8:9] offset:16
	s_add_u32 s8, s8, 0xc000
	s_addc_u32 s9, s9, 0
	global_load_dwordx4 v[216:219], v148, s[8:9]
	global_load_dwordx4 v[230:233], v148, s[8:9] offset:16
	s_barrier
	s_add_u32 m0, s38, 32768
	s_nop 0
	global_load_lds_dwordx4 v226, s[4:5]
	s_add_u32 m0, s38, 36864
	s_nop 0
	global_load_lds_dwordx4 v228, s[4:5]
	s_add_u32 m0, s38, 40960
	s_nop 0
	global_load_lds_dwordx4 v244, s[4:5]
	s_add_u32 m0, s38, 45056
	s_nop 0
	global_load_lds_dwordx4 v245, s[4:5]
	s_add_u32 s4, s4, 128
	s_addc_u32 s5, s5, 0
	s_add_u32 m0, s38, 0
	s_nop 0
	global_load_lds_dwordx4 v226, s[98:99]
	s_add_u32 m0, s38, 4096
	s_nop 0
	global_load_lds_dwordx4 v228, s[98:99]
	s_add_u32 m0, s38, 8192
	s_nop 0
	global_load_lds_dwordx4 v244, s[98:99]
	s_add_u32 m0, s38, 12288
	s_nop 0
	global_load_lds_dwordx4 v245, s[98:99]
	s_add_u32 s98, s98, 128
	s_addc_u32 s99, s99, 0
	s_add_u32 m0, s38, 16384
	s_nop 0
	global_load_lds_dwordx4 v226, s[100:101]
	s_add_u32 m0, s38, 20480
	s_nop 0
	global_load_lds_dwordx4 v228, s[100:101]
	s_add_u32 m0, s38, 24576
	s_nop 0
	global_load_lds_dwordx4 v244, s[100:101]
	s_add_u32 m0, s38, 28672
	s_nop 0
	global_load_lds_dwordx4 v245, s[100:101]
	s_add_u32 s100, s100, 128
	s_addc_u32 s101, s101, 0
	s_add_u32 m0, s38, 49152
	s_nop 0
	global_load_lds_dwordx4 v226, s[4:5]
	s_add_u32 m0, s38, 53248
	s_nop 0
	global_load_lds_dwordx4 v228, s[4:5]
	s_add_u32 m0, s38, 57344
	s_nop 0
	global_load_lds_dwordx4 v244, s[4:5]
	s_add_u32 m0, s38, 61440
	s_nop 0
	global_load_lds_dwordx4 v245, s[4:5]
	s_add_u32 s4, s4, 128
	s_addc_u32 s5, s5, 0
	s_waitcnt vmcnt(16)
	v_add_f32_e32 v142, 0, v0
	v_add_f32_e32 v143, 0, v1
	v_add_f32_e32 v144, 0, v2
	v_add_f32_e32 v145, 0, v3
	v_add_f32_e32 v146, 0, v4
	v_add_f32_e32 v147, 0, v5
	v_add_f32_e32 v234, 0, v6
	v_add_f32_e32 v235, 0, v7
	v_add_f32_e32 v142, v142, v8
	v_add_f32_e32 v143, v143, v9
	v_add_f32_e32 v144, v144, v10
	v_add_f32_e32 v145, v145, v11
	v_add_f32_e32 v146, v146, v12
	v_add_f32_e32 v147, v147, v13
	v_add_f32_e32 v234, v234, v14
	v_add_f32_e32 v235, v235, v15
	v_add_f32_e32 v142, v142, v16
	v_add_f32_e32 v143, v143, v17
	v_add_f32_e32 v144, v144, v18
	v_add_f32_e32 v145, v145, v19
	v_add_f32_e32 v146, v146, v20
	v_add_f32_e32 v147, v147, v21
	v_add_f32_e32 v234, v234, v22
	v_add_f32_e32 v235, v235, v23
	v_add_f32_e32 v142, v142, v24
	v_add_f32_e32 v143, v143, v25
	v_add_f32_e32 v144, v144, v26
	v_add_f32_e32 v145, v145, v27
	v_add_f32_e32 v146, v146, v28
	v_add_f32_e32 v147, v147, v29
	v_add_f32_e32 v234, v234, v30
	v_add_f32_e32 v235, v235, v31
	v_add_f32_e32 v142, v142, v32
	v_add_f32_e32 v143, v143, v33
	v_add_f32_e32 v144, v144, v34
	v_add_f32_e32 v145, v145, v35
	v_add_f32_e32 v146, v146, v36
	v_add_f32_e32 v147, v147, v37
	v_add_f32_e32 v234, v234, v38
	v_add_f32_e32 v235, v235, v39
	v_add_f32_e32 v142, v142, v40
	v_add_f32_e32 v143, v143, v41
	v_add_f32_e32 v144, v144, v42
	v_add_f32_e32 v145, v145, v43
	v_add_f32_e32 v146, v146, v44
	v_add_f32_e32 v147, v147, v45
	v_add_f32_e32 v234, v234, v46
	v_add_f32_e32 v235, v235, v47
	v_add_f32_e32 v142, v142, v48
	v_add_f32_e32 v143, v143, v49
	v_add_f32_e32 v144, v144, v50
	v_add_f32_e32 v145, v145, v51
	v_add_f32_e32 v146, v146, v52
	v_add_f32_e32 v147, v147, v53
	v_add_f32_e32 v234, v234, v54
	v_add_f32_e32 v235, v235, v55
	v_add_f32_e32 v142, v142, v56
	v_add_f32_e32 v143, v143, v57
	v_add_f32_e32 v144, v144, v58
	v_add_f32_e32 v145, v145, v59
	v_add_f32_e32 v146, v146, v60
	v_add_f32_e32 v147, v147, v61
	v_add_f32_e32 v234, v234, v62
	v_add_f32_e32 v235, v235, v63
	v_add_f32_e32 v236, 0, v160
	v_add_f32_e32 v237, 0, v161
	v_add_f32_e32 v238, 0, v162
	v_add_f32_e32 v239, 0, v163
	v_add_f32_e32 v240, 0, v164
	v_add_f32_e32 v241, 0, v165
	v_add_f32_e32 v242, 0, v166
	v_add_f32_e32 v243, 0, v167
	v_add_f32_e32 v236, v236, v168
	v_add_f32_e32 v237, v237, v169
	v_add_f32_e32 v238, v238, v170
	v_add_f32_e32 v239, v239, v171
	v_add_f32_e32 v240, v240, v172
	v_add_f32_e32 v241, v241, v173
	v_add_f32_e32 v242, v242, v174
	v_add_f32_e32 v243, v243, v175
	v_add_f32_e32 v236, v236, v176
	v_add_f32_e32 v237, v237, v177
	v_add_f32_e32 v238, v238, v178
	v_add_f32_e32 v239, v239, v179
	v_add_f32_e32 v240, v240, v180
	v_add_f32_e32 v241, v241, v181
	v_add_f32_e32 v242, v242, v182
	v_add_f32_e32 v243, v243, v183
	v_add_f32_e32 v236, v236, v184
	v_add_f32_e32 v237, v237, v185
	v_add_f32_e32 v238, v238, v186
	v_add_f32_e32 v239, v239, v187
	v_add_f32_e32 v240, v240, v188
	v_add_f32_e32 v241, v241, v189
	v_add_f32_e32 v242, v242, v190
	v_add_f32_e32 v243, v243, v191
	v_add_f32_e32 v236, v236, v192
	v_add_f32_e32 v237, v237, v193
	v_add_f32_e32 v238, v238, v194
	v_add_f32_e32 v239, v239, v195
	v_add_f32_e32 v240, v240, v196
	v_add_f32_e32 v241, v241, v197
	v_add_f32_e32 v242, v242, v198
	v_add_f32_e32 v243, v243, v199
	v_add_f32_e32 v236, v236, v200
	v_add_f32_e32 v237, v237, v201
	v_add_f32_e32 v238, v238, v202
	v_add_f32_e32 v239, v239, v203
	v_add_f32_e32 v240, v240, v204
	v_add_f32_e32 v241, v241, v205
	v_add_f32_e32 v242, v242, v206
	v_add_f32_e32 v243, v243, v207
	v_add_f32_e32 v236, v236, v208
	v_add_f32_e32 v237, v237, v209
	v_add_f32_e32 v238, v238, v210
	v_add_f32_e32 v239, v239, v211
	v_add_f32_e32 v240, v240, v212
	v_add_f32_e32 v241, v241, v213
	v_add_f32_e32 v242, v242, v214
	v_add_f32_e32 v243, v243, v215
	v_add_f32_e32 v236, v236, v216
	v_add_f32_e32 v237, v237, v217
	v_add_f32_e32 v238, v238, v218
	v_add_f32_e32 v239, v239, v219
	v_add_f32_e32 v240, v240, v230
	v_add_f32_e32 v241, v241, v231
	v_add_f32_e32 v242, v242, v232
	v_add_f32_e32 v243, v243, v233
	s_waitcnt vmcnt(8)
	s_barrier
	ds_read_b128 v[64:67], v151 offset:0
	ds_read_b128 v[96:99], v222 offset:32768
	ds_read_b128 v[100:103], v222 offset:34816
	ds_read_b128 v[104:107], v222 offset:36864
	ds_read_b128 v[108:111], v222 offset:38912
	ds_read_b128 v[68:71], v151 offset:2048
	ds_read_b128 v[72:75], v151 offset:4096
	ds_read_b128 v[76:79], v151 offset:6144
	s_waitcnt lgkmcnt(6)
	v_mfma_f32_16x16x32_bf16 v[0:3], v[64:67], v[96:99], 0
	ds_read_b128 v[80:83], v220 offset:0
	s_waitcnt lgkmcnt(6)
	v_mfma_f32_16x16x32_bf16 v[4:7], v[64:67], v[100:103], 0
	ds_read_b128 v[112:115], v224 offset:32768
	s_waitcnt lgkmcnt(6)
	v_mfma_f32_16x16x32_bf16 v[8:11], v[64:67], v[104:107], 0
	ds_read_b128 v[116:119], v224 offset:34816
	s_waitcnt lgkmcnt(6)
	v_mfma_f32_16x16x32_bf16 v[12:15], v[64:67], v[108:111], 0
	ds_read_b128 v[120:123], v224 offset:36864
	s_waitcnt lgkmcnt(6)
	v_mfma_f32_16x16x32_bf16 v[16:19], v[68:71], v[96:99], 0
	ds_read_b128 v[124:127], v224 offset:38912
	s_waitcnt lgkmcnt(7)
	v_mfma_f32_16x16x32_bf16 v[20:23], v[68:71], v[100:103], 0
	ds_read_b128 v[84:87], v220 offset:2048
	s_waitcnt lgkmcnt(8)
	v_mfma_f32_16x16x32_bf16 v[24:27], v[68:71], v[104:107], 0
	ds_read_b128 v[88:91], v220 offset:4096
	s_waitcnt lgkmcnt(9)
	v_mfma_f32_16x16x32_bf16 v[28:31], v[68:71], v[108:111], 0
	ds_read_b128 v[92:95], v220 offset:6144
	s_waitcnt lgkmcnt(9)
	v_mfma_f32_16x16x32_bf16 v[32:35], v[72:75], v[96:99], 0
	s_waitcnt lgkmcnt(9)
	v_mfma_f32_16x16x32_bf16 v[36:39], v[72:75], v[100:103], 0
	s_waitcnt lgkmcnt(9)
	v_mfma_f32_16x16x32_bf16 v[40:43], v[72:75], v[104:107], 0
	s_waitcnt lgkmcnt(9)
	v_mfma_f32_16x16x32_bf16 v[44:47], v[72:75], v[108:111], 0
	s_waitcnt vmcnt(4) lgkmcnt(0)
	s_barrier
	s_add_u32 m0, s38, 0
	s_nop 0
	global_load_lds_dwordx4 v226, s[98:99]
	s_waitcnt lgkmcnt(8)
	v_mfma_f32_16x16x32_bf16 v[48:51], v[76:79], v[96:99], 0
	s_add_u32 m0, s38, 4096
	s_nop 0
	global_load_lds_dwordx4 v228, s[98:99]
	s_waitcnt lgkmcnt(8)
	v_mfma_f32_16x16x32_bf16 v[52:55], v[76:79], v[100:103], 0
	s_add_u32 m0, s38, 8192
	s_nop 0
	global_load_lds_dwordx4 v244, s[98:99]
	s_waitcnt lgkmcnt(8)
	v_mfma_f32_16x16x32_bf16 v[56:59], v[76:79], v[104:107], 0
	s_add_u32 m0, s38, 12288
	s_nop 0
	global_load_lds_dwordx4 v245, s[98:99]
	s_add_u32 s98, s98, 128
	s_addc_u32 s99, s99, 0
	s_waitcnt lgkmcnt(8)
	v_mfma_f32_16x16x32_bf16 v[60:63], v[76:79], v[108:111], 0
	s_waitcnt lgkmcnt(6)
	v_mfma_f32_16x16x32_bf16 v[0:3], v[80:83], v[112:115], v[0:3]
	ds_read_b128 v[64:67], v151 offset:16384
	s_waitcnt lgkmcnt(6)
	v_mfma_f32_16x16x32_bf16 v[4:7], v[80:83], v[116:119], v[4:7]
	ds_read_b128 v[96:99], v222 offset:32768
	s_waitcnt lgkmcnt(6)
	v_mfma_f32_16x16x32_bf16 v[8:11], v[80:83], v[120:123], v[8:11]
	ds_read_b128 v[100:103], v222 offset:34816
	s_waitcnt lgkmcnt(6)
	v_mfma_f32_16x16x32_bf16 v[12:15], v[80:83], v[124:127], v[12:15]
	ds_read_b128 v[104:107], v222 offset:36864
	s_waitcnt lgkmcnt(6)
	v_mfma_f32_16x16x32_bf16 v[16:19], v[84:87], v[112:115], v[16:19]
	ds_read_b128 v[108:111], v222 offset:38912
	s_waitcnt lgkmcnt(7)
	v_mfma_f32_16x16x32_bf16 v[20:23], v[84:87], v[116:119], v[20:23]
	ds_read_b128 v[68:71], v151 offset:18432
	s_waitcnt lgkmcnt(8)
	v_mfma_f32_16x16x32_bf16 v[24:27], v[84:87], v[120:123], v[24:27]
	ds_read_b128 v[72:75], v151 offset:20480
	s_waitcnt lgkmcnt(9)
	v_mfma_f32_16x16x32_bf16 v[28:31], v[84:87], v[124:127], v[28:31]
	ds_read_b128 v[76:79], v151 offset:22528
	s_waitcnt lgkmcnt(9)
	v_mfma_f32_16x16x32_bf16 v[32:35], v[88:91], v[112:115], v[32:35]
	s_waitcnt lgkmcnt(9)
	v_mfma_f32_16x16x32_bf16 v[36:39], v[88:91], v[116:119], v[36:39]
	s_waitcnt lgkmcnt(9)
	v_mfma_f32_16x16x32_bf16 v[40:43], v[88:91], v[120:123], v[40:43]
	s_waitcnt lgkmcnt(9)
	v_mfma_f32_16x16x32_bf16 v[44:47], v[88:91], v[124:127], v[44:47]
	s_waitcnt lgkmcnt(8)
	v_mfma_f32_16x16x32_bf16 v[48:51], v[92:95], v[112:115], v[48:51]
	s_waitcnt lgkmcnt(8)
	v_mfma_f32_16x16x32_bf16 v[52:55], v[92:95], v[116:119], v[52:55]
	s_waitcnt lgkmcnt(8)
	v_mfma_f32_16x16x32_bf16 v[56:59], v[92:95], v[120:123], v[56:59]
	s_waitcnt lgkmcnt(8)
	v_mfma_f32_16x16x32_bf16 v[60:63], v[92:95], v[124:127], v[60:63]
	s_waitcnt lgkmcnt(6)
	v_mfma_f32_16x16x32_bf16 v[160:163], v[64:67], v[96:99], 0
	ds_read_b128 v[80:83], v220 offset:16384
	s_waitcnt lgkmcnt(6)
	v_mfma_f32_16x16x32_bf16 v[164:167], v[64:67], v[100:103], 0
	ds_read_b128 v[112:115], v224 offset:32768
	s_waitcnt lgkmcnt(6)
	v_mfma_f32_16x16x32_bf16 v[168:171], v[64:67], v[104:107], 0
	ds_read_b128 v[116:119], v224 offset:34816
	s_waitcnt lgkmcnt(6)
	v_mfma_f32_16x16x32_bf16 v[172:175], v[64:67], v[108:111], 0
	ds_read_b128 v[120:123], v224 offset:36864
	s_waitcnt lgkmcnt(6)
	v_mfma_f32_16x16x32_bf16 v[176:179], v[68:71], v[96:99], 0
	ds_read_b128 v[124:127], v224 offset:38912
	s_waitcnt lgkmcnt(7)
	v_mfma_f32_16x16x32_bf16 v[180:183], v[68:71], v[100:103], 0
	ds_read_b128 v[84:87], v220 offset:18432
	s_waitcnt lgkmcnt(8)
	v_mfma_f32_16x16x32_bf16 v[184:187], v[68:71], v[104:107], 0
	ds_read_b128 v[88:91], v220 offset:20480
	s_waitcnt lgkmcnt(9)
	v_mfma_f32_16x16x32_bf16 v[188:191], v[68:71], v[108:111], 0
	ds_read_b128 v[92:95], v220 offset:22528
	s_waitcnt lgkmcnt(9)
	v_mfma_f32_16x16x32_bf16 v[192:195], v[72:75], v[96:99], 0
	s_waitcnt lgkmcnt(9)
	v_mfma_f32_16x16x32_bf16 v[196:199], v[72:75], v[100:103], 0
	s_waitcnt lgkmcnt(9)
	v_mfma_f32_16x16x32_bf16 v[200:203], v[72:75], v[104:107], 0
	s_waitcnt lgkmcnt(9)
	v_mfma_f32_16x16x32_bf16 v[204:207], v[72:75], v[108:111], 0
	s_waitcnt vmcnt(0) lgkmcnt(0)
	s_barrier
	s_add_u32 m0, s38, 16384
	s_nop 0
	global_load_lds_dwordx4 v226, s[100:101]
	s_waitcnt lgkmcnt(8)
	v_mfma_f32_16x16x32_bf16 v[208:211], v[76:79], v[96:99], 0
	s_add_u32 m0, s38, 20480
	s_nop 0
	global_load_lds_dwordx4 v228, s[100:101]
	s_waitcnt lgkmcnt(8)
	v_mfma_f32_16x16x32_bf16 v[212:215], v[76:79], v[100:103], 0
	s_add_u32 m0, s38, 24576
	s_nop 0
	global_load_lds_dwordx4 v244, s[100:101]
	s_waitcnt lgkmcnt(8)
	v_mfma_f32_16x16x32_bf16 v[216:219], v[76:79], v[104:107], 0
	s_add_u32 m0, s38, 28672
	s_nop 0
	global_load_lds_dwordx4 v245, s[100:101]
	s_add_u32 s100, s100, 128
	s_addc_u32 s101, s101, 0
	s_waitcnt lgkmcnt(8)
	v_mfma_f32_16x16x32_bf16 v[230:233], v[76:79], v[108:111], 0
	s_add_u32 m0, s38, 32768
	s_nop 0
	global_load_lds_dwordx4 v226, s[4:5]
	s_waitcnt lgkmcnt(6)
	v_mfma_f32_16x16x32_bf16 v[160:163], v[80:83], v[112:115], v[160:163]
	ds_read_b128 v[64:67], v151 offset:0
	s_add_u32 m0, s38, 36864
	s_nop 0
	global_load_lds_dwordx4 v228, s[4:5]
	s_waitcnt lgkmcnt(6)
	v_mfma_f32_16x16x32_bf16 v[164:167], v[80:83], v[116:119], v[164:167]
	ds_read_b128 v[96:99], v222 offset:49152
	s_add_u32 m0, s38, 40960
	s_nop 0
	global_load_lds_dwordx4 v244, s[4:5]
	s_waitcnt lgkmcnt(6)
	v_mfma_f32_16x16x32_bf16 v[168:171], v[80:83], v[120:123], v[168:171]
	ds_read_b128 v[100:103], v222 offset:51200
	s_add_u32 m0, s38, 45056
	s_nop 0
	global_load_lds_dwordx4 v245, s[4:5]
	s_add_u32 s4, s4, 128
	s_addc_u32 s5, s5, 0
	s_waitcnt lgkmcnt(6)
	v_mfma_f32_16x16x32_bf16 v[172:175], v[80:83], v[124:127], v[172:175]
	ds_read_b128 v[104:107], v222 offset:53248
	s_waitcnt lgkmcnt(6)
	v_mfma_f32_16x16x32_bf16 v[176:179], v[84:87], v[112:115], v[176:179]
	ds_read_b128 v[108:111], v222 offset:55296
	s_waitcnt lgkmcnt(7)
	v_mfma_f32_16x16x32_bf16 v[180:183], v[84:87], v[116:119], v[180:183]
	ds_read_b128 v[68:71], v151 offset:2048
	s_waitcnt lgkmcnt(8)
	v_mfma_f32_16x16x32_bf16 v[184:187], v[84:87], v[120:123], v[184:187]
	ds_read_b128 v[72:75], v151 offset:4096
	s_waitcnt lgkmcnt(9)
	v_mfma_f32_16x16x32_bf16 v[188:191], v[84:87], v[124:127], v[188:191]
	ds_read_b128 v[76:79], v151 offset:6144
	s_waitcnt lgkmcnt(9)
	v_mfma_f32_16x16x32_bf16 v[192:195], v[88:91], v[112:115], v[192:195]
	s_waitcnt lgkmcnt(9)
	v_mfma_f32_16x16x32_bf16 v[196:199], v[88:91], v[116:119], v[196:199]
	s_waitcnt lgkmcnt(9)
	v_mfma_f32_16x16x32_bf16 v[200:203], v[88:91], v[120:123], v[200:203]
	s_waitcnt lgkmcnt(9)
	v_mfma_f32_16x16x32_bf16 v[204:207], v[88:91], v[124:127], v[204:207]
	s_waitcnt lgkmcnt(8)
	v_mfma_f32_16x16x32_bf16 v[208:211], v[92:95], v[112:115], v[208:211]
	s_waitcnt lgkmcnt(8)
	v_mfma_f32_16x16x32_bf16 v[212:215], v[92:95], v[116:119], v[212:215]
	s_waitcnt lgkmcnt(8)
	v_mfma_f32_16x16x32_bf16 v[216:219], v[92:95], v[120:123], v[216:219]
	s_waitcnt lgkmcnt(8)
	v_mfma_f32_16x16x32_bf16 v[230:233], v[92:95], v[124:127], v[230:233]
	s_waitcnt lgkmcnt(6)
	v_mfma_f32_16x16x32_bf16 v[0:3], v[64:67], v[96:99], v[0:3]
	ds_read_b128 v[80:83], v220 offset:0
	s_waitcnt lgkmcnt(6)
	v_mfma_f32_16x16x32_bf16 v[4:7], v[64:67], v[100:103], v[4:7]
	ds_read_b128 v[112:115], v224 offset:49152
	s_waitcnt lgkmcnt(6)
	v_mfma_f32_16x16x32_bf16 v[8:11], v[64:67], v[104:107], v[8:11]
	ds_read_b128 v[116:119], v224 offset:51200
	s_waitcnt lgkmcnt(6)
	v_mfma_f32_16x16x32_bf16 v[12:15], v[64:67], v[108:111], v[12:15]
	ds_read_b128 v[120:123], v224 offset:53248
	s_waitcnt lgkmcnt(6)
	v_mfma_f32_16x16x32_bf16 v[16:19], v[68:71], v[96:99], v[16:19]
	ds_read_b128 v[124:127], v224 offset:55296
	s_waitcnt lgkmcnt(7)
	v_mfma_f32_16x16x32_bf16 v[20:23], v[68:71], v[100:103], v[20:23]
	ds_read_b128 v[84:87], v220 offset:2048
	s_waitcnt lgkmcnt(8)
	v_mfma_f32_16x16x32_bf16 v[24:27], v[68:71], v[104:107], v[24:27]
	ds_read_b128 v[88:91], v220 offset:4096
	s_waitcnt lgkmcnt(9)
	v_mfma_f32_16x16x32_bf16 v[28:31], v[68:71], v[108:111], v[28:31]
	ds_read_b128 v[92:95], v220 offset:6144
	s_waitcnt lgkmcnt(9)
	v_mfma_f32_16x16x32_bf16 v[32:35], v[72:75], v[96:99], v[32:35]
	s_waitcnt lgkmcnt(9)
	v_mfma_f32_16x16x32_bf16 v[36:39], v[72:75], v[100:103], v[36:39]
	s_waitcnt lgkmcnt(9)
	v_mfma_f32_16x16x32_bf16 v[40:43], v[72:75], v[104:107], v[40:43]
	s_waitcnt lgkmcnt(9)
	v_mfma_f32_16x16x32_bf16 v[44:47], v[72:75], v[108:111], v[44:47]
	s_waitcnt vmcnt(4) lgkmcnt(0)
	s_barrier
	s_add_u32 m0, s38, 0
	s_nop 0
	global_load_lds_dwordx4 v226, s[98:99]
	s_waitcnt lgkmcnt(8)
	v_mfma_f32_16x16x32_bf16 v[48:51], v[76:79], v[96:99], v[48:51]
	s_add_u32 m0, s38, 4096
	s_nop 0
	global_load_lds_dwordx4 v228, s[98:99]
	s_waitcnt lgkmcnt(8)
	v_mfma_f32_16x16x32_bf16 v[52:55], v[76:79], v[100:103], v[52:55]
	s_add_u32 m0, s38, 8192
	s_nop 0
	global_load_lds_dwordx4 v244, s[98:99]
	s_waitcnt lgkmcnt(8)
	v_mfma_f32_16x16x32_bf16 v[56:59], v[76:79], v[104:107], v[56:59]
	s_add_u32 m0, s38, 12288
	s_nop 0
	global_load_lds_dwordx4 v245, s[98:99]
	s_add_u32 s98, s98, 128
	s_addc_u32 s99, s99, 0
	s_waitcnt lgkmcnt(8)
	v_mfma_f32_16x16x32_bf16 v[60:63], v[76:79], v[108:111], v[60:63]
	s_waitcnt lgkmcnt(6)
	v_mfma_f32_16x16x32_bf16 v[0:3], v[80:83], v[112:115], v[0:3]
	ds_read_b128 v[64:67], v151 offset:16384
	s_waitcnt lgkmcnt(6)
	v_mfma_f32_16x16x32_bf16 v[4:7], v[80:83], v[116:119], v[4:7]
	ds_read_b128 v[96:99], v222 offset:49152
	s_waitcnt lgkmcnt(6)
	v_mfma_f32_16x16x32_bf16 v[8:11], v[80:83], v[120:123], v[8:11]
	ds_read_b128 v[100:103], v222 offset:51200
	s_waitcnt lgkmcnt(6)
	v_mfma_f32_16x16x32_bf16 v[12:15], v[80:83], v[124:127], v[12:15]
	ds_read_b128 v[104:107], v222 offset:53248
	s_waitcnt lgkmcnt(6)
	v_mfma_f32_16x16x32_bf16 v[16:19], v[84:87], v[112:115], v[16:19]
	ds_read_b128 v[108:111], v222 offset:55296
	s_waitcnt lgkmcnt(7)
	v_mfma_f32_16x16x32_bf16 v[20:23], v[84:87], v[116:119], v[20:23]
	ds_read_b128 v[68:71], v151 offset:18432
	s_waitcnt lgkmcnt(8)
	v_mfma_f32_16x16x32_bf16 v[24:27], v[84:87], v[120:123], v[24:27]
	ds_read_b128 v[72:75], v151 offset:20480
	s_waitcnt lgkmcnt(9)
	v_mfma_f32_16x16x32_bf16 v[28:31], v[84:87], v[124:127], v[28:31]
	ds_read_b128 v[76:79], v151 offset:22528
	s_waitcnt lgkmcnt(9)
	v_mfma_f32_16x16x32_bf16 v[32:35], v[88:91], v[112:115], v[32:35]
	s_waitcnt lgkmcnt(9)
	v_mfma_f32_16x16x32_bf16 v[36:39], v[88:91], v[116:119], v[36:39]
	s_waitcnt lgkmcnt(9)
	v_mfma_f32_16x16x32_bf16 v[40:43], v[88:91], v[120:123], v[40:43]
	s_waitcnt lgkmcnt(9)
	v_mfma_f32_16x16x32_bf16 v[44:47], v[88:91], v[124:127], v[44:47]
	s_waitcnt lgkmcnt(8)
	v_mfma_f32_16x16x32_bf16 v[48:51], v[92:95], v[112:115], v[48:51]
	s_waitcnt lgkmcnt(8)
	v_mfma_f32_16x16x32_bf16 v[52:55], v[92:95], v[116:119], v[52:55]
	s_waitcnt lgkmcnt(8)
	v_mfma_f32_16x16x32_bf16 v[56:59], v[92:95], v[120:123], v[56:59]
	s_waitcnt lgkmcnt(8)
	v_mfma_f32_16x16x32_bf16 v[60:63], v[92:95], v[124:127], v[60:63]
	s_waitcnt lgkmcnt(6)
	v_mfma_f32_16x16x32_bf16 v[160:163], v[64:67], v[96:99], v[160:163]
	ds_read_b128 v[80:83], v220 offset:16384
	s_waitcnt lgkmcnt(6)
	v_mfma_f32_16x16x32_bf16 v[164:167], v[64:67], v[100:103], v[164:167]
	ds_read_b128 v[112:115], v224 offset:49152
	s_waitcnt lgkmcnt(6)
	v_mfma_f32_16x16x32_bf16 v[168:171], v[64:67], v[104:107], v[168:171]
	ds_read_b128 v[116:119], v224 offset:51200
	s_waitcnt lgkmcnt(6)
	v_mfma_f32_16x16x32_bf16 v[172:175], v[64:67], v[108:111], v[172:175]
	ds_read_b128 v[120:123], v224 offset:53248
	s_waitcnt lgkmcnt(6)
	v_mfma_f32_16x16x32_bf16 v[176:179], v[68:71], v[96:99], v[176:179]
	ds_read_b128 v[124:127], v224 offset:55296
	s_waitcnt lgkmcnt(7)
	v_mfma_f32_16x16x32_bf16 v[180:183], v[68:71], v[100:103], v[180:183]
	ds_read_b128 v[84:87], v220 offset:18432
	s_waitcnt lgkmcnt(8)
	v_mfma_f32_16x16x32_bf16 v[184:187], v[68:71], v[104:107], v[184:187]
	ds_read_b128 v[88:91], v220 offset:20480
	s_waitcnt lgkmcnt(9)
	v_mfma_f32_16x16x32_bf16 v[188:191], v[68:71], v[108:111], v[188:191]
	ds_read_b128 v[92:95], v220 offset:22528
	s_waitcnt lgkmcnt(9)
	v_mfma_f32_16x16x32_bf16 v[192:195], v[72:75], v[96:99], v[192:195]
	s_waitcnt lgkmcnt(9)
	v_mfma_f32_16x16x32_bf16 v[196:199], v[72:75], v[100:103], v[196:199]
	s_waitcnt lgkmcnt(9)
	v_mfma_f32_16x16x32_bf16 v[200:203], v[72:75], v[104:107], v[200:203]
	s_waitcnt lgkmcnt(9)
	v_mfma_f32_16x16x32_bf16 v[204:207], v[72:75], v[108:111], v[204:207]
	s_waitcnt vmcnt(0) lgkmcnt(0)
	s_barrier
	s_add_u32 m0, s38, 16384
	s_nop 0
	global_load_lds_dwordx4 v226, s[100:101]
	s_waitcnt lgkmcnt(8)
	v_mfma_f32_16x16x32_bf16 v[208:211], v[76:79], v[96:99], v[208:211]
	s_add_u32 m0, s38, 20480
	s_nop 0
	global_load_lds_dwordx4 v228, s[100:101]
	s_waitcnt lgkmcnt(8)
	v_mfma_f32_16x16x32_bf16 v[212:215], v[76:79], v[100:103], v[212:215]
	s_add_u32 m0, s38, 24576
	s_nop 0
	global_load_lds_dwordx4 v244, s[100:101]
	s_waitcnt lgkmcnt(8)
	v_mfma_f32_16x16x32_bf16 v[216:219], v[76:79], v[104:107], v[216:219]
	s_add_u32 m0, s38, 28672
	s_nop 0
	global_load_lds_dwordx4 v245, s[100:101]
	s_add_u32 s100, s100, 128
	s_addc_u32 s101, s101, 0
	s_waitcnt lgkmcnt(8)
	v_mfma_f32_16x16x32_bf16 v[230:233], v[76:79], v[108:111], v[230:233]
	s_add_u32 m0, s38, 49152
	s_nop 0
	global_load_lds_dwordx4 v226, s[4:5]
	s_waitcnt lgkmcnt(6)
	v_mfma_f32_16x16x32_bf16 v[160:163], v[80:83], v[112:115], v[160:163]
	ds_read_b128 v[64:67], v151 offset:0
	s_add_u32 m0, s38, 53248
	s_nop 0
	global_load_lds_dwordx4 v228, s[4:5]
	s_waitcnt lgkmcnt(6)
	v_mfma_f32_16x16x32_bf16 v[164:167], v[80:83], v[116:119], v[164:167]
	ds_read_b128 v[96:99], v222 offset:32768
	s_add_u32 m0, s38, 57344
	s_nop 0
	global_load_lds_dwordx4 v244, s[4:5]
	s_waitcnt lgkmcnt(6)
	v_mfma_f32_16x16x32_bf16 v[168:171], v[80:83], v[120:123], v[168:171]
	ds_read_b128 v[100:103], v222 offset:34816
	s_add_u32 m0, s38, 61440
	s_nop 0
	global_load_lds_dwordx4 v245, s[4:5]
	s_add_u32 s4, s4, 128
	s_addc_u32 s5, s5, 0
	s_waitcnt lgkmcnt(6)
	v_mfma_f32_16x16x32_bf16 v[172:175], v[80:83], v[124:127], v[172:175]
	ds_read_b128 v[104:107], v222 offset:36864
	s_waitcnt lgkmcnt(6)
	v_mfma_f32_16x16x32_bf16 v[176:179], v[84:87], v[112:115], v[176:179]
	ds_read_b128 v[108:111], v222 offset:38912
	s_waitcnt lgkmcnt(7)
	v_mfma_f32_16x16x32_bf16 v[180:183], v[84:87], v[116:119], v[180:183]
	ds_read_b128 v[68:71], v151 offset:2048
	s_waitcnt lgkmcnt(8)
	v_mfma_f32_16x16x32_bf16 v[184:187], v[84:87], v[120:123], v[184:187]
	ds_read_b128 v[72:75], v151 offset:4096
	s_waitcnt lgkmcnt(9)
	v_mfma_f32_16x16x32_bf16 v[188:191], v[84:87], v[124:127], v[188:191]
	ds_read_b128 v[76:79], v151 offset:6144
	s_waitcnt lgkmcnt(9)
	v_mfma_f32_16x16x32_bf16 v[192:195], v[88:91], v[112:115], v[192:195]
	s_waitcnt lgkmcnt(9)
	v_mfma_f32_16x16x32_bf16 v[196:199], v[88:91], v[116:119], v[196:199]
	s_waitcnt lgkmcnt(9)
	v_mfma_f32_16x16x32_bf16 v[200:203], v[88:91], v[120:123], v[200:203]
	s_waitcnt lgkmcnt(9)
	v_mfma_f32_16x16x32_bf16 v[204:207], v[88:91], v[124:127], v[204:207]
	s_waitcnt lgkmcnt(8)
	v_mfma_f32_16x16x32_bf16 v[208:211], v[92:95], v[112:115], v[208:211]
	s_waitcnt lgkmcnt(8)
	v_mfma_f32_16x16x32_bf16 v[212:215], v[92:95], v[116:119], v[212:215]
	s_waitcnt lgkmcnt(8)
	v_mfma_f32_16x16x32_bf16 v[216:219], v[92:95], v[120:123], v[216:219]
	s_waitcnt lgkmcnt(8)
	v_mfma_f32_16x16x32_bf16 v[230:233], v[92:95], v[124:127], v[230:233]
	s_waitcnt lgkmcnt(6)
	v_mfma_f32_16x16x32_bf16 v[0:3], v[64:67], v[96:99], v[0:3]
	ds_read_b128 v[80:83], v220 offset:0
	s_waitcnt lgkmcnt(6)
	v_mfma_f32_16x16x32_bf16 v[4:7], v[64:67], v[100:103], v[4:7]
	ds_read_b128 v[112:115], v224 offset:32768
	s_waitcnt lgkmcnt(6)
	v_mfma_f32_16x16x32_bf16 v[8:11], v[64:67], v[104:107], v[8:11]
	ds_read_b128 v[116:119], v224 offset:34816
	s_waitcnt lgkmcnt(6)
	v_mfma_f32_16x16x32_bf16 v[12:15], v[64:67], v[108:111], v[12:15]
	ds_read_b128 v[120:123], v224 offset:36864
	s_waitcnt lgkmcnt(6)
	v_mfma_f32_16x16x32_bf16 v[16:19], v[68:71], v[96:99], v[16:19]
	ds_read_b128 v[124:127], v224 offset:38912
	s_waitcnt lgkmcnt(7)
	v_mfma_f32_16x16x32_bf16 v[20:23], v[68:71], v[100:103], v[20:23]
	ds_read_b128 v[84:87], v220 offset:2048
	s_waitcnt lgkmcnt(8)
	v_mfma_f32_16x16x32_bf16 v[24:27], v[68:71], v[104:107], v[24:27]
	ds_read_b128 v[88:91], v220 offset:4096
	s_waitcnt lgkmcnt(9)
	v_mfma_f32_16x16x32_bf16 v[28:31], v[68:71], v[108:111], v[28:31]
	ds_read_b128 v[92:95], v220 offset:6144
	s_waitcnt lgkmcnt(9)
	v_mfma_f32_16x16x32_bf16 v[32:35], v[72:75], v[96:99], v[32:35]
	s_waitcnt lgkmcnt(9)
	v_mfma_f32_16x16x32_bf16 v[36:39], v[72:75], v[100:103], v[36:39]
	s_waitcnt lgkmcnt(9)
	v_mfma_f32_16x16x32_bf16 v[40:43], v[72:75], v[104:107], v[40:43]
	s_waitcnt lgkmcnt(9)
	v_mfma_f32_16x16x32_bf16 v[44:47], v[72:75], v[108:111], v[44:47]
	s_waitcnt vmcnt(4) lgkmcnt(0)
	s_barrier
	s_add_u32 m0, s38, 0
	s_nop 0
	global_load_lds_dwordx4 v226, s[98:99]
	s_waitcnt lgkmcnt(8)
	v_mfma_f32_16x16x32_bf16 v[48:51], v[76:79], v[96:99], v[48:51]
	s_add_u32 m0, s38, 4096
	s_nop 0
	global_load_lds_dwordx4 v228, s[98:99]
	s_waitcnt lgkmcnt(8)
	v_mfma_f32_16x16x32_bf16 v[52:55], v[76:79], v[100:103], v[52:55]
	s_add_u32 m0, s38, 8192
	s_nop 0
	global_load_lds_dwordx4 v244, s[98:99]
	s_waitcnt lgkmcnt(8)
	v_mfma_f32_16x16x32_bf16 v[56:59], v[76:79], v[104:107], v[56:59]
	s_add_u32 m0, s38, 12288
	s_nop 0
	global_load_lds_dwordx4 v245, s[98:99]
	s_add_u32 s98, s98, 128
	s_addc_u32 s99, s99, 0
	s_waitcnt lgkmcnt(8)
	v_mfma_f32_16x16x32_bf16 v[60:63], v[76:79], v[108:111], v[60:63]
	s_waitcnt lgkmcnt(6)
	v_mfma_f32_16x16x32_bf16 v[0:3], v[80:83], v[112:115], v[0:3]
	ds_read_b128 v[64:67], v151 offset:16384
	s_waitcnt lgkmcnt(6)
	v_mfma_f32_16x16x32_bf16 v[4:7], v[80:83], v[116:119], v[4:7]
	ds_read_b128 v[96:99], v222 offset:32768
	s_waitcnt lgkmcnt(6)
	v_mfma_f32_16x16x32_bf16 v[8:11], v[80:83], v[120:123], v[8:11]
	ds_read_b128 v[100:103], v222 offset:34816
	s_waitcnt lgkmcnt(6)
	v_mfma_f32_16x16x32_bf16 v[12:15], v[80:83], v[124:127], v[12:15]
	ds_read_b128 v[104:107], v222 offset:36864
	s_waitcnt lgkmcnt(6)
	v_mfma_f32_16x16x32_bf16 v[16:19], v[84:87], v[112:115], v[16:19]
	ds_read_b128 v[108:111], v222 offset:38912
	s_waitcnt lgkmcnt(7)
	v_mfma_f32_16x16x32_bf16 v[20:23], v[84:87], v[116:119], v[20:23]
	ds_read_b128 v[68:71], v151 offset:18432
	s_waitcnt lgkmcnt(8)
	v_mfma_f32_16x16x32_bf16 v[24:27], v[84:87], v[120:123], v[24:27]
	ds_read_b128 v[72:75], v151 offset:20480
	s_waitcnt lgkmcnt(9)
	v_mfma_f32_16x16x32_bf16 v[28:31], v[84:87], v[124:127], v[28:31]
	ds_read_b128 v[76:79], v151 offset:22528
	s_waitcnt lgkmcnt(9)
	v_mfma_f32_16x16x32_bf16 v[32:35], v[88:91], v[112:115], v[32:35]
	s_waitcnt lgkmcnt(9)
	v_mfma_f32_16x16x32_bf16 v[36:39], v[88:91], v[116:119], v[36:39]
	s_waitcnt lgkmcnt(9)
	v_mfma_f32_16x16x32_bf16 v[40:43], v[88:91], v[120:123], v[40:43]
	s_waitcnt lgkmcnt(9)
	v_mfma_f32_16x16x32_bf16 v[44:47], v[88:91], v[124:127], v[44:47]
	s_waitcnt lgkmcnt(8)
	v_mfma_f32_16x16x32_bf16 v[48:51], v[92:95], v[112:115], v[48:51]
	s_waitcnt lgkmcnt(8)
	v_mfma_f32_16x16x32_bf16 v[52:55], v[92:95], v[116:119], v[52:55]
	s_waitcnt lgkmcnt(8)
	v_mfma_f32_16x16x32_bf16 v[56:59], v[92:95], v[120:123], v[56:59]
	s_waitcnt lgkmcnt(8)
	v_mfma_f32_16x16x32_bf16 v[60:63], v[92:95], v[124:127], v[60:63]
	s_waitcnt lgkmcnt(6)
	v_mfma_f32_16x16x32_bf16 v[160:163], v[64:67], v[96:99], v[160:163]
	ds_read_b128 v[80:83], v220 offset:16384
	s_waitcnt lgkmcnt(6)
	v_mfma_f32_16x16x32_bf16 v[164:167], v[64:67], v[100:103], v[164:167]
	ds_read_b128 v[112:115], v224 offset:32768
	s_waitcnt lgkmcnt(6)
	v_mfma_f32_16x16x32_bf16 v[168:171], v[64:67], v[104:107], v[168:171]
	ds_read_b128 v[116:119], v224 offset:34816
	s_waitcnt lgkmcnt(6)
	v_mfma_f32_16x16x32_bf16 v[172:175], v[64:67], v[108:111], v[172:175]
	ds_read_b128 v[120:123], v224 offset:36864
	s_waitcnt lgkmcnt(6)
	v_mfma_f32_16x16x32_bf16 v[176:179], v[68:71], v[96:99], v[176:179]
	ds_read_b128 v[124:127], v224 offset:38912
	s_waitcnt lgkmcnt(7)
	v_mfma_f32_16x16x32_bf16 v[180:183], v[68:71], v[100:103], v[180:183]
	ds_read_b128 v[84:87], v220 offset:18432
	s_waitcnt lgkmcnt(8)
	v_mfma_f32_16x16x32_bf16 v[184:187], v[68:71], v[104:107], v[184:187]
	ds_read_b128 v[88:91], v220 offset:20480
	s_waitcnt lgkmcnt(9)
	v_mfma_f32_16x16x32_bf16 v[188:191], v[68:71], v[108:111], v[188:191]
	ds_read_b128 v[92:95], v220 offset:22528
	s_waitcnt lgkmcnt(9)
	v_mfma_f32_16x16x32_bf16 v[192:195], v[72:75], v[96:99], v[192:195]
	s_waitcnt lgkmcnt(9)
	v_mfma_f32_16x16x32_bf16 v[196:199], v[72:75], v[100:103], v[196:199]
	s_waitcnt lgkmcnt(9)
	v_mfma_f32_16x16x32_bf16 v[200:203], v[72:75], v[104:107], v[200:203]
	s_waitcnt lgkmcnt(9)
	v_mfma_f32_16x16x32_bf16 v[204:207], v[72:75], v[108:111], v[204:207]
	s_waitcnt vmcnt(0) lgkmcnt(0)
	s_barrier
	s_add_u32 m0, s38, 16384
	s_nop 0
	global_load_lds_dwordx4 v226, s[100:101]
	s_waitcnt lgkmcnt(8)
	v_mfma_f32_16x16x32_bf16 v[208:211], v[76:79], v[96:99], v[208:211]
	s_add_u32 m0, s38, 20480
	s_nop 0
	global_load_lds_dwordx4 v228, s[100:101]
	s_waitcnt lgkmcnt(8)
	v_mfma_f32_16x16x32_bf16 v[212:215], v[76:79], v[100:103], v[212:215]
	s_add_u32 m0, s38, 24576
	s_nop 0
	global_load_lds_dwordx4 v244, s[100:101]
	s_waitcnt lgkmcnt(8)
	v_mfma_f32_16x16x32_bf16 v[216:219], v[76:79], v[104:107], v[216:219]
	s_add_u32 m0, s38, 28672
	s_nop 0
	global_load_lds_dwordx4 v245, s[100:101]
	s_add_u32 s100, s100, 128
	s_addc_u32 s101, s101, 0
	s_waitcnt lgkmcnt(8)
	v_mfma_f32_16x16x32_bf16 v[230:233], v[76:79], v[108:111], v[230:233]
	s_add_u32 m0, s38, 32768
	s_nop 0
	global_load_lds_dwordx4 v226, s[4:5]
	s_waitcnt lgkmcnt(6)
	v_mfma_f32_16x16x32_bf16 v[160:163], v[80:83], v[112:115], v[160:163]
	ds_read_b128 v[64:67], v151 offset:0
	s_add_u32 m0, s38, 36864
	s_nop 0
	global_load_lds_dwordx4 v228, s[4:5]
	s_waitcnt lgkmcnt(6)
	v_mfma_f32_16x16x32_bf16 v[164:167], v[80:83], v[116:119], v[164:167]
	ds_read_b128 v[96:99], v222 offset:49152
	s_add_u32 m0, s38, 40960
	s_nop 0
	global_load_lds_dwordx4 v244, s[4:5]
	s_waitcnt lgkmcnt(6)
	v_mfma_f32_16x16x32_bf16 v[168:171], v[80:83], v[120:123], v[168:171]
	ds_read_b128 v[100:103], v222 offset:51200
	s_add_u32 m0, s38, 45056
	s_nop 0
	global_load_lds_dwordx4 v245, s[4:5]
	s_add_u32 s4, s4, 128
	s_addc_u32 s5, s5, 0
	s_waitcnt lgkmcnt(6)
	v_mfma_f32_16x16x32_bf16 v[172:175], v[80:83], v[124:127], v[172:175]
	ds_read_b128 v[104:107], v222 offset:53248
	s_waitcnt lgkmcnt(6)
	v_mfma_f32_16x16x32_bf16 v[176:179], v[84:87], v[112:115], v[176:179]
	ds_read_b128 v[108:111], v222 offset:55296
	s_waitcnt lgkmcnt(7)
	v_mfma_f32_16x16x32_bf16 v[180:183], v[84:87], v[116:119], v[180:183]
	ds_read_b128 v[68:71], v151 offset:2048
	s_waitcnt lgkmcnt(8)
	v_mfma_f32_16x16x32_bf16 v[184:187], v[84:87], v[120:123], v[184:187]
	ds_read_b128 v[72:75], v151 offset:4096
	s_waitcnt lgkmcnt(9)
	v_mfma_f32_16x16x32_bf16 v[188:191], v[84:87], v[124:127], v[188:191]
	ds_read_b128 v[76:79], v151 offset:6144
	s_waitcnt lgkmcnt(9)
	v_mfma_f32_16x16x32_bf16 v[192:195], v[88:91], v[112:115], v[192:195]
	s_waitcnt lgkmcnt(9)
	v_mfma_f32_16x16x32_bf16 v[196:199], v[88:91], v[116:119], v[196:199]
	s_waitcnt lgkmcnt(9)
	v_mfma_f32_16x16x32_bf16 v[200:203], v[88:91], v[120:123], v[200:203]
	s_waitcnt lgkmcnt(9)
	v_mfma_f32_16x16x32_bf16 v[204:207], v[88:91], v[124:127], v[204:207]
	s_waitcnt lgkmcnt(8)
	v_mfma_f32_16x16x32_bf16 v[208:211], v[92:95], v[112:115], v[208:211]
	s_waitcnt lgkmcnt(8)
	v_mfma_f32_16x16x32_bf16 v[212:215], v[92:95], v[116:119], v[212:215]
	s_waitcnt lgkmcnt(8)
	v_mfma_f32_16x16x32_bf16 v[216:219], v[92:95], v[120:123], v[216:219]
	s_waitcnt lgkmcnt(8)
	v_mfma_f32_16x16x32_bf16 v[230:233], v[92:95], v[124:127], v[230:233]
	s_waitcnt lgkmcnt(6)
	v_mfma_f32_16x16x32_bf16 v[0:3], v[64:67], v[96:99], v[0:3]
	ds_read_b128 v[80:83], v220 offset:0
	s_waitcnt lgkmcnt(6)
	v_mfma_f32_16x16x32_bf16 v[4:7], v[64:67], v[100:103], v[4:7]
	ds_read_b128 v[112:115], v224 offset:49152
	s_waitcnt lgkmcnt(6)
	v_mfma_f32_16x16x32_bf16 v[8:11], v[64:67], v[104:107], v[8:11]
	ds_read_b128 v[116:119], v224 offset:51200
	s_waitcnt lgkmcnt(6)
	v_mfma_f32_16x16x32_bf16 v[12:15], v[64:67], v[108:111], v[12:15]
	ds_read_b128 v[120:123], v224 offset:53248
	s_waitcnt lgkmcnt(6)
	v_mfma_f32_16x16x32_bf16 v[16:19], v[68:71], v[96:99], v[16:19]
	ds_read_b128 v[124:127], v224 offset:55296
	s_waitcnt lgkmcnt(7)
	v_mfma_f32_16x16x32_bf16 v[20:23], v[68:71], v[100:103], v[20:23]
	ds_read_b128 v[84:87], v220 offset:2048
	s_waitcnt lgkmcnt(8)
	v_mfma_f32_16x16x32_bf16 v[24:27], v[68:71], v[104:107], v[24:27]
	ds_read_b128 v[88:91], v220 offset:4096
	s_waitcnt lgkmcnt(9)
	v_mfma_f32_16x16x32_bf16 v[28:31], v[68:71], v[108:111], v[28:31]
	ds_read_b128 v[92:95], v220 offset:6144
	s_waitcnt lgkmcnt(9)
	v_mfma_f32_16x16x32_bf16 v[32:35], v[72:75], v[96:99], v[32:35]
	s_waitcnt lgkmcnt(9)
	v_mfma_f32_16x16x32_bf16 v[36:39], v[72:75], v[100:103], v[36:39]
	s_waitcnt lgkmcnt(9)
	v_mfma_f32_16x16x32_bf16 v[40:43], v[72:75], v[104:107], v[40:43]
	s_waitcnt lgkmcnt(9)
	v_mfma_f32_16x16x32_bf16 v[44:47], v[72:75], v[108:111], v[44:47]
	s_waitcnt vmcnt(4) lgkmcnt(0)
	s_barrier
	s_add_u32 m0, s38, 0
	s_nop 0
	global_load_lds_dwordx4 v226, s[98:99]
	s_waitcnt lgkmcnt(8)
	v_mfma_f32_16x16x32_bf16 v[48:51], v[76:79], v[96:99], v[48:51]
	s_add_u32 m0, s38, 4096
	s_nop 0
	global_load_lds_dwordx4 v228, s[98:99]
	s_waitcnt lgkmcnt(8)
	v_mfma_f32_16x16x32_bf16 v[52:55], v[76:79], v[100:103], v[52:55]
	s_add_u32 m0, s38, 8192
	s_nop 0
	global_load_lds_dwordx4 v244, s[98:99]
	s_waitcnt lgkmcnt(8)
	v_mfma_f32_16x16x32_bf16 v[56:59], v[76:79], v[104:107], v[56:59]
	s_add_u32 m0, s38, 12288
	s_nop 0
	global_load_lds_dwordx4 v245, s[98:99]
	s_add_u32 s98, s98, 128
	s_addc_u32 s99, s99, 0
	s_waitcnt lgkmcnt(8)
	v_mfma_f32_16x16x32_bf16 v[60:63], v[76:79], v[108:111], v[60:63]
	s_waitcnt lgkmcnt(6)
	v_mfma_f32_16x16x32_bf16 v[0:3], v[80:83], v[112:115], v[0:3]
	ds_read_b128 v[64:67], v151 offset:16384
	s_waitcnt lgkmcnt(6)
	v_mfma_f32_16x16x32_bf16 v[4:7], v[80:83], v[116:119], v[4:7]
	ds_read_b128 v[96:99], v222 offset:49152
	s_waitcnt lgkmcnt(6)
	v_mfma_f32_16x16x32_bf16 v[8:11], v[80:83], v[120:123], v[8:11]
	ds_read_b128 v[100:103], v222 offset:51200
	s_waitcnt lgkmcnt(6)
	v_mfma_f32_16x16x32_bf16 v[12:15], v[80:83], v[124:127], v[12:15]
	ds_read_b128 v[104:107], v222 offset:53248
	s_waitcnt lgkmcnt(6)
	v_mfma_f32_16x16x32_bf16 v[16:19], v[84:87], v[112:115], v[16:19]
	ds_read_b128 v[108:111], v222 offset:55296
	s_waitcnt lgkmcnt(7)
	v_mfma_f32_16x16x32_bf16 v[20:23], v[84:87], v[116:119], v[20:23]
	ds_read_b128 v[68:71], v151 offset:18432
	s_waitcnt lgkmcnt(8)
	v_mfma_f32_16x16x32_bf16 v[24:27], v[84:87], v[120:123], v[24:27]
	ds_read_b128 v[72:75], v151 offset:20480
	s_waitcnt lgkmcnt(9)
	v_mfma_f32_16x16x32_bf16 v[28:31], v[84:87], v[124:127], v[28:31]
	ds_read_b128 v[76:79], v151 offset:22528
	s_waitcnt lgkmcnt(9)
	v_mfma_f32_16x16x32_bf16 v[32:35], v[88:91], v[112:115], v[32:35]
	s_waitcnt lgkmcnt(9)
	v_mfma_f32_16x16x32_bf16 v[36:39], v[88:91], v[116:119], v[36:39]
	s_waitcnt lgkmcnt(9)
	v_mfma_f32_16x16x32_bf16 v[40:43], v[88:91], v[120:123], v[40:43]
	s_waitcnt lgkmcnt(9)
	v_mfma_f32_16x16x32_bf16 v[44:47], v[88:91], v[124:127], v[44:47]
	s_waitcnt lgkmcnt(8)
	v_mfma_f32_16x16x32_bf16 v[48:51], v[92:95], v[112:115], v[48:51]
	s_waitcnt lgkmcnt(8)
	v_mfma_f32_16x16x32_bf16 v[52:55], v[92:95], v[116:119], v[52:55]
	s_waitcnt lgkmcnt(8)
	v_mfma_f32_16x16x32_bf16 v[56:59], v[92:95], v[120:123], v[56:59]
	s_waitcnt lgkmcnt(8)
	v_mfma_f32_16x16x32_bf16 v[60:63], v[92:95], v[124:127], v[60:63]
	s_waitcnt lgkmcnt(6)
	v_mfma_f32_16x16x32_bf16 v[160:163], v[64:67], v[96:99], v[160:163]
	ds_read_b128 v[80:83], v220 offset:16384
	s_waitcnt lgkmcnt(6)
	v_mfma_f32_16x16x32_bf16 v[164:167], v[64:67], v[100:103], v[164:167]
	ds_read_b128 v[112:115], v224 offset:49152
	s_waitcnt lgkmcnt(6)
	v_mfma_f32_16x16x32_bf16 v[168:171], v[64:67], v[104:107], v[168:171]
	ds_read_b128 v[116:119], v224 offset:51200
	s_waitcnt lgkmcnt(6)
	v_mfma_f32_16x16x32_bf16 v[172:175], v[64:67], v[108:111], v[172:175]
	ds_read_b128 v[120:123], v224 offset:53248
	s_waitcnt lgkmcnt(6)
	v_mfma_f32_16x16x32_bf16 v[176:179], v[68:71], v[96:99], v[176:179]
	ds_read_b128 v[124:127], v224 offset:55296
	s_waitcnt lgkmcnt(7)
	v_mfma_f32_16x16x32_bf16 v[180:183], v[68:71], v[100:103], v[180:183]
	ds_read_b128 v[84:87], v220 offset:18432
	s_waitcnt lgkmcnt(8)
	v_mfma_f32_16x16x32_bf16 v[184:187], v[68:71], v[104:107], v[184:187]
	ds_read_b128 v[88:91], v220 offset:20480
	s_waitcnt lgkmcnt(9)
	v_mfma_f32_16x16x32_bf16 v[188:191], v[68:71], v[108:111], v[188:191]
	ds_read_b128 v[92:95], v220 offset:22528
	s_waitcnt lgkmcnt(9)
	v_mfma_f32_16x16x32_bf16 v[192:195], v[72:75], v[96:99], v[192:195]
	s_waitcnt lgkmcnt(9)
	v_mfma_f32_16x16x32_bf16 v[196:199], v[72:75], v[100:103], v[196:199]
	s_waitcnt lgkmcnt(9)
	v_mfma_f32_16x16x32_bf16 v[200:203], v[72:75], v[104:107], v[200:203]
	s_waitcnt lgkmcnt(9)
	v_mfma_f32_16x16x32_bf16 v[204:207], v[72:75], v[108:111], v[204:207]
	s_waitcnt vmcnt(0) lgkmcnt(0)
	s_barrier
	s_add_u32 m0, s38, 16384
	s_nop 0
	global_load_lds_dwordx4 v226, s[100:101]
	s_waitcnt lgkmcnt(8)
	v_mfma_f32_16x16x32_bf16 v[208:211], v[76:79], v[96:99], v[208:211]
	s_add_u32 m0, s38, 20480
	s_nop 0
	global_load_lds_dwordx4 v228, s[100:101]
	s_waitcnt lgkmcnt(8)
	v_mfma_f32_16x16x32_bf16 v[212:215], v[76:79], v[100:103], v[212:215]
	s_add_u32 m0, s38, 24576
	s_nop 0
	global_load_lds_dwordx4 v244, s[100:101]
	s_waitcnt lgkmcnt(8)
	v_mfma_f32_16x16x32_bf16 v[216:219], v[76:79], v[104:107], v[216:219]
	s_add_u32 m0, s38, 28672
	s_nop 0
	global_load_lds_dwordx4 v245, s[100:101]
	s_add_u32 s100, s100, 128
	s_addc_u32 s101, s101, 0
	s_waitcnt lgkmcnt(8)
	v_mfma_f32_16x16x32_bf16 v[230:233], v[76:79], v[108:111], v[230:233]
	s_add_u32 m0, s38, 49152
	s_nop 0
	global_load_lds_dwordx4 v226, s[4:5]
	s_waitcnt lgkmcnt(6)
	v_mfma_f32_16x16x32_bf16 v[160:163], v[80:83], v[112:115], v[160:163]
	ds_read_b128 v[64:67], v151 offset:0
	s_add_u32 m0, s38, 53248
	s_nop 0
	global_load_lds_dwordx4 v228, s[4:5]
	s_waitcnt lgkmcnt(6)
	v_mfma_f32_16x16x32_bf16 v[164:167], v[80:83], v[116:119], v[164:167]
	ds_read_b128 v[96:99], v222 offset:32768
	s_add_u32 m0, s38, 57344
	s_nop 0
	global_load_lds_dwordx4 v244, s[4:5]
	s_waitcnt lgkmcnt(6)
	v_mfma_f32_16x16x32_bf16 v[168:171], v[80:83], v[120:123], v[168:171]
	ds_read_b128 v[100:103], v222 offset:34816
	s_add_u32 m0, s38, 61440
	s_nop 0
	global_load_lds_dwordx4 v245, s[4:5]
	s_add_u32 s4, s4, 128
	s_addc_u32 s5, s5, 0
	s_waitcnt lgkmcnt(6)
	v_mfma_f32_16x16x32_bf16 v[172:175], v[80:83], v[124:127], v[172:175]
	ds_read_b128 v[104:107], v222 offset:36864
	s_waitcnt lgkmcnt(6)
	v_mfma_f32_16x16x32_bf16 v[176:179], v[84:87], v[112:115], v[176:179]
	ds_read_b128 v[108:111], v222 offset:38912
	s_waitcnt lgkmcnt(7)
	v_mfma_f32_16x16x32_bf16 v[180:183], v[84:87], v[116:119], v[180:183]
	ds_read_b128 v[68:71], v151 offset:2048
	s_waitcnt lgkmcnt(8)
	v_mfma_f32_16x16x32_bf16 v[184:187], v[84:87], v[120:123], v[184:187]
	ds_read_b128 v[72:75], v151 offset:4096
	s_waitcnt lgkmcnt(9)
	v_mfma_f32_16x16x32_bf16 v[188:191], v[84:87], v[124:127], v[188:191]
	ds_read_b128 v[76:79], v151 offset:6144
	s_waitcnt lgkmcnt(9)
	v_mfma_f32_16x16x32_bf16 v[192:195], v[88:91], v[112:115], v[192:195]
	s_waitcnt lgkmcnt(9)
	v_mfma_f32_16x16x32_bf16 v[196:199], v[88:91], v[116:119], v[196:199]
	s_waitcnt lgkmcnt(9)
	v_mfma_f32_16x16x32_bf16 v[200:203], v[88:91], v[120:123], v[200:203]
	s_waitcnt lgkmcnt(9)
	v_mfma_f32_16x16x32_bf16 v[204:207], v[88:91], v[124:127], v[204:207]
	s_waitcnt lgkmcnt(8)
	v_mfma_f32_16x16x32_bf16 v[208:211], v[92:95], v[112:115], v[208:211]
	s_waitcnt lgkmcnt(8)
	v_mfma_f32_16x16x32_bf16 v[212:215], v[92:95], v[116:119], v[212:215]
	s_waitcnt lgkmcnt(8)
	v_mfma_f32_16x16x32_bf16 v[216:219], v[92:95], v[120:123], v[216:219]
	s_waitcnt lgkmcnt(8)
	v_mfma_f32_16x16x32_bf16 v[230:233], v[92:95], v[124:127], v[230:233]
	s_waitcnt lgkmcnt(6)
	v_mfma_f32_16x16x32_bf16 v[0:3], v[64:67], v[96:99], v[0:3]
	ds_read_b128 v[80:83], v220 offset:0
	s_waitcnt lgkmcnt(6)
	v_mfma_f32_16x16x32_bf16 v[4:7], v[64:67], v[100:103], v[4:7]
	ds_read_b128 v[112:115], v224 offset:32768
	s_waitcnt lgkmcnt(6)
	v_mfma_f32_16x16x32_bf16 v[8:11], v[64:67], v[104:107], v[8:11]
	ds_read_b128 v[116:119], v224 offset:34816
	s_waitcnt lgkmcnt(6)
	v_mfma_f32_16x16x32_bf16 v[12:15], v[64:67], v[108:111], v[12:15]
	ds_read_b128 v[120:123], v224 offset:36864
	s_waitcnt lgkmcnt(6)
	v_mfma_f32_16x16x32_bf16 v[16:19], v[68:71], v[96:99], v[16:19]
	ds_read_b128 v[124:127], v224 offset:38912
	s_waitcnt lgkmcnt(7)
	v_mfma_f32_16x16x32_bf16 v[20:23], v[68:71], v[100:103], v[20:23]
	ds_read_b128 v[84:87], v220 offset:2048
	s_waitcnt lgkmcnt(8)
	v_mfma_f32_16x16x32_bf16 v[24:27], v[68:71], v[104:107], v[24:27]
	ds_read_b128 v[88:91], v220 offset:4096
	s_waitcnt lgkmcnt(9)
	v_mfma_f32_16x16x32_bf16 v[28:31], v[68:71], v[108:111], v[28:31]
	ds_read_b128 v[92:95], v220 offset:6144
	s_waitcnt lgkmcnt(9)
	v_mfma_f32_16x16x32_bf16 v[32:35], v[72:75], v[96:99], v[32:35]
	s_waitcnt lgkmcnt(9)
	v_mfma_f32_16x16x32_bf16 v[36:39], v[72:75], v[100:103], v[36:39]
	s_waitcnt lgkmcnt(9)
	v_mfma_f32_16x16x32_bf16 v[40:43], v[72:75], v[104:107], v[40:43]
	s_waitcnt lgkmcnt(9)
	v_mfma_f32_16x16x32_bf16 v[44:47], v[72:75], v[108:111], v[44:47]
	s_waitcnt vmcnt(4) lgkmcnt(0)
	s_barrier
	s_add_u32 m0, s38, 0
	s_nop 0
	global_load_lds_dwordx4 v226, s[98:99]
	s_waitcnt lgkmcnt(8)
	v_mfma_f32_16x16x32_bf16 v[48:51], v[76:79], v[96:99], v[48:51]
	s_add_u32 m0, s38, 4096
	s_nop 0
	global_load_lds_dwordx4 v228, s[98:99]
	s_waitcnt lgkmcnt(8)
	v_mfma_f32_16x16x32_bf16 v[52:55], v[76:79], v[100:103], v[52:55]
	s_add_u32 m0, s38, 8192
	s_nop 0
	global_load_lds_dwordx4 v244, s[98:99]
	s_waitcnt lgkmcnt(8)
	v_mfma_f32_16x16x32_bf16 v[56:59], v[76:79], v[104:107], v[56:59]
	s_add_u32 m0, s38, 12288
	s_nop 0
	global_load_lds_dwordx4 v245, s[98:99]
	s_add_u32 s98, s98, 128
	s_addc_u32 s99, s99, 0
	s_waitcnt lgkmcnt(8)
	v_mfma_f32_16x16x32_bf16 v[60:63], v[76:79], v[108:111], v[60:63]
	s_waitcnt lgkmcnt(6)
	v_mfma_f32_16x16x32_bf16 v[0:3], v[80:83], v[112:115], v[0:3]
	ds_read_b128 v[64:67], v151 offset:16384
	s_waitcnt lgkmcnt(6)
	v_mfma_f32_16x16x32_bf16 v[4:7], v[80:83], v[116:119], v[4:7]
	ds_read_b128 v[96:99], v222 offset:32768
	s_waitcnt lgkmcnt(6)
	v_mfma_f32_16x16x32_bf16 v[8:11], v[80:83], v[120:123], v[8:11]
	ds_read_b128 v[100:103], v222 offset:34816
	s_waitcnt lgkmcnt(6)
	v_mfma_f32_16x16x32_bf16 v[12:15], v[80:83], v[124:127], v[12:15]
	ds_read_b128 v[104:107], v222 offset:36864
	s_waitcnt lgkmcnt(6)
	v_mfma_f32_16x16x32_bf16 v[16:19], v[84:87], v[112:115], v[16:19]
	ds_read_b128 v[108:111], v222 offset:38912
	s_waitcnt lgkmcnt(7)
	v_mfma_f32_16x16x32_bf16 v[20:23], v[84:87], v[116:119], v[20:23]
	ds_read_b128 v[68:71], v151 offset:18432
	s_waitcnt lgkmcnt(8)
	v_mfma_f32_16x16x32_bf16 v[24:27], v[84:87], v[120:123], v[24:27]
	ds_read_b128 v[72:75], v151 offset:20480
	s_waitcnt lgkmcnt(9)
	v_mfma_f32_16x16x32_bf16 v[28:31], v[84:87], v[124:127], v[28:31]
	ds_read_b128 v[76:79], v151 offset:22528
	s_waitcnt lgkmcnt(9)
	v_mfma_f32_16x16x32_bf16 v[32:35], v[88:91], v[112:115], v[32:35]
	s_waitcnt lgkmcnt(9)
	v_mfma_f32_16x16x32_bf16 v[36:39], v[88:91], v[116:119], v[36:39]
	s_waitcnt lgkmcnt(9)
	v_mfma_f32_16x16x32_bf16 v[40:43], v[88:91], v[120:123], v[40:43]
	s_waitcnt lgkmcnt(9)
	v_mfma_f32_16x16x32_bf16 v[44:47], v[88:91], v[124:127], v[44:47]
	s_waitcnt lgkmcnt(8)
	v_mfma_f32_16x16x32_bf16 v[48:51], v[92:95], v[112:115], v[48:51]
	s_waitcnt lgkmcnt(8)
	v_mfma_f32_16x16x32_bf16 v[52:55], v[92:95], v[116:119], v[52:55]
	s_waitcnt lgkmcnt(8)
	v_mfma_f32_16x16x32_bf16 v[56:59], v[92:95], v[120:123], v[56:59]
	s_waitcnt lgkmcnt(8)
	v_mfma_f32_16x16x32_bf16 v[60:63], v[92:95], v[124:127], v[60:63]
	s_waitcnt lgkmcnt(6)
	v_mfma_f32_16x16x32_bf16 v[160:163], v[64:67], v[96:99], v[160:163]
	ds_read_b128 v[80:83], v220 offset:16384
	s_waitcnt lgkmcnt(6)
	v_mfma_f32_16x16x32_bf16 v[164:167], v[64:67], v[100:103], v[164:167]
	ds_read_b128 v[112:115], v224 offset:32768
	s_waitcnt lgkmcnt(6)
	v_mfma_f32_16x16x32_bf16 v[168:171], v[64:67], v[104:107], v[168:171]
	ds_read_b128 v[116:119], v224 offset:34816
	s_waitcnt lgkmcnt(6)
	v_mfma_f32_16x16x32_bf16 v[172:175], v[64:67], v[108:111], v[172:175]
	ds_read_b128 v[120:123], v224 offset:36864
	s_waitcnt lgkmcnt(6)
	v_mfma_f32_16x16x32_bf16 v[176:179], v[68:71], v[96:99], v[176:179]
	ds_read_b128 v[124:127], v224 offset:38912
	s_waitcnt lgkmcnt(7)
	v_mfma_f32_16x16x32_bf16 v[180:183], v[68:71], v[100:103], v[180:183]
	ds_read_b128 v[84:87], v220 offset:18432
	s_waitcnt lgkmcnt(8)
	v_mfma_f32_16x16x32_bf16 v[184:187], v[68:71], v[104:107], v[184:187]
	ds_read_b128 v[88:91], v220 offset:20480
	s_waitcnt lgkmcnt(9)
	v_mfma_f32_16x16x32_bf16 v[188:191], v[68:71], v[108:111], v[188:191]
	ds_read_b128 v[92:95], v220 offset:22528
	s_waitcnt lgkmcnt(9)
	v_mfma_f32_16x16x32_bf16 v[192:195], v[72:75], v[96:99], v[192:195]
	s_waitcnt lgkmcnt(9)
	v_mfma_f32_16x16x32_bf16 v[196:199], v[72:75], v[100:103], v[196:199]
	s_waitcnt lgkmcnt(9)
	v_mfma_f32_16x16x32_bf16 v[200:203], v[72:75], v[104:107], v[200:203]
	s_waitcnt lgkmcnt(9)
	v_mfma_f32_16x16x32_bf16 v[204:207], v[72:75], v[108:111], v[204:207]
	s_waitcnt vmcnt(0) lgkmcnt(0)
	s_barrier
	s_add_u32 m0, s38, 16384
	s_nop 0
	global_load_lds_dwordx4 v226, s[100:101]
	s_waitcnt lgkmcnt(8)
	v_mfma_f32_16x16x32_bf16 v[208:211], v[76:79], v[96:99], v[208:211]
	s_add_u32 m0, s38, 20480
	s_nop 0
	global_load_lds_dwordx4 v228, s[100:101]
	s_waitcnt lgkmcnt(8)
	v_mfma_f32_16x16x32_bf16 v[212:215], v[76:79], v[100:103], v[212:215]
	s_add_u32 m0, s38, 24576
	s_nop 0
	global_load_lds_dwordx4 v244, s[100:101]
	s_waitcnt lgkmcnt(8)
	v_mfma_f32_16x16x32_bf16 v[216:219], v[76:79], v[104:107], v[216:219]
	s_add_u32 m0, s38, 28672
	s_nop 0
	global_load_lds_dwordx4 v245, s[100:101]
	s_add_u32 s100, s100, 128
	s_addc_u32 s101, s101, 0
	s_waitcnt lgkmcnt(8)
	v_mfma_f32_16x16x32_bf16 v[230:233], v[76:79], v[108:111], v[230:233]
	s_add_u32 m0, s38, 32768
	s_nop 0
	global_load_lds_dwordx4 v226, s[4:5]
	s_waitcnt lgkmcnt(6)
	v_mfma_f32_16x16x32_bf16 v[160:163], v[80:83], v[112:115], v[160:163]
	ds_read_b128 v[64:67], v151 offset:0
	s_add_u32 m0, s38, 36864
	s_nop 0
	global_load_lds_dwordx4 v228, s[4:5]
	s_waitcnt lgkmcnt(6)
	v_mfma_f32_16x16x32_bf16 v[164:167], v[80:83], v[116:119], v[164:167]
	ds_read_b128 v[96:99], v222 offset:49152
	s_add_u32 m0, s38, 40960
	s_nop 0
	global_load_lds_dwordx4 v244, s[4:5]
	s_waitcnt lgkmcnt(6)
	v_mfma_f32_16x16x32_bf16 v[168:171], v[80:83], v[120:123], v[168:171]
	ds_read_b128 v[100:103], v222 offset:51200
	s_add_u32 m0, s38, 45056
	s_nop 0
	global_load_lds_dwordx4 v245, s[4:5]
	s_add_u32 s4, s4, 128
	s_addc_u32 s5, s5, 0
	s_waitcnt lgkmcnt(6)
	v_mfma_f32_16x16x32_bf16 v[172:175], v[80:83], v[124:127], v[172:175]
	ds_read_b128 v[104:107], v222 offset:53248
	s_waitcnt lgkmcnt(6)
	v_mfma_f32_16x16x32_bf16 v[176:179], v[84:87], v[112:115], v[176:179]
	ds_read_b128 v[108:111], v222 offset:55296
	s_waitcnt lgkmcnt(7)
	v_mfma_f32_16x16x32_bf16 v[180:183], v[84:87], v[116:119], v[180:183]
	ds_read_b128 v[68:71], v151 offset:2048
	s_waitcnt lgkmcnt(8)
	v_mfma_f32_16x16x32_bf16 v[184:187], v[84:87], v[120:123], v[184:187]
	ds_read_b128 v[72:75], v151 offset:4096
	s_waitcnt lgkmcnt(9)
	v_mfma_f32_16x16x32_bf16 v[188:191], v[84:87], v[124:127], v[188:191]
	ds_read_b128 v[76:79], v151 offset:6144
	s_waitcnt lgkmcnt(9)
	v_mfma_f32_16x16x32_bf16 v[192:195], v[88:91], v[112:115], v[192:195]
	s_waitcnt lgkmcnt(9)
	v_mfma_f32_16x16x32_bf16 v[196:199], v[88:91], v[116:119], v[196:199]
	s_waitcnt lgkmcnt(9)
	v_mfma_f32_16x16x32_bf16 v[200:203], v[88:91], v[120:123], v[200:203]
	s_waitcnt lgkmcnt(9)
	v_mfma_f32_16x16x32_bf16 v[204:207], v[88:91], v[124:127], v[204:207]
	s_waitcnt lgkmcnt(8)
	v_mfma_f32_16x16x32_bf16 v[208:211], v[92:95], v[112:115], v[208:211]
	s_waitcnt lgkmcnt(8)
	v_mfma_f32_16x16x32_bf16 v[212:215], v[92:95], v[116:119], v[212:215]
	s_waitcnt lgkmcnt(8)
	v_mfma_f32_16x16x32_bf16 v[216:219], v[92:95], v[120:123], v[216:219]
	s_waitcnt lgkmcnt(8)
	v_mfma_f32_16x16x32_bf16 v[230:233], v[92:95], v[124:127], v[230:233]
	s_waitcnt lgkmcnt(6)
	v_mfma_f32_16x16x32_bf16 v[0:3], v[64:67], v[96:99], v[0:3]
	ds_read_b128 v[80:83], v220 offset:0
	s_waitcnt lgkmcnt(6)
	v_mfma_f32_16x16x32_bf16 v[4:7], v[64:67], v[100:103], v[4:7]
	ds_read_b128 v[112:115], v224 offset:49152
	s_waitcnt lgkmcnt(6)
	v_mfma_f32_16x16x32_bf16 v[8:11], v[64:67], v[104:107], v[8:11]
	ds_read_b128 v[116:119], v224 offset:51200
	s_waitcnt lgkmcnt(6)
	v_mfma_f32_16x16x32_bf16 v[12:15], v[64:67], v[108:111], v[12:15]
	ds_read_b128 v[120:123], v224 offset:53248
	s_waitcnt lgkmcnt(6)
	v_mfma_f32_16x16x32_bf16 v[16:19], v[68:71], v[96:99], v[16:19]
	ds_read_b128 v[124:127], v224 offset:55296
	s_waitcnt lgkmcnt(7)
	v_mfma_f32_16x16x32_bf16 v[20:23], v[68:71], v[100:103], v[20:23]
	ds_read_b128 v[84:87], v220 offset:2048
	s_waitcnt lgkmcnt(8)
	v_mfma_f32_16x16x32_bf16 v[24:27], v[68:71], v[104:107], v[24:27]
	ds_read_b128 v[88:91], v220 offset:4096
	s_waitcnt lgkmcnt(9)
	v_mfma_f32_16x16x32_bf16 v[28:31], v[68:71], v[108:111], v[28:31]
	ds_read_b128 v[92:95], v220 offset:6144
	s_waitcnt lgkmcnt(9)
	v_mfma_f32_16x16x32_bf16 v[32:35], v[72:75], v[96:99], v[32:35]
	s_waitcnt lgkmcnt(9)
	v_mfma_f32_16x16x32_bf16 v[36:39], v[72:75], v[100:103], v[36:39]
	s_waitcnt lgkmcnt(9)
	v_mfma_f32_16x16x32_bf16 v[40:43], v[72:75], v[104:107], v[40:43]
	s_waitcnt lgkmcnt(9)
	v_mfma_f32_16x16x32_bf16 v[44:47], v[72:75], v[108:111], v[44:47]
	s_waitcnt vmcnt(4) lgkmcnt(0)
	s_barrier
	s_add_u32 m0, s38, 0
	s_nop 0
	global_load_lds_dwordx4 v226, s[98:99]
	s_waitcnt lgkmcnt(8)
	v_mfma_f32_16x16x32_bf16 v[48:51], v[76:79], v[96:99], v[48:51]
	s_add_u32 m0, s38, 4096
	s_nop 0
	global_load_lds_dwordx4 v228, s[98:99]
	s_waitcnt lgkmcnt(8)
	v_mfma_f32_16x16x32_bf16 v[52:55], v[76:79], v[100:103], v[52:55]
	s_add_u32 m0, s38, 8192
	s_nop 0
	global_load_lds_dwordx4 v244, s[98:99]
	s_waitcnt lgkmcnt(8)
	v_mfma_f32_16x16x32_bf16 v[56:59], v[76:79], v[104:107], v[56:59]
	s_add_u32 m0, s38, 12288
	s_nop 0
	global_load_lds_dwordx4 v245, s[98:99]
	s_add_u32 s98, s98, 128
	s_addc_u32 s99, s99, 0
	s_waitcnt lgkmcnt(8)
	v_mfma_f32_16x16x32_bf16 v[60:63], v[76:79], v[108:111], v[60:63]
	s_waitcnt lgkmcnt(6)
	v_mfma_f32_16x16x32_bf16 v[0:3], v[80:83], v[112:115], v[0:3]
	ds_read_b128 v[64:67], v151 offset:16384
	s_waitcnt lgkmcnt(6)
	v_mfma_f32_16x16x32_bf16 v[4:7], v[80:83], v[116:119], v[4:7]
	ds_read_b128 v[96:99], v222 offset:49152
	s_waitcnt lgkmcnt(6)
	v_mfma_f32_16x16x32_bf16 v[8:11], v[80:83], v[120:123], v[8:11]
	ds_read_b128 v[100:103], v222 offset:51200
	s_waitcnt lgkmcnt(6)
	v_mfma_f32_16x16x32_bf16 v[12:15], v[80:83], v[124:127], v[12:15]
	ds_read_b128 v[104:107], v222 offset:53248
	s_waitcnt lgkmcnt(6)
	v_mfma_f32_16x16x32_bf16 v[16:19], v[84:87], v[112:115], v[16:19]
	ds_read_b128 v[108:111], v222 offset:55296
	s_waitcnt lgkmcnt(7)
	v_mfma_f32_16x16x32_bf16 v[20:23], v[84:87], v[116:119], v[20:23]
	ds_read_b128 v[68:71], v151 offset:18432
	s_waitcnt lgkmcnt(8)
	v_mfma_f32_16x16x32_bf16 v[24:27], v[84:87], v[120:123], v[24:27]
	ds_read_b128 v[72:75], v151 offset:20480
	s_waitcnt lgkmcnt(9)
	v_mfma_f32_16x16x32_bf16 v[28:31], v[84:87], v[124:127], v[28:31]
	ds_read_b128 v[76:79], v151 offset:22528
	s_waitcnt lgkmcnt(9)
	v_mfma_f32_16x16x32_bf16 v[32:35], v[88:91], v[112:115], v[32:35]
	s_waitcnt lgkmcnt(9)
	v_mfma_f32_16x16x32_bf16 v[36:39], v[88:91], v[116:119], v[36:39]
	s_waitcnt lgkmcnt(9)
	v_mfma_f32_16x16x32_bf16 v[40:43], v[88:91], v[120:123], v[40:43]
	s_waitcnt lgkmcnt(9)
	v_mfma_f32_16x16x32_bf16 v[44:47], v[88:91], v[124:127], v[44:47]
	s_waitcnt lgkmcnt(8)
	v_mfma_f32_16x16x32_bf16 v[48:51], v[92:95], v[112:115], v[48:51]
	s_waitcnt lgkmcnt(8)
	v_mfma_f32_16x16x32_bf16 v[52:55], v[92:95], v[116:119], v[52:55]
	s_waitcnt lgkmcnt(8)
	v_mfma_f32_16x16x32_bf16 v[56:59], v[92:95], v[120:123], v[56:59]
	s_waitcnt lgkmcnt(8)
	v_mfma_f32_16x16x32_bf16 v[60:63], v[92:95], v[124:127], v[60:63]
	s_waitcnt lgkmcnt(6)
	v_mfma_f32_16x16x32_bf16 v[160:163], v[64:67], v[96:99], v[160:163]
	ds_read_b128 v[80:83], v220 offset:16384
	s_waitcnt lgkmcnt(6)
	v_mfma_f32_16x16x32_bf16 v[164:167], v[64:67], v[100:103], v[164:167]
	ds_read_b128 v[112:115], v224 offset:49152
	s_waitcnt lgkmcnt(6)
	v_mfma_f32_16x16x32_bf16 v[168:171], v[64:67], v[104:107], v[168:171]
	ds_read_b128 v[116:119], v224 offset:51200
	s_waitcnt lgkmcnt(6)
	v_mfma_f32_16x16x32_bf16 v[172:175], v[64:67], v[108:111], v[172:175]
	ds_read_b128 v[120:123], v224 offset:53248
	s_waitcnt lgkmcnt(6)
	v_mfma_f32_16x16x32_bf16 v[176:179], v[68:71], v[96:99], v[176:179]
	ds_read_b128 v[124:127], v224 offset:55296
	s_waitcnt lgkmcnt(7)
	v_mfma_f32_16x16x32_bf16 v[180:183], v[68:71], v[100:103], v[180:183]
	ds_read_b128 v[84:87], v220 offset:18432
	s_waitcnt lgkmcnt(8)
	v_mfma_f32_16x16x32_bf16 v[184:187], v[68:71], v[104:107], v[184:187]
	ds_read_b128 v[88:91], v220 offset:20480
	s_waitcnt lgkmcnt(9)
	v_mfma_f32_16x16x32_bf16 v[188:191], v[68:71], v[108:111], v[188:191]
	ds_read_b128 v[92:95], v220 offset:22528
	s_waitcnt lgkmcnt(9)
	v_mfma_f32_16x16x32_bf16 v[192:195], v[72:75], v[96:99], v[192:195]
	s_waitcnt lgkmcnt(9)
	v_mfma_f32_16x16x32_bf16 v[196:199], v[72:75], v[100:103], v[196:199]
	s_waitcnt lgkmcnt(9)
	v_mfma_f32_16x16x32_bf16 v[200:203], v[72:75], v[104:107], v[200:203]
	s_waitcnt lgkmcnt(9)
	v_mfma_f32_16x16x32_bf16 v[204:207], v[72:75], v[108:111], v[204:207]
	s_waitcnt vmcnt(0) lgkmcnt(0)
	s_barrier
	s_add_u32 m0, s38, 16384
	s_nop 0
	global_load_lds_dwordx4 v226, s[100:101]
	s_waitcnt lgkmcnt(8)
	v_mfma_f32_16x16x32_bf16 v[208:211], v[76:79], v[96:99], v[208:211]
	s_add_u32 m0, s38, 20480
	s_nop 0
	global_load_lds_dwordx4 v228, s[100:101]
	s_waitcnt lgkmcnt(8)
	v_mfma_f32_16x16x32_bf16 v[212:215], v[76:79], v[100:103], v[212:215]
	s_add_u32 m0, s38, 24576
	s_nop 0
	global_load_lds_dwordx4 v244, s[100:101]
	s_waitcnt lgkmcnt(8)
	v_mfma_f32_16x16x32_bf16 v[216:219], v[76:79], v[104:107], v[216:219]
	s_add_u32 m0, s38, 28672
	s_nop 0
	global_load_lds_dwordx4 v245, s[100:101]
	s_add_u32 s100, s100, 128
	s_addc_u32 s101, s101, 0
	s_waitcnt lgkmcnt(8)
	v_mfma_f32_16x16x32_bf16 v[230:233], v[76:79], v[108:111], v[230:233]
	s_add_u32 m0, s38, 49152
	s_nop 0
	global_load_lds_dwordx4 v226, s[4:5]
	s_waitcnt lgkmcnt(6)
	v_mfma_f32_16x16x32_bf16 v[160:163], v[80:83], v[112:115], v[160:163]
	ds_read_b128 v[64:67], v151 offset:0
	s_add_u32 m0, s38, 53248
	s_nop 0
	global_load_lds_dwordx4 v228, s[4:5]
	s_waitcnt lgkmcnt(6)
	v_mfma_f32_16x16x32_bf16 v[164:167], v[80:83], v[116:119], v[164:167]
	ds_read_b128 v[96:99], v222 offset:32768
	s_add_u32 m0, s38, 57344
	s_nop 0
	global_load_lds_dwordx4 v244, s[4:5]
	s_waitcnt lgkmcnt(6)
	v_mfma_f32_16x16x32_bf16 v[168:171], v[80:83], v[120:123], v[168:171]
	ds_read_b128 v[100:103], v222 offset:34816
	s_add_u32 m0, s38, 61440
	s_nop 0
	global_load_lds_dwordx4 v245, s[4:5]
	s_add_u32 s4, s4, 128
	s_addc_u32 s5, s5, 0
	s_waitcnt lgkmcnt(6)
	v_mfma_f32_16x16x32_bf16 v[172:175], v[80:83], v[124:127], v[172:175]
	ds_read_b128 v[104:107], v222 offset:36864
	s_waitcnt lgkmcnt(6)
	v_mfma_f32_16x16x32_bf16 v[176:179], v[84:87], v[112:115], v[176:179]
	ds_read_b128 v[108:111], v222 offset:38912
	s_waitcnt lgkmcnt(7)
	v_mfma_f32_16x16x32_bf16 v[180:183], v[84:87], v[116:119], v[180:183]
	ds_read_b128 v[68:71], v151 offset:2048
	s_waitcnt lgkmcnt(8)
	v_mfma_f32_16x16x32_bf16 v[184:187], v[84:87], v[120:123], v[184:187]
	ds_read_b128 v[72:75], v151 offset:4096
	s_waitcnt lgkmcnt(9)
	v_mfma_f32_16x16x32_bf16 v[188:191], v[84:87], v[124:127], v[188:191]
	ds_read_b128 v[76:79], v151 offset:6144
	s_waitcnt lgkmcnt(9)
	v_mfma_f32_16x16x32_bf16 v[192:195], v[88:91], v[112:115], v[192:195]
	s_waitcnt lgkmcnt(9)
	v_mfma_f32_16x16x32_bf16 v[196:199], v[88:91], v[116:119], v[196:199]
	s_waitcnt lgkmcnt(9)
	v_mfma_f32_16x16x32_bf16 v[200:203], v[88:91], v[120:123], v[200:203]
	s_waitcnt lgkmcnt(9)
	v_mfma_f32_16x16x32_bf16 v[204:207], v[88:91], v[124:127], v[204:207]
	s_waitcnt lgkmcnt(8)
	v_mfma_f32_16x16x32_bf16 v[208:211], v[92:95], v[112:115], v[208:211]
	s_waitcnt lgkmcnt(8)
	v_mfma_f32_16x16x32_bf16 v[212:215], v[92:95], v[116:119], v[212:215]
	s_waitcnt lgkmcnt(8)
	v_mfma_f32_16x16x32_bf16 v[216:219], v[92:95], v[120:123], v[216:219]
	s_waitcnt lgkmcnt(8)
	v_mfma_f32_16x16x32_bf16 v[230:233], v[92:95], v[124:127], v[230:233]
	s_waitcnt lgkmcnt(6)
	v_mfma_f32_16x16x32_bf16 v[0:3], v[64:67], v[96:99], v[0:3]
	ds_read_b128 v[80:83], v220 offset:0
	s_waitcnt lgkmcnt(6)
	v_mfma_f32_16x16x32_bf16 v[4:7], v[64:67], v[100:103], v[4:7]
	ds_read_b128 v[112:115], v224 offset:32768
	s_waitcnt lgkmcnt(6)
	v_mfma_f32_16x16x32_bf16 v[8:11], v[64:67], v[104:107], v[8:11]
	ds_read_b128 v[116:119], v224 offset:34816
	s_waitcnt lgkmcnt(6)
	v_mfma_f32_16x16x32_bf16 v[12:15], v[64:67], v[108:111], v[12:15]
	ds_read_b128 v[120:123], v224 offset:36864
	s_waitcnt lgkmcnt(6)
	v_mfma_f32_16x16x32_bf16 v[16:19], v[68:71], v[96:99], v[16:19]
	ds_read_b128 v[124:127], v224 offset:38912
	s_waitcnt lgkmcnt(7)
	v_mfma_f32_16x16x32_bf16 v[20:23], v[68:71], v[100:103], v[20:23]
	ds_read_b128 v[84:87], v220 offset:2048
	s_waitcnt lgkmcnt(8)
	v_mfma_f32_16x16x32_bf16 v[24:27], v[68:71], v[104:107], v[24:27]
	ds_read_b128 v[88:91], v220 offset:4096
	s_waitcnt lgkmcnt(9)
	v_mfma_f32_16x16x32_bf16 v[28:31], v[68:71], v[108:111], v[28:31]
	ds_read_b128 v[92:95], v220 offset:6144
	s_waitcnt lgkmcnt(9)
	v_mfma_f32_16x16x32_bf16 v[32:35], v[72:75], v[96:99], v[32:35]
	s_waitcnt lgkmcnt(9)
	v_mfma_f32_16x16x32_bf16 v[36:39], v[72:75], v[100:103], v[36:39]
	s_waitcnt lgkmcnt(9)
	v_mfma_f32_16x16x32_bf16 v[40:43], v[72:75], v[104:107], v[40:43]
	s_waitcnt lgkmcnt(9)
	v_mfma_f32_16x16x32_bf16 v[44:47], v[72:75], v[108:111], v[44:47]
	s_waitcnt vmcnt(4) lgkmcnt(0)
	s_barrier
	s_add_u32 m0, s38, 0
	s_nop 0
	global_load_lds_dwordx4 v226, s[98:99]
	s_waitcnt lgkmcnt(8)
	v_mfma_f32_16x16x32_bf16 v[48:51], v[76:79], v[96:99], v[48:51]
	s_add_u32 m0, s38, 4096
	s_nop 0
	global_load_lds_dwordx4 v228, s[98:99]
	s_waitcnt lgkmcnt(8)
	v_mfma_f32_16x16x32_bf16 v[52:55], v[76:79], v[100:103], v[52:55]
	s_add_u32 m0, s38, 8192
	s_nop 0
	global_load_lds_dwordx4 v244, s[98:99]
	s_waitcnt lgkmcnt(8)
	v_mfma_f32_16x16x32_bf16 v[56:59], v[76:79], v[104:107], v[56:59]
	s_add_u32 m0, s38, 12288
	s_nop 0
	global_load_lds_dwordx4 v245, s[98:99]
	s_add_u32 s98, s98, 128
	s_addc_u32 s99, s99, 0
	s_waitcnt lgkmcnt(8)
	v_mfma_f32_16x16x32_bf16 v[60:63], v[76:79], v[108:111], v[60:63]
	s_waitcnt lgkmcnt(6)
	v_mfma_f32_16x16x32_bf16 v[0:3], v[80:83], v[112:115], v[0:3]
	ds_read_b128 v[64:67], v151 offset:16384
	s_waitcnt lgkmcnt(6)
	v_mfma_f32_16x16x32_bf16 v[4:7], v[80:83], v[116:119], v[4:7]
	ds_read_b128 v[96:99], v222 offset:32768
	s_waitcnt lgkmcnt(6)
	v_mfma_f32_16x16x32_bf16 v[8:11], v[80:83], v[120:123], v[8:11]
	ds_read_b128 v[100:103], v222 offset:34816
	s_waitcnt lgkmcnt(6)
	v_mfma_f32_16x16x32_bf16 v[12:15], v[80:83], v[124:127], v[12:15]
	ds_read_b128 v[104:107], v222 offset:36864
	s_waitcnt lgkmcnt(6)
	v_mfma_f32_16x16x32_bf16 v[16:19], v[84:87], v[112:115], v[16:19]
	ds_read_b128 v[108:111], v222 offset:38912
	s_waitcnt lgkmcnt(7)
	v_mfma_f32_16x16x32_bf16 v[20:23], v[84:87], v[116:119], v[20:23]
	ds_read_b128 v[68:71], v151 offset:18432
	s_waitcnt lgkmcnt(8)
	v_mfma_f32_16x16x32_bf16 v[24:27], v[84:87], v[120:123], v[24:27]
	ds_read_b128 v[72:75], v151 offset:20480
	s_waitcnt lgkmcnt(9)
	v_mfma_f32_16x16x32_bf16 v[28:31], v[84:87], v[124:127], v[28:31]
	ds_read_b128 v[76:79], v151 offset:22528
	s_waitcnt lgkmcnt(9)
	v_mfma_f32_16x16x32_bf16 v[32:35], v[88:91], v[112:115], v[32:35]
	s_waitcnt lgkmcnt(9)
	v_mfma_f32_16x16x32_bf16 v[36:39], v[88:91], v[116:119], v[36:39]
	s_waitcnt lgkmcnt(9)
	v_mfma_f32_16x16x32_bf16 v[40:43], v[88:91], v[120:123], v[40:43]
	s_waitcnt lgkmcnt(9)
	v_mfma_f32_16x16x32_bf16 v[44:47], v[88:91], v[124:127], v[44:47]
	s_waitcnt lgkmcnt(8)
	v_mfma_f32_16x16x32_bf16 v[48:51], v[92:95], v[112:115], v[48:51]
	s_waitcnt lgkmcnt(8)
	v_mfma_f32_16x16x32_bf16 v[52:55], v[92:95], v[116:119], v[52:55]
	s_waitcnt lgkmcnt(8)
	v_mfma_f32_16x16x32_bf16 v[56:59], v[92:95], v[120:123], v[56:59]
	s_waitcnt lgkmcnt(8)
	v_mfma_f32_16x16x32_bf16 v[60:63], v[92:95], v[124:127], v[60:63]
	s_waitcnt lgkmcnt(6)
	v_mfma_f32_16x16x32_bf16 v[160:163], v[64:67], v[96:99], v[160:163]
	ds_read_b128 v[80:83], v220 offset:16384
	s_waitcnt lgkmcnt(6)
	v_mfma_f32_16x16x32_bf16 v[164:167], v[64:67], v[100:103], v[164:167]
	ds_read_b128 v[112:115], v224 offset:32768
	s_waitcnt lgkmcnt(6)
	v_mfma_f32_16x16x32_bf16 v[168:171], v[64:67], v[104:107], v[168:171]
	ds_read_b128 v[116:119], v224 offset:34816
	s_waitcnt lgkmcnt(6)
	v_mfma_f32_16x16x32_bf16 v[172:175], v[64:67], v[108:111], v[172:175]
	ds_read_b128 v[120:123], v224 offset:36864
	s_waitcnt lgkmcnt(6)
	v_mfma_f32_16x16x32_bf16 v[176:179], v[68:71], v[96:99], v[176:179]
	ds_read_b128 v[124:127], v224 offset:38912
	s_waitcnt lgkmcnt(7)
	v_mfma_f32_16x16x32_bf16 v[180:183], v[68:71], v[100:103], v[180:183]
	ds_read_b128 v[84:87], v220 offset:18432
	s_waitcnt lgkmcnt(8)
	v_mfma_f32_16x16x32_bf16 v[184:187], v[68:71], v[104:107], v[184:187]
	ds_read_b128 v[88:91], v220 offset:20480
	s_waitcnt lgkmcnt(9)
	v_mfma_f32_16x16x32_bf16 v[188:191], v[68:71], v[108:111], v[188:191]
	ds_read_b128 v[92:95], v220 offset:22528
	s_waitcnt lgkmcnt(9)
	v_mfma_f32_16x16x32_bf16 v[192:195], v[72:75], v[96:99], v[192:195]
	s_waitcnt lgkmcnt(9)
	v_mfma_f32_16x16x32_bf16 v[196:199], v[72:75], v[100:103], v[196:199]
	s_waitcnt lgkmcnt(9)
	v_mfma_f32_16x16x32_bf16 v[200:203], v[72:75], v[104:107], v[200:203]
	s_waitcnt lgkmcnt(9)
	v_mfma_f32_16x16x32_bf16 v[204:207], v[72:75], v[108:111], v[204:207]
	s_waitcnt vmcnt(0) lgkmcnt(0)
	s_barrier
	s_add_u32 m0, s38, 16384
	s_nop 0
	global_load_lds_dwordx4 v226, s[100:101]
	s_waitcnt lgkmcnt(8)
	v_mfma_f32_16x16x32_bf16 v[208:211], v[76:79], v[96:99], v[208:211]
	s_add_u32 m0, s38, 20480
	s_nop 0
	global_load_lds_dwordx4 v228, s[100:101]
	s_waitcnt lgkmcnt(8)
	v_mfma_f32_16x16x32_bf16 v[212:215], v[76:79], v[100:103], v[212:215]
	s_add_u32 m0, s38, 24576
	s_nop 0
	global_load_lds_dwordx4 v244, s[100:101]
	s_waitcnt lgkmcnt(8)
	v_mfma_f32_16x16x32_bf16 v[216:219], v[76:79], v[104:107], v[216:219]
	s_add_u32 m0, s38, 28672
	s_nop 0
	global_load_lds_dwordx4 v245, s[100:101]
	s_add_u32 s100, s100, 128
	s_addc_u32 s101, s101, 0
	s_waitcnt lgkmcnt(8)
	v_mfma_f32_16x16x32_bf16 v[230:233], v[76:79], v[108:111], v[230:233]
	s_add_u32 m0, s38, 32768
	s_nop 0
	global_load_lds_dwordx4 v226, s[4:5]
	s_waitcnt lgkmcnt(6)
	v_mfma_f32_16x16x32_bf16 v[160:163], v[80:83], v[112:115], v[160:163]
	ds_read_b128 v[64:67], v151 offset:0
	s_add_u32 m0, s38, 36864
	s_nop 0
	global_load_lds_dwordx4 v228, s[4:5]
	s_waitcnt lgkmcnt(6)
	v_mfma_f32_16x16x32_bf16 v[164:167], v[80:83], v[116:119], v[164:167]
	ds_read_b128 v[96:99], v222 offset:49152
	s_add_u32 m0, s38, 40960
	s_nop 0
	global_load_lds_dwordx4 v244, s[4:5]
	s_waitcnt lgkmcnt(6)
	v_mfma_f32_16x16x32_bf16 v[168:171], v[80:83], v[120:123], v[168:171]
	ds_read_b128 v[100:103], v222 offset:51200
	s_add_u32 m0, s38, 45056
	s_nop 0
	global_load_lds_dwordx4 v245, s[4:5]
	s_add_u32 s4, s4, 128
	s_addc_u32 s5, s5, 0
	s_waitcnt lgkmcnt(6)
	v_mfma_f32_16x16x32_bf16 v[172:175], v[80:83], v[124:127], v[172:175]
	ds_read_b128 v[104:107], v222 offset:53248
	s_waitcnt lgkmcnt(6)
	v_mfma_f32_16x16x32_bf16 v[176:179], v[84:87], v[112:115], v[176:179]
	ds_read_b128 v[108:111], v222 offset:55296
	s_waitcnt lgkmcnt(7)
	v_mfma_f32_16x16x32_bf16 v[180:183], v[84:87], v[116:119], v[180:183]
	ds_read_b128 v[68:71], v151 offset:2048
	s_waitcnt lgkmcnt(8)
	v_mfma_f32_16x16x32_bf16 v[184:187], v[84:87], v[120:123], v[184:187]
	ds_read_b128 v[72:75], v151 offset:4096
	s_waitcnt lgkmcnt(9)
	v_mfma_f32_16x16x32_bf16 v[188:191], v[84:87], v[124:127], v[188:191]
	ds_read_b128 v[76:79], v151 offset:6144
	s_waitcnt lgkmcnt(9)
	v_mfma_f32_16x16x32_bf16 v[192:195], v[88:91], v[112:115], v[192:195]
	s_waitcnt lgkmcnt(9)
	v_mfma_f32_16x16x32_bf16 v[196:199], v[88:91], v[116:119], v[196:199]
	s_waitcnt lgkmcnt(9)
	v_mfma_f32_16x16x32_bf16 v[200:203], v[88:91], v[120:123], v[200:203]
	s_waitcnt lgkmcnt(9)
	v_mfma_f32_16x16x32_bf16 v[204:207], v[88:91], v[124:127], v[204:207]
	s_waitcnt lgkmcnt(8)
	v_mfma_f32_16x16x32_bf16 v[208:211], v[92:95], v[112:115], v[208:211]
	s_waitcnt lgkmcnt(8)
	v_mfma_f32_16x16x32_bf16 v[212:215], v[92:95], v[116:119], v[212:215]
	s_waitcnt lgkmcnt(8)
	v_mfma_f32_16x16x32_bf16 v[216:219], v[92:95], v[120:123], v[216:219]
	s_waitcnt lgkmcnt(8)
	v_mfma_f32_16x16x32_bf16 v[230:233], v[92:95], v[124:127], v[230:233]
	s_waitcnt lgkmcnt(6)
	v_mfma_f32_16x16x32_bf16 v[0:3], v[64:67], v[96:99], v[0:3]
	ds_read_b128 v[80:83], v220 offset:0
	s_waitcnt lgkmcnt(6)
	v_mfma_f32_16x16x32_bf16 v[4:7], v[64:67], v[100:103], v[4:7]
	ds_read_b128 v[112:115], v224 offset:49152
	s_waitcnt lgkmcnt(6)
	v_mfma_f32_16x16x32_bf16 v[8:11], v[64:67], v[104:107], v[8:11]
	ds_read_b128 v[116:119], v224 offset:51200
	s_waitcnt lgkmcnt(6)
	v_mfma_f32_16x16x32_bf16 v[12:15], v[64:67], v[108:111], v[12:15]
	ds_read_b128 v[120:123], v224 offset:53248
	s_waitcnt lgkmcnt(6)
	v_mfma_f32_16x16x32_bf16 v[16:19], v[68:71], v[96:99], v[16:19]
	ds_read_b128 v[124:127], v224 offset:55296
	s_waitcnt lgkmcnt(7)
	v_mfma_f32_16x16x32_bf16 v[20:23], v[68:71], v[100:103], v[20:23]
	ds_read_b128 v[84:87], v220 offset:2048
	s_waitcnt lgkmcnt(8)
	v_mfma_f32_16x16x32_bf16 v[24:27], v[68:71], v[104:107], v[24:27]
	ds_read_b128 v[88:91], v220 offset:4096
	s_waitcnt lgkmcnt(9)
	v_mfma_f32_16x16x32_bf16 v[28:31], v[68:71], v[108:111], v[28:31]
	ds_read_b128 v[92:95], v220 offset:6144
	s_waitcnt lgkmcnt(9)
	v_mfma_f32_16x16x32_bf16 v[32:35], v[72:75], v[96:99], v[32:35]
	s_waitcnt lgkmcnt(9)
	v_mfma_f32_16x16x32_bf16 v[36:39], v[72:75], v[100:103], v[36:39]
	s_waitcnt lgkmcnt(9)
	v_mfma_f32_16x16x32_bf16 v[40:43], v[72:75], v[104:107], v[40:43]
	s_waitcnt lgkmcnt(9)
	v_mfma_f32_16x16x32_bf16 v[44:47], v[72:75], v[108:111], v[44:47]
	s_waitcnt vmcnt(4) lgkmcnt(0)
	s_barrier
	s_add_u32 m0, s38, 0
	s_nop 0
	global_load_lds_dwordx4 v226, s[98:99]
	s_waitcnt lgkmcnt(8)
	v_mfma_f32_16x16x32_bf16 v[48:51], v[76:79], v[96:99], v[48:51]
	s_add_u32 m0, s38, 4096
	s_nop 0
	global_load_lds_dwordx4 v228, s[98:99]
	s_waitcnt lgkmcnt(8)
	v_mfma_f32_16x16x32_bf16 v[52:55], v[76:79], v[100:103], v[52:55]
	s_add_u32 m0, s38, 8192
	s_nop 0
	global_load_lds_dwordx4 v244, s[98:99]
	s_waitcnt lgkmcnt(8)
	v_mfma_f32_16x16x32_bf16 v[56:59], v[76:79], v[104:107], v[56:59]
	s_add_u32 m0, s38, 12288
	s_nop 0
	global_load_lds_dwordx4 v245, s[98:99]
	s_add_u32 s98, s98, 128
	s_addc_u32 s99, s99, 0
	s_waitcnt lgkmcnt(8)
	v_mfma_f32_16x16x32_bf16 v[60:63], v[76:79], v[108:111], v[60:63]
	s_waitcnt lgkmcnt(6)
	v_mfma_f32_16x16x32_bf16 v[0:3], v[80:83], v[112:115], v[0:3]
	ds_read_b128 v[64:67], v151 offset:16384
	s_waitcnt lgkmcnt(6)
	v_mfma_f32_16x16x32_bf16 v[4:7], v[80:83], v[116:119], v[4:7]
	ds_read_b128 v[96:99], v222 offset:49152
	s_waitcnt lgkmcnt(6)
	v_mfma_f32_16x16x32_bf16 v[8:11], v[80:83], v[120:123], v[8:11]
	ds_read_b128 v[100:103], v222 offset:51200
	s_waitcnt lgkmcnt(6)
	v_mfma_f32_16x16x32_bf16 v[12:15], v[80:83], v[124:127], v[12:15]
	ds_read_b128 v[104:107], v222 offset:53248
	s_waitcnt lgkmcnt(6)
	v_mfma_f32_16x16x32_bf16 v[16:19], v[84:87], v[112:115], v[16:19]
	ds_read_b128 v[108:111], v222 offset:55296
	s_waitcnt lgkmcnt(7)
	v_mfma_f32_16x16x32_bf16 v[20:23], v[84:87], v[116:119], v[20:23]
	ds_read_b128 v[68:71], v151 offset:18432
	s_waitcnt lgkmcnt(8)
	v_mfma_f32_16x16x32_bf16 v[24:27], v[84:87], v[120:123], v[24:27]
	ds_read_b128 v[72:75], v151 offset:20480
	s_waitcnt lgkmcnt(9)
	v_mfma_f32_16x16x32_bf16 v[28:31], v[84:87], v[124:127], v[28:31]
	ds_read_b128 v[76:79], v151 offset:22528
	s_waitcnt lgkmcnt(9)
	v_mfma_f32_16x16x32_bf16 v[32:35], v[88:91], v[112:115], v[32:35]
	s_waitcnt lgkmcnt(9)
	v_mfma_f32_16x16x32_bf16 v[36:39], v[88:91], v[116:119], v[36:39]
	s_waitcnt lgkmcnt(9)
	v_mfma_f32_16x16x32_bf16 v[40:43], v[88:91], v[120:123], v[40:43]
	s_waitcnt lgkmcnt(9)
	v_mfma_f32_16x16x32_bf16 v[44:47], v[88:91], v[124:127], v[44:47]
	s_waitcnt lgkmcnt(8)
	v_mfma_f32_16x16x32_bf16 v[48:51], v[92:95], v[112:115], v[48:51]
	s_waitcnt lgkmcnt(8)
	v_mfma_f32_16x16x32_bf16 v[52:55], v[92:95], v[116:119], v[52:55]
	s_waitcnt lgkmcnt(8)
	v_mfma_f32_16x16x32_bf16 v[56:59], v[92:95], v[120:123], v[56:59]
	s_waitcnt lgkmcnt(8)
	v_mfma_f32_16x16x32_bf16 v[60:63], v[92:95], v[124:127], v[60:63]
	s_waitcnt lgkmcnt(6)
	v_mfma_f32_16x16x32_bf16 v[160:163], v[64:67], v[96:99], v[160:163]
	ds_read_b128 v[80:83], v220 offset:16384
	s_waitcnt lgkmcnt(6)
	v_mfma_f32_16x16x32_bf16 v[164:167], v[64:67], v[100:103], v[164:167]
	ds_read_b128 v[112:115], v224 offset:49152
	s_waitcnt lgkmcnt(6)
	v_mfma_f32_16x16x32_bf16 v[168:171], v[64:67], v[104:107], v[168:171]
	ds_read_b128 v[116:119], v224 offset:51200
	s_waitcnt lgkmcnt(6)
	v_mfma_f32_16x16x32_bf16 v[172:175], v[64:67], v[108:111], v[172:175]
	ds_read_b128 v[120:123], v224 offset:53248
	s_waitcnt lgkmcnt(6)
	v_mfma_f32_16x16x32_bf16 v[176:179], v[68:71], v[96:99], v[176:179]
	ds_read_b128 v[124:127], v224 offset:55296
	s_waitcnt lgkmcnt(7)
	v_mfma_f32_16x16x32_bf16 v[180:183], v[68:71], v[100:103], v[180:183]
	ds_read_b128 v[84:87], v220 offset:18432
	s_waitcnt lgkmcnt(8)
	v_mfma_f32_16x16x32_bf16 v[184:187], v[68:71], v[104:107], v[184:187]
	ds_read_b128 v[88:91], v220 offset:20480
	s_waitcnt lgkmcnt(9)
	v_mfma_f32_16x16x32_bf16 v[188:191], v[68:71], v[108:111], v[188:191]
	ds_read_b128 v[92:95], v220 offset:22528
	s_waitcnt lgkmcnt(9)
	v_mfma_f32_16x16x32_bf16 v[192:195], v[72:75], v[96:99], v[192:195]
	s_waitcnt lgkmcnt(9)
	v_mfma_f32_16x16x32_bf16 v[196:199], v[72:75], v[100:103], v[196:199]
	s_waitcnt lgkmcnt(9)
	v_mfma_f32_16x16x32_bf16 v[200:203], v[72:75], v[104:107], v[200:203]
	s_waitcnt lgkmcnt(9)
	v_mfma_f32_16x16x32_bf16 v[204:207], v[72:75], v[108:111], v[204:207]
	s_waitcnt vmcnt(0) lgkmcnt(0)
	s_barrier
	s_add_u32 m0, s38, 16384
	s_nop 0
	global_load_lds_dwordx4 v226, s[100:101]
	s_waitcnt lgkmcnt(8)
	v_mfma_f32_16x16x32_bf16 v[208:211], v[76:79], v[96:99], v[208:211]
	s_add_u32 m0, s38, 20480
	s_nop 0
	global_load_lds_dwordx4 v228, s[100:101]
	s_waitcnt lgkmcnt(8)
	v_mfma_f32_16x16x32_bf16 v[212:215], v[76:79], v[100:103], v[212:215]
	s_add_u32 m0, s38, 24576
	s_nop 0
	global_load_lds_dwordx4 v244, s[100:101]
	s_waitcnt lgkmcnt(8)
	v_mfma_f32_16x16x32_bf16 v[216:219], v[76:79], v[104:107], v[216:219]
	s_add_u32 m0, s38, 28672
	s_nop 0
	global_load_lds_dwordx4 v245, s[100:101]
	s_add_u32 s100, s100, 128
	s_addc_u32 s101, s101, 0
	s_waitcnt lgkmcnt(8)
	v_mfma_f32_16x16x32_bf16 v[230:233], v[76:79], v[108:111], v[230:233]
	s_add_u32 m0, s38, 49152
	s_nop 0
	global_load_lds_dwordx4 v226, s[4:5]
	s_waitcnt lgkmcnt(6)
	v_mfma_f32_16x16x32_bf16 v[160:163], v[80:83], v[112:115], v[160:163]
	ds_read_b128 v[64:67], v151 offset:0
	s_add_u32 m0, s38, 53248
	s_nop 0
	global_load_lds_dwordx4 v228, s[4:5]
	s_waitcnt lgkmcnt(6)
	v_mfma_f32_16x16x32_bf16 v[164:167], v[80:83], v[116:119], v[164:167]
	ds_read_b128 v[96:99], v222 offset:32768
	s_add_u32 m0, s38, 57344
	s_nop 0
	global_load_lds_dwordx4 v244, s[4:5]
	s_waitcnt lgkmcnt(6)
	v_mfma_f32_16x16x32_bf16 v[168:171], v[80:83], v[120:123], v[168:171]
	ds_read_b128 v[100:103], v222 offset:34816
	s_add_u32 m0, s38, 61440
	s_nop 0
	global_load_lds_dwordx4 v245, s[4:5]
	s_add_u32 s4, s4, 128
	s_addc_u32 s5, s5, 0
	s_waitcnt lgkmcnt(6)
	v_mfma_f32_16x16x32_bf16 v[172:175], v[80:83], v[124:127], v[172:175]
	ds_read_b128 v[104:107], v222 offset:36864
	s_waitcnt lgkmcnt(6)
	v_mfma_f32_16x16x32_bf16 v[176:179], v[84:87], v[112:115], v[176:179]
	ds_read_b128 v[108:111], v222 offset:38912
	s_waitcnt lgkmcnt(7)
	v_mfma_f32_16x16x32_bf16 v[180:183], v[84:87], v[116:119], v[180:183]
	ds_read_b128 v[68:71], v151 offset:2048
	s_waitcnt lgkmcnt(8)
	v_mfma_f32_16x16x32_bf16 v[184:187], v[84:87], v[120:123], v[184:187]
	ds_read_b128 v[72:75], v151 offset:4096
	s_waitcnt lgkmcnt(9)
	v_mfma_f32_16x16x32_bf16 v[188:191], v[84:87], v[124:127], v[188:191]
	ds_read_b128 v[76:79], v151 offset:6144
	s_waitcnt lgkmcnt(9)
	v_mfma_f32_16x16x32_bf16 v[192:195], v[88:91], v[112:115], v[192:195]
	s_waitcnt lgkmcnt(9)
	v_mfma_f32_16x16x32_bf16 v[196:199], v[88:91], v[116:119], v[196:199]
	s_waitcnt lgkmcnt(9)
	v_mfma_f32_16x16x32_bf16 v[200:203], v[88:91], v[120:123], v[200:203]
	s_waitcnt lgkmcnt(9)
	v_mfma_f32_16x16x32_bf16 v[204:207], v[88:91], v[124:127], v[204:207]
	s_waitcnt lgkmcnt(8)
	v_mfma_f32_16x16x32_bf16 v[208:211], v[92:95], v[112:115], v[208:211]
	s_waitcnt lgkmcnt(8)
	v_mfma_f32_16x16x32_bf16 v[212:215], v[92:95], v[116:119], v[212:215]
	s_waitcnt lgkmcnt(8)
	v_mfma_f32_16x16x32_bf16 v[216:219], v[92:95], v[120:123], v[216:219]
	s_waitcnt lgkmcnt(8)
	v_mfma_f32_16x16x32_bf16 v[230:233], v[92:95], v[124:127], v[230:233]
	s_waitcnt lgkmcnt(6)
	v_mfma_f32_16x16x32_bf16 v[0:3], v[64:67], v[96:99], v[0:3]
	ds_read_b128 v[80:83], v220 offset:0
	s_waitcnt lgkmcnt(6)
	v_mfma_f32_16x16x32_bf16 v[4:7], v[64:67], v[100:103], v[4:7]
	ds_read_b128 v[112:115], v224 offset:32768
	s_waitcnt lgkmcnt(6)
	v_mfma_f32_16x16x32_bf16 v[8:11], v[64:67], v[104:107], v[8:11]
	ds_read_b128 v[116:119], v224 offset:34816
	s_waitcnt lgkmcnt(6)
	v_mfma_f32_16x16x32_bf16 v[12:15], v[64:67], v[108:111], v[12:15]
	ds_read_b128 v[120:123], v224 offset:36864
	s_waitcnt lgkmcnt(6)
	v_mfma_f32_16x16x32_bf16 v[16:19], v[68:71], v[96:99], v[16:19]
	ds_read_b128 v[124:127], v224 offset:38912
	s_waitcnt lgkmcnt(7)
	v_mfma_f32_16x16x32_bf16 v[20:23], v[68:71], v[100:103], v[20:23]
	ds_read_b128 v[84:87], v220 offset:2048
	s_waitcnt lgkmcnt(8)
	v_mfma_f32_16x16x32_bf16 v[24:27], v[68:71], v[104:107], v[24:27]
	ds_read_b128 v[88:91], v220 offset:4096
	s_waitcnt lgkmcnt(9)
	v_mfma_f32_16x16x32_bf16 v[28:31], v[68:71], v[108:111], v[28:31]
	ds_read_b128 v[92:95], v220 offset:6144
	s_waitcnt lgkmcnt(9)
	v_mfma_f32_16x16x32_bf16 v[32:35], v[72:75], v[96:99], v[32:35]
	s_waitcnt lgkmcnt(9)
	v_mfma_f32_16x16x32_bf16 v[36:39], v[72:75], v[100:103], v[36:39]
	s_waitcnt lgkmcnt(9)
	v_mfma_f32_16x16x32_bf16 v[40:43], v[72:75], v[104:107], v[40:43]
	s_waitcnt lgkmcnt(9)
	v_mfma_f32_16x16x32_bf16 v[44:47], v[72:75], v[108:111], v[44:47]
	s_waitcnt vmcnt(4) lgkmcnt(0)
	s_barrier
	s_add_u32 m0, s38, 0
	s_nop 0
	global_load_lds_dwordx4 v226, s[98:99]
	s_waitcnt lgkmcnt(8)
	v_mfma_f32_16x16x32_bf16 v[48:51], v[76:79], v[96:99], v[48:51]
	s_add_u32 m0, s38, 4096
	s_nop 0
	global_load_lds_dwordx4 v228, s[98:99]
	s_waitcnt lgkmcnt(8)
	v_mfma_f32_16x16x32_bf16 v[52:55], v[76:79], v[100:103], v[52:55]
	s_add_u32 m0, s38, 8192
	s_nop 0
	global_load_lds_dwordx4 v244, s[98:99]
	s_waitcnt lgkmcnt(8)
	v_mfma_f32_16x16x32_bf16 v[56:59], v[76:79], v[104:107], v[56:59]
	s_add_u32 m0, s38, 12288
	s_nop 0
	global_load_lds_dwordx4 v245, s[98:99]
	s_add_u32 s98, s98, 128
	s_addc_u32 s99, s99, 0
	s_waitcnt lgkmcnt(8)
	v_mfma_f32_16x16x32_bf16 v[60:63], v[76:79], v[108:111], v[60:63]
	s_waitcnt lgkmcnt(6)
	v_mfma_f32_16x16x32_bf16 v[0:3], v[80:83], v[112:115], v[0:3]
	ds_read_b128 v[64:67], v151 offset:16384
	s_waitcnt lgkmcnt(6)
	v_mfma_f32_16x16x32_bf16 v[4:7], v[80:83], v[116:119], v[4:7]
	ds_read_b128 v[96:99], v222 offset:32768
	s_waitcnt lgkmcnt(6)
	v_mfma_f32_16x16x32_bf16 v[8:11], v[80:83], v[120:123], v[8:11]
	ds_read_b128 v[100:103], v222 offset:34816
	s_waitcnt lgkmcnt(6)
	v_mfma_f32_16x16x32_bf16 v[12:15], v[80:83], v[124:127], v[12:15]
	ds_read_b128 v[104:107], v222 offset:36864
	s_waitcnt lgkmcnt(6)
	v_mfma_f32_16x16x32_bf16 v[16:19], v[84:87], v[112:115], v[16:19]
	ds_read_b128 v[108:111], v222 offset:38912
	s_waitcnt lgkmcnt(7)
	v_mfma_f32_16x16x32_bf16 v[20:23], v[84:87], v[116:119], v[20:23]
	ds_read_b128 v[68:71], v151 offset:18432
	s_waitcnt lgkmcnt(8)
	v_mfma_f32_16x16x32_bf16 v[24:27], v[84:87], v[120:123], v[24:27]
	ds_read_b128 v[72:75], v151 offset:20480
	s_waitcnt lgkmcnt(9)
	v_mfma_f32_16x16x32_bf16 v[28:31], v[84:87], v[124:127], v[28:31]
	ds_read_b128 v[76:79], v151 offset:22528
	s_waitcnt lgkmcnt(9)
	v_mfma_f32_16x16x32_bf16 v[32:35], v[88:91], v[112:115], v[32:35]
	s_waitcnt lgkmcnt(9)
	v_mfma_f32_16x16x32_bf16 v[36:39], v[88:91], v[116:119], v[36:39]
	s_waitcnt lgkmcnt(9)
	v_mfma_f32_16x16x32_bf16 v[40:43], v[88:91], v[120:123], v[40:43]
	s_waitcnt lgkmcnt(9)
	v_mfma_f32_16x16x32_bf16 v[44:47], v[88:91], v[124:127], v[44:47]
	s_waitcnt lgkmcnt(8)
	v_mfma_f32_16x16x32_bf16 v[48:51], v[92:95], v[112:115], v[48:51]
	s_waitcnt lgkmcnt(8)
	v_mfma_f32_16x16x32_bf16 v[52:55], v[92:95], v[116:119], v[52:55]
	s_waitcnt lgkmcnt(8)
	v_mfma_f32_16x16x32_bf16 v[56:59], v[92:95], v[120:123], v[56:59]
	s_waitcnt lgkmcnt(8)
	v_mfma_f32_16x16x32_bf16 v[60:63], v[92:95], v[124:127], v[60:63]
	s_waitcnt lgkmcnt(6)
	v_mfma_f32_16x16x32_bf16 v[160:163], v[64:67], v[96:99], v[160:163]
	ds_read_b128 v[80:83], v220 offset:16384
	s_waitcnt lgkmcnt(6)
	v_mfma_f32_16x16x32_bf16 v[164:167], v[64:67], v[100:103], v[164:167]
	ds_read_b128 v[112:115], v224 offset:32768
	s_waitcnt lgkmcnt(6)
	v_mfma_f32_16x16x32_bf16 v[168:171], v[64:67], v[104:107], v[168:171]
	ds_read_b128 v[116:119], v224 offset:34816
	s_waitcnt lgkmcnt(6)
	v_mfma_f32_16x16x32_bf16 v[172:175], v[64:67], v[108:111], v[172:175]
	ds_read_b128 v[120:123], v224 offset:36864
	s_waitcnt lgkmcnt(6)
	v_mfma_f32_16x16x32_bf16 v[176:179], v[68:71], v[96:99], v[176:179]
	ds_read_b128 v[124:127], v224 offset:38912
	s_waitcnt lgkmcnt(7)
	v_mfma_f32_16x16x32_bf16 v[180:183], v[68:71], v[100:103], v[180:183]
	ds_read_b128 v[84:87], v220 offset:18432
	s_waitcnt lgkmcnt(8)
	v_mfma_f32_16x16x32_bf16 v[184:187], v[68:71], v[104:107], v[184:187]
	ds_read_b128 v[88:91], v220 offset:20480
	s_waitcnt lgkmcnt(9)
	v_mfma_f32_16x16x32_bf16 v[188:191], v[68:71], v[108:111], v[188:191]
	ds_read_b128 v[92:95], v220 offset:22528
	s_waitcnt lgkmcnt(9)
	v_mfma_f32_16x16x32_bf16 v[192:195], v[72:75], v[96:99], v[192:195]
	s_waitcnt lgkmcnt(9)
	v_mfma_f32_16x16x32_bf16 v[196:199], v[72:75], v[100:103], v[196:199]
	s_waitcnt lgkmcnt(9)
	v_mfma_f32_16x16x32_bf16 v[200:203], v[72:75], v[104:107], v[200:203]
	s_waitcnt lgkmcnt(9)
	v_mfma_f32_16x16x32_bf16 v[204:207], v[72:75], v[108:111], v[204:207]
	s_waitcnt vmcnt(0) lgkmcnt(0)
	s_barrier
	s_add_u32 m0, s38, 16384
	s_nop 0
	global_load_lds_dwordx4 v226, s[100:101]
	s_waitcnt lgkmcnt(8)
	v_mfma_f32_16x16x32_bf16 v[208:211], v[76:79], v[96:99], v[208:211]
	s_add_u32 m0, s38, 20480
	s_nop 0
	global_load_lds_dwordx4 v228, s[100:101]
	s_waitcnt lgkmcnt(8)
	v_mfma_f32_16x16x32_bf16 v[212:215], v[76:79], v[100:103], v[212:215]
	s_add_u32 m0, s38, 24576
	s_nop 0
	global_load_lds_dwordx4 v244, s[100:101]
	s_waitcnt lgkmcnt(8)
	v_mfma_f32_16x16x32_bf16 v[216:219], v[76:79], v[104:107], v[216:219]
	s_add_u32 m0, s38, 28672
	s_nop 0
	global_load_lds_dwordx4 v245, s[100:101]
	s_add_u32 s100, s100, 128
	s_addc_u32 s101, s101, 0
	s_waitcnt lgkmcnt(8)
	v_mfma_f32_16x16x32_bf16 v[230:233], v[76:79], v[108:111], v[230:233]
	s_add_u32 m0, s38, 32768
	s_nop 0
	global_load_lds_dwordx4 v226, s[4:5]
	s_waitcnt lgkmcnt(6)
	v_mfma_f32_16x16x32_bf16 v[160:163], v[80:83], v[112:115], v[160:163]
	ds_read_b128 v[64:67], v151 offset:0
	s_add_u32 m0, s38, 36864
	s_nop 0
	global_load_lds_dwordx4 v228, s[4:5]
	s_waitcnt lgkmcnt(6)
	v_mfma_f32_16x16x32_bf16 v[164:167], v[80:83], v[116:119], v[164:167]
	ds_read_b128 v[96:99], v222 offset:49152
	s_add_u32 m0, s38, 40960
	s_nop 0
	global_load_lds_dwordx4 v244, s[4:5]
	s_waitcnt lgkmcnt(6)
	v_mfma_f32_16x16x32_bf16 v[168:171], v[80:83], v[120:123], v[168:171]
	ds_read_b128 v[100:103], v222 offset:51200
	s_add_u32 m0, s38, 45056
	s_nop 0
	global_load_lds_dwordx4 v245, s[4:5]
	s_add_u32 s4, s4, 128
	s_addc_u32 s5, s5, 0
	s_waitcnt lgkmcnt(6)
	v_mfma_f32_16x16x32_bf16 v[172:175], v[80:83], v[124:127], v[172:175]
	ds_read_b128 v[104:107], v222 offset:53248
	s_waitcnt lgkmcnt(6)
	v_mfma_f32_16x16x32_bf16 v[176:179], v[84:87], v[112:115], v[176:179]
	ds_read_b128 v[108:111], v222 offset:55296
	s_waitcnt lgkmcnt(7)
	v_mfma_f32_16x16x32_bf16 v[180:183], v[84:87], v[116:119], v[180:183]
	ds_read_b128 v[68:71], v151 offset:2048
	s_waitcnt lgkmcnt(8)
	v_mfma_f32_16x16x32_bf16 v[184:187], v[84:87], v[120:123], v[184:187]
	ds_read_b128 v[72:75], v151 offset:4096
	s_waitcnt lgkmcnt(9)
	v_mfma_f32_16x16x32_bf16 v[188:191], v[84:87], v[124:127], v[188:191]
	ds_read_b128 v[76:79], v151 offset:6144
	s_waitcnt lgkmcnt(9)
	v_mfma_f32_16x16x32_bf16 v[192:195], v[88:91], v[112:115], v[192:195]
	s_waitcnt lgkmcnt(9)
	v_mfma_f32_16x16x32_bf16 v[196:199], v[88:91], v[116:119], v[196:199]
	s_waitcnt lgkmcnt(9)
	v_mfma_f32_16x16x32_bf16 v[200:203], v[88:91], v[120:123], v[200:203]
	s_waitcnt lgkmcnt(9)
	v_mfma_f32_16x16x32_bf16 v[204:207], v[88:91], v[124:127], v[204:207]
	s_waitcnt lgkmcnt(8)
	v_mfma_f32_16x16x32_bf16 v[208:211], v[92:95], v[112:115], v[208:211]
	s_waitcnt lgkmcnt(8)
	v_mfma_f32_16x16x32_bf16 v[212:215], v[92:95], v[116:119], v[212:215]
	s_waitcnt lgkmcnt(8)
	v_mfma_f32_16x16x32_bf16 v[216:219], v[92:95], v[120:123], v[216:219]
	s_waitcnt lgkmcnt(8)
	v_mfma_f32_16x16x32_bf16 v[230:233], v[92:95], v[124:127], v[230:233]
	s_waitcnt lgkmcnt(6)
	v_mfma_f32_16x16x32_bf16 v[0:3], v[64:67], v[96:99], v[0:3]
	ds_read_b128 v[80:83], v220 offset:0
	s_waitcnt lgkmcnt(6)
	v_mfma_f32_16x16x32_bf16 v[4:7], v[64:67], v[100:103], v[4:7]
	ds_read_b128 v[112:115], v224 offset:49152
	s_waitcnt lgkmcnt(6)
	v_mfma_f32_16x16x32_bf16 v[8:11], v[64:67], v[104:107], v[8:11]
	ds_read_b128 v[116:119], v224 offset:51200
	s_waitcnt lgkmcnt(6)
	v_mfma_f32_16x16x32_bf16 v[12:15], v[64:67], v[108:111], v[12:15]
	ds_read_b128 v[120:123], v224 offset:53248
	s_waitcnt lgkmcnt(6)
	v_mfma_f32_16x16x32_bf16 v[16:19], v[68:71], v[96:99], v[16:19]
	ds_read_b128 v[124:127], v224 offset:55296
	s_waitcnt lgkmcnt(7)
	v_mfma_f32_16x16x32_bf16 v[20:23], v[68:71], v[100:103], v[20:23]
	ds_read_b128 v[84:87], v220 offset:2048
	s_waitcnt lgkmcnt(8)
	v_mfma_f32_16x16x32_bf16 v[24:27], v[68:71], v[104:107], v[24:27]
	ds_read_b128 v[88:91], v220 offset:4096
	s_waitcnt lgkmcnt(9)
	v_mfma_f32_16x16x32_bf16 v[28:31], v[68:71], v[108:111], v[28:31]
	ds_read_b128 v[92:95], v220 offset:6144
	s_waitcnt lgkmcnt(9)
	v_mfma_f32_16x16x32_bf16 v[32:35], v[72:75], v[96:99], v[32:35]
	s_waitcnt lgkmcnt(9)
	v_mfma_f32_16x16x32_bf16 v[36:39], v[72:75], v[100:103], v[36:39]
	s_waitcnt lgkmcnt(9)
	v_mfma_f32_16x16x32_bf16 v[40:43], v[72:75], v[104:107], v[40:43]
	s_waitcnt lgkmcnt(9)
	v_mfma_f32_16x16x32_bf16 v[44:47], v[72:75], v[108:111], v[44:47]
	s_waitcnt vmcnt(4) lgkmcnt(0)
	s_barrier
	s_add_u32 m0, s38, 0
	s_nop 0
	global_load_lds_dwordx4 v226, s[98:99]
	s_waitcnt lgkmcnt(8)
	v_mfma_f32_16x16x32_bf16 v[48:51], v[76:79], v[96:99], v[48:51]
	s_add_u32 m0, s38, 4096
	s_nop 0
	global_load_lds_dwordx4 v228, s[98:99]
	s_waitcnt lgkmcnt(8)
	v_mfma_f32_16x16x32_bf16 v[52:55], v[76:79], v[100:103], v[52:55]
	s_add_u32 m0, s38, 8192
	s_nop 0
	global_load_lds_dwordx4 v244, s[98:99]
	s_waitcnt lgkmcnt(8)
	v_mfma_f32_16x16x32_bf16 v[56:59], v[76:79], v[104:107], v[56:59]
	s_add_u32 m0, s38, 12288
	s_nop 0
	global_load_lds_dwordx4 v245, s[98:99]
	s_add_u32 s98, s98, 128
	s_addc_u32 s99, s99, 0
	s_waitcnt lgkmcnt(8)
	v_mfma_f32_16x16x32_bf16 v[60:63], v[76:79], v[108:111], v[60:63]
	s_waitcnt lgkmcnt(6)
	v_mfma_f32_16x16x32_bf16 v[0:3], v[80:83], v[112:115], v[0:3]
	ds_read_b128 v[64:67], v151 offset:16384
	s_waitcnt lgkmcnt(6)
	v_mfma_f32_16x16x32_bf16 v[4:7], v[80:83], v[116:119], v[4:7]
	ds_read_b128 v[96:99], v222 offset:49152
	s_waitcnt lgkmcnt(6)
	v_mfma_f32_16x16x32_bf16 v[8:11], v[80:83], v[120:123], v[8:11]
	ds_read_b128 v[100:103], v222 offset:51200
	s_waitcnt lgkmcnt(6)
	v_mfma_f32_16x16x32_bf16 v[12:15], v[80:83], v[124:127], v[12:15]
	ds_read_b128 v[104:107], v222 offset:53248
	s_waitcnt lgkmcnt(6)
	v_mfma_f32_16x16x32_bf16 v[16:19], v[84:87], v[112:115], v[16:19]
	ds_read_b128 v[108:111], v222 offset:55296
	s_waitcnt lgkmcnt(7)
	v_mfma_f32_16x16x32_bf16 v[20:23], v[84:87], v[116:119], v[20:23]
	ds_read_b128 v[68:71], v151 offset:18432
	s_waitcnt lgkmcnt(8)
	v_mfma_f32_16x16x32_bf16 v[24:27], v[84:87], v[120:123], v[24:27]
	ds_read_b128 v[72:75], v151 offset:20480
	s_waitcnt lgkmcnt(9)
	v_mfma_f32_16x16x32_bf16 v[28:31], v[84:87], v[124:127], v[28:31]
	ds_read_b128 v[76:79], v151 offset:22528
	s_waitcnt lgkmcnt(9)
	v_mfma_f32_16x16x32_bf16 v[32:35], v[88:91], v[112:115], v[32:35]
	s_waitcnt lgkmcnt(9)
	v_mfma_f32_16x16x32_bf16 v[36:39], v[88:91], v[116:119], v[36:39]
	s_waitcnt lgkmcnt(9)
	v_mfma_f32_16x16x32_bf16 v[40:43], v[88:91], v[120:123], v[40:43]
	s_waitcnt lgkmcnt(9)
	v_mfma_f32_16x16x32_bf16 v[44:47], v[88:91], v[124:127], v[44:47]
	s_waitcnt lgkmcnt(8)
	v_mfma_f32_16x16x32_bf16 v[48:51], v[92:95], v[112:115], v[48:51]
	s_waitcnt lgkmcnt(8)
	v_mfma_f32_16x16x32_bf16 v[52:55], v[92:95], v[116:119], v[52:55]
	s_waitcnt lgkmcnt(8)
	v_mfma_f32_16x16x32_bf16 v[56:59], v[92:95], v[120:123], v[56:59]
	s_waitcnt lgkmcnt(8)
	v_mfma_f32_16x16x32_bf16 v[60:63], v[92:95], v[124:127], v[60:63]
	s_waitcnt lgkmcnt(6)
	v_mfma_f32_16x16x32_bf16 v[160:163], v[64:67], v[96:99], v[160:163]
	ds_read_b128 v[80:83], v220 offset:16384
	s_waitcnt lgkmcnt(6)
	v_mfma_f32_16x16x32_bf16 v[164:167], v[64:67], v[100:103], v[164:167]
	ds_read_b128 v[112:115], v224 offset:49152
	s_waitcnt lgkmcnt(6)
	v_mfma_f32_16x16x32_bf16 v[168:171], v[64:67], v[104:107], v[168:171]
	ds_read_b128 v[116:119], v224 offset:51200
	s_waitcnt lgkmcnt(6)
	v_mfma_f32_16x16x32_bf16 v[172:175], v[64:67], v[108:111], v[172:175]
	ds_read_b128 v[120:123], v224 offset:53248
	s_waitcnt lgkmcnt(6)
	v_mfma_f32_16x16x32_bf16 v[176:179], v[68:71], v[96:99], v[176:179]
	ds_read_b128 v[124:127], v224 offset:55296
	s_waitcnt lgkmcnt(7)
	v_mfma_f32_16x16x32_bf16 v[180:183], v[68:71], v[100:103], v[180:183]
	ds_read_b128 v[84:87], v220 offset:18432
	s_waitcnt lgkmcnt(8)
	v_mfma_f32_16x16x32_bf16 v[184:187], v[68:71], v[104:107], v[184:187]
	ds_read_b128 v[88:91], v220 offset:20480
	s_waitcnt lgkmcnt(9)
	v_mfma_f32_16x16x32_bf16 v[188:191], v[68:71], v[108:111], v[188:191]
	ds_read_b128 v[92:95], v220 offset:22528
	s_waitcnt lgkmcnt(9)
	v_mfma_f32_16x16x32_bf16 v[192:195], v[72:75], v[96:99], v[192:195]
	s_waitcnt lgkmcnt(9)
	v_mfma_f32_16x16x32_bf16 v[196:199], v[72:75], v[100:103], v[196:199]
	s_waitcnt lgkmcnt(9)
	v_mfma_f32_16x16x32_bf16 v[200:203], v[72:75], v[104:107], v[200:203]
	s_waitcnt lgkmcnt(9)
	v_mfma_f32_16x16x32_bf16 v[204:207], v[72:75], v[108:111], v[204:207]
	s_waitcnt vmcnt(0) lgkmcnt(0)
	s_barrier
	s_add_u32 m0, s38, 16384
	s_nop 0
	global_load_lds_dwordx4 v226, s[100:101]
	s_waitcnt lgkmcnt(8)
	v_mfma_f32_16x16x32_bf16 v[208:211], v[76:79], v[96:99], v[208:211]
	s_add_u32 m0, s38, 20480
	s_nop 0
	global_load_lds_dwordx4 v228, s[100:101]
	s_waitcnt lgkmcnt(8)
	v_mfma_f32_16x16x32_bf16 v[212:215], v[76:79], v[100:103], v[212:215]
	s_add_u32 m0, s38, 24576
	s_nop 0
	global_load_lds_dwordx4 v244, s[100:101]
	s_waitcnt lgkmcnt(8)
	v_mfma_f32_16x16x32_bf16 v[216:219], v[76:79], v[104:107], v[216:219]
	s_add_u32 m0, s38, 28672
	s_nop 0
	global_load_lds_dwordx4 v245, s[100:101]
	s_add_u32 s100, s100, 128
	s_addc_u32 s101, s101, 0
	s_waitcnt lgkmcnt(8)
	v_mfma_f32_16x16x32_bf16 v[230:233], v[76:79], v[108:111], v[230:233]
	s_add_u32 m0, s38, 49152
	s_nop 0
	global_load_lds_dwordx4 v226, s[4:5]
	s_waitcnt lgkmcnt(6)
	v_mfma_f32_16x16x32_bf16 v[160:163], v[80:83], v[112:115], v[160:163]
	ds_read_b128 v[64:67], v151 offset:0
	s_add_u32 m0, s38, 53248
	s_nop 0
	global_load_lds_dwordx4 v228, s[4:5]
	s_waitcnt lgkmcnt(6)
	v_mfma_f32_16x16x32_bf16 v[164:167], v[80:83], v[116:119], v[164:167]
	ds_read_b128 v[96:99], v222 offset:32768
	s_add_u32 m0, s38, 57344
	s_nop 0
	global_load_lds_dwordx4 v244, s[4:5]
	s_waitcnt lgkmcnt(6)
	v_mfma_f32_16x16x32_bf16 v[168:171], v[80:83], v[120:123], v[168:171]
	ds_read_b128 v[100:103], v222 offset:34816
	s_add_u32 m0, s38, 61440
	s_nop 0
	global_load_lds_dwordx4 v245, s[4:5]
	s_add_u32 s4, s4, 128
	s_addc_u32 s5, s5, 0
	s_waitcnt lgkmcnt(6)
	v_mfma_f32_16x16x32_bf16 v[172:175], v[80:83], v[124:127], v[172:175]
	ds_read_b128 v[104:107], v222 offset:36864
	s_waitcnt lgkmcnt(6)
	v_mfma_f32_16x16x32_bf16 v[176:179], v[84:87], v[112:115], v[176:179]
	ds_read_b128 v[108:111], v222 offset:38912
	s_waitcnt lgkmcnt(7)
	v_mfma_f32_16x16x32_bf16 v[180:183], v[84:87], v[116:119], v[180:183]
	ds_read_b128 v[68:71], v151 offset:2048
	s_waitcnt lgkmcnt(8)
	v_mfma_f32_16x16x32_bf16 v[184:187], v[84:87], v[120:123], v[184:187]
	ds_read_b128 v[72:75], v151 offset:4096
	s_waitcnt lgkmcnt(9)
	v_mfma_f32_16x16x32_bf16 v[188:191], v[84:87], v[124:127], v[188:191]
	ds_read_b128 v[76:79], v151 offset:6144
	s_waitcnt lgkmcnt(9)
	v_mfma_f32_16x16x32_bf16 v[192:195], v[88:91], v[112:115], v[192:195]
	s_waitcnt lgkmcnt(9)
	v_mfma_f32_16x16x32_bf16 v[196:199], v[88:91], v[116:119], v[196:199]
	s_waitcnt lgkmcnt(9)
	v_mfma_f32_16x16x32_bf16 v[200:203], v[88:91], v[120:123], v[200:203]
	s_waitcnt lgkmcnt(9)
	v_mfma_f32_16x16x32_bf16 v[204:207], v[88:91], v[124:127], v[204:207]
	s_waitcnt lgkmcnt(8)
	v_mfma_f32_16x16x32_bf16 v[208:211], v[92:95], v[112:115], v[208:211]
	s_waitcnt lgkmcnt(8)
	v_mfma_f32_16x16x32_bf16 v[212:215], v[92:95], v[116:119], v[212:215]
	s_waitcnt lgkmcnt(8)
	v_mfma_f32_16x16x32_bf16 v[216:219], v[92:95], v[120:123], v[216:219]
	s_waitcnt lgkmcnt(8)
	v_mfma_f32_16x16x32_bf16 v[230:233], v[92:95], v[124:127], v[230:233]
	s_waitcnt lgkmcnt(6)
	v_mfma_f32_16x16x32_bf16 v[0:3], v[64:67], v[96:99], v[0:3]
	ds_read_b128 v[80:83], v220 offset:0
	s_waitcnt lgkmcnt(6)
	v_mfma_f32_16x16x32_bf16 v[4:7], v[64:67], v[100:103], v[4:7]
	ds_read_b128 v[112:115], v224 offset:32768
	s_waitcnt lgkmcnt(6)
	v_mfma_f32_16x16x32_bf16 v[8:11], v[64:67], v[104:107], v[8:11]
	ds_read_b128 v[116:119], v224 offset:34816
	s_waitcnt lgkmcnt(6)
	v_mfma_f32_16x16x32_bf16 v[12:15], v[64:67], v[108:111], v[12:15]
	ds_read_b128 v[120:123], v224 offset:36864
	s_waitcnt lgkmcnt(6)
	v_mfma_f32_16x16x32_bf16 v[16:19], v[68:71], v[96:99], v[16:19]
	ds_read_b128 v[124:127], v224 offset:38912
	s_waitcnt lgkmcnt(7)
	v_mfma_f32_16x16x32_bf16 v[20:23], v[68:71], v[100:103], v[20:23]
	ds_read_b128 v[84:87], v220 offset:2048
	s_waitcnt lgkmcnt(8)
	v_mfma_f32_16x16x32_bf16 v[24:27], v[68:71], v[104:107], v[24:27]
	ds_read_b128 v[88:91], v220 offset:4096
	s_waitcnt lgkmcnt(9)
	v_mfma_f32_16x16x32_bf16 v[28:31], v[68:71], v[108:111], v[28:31]
	ds_read_b128 v[92:95], v220 offset:6144
	s_waitcnt lgkmcnt(9)
	v_mfma_f32_16x16x32_bf16 v[32:35], v[72:75], v[96:99], v[32:35]
	s_waitcnt lgkmcnt(9)
	v_mfma_f32_16x16x32_bf16 v[36:39], v[72:75], v[100:103], v[36:39]
	s_waitcnt lgkmcnt(9)
	v_mfma_f32_16x16x32_bf16 v[40:43], v[72:75], v[104:107], v[40:43]
	s_waitcnt lgkmcnt(9)
	v_mfma_f32_16x16x32_bf16 v[44:47], v[72:75], v[108:111], v[44:47]
	s_waitcnt vmcnt(4) lgkmcnt(0)
	s_barrier
	s_add_u32 m0, s38, 0
	s_nop 0
	global_load_lds_dwordx4 v226, s[98:99]
	s_waitcnt lgkmcnt(8)
	v_mfma_f32_16x16x32_bf16 v[48:51], v[76:79], v[96:99], v[48:51]
	s_add_u32 m0, s38, 4096
	s_nop 0
	global_load_lds_dwordx4 v228, s[98:99]
	s_waitcnt lgkmcnt(8)
	v_mfma_f32_16x16x32_bf16 v[52:55], v[76:79], v[100:103], v[52:55]
	s_add_u32 m0, s38, 8192
	s_nop 0
	global_load_lds_dwordx4 v244, s[98:99]
	s_waitcnt lgkmcnt(8)
	v_mfma_f32_16x16x32_bf16 v[56:59], v[76:79], v[104:107], v[56:59]
	s_add_u32 m0, s38, 12288
	s_nop 0
	global_load_lds_dwordx4 v245, s[98:99]
	s_add_u32 s98, s98, 128
	s_addc_u32 s99, s99, 0
	s_waitcnt lgkmcnt(8)
	v_mfma_f32_16x16x32_bf16 v[60:63], v[76:79], v[108:111], v[60:63]
	s_waitcnt lgkmcnt(6)
	v_mfma_f32_16x16x32_bf16 v[0:3], v[80:83], v[112:115], v[0:3]
	ds_read_b128 v[64:67], v151 offset:16384
	s_waitcnt lgkmcnt(6)
	v_mfma_f32_16x16x32_bf16 v[4:7], v[80:83], v[116:119], v[4:7]
	ds_read_b128 v[96:99], v222 offset:32768
	s_waitcnt lgkmcnt(6)
	v_mfma_f32_16x16x32_bf16 v[8:11], v[80:83], v[120:123], v[8:11]
	ds_read_b128 v[100:103], v222 offset:34816
	s_waitcnt lgkmcnt(6)
	v_mfma_f32_16x16x32_bf16 v[12:15], v[80:83], v[124:127], v[12:15]
	ds_read_b128 v[104:107], v222 offset:36864
	s_waitcnt lgkmcnt(6)
	v_mfma_f32_16x16x32_bf16 v[16:19], v[84:87], v[112:115], v[16:19]
	ds_read_b128 v[108:111], v222 offset:38912
	s_waitcnt lgkmcnt(7)
	v_mfma_f32_16x16x32_bf16 v[20:23], v[84:87], v[116:119], v[20:23]
	ds_read_b128 v[68:71], v151 offset:18432
	s_waitcnt lgkmcnt(8)
	v_mfma_f32_16x16x32_bf16 v[24:27], v[84:87], v[120:123], v[24:27]
	ds_read_b128 v[72:75], v151 offset:20480
	s_waitcnt lgkmcnt(9)
	v_mfma_f32_16x16x32_bf16 v[28:31], v[84:87], v[124:127], v[28:31]
	ds_read_b128 v[76:79], v151 offset:22528
	s_waitcnt lgkmcnt(9)
	v_mfma_f32_16x16x32_bf16 v[32:35], v[88:91], v[112:115], v[32:35]
	s_waitcnt lgkmcnt(9)
	v_mfma_f32_16x16x32_bf16 v[36:39], v[88:91], v[116:119], v[36:39]
	s_waitcnt lgkmcnt(9)
	v_mfma_f32_16x16x32_bf16 v[40:43], v[88:91], v[120:123], v[40:43]
	s_waitcnt lgkmcnt(9)
	v_mfma_f32_16x16x32_bf16 v[44:47], v[88:91], v[124:127], v[44:47]
	s_waitcnt lgkmcnt(8)
	v_mfma_f32_16x16x32_bf16 v[48:51], v[92:95], v[112:115], v[48:51]
	s_waitcnt lgkmcnt(8)
	v_mfma_f32_16x16x32_bf16 v[52:55], v[92:95], v[116:119], v[52:55]
	s_waitcnt lgkmcnt(8)
	v_mfma_f32_16x16x32_bf16 v[56:59], v[92:95], v[120:123], v[56:59]
	s_waitcnt lgkmcnt(8)
	v_mfma_f32_16x16x32_bf16 v[60:63], v[92:95], v[124:127], v[60:63]
	s_waitcnt lgkmcnt(6)
	v_mfma_f32_16x16x32_bf16 v[160:163], v[64:67], v[96:99], v[160:163]
	ds_read_b128 v[80:83], v220 offset:16384
	s_waitcnt lgkmcnt(6)
	v_mfma_f32_16x16x32_bf16 v[164:167], v[64:67], v[100:103], v[164:167]
	ds_read_b128 v[112:115], v224 offset:32768
	s_waitcnt lgkmcnt(6)
	v_mfma_f32_16x16x32_bf16 v[168:171], v[64:67], v[104:107], v[168:171]
	ds_read_b128 v[116:119], v224 offset:34816
	s_waitcnt lgkmcnt(6)
	v_mfma_f32_16x16x32_bf16 v[172:175], v[64:67], v[108:111], v[172:175]
	ds_read_b128 v[120:123], v224 offset:36864
	s_waitcnt lgkmcnt(6)
	v_mfma_f32_16x16x32_bf16 v[176:179], v[68:71], v[96:99], v[176:179]
	ds_read_b128 v[124:127], v224 offset:38912
	s_waitcnt lgkmcnt(7)
	v_mfma_f32_16x16x32_bf16 v[180:183], v[68:71], v[100:103], v[180:183]
	ds_read_b128 v[84:87], v220 offset:18432
	s_waitcnt lgkmcnt(8)
	v_mfma_f32_16x16x32_bf16 v[184:187], v[68:71], v[104:107], v[184:187]
	ds_read_b128 v[88:91], v220 offset:20480
	s_waitcnt lgkmcnt(9)
	v_mfma_f32_16x16x32_bf16 v[188:191], v[68:71], v[108:111], v[188:191]
	ds_read_b128 v[92:95], v220 offset:22528
	s_waitcnt lgkmcnt(9)
	v_mfma_f32_16x16x32_bf16 v[192:195], v[72:75], v[96:99], v[192:195]
	s_waitcnt lgkmcnt(9)
	v_mfma_f32_16x16x32_bf16 v[196:199], v[72:75], v[100:103], v[196:199]
	s_waitcnt lgkmcnt(9)
	v_mfma_f32_16x16x32_bf16 v[200:203], v[72:75], v[104:107], v[200:203]
	s_waitcnt lgkmcnt(9)
	v_mfma_f32_16x16x32_bf16 v[204:207], v[72:75], v[108:111], v[204:207]
	s_waitcnt vmcnt(0) lgkmcnt(0)
	s_barrier
	s_add_u32 m0, s38, 16384
	s_nop 0
	global_load_lds_dwordx4 v226, s[100:101]
	s_waitcnt lgkmcnt(8)
	v_mfma_f32_16x16x32_bf16 v[208:211], v[76:79], v[96:99], v[208:211]
	s_add_u32 m0, s38, 20480
	s_nop 0
	global_load_lds_dwordx4 v228, s[100:101]
	s_waitcnt lgkmcnt(8)
	v_mfma_f32_16x16x32_bf16 v[212:215], v[76:79], v[100:103], v[212:215]
	s_add_u32 m0, s38, 24576
	s_nop 0
	global_load_lds_dwordx4 v244, s[100:101]
	s_waitcnt lgkmcnt(8)
	v_mfma_f32_16x16x32_bf16 v[216:219], v[76:79], v[104:107], v[216:219]
	s_add_u32 m0, s38, 28672
	s_nop 0
	global_load_lds_dwordx4 v245, s[100:101]
	s_add_u32 s100, s100, 128
	s_addc_u32 s101, s101, 0
	s_waitcnt lgkmcnt(8)
	v_mfma_f32_16x16x32_bf16 v[230:233], v[76:79], v[108:111], v[230:233]
	s_add_u32 m0, s38, 32768
	s_nop 0
	global_load_lds_dwordx4 v226, s[4:5]
	s_waitcnt lgkmcnt(6)
	v_mfma_f32_16x16x32_bf16 v[160:163], v[80:83], v[112:115], v[160:163]
	ds_read_b128 v[64:67], v151 offset:0
	s_add_u32 m0, s38, 36864
	s_nop 0
	global_load_lds_dwordx4 v228, s[4:5]
	s_waitcnt lgkmcnt(6)
	v_mfma_f32_16x16x32_bf16 v[164:167], v[80:83], v[116:119], v[164:167]
	ds_read_b128 v[96:99], v222 offset:49152
	s_add_u32 m0, s38, 40960
	s_nop 0
	global_load_lds_dwordx4 v244, s[4:5]
	s_waitcnt lgkmcnt(6)
	v_mfma_f32_16x16x32_bf16 v[168:171], v[80:83], v[120:123], v[168:171]
	ds_read_b128 v[100:103], v222 offset:51200
	s_add_u32 m0, s38, 45056
	s_nop 0
	global_load_lds_dwordx4 v245, s[4:5]
	s_add_u32 s4, s4, 128
	s_addc_u32 s5, s5, 0
	s_waitcnt lgkmcnt(6)
	v_mfma_f32_16x16x32_bf16 v[172:175], v[80:83], v[124:127], v[172:175]
	ds_read_b128 v[104:107], v222 offset:53248
	s_waitcnt lgkmcnt(6)
	v_mfma_f32_16x16x32_bf16 v[176:179], v[84:87], v[112:115], v[176:179]
	ds_read_b128 v[108:111], v222 offset:55296
	s_waitcnt lgkmcnt(7)
	v_mfma_f32_16x16x32_bf16 v[180:183], v[84:87], v[116:119], v[180:183]
	ds_read_b128 v[68:71], v151 offset:2048
	s_waitcnt lgkmcnt(8)
	v_mfma_f32_16x16x32_bf16 v[184:187], v[84:87], v[120:123], v[184:187]
	ds_read_b128 v[72:75], v151 offset:4096
	s_waitcnt lgkmcnt(9)
	v_mfma_f32_16x16x32_bf16 v[188:191], v[84:87], v[124:127], v[188:191]
	ds_read_b128 v[76:79], v151 offset:6144
	s_waitcnt lgkmcnt(9)
	v_mfma_f32_16x16x32_bf16 v[192:195], v[88:91], v[112:115], v[192:195]
	s_waitcnt lgkmcnt(9)
	v_mfma_f32_16x16x32_bf16 v[196:199], v[88:91], v[116:119], v[196:199]
	s_waitcnt lgkmcnt(9)
	v_mfma_f32_16x16x32_bf16 v[200:203], v[88:91], v[120:123], v[200:203]
	s_waitcnt lgkmcnt(9)
	v_mfma_f32_16x16x32_bf16 v[204:207], v[88:91], v[124:127], v[204:207]
	s_waitcnt lgkmcnt(8)
	v_mfma_f32_16x16x32_bf16 v[208:211], v[92:95], v[112:115], v[208:211]
	s_waitcnt lgkmcnt(8)
	v_mfma_f32_16x16x32_bf16 v[212:215], v[92:95], v[116:119], v[212:215]
	s_waitcnt lgkmcnt(8)
	v_mfma_f32_16x16x32_bf16 v[216:219], v[92:95], v[120:123], v[216:219]
	s_waitcnt lgkmcnt(8)
	v_mfma_f32_16x16x32_bf16 v[230:233], v[92:95], v[124:127], v[230:233]
	s_waitcnt lgkmcnt(6)
	v_mfma_f32_16x16x32_bf16 v[0:3], v[64:67], v[96:99], v[0:3]
	ds_read_b128 v[80:83], v220 offset:0
	s_waitcnt lgkmcnt(6)
	v_mfma_f32_16x16x32_bf16 v[4:7], v[64:67], v[100:103], v[4:7]
	ds_read_b128 v[112:115], v224 offset:49152
	s_waitcnt lgkmcnt(6)
	v_mfma_f32_16x16x32_bf16 v[8:11], v[64:67], v[104:107], v[8:11]
	ds_read_b128 v[116:119], v224 offset:51200
	s_waitcnt lgkmcnt(6)
	v_mfma_f32_16x16x32_bf16 v[12:15], v[64:67], v[108:111], v[12:15]
	ds_read_b128 v[120:123], v224 offset:53248
	s_waitcnt lgkmcnt(6)
	v_mfma_f32_16x16x32_bf16 v[16:19], v[68:71], v[96:99], v[16:19]
	ds_read_b128 v[124:127], v224 offset:55296
	s_waitcnt lgkmcnt(7)
	v_mfma_f32_16x16x32_bf16 v[20:23], v[68:71], v[100:103], v[20:23]
	ds_read_b128 v[84:87], v220 offset:2048
	s_waitcnt lgkmcnt(8)
	v_mfma_f32_16x16x32_bf16 v[24:27], v[68:71], v[104:107], v[24:27]
	ds_read_b128 v[88:91], v220 offset:4096
	s_waitcnt lgkmcnt(9)
	v_mfma_f32_16x16x32_bf16 v[28:31], v[68:71], v[108:111], v[28:31]
	ds_read_b128 v[92:95], v220 offset:6144
	s_waitcnt lgkmcnt(9)
	v_mfma_f32_16x16x32_bf16 v[32:35], v[72:75], v[96:99], v[32:35]
	s_waitcnt lgkmcnt(9)
	v_mfma_f32_16x16x32_bf16 v[36:39], v[72:75], v[100:103], v[36:39]
	s_waitcnt lgkmcnt(9)
	v_mfma_f32_16x16x32_bf16 v[40:43], v[72:75], v[104:107], v[40:43]
	s_waitcnt lgkmcnt(9)
	v_mfma_f32_16x16x32_bf16 v[44:47], v[72:75], v[108:111], v[44:47]
	s_waitcnt vmcnt(4) lgkmcnt(0)
	s_barrier
	s_add_u32 m0, s38, 0
	s_nop 0
	global_load_lds_dwordx4 v226, s[98:99]
	s_waitcnt lgkmcnt(8)
	v_mfma_f32_16x16x32_bf16 v[48:51], v[76:79], v[96:99], v[48:51]
	s_add_u32 m0, s38, 4096
	s_nop 0
	global_load_lds_dwordx4 v228, s[98:99]
	s_waitcnt lgkmcnt(8)
	v_mfma_f32_16x16x32_bf16 v[52:55], v[76:79], v[100:103], v[52:55]
	s_add_u32 m0, s38, 8192
	s_nop 0
	global_load_lds_dwordx4 v244, s[98:99]
	s_waitcnt lgkmcnt(8)
	v_mfma_f32_16x16x32_bf16 v[56:59], v[76:79], v[104:107], v[56:59]
	s_add_u32 m0, s38, 12288
	s_nop 0
	global_load_lds_dwordx4 v245, s[98:99]
	s_add_u32 s98, s98, 128
	s_addc_u32 s99, s99, 0
	s_waitcnt lgkmcnt(8)
	v_mfma_f32_16x16x32_bf16 v[60:63], v[76:79], v[108:111], v[60:63]
	s_waitcnt lgkmcnt(6)
	v_mfma_f32_16x16x32_bf16 v[0:3], v[80:83], v[112:115], v[0:3]
	ds_read_b128 v[64:67], v151 offset:16384
	s_waitcnt lgkmcnt(6)
	v_mfma_f32_16x16x32_bf16 v[4:7], v[80:83], v[116:119], v[4:7]
	ds_read_b128 v[96:99], v222 offset:49152
	s_waitcnt lgkmcnt(6)
	v_mfma_f32_16x16x32_bf16 v[8:11], v[80:83], v[120:123], v[8:11]
	ds_read_b128 v[100:103], v222 offset:51200
	s_waitcnt lgkmcnt(6)
	v_mfma_f32_16x16x32_bf16 v[12:15], v[80:83], v[124:127], v[12:15]
	ds_read_b128 v[104:107], v222 offset:53248
	s_waitcnt lgkmcnt(6)
	v_mfma_f32_16x16x32_bf16 v[16:19], v[84:87], v[112:115], v[16:19]
	ds_read_b128 v[108:111], v222 offset:55296
	s_waitcnt lgkmcnt(7)
	v_mfma_f32_16x16x32_bf16 v[20:23], v[84:87], v[116:119], v[20:23]
	ds_read_b128 v[68:71], v151 offset:18432
	s_waitcnt lgkmcnt(8)
	v_mfma_f32_16x16x32_bf16 v[24:27], v[84:87], v[120:123], v[24:27]
	ds_read_b128 v[72:75], v151 offset:20480
	s_waitcnt lgkmcnt(9)
	v_mfma_f32_16x16x32_bf16 v[28:31], v[84:87], v[124:127], v[28:31]
	ds_read_b128 v[76:79], v151 offset:22528
	s_waitcnt lgkmcnt(9)
	v_mfma_f32_16x16x32_bf16 v[32:35], v[88:91], v[112:115], v[32:35]
	s_waitcnt lgkmcnt(9)
	v_mfma_f32_16x16x32_bf16 v[36:39], v[88:91], v[116:119], v[36:39]
	s_waitcnt lgkmcnt(9)
	v_mfma_f32_16x16x32_bf16 v[40:43], v[88:91], v[120:123], v[40:43]
	s_waitcnt lgkmcnt(9)
	v_mfma_f32_16x16x32_bf16 v[44:47], v[88:91], v[124:127], v[44:47]
	s_waitcnt lgkmcnt(8)
	v_mfma_f32_16x16x32_bf16 v[48:51], v[92:95], v[112:115], v[48:51]
	s_waitcnt lgkmcnt(8)
	v_mfma_f32_16x16x32_bf16 v[52:55], v[92:95], v[116:119], v[52:55]
	s_waitcnt lgkmcnt(8)
	v_mfma_f32_16x16x32_bf16 v[56:59], v[92:95], v[120:123], v[56:59]
	s_waitcnt lgkmcnt(8)
	v_mfma_f32_16x16x32_bf16 v[60:63], v[92:95], v[124:127], v[60:63]
	s_waitcnt lgkmcnt(6)
	v_mfma_f32_16x16x32_bf16 v[160:163], v[64:67], v[96:99], v[160:163]
	ds_read_b128 v[80:83], v220 offset:16384
	s_waitcnt lgkmcnt(6)
	v_mfma_f32_16x16x32_bf16 v[164:167], v[64:67], v[100:103], v[164:167]
	ds_read_b128 v[112:115], v224 offset:49152
	s_waitcnt lgkmcnt(6)
	v_mfma_f32_16x16x32_bf16 v[168:171], v[64:67], v[104:107], v[168:171]
	ds_read_b128 v[116:119], v224 offset:51200
	s_waitcnt lgkmcnt(6)
	v_mfma_f32_16x16x32_bf16 v[172:175], v[64:67], v[108:111], v[172:175]
	ds_read_b128 v[120:123], v224 offset:53248
	s_waitcnt lgkmcnt(6)
	v_mfma_f32_16x16x32_bf16 v[176:179], v[68:71], v[96:99], v[176:179]
	ds_read_b128 v[124:127], v224 offset:55296
	s_waitcnt lgkmcnt(7)
	v_mfma_f32_16x16x32_bf16 v[180:183], v[68:71], v[100:103], v[180:183]
	ds_read_b128 v[84:87], v220 offset:18432
	s_waitcnt lgkmcnt(8)
	v_mfma_f32_16x16x32_bf16 v[184:187], v[68:71], v[104:107], v[184:187]
	ds_read_b128 v[88:91], v220 offset:20480
	s_waitcnt lgkmcnt(9)
	v_mfma_f32_16x16x32_bf16 v[188:191], v[68:71], v[108:111], v[188:191]
	ds_read_b128 v[92:95], v220 offset:22528
	s_waitcnt lgkmcnt(9)
	v_mfma_f32_16x16x32_bf16 v[192:195], v[72:75], v[96:99], v[192:195]
	s_waitcnt lgkmcnt(9)
	v_mfma_f32_16x16x32_bf16 v[196:199], v[72:75], v[100:103], v[196:199]
	s_waitcnt lgkmcnt(9)
	v_mfma_f32_16x16x32_bf16 v[200:203], v[72:75], v[104:107], v[200:203]
	s_waitcnt lgkmcnt(9)
	v_mfma_f32_16x16x32_bf16 v[204:207], v[72:75], v[108:111], v[204:207]
	s_waitcnt vmcnt(0) lgkmcnt(0)
	s_barrier
	s_add_u32 m0, s38, 16384
	s_nop 0
	global_load_lds_dwordx4 v226, s[100:101]
	s_waitcnt lgkmcnt(8)
	v_mfma_f32_16x16x32_bf16 v[208:211], v[76:79], v[96:99], v[208:211]
	s_add_u32 m0, s38, 20480
	s_nop 0
	global_load_lds_dwordx4 v228, s[100:101]
	s_waitcnt lgkmcnt(8)
	v_mfma_f32_16x16x32_bf16 v[212:215], v[76:79], v[100:103], v[212:215]
	s_add_u32 m0, s38, 24576
	s_nop 0
	global_load_lds_dwordx4 v244, s[100:101]
	s_waitcnt lgkmcnt(8)
	v_mfma_f32_16x16x32_bf16 v[216:219], v[76:79], v[104:107], v[216:219]
	s_add_u32 m0, s38, 28672
	s_nop 0
	global_load_lds_dwordx4 v245, s[100:101]
	s_add_u32 s100, s100, 128
	s_addc_u32 s101, s101, 0
	s_waitcnt lgkmcnt(8)
	v_mfma_f32_16x16x32_bf16 v[230:233], v[76:79], v[108:111], v[230:233]
	s_add_u32 m0, s38, 49152
	s_nop 0
	global_load_lds_dwordx4 v226, s[4:5]
	s_waitcnt lgkmcnt(6)
	v_mfma_f32_16x16x32_bf16 v[160:163], v[80:83], v[112:115], v[160:163]
	ds_read_b128 v[64:67], v151 offset:0
	s_add_u32 m0, s38, 53248
	s_nop 0
	global_load_lds_dwordx4 v228, s[4:5]
	s_waitcnt lgkmcnt(6)
	v_mfma_f32_16x16x32_bf16 v[164:167], v[80:83], v[116:119], v[164:167]
	ds_read_b128 v[96:99], v222 offset:32768
	s_add_u32 m0, s38, 57344
	s_nop 0
	global_load_lds_dwordx4 v244, s[4:5]
	s_waitcnt lgkmcnt(6)
	v_mfma_f32_16x16x32_bf16 v[168:171], v[80:83], v[120:123], v[168:171]
	ds_read_b128 v[100:103], v222 offset:34816
	s_add_u32 m0, s38, 61440
	s_nop 0
	global_load_lds_dwordx4 v245, s[4:5]
	s_add_u32 s4, s4, 128
	s_addc_u32 s5, s5, 0
	s_waitcnt lgkmcnt(6)
	v_mfma_f32_16x16x32_bf16 v[172:175], v[80:83], v[124:127], v[172:175]
	ds_read_b128 v[104:107], v222 offset:36864
	s_waitcnt lgkmcnt(6)
	v_mfma_f32_16x16x32_bf16 v[176:179], v[84:87], v[112:115], v[176:179]
	ds_read_b128 v[108:111], v222 offset:38912
	s_waitcnt lgkmcnt(7)
	v_mfma_f32_16x16x32_bf16 v[180:183], v[84:87], v[116:119], v[180:183]
	ds_read_b128 v[68:71], v151 offset:2048
	s_waitcnt lgkmcnt(8)
	v_mfma_f32_16x16x32_bf16 v[184:187], v[84:87], v[120:123], v[184:187]
	ds_read_b128 v[72:75], v151 offset:4096
	s_waitcnt lgkmcnt(9)
	v_mfma_f32_16x16x32_bf16 v[188:191], v[84:87], v[124:127], v[188:191]
	ds_read_b128 v[76:79], v151 offset:6144
	s_waitcnt lgkmcnt(9)
	v_mfma_f32_16x16x32_bf16 v[192:195], v[88:91], v[112:115], v[192:195]
	s_waitcnt lgkmcnt(9)
	v_mfma_f32_16x16x32_bf16 v[196:199], v[88:91], v[116:119], v[196:199]
	s_waitcnt lgkmcnt(9)
	v_mfma_f32_16x16x32_bf16 v[200:203], v[88:91], v[120:123], v[200:203]
	s_waitcnt lgkmcnt(9)
	v_mfma_f32_16x16x32_bf16 v[204:207], v[88:91], v[124:127], v[204:207]
	s_waitcnt lgkmcnt(8)
	v_mfma_f32_16x16x32_bf16 v[208:211], v[92:95], v[112:115], v[208:211]
	s_waitcnt lgkmcnt(8)
	v_mfma_f32_16x16x32_bf16 v[212:215], v[92:95], v[116:119], v[212:215]
	s_waitcnt lgkmcnt(8)
	v_mfma_f32_16x16x32_bf16 v[216:219], v[92:95], v[120:123], v[216:219]
	s_waitcnt lgkmcnt(8)
	v_mfma_f32_16x16x32_bf16 v[230:233], v[92:95], v[124:127], v[230:233]
	s_waitcnt lgkmcnt(6)
	v_mfma_f32_16x16x32_bf16 v[0:3], v[64:67], v[96:99], v[0:3]
	ds_read_b128 v[80:83], v220 offset:0
	s_waitcnt lgkmcnt(6)
	v_mfma_f32_16x16x32_bf16 v[4:7], v[64:67], v[100:103], v[4:7]
	ds_read_b128 v[112:115], v224 offset:32768
	s_waitcnt lgkmcnt(6)
	v_mfma_f32_16x16x32_bf16 v[8:11], v[64:67], v[104:107], v[8:11]
	ds_read_b128 v[116:119], v224 offset:34816
	s_waitcnt lgkmcnt(6)
	v_mfma_f32_16x16x32_bf16 v[12:15], v[64:67], v[108:111], v[12:15]
	ds_read_b128 v[120:123], v224 offset:36864
	s_waitcnt lgkmcnt(6)
	v_mfma_f32_16x16x32_bf16 v[16:19], v[68:71], v[96:99], v[16:19]
	ds_read_b128 v[124:127], v224 offset:38912
	s_waitcnt lgkmcnt(7)
	v_mfma_f32_16x16x32_bf16 v[20:23], v[68:71], v[100:103], v[20:23]
	ds_read_b128 v[84:87], v220 offset:2048
	s_waitcnt lgkmcnt(8)
	v_mfma_f32_16x16x32_bf16 v[24:27], v[68:71], v[104:107], v[24:27]
	ds_read_b128 v[88:91], v220 offset:4096
	s_waitcnt lgkmcnt(9)
	v_mfma_f32_16x16x32_bf16 v[28:31], v[68:71], v[108:111], v[28:31]
	ds_read_b128 v[92:95], v220 offset:6144
	s_waitcnt lgkmcnt(9)
	v_mfma_f32_16x16x32_bf16 v[32:35], v[72:75], v[96:99], v[32:35]
	s_waitcnt lgkmcnt(9)
	v_mfma_f32_16x16x32_bf16 v[36:39], v[72:75], v[100:103], v[36:39]
	s_waitcnt lgkmcnt(9)
	v_mfma_f32_16x16x32_bf16 v[40:43], v[72:75], v[104:107], v[40:43]
	s_waitcnt lgkmcnt(9)
	v_mfma_f32_16x16x32_bf16 v[44:47], v[72:75], v[108:111], v[44:47]
	s_waitcnt vmcnt(4) lgkmcnt(0)
	s_barrier
	s_add_u32 m0, s38, 0
	s_nop 0
	global_load_lds_dwordx4 v226, s[98:99]
	s_waitcnt lgkmcnt(8)
	v_mfma_f32_16x16x32_bf16 v[48:51], v[76:79], v[96:99], v[48:51]
	s_add_u32 m0, s38, 4096
	s_nop 0
	global_load_lds_dwordx4 v228, s[98:99]
	s_waitcnt lgkmcnt(8)
	v_mfma_f32_16x16x32_bf16 v[52:55], v[76:79], v[100:103], v[52:55]
	s_add_u32 m0, s38, 8192
	s_nop 0
	global_load_lds_dwordx4 v244, s[98:99]
	s_waitcnt lgkmcnt(8)
	v_mfma_f32_16x16x32_bf16 v[56:59], v[76:79], v[104:107], v[56:59]
	s_add_u32 m0, s38, 12288
	s_nop 0
	global_load_lds_dwordx4 v245, s[98:99]
	s_add_u32 s98, s98, 128
	s_addc_u32 s99, s99, 0
	s_waitcnt lgkmcnt(8)
	v_mfma_f32_16x16x32_bf16 v[60:63], v[76:79], v[108:111], v[60:63]
	s_waitcnt lgkmcnt(6)
	v_mfma_f32_16x16x32_bf16 v[0:3], v[80:83], v[112:115], v[0:3]
	ds_read_b128 v[64:67], v151 offset:16384
	s_waitcnt lgkmcnt(6)
	v_mfma_f32_16x16x32_bf16 v[4:7], v[80:83], v[116:119], v[4:7]
	ds_read_b128 v[96:99], v222 offset:32768
	s_waitcnt lgkmcnt(6)
	v_mfma_f32_16x16x32_bf16 v[8:11], v[80:83], v[120:123], v[8:11]
	ds_read_b128 v[100:103], v222 offset:34816
	s_waitcnt lgkmcnt(6)
	v_mfma_f32_16x16x32_bf16 v[12:15], v[80:83], v[124:127], v[12:15]
	ds_read_b128 v[104:107], v222 offset:36864
	s_waitcnt lgkmcnt(6)
	v_mfma_f32_16x16x32_bf16 v[16:19], v[84:87], v[112:115], v[16:19]
	ds_read_b128 v[108:111], v222 offset:38912
	s_waitcnt lgkmcnt(7)
	v_mfma_f32_16x16x32_bf16 v[20:23], v[84:87], v[116:119], v[20:23]
	ds_read_b128 v[68:71], v151 offset:18432
	s_waitcnt lgkmcnt(8)
	v_mfma_f32_16x16x32_bf16 v[24:27], v[84:87], v[120:123], v[24:27]
	ds_read_b128 v[72:75], v151 offset:20480
	s_waitcnt lgkmcnt(9)
	v_mfma_f32_16x16x32_bf16 v[28:31], v[84:87], v[124:127], v[28:31]
	ds_read_b128 v[76:79], v151 offset:22528
	s_waitcnt lgkmcnt(9)
	v_mfma_f32_16x16x32_bf16 v[32:35], v[88:91], v[112:115], v[32:35]
	s_waitcnt lgkmcnt(9)
	v_mfma_f32_16x16x32_bf16 v[36:39], v[88:91], v[116:119], v[36:39]
	s_waitcnt lgkmcnt(9)
	v_mfma_f32_16x16x32_bf16 v[40:43], v[88:91], v[120:123], v[40:43]
	s_waitcnt lgkmcnt(9)
	v_mfma_f32_16x16x32_bf16 v[44:47], v[88:91], v[124:127], v[44:47]
	s_waitcnt lgkmcnt(8)
	v_mfma_f32_16x16x32_bf16 v[48:51], v[92:95], v[112:115], v[48:51]
	s_waitcnt lgkmcnt(8)
	v_mfma_f32_16x16x32_bf16 v[52:55], v[92:95], v[116:119], v[52:55]
	s_waitcnt lgkmcnt(8)
	v_mfma_f32_16x16x32_bf16 v[56:59], v[92:95], v[120:123], v[56:59]
	s_waitcnt lgkmcnt(8)
	v_mfma_f32_16x16x32_bf16 v[60:63], v[92:95], v[124:127], v[60:63]
	s_waitcnt lgkmcnt(6)
	v_mfma_f32_16x16x32_bf16 v[160:163], v[64:67], v[96:99], v[160:163]
	ds_read_b128 v[80:83], v220 offset:16384
	s_waitcnt lgkmcnt(6)
	v_mfma_f32_16x16x32_bf16 v[164:167], v[64:67], v[100:103], v[164:167]
	ds_read_b128 v[112:115], v224 offset:32768
	s_waitcnt lgkmcnt(6)
	v_mfma_f32_16x16x32_bf16 v[168:171], v[64:67], v[104:107], v[168:171]
	ds_read_b128 v[116:119], v224 offset:34816
	s_waitcnt lgkmcnt(6)
	v_mfma_f32_16x16x32_bf16 v[172:175], v[64:67], v[108:111], v[172:175]
	ds_read_b128 v[120:123], v224 offset:36864
	s_waitcnt lgkmcnt(6)
	v_mfma_f32_16x16x32_bf16 v[176:179], v[68:71], v[96:99], v[176:179]
	ds_read_b128 v[124:127], v224 offset:38912
	s_waitcnt lgkmcnt(7)
	v_mfma_f32_16x16x32_bf16 v[180:183], v[68:71], v[100:103], v[180:183]
	ds_read_b128 v[84:87], v220 offset:18432
	s_waitcnt lgkmcnt(8)
	v_mfma_f32_16x16x32_bf16 v[184:187], v[68:71], v[104:107], v[184:187]
	ds_read_b128 v[88:91], v220 offset:20480
	s_waitcnt lgkmcnt(9)
	v_mfma_f32_16x16x32_bf16 v[188:191], v[68:71], v[108:111], v[188:191]
	ds_read_b128 v[92:95], v220 offset:22528
	s_waitcnt lgkmcnt(9)
	v_mfma_f32_16x16x32_bf16 v[192:195], v[72:75], v[96:99], v[192:195]
	s_waitcnt lgkmcnt(9)
	v_mfma_f32_16x16x32_bf16 v[196:199], v[72:75], v[100:103], v[196:199]
	s_waitcnt lgkmcnt(9)
	v_mfma_f32_16x16x32_bf16 v[200:203], v[72:75], v[104:107], v[200:203]
	s_waitcnt lgkmcnt(9)
	v_mfma_f32_16x16x32_bf16 v[204:207], v[72:75], v[108:111], v[204:207]
	s_waitcnt vmcnt(0) lgkmcnt(0)
	s_barrier
	s_add_u32 m0, s38, 16384
	s_nop 0
	global_load_lds_dwordx4 v226, s[100:101]
	s_waitcnt lgkmcnt(8)
	v_mfma_f32_16x16x32_bf16 v[208:211], v[76:79], v[96:99], v[208:211]
	s_add_u32 m0, s38, 20480
	s_nop 0
	global_load_lds_dwordx4 v228, s[100:101]
	s_waitcnt lgkmcnt(8)
	v_mfma_f32_16x16x32_bf16 v[212:215], v[76:79], v[100:103], v[212:215]
	s_add_u32 m0, s38, 24576
	s_nop 0
	global_load_lds_dwordx4 v244, s[100:101]
	s_waitcnt lgkmcnt(8)
	v_mfma_f32_16x16x32_bf16 v[216:219], v[76:79], v[104:107], v[216:219]
	s_add_u32 m0, s38, 28672
	s_nop 0
	global_load_lds_dwordx4 v245, s[100:101]
	s_add_u32 s100, s100, 128
	s_addc_u32 s101, s101, 0
	s_waitcnt lgkmcnt(8)
	v_mfma_f32_16x16x32_bf16 v[230:233], v[76:79], v[108:111], v[230:233]
	s_add_u32 m0, s38, 32768
	s_nop 0
	global_load_lds_dwordx4 v226, s[4:5]
	s_waitcnt lgkmcnt(6)
	v_mfma_f32_16x16x32_bf16 v[160:163], v[80:83], v[112:115], v[160:163]
	ds_read_b128 v[64:67], v151 offset:0
	s_add_u32 m0, s38, 36864
	s_nop 0
	global_load_lds_dwordx4 v228, s[4:5]
	s_waitcnt lgkmcnt(6)
	v_mfma_f32_16x16x32_bf16 v[164:167], v[80:83], v[116:119], v[164:167]
	ds_read_b128 v[96:99], v222 offset:49152
	s_add_u32 m0, s38, 40960
	s_nop 0
	global_load_lds_dwordx4 v244, s[4:5]
	s_waitcnt lgkmcnt(6)
	v_mfma_f32_16x16x32_bf16 v[168:171], v[80:83], v[120:123], v[168:171]
	ds_read_b128 v[100:103], v222 offset:51200
	s_add_u32 m0, s38, 45056
	s_nop 0
	global_load_lds_dwordx4 v245, s[4:5]
	s_add_u32 s4, s4, 128
	s_addc_u32 s5, s5, 0
	s_waitcnt lgkmcnt(6)
	v_mfma_f32_16x16x32_bf16 v[172:175], v[80:83], v[124:127], v[172:175]
	ds_read_b128 v[104:107], v222 offset:53248
	s_waitcnt lgkmcnt(6)
	v_mfma_f32_16x16x32_bf16 v[176:179], v[84:87], v[112:115], v[176:179]
	ds_read_b128 v[108:111], v222 offset:55296
	s_waitcnt lgkmcnt(7)
	v_mfma_f32_16x16x32_bf16 v[180:183], v[84:87], v[116:119], v[180:183]
	ds_read_b128 v[68:71], v151 offset:2048
	s_waitcnt lgkmcnt(8)
	v_mfma_f32_16x16x32_bf16 v[184:187], v[84:87], v[120:123], v[184:187]
	ds_read_b128 v[72:75], v151 offset:4096
	s_waitcnt lgkmcnt(9)
	v_mfma_f32_16x16x32_bf16 v[188:191], v[84:87], v[124:127], v[188:191]
	ds_read_b128 v[76:79], v151 offset:6144
	s_waitcnt lgkmcnt(9)
	v_mfma_f32_16x16x32_bf16 v[192:195], v[88:91], v[112:115], v[192:195]
	s_waitcnt lgkmcnt(9)
	v_mfma_f32_16x16x32_bf16 v[196:199], v[88:91], v[116:119], v[196:199]
	s_waitcnt lgkmcnt(9)
	v_mfma_f32_16x16x32_bf16 v[200:203], v[88:91], v[120:123], v[200:203]
	s_waitcnt lgkmcnt(9)
	v_mfma_f32_16x16x32_bf16 v[204:207], v[88:91], v[124:127], v[204:207]
	s_waitcnt lgkmcnt(8)
	v_mfma_f32_16x16x32_bf16 v[208:211], v[92:95], v[112:115], v[208:211]
	s_waitcnt lgkmcnt(8)
	v_mfma_f32_16x16x32_bf16 v[212:215], v[92:95], v[116:119], v[212:215]
	s_waitcnt lgkmcnt(8)
	v_mfma_f32_16x16x32_bf16 v[216:219], v[92:95], v[120:123], v[216:219]
	s_waitcnt lgkmcnt(8)
	v_mfma_f32_16x16x32_bf16 v[230:233], v[92:95], v[124:127], v[230:233]
	s_waitcnt lgkmcnt(6)
	v_mfma_f32_16x16x32_bf16 v[0:3], v[64:67], v[96:99], v[0:3]
	ds_read_b128 v[80:83], v220 offset:0
	s_waitcnt lgkmcnt(6)
	v_mfma_f32_16x16x32_bf16 v[4:7], v[64:67], v[100:103], v[4:7]
	ds_read_b128 v[112:115], v224 offset:49152
	s_waitcnt lgkmcnt(6)
	v_mfma_f32_16x16x32_bf16 v[8:11], v[64:67], v[104:107], v[8:11]
	ds_read_b128 v[116:119], v224 offset:51200
	s_waitcnt lgkmcnt(6)
	v_mfma_f32_16x16x32_bf16 v[12:15], v[64:67], v[108:111], v[12:15]
	ds_read_b128 v[120:123], v224 offset:53248
	s_waitcnt lgkmcnt(6)
	v_mfma_f32_16x16x32_bf16 v[16:19], v[68:71], v[96:99], v[16:19]
	ds_read_b128 v[124:127], v224 offset:55296
	s_waitcnt lgkmcnt(7)
	v_mfma_f32_16x16x32_bf16 v[20:23], v[68:71], v[100:103], v[20:23]
	ds_read_b128 v[84:87], v220 offset:2048
	s_waitcnt lgkmcnt(8)
	v_mfma_f32_16x16x32_bf16 v[24:27], v[68:71], v[104:107], v[24:27]
	ds_read_b128 v[88:91], v220 offset:4096
	s_waitcnt lgkmcnt(9)
	v_mfma_f32_16x16x32_bf16 v[28:31], v[68:71], v[108:111], v[28:31]
	ds_read_b128 v[92:95], v220 offset:6144
	s_waitcnt lgkmcnt(9)
	v_mfma_f32_16x16x32_bf16 v[32:35], v[72:75], v[96:99], v[32:35]
	s_waitcnt lgkmcnt(9)
	v_mfma_f32_16x16x32_bf16 v[36:39], v[72:75], v[100:103], v[36:39]
	s_waitcnt lgkmcnt(9)
	v_mfma_f32_16x16x32_bf16 v[40:43], v[72:75], v[104:107], v[40:43]
	s_waitcnt lgkmcnt(9)
	v_mfma_f32_16x16x32_bf16 v[44:47], v[72:75], v[108:111], v[44:47]
	s_waitcnt vmcnt(4) lgkmcnt(0)
	s_barrier
	s_add_u32 m0, s38, 0
	s_nop 0
	global_load_lds_dwordx4 v226, s[98:99]
	s_waitcnt lgkmcnt(8)
	v_mfma_f32_16x16x32_bf16 v[48:51], v[76:79], v[96:99], v[48:51]
	s_add_u32 m0, s38, 4096
	s_nop 0
	global_load_lds_dwordx4 v228, s[98:99]
	s_waitcnt lgkmcnt(8)
	v_mfma_f32_16x16x32_bf16 v[52:55], v[76:79], v[100:103], v[52:55]
	s_add_u32 m0, s38, 8192
	s_nop 0
	global_load_lds_dwordx4 v244, s[98:99]
	s_waitcnt lgkmcnt(8)
	v_mfma_f32_16x16x32_bf16 v[56:59], v[76:79], v[104:107], v[56:59]
	s_add_u32 m0, s38, 12288
	s_nop 0
	global_load_lds_dwordx4 v245, s[98:99]
	s_add_u32 s98, s98, 128
	s_addc_u32 s99, s99, 0
	s_waitcnt lgkmcnt(8)
	v_mfma_f32_16x16x32_bf16 v[60:63], v[76:79], v[108:111], v[60:63]
	s_waitcnt lgkmcnt(6)
	v_mfma_f32_16x16x32_bf16 v[0:3], v[80:83], v[112:115], v[0:3]
	ds_read_b128 v[64:67], v151 offset:16384
	s_waitcnt lgkmcnt(6)
	v_mfma_f32_16x16x32_bf16 v[4:7], v[80:83], v[116:119], v[4:7]
	ds_read_b128 v[96:99], v222 offset:49152
	s_waitcnt lgkmcnt(6)
	v_mfma_f32_16x16x32_bf16 v[8:11], v[80:83], v[120:123], v[8:11]
	ds_read_b128 v[100:103], v222 offset:51200
	s_waitcnt lgkmcnt(6)
	v_mfma_f32_16x16x32_bf16 v[12:15], v[80:83], v[124:127], v[12:15]
	ds_read_b128 v[104:107], v222 offset:53248
	s_waitcnt lgkmcnt(6)
	v_mfma_f32_16x16x32_bf16 v[16:19], v[84:87], v[112:115], v[16:19]
	ds_read_b128 v[108:111], v222 offset:55296
	s_waitcnt lgkmcnt(7)
	v_mfma_f32_16x16x32_bf16 v[20:23], v[84:87], v[116:119], v[20:23]
	ds_read_b128 v[68:71], v151 offset:18432
	s_waitcnt lgkmcnt(8)
	v_mfma_f32_16x16x32_bf16 v[24:27], v[84:87], v[120:123], v[24:27]
	ds_read_b128 v[72:75], v151 offset:20480
	s_waitcnt lgkmcnt(9)
	v_mfma_f32_16x16x32_bf16 v[28:31], v[84:87], v[124:127], v[28:31]
	ds_read_b128 v[76:79], v151 offset:22528
	s_waitcnt lgkmcnt(9)
	v_mfma_f32_16x16x32_bf16 v[32:35], v[88:91], v[112:115], v[32:35]
	s_waitcnt lgkmcnt(9)
	v_mfma_f32_16x16x32_bf16 v[36:39], v[88:91], v[116:119], v[36:39]
	s_waitcnt lgkmcnt(9)
	v_mfma_f32_16x16x32_bf16 v[40:43], v[88:91], v[120:123], v[40:43]
	s_waitcnt lgkmcnt(9)
	v_mfma_f32_16x16x32_bf16 v[44:47], v[88:91], v[124:127], v[44:47]
	s_waitcnt lgkmcnt(8)
	v_mfma_f32_16x16x32_bf16 v[48:51], v[92:95], v[112:115], v[48:51]
	s_waitcnt lgkmcnt(8)
	v_mfma_f32_16x16x32_bf16 v[52:55], v[92:95], v[116:119], v[52:55]
	s_waitcnt lgkmcnt(8)
	v_mfma_f32_16x16x32_bf16 v[56:59], v[92:95], v[120:123], v[56:59]
	s_waitcnt lgkmcnt(8)
	v_mfma_f32_16x16x32_bf16 v[60:63], v[92:95], v[124:127], v[60:63]
	s_waitcnt lgkmcnt(6)
	v_mfma_f32_16x16x32_bf16 v[160:163], v[64:67], v[96:99], v[160:163]
	ds_read_b128 v[80:83], v220 offset:16384
	s_waitcnt lgkmcnt(6)
	v_mfma_f32_16x16x32_bf16 v[164:167], v[64:67], v[100:103], v[164:167]
	ds_read_b128 v[112:115], v224 offset:49152
	s_waitcnt lgkmcnt(6)
	v_mfma_f32_16x16x32_bf16 v[168:171], v[64:67], v[104:107], v[168:171]
	ds_read_b128 v[116:119], v224 offset:51200
	s_waitcnt lgkmcnt(6)
	v_mfma_f32_16x16x32_bf16 v[172:175], v[64:67], v[108:111], v[172:175]
	ds_read_b128 v[120:123], v224 offset:53248
	s_waitcnt lgkmcnt(6)
	v_mfma_f32_16x16x32_bf16 v[176:179], v[68:71], v[96:99], v[176:179]
	ds_read_b128 v[124:127], v224 offset:55296
	s_waitcnt lgkmcnt(7)
	v_mfma_f32_16x16x32_bf16 v[180:183], v[68:71], v[100:103], v[180:183]
	ds_read_b128 v[84:87], v220 offset:18432
	s_waitcnt lgkmcnt(8)
	v_mfma_f32_16x16x32_bf16 v[184:187], v[68:71], v[104:107], v[184:187]
	ds_read_b128 v[88:91], v220 offset:20480
	s_waitcnt lgkmcnt(9)
	v_mfma_f32_16x16x32_bf16 v[188:191], v[68:71], v[108:111], v[188:191]
	ds_read_b128 v[92:95], v220 offset:22528
	s_waitcnt lgkmcnt(9)
	v_mfma_f32_16x16x32_bf16 v[192:195], v[72:75], v[96:99], v[192:195]
	s_waitcnt lgkmcnt(9)
	v_mfma_f32_16x16x32_bf16 v[196:199], v[72:75], v[100:103], v[196:199]
	s_waitcnt lgkmcnt(9)
	v_mfma_f32_16x16x32_bf16 v[200:203], v[72:75], v[104:107], v[200:203]
	s_waitcnt lgkmcnt(9)
	v_mfma_f32_16x16x32_bf16 v[204:207], v[72:75], v[108:111], v[204:207]
	s_waitcnt vmcnt(0) lgkmcnt(0)
	s_barrier
	s_add_u32 m0, s38, 16384
	s_nop 0
	global_load_lds_dwordx4 v226, s[100:101]
	s_waitcnt lgkmcnt(8)
	v_mfma_f32_16x16x32_bf16 v[208:211], v[76:79], v[96:99], v[208:211]
	s_add_u32 m0, s38, 20480
	s_nop 0
	global_load_lds_dwordx4 v228, s[100:101]
	s_waitcnt lgkmcnt(8)
	v_mfma_f32_16x16x32_bf16 v[212:215], v[76:79], v[100:103], v[212:215]
	s_add_u32 m0, s38, 24576
	s_nop 0
	global_load_lds_dwordx4 v244, s[100:101]
	s_waitcnt lgkmcnt(8)
	v_mfma_f32_16x16x32_bf16 v[216:219], v[76:79], v[104:107], v[216:219]
	s_add_u32 m0, s38, 28672
	s_nop 0
	global_load_lds_dwordx4 v245, s[100:101]
	s_add_u32 s100, s100, 128
	s_addc_u32 s101, s101, 0
	s_waitcnt lgkmcnt(8)
	v_mfma_f32_16x16x32_bf16 v[230:233], v[76:79], v[108:111], v[230:233]
	s_add_u32 m0, s38, 49152
	s_nop 0
	global_load_lds_dwordx4 v226, s[4:5]
	s_waitcnt lgkmcnt(6)
	v_mfma_f32_16x16x32_bf16 v[160:163], v[80:83], v[112:115], v[160:163]
	ds_read_b128 v[64:67], v151 offset:0
	s_add_u32 m0, s38, 53248
	s_nop 0
	global_load_lds_dwordx4 v228, s[4:5]
	s_waitcnt lgkmcnt(6)
	v_mfma_f32_16x16x32_bf16 v[164:167], v[80:83], v[116:119], v[164:167]
	ds_read_b128 v[96:99], v222 offset:32768
	s_add_u32 m0, s38, 57344
	s_nop 0
	global_load_lds_dwordx4 v244, s[4:5]
	s_waitcnt lgkmcnt(6)
	v_mfma_f32_16x16x32_bf16 v[168:171], v[80:83], v[120:123], v[168:171]
	ds_read_b128 v[100:103], v222 offset:34816
	s_add_u32 m0, s38, 61440
	s_nop 0
	global_load_lds_dwordx4 v245, s[4:5]
	s_add_u32 s4, s4, 128
	s_addc_u32 s5, s5, 0
	s_waitcnt lgkmcnt(6)
	v_mfma_f32_16x16x32_bf16 v[172:175], v[80:83], v[124:127], v[172:175]
	ds_read_b128 v[104:107], v222 offset:36864
	s_waitcnt lgkmcnt(6)
	v_mfma_f32_16x16x32_bf16 v[176:179], v[84:87], v[112:115], v[176:179]
	ds_read_b128 v[108:111], v222 offset:38912
	s_waitcnt lgkmcnt(7)
	v_mfma_f32_16x16x32_bf16 v[180:183], v[84:87], v[116:119], v[180:183]
	ds_read_b128 v[68:71], v151 offset:2048
	s_waitcnt lgkmcnt(8)
	v_mfma_f32_16x16x32_bf16 v[184:187], v[84:87], v[120:123], v[184:187]
	ds_read_b128 v[72:75], v151 offset:4096
	s_waitcnt lgkmcnt(9)
	v_mfma_f32_16x16x32_bf16 v[188:191], v[84:87], v[124:127], v[188:191]
	ds_read_b128 v[76:79], v151 offset:6144
	s_waitcnt lgkmcnt(9)
	v_mfma_f32_16x16x32_bf16 v[192:195], v[88:91], v[112:115], v[192:195]
	s_waitcnt lgkmcnt(9)
	v_mfma_f32_16x16x32_bf16 v[196:199], v[88:91], v[116:119], v[196:199]
	s_waitcnt lgkmcnt(9)
	v_mfma_f32_16x16x32_bf16 v[200:203], v[88:91], v[120:123], v[200:203]
	s_waitcnt lgkmcnt(9)
	v_mfma_f32_16x16x32_bf16 v[204:207], v[88:91], v[124:127], v[204:207]
	s_waitcnt lgkmcnt(8)
	v_mfma_f32_16x16x32_bf16 v[208:211], v[92:95], v[112:115], v[208:211]
	s_waitcnt lgkmcnt(8)
	v_mfma_f32_16x16x32_bf16 v[212:215], v[92:95], v[116:119], v[212:215]
	s_waitcnt lgkmcnt(8)
	v_mfma_f32_16x16x32_bf16 v[216:219], v[92:95], v[120:123], v[216:219]
	s_waitcnt lgkmcnt(8)
	v_mfma_f32_16x16x32_bf16 v[230:233], v[92:95], v[124:127], v[230:233]
	s_waitcnt lgkmcnt(6)
	v_mfma_f32_16x16x32_bf16 v[0:3], v[64:67], v[96:99], v[0:3]
	ds_read_b128 v[80:83], v220 offset:0
	s_waitcnt lgkmcnt(6)
	v_mfma_f32_16x16x32_bf16 v[4:7], v[64:67], v[100:103], v[4:7]
	ds_read_b128 v[112:115], v224 offset:32768
	s_waitcnt lgkmcnt(6)
	v_mfma_f32_16x16x32_bf16 v[8:11], v[64:67], v[104:107], v[8:11]
	ds_read_b128 v[116:119], v224 offset:34816
	s_waitcnt lgkmcnt(6)
	v_mfma_f32_16x16x32_bf16 v[12:15], v[64:67], v[108:111], v[12:15]
	ds_read_b128 v[120:123], v224 offset:36864
	s_waitcnt lgkmcnt(6)
	v_mfma_f32_16x16x32_bf16 v[16:19], v[68:71], v[96:99], v[16:19]
	ds_read_b128 v[124:127], v224 offset:38912
	s_waitcnt lgkmcnt(7)
	v_mfma_f32_16x16x32_bf16 v[20:23], v[68:71], v[100:103], v[20:23]
	ds_read_b128 v[84:87], v220 offset:2048
	s_waitcnt lgkmcnt(8)
	v_mfma_f32_16x16x32_bf16 v[24:27], v[68:71], v[104:107], v[24:27]
	ds_read_b128 v[88:91], v220 offset:4096
	s_waitcnt lgkmcnt(9)
	v_mfma_f32_16x16x32_bf16 v[28:31], v[68:71], v[108:111], v[28:31]
	ds_read_b128 v[92:95], v220 offset:6144
	s_waitcnt lgkmcnt(9)
	v_mfma_f32_16x16x32_bf16 v[32:35], v[72:75], v[96:99], v[32:35]
	s_waitcnt lgkmcnt(9)
	v_mfma_f32_16x16x32_bf16 v[36:39], v[72:75], v[100:103], v[36:39]
	s_waitcnt lgkmcnt(9)
	v_mfma_f32_16x16x32_bf16 v[40:43], v[72:75], v[104:107], v[40:43]
	s_waitcnt lgkmcnt(9)
	v_mfma_f32_16x16x32_bf16 v[44:47], v[72:75], v[108:111], v[44:47]
	s_waitcnt vmcnt(4) lgkmcnt(0)
	s_barrier
	s_add_u32 m0, s38, 0
	s_nop 0
	global_load_lds_dwordx4 v226, s[98:99]
	s_waitcnt lgkmcnt(8)
	v_mfma_f32_16x16x32_bf16 v[48:51], v[76:79], v[96:99], v[48:51]
	s_add_u32 m0, s38, 4096
	s_nop 0
	global_load_lds_dwordx4 v228, s[98:99]
	s_waitcnt lgkmcnt(8)
	v_mfma_f32_16x16x32_bf16 v[52:55], v[76:79], v[100:103], v[52:55]
	s_add_u32 m0, s38, 8192
	s_nop 0
	global_load_lds_dwordx4 v244, s[98:99]
	s_waitcnt lgkmcnt(8)
	v_mfma_f32_16x16x32_bf16 v[56:59], v[76:79], v[104:107], v[56:59]
	s_add_u32 m0, s38, 12288
	s_nop 0
	global_load_lds_dwordx4 v245, s[98:99]
	s_add_u32 s98, s98, 128
	s_addc_u32 s99, s99, 0
	s_waitcnt lgkmcnt(8)
	v_mfma_f32_16x16x32_bf16 v[60:63], v[76:79], v[108:111], v[60:63]
	s_waitcnt lgkmcnt(6)
	v_mfma_f32_16x16x32_bf16 v[0:3], v[80:83], v[112:115], v[0:3]
	ds_read_b128 v[64:67], v151 offset:16384
	s_waitcnt lgkmcnt(6)
	v_mfma_f32_16x16x32_bf16 v[4:7], v[80:83], v[116:119], v[4:7]
	ds_read_b128 v[96:99], v222 offset:32768
	s_waitcnt lgkmcnt(6)
	v_mfma_f32_16x16x32_bf16 v[8:11], v[80:83], v[120:123], v[8:11]
	ds_read_b128 v[100:103], v222 offset:34816
	s_waitcnt lgkmcnt(6)
	v_mfma_f32_16x16x32_bf16 v[12:15], v[80:83], v[124:127], v[12:15]
	ds_read_b128 v[104:107], v222 offset:36864
	s_waitcnt lgkmcnt(6)
	v_mfma_f32_16x16x32_bf16 v[16:19], v[84:87], v[112:115], v[16:19]
	ds_read_b128 v[108:111], v222 offset:38912
	s_waitcnt lgkmcnt(7)
	v_mfma_f32_16x16x32_bf16 v[20:23], v[84:87], v[116:119], v[20:23]
	ds_read_b128 v[68:71], v151 offset:18432
	s_waitcnt lgkmcnt(8)
	v_mfma_f32_16x16x32_bf16 v[24:27], v[84:87], v[120:123], v[24:27]
	ds_read_b128 v[72:75], v151 offset:20480
	s_waitcnt lgkmcnt(9)
	v_mfma_f32_16x16x32_bf16 v[28:31], v[84:87], v[124:127], v[28:31]
	ds_read_b128 v[76:79], v151 offset:22528
	s_waitcnt lgkmcnt(9)
	v_mfma_f32_16x16x32_bf16 v[32:35], v[88:91], v[112:115], v[32:35]
	s_waitcnt lgkmcnt(9)
	v_mfma_f32_16x16x32_bf16 v[36:39], v[88:91], v[116:119], v[36:39]
	s_waitcnt lgkmcnt(9)
	v_mfma_f32_16x16x32_bf16 v[40:43], v[88:91], v[120:123], v[40:43]
	s_waitcnt lgkmcnt(9)
	v_mfma_f32_16x16x32_bf16 v[44:47], v[88:91], v[124:127], v[44:47]
	s_waitcnt lgkmcnt(8)
	v_mfma_f32_16x16x32_bf16 v[48:51], v[92:95], v[112:115], v[48:51]
	s_waitcnt lgkmcnt(8)
	v_mfma_f32_16x16x32_bf16 v[52:55], v[92:95], v[116:119], v[52:55]
	s_waitcnt lgkmcnt(8)
	v_mfma_f32_16x16x32_bf16 v[56:59], v[92:95], v[120:123], v[56:59]
	s_waitcnt lgkmcnt(8)
	v_mfma_f32_16x16x32_bf16 v[60:63], v[92:95], v[124:127], v[60:63]
	s_waitcnt lgkmcnt(6)
	v_mfma_f32_16x16x32_bf16 v[160:163], v[64:67], v[96:99], v[160:163]
	ds_read_b128 v[80:83], v220 offset:16384
	s_waitcnt lgkmcnt(6)
	v_mfma_f32_16x16x32_bf16 v[164:167], v[64:67], v[100:103], v[164:167]
	ds_read_b128 v[112:115], v224 offset:32768
	s_waitcnt lgkmcnt(6)
	v_mfma_f32_16x16x32_bf16 v[168:171], v[64:67], v[104:107], v[168:171]
	ds_read_b128 v[116:119], v224 offset:34816
	s_waitcnt lgkmcnt(6)
	v_mfma_f32_16x16x32_bf16 v[172:175], v[64:67], v[108:111], v[172:175]
	ds_read_b128 v[120:123], v224 offset:36864
	s_waitcnt lgkmcnt(6)
	v_mfma_f32_16x16x32_bf16 v[176:179], v[68:71], v[96:99], v[176:179]
	ds_read_b128 v[124:127], v224 offset:38912
	s_waitcnt lgkmcnt(7)
	v_mfma_f32_16x16x32_bf16 v[180:183], v[68:71], v[100:103], v[180:183]
	ds_read_b128 v[84:87], v220 offset:18432
	s_waitcnt lgkmcnt(8)
	v_mfma_f32_16x16x32_bf16 v[184:187], v[68:71], v[104:107], v[184:187]
	ds_read_b128 v[88:91], v220 offset:20480
	s_waitcnt lgkmcnt(9)
	v_mfma_f32_16x16x32_bf16 v[188:191], v[68:71], v[108:111], v[188:191]
	ds_read_b128 v[92:95], v220 offset:22528
	s_waitcnt lgkmcnt(9)
	v_mfma_f32_16x16x32_bf16 v[192:195], v[72:75], v[96:99], v[192:195]
	s_waitcnt lgkmcnt(9)
	v_mfma_f32_16x16x32_bf16 v[196:199], v[72:75], v[100:103], v[196:199]
	s_waitcnt lgkmcnt(9)
	v_mfma_f32_16x16x32_bf16 v[200:203], v[72:75], v[104:107], v[200:203]
	s_waitcnt lgkmcnt(9)
	v_mfma_f32_16x16x32_bf16 v[204:207], v[72:75], v[108:111], v[204:207]
	s_waitcnt vmcnt(0) lgkmcnt(0)
	s_barrier
	s_add_u32 m0, s38, 16384
	s_nop 0
	global_load_lds_dwordx4 v226, s[100:101]
	s_waitcnt lgkmcnt(8)
	v_mfma_f32_16x16x32_bf16 v[208:211], v[76:79], v[96:99], v[208:211]
	s_add_u32 m0, s38, 20480
	s_nop 0
	global_load_lds_dwordx4 v228, s[100:101]
	s_waitcnt lgkmcnt(8)
	v_mfma_f32_16x16x32_bf16 v[212:215], v[76:79], v[100:103], v[212:215]
	s_add_u32 m0, s38, 24576
	s_nop 0
	global_load_lds_dwordx4 v244, s[100:101]
	s_waitcnt lgkmcnt(8)
	v_mfma_f32_16x16x32_bf16 v[216:219], v[76:79], v[104:107], v[216:219]
	s_add_u32 m0, s38, 28672
	s_nop 0
	global_load_lds_dwordx4 v245, s[100:101]
	s_add_u32 s100, s100, 128
	s_addc_u32 s101, s101, 0
	s_waitcnt lgkmcnt(8)
	v_mfma_f32_16x16x32_bf16 v[230:233], v[76:79], v[108:111], v[230:233]
	s_add_u32 m0, s38, 32768
	s_nop 0
	global_load_lds_dwordx4 v226, s[4:5]
	s_waitcnt lgkmcnt(6)
	v_mfma_f32_16x16x32_bf16 v[160:163], v[80:83], v[112:115], v[160:163]
	ds_read_b128 v[64:67], v151 offset:0
	s_add_u32 m0, s38, 36864
	s_nop 0
	global_load_lds_dwordx4 v228, s[4:5]
	s_waitcnt lgkmcnt(6)
	v_mfma_f32_16x16x32_bf16 v[164:167], v[80:83], v[116:119], v[164:167]
	ds_read_b128 v[96:99], v222 offset:49152
	s_add_u32 m0, s38, 40960
	s_nop 0
	global_load_lds_dwordx4 v244, s[4:5]
	s_waitcnt lgkmcnt(6)
	v_mfma_f32_16x16x32_bf16 v[168:171], v[80:83], v[120:123], v[168:171]
	ds_read_b128 v[100:103], v222 offset:51200
	s_add_u32 m0, s38, 45056
	s_nop 0
	global_load_lds_dwordx4 v245, s[4:5]
	s_add_u32 s4, s4, 128
	s_addc_u32 s5, s5, 0
	s_waitcnt lgkmcnt(6)
	v_mfma_f32_16x16x32_bf16 v[172:175], v[80:83], v[124:127], v[172:175]
	ds_read_b128 v[104:107], v222 offset:53248
	s_waitcnt lgkmcnt(6)
	v_mfma_f32_16x16x32_bf16 v[176:179], v[84:87], v[112:115], v[176:179]
	ds_read_b128 v[108:111], v222 offset:55296
	s_waitcnt lgkmcnt(7)
	v_mfma_f32_16x16x32_bf16 v[180:183], v[84:87], v[116:119], v[180:183]
	ds_read_b128 v[68:71], v151 offset:2048
	s_waitcnt lgkmcnt(8)
	v_mfma_f32_16x16x32_bf16 v[184:187], v[84:87], v[120:123], v[184:187]
	ds_read_b128 v[72:75], v151 offset:4096
	s_waitcnt lgkmcnt(9)
	v_mfma_f32_16x16x32_bf16 v[188:191], v[84:87], v[124:127], v[188:191]
	ds_read_b128 v[76:79], v151 offset:6144
	s_waitcnt lgkmcnt(9)
	v_mfma_f32_16x16x32_bf16 v[192:195], v[88:91], v[112:115], v[192:195]
	s_waitcnt lgkmcnt(9)
	v_mfma_f32_16x16x32_bf16 v[196:199], v[88:91], v[116:119], v[196:199]
	s_waitcnt lgkmcnt(9)
	v_mfma_f32_16x16x32_bf16 v[200:203], v[88:91], v[120:123], v[200:203]
	s_waitcnt lgkmcnt(9)
	v_mfma_f32_16x16x32_bf16 v[204:207], v[88:91], v[124:127], v[204:207]
	s_waitcnt lgkmcnt(8)
	v_mfma_f32_16x16x32_bf16 v[208:211], v[92:95], v[112:115], v[208:211]
	s_waitcnt lgkmcnt(8)
	v_mfma_f32_16x16x32_bf16 v[212:215], v[92:95], v[116:119], v[212:215]
	s_waitcnt lgkmcnt(8)
	v_mfma_f32_16x16x32_bf16 v[216:219], v[92:95], v[120:123], v[216:219]
	s_waitcnt lgkmcnt(8)
	v_mfma_f32_16x16x32_bf16 v[230:233], v[92:95], v[124:127], v[230:233]
	s_waitcnt lgkmcnt(6)
	v_mfma_f32_16x16x32_bf16 v[0:3], v[64:67], v[96:99], v[0:3]
	ds_read_b128 v[80:83], v220 offset:0
	s_waitcnt lgkmcnt(6)
	v_mfma_f32_16x16x32_bf16 v[4:7], v[64:67], v[100:103], v[4:7]
	ds_read_b128 v[112:115], v224 offset:49152
	s_waitcnt lgkmcnt(6)
	v_mfma_f32_16x16x32_bf16 v[8:11], v[64:67], v[104:107], v[8:11]
	ds_read_b128 v[116:119], v224 offset:51200
	s_waitcnt lgkmcnt(6)
	v_mfma_f32_16x16x32_bf16 v[12:15], v[64:67], v[108:111], v[12:15]
	ds_read_b128 v[120:123], v224 offset:53248
	s_waitcnt lgkmcnt(6)
	v_mfma_f32_16x16x32_bf16 v[16:19], v[68:71], v[96:99], v[16:19]
	ds_read_b128 v[124:127], v224 offset:55296
	s_waitcnt lgkmcnt(7)
	v_mfma_f32_16x16x32_bf16 v[20:23], v[68:71], v[100:103], v[20:23]
	ds_read_b128 v[84:87], v220 offset:2048
	s_waitcnt lgkmcnt(8)
	v_mfma_f32_16x16x32_bf16 v[24:27], v[68:71], v[104:107], v[24:27]
	ds_read_b128 v[88:91], v220 offset:4096
	s_waitcnt lgkmcnt(9)
	v_mfma_f32_16x16x32_bf16 v[28:31], v[68:71], v[108:111], v[28:31]
	ds_read_b128 v[92:95], v220 offset:6144
	s_waitcnt lgkmcnt(9)
	v_mfma_f32_16x16x32_bf16 v[32:35], v[72:75], v[96:99], v[32:35]
	s_waitcnt lgkmcnt(9)
	v_mfma_f32_16x16x32_bf16 v[36:39], v[72:75], v[100:103], v[36:39]
	s_waitcnt lgkmcnt(9)
	v_mfma_f32_16x16x32_bf16 v[40:43], v[72:75], v[104:107], v[40:43]
	s_waitcnt lgkmcnt(9)
	v_mfma_f32_16x16x32_bf16 v[44:47], v[72:75], v[108:111], v[44:47]
	s_waitcnt vmcnt(4) lgkmcnt(0)
	s_barrier
	s_add_u32 m0, s38, 0
	s_nop 0
	global_load_lds_dwordx4 v226, s[98:99]
	s_waitcnt lgkmcnt(8)
	v_mfma_f32_16x16x32_bf16 v[48:51], v[76:79], v[96:99], v[48:51]
	s_add_u32 m0, s38, 4096
	s_nop 0
	global_load_lds_dwordx4 v228, s[98:99]
	s_waitcnt lgkmcnt(8)
	v_mfma_f32_16x16x32_bf16 v[52:55], v[76:79], v[100:103], v[52:55]
	s_add_u32 m0, s38, 8192
	s_nop 0
	global_load_lds_dwordx4 v244, s[98:99]
	s_waitcnt lgkmcnt(8)
	v_mfma_f32_16x16x32_bf16 v[56:59], v[76:79], v[104:107], v[56:59]
	s_add_u32 m0, s38, 12288
	s_nop 0
	global_load_lds_dwordx4 v245, s[98:99]
	s_add_u32 s98, s98, 128
	s_addc_u32 s99, s99, 0
	s_waitcnt lgkmcnt(8)
	v_mfma_f32_16x16x32_bf16 v[60:63], v[76:79], v[108:111], v[60:63]
	s_waitcnt lgkmcnt(6)
	v_mfma_f32_16x16x32_bf16 v[0:3], v[80:83], v[112:115], v[0:3]
	ds_read_b128 v[64:67], v151 offset:16384
	s_waitcnt lgkmcnt(6)
	v_mfma_f32_16x16x32_bf16 v[4:7], v[80:83], v[116:119], v[4:7]
	ds_read_b128 v[96:99], v222 offset:49152
	s_waitcnt lgkmcnt(6)
	v_mfma_f32_16x16x32_bf16 v[8:11], v[80:83], v[120:123], v[8:11]
	ds_read_b128 v[100:103], v222 offset:51200
	s_waitcnt lgkmcnt(6)
	v_mfma_f32_16x16x32_bf16 v[12:15], v[80:83], v[124:127], v[12:15]
	ds_read_b128 v[104:107], v222 offset:53248
	s_waitcnt lgkmcnt(6)
	v_mfma_f32_16x16x32_bf16 v[16:19], v[84:87], v[112:115], v[16:19]
	ds_read_b128 v[108:111], v222 offset:55296
	s_waitcnt lgkmcnt(7)
	v_mfma_f32_16x16x32_bf16 v[20:23], v[84:87], v[116:119], v[20:23]
	ds_read_b128 v[68:71], v151 offset:18432
	s_waitcnt lgkmcnt(8)
	v_mfma_f32_16x16x32_bf16 v[24:27], v[84:87], v[120:123], v[24:27]
	ds_read_b128 v[72:75], v151 offset:20480
	s_waitcnt lgkmcnt(9)
	v_mfma_f32_16x16x32_bf16 v[28:31], v[84:87], v[124:127], v[28:31]
	ds_read_b128 v[76:79], v151 offset:22528
	s_waitcnt lgkmcnt(9)
	v_mfma_f32_16x16x32_bf16 v[32:35], v[88:91], v[112:115], v[32:35]
	s_waitcnt lgkmcnt(9)
	v_mfma_f32_16x16x32_bf16 v[36:39], v[88:91], v[116:119], v[36:39]
	s_waitcnt lgkmcnt(9)
	v_mfma_f32_16x16x32_bf16 v[40:43], v[88:91], v[120:123], v[40:43]
	s_waitcnt lgkmcnt(9)
	v_mfma_f32_16x16x32_bf16 v[44:47], v[88:91], v[124:127], v[44:47]
	s_waitcnt lgkmcnt(8)
	v_mfma_f32_16x16x32_bf16 v[48:51], v[92:95], v[112:115], v[48:51]
	s_waitcnt lgkmcnt(8)
	v_mfma_f32_16x16x32_bf16 v[52:55], v[92:95], v[116:119], v[52:55]
	s_waitcnt lgkmcnt(8)
	v_mfma_f32_16x16x32_bf16 v[56:59], v[92:95], v[120:123], v[56:59]
	s_waitcnt lgkmcnt(8)
	v_mfma_f32_16x16x32_bf16 v[60:63], v[92:95], v[124:127], v[60:63]
	s_waitcnt lgkmcnt(6)
	v_mfma_f32_16x16x32_bf16 v[160:163], v[64:67], v[96:99], v[160:163]
	ds_read_b128 v[80:83], v220 offset:16384
	s_waitcnt lgkmcnt(6)
	v_mfma_f32_16x16x32_bf16 v[164:167], v[64:67], v[100:103], v[164:167]
	ds_read_b128 v[112:115], v224 offset:49152
	s_waitcnt lgkmcnt(6)
	v_mfma_f32_16x16x32_bf16 v[168:171], v[64:67], v[104:107], v[168:171]
	ds_read_b128 v[116:119], v224 offset:51200
	s_waitcnt lgkmcnt(6)
	v_mfma_f32_16x16x32_bf16 v[172:175], v[64:67], v[108:111], v[172:175]
	ds_read_b128 v[120:123], v224 offset:53248
	s_waitcnt lgkmcnt(6)
	v_mfma_f32_16x16x32_bf16 v[176:179], v[68:71], v[96:99], v[176:179]
	ds_read_b128 v[124:127], v224 offset:55296
	s_waitcnt lgkmcnt(7)
	v_mfma_f32_16x16x32_bf16 v[180:183], v[68:71], v[100:103], v[180:183]
	ds_read_b128 v[84:87], v220 offset:18432
	s_waitcnt lgkmcnt(8)
	v_mfma_f32_16x16x32_bf16 v[184:187], v[68:71], v[104:107], v[184:187]
	ds_read_b128 v[88:91], v220 offset:20480
	s_waitcnt lgkmcnt(9)
	v_mfma_f32_16x16x32_bf16 v[188:191], v[68:71], v[108:111], v[188:191]
	ds_read_b128 v[92:95], v220 offset:22528
	s_waitcnt lgkmcnt(9)
	v_mfma_f32_16x16x32_bf16 v[192:195], v[72:75], v[96:99], v[192:195]
	s_waitcnt lgkmcnt(9)
	v_mfma_f32_16x16x32_bf16 v[196:199], v[72:75], v[100:103], v[196:199]
	s_waitcnt lgkmcnt(9)
	v_mfma_f32_16x16x32_bf16 v[200:203], v[72:75], v[104:107], v[200:203]
	s_waitcnt lgkmcnt(9)
	v_mfma_f32_16x16x32_bf16 v[204:207], v[72:75], v[108:111], v[204:207]
	s_waitcnt vmcnt(0) lgkmcnt(0)
	s_barrier
	s_add_u32 m0, s38, 16384
	s_nop 0
	global_load_lds_dwordx4 v226, s[100:101]
	s_waitcnt lgkmcnt(8)
	v_mfma_f32_16x16x32_bf16 v[208:211], v[76:79], v[96:99], v[208:211]
	s_add_u32 m0, s38, 20480
	s_nop 0
	global_load_lds_dwordx4 v228, s[100:101]
	s_waitcnt lgkmcnt(8)
	v_mfma_f32_16x16x32_bf16 v[212:215], v[76:79], v[100:103], v[212:215]
	s_add_u32 m0, s38, 24576
	s_nop 0
	global_load_lds_dwordx4 v244, s[100:101]
	s_waitcnt lgkmcnt(8)
	v_mfma_f32_16x16x32_bf16 v[216:219], v[76:79], v[104:107], v[216:219]
	s_add_u32 m0, s38, 28672
	s_nop 0
	global_load_lds_dwordx4 v245, s[100:101]
	s_add_u32 s100, s100, 128
	s_addc_u32 s101, s101, 0
	s_waitcnt lgkmcnt(8)
	v_mfma_f32_16x16x32_bf16 v[230:233], v[76:79], v[108:111], v[230:233]
	s_add_u32 m0, s38, 49152
	s_nop 0
	global_load_lds_dwordx4 v226, s[4:5]
	s_waitcnt lgkmcnt(6)
	v_mfma_f32_16x16x32_bf16 v[160:163], v[80:83], v[112:115], v[160:163]
	ds_read_b128 v[64:67], v151 offset:0
	s_add_u32 m0, s38, 53248
	s_nop 0
	global_load_lds_dwordx4 v228, s[4:5]
	s_waitcnt lgkmcnt(6)
	v_mfma_f32_16x16x32_bf16 v[164:167], v[80:83], v[116:119], v[164:167]
	ds_read_b128 v[96:99], v222 offset:32768
	s_add_u32 m0, s38, 57344
	s_nop 0
	global_load_lds_dwordx4 v244, s[4:5]
	s_waitcnt lgkmcnt(6)
	v_mfma_f32_16x16x32_bf16 v[168:171], v[80:83], v[120:123], v[168:171]
	ds_read_b128 v[100:103], v222 offset:34816
	s_add_u32 m0, s38, 61440
	s_nop 0
	global_load_lds_dwordx4 v245, s[4:5]
	s_add_u32 s4, s4, 128
	s_addc_u32 s5, s5, 0
	s_waitcnt lgkmcnt(6)
	v_mfma_f32_16x16x32_bf16 v[172:175], v[80:83], v[124:127], v[172:175]
	ds_read_b128 v[104:107], v222 offset:36864
	s_waitcnt lgkmcnt(6)
	v_mfma_f32_16x16x32_bf16 v[176:179], v[84:87], v[112:115], v[176:179]
	ds_read_b128 v[108:111], v222 offset:38912
	s_waitcnt lgkmcnt(7)
	v_mfma_f32_16x16x32_bf16 v[180:183], v[84:87], v[116:119], v[180:183]
	ds_read_b128 v[68:71], v151 offset:2048
	s_waitcnt lgkmcnt(8)
	v_mfma_f32_16x16x32_bf16 v[184:187], v[84:87], v[120:123], v[184:187]
	ds_read_b128 v[72:75], v151 offset:4096
	s_waitcnt lgkmcnt(9)
	v_mfma_f32_16x16x32_bf16 v[188:191], v[84:87], v[124:127], v[188:191]
	ds_read_b128 v[76:79], v151 offset:6144
	s_waitcnt lgkmcnt(9)
	v_mfma_f32_16x16x32_bf16 v[192:195], v[88:91], v[112:115], v[192:195]
	s_waitcnt lgkmcnt(9)
	v_mfma_f32_16x16x32_bf16 v[196:199], v[88:91], v[116:119], v[196:199]
	s_waitcnt lgkmcnt(9)
	v_mfma_f32_16x16x32_bf16 v[200:203], v[88:91], v[120:123], v[200:203]
	s_waitcnt lgkmcnt(9)
	v_mfma_f32_16x16x32_bf16 v[204:207], v[88:91], v[124:127], v[204:207]
	s_waitcnt lgkmcnt(8)
	v_mfma_f32_16x16x32_bf16 v[208:211], v[92:95], v[112:115], v[208:211]
	s_waitcnt lgkmcnt(8)
	v_mfma_f32_16x16x32_bf16 v[212:215], v[92:95], v[116:119], v[212:215]
	s_waitcnt lgkmcnt(8)
	v_mfma_f32_16x16x32_bf16 v[216:219], v[92:95], v[120:123], v[216:219]
	s_waitcnt lgkmcnt(8)
	v_mfma_f32_16x16x32_bf16 v[230:233], v[92:95], v[124:127], v[230:233]
	s_waitcnt lgkmcnt(6)
	v_mfma_f32_16x16x32_bf16 v[0:3], v[64:67], v[96:99], v[0:3]
	ds_read_b128 v[80:83], v220 offset:0
	s_waitcnt lgkmcnt(6)
	v_mfma_f32_16x16x32_bf16 v[4:7], v[64:67], v[100:103], v[4:7]
	ds_read_b128 v[112:115], v224 offset:32768
	s_waitcnt lgkmcnt(6)
	v_mfma_f32_16x16x32_bf16 v[8:11], v[64:67], v[104:107], v[8:11]
	ds_read_b128 v[116:119], v224 offset:34816
	s_waitcnt lgkmcnt(6)
	v_mfma_f32_16x16x32_bf16 v[12:15], v[64:67], v[108:111], v[12:15]
	ds_read_b128 v[120:123], v224 offset:36864
	s_waitcnt lgkmcnt(6)
	v_mfma_f32_16x16x32_bf16 v[16:19], v[68:71], v[96:99], v[16:19]
	ds_read_b128 v[124:127], v224 offset:38912
	s_waitcnt lgkmcnt(7)
	v_mfma_f32_16x16x32_bf16 v[20:23], v[68:71], v[100:103], v[20:23]
	ds_read_b128 v[84:87], v220 offset:2048
	s_waitcnt lgkmcnt(8)
	v_mfma_f32_16x16x32_bf16 v[24:27], v[68:71], v[104:107], v[24:27]
	ds_read_b128 v[88:91], v220 offset:4096
	s_waitcnt lgkmcnt(9)
	v_mfma_f32_16x16x32_bf16 v[28:31], v[68:71], v[108:111], v[28:31]
	ds_read_b128 v[92:95], v220 offset:6144
	s_waitcnt lgkmcnt(9)
	v_mfma_f32_16x16x32_bf16 v[32:35], v[72:75], v[96:99], v[32:35]
	s_waitcnt lgkmcnt(9)
	v_mfma_f32_16x16x32_bf16 v[36:39], v[72:75], v[100:103], v[36:39]
	s_waitcnt lgkmcnt(9)
	v_mfma_f32_16x16x32_bf16 v[40:43], v[72:75], v[104:107], v[40:43]
	s_waitcnt lgkmcnt(9)
	v_mfma_f32_16x16x32_bf16 v[44:47], v[72:75], v[108:111], v[44:47]
	s_waitcnt vmcnt(4) lgkmcnt(0)
	s_barrier
	s_add_u32 m0, s38, 0
	s_nop 0
	global_load_lds_dwordx4 v226, s[98:99]
	s_waitcnt lgkmcnt(8)
	v_mfma_f32_16x16x32_bf16 v[48:51], v[76:79], v[96:99], v[48:51]
	s_add_u32 m0, s38, 4096
	s_nop 0
	global_load_lds_dwordx4 v228, s[98:99]
	s_waitcnt lgkmcnt(8)
	v_mfma_f32_16x16x32_bf16 v[52:55], v[76:79], v[100:103], v[52:55]
	s_add_u32 m0, s38, 8192
	s_nop 0
	global_load_lds_dwordx4 v244, s[98:99]
	s_waitcnt lgkmcnt(8)
	v_mfma_f32_16x16x32_bf16 v[56:59], v[76:79], v[104:107], v[56:59]
	s_add_u32 m0, s38, 12288
	s_nop 0
	global_load_lds_dwordx4 v245, s[98:99]
	s_add_u32 s98, s98, 128
	s_addc_u32 s99, s99, 0
	s_waitcnt lgkmcnt(8)
	v_mfma_f32_16x16x32_bf16 v[60:63], v[76:79], v[108:111], v[60:63]
	s_waitcnt lgkmcnt(6)
	v_mfma_f32_16x16x32_bf16 v[0:3], v[80:83], v[112:115], v[0:3]
	ds_read_b128 v[64:67], v151 offset:16384
	s_waitcnt lgkmcnt(6)
	v_mfma_f32_16x16x32_bf16 v[4:7], v[80:83], v[116:119], v[4:7]
	ds_read_b128 v[96:99], v222 offset:32768
	s_waitcnt lgkmcnt(6)
	v_mfma_f32_16x16x32_bf16 v[8:11], v[80:83], v[120:123], v[8:11]
	ds_read_b128 v[100:103], v222 offset:34816
	s_waitcnt lgkmcnt(6)
	v_mfma_f32_16x16x32_bf16 v[12:15], v[80:83], v[124:127], v[12:15]
	ds_read_b128 v[104:107], v222 offset:36864
	s_waitcnt lgkmcnt(6)
	v_mfma_f32_16x16x32_bf16 v[16:19], v[84:87], v[112:115], v[16:19]
	ds_read_b128 v[108:111], v222 offset:38912
	s_waitcnt lgkmcnt(7)
	v_mfma_f32_16x16x32_bf16 v[20:23], v[84:87], v[116:119], v[20:23]
	ds_read_b128 v[68:71], v151 offset:18432
	s_waitcnt lgkmcnt(8)
	v_mfma_f32_16x16x32_bf16 v[24:27], v[84:87], v[120:123], v[24:27]
	ds_read_b128 v[72:75], v151 offset:20480
	s_waitcnt lgkmcnt(9)
	v_mfma_f32_16x16x32_bf16 v[28:31], v[84:87], v[124:127], v[28:31]
	ds_read_b128 v[76:79], v151 offset:22528
	s_waitcnt lgkmcnt(9)
	v_mfma_f32_16x16x32_bf16 v[32:35], v[88:91], v[112:115], v[32:35]
	s_waitcnt lgkmcnt(9)
	v_mfma_f32_16x16x32_bf16 v[36:39], v[88:91], v[116:119], v[36:39]
	s_waitcnt lgkmcnt(9)
	v_mfma_f32_16x16x32_bf16 v[40:43], v[88:91], v[120:123], v[40:43]
	s_waitcnt lgkmcnt(9)
	v_mfma_f32_16x16x32_bf16 v[44:47], v[88:91], v[124:127], v[44:47]
	s_waitcnt lgkmcnt(8)
	v_mfma_f32_16x16x32_bf16 v[48:51], v[92:95], v[112:115], v[48:51]
	s_waitcnt lgkmcnt(8)
	v_mfma_f32_16x16x32_bf16 v[52:55], v[92:95], v[116:119], v[52:55]
	s_waitcnt lgkmcnt(8)
	v_mfma_f32_16x16x32_bf16 v[56:59], v[92:95], v[120:123], v[56:59]
	s_waitcnt lgkmcnt(8)
	v_mfma_f32_16x16x32_bf16 v[60:63], v[92:95], v[124:127], v[60:63]
	s_waitcnt lgkmcnt(6)
	v_mfma_f32_16x16x32_bf16 v[160:163], v[64:67], v[96:99], v[160:163]
	ds_read_b128 v[80:83], v220 offset:16384
	s_waitcnt lgkmcnt(6)
	v_mfma_f32_16x16x32_bf16 v[164:167], v[64:67], v[100:103], v[164:167]
	ds_read_b128 v[112:115], v224 offset:32768
	s_waitcnt lgkmcnt(6)
	v_mfma_f32_16x16x32_bf16 v[168:171], v[64:67], v[104:107], v[168:171]
	ds_read_b128 v[116:119], v224 offset:34816
	s_waitcnt lgkmcnt(6)
	v_mfma_f32_16x16x32_bf16 v[172:175], v[64:67], v[108:111], v[172:175]
	ds_read_b128 v[120:123], v224 offset:36864
	s_waitcnt lgkmcnt(6)
	v_mfma_f32_16x16x32_bf16 v[176:179], v[68:71], v[96:99], v[176:179]
	ds_read_b128 v[124:127], v224 offset:38912
	s_waitcnt lgkmcnt(7)
	v_mfma_f32_16x16x32_bf16 v[180:183], v[68:71], v[100:103], v[180:183]
	ds_read_b128 v[84:87], v220 offset:18432
	s_waitcnt lgkmcnt(8)
	v_mfma_f32_16x16x32_bf16 v[184:187], v[68:71], v[104:107], v[184:187]
	ds_read_b128 v[88:91], v220 offset:20480
	s_waitcnt lgkmcnt(9)
	v_mfma_f32_16x16x32_bf16 v[188:191], v[68:71], v[108:111], v[188:191]
	ds_read_b128 v[92:95], v220 offset:22528
	s_waitcnt lgkmcnt(9)
	v_mfma_f32_16x16x32_bf16 v[192:195], v[72:75], v[96:99], v[192:195]
	s_waitcnt lgkmcnt(9)
	v_mfma_f32_16x16x32_bf16 v[196:199], v[72:75], v[100:103], v[196:199]
	s_waitcnt lgkmcnt(9)
	v_mfma_f32_16x16x32_bf16 v[200:203], v[72:75], v[104:107], v[200:203]
	s_waitcnt lgkmcnt(9)
	v_mfma_f32_16x16x32_bf16 v[204:207], v[72:75], v[108:111], v[204:207]
	s_waitcnt vmcnt(0) lgkmcnt(0)
	s_barrier
	s_add_u32 m0, s38, 16384
	s_nop 0
	global_load_lds_dwordx4 v226, s[100:101]
	s_waitcnt lgkmcnt(8)
	v_mfma_f32_16x16x32_bf16 v[208:211], v[76:79], v[96:99], v[208:211]
	s_add_u32 m0, s38, 20480
	s_nop 0
	global_load_lds_dwordx4 v228, s[100:101]
	s_waitcnt lgkmcnt(8)
	v_mfma_f32_16x16x32_bf16 v[212:215], v[76:79], v[100:103], v[212:215]
	s_add_u32 m0, s38, 24576
	s_nop 0
	global_load_lds_dwordx4 v244, s[100:101]
	s_waitcnt lgkmcnt(8)
	v_mfma_f32_16x16x32_bf16 v[216:219], v[76:79], v[104:107], v[216:219]
	s_add_u32 m0, s38, 28672
	s_nop 0
	global_load_lds_dwordx4 v245, s[100:101]
	s_add_u32 s100, s100, 128
	s_addc_u32 s101, s101, 0
	s_waitcnt lgkmcnt(8)
	v_mfma_f32_16x16x32_bf16 v[230:233], v[76:79], v[108:111], v[230:233]
	s_add_u32 m0, s38, 32768
	s_nop 0
	global_load_lds_dwordx4 v226, s[4:5]
	s_waitcnt lgkmcnt(6)
	v_mfma_f32_16x16x32_bf16 v[160:163], v[80:83], v[112:115], v[160:163]
	ds_read_b128 v[64:67], v151 offset:0
	s_add_u32 m0, s38, 36864
	s_nop 0
	global_load_lds_dwordx4 v228, s[4:5]
	s_waitcnt lgkmcnt(6)
	v_mfma_f32_16x16x32_bf16 v[164:167], v[80:83], v[116:119], v[164:167]
	ds_read_b128 v[96:99], v222 offset:49152
	s_add_u32 m0, s38, 40960
	s_nop 0
	global_load_lds_dwordx4 v244, s[4:5]
	s_waitcnt lgkmcnt(6)
	v_mfma_f32_16x16x32_bf16 v[168:171], v[80:83], v[120:123], v[168:171]
	ds_read_b128 v[100:103], v222 offset:51200
	s_add_u32 m0, s38, 45056
	s_nop 0
	global_load_lds_dwordx4 v245, s[4:5]
	s_add_u32 s4, s4, 128
	s_addc_u32 s5, s5, 0
	s_waitcnt lgkmcnt(6)
	v_mfma_f32_16x16x32_bf16 v[172:175], v[80:83], v[124:127], v[172:175]
	ds_read_b128 v[104:107], v222 offset:53248
	s_waitcnt lgkmcnt(6)
	v_mfma_f32_16x16x32_bf16 v[176:179], v[84:87], v[112:115], v[176:179]
	ds_read_b128 v[108:111], v222 offset:55296
	s_waitcnt lgkmcnt(7)
	v_mfma_f32_16x16x32_bf16 v[180:183], v[84:87], v[116:119], v[180:183]
	ds_read_b128 v[68:71], v151 offset:2048
	s_waitcnt lgkmcnt(8)
	v_mfma_f32_16x16x32_bf16 v[184:187], v[84:87], v[120:123], v[184:187]
	ds_read_b128 v[72:75], v151 offset:4096
	s_waitcnt lgkmcnt(9)
	v_mfma_f32_16x16x32_bf16 v[188:191], v[84:87], v[124:127], v[188:191]
	ds_read_b128 v[76:79], v151 offset:6144
	s_waitcnt lgkmcnt(9)
	v_mfma_f32_16x16x32_bf16 v[192:195], v[88:91], v[112:115], v[192:195]
	s_waitcnt lgkmcnt(9)
	v_mfma_f32_16x16x32_bf16 v[196:199], v[88:91], v[116:119], v[196:199]
	s_waitcnt lgkmcnt(9)
	v_mfma_f32_16x16x32_bf16 v[200:203], v[88:91], v[120:123], v[200:203]
	s_waitcnt lgkmcnt(9)
	v_mfma_f32_16x16x32_bf16 v[204:207], v[88:91], v[124:127], v[204:207]
	s_waitcnt lgkmcnt(8)
	v_mfma_f32_16x16x32_bf16 v[208:211], v[92:95], v[112:115], v[208:211]
	s_waitcnt lgkmcnt(8)
	v_mfma_f32_16x16x32_bf16 v[212:215], v[92:95], v[116:119], v[212:215]
	s_waitcnt lgkmcnt(8)
	v_mfma_f32_16x16x32_bf16 v[216:219], v[92:95], v[120:123], v[216:219]
	s_waitcnt lgkmcnt(8)
	v_mfma_f32_16x16x32_bf16 v[230:233], v[92:95], v[124:127], v[230:233]
	s_waitcnt lgkmcnt(6)
	v_mfma_f32_16x16x32_bf16 v[0:3], v[64:67], v[96:99], v[0:3]
	ds_read_b128 v[80:83], v220 offset:0
	s_waitcnt lgkmcnt(6)
	v_mfma_f32_16x16x32_bf16 v[4:7], v[64:67], v[100:103], v[4:7]
	ds_read_b128 v[112:115], v224 offset:49152
	s_waitcnt lgkmcnt(6)
	v_mfma_f32_16x16x32_bf16 v[8:11], v[64:67], v[104:107], v[8:11]
	ds_read_b128 v[116:119], v224 offset:51200
	s_waitcnt lgkmcnt(6)
	v_mfma_f32_16x16x32_bf16 v[12:15], v[64:67], v[108:111], v[12:15]
	ds_read_b128 v[120:123], v224 offset:53248
	s_waitcnt lgkmcnt(6)
	v_mfma_f32_16x16x32_bf16 v[16:19], v[68:71], v[96:99], v[16:19]
	ds_read_b128 v[124:127], v224 offset:55296
	s_waitcnt lgkmcnt(7)
	v_mfma_f32_16x16x32_bf16 v[20:23], v[68:71], v[100:103], v[20:23]
	ds_read_b128 v[84:87], v220 offset:2048
	s_waitcnt lgkmcnt(8)
	v_mfma_f32_16x16x32_bf16 v[24:27], v[68:71], v[104:107], v[24:27]
	ds_read_b128 v[88:91], v220 offset:4096
	s_waitcnt lgkmcnt(9)
	v_mfma_f32_16x16x32_bf16 v[28:31], v[68:71], v[108:111], v[28:31]
	ds_read_b128 v[92:95], v220 offset:6144
	s_waitcnt lgkmcnt(9)
	v_mfma_f32_16x16x32_bf16 v[32:35], v[72:75], v[96:99], v[32:35]
	s_waitcnt lgkmcnt(9)
	v_mfma_f32_16x16x32_bf16 v[36:39], v[72:75], v[100:103], v[36:39]
	s_waitcnt lgkmcnt(9)
	v_mfma_f32_16x16x32_bf16 v[40:43], v[72:75], v[104:107], v[40:43]
	s_waitcnt lgkmcnt(9)
	v_mfma_f32_16x16x32_bf16 v[44:47], v[72:75], v[108:111], v[44:47]
	s_waitcnt vmcnt(4) lgkmcnt(0)
	s_barrier
	s_add_u32 m0, s38, 0
	s_nop 0
	global_load_lds_dwordx4 v226, s[98:99]
	s_waitcnt lgkmcnt(8)
	v_mfma_f32_16x16x32_bf16 v[48:51], v[76:79], v[96:99], v[48:51]
	s_add_u32 m0, s38, 4096
	s_nop 0
	global_load_lds_dwordx4 v228, s[98:99]
	s_waitcnt lgkmcnt(8)
	v_mfma_f32_16x16x32_bf16 v[52:55], v[76:79], v[100:103], v[52:55]
	s_add_u32 m0, s38, 8192
	s_nop 0
	global_load_lds_dwordx4 v244, s[98:99]
	s_waitcnt lgkmcnt(8)
	v_mfma_f32_16x16x32_bf16 v[56:59], v[76:79], v[104:107], v[56:59]
	s_add_u32 m0, s38, 12288
	s_nop 0
	global_load_lds_dwordx4 v245, s[98:99]
	s_add_u32 s98, s98, 128
	s_addc_u32 s99, s99, 0
	s_waitcnt lgkmcnt(8)
	v_mfma_f32_16x16x32_bf16 v[60:63], v[76:79], v[108:111], v[60:63]
	s_waitcnt lgkmcnt(6)
	v_mfma_f32_16x16x32_bf16 v[0:3], v[80:83], v[112:115], v[0:3]
	ds_read_b128 v[64:67], v151 offset:16384
	s_waitcnt lgkmcnt(6)
	v_mfma_f32_16x16x32_bf16 v[4:7], v[80:83], v[116:119], v[4:7]
	ds_read_b128 v[96:99], v222 offset:49152
	s_waitcnt lgkmcnt(6)
	v_mfma_f32_16x16x32_bf16 v[8:11], v[80:83], v[120:123], v[8:11]
	ds_read_b128 v[100:103], v222 offset:51200
	s_waitcnt lgkmcnt(6)
	v_mfma_f32_16x16x32_bf16 v[12:15], v[80:83], v[124:127], v[12:15]
	ds_read_b128 v[104:107], v222 offset:53248
	s_waitcnt lgkmcnt(6)
	v_mfma_f32_16x16x32_bf16 v[16:19], v[84:87], v[112:115], v[16:19]
	ds_read_b128 v[108:111], v222 offset:55296
	s_waitcnt lgkmcnt(7)
	v_mfma_f32_16x16x32_bf16 v[20:23], v[84:87], v[116:119], v[20:23]
	ds_read_b128 v[68:71], v151 offset:18432
	s_waitcnt lgkmcnt(8)
	v_mfma_f32_16x16x32_bf16 v[24:27], v[84:87], v[120:123], v[24:27]
	ds_read_b128 v[72:75], v151 offset:20480
	s_waitcnt lgkmcnt(9)
	v_mfma_f32_16x16x32_bf16 v[28:31], v[84:87], v[124:127], v[28:31]
	ds_read_b128 v[76:79], v151 offset:22528
	s_waitcnt lgkmcnt(9)
	v_mfma_f32_16x16x32_bf16 v[32:35], v[88:91], v[112:115], v[32:35]
	s_waitcnt lgkmcnt(9)
	v_mfma_f32_16x16x32_bf16 v[36:39], v[88:91], v[116:119], v[36:39]
	s_waitcnt lgkmcnt(9)
	v_mfma_f32_16x16x32_bf16 v[40:43], v[88:91], v[120:123], v[40:43]
	s_waitcnt lgkmcnt(9)
	v_mfma_f32_16x16x32_bf16 v[44:47], v[88:91], v[124:127], v[44:47]
	s_waitcnt lgkmcnt(8)
	v_mfma_f32_16x16x32_bf16 v[48:51], v[92:95], v[112:115], v[48:51]
	s_waitcnt lgkmcnt(8)
	v_mfma_f32_16x16x32_bf16 v[52:55], v[92:95], v[116:119], v[52:55]
	s_waitcnt lgkmcnt(8)
	v_mfma_f32_16x16x32_bf16 v[56:59], v[92:95], v[120:123], v[56:59]
	s_waitcnt lgkmcnt(8)
	v_mfma_f32_16x16x32_bf16 v[60:63], v[92:95], v[124:127], v[60:63]
	s_waitcnt lgkmcnt(6)
	v_mfma_f32_16x16x32_bf16 v[160:163], v[64:67], v[96:99], v[160:163]
	ds_read_b128 v[80:83], v220 offset:16384
	s_waitcnt lgkmcnt(6)
	v_mfma_f32_16x16x32_bf16 v[164:167], v[64:67], v[100:103], v[164:167]
	ds_read_b128 v[112:115], v224 offset:49152
	s_waitcnt lgkmcnt(6)
	v_mfma_f32_16x16x32_bf16 v[168:171], v[64:67], v[104:107], v[168:171]
	ds_read_b128 v[116:119], v224 offset:51200
	s_waitcnt lgkmcnt(6)
	v_mfma_f32_16x16x32_bf16 v[172:175], v[64:67], v[108:111], v[172:175]
	ds_read_b128 v[120:123], v224 offset:53248
	s_waitcnt lgkmcnt(6)
	v_mfma_f32_16x16x32_bf16 v[176:179], v[68:71], v[96:99], v[176:179]
	ds_read_b128 v[124:127], v224 offset:55296
	s_waitcnt lgkmcnt(7)
	v_mfma_f32_16x16x32_bf16 v[180:183], v[68:71], v[100:103], v[180:183]
	ds_read_b128 v[84:87], v220 offset:18432
	s_waitcnt lgkmcnt(8)
	v_mfma_f32_16x16x32_bf16 v[184:187], v[68:71], v[104:107], v[184:187]
	ds_read_b128 v[88:91], v220 offset:20480
	s_waitcnt lgkmcnt(9)
	v_mfma_f32_16x16x32_bf16 v[188:191], v[68:71], v[108:111], v[188:191]
	ds_read_b128 v[92:95], v220 offset:22528
	s_waitcnt lgkmcnt(9)
	v_mfma_f32_16x16x32_bf16 v[192:195], v[72:75], v[96:99], v[192:195]
	s_waitcnt lgkmcnt(9)
	v_mfma_f32_16x16x32_bf16 v[196:199], v[72:75], v[100:103], v[196:199]
	s_waitcnt lgkmcnt(9)
	v_mfma_f32_16x16x32_bf16 v[200:203], v[72:75], v[104:107], v[200:203]
	s_waitcnt lgkmcnt(9)
	v_mfma_f32_16x16x32_bf16 v[204:207], v[72:75], v[108:111], v[204:207]
	s_waitcnt vmcnt(0) lgkmcnt(0)
	s_barrier
	s_add_u32 m0, s38, 16384
	s_nop 0
	global_load_lds_dwordx4 v226, s[100:101]
	s_waitcnt lgkmcnt(8)
	v_mfma_f32_16x16x32_bf16 v[208:211], v[76:79], v[96:99], v[208:211]
	s_add_u32 m0, s38, 20480
	s_nop 0
	global_load_lds_dwordx4 v228, s[100:101]
	s_waitcnt lgkmcnt(8)
	v_mfma_f32_16x16x32_bf16 v[212:215], v[76:79], v[100:103], v[212:215]
	s_add_u32 m0, s38, 24576
	s_nop 0
	global_load_lds_dwordx4 v244, s[100:101]
	s_waitcnt lgkmcnt(8)
	v_mfma_f32_16x16x32_bf16 v[216:219], v[76:79], v[104:107], v[216:219]
	s_add_u32 m0, s38, 28672
	s_nop 0
	global_load_lds_dwordx4 v245, s[100:101]
	s_add_u32 s100, s100, 128
	s_addc_u32 s101, s101, 0
	s_waitcnt lgkmcnt(8)
	v_mfma_f32_16x16x32_bf16 v[230:233], v[76:79], v[108:111], v[230:233]
	s_add_u32 m0, s38, 49152
	s_nop 0
	global_load_lds_dwordx4 v226, s[4:5]
	s_waitcnt lgkmcnt(6)
	v_mfma_f32_16x16x32_bf16 v[160:163], v[80:83], v[112:115], v[160:163]
	ds_read_b128 v[64:67], v151 offset:0
	s_add_u32 m0, s38, 53248
	s_nop 0
	global_load_lds_dwordx4 v228, s[4:5]
	s_waitcnt lgkmcnt(6)
	v_mfma_f32_16x16x32_bf16 v[164:167], v[80:83], v[116:119], v[164:167]
	ds_read_b128 v[96:99], v222 offset:32768
	s_add_u32 m0, s38, 57344
	s_nop 0
	global_load_lds_dwordx4 v244, s[4:5]
	s_waitcnt lgkmcnt(6)
	v_mfma_f32_16x16x32_bf16 v[168:171], v[80:83], v[120:123], v[168:171]
	ds_read_b128 v[100:103], v222 offset:34816
	s_add_u32 m0, s38, 61440
	s_nop 0
	global_load_lds_dwordx4 v245, s[4:5]
	s_add_u32 s4, s4, 128
	s_addc_u32 s5, s5, 0
	s_waitcnt lgkmcnt(6)
	v_mfma_f32_16x16x32_bf16 v[172:175], v[80:83], v[124:127], v[172:175]
	ds_read_b128 v[104:107], v222 offset:36864
	s_waitcnt lgkmcnt(6)
	v_mfma_f32_16x16x32_bf16 v[176:179], v[84:87], v[112:115], v[176:179]
	ds_read_b128 v[108:111], v222 offset:38912
	s_waitcnt lgkmcnt(7)
	v_mfma_f32_16x16x32_bf16 v[180:183], v[84:87], v[116:119], v[180:183]
	ds_read_b128 v[68:71], v151 offset:2048
	s_waitcnt lgkmcnt(8)
	v_mfma_f32_16x16x32_bf16 v[184:187], v[84:87], v[120:123], v[184:187]
	ds_read_b128 v[72:75], v151 offset:4096
	s_waitcnt lgkmcnt(9)
	v_mfma_f32_16x16x32_bf16 v[188:191], v[84:87], v[124:127], v[188:191]
	ds_read_b128 v[76:79], v151 offset:6144
	s_waitcnt lgkmcnt(9)
	v_mfma_f32_16x16x32_bf16 v[192:195], v[88:91], v[112:115], v[192:195]
	s_waitcnt lgkmcnt(9)
	v_mfma_f32_16x16x32_bf16 v[196:199], v[88:91], v[116:119], v[196:199]
	s_waitcnt lgkmcnt(9)
	v_mfma_f32_16x16x32_bf16 v[200:203], v[88:91], v[120:123], v[200:203]
	s_waitcnt lgkmcnt(9)
	v_mfma_f32_16x16x32_bf16 v[204:207], v[88:91], v[124:127], v[204:207]
	s_waitcnt lgkmcnt(8)
	v_mfma_f32_16x16x32_bf16 v[208:211], v[92:95], v[112:115], v[208:211]
	s_waitcnt lgkmcnt(8)
	v_mfma_f32_16x16x32_bf16 v[212:215], v[92:95], v[116:119], v[212:215]
	s_waitcnt lgkmcnt(8)
	v_mfma_f32_16x16x32_bf16 v[216:219], v[92:95], v[120:123], v[216:219]
	s_waitcnt lgkmcnt(8)
	v_mfma_f32_16x16x32_bf16 v[230:233], v[92:95], v[124:127], v[230:233]
	s_waitcnt lgkmcnt(6)
	v_mfma_f32_16x16x32_bf16 v[0:3], v[64:67], v[96:99], v[0:3]
	ds_read_b128 v[80:83], v220 offset:0
	s_waitcnt lgkmcnt(6)
	v_mfma_f32_16x16x32_bf16 v[4:7], v[64:67], v[100:103], v[4:7]
	ds_read_b128 v[112:115], v224 offset:32768
	s_waitcnt lgkmcnt(6)
	v_mfma_f32_16x16x32_bf16 v[8:11], v[64:67], v[104:107], v[8:11]
	ds_read_b128 v[116:119], v224 offset:34816
	s_waitcnt lgkmcnt(6)
	v_mfma_f32_16x16x32_bf16 v[12:15], v[64:67], v[108:111], v[12:15]
	ds_read_b128 v[120:123], v224 offset:36864
	s_waitcnt lgkmcnt(6)
	v_mfma_f32_16x16x32_bf16 v[16:19], v[68:71], v[96:99], v[16:19]
	ds_read_b128 v[124:127], v224 offset:38912
	s_waitcnt lgkmcnt(7)
	v_mfma_f32_16x16x32_bf16 v[20:23], v[68:71], v[100:103], v[20:23]
	ds_read_b128 v[84:87], v220 offset:2048
	s_waitcnt lgkmcnt(8)
	v_mfma_f32_16x16x32_bf16 v[24:27], v[68:71], v[104:107], v[24:27]
	ds_read_b128 v[88:91], v220 offset:4096
	s_waitcnt lgkmcnt(9)
	v_mfma_f32_16x16x32_bf16 v[28:31], v[68:71], v[108:111], v[28:31]
	ds_read_b128 v[92:95], v220 offset:6144
	s_waitcnt lgkmcnt(9)
	v_mfma_f32_16x16x32_bf16 v[32:35], v[72:75], v[96:99], v[32:35]
	s_waitcnt lgkmcnt(9)
	v_mfma_f32_16x16x32_bf16 v[36:39], v[72:75], v[100:103], v[36:39]
	s_waitcnt lgkmcnt(9)
	v_mfma_f32_16x16x32_bf16 v[40:43], v[72:75], v[104:107], v[40:43]
	s_waitcnt lgkmcnt(9)
	v_mfma_f32_16x16x32_bf16 v[44:47], v[72:75], v[108:111], v[44:47]
	s_waitcnt vmcnt(4) lgkmcnt(0)
	s_barrier
	s_add_u32 m0, s38, 0
	s_nop 0
	global_load_lds_dwordx4 v226, s[98:99]
	s_waitcnt lgkmcnt(8)
	v_mfma_f32_16x16x32_bf16 v[48:51], v[76:79], v[96:99], v[48:51]
	s_add_u32 m0, s38, 4096
	s_nop 0
	global_load_lds_dwordx4 v228, s[98:99]
	s_waitcnt lgkmcnt(8)
	v_mfma_f32_16x16x32_bf16 v[52:55], v[76:79], v[100:103], v[52:55]
	s_add_u32 m0, s38, 8192
	s_nop 0
	global_load_lds_dwordx4 v244, s[98:99]
	s_waitcnt lgkmcnt(8)
	v_mfma_f32_16x16x32_bf16 v[56:59], v[76:79], v[104:107], v[56:59]
	s_add_u32 m0, s38, 12288
	s_nop 0
	global_load_lds_dwordx4 v245, s[98:99]
	s_add_u32 s98, s98, 128
	s_addc_u32 s99, s99, 0
	s_waitcnt lgkmcnt(8)
	v_mfma_f32_16x16x32_bf16 v[60:63], v[76:79], v[108:111], v[60:63]
	s_waitcnt lgkmcnt(6)
	v_mfma_f32_16x16x32_bf16 v[0:3], v[80:83], v[112:115], v[0:3]
	ds_read_b128 v[64:67], v151 offset:16384
	s_waitcnt lgkmcnt(6)
	v_mfma_f32_16x16x32_bf16 v[4:7], v[80:83], v[116:119], v[4:7]
	ds_read_b128 v[96:99], v222 offset:32768
	s_waitcnt lgkmcnt(6)
	v_mfma_f32_16x16x32_bf16 v[8:11], v[80:83], v[120:123], v[8:11]
	ds_read_b128 v[100:103], v222 offset:34816
	s_waitcnt lgkmcnt(6)
	v_mfma_f32_16x16x32_bf16 v[12:15], v[80:83], v[124:127], v[12:15]
	ds_read_b128 v[104:107], v222 offset:36864
	s_waitcnt lgkmcnt(6)
	v_mfma_f32_16x16x32_bf16 v[16:19], v[84:87], v[112:115], v[16:19]
	ds_read_b128 v[108:111], v222 offset:38912
	s_waitcnt lgkmcnt(7)
	v_mfma_f32_16x16x32_bf16 v[20:23], v[84:87], v[116:119], v[20:23]
	ds_read_b128 v[68:71], v151 offset:18432
	s_waitcnt lgkmcnt(8)
	v_mfma_f32_16x16x32_bf16 v[24:27], v[84:87], v[120:123], v[24:27]
	ds_read_b128 v[72:75], v151 offset:20480
	s_waitcnt lgkmcnt(9)
	v_mfma_f32_16x16x32_bf16 v[28:31], v[84:87], v[124:127], v[28:31]
	ds_read_b128 v[76:79], v151 offset:22528
	s_waitcnt lgkmcnt(9)
	v_mfma_f32_16x16x32_bf16 v[32:35], v[88:91], v[112:115], v[32:35]
	s_waitcnt lgkmcnt(9)
	v_mfma_f32_16x16x32_bf16 v[36:39], v[88:91], v[116:119], v[36:39]
	s_waitcnt lgkmcnt(9)
	v_mfma_f32_16x16x32_bf16 v[40:43], v[88:91], v[120:123], v[40:43]
	s_waitcnt lgkmcnt(9)
	v_mfma_f32_16x16x32_bf16 v[44:47], v[88:91], v[124:127], v[44:47]
	s_waitcnt lgkmcnt(8)
	v_mfma_f32_16x16x32_bf16 v[48:51], v[92:95], v[112:115], v[48:51]
	s_waitcnt lgkmcnt(8)
	v_mfma_f32_16x16x32_bf16 v[52:55], v[92:95], v[116:119], v[52:55]
	s_waitcnt lgkmcnt(8)
	v_mfma_f32_16x16x32_bf16 v[56:59], v[92:95], v[120:123], v[56:59]
	s_waitcnt lgkmcnt(8)
	v_mfma_f32_16x16x32_bf16 v[60:63], v[92:95], v[124:127], v[60:63]
	s_waitcnt lgkmcnt(6)
	v_mfma_f32_16x16x32_bf16 v[160:163], v[64:67], v[96:99], v[160:163]
	ds_read_b128 v[80:83], v220 offset:16384
	s_waitcnt lgkmcnt(6)
	v_mfma_f32_16x16x32_bf16 v[164:167], v[64:67], v[100:103], v[164:167]
	ds_read_b128 v[112:115], v224 offset:32768
	s_waitcnt lgkmcnt(6)
	v_mfma_f32_16x16x32_bf16 v[168:171], v[64:67], v[104:107], v[168:171]
	ds_read_b128 v[116:119], v224 offset:34816
	s_waitcnt lgkmcnt(6)
	v_mfma_f32_16x16x32_bf16 v[172:175], v[64:67], v[108:111], v[172:175]
	ds_read_b128 v[120:123], v224 offset:36864
	s_waitcnt lgkmcnt(6)
	v_mfma_f32_16x16x32_bf16 v[176:179], v[68:71], v[96:99], v[176:179]
	ds_read_b128 v[124:127], v224 offset:38912
	s_waitcnt lgkmcnt(7)
	v_mfma_f32_16x16x32_bf16 v[180:183], v[68:71], v[100:103], v[180:183]
	ds_read_b128 v[84:87], v220 offset:18432
	s_waitcnt lgkmcnt(8)
	v_mfma_f32_16x16x32_bf16 v[184:187], v[68:71], v[104:107], v[184:187]
	ds_read_b128 v[88:91], v220 offset:20480
	s_waitcnt lgkmcnt(9)
	v_mfma_f32_16x16x32_bf16 v[188:191], v[68:71], v[108:111], v[188:191]
	ds_read_b128 v[92:95], v220 offset:22528
	s_waitcnt lgkmcnt(9)
	v_mfma_f32_16x16x32_bf16 v[192:195], v[72:75], v[96:99], v[192:195]
	s_waitcnt lgkmcnt(9)
	v_mfma_f32_16x16x32_bf16 v[196:199], v[72:75], v[100:103], v[196:199]
	s_waitcnt lgkmcnt(9)
	v_mfma_f32_16x16x32_bf16 v[200:203], v[72:75], v[104:107], v[200:203]
	s_waitcnt lgkmcnt(9)
	v_mfma_f32_16x16x32_bf16 v[204:207], v[72:75], v[108:111], v[204:207]
	s_waitcnt vmcnt(0) lgkmcnt(0)
	s_barrier
	s_add_u32 m0, s38, 16384
	s_nop 0
	global_load_lds_dwordx4 v226, s[100:101]
	s_waitcnt lgkmcnt(8)
	v_mfma_f32_16x16x32_bf16 v[208:211], v[76:79], v[96:99], v[208:211]
	s_add_u32 m0, s38, 20480
	s_nop 0
	global_load_lds_dwordx4 v228, s[100:101]
	s_waitcnt lgkmcnt(8)
	v_mfma_f32_16x16x32_bf16 v[212:215], v[76:79], v[100:103], v[212:215]
	s_add_u32 m0, s38, 24576
	s_nop 0
	global_load_lds_dwordx4 v244, s[100:101]
	s_waitcnt lgkmcnt(8)
	v_mfma_f32_16x16x32_bf16 v[216:219], v[76:79], v[104:107], v[216:219]
	s_add_u32 m0, s38, 28672
	s_nop 0
	global_load_lds_dwordx4 v245, s[100:101]
	s_add_u32 s100, s100, 128
	s_addc_u32 s101, s101, 0
	s_waitcnt lgkmcnt(8)
	v_mfma_f32_16x16x32_bf16 v[230:233], v[76:79], v[108:111], v[230:233]
	s_add_u32 m0, s38, 32768
	s_nop 0
	global_load_lds_dwordx4 v226, s[4:5]
	s_waitcnt lgkmcnt(6)
	v_mfma_f32_16x16x32_bf16 v[160:163], v[80:83], v[112:115], v[160:163]
	ds_read_b128 v[64:67], v151 offset:0
	s_add_u32 m0, s38, 36864
	s_nop 0
	global_load_lds_dwordx4 v228, s[4:5]
	s_waitcnt lgkmcnt(6)
	v_mfma_f32_16x16x32_bf16 v[164:167], v[80:83], v[116:119], v[164:167]
	ds_read_b128 v[96:99], v222 offset:49152
	s_add_u32 m0, s38, 40960
	s_nop 0
	global_load_lds_dwordx4 v244, s[4:5]
	s_waitcnt lgkmcnt(6)
	v_mfma_f32_16x16x32_bf16 v[168:171], v[80:83], v[120:123], v[168:171]
	ds_read_b128 v[100:103], v222 offset:51200
	s_add_u32 m0, s38, 45056
	s_nop 0
	global_load_lds_dwordx4 v245, s[4:5]
	s_add_u32 s4, s4, 128
	s_addc_u32 s5, s5, 0
	s_waitcnt lgkmcnt(6)
	v_mfma_f32_16x16x32_bf16 v[172:175], v[80:83], v[124:127], v[172:175]
	ds_read_b128 v[104:107], v222 offset:53248
	s_waitcnt lgkmcnt(6)
	v_mfma_f32_16x16x32_bf16 v[176:179], v[84:87], v[112:115], v[176:179]
	ds_read_b128 v[108:111], v222 offset:55296
	s_waitcnt lgkmcnt(7)
	v_mfma_f32_16x16x32_bf16 v[180:183], v[84:87], v[116:119], v[180:183]
	ds_read_b128 v[68:71], v151 offset:2048
	s_waitcnt lgkmcnt(8)
	v_mfma_f32_16x16x32_bf16 v[184:187], v[84:87], v[120:123], v[184:187]
	ds_read_b128 v[72:75], v151 offset:4096
	s_waitcnt lgkmcnt(9)
	v_mfma_f32_16x16x32_bf16 v[188:191], v[84:87], v[124:127], v[188:191]
	ds_read_b128 v[76:79], v151 offset:6144
	s_waitcnt lgkmcnt(9)
	v_mfma_f32_16x16x32_bf16 v[192:195], v[88:91], v[112:115], v[192:195]
	s_waitcnt lgkmcnt(9)
	v_mfma_f32_16x16x32_bf16 v[196:199], v[88:91], v[116:119], v[196:199]
	s_waitcnt lgkmcnt(9)
	v_mfma_f32_16x16x32_bf16 v[200:203], v[88:91], v[120:123], v[200:203]
	s_waitcnt lgkmcnt(9)
	v_mfma_f32_16x16x32_bf16 v[204:207], v[88:91], v[124:127], v[204:207]
	s_waitcnt lgkmcnt(8)
	v_mfma_f32_16x16x32_bf16 v[208:211], v[92:95], v[112:115], v[208:211]
	s_waitcnt lgkmcnt(8)
	v_mfma_f32_16x16x32_bf16 v[212:215], v[92:95], v[116:119], v[212:215]
	s_waitcnt lgkmcnt(8)
	v_mfma_f32_16x16x32_bf16 v[216:219], v[92:95], v[120:123], v[216:219]
	s_waitcnt lgkmcnt(8)
	v_mfma_f32_16x16x32_bf16 v[230:233], v[92:95], v[124:127], v[230:233]
	s_waitcnt lgkmcnt(6)
	v_mfma_f32_16x16x32_bf16 v[0:3], v[64:67], v[96:99], v[0:3]
	ds_read_b128 v[80:83], v220 offset:0
	s_waitcnt lgkmcnt(6)
	v_mfma_f32_16x16x32_bf16 v[4:7], v[64:67], v[100:103], v[4:7]
	ds_read_b128 v[112:115], v224 offset:49152
	s_waitcnt lgkmcnt(6)
	v_mfma_f32_16x16x32_bf16 v[8:11], v[64:67], v[104:107], v[8:11]
	ds_read_b128 v[116:119], v224 offset:51200
	s_waitcnt lgkmcnt(6)
	v_mfma_f32_16x16x32_bf16 v[12:15], v[64:67], v[108:111], v[12:15]
	ds_read_b128 v[120:123], v224 offset:53248
	s_waitcnt lgkmcnt(6)
	v_mfma_f32_16x16x32_bf16 v[16:19], v[68:71], v[96:99], v[16:19]
	ds_read_b128 v[124:127], v224 offset:55296
	s_waitcnt lgkmcnt(7)
	v_mfma_f32_16x16x32_bf16 v[20:23], v[68:71], v[100:103], v[20:23]
	ds_read_b128 v[84:87], v220 offset:2048
	s_waitcnt lgkmcnt(8)
	v_mfma_f32_16x16x32_bf16 v[24:27], v[68:71], v[104:107], v[24:27]
	ds_read_b128 v[88:91], v220 offset:4096
	s_waitcnt lgkmcnt(9)
	v_mfma_f32_16x16x32_bf16 v[28:31], v[68:71], v[108:111], v[28:31]
	ds_read_b128 v[92:95], v220 offset:6144
	s_waitcnt lgkmcnt(9)
	v_mfma_f32_16x16x32_bf16 v[32:35], v[72:75], v[96:99], v[32:35]
	s_waitcnt lgkmcnt(9)
	v_mfma_f32_16x16x32_bf16 v[36:39], v[72:75], v[100:103], v[36:39]
	s_waitcnt lgkmcnt(9)
	v_mfma_f32_16x16x32_bf16 v[40:43], v[72:75], v[104:107], v[40:43]
	s_waitcnt lgkmcnt(9)
	v_mfma_f32_16x16x32_bf16 v[44:47], v[72:75], v[108:111], v[44:47]
	s_waitcnt vmcnt(4) lgkmcnt(0)
	s_barrier
	s_add_u32 m0, s38, 0
	s_nop 0
	global_load_lds_dwordx4 v226, s[98:99]
	s_waitcnt lgkmcnt(8)
	v_mfma_f32_16x16x32_bf16 v[48:51], v[76:79], v[96:99], v[48:51]
	s_add_u32 m0, s38, 4096
	s_nop 0
	global_load_lds_dwordx4 v228, s[98:99]
	s_waitcnt lgkmcnt(8)
	v_mfma_f32_16x16x32_bf16 v[52:55], v[76:79], v[100:103], v[52:55]
	s_add_u32 m0, s38, 8192
	s_nop 0
	global_load_lds_dwordx4 v244, s[98:99]
	s_waitcnt lgkmcnt(8)
	v_mfma_f32_16x16x32_bf16 v[56:59], v[76:79], v[104:107], v[56:59]
	s_add_u32 m0, s38, 12288
	s_nop 0
	global_load_lds_dwordx4 v245, s[98:99]
	s_add_u32 s98, s98, 128
	s_addc_u32 s99, s99, 0
	s_waitcnt lgkmcnt(8)
	v_mfma_f32_16x16x32_bf16 v[60:63], v[76:79], v[108:111], v[60:63]
	s_waitcnt lgkmcnt(6)
	v_mfma_f32_16x16x32_bf16 v[0:3], v[80:83], v[112:115], v[0:3]
	ds_read_b128 v[64:67], v151 offset:16384
	s_waitcnt lgkmcnt(6)
	v_mfma_f32_16x16x32_bf16 v[4:7], v[80:83], v[116:119], v[4:7]
	ds_read_b128 v[96:99], v222 offset:49152
	s_waitcnt lgkmcnt(6)
	v_mfma_f32_16x16x32_bf16 v[8:11], v[80:83], v[120:123], v[8:11]
	ds_read_b128 v[100:103], v222 offset:51200
	s_waitcnt lgkmcnt(6)
	v_mfma_f32_16x16x32_bf16 v[12:15], v[80:83], v[124:127], v[12:15]
	ds_read_b128 v[104:107], v222 offset:53248
	s_waitcnt lgkmcnt(6)
	v_mfma_f32_16x16x32_bf16 v[16:19], v[84:87], v[112:115], v[16:19]
	ds_read_b128 v[108:111], v222 offset:55296
	s_waitcnt lgkmcnt(7)
	v_mfma_f32_16x16x32_bf16 v[20:23], v[84:87], v[116:119], v[20:23]
	ds_read_b128 v[68:71], v151 offset:18432
	s_waitcnt lgkmcnt(8)
	v_mfma_f32_16x16x32_bf16 v[24:27], v[84:87], v[120:123], v[24:27]
	ds_read_b128 v[72:75], v151 offset:20480
	s_waitcnt lgkmcnt(9)
	v_mfma_f32_16x16x32_bf16 v[28:31], v[84:87], v[124:127], v[28:31]
	ds_read_b128 v[76:79], v151 offset:22528
	s_waitcnt lgkmcnt(9)
	v_mfma_f32_16x16x32_bf16 v[32:35], v[88:91], v[112:115], v[32:35]
	s_waitcnt lgkmcnt(9)
	v_mfma_f32_16x16x32_bf16 v[36:39], v[88:91], v[116:119], v[36:39]
	s_waitcnt lgkmcnt(9)
	v_mfma_f32_16x16x32_bf16 v[40:43], v[88:91], v[120:123], v[40:43]
	s_waitcnt lgkmcnt(9)
	v_mfma_f32_16x16x32_bf16 v[44:47], v[88:91], v[124:127], v[44:47]
	s_waitcnt lgkmcnt(8)
	v_mfma_f32_16x16x32_bf16 v[48:51], v[92:95], v[112:115], v[48:51]
	s_waitcnt lgkmcnt(8)
	v_mfma_f32_16x16x32_bf16 v[52:55], v[92:95], v[116:119], v[52:55]
	s_waitcnt lgkmcnt(8)
	v_mfma_f32_16x16x32_bf16 v[56:59], v[92:95], v[120:123], v[56:59]
	s_waitcnt lgkmcnt(8)
	v_mfma_f32_16x16x32_bf16 v[60:63], v[92:95], v[124:127], v[60:63]
	s_waitcnt lgkmcnt(6)
	v_mfma_f32_16x16x32_bf16 v[160:163], v[64:67], v[96:99], v[160:163]
	ds_read_b128 v[80:83], v220 offset:16384
	s_waitcnt lgkmcnt(6)
	v_mfma_f32_16x16x32_bf16 v[164:167], v[64:67], v[100:103], v[164:167]
	ds_read_b128 v[112:115], v224 offset:49152
	s_waitcnt lgkmcnt(6)
	v_mfma_f32_16x16x32_bf16 v[168:171], v[64:67], v[104:107], v[168:171]
	ds_read_b128 v[116:119], v224 offset:51200
	s_waitcnt lgkmcnt(6)
	v_mfma_f32_16x16x32_bf16 v[172:175], v[64:67], v[108:111], v[172:175]
	ds_read_b128 v[120:123], v224 offset:53248
	s_waitcnt lgkmcnt(6)
	v_mfma_f32_16x16x32_bf16 v[176:179], v[68:71], v[96:99], v[176:179]
	ds_read_b128 v[124:127], v224 offset:55296
	s_waitcnt lgkmcnt(7)
	v_mfma_f32_16x16x32_bf16 v[180:183], v[68:71], v[100:103], v[180:183]
	ds_read_b128 v[84:87], v220 offset:18432
	s_waitcnt lgkmcnt(8)
	v_mfma_f32_16x16x32_bf16 v[184:187], v[68:71], v[104:107], v[184:187]
	ds_read_b128 v[88:91], v220 offset:20480
	s_waitcnt lgkmcnt(9)
	v_mfma_f32_16x16x32_bf16 v[188:191], v[68:71], v[108:111], v[188:191]
	ds_read_b128 v[92:95], v220 offset:22528
	s_waitcnt lgkmcnt(9)
	v_mfma_f32_16x16x32_bf16 v[192:195], v[72:75], v[96:99], v[192:195]
	s_waitcnt lgkmcnt(9)
	v_mfma_f32_16x16x32_bf16 v[196:199], v[72:75], v[100:103], v[196:199]
	s_waitcnt lgkmcnt(9)
	v_mfma_f32_16x16x32_bf16 v[200:203], v[72:75], v[104:107], v[200:203]
	s_waitcnt lgkmcnt(9)
	v_mfma_f32_16x16x32_bf16 v[204:207], v[72:75], v[108:111], v[204:207]
	s_waitcnt vmcnt(0) lgkmcnt(0)
	s_barrier
	s_add_u32 m0, s38, 16384
	s_nop 0
	global_load_lds_dwordx4 v226, s[100:101]
	s_waitcnt lgkmcnt(8)
	v_mfma_f32_16x16x32_bf16 v[208:211], v[76:79], v[96:99], v[208:211]
	s_add_u32 m0, s38, 20480
	s_nop 0
	global_load_lds_dwordx4 v228, s[100:101]
	s_waitcnt lgkmcnt(8)
	v_mfma_f32_16x16x32_bf16 v[212:215], v[76:79], v[100:103], v[212:215]
	s_add_u32 m0, s38, 24576
	s_nop 0
	global_load_lds_dwordx4 v244, s[100:101]
	s_waitcnt lgkmcnt(8)
	v_mfma_f32_16x16x32_bf16 v[216:219], v[76:79], v[104:107], v[216:219]
	s_add_u32 m0, s38, 28672
	s_nop 0
	global_load_lds_dwordx4 v245, s[100:101]
	s_add_u32 s100, s100, 128
	s_addc_u32 s101, s101, 0
	s_waitcnt lgkmcnt(8)
	v_mfma_f32_16x16x32_bf16 v[230:233], v[76:79], v[108:111], v[230:233]
	s_add_u32 m0, s38, 49152
	s_nop 0
	global_load_lds_dwordx4 v226, s[4:5]
	s_waitcnt lgkmcnt(6)
	v_mfma_f32_16x16x32_bf16 v[160:163], v[80:83], v[112:115], v[160:163]
	ds_read_b128 v[64:67], v151 offset:0
	s_add_u32 m0, s38, 53248
	s_nop 0
	global_load_lds_dwordx4 v228, s[4:5]
	s_waitcnt lgkmcnt(6)
	v_mfma_f32_16x16x32_bf16 v[164:167], v[80:83], v[116:119], v[164:167]
	ds_read_b128 v[96:99], v222 offset:32768
	s_add_u32 m0, s38, 57344
	s_nop 0
	global_load_lds_dwordx4 v244, s[4:5]
	s_waitcnt lgkmcnt(6)
	v_mfma_f32_16x16x32_bf16 v[168:171], v[80:83], v[120:123], v[168:171]
	ds_read_b128 v[100:103], v222 offset:34816
	s_add_u32 m0, s38, 61440
	s_nop 0
	global_load_lds_dwordx4 v245, s[4:5]
	s_add_u32 s4, s4, 128
	s_addc_u32 s5, s5, 0
	s_waitcnt lgkmcnt(6)
	v_mfma_f32_16x16x32_bf16 v[172:175], v[80:83], v[124:127], v[172:175]
	ds_read_b128 v[104:107], v222 offset:36864
	s_waitcnt lgkmcnt(6)
	v_mfma_f32_16x16x32_bf16 v[176:179], v[84:87], v[112:115], v[176:179]
	ds_read_b128 v[108:111], v222 offset:38912
	s_waitcnt lgkmcnt(7)
	v_mfma_f32_16x16x32_bf16 v[180:183], v[84:87], v[116:119], v[180:183]
	ds_read_b128 v[68:71], v151 offset:2048
	s_waitcnt lgkmcnt(8)
	v_mfma_f32_16x16x32_bf16 v[184:187], v[84:87], v[120:123], v[184:187]
	ds_read_b128 v[72:75], v151 offset:4096
	s_waitcnt lgkmcnt(9)
	v_mfma_f32_16x16x32_bf16 v[188:191], v[84:87], v[124:127], v[188:191]
	ds_read_b128 v[76:79], v151 offset:6144
	s_waitcnt lgkmcnt(9)
	v_mfma_f32_16x16x32_bf16 v[192:195], v[88:91], v[112:115], v[192:195]
	s_waitcnt lgkmcnt(9)
	v_mfma_f32_16x16x32_bf16 v[196:199], v[88:91], v[116:119], v[196:199]
	s_waitcnt lgkmcnt(9)
	v_mfma_f32_16x16x32_bf16 v[200:203], v[88:91], v[120:123], v[200:203]
	s_waitcnt lgkmcnt(9)
	v_mfma_f32_16x16x32_bf16 v[204:207], v[88:91], v[124:127], v[204:207]
	s_waitcnt lgkmcnt(8)
	v_mfma_f32_16x16x32_bf16 v[208:211], v[92:95], v[112:115], v[208:211]
	s_waitcnt lgkmcnt(8)
	v_mfma_f32_16x16x32_bf16 v[212:215], v[92:95], v[116:119], v[212:215]
	s_waitcnt lgkmcnt(8)
	v_mfma_f32_16x16x32_bf16 v[216:219], v[92:95], v[120:123], v[216:219]
	s_waitcnt lgkmcnt(8)
	v_mfma_f32_16x16x32_bf16 v[230:233], v[92:95], v[124:127], v[230:233]
	s_waitcnt lgkmcnt(6)
	v_mfma_f32_16x16x32_bf16 v[0:3], v[64:67], v[96:99], v[0:3]
	ds_read_b128 v[80:83], v220 offset:0
	s_waitcnt lgkmcnt(6)
	v_mfma_f32_16x16x32_bf16 v[4:7], v[64:67], v[100:103], v[4:7]
	ds_read_b128 v[112:115], v224 offset:32768
	s_waitcnt lgkmcnt(6)
	v_mfma_f32_16x16x32_bf16 v[8:11], v[64:67], v[104:107], v[8:11]
	ds_read_b128 v[116:119], v224 offset:34816
	s_waitcnt lgkmcnt(6)
	v_mfma_f32_16x16x32_bf16 v[12:15], v[64:67], v[108:111], v[12:15]
	ds_read_b128 v[120:123], v224 offset:36864
	s_waitcnt lgkmcnt(6)
	v_mfma_f32_16x16x32_bf16 v[16:19], v[68:71], v[96:99], v[16:19]
	ds_read_b128 v[124:127], v224 offset:38912
	s_waitcnt lgkmcnt(7)
	v_mfma_f32_16x16x32_bf16 v[20:23], v[68:71], v[100:103], v[20:23]
	ds_read_b128 v[84:87], v220 offset:2048
	s_waitcnt lgkmcnt(8)
	v_mfma_f32_16x16x32_bf16 v[24:27], v[68:71], v[104:107], v[24:27]
	ds_read_b128 v[88:91], v220 offset:4096
	s_waitcnt lgkmcnt(9)
	v_mfma_f32_16x16x32_bf16 v[28:31], v[68:71], v[108:111], v[28:31]
	ds_read_b128 v[92:95], v220 offset:6144
	s_waitcnt lgkmcnt(9)
	v_mfma_f32_16x16x32_bf16 v[32:35], v[72:75], v[96:99], v[32:35]
	s_waitcnt lgkmcnt(9)
	v_mfma_f32_16x16x32_bf16 v[36:39], v[72:75], v[100:103], v[36:39]
	s_waitcnt lgkmcnt(9)
	v_mfma_f32_16x16x32_bf16 v[40:43], v[72:75], v[104:107], v[40:43]
	s_waitcnt lgkmcnt(9)
	v_mfma_f32_16x16x32_bf16 v[44:47], v[72:75], v[108:111], v[44:47]
	s_waitcnt vmcnt(4) lgkmcnt(0)
	s_barrier
	s_add_u32 m0, s38, 0
	s_nop 0
	global_load_lds_dwordx4 v226, s[98:99]
	s_waitcnt lgkmcnt(8)
	v_mfma_f32_16x16x32_bf16 v[48:51], v[76:79], v[96:99], v[48:51]
	s_add_u32 m0, s38, 4096
	s_nop 0
	global_load_lds_dwordx4 v228, s[98:99]
	s_waitcnt lgkmcnt(8)
	v_mfma_f32_16x16x32_bf16 v[52:55], v[76:79], v[100:103], v[52:55]
	s_add_u32 m0, s38, 8192
	s_nop 0
	global_load_lds_dwordx4 v244, s[98:99]
	s_waitcnt lgkmcnt(8)
	v_mfma_f32_16x16x32_bf16 v[56:59], v[76:79], v[104:107], v[56:59]
	s_add_u32 m0, s38, 12288
	s_nop 0
	global_load_lds_dwordx4 v245, s[98:99]
	s_add_u32 s98, s98, 128
	s_addc_u32 s99, s99, 0
	s_waitcnt lgkmcnt(8)
	v_mfma_f32_16x16x32_bf16 v[60:63], v[76:79], v[108:111], v[60:63]
	s_waitcnt lgkmcnt(6)
	v_mfma_f32_16x16x32_bf16 v[0:3], v[80:83], v[112:115], v[0:3]
	ds_read_b128 v[64:67], v151 offset:16384
	s_waitcnt lgkmcnt(6)
	v_mfma_f32_16x16x32_bf16 v[4:7], v[80:83], v[116:119], v[4:7]
	ds_read_b128 v[96:99], v222 offset:32768
	s_waitcnt lgkmcnt(6)
	v_mfma_f32_16x16x32_bf16 v[8:11], v[80:83], v[120:123], v[8:11]
	ds_read_b128 v[100:103], v222 offset:34816
	s_waitcnt lgkmcnt(6)
	v_mfma_f32_16x16x32_bf16 v[12:15], v[80:83], v[124:127], v[12:15]
	ds_read_b128 v[104:107], v222 offset:36864
	s_waitcnt lgkmcnt(6)
	v_mfma_f32_16x16x32_bf16 v[16:19], v[84:87], v[112:115], v[16:19]
	ds_read_b128 v[108:111], v222 offset:38912
	s_waitcnt lgkmcnt(7)
	v_mfma_f32_16x16x32_bf16 v[20:23], v[84:87], v[116:119], v[20:23]
	ds_read_b128 v[68:71], v151 offset:18432
	s_waitcnt lgkmcnt(8)
	v_mfma_f32_16x16x32_bf16 v[24:27], v[84:87], v[120:123], v[24:27]
	ds_read_b128 v[72:75], v151 offset:20480
	s_waitcnt lgkmcnt(9)
	v_mfma_f32_16x16x32_bf16 v[28:31], v[84:87], v[124:127], v[28:31]
	ds_read_b128 v[76:79], v151 offset:22528
	s_waitcnt lgkmcnt(9)
	v_mfma_f32_16x16x32_bf16 v[32:35], v[88:91], v[112:115], v[32:35]
	s_waitcnt lgkmcnt(9)
	v_mfma_f32_16x16x32_bf16 v[36:39], v[88:91], v[116:119], v[36:39]
	s_waitcnt lgkmcnt(9)
	v_mfma_f32_16x16x32_bf16 v[40:43], v[88:91], v[120:123], v[40:43]
	s_waitcnt lgkmcnt(9)
	v_mfma_f32_16x16x32_bf16 v[44:47], v[88:91], v[124:127], v[44:47]
	s_waitcnt lgkmcnt(8)
	v_mfma_f32_16x16x32_bf16 v[48:51], v[92:95], v[112:115], v[48:51]
	s_waitcnt lgkmcnt(8)
	v_mfma_f32_16x16x32_bf16 v[52:55], v[92:95], v[116:119], v[52:55]
	s_waitcnt lgkmcnt(8)
	v_mfma_f32_16x16x32_bf16 v[56:59], v[92:95], v[120:123], v[56:59]
	s_waitcnt lgkmcnt(8)
	v_mfma_f32_16x16x32_bf16 v[60:63], v[92:95], v[124:127], v[60:63]
	s_waitcnt lgkmcnt(6)
	v_mfma_f32_16x16x32_bf16 v[160:163], v[64:67], v[96:99], v[160:163]
	ds_read_b128 v[80:83], v220 offset:16384
	s_waitcnt lgkmcnt(6)
	v_mfma_f32_16x16x32_bf16 v[164:167], v[64:67], v[100:103], v[164:167]
	ds_read_b128 v[112:115], v224 offset:32768
	s_waitcnt lgkmcnt(6)
	v_mfma_f32_16x16x32_bf16 v[168:171], v[64:67], v[104:107], v[168:171]
	ds_read_b128 v[116:119], v224 offset:34816
	s_waitcnt lgkmcnt(6)
	v_mfma_f32_16x16x32_bf16 v[172:175], v[64:67], v[108:111], v[172:175]
	ds_read_b128 v[120:123], v224 offset:36864
	s_waitcnt lgkmcnt(6)
	v_mfma_f32_16x16x32_bf16 v[176:179], v[68:71], v[96:99], v[176:179]
	ds_read_b128 v[124:127], v224 offset:38912
	s_waitcnt lgkmcnt(7)
	v_mfma_f32_16x16x32_bf16 v[180:183], v[68:71], v[100:103], v[180:183]
	ds_read_b128 v[84:87], v220 offset:18432
	s_waitcnt lgkmcnt(8)
	v_mfma_f32_16x16x32_bf16 v[184:187], v[68:71], v[104:107], v[184:187]
	ds_read_b128 v[88:91], v220 offset:20480
	s_waitcnt lgkmcnt(9)
	v_mfma_f32_16x16x32_bf16 v[188:191], v[68:71], v[108:111], v[188:191]
	ds_read_b128 v[92:95], v220 offset:22528
	s_waitcnt lgkmcnt(9)
	v_mfma_f32_16x16x32_bf16 v[192:195], v[72:75], v[96:99], v[192:195]
	s_waitcnt lgkmcnt(9)
	v_mfma_f32_16x16x32_bf16 v[196:199], v[72:75], v[100:103], v[196:199]
	s_waitcnt lgkmcnt(9)
	v_mfma_f32_16x16x32_bf16 v[200:203], v[72:75], v[104:107], v[200:203]
	s_waitcnt lgkmcnt(9)
	v_mfma_f32_16x16x32_bf16 v[204:207], v[72:75], v[108:111], v[204:207]
	s_waitcnt vmcnt(0) lgkmcnt(0)
	s_barrier
	s_add_u32 m0, s38, 16384
	s_nop 0
	global_load_lds_dwordx4 v226, s[100:101]
	s_waitcnt lgkmcnt(8)
	v_mfma_f32_16x16x32_bf16 v[208:211], v[76:79], v[96:99], v[208:211]
	s_add_u32 m0, s38, 20480
	s_nop 0
	global_load_lds_dwordx4 v228, s[100:101]
	s_waitcnt lgkmcnt(8)
	v_mfma_f32_16x16x32_bf16 v[212:215], v[76:79], v[100:103], v[212:215]
	s_add_u32 m0, s38, 24576
	s_nop 0
	global_load_lds_dwordx4 v244, s[100:101]
	s_waitcnt lgkmcnt(8)
	v_mfma_f32_16x16x32_bf16 v[216:219], v[76:79], v[104:107], v[216:219]
	s_add_u32 m0, s38, 28672
	s_nop 0
	global_load_lds_dwordx4 v245, s[100:101]
	s_add_u32 s100, s100, 128
	s_addc_u32 s101, s101, 0
	s_waitcnt lgkmcnt(8)
	v_mfma_f32_16x16x32_bf16 v[230:233], v[76:79], v[108:111], v[230:233]
	s_add_u32 m0, s38, 32768
	s_nop 0
	global_load_lds_dwordx4 v226, s[4:5]
	s_waitcnt lgkmcnt(6)
	v_mfma_f32_16x16x32_bf16 v[160:163], v[80:83], v[112:115], v[160:163]
	ds_read_b128 v[64:67], v151 offset:0
	s_add_u32 m0, s38, 36864
	s_nop 0
	global_load_lds_dwordx4 v228, s[4:5]
	s_waitcnt lgkmcnt(6)
	v_mfma_f32_16x16x32_bf16 v[164:167], v[80:83], v[116:119], v[164:167]
	ds_read_b128 v[96:99], v222 offset:49152
	s_add_u32 m0, s38, 40960
	s_nop 0
	global_load_lds_dwordx4 v244, s[4:5]
	s_waitcnt lgkmcnt(6)
	v_mfma_f32_16x16x32_bf16 v[168:171], v[80:83], v[120:123], v[168:171]
	ds_read_b128 v[100:103], v222 offset:51200
	s_add_u32 m0, s38, 45056
	s_nop 0
	global_load_lds_dwordx4 v245, s[4:5]
	s_add_u32 s4, s4, 128
	s_addc_u32 s5, s5, 0
	s_waitcnt lgkmcnt(6)
	v_mfma_f32_16x16x32_bf16 v[172:175], v[80:83], v[124:127], v[172:175]
	ds_read_b128 v[104:107], v222 offset:53248
	s_waitcnt lgkmcnt(6)
	v_mfma_f32_16x16x32_bf16 v[176:179], v[84:87], v[112:115], v[176:179]
	ds_read_b128 v[108:111], v222 offset:55296
	s_waitcnt lgkmcnt(7)
	v_mfma_f32_16x16x32_bf16 v[180:183], v[84:87], v[116:119], v[180:183]
	ds_read_b128 v[68:71], v151 offset:2048
	s_waitcnt lgkmcnt(8)
	v_mfma_f32_16x16x32_bf16 v[184:187], v[84:87], v[120:123], v[184:187]
	ds_read_b128 v[72:75], v151 offset:4096
	s_waitcnt lgkmcnt(9)
	v_mfma_f32_16x16x32_bf16 v[188:191], v[84:87], v[124:127], v[188:191]
	ds_read_b128 v[76:79], v151 offset:6144
	s_waitcnt lgkmcnt(9)
	v_mfma_f32_16x16x32_bf16 v[192:195], v[88:91], v[112:115], v[192:195]
	s_waitcnt lgkmcnt(9)
	v_mfma_f32_16x16x32_bf16 v[196:199], v[88:91], v[116:119], v[196:199]
	s_waitcnt lgkmcnt(9)
	v_mfma_f32_16x16x32_bf16 v[200:203], v[88:91], v[120:123], v[200:203]
	s_waitcnt lgkmcnt(9)
	v_mfma_f32_16x16x32_bf16 v[204:207], v[88:91], v[124:127], v[204:207]
	s_waitcnt lgkmcnt(8)
	v_mfma_f32_16x16x32_bf16 v[208:211], v[92:95], v[112:115], v[208:211]
	s_waitcnt lgkmcnt(8)
	v_mfma_f32_16x16x32_bf16 v[212:215], v[92:95], v[116:119], v[212:215]
	s_waitcnt lgkmcnt(8)
	v_mfma_f32_16x16x32_bf16 v[216:219], v[92:95], v[120:123], v[216:219]
	s_waitcnt lgkmcnt(8)
	v_mfma_f32_16x16x32_bf16 v[230:233], v[92:95], v[124:127], v[230:233]
	s_waitcnt lgkmcnt(6)
	v_mfma_f32_16x16x32_bf16 v[0:3], v[64:67], v[96:99], v[0:3]
	ds_read_b128 v[80:83], v220 offset:0
	s_waitcnt lgkmcnt(6)
	v_mfma_f32_16x16x32_bf16 v[4:7], v[64:67], v[100:103], v[4:7]
	ds_read_b128 v[112:115], v224 offset:49152
	s_waitcnt lgkmcnt(6)
	v_mfma_f32_16x16x32_bf16 v[8:11], v[64:67], v[104:107], v[8:11]
	ds_read_b128 v[116:119], v224 offset:51200
	s_waitcnt lgkmcnt(6)
	v_mfma_f32_16x16x32_bf16 v[12:15], v[64:67], v[108:111], v[12:15]
	ds_read_b128 v[120:123], v224 offset:53248
	s_waitcnt lgkmcnt(6)
	v_mfma_f32_16x16x32_bf16 v[16:19], v[68:71], v[96:99], v[16:19]
	ds_read_b128 v[124:127], v224 offset:55296
	s_waitcnt lgkmcnt(7)
	v_mfma_f32_16x16x32_bf16 v[20:23], v[68:71], v[100:103], v[20:23]
	ds_read_b128 v[84:87], v220 offset:2048
	s_waitcnt lgkmcnt(8)
	v_mfma_f32_16x16x32_bf16 v[24:27], v[68:71], v[104:107], v[24:27]
	ds_read_b128 v[88:91], v220 offset:4096
	s_waitcnt lgkmcnt(9)
	v_mfma_f32_16x16x32_bf16 v[28:31], v[68:71], v[108:111], v[28:31]
	ds_read_b128 v[92:95], v220 offset:6144
	s_waitcnt lgkmcnt(9)
	v_mfma_f32_16x16x32_bf16 v[32:35], v[72:75], v[96:99], v[32:35]
	s_waitcnt lgkmcnt(9)
	v_mfma_f32_16x16x32_bf16 v[36:39], v[72:75], v[100:103], v[36:39]
	s_waitcnt lgkmcnt(9)
	v_mfma_f32_16x16x32_bf16 v[40:43], v[72:75], v[104:107], v[40:43]
	s_waitcnt lgkmcnt(9)
	v_mfma_f32_16x16x32_bf16 v[44:47], v[72:75], v[108:111], v[44:47]
	s_waitcnt vmcnt(4) lgkmcnt(0)
	s_barrier
	s_add_u32 m0, s38, 0
	s_nop 0
	global_load_lds_dwordx4 v226, s[98:99]
	s_waitcnt lgkmcnt(8)
	v_mfma_f32_16x16x32_bf16 v[48:51], v[76:79], v[96:99], v[48:51]
	s_add_u32 m0, s38, 4096
	s_nop 0
	global_load_lds_dwordx4 v228, s[98:99]
	s_waitcnt lgkmcnt(8)
	v_mfma_f32_16x16x32_bf16 v[52:55], v[76:79], v[100:103], v[52:55]
	s_add_u32 m0, s38, 8192
	s_nop 0
	global_load_lds_dwordx4 v244, s[98:99]
	s_waitcnt lgkmcnt(8)
	v_mfma_f32_16x16x32_bf16 v[56:59], v[76:79], v[104:107], v[56:59]
	s_add_u32 m0, s38, 12288
	s_nop 0
	global_load_lds_dwordx4 v245, s[98:99]
	s_add_u32 s98, s98, 128
	s_addc_u32 s99, s99, 0
	s_waitcnt lgkmcnt(8)
	v_mfma_f32_16x16x32_bf16 v[60:63], v[76:79], v[108:111], v[60:63]
	s_waitcnt lgkmcnt(6)
	v_mfma_f32_16x16x32_bf16 v[0:3], v[80:83], v[112:115], v[0:3]
	ds_read_b128 v[64:67], v151 offset:16384
	s_waitcnt lgkmcnt(6)
	v_mfma_f32_16x16x32_bf16 v[4:7], v[80:83], v[116:119], v[4:7]
	ds_read_b128 v[96:99], v222 offset:49152
	s_waitcnt lgkmcnt(6)
	v_mfma_f32_16x16x32_bf16 v[8:11], v[80:83], v[120:123], v[8:11]
	ds_read_b128 v[100:103], v222 offset:51200
	s_waitcnt lgkmcnt(6)
	v_mfma_f32_16x16x32_bf16 v[12:15], v[80:83], v[124:127], v[12:15]
	ds_read_b128 v[104:107], v222 offset:53248
	s_waitcnt lgkmcnt(6)
	v_mfma_f32_16x16x32_bf16 v[16:19], v[84:87], v[112:115], v[16:19]
	ds_read_b128 v[108:111], v222 offset:55296
	s_waitcnt lgkmcnt(7)
	v_mfma_f32_16x16x32_bf16 v[20:23], v[84:87], v[116:119], v[20:23]
	ds_read_b128 v[68:71], v151 offset:18432
	s_waitcnt lgkmcnt(8)
	v_mfma_f32_16x16x32_bf16 v[24:27], v[84:87], v[120:123], v[24:27]
	ds_read_b128 v[72:75], v151 offset:20480
	s_waitcnt lgkmcnt(9)
	v_mfma_f32_16x16x32_bf16 v[28:31], v[84:87], v[124:127], v[28:31]
	ds_read_b128 v[76:79], v151 offset:22528
	s_waitcnt lgkmcnt(9)
	v_mfma_f32_16x16x32_bf16 v[32:35], v[88:91], v[112:115], v[32:35]
	s_waitcnt lgkmcnt(9)
	v_mfma_f32_16x16x32_bf16 v[36:39], v[88:91], v[116:119], v[36:39]
	s_waitcnt lgkmcnt(9)
	v_mfma_f32_16x16x32_bf16 v[40:43], v[88:91], v[120:123], v[40:43]
	s_waitcnt lgkmcnt(9)
	v_mfma_f32_16x16x32_bf16 v[44:47], v[88:91], v[124:127], v[44:47]
	s_waitcnt lgkmcnt(8)
	v_mfma_f32_16x16x32_bf16 v[48:51], v[92:95], v[112:115], v[48:51]
	s_waitcnt lgkmcnt(8)
	v_mfma_f32_16x16x32_bf16 v[52:55], v[92:95], v[116:119], v[52:55]
	s_waitcnt lgkmcnt(8)
	v_mfma_f32_16x16x32_bf16 v[56:59], v[92:95], v[120:123], v[56:59]
	s_waitcnt lgkmcnt(8)
	v_mfma_f32_16x16x32_bf16 v[60:63], v[92:95], v[124:127], v[60:63]
	s_waitcnt lgkmcnt(6)
	v_mfma_f32_16x16x32_bf16 v[160:163], v[64:67], v[96:99], v[160:163]
	ds_read_b128 v[80:83], v220 offset:16384
	s_waitcnt lgkmcnt(6)
	v_mfma_f32_16x16x32_bf16 v[164:167], v[64:67], v[100:103], v[164:167]
	ds_read_b128 v[112:115], v224 offset:49152
	s_waitcnt lgkmcnt(6)
	v_mfma_f32_16x16x32_bf16 v[168:171], v[64:67], v[104:107], v[168:171]
	ds_read_b128 v[116:119], v224 offset:51200
	s_waitcnt lgkmcnt(6)
	v_mfma_f32_16x16x32_bf16 v[172:175], v[64:67], v[108:111], v[172:175]
	ds_read_b128 v[120:123], v224 offset:53248
	s_waitcnt lgkmcnt(6)
	v_mfma_f32_16x16x32_bf16 v[176:179], v[68:71], v[96:99], v[176:179]
	ds_read_b128 v[124:127], v224 offset:55296
	s_waitcnt lgkmcnt(7)
	v_mfma_f32_16x16x32_bf16 v[180:183], v[68:71], v[100:103], v[180:183]
	ds_read_b128 v[84:87], v220 offset:18432
	s_waitcnt lgkmcnt(8)
	v_mfma_f32_16x16x32_bf16 v[184:187], v[68:71], v[104:107], v[184:187]
	ds_read_b128 v[88:91], v220 offset:20480
	s_waitcnt lgkmcnt(9)
	v_mfma_f32_16x16x32_bf16 v[188:191], v[68:71], v[108:111], v[188:191]
	ds_read_b128 v[92:95], v220 offset:22528
	s_waitcnt lgkmcnt(9)
	v_mfma_f32_16x16x32_bf16 v[192:195], v[72:75], v[96:99], v[192:195]
	s_waitcnt lgkmcnt(9)
	v_mfma_f32_16x16x32_bf16 v[196:199], v[72:75], v[100:103], v[196:199]
	s_waitcnt lgkmcnt(9)
	v_mfma_f32_16x16x32_bf16 v[200:203], v[72:75], v[104:107], v[200:203]
	s_waitcnt lgkmcnt(9)
	v_mfma_f32_16x16x32_bf16 v[204:207], v[72:75], v[108:111], v[204:207]
	s_waitcnt vmcnt(0) lgkmcnt(0)
	s_barrier
	s_add_u32 m0, s38, 16384
	s_nop 0
	global_load_lds_dwordx4 v226, s[100:101]
	s_waitcnt lgkmcnt(8)
	v_mfma_f32_16x16x32_bf16 v[208:211], v[76:79], v[96:99], v[208:211]
	s_add_u32 m0, s38, 20480
	s_nop 0
	global_load_lds_dwordx4 v228, s[100:101]
	s_waitcnt lgkmcnt(8)
	v_mfma_f32_16x16x32_bf16 v[212:215], v[76:79], v[100:103], v[212:215]
	s_add_u32 m0, s38, 24576
	s_nop 0
	global_load_lds_dwordx4 v244, s[100:101]
	s_waitcnt lgkmcnt(8)
	v_mfma_f32_16x16x32_bf16 v[216:219], v[76:79], v[104:107], v[216:219]
	s_add_u32 m0, s38, 28672
	s_nop 0
	global_load_lds_dwordx4 v245, s[100:101]
	s_add_u32 s100, s100, 128
	s_addc_u32 s101, s101, 0
	s_waitcnt lgkmcnt(8)
	v_mfma_f32_16x16x32_bf16 v[230:233], v[76:79], v[108:111], v[230:233]
	s_add_u32 m0, s38, 49152
	s_nop 0
	global_load_lds_dwordx4 v226, s[4:5]
	s_waitcnt lgkmcnt(6)
	v_mfma_f32_16x16x32_bf16 v[160:163], v[80:83], v[112:115], v[160:163]
	ds_read_b128 v[64:67], v151 offset:0
	s_add_u32 m0, s38, 53248
	s_nop 0
	global_load_lds_dwordx4 v228, s[4:5]
	s_waitcnt lgkmcnt(6)
	v_mfma_f32_16x16x32_bf16 v[164:167], v[80:83], v[116:119], v[164:167]
	ds_read_b128 v[96:99], v222 offset:32768
	s_add_u32 m0, s38, 57344
	s_nop 0
	global_load_lds_dwordx4 v244, s[4:5]
	s_waitcnt lgkmcnt(6)
	v_mfma_f32_16x16x32_bf16 v[168:171], v[80:83], v[120:123], v[168:171]
	ds_read_b128 v[100:103], v222 offset:34816
	s_add_u32 m0, s38, 61440
	s_nop 0
	global_load_lds_dwordx4 v245, s[4:5]
	s_add_u32 s4, s4, 128
	s_addc_u32 s5, s5, 0
	s_waitcnt lgkmcnt(6)
	v_mfma_f32_16x16x32_bf16 v[172:175], v[80:83], v[124:127], v[172:175]
	ds_read_b128 v[104:107], v222 offset:36864
	s_waitcnt lgkmcnt(6)
	v_mfma_f32_16x16x32_bf16 v[176:179], v[84:87], v[112:115], v[176:179]
	ds_read_b128 v[108:111], v222 offset:38912
	s_waitcnt lgkmcnt(7)
	v_mfma_f32_16x16x32_bf16 v[180:183], v[84:87], v[116:119], v[180:183]
	ds_read_b128 v[68:71], v151 offset:2048
	s_waitcnt lgkmcnt(8)
	v_mfma_f32_16x16x32_bf16 v[184:187], v[84:87], v[120:123], v[184:187]
	ds_read_b128 v[72:75], v151 offset:4096
	s_waitcnt lgkmcnt(9)
	v_mfma_f32_16x16x32_bf16 v[188:191], v[84:87], v[124:127], v[188:191]
	ds_read_b128 v[76:79], v151 offset:6144
	s_waitcnt lgkmcnt(9)
	v_mfma_f32_16x16x32_bf16 v[192:195], v[88:91], v[112:115], v[192:195]
	s_waitcnt lgkmcnt(9)
	v_mfma_f32_16x16x32_bf16 v[196:199], v[88:91], v[116:119], v[196:199]
	s_waitcnt lgkmcnt(9)
	v_mfma_f32_16x16x32_bf16 v[200:203], v[88:91], v[120:123], v[200:203]
	s_waitcnt lgkmcnt(9)
	v_mfma_f32_16x16x32_bf16 v[204:207], v[88:91], v[124:127], v[204:207]
	s_waitcnt lgkmcnt(8)
	v_mfma_f32_16x16x32_bf16 v[208:211], v[92:95], v[112:115], v[208:211]
	s_waitcnt lgkmcnt(8)
	v_mfma_f32_16x16x32_bf16 v[212:215], v[92:95], v[116:119], v[212:215]
	s_waitcnt lgkmcnt(8)
	v_mfma_f32_16x16x32_bf16 v[216:219], v[92:95], v[120:123], v[216:219]
	s_waitcnt lgkmcnt(8)
	v_mfma_f32_16x16x32_bf16 v[230:233], v[92:95], v[124:127], v[230:233]
	s_waitcnt lgkmcnt(6)
	v_mfma_f32_16x16x32_bf16 v[0:3], v[64:67], v[96:99], v[0:3]
	ds_read_b128 v[80:83], v220 offset:0
	s_waitcnt lgkmcnt(6)
	v_mfma_f32_16x16x32_bf16 v[4:7], v[64:67], v[100:103], v[4:7]
	ds_read_b128 v[112:115], v224 offset:32768
	s_waitcnt lgkmcnt(6)
	v_mfma_f32_16x16x32_bf16 v[8:11], v[64:67], v[104:107], v[8:11]
	ds_read_b128 v[116:119], v224 offset:34816
	s_waitcnt lgkmcnt(6)
	v_mfma_f32_16x16x32_bf16 v[12:15], v[64:67], v[108:111], v[12:15]
	ds_read_b128 v[120:123], v224 offset:36864
	s_waitcnt lgkmcnt(6)
	v_mfma_f32_16x16x32_bf16 v[16:19], v[68:71], v[96:99], v[16:19]
	ds_read_b128 v[124:127], v224 offset:38912
	s_waitcnt lgkmcnt(7)
	v_mfma_f32_16x16x32_bf16 v[20:23], v[68:71], v[100:103], v[20:23]
	ds_read_b128 v[84:87], v220 offset:2048
	s_waitcnt lgkmcnt(8)
	v_mfma_f32_16x16x32_bf16 v[24:27], v[68:71], v[104:107], v[24:27]
	ds_read_b128 v[88:91], v220 offset:4096
	s_waitcnt lgkmcnt(9)
	v_mfma_f32_16x16x32_bf16 v[28:31], v[68:71], v[108:111], v[28:31]
	ds_read_b128 v[92:95], v220 offset:6144
	s_waitcnt lgkmcnt(9)
	v_mfma_f32_16x16x32_bf16 v[32:35], v[72:75], v[96:99], v[32:35]
	s_waitcnt lgkmcnt(9)
	v_mfma_f32_16x16x32_bf16 v[36:39], v[72:75], v[100:103], v[36:39]
	s_waitcnt lgkmcnt(9)
	v_mfma_f32_16x16x32_bf16 v[40:43], v[72:75], v[104:107], v[40:43]
	s_waitcnt lgkmcnt(9)
	v_mfma_f32_16x16x32_bf16 v[44:47], v[72:75], v[108:111], v[44:47]
	s_waitcnt vmcnt(4) lgkmcnt(0)
	s_barrier
	s_add_u32 m0, s38, 0
	s_nop 0
	global_load_lds_dwordx4 v226, s[98:99]
	s_waitcnt lgkmcnt(8)
	v_mfma_f32_16x16x32_bf16 v[48:51], v[76:79], v[96:99], v[48:51]
	s_add_u32 m0, s38, 4096
	s_nop 0
	global_load_lds_dwordx4 v228, s[98:99]
	s_waitcnt lgkmcnt(8)
	v_mfma_f32_16x16x32_bf16 v[52:55], v[76:79], v[100:103], v[52:55]
	s_add_u32 m0, s38, 8192
	s_nop 0
	global_load_lds_dwordx4 v244, s[98:99]
	s_waitcnt lgkmcnt(8)
	v_mfma_f32_16x16x32_bf16 v[56:59], v[76:79], v[104:107], v[56:59]
	s_add_u32 m0, s38, 12288
	s_nop 0
	global_load_lds_dwordx4 v245, s[98:99]
	s_add_u32 s98, s98, 128
	s_addc_u32 s99, s99, 0
	s_waitcnt lgkmcnt(8)
	v_mfma_f32_16x16x32_bf16 v[60:63], v[76:79], v[108:111], v[60:63]
	s_waitcnt lgkmcnt(6)
	v_mfma_f32_16x16x32_bf16 v[0:3], v[80:83], v[112:115], v[0:3]
	ds_read_b128 v[64:67], v151 offset:16384
	s_waitcnt lgkmcnt(6)
	v_mfma_f32_16x16x32_bf16 v[4:7], v[80:83], v[116:119], v[4:7]
	ds_read_b128 v[96:99], v222 offset:32768
	s_waitcnt lgkmcnt(6)
	v_mfma_f32_16x16x32_bf16 v[8:11], v[80:83], v[120:123], v[8:11]
	ds_read_b128 v[100:103], v222 offset:34816
	s_waitcnt lgkmcnt(6)
	v_mfma_f32_16x16x32_bf16 v[12:15], v[80:83], v[124:127], v[12:15]
	ds_read_b128 v[104:107], v222 offset:36864
	s_waitcnt lgkmcnt(6)
	v_mfma_f32_16x16x32_bf16 v[16:19], v[84:87], v[112:115], v[16:19]
	ds_read_b128 v[108:111], v222 offset:38912
	s_waitcnt lgkmcnt(7)
	v_mfma_f32_16x16x32_bf16 v[20:23], v[84:87], v[116:119], v[20:23]
	ds_read_b128 v[68:71], v151 offset:18432
	s_waitcnt lgkmcnt(8)
	v_mfma_f32_16x16x32_bf16 v[24:27], v[84:87], v[120:123], v[24:27]
	ds_read_b128 v[72:75], v151 offset:20480
	s_waitcnt lgkmcnt(9)
	v_mfma_f32_16x16x32_bf16 v[28:31], v[84:87], v[124:127], v[28:31]
	ds_read_b128 v[76:79], v151 offset:22528
	s_waitcnt lgkmcnt(9)
	v_mfma_f32_16x16x32_bf16 v[32:35], v[88:91], v[112:115], v[32:35]
	s_waitcnt lgkmcnt(9)
	v_mfma_f32_16x16x32_bf16 v[36:39], v[88:91], v[116:119], v[36:39]
	s_waitcnt lgkmcnt(9)
	v_mfma_f32_16x16x32_bf16 v[40:43], v[88:91], v[120:123], v[40:43]
	s_waitcnt lgkmcnt(9)
	v_mfma_f32_16x16x32_bf16 v[44:47], v[88:91], v[124:127], v[44:47]
	s_waitcnt lgkmcnt(8)
	v_mfma_f32_16x16x32_bf16 v[48:51], v[92:95], v[112:115], v[48:51]
	s_waitcnt lgkmcnt(8)
	v_mfma_f32_16x16x32_bf16 v[52:55], v[92:95], v[116:119], v[52:55]
	s_waitcnt lgkmcnt(8)
	v_mfma_f32_16x16x32_bf16 v[56:59], v[92:95], v[120:123], v[56:59]
	s_waitcnt lgkmcnt(8)
	v_mfma_f32_16x16x32_bf16 v[60:63], v[92:95], v[124:127], v[60:63]
	s_waitcnt lgkmcnt(6)
	v_mfma_f32_16x16x32_bf16 v[160:163], v[64:67], v[96:99], v[160:163]
	ds_read_b128 v[80:83], v220 offset:16384
	s_waitcnt lgkmcnt(6)
	v_mfma_f32_16x16x32_bf16 v[164:167], v[64:67], v[100:103], v[164:167]
	ds_read_b128 v[112:115], v224 offset:32768
	s_waitcnt lgkmcnt(6)
	v_mfma_f32_16x16x32_bf16 v[168:171], v[64:67], v[104:107], v[168:171]
	ds_read_b128 v[116:119], v224 offset:34816
	s_waitcnt lgkmcnt(6)
	v_mfma_f32_16x16x32_bf16 v[172:175], v[64:67], v[108:111], v[172:175]
	ds_read_b128 v[120:123], v224 offset:36864
	s_waitcnt lgkmcnt(6)
	v_mfma_f32_16x16x32_bf16 v[176:179], v[68:71], v[96:99], v[176:179]
	ds_read_b128 v[124:127], v224 offset:38912
	s_waitcnt lgkmcnt(7)
	v_mfma_f32_16x16x32_bf16 v[180:183], v[68:71], v[100:103], v[180:183]
	ds_read_b128 v[84:87], v220 offset:18432
	s_waitcnt lgkmcnt(8)
	v_mfma_f32_16x16x32_bf16 v[184:187], v[68:71], v[104:107], v[184:187]
	ds_read_b128 v[88:91], v220 offset:20480
	s_waitcnt lgkmcnt(9)
	v_mfma_f32_16x16x32_bf16 v[188:191], v[68:71], v[108:111], v[188:191]
	ds_read_b128 v[92:95], v220 offset:22528
	s_waitcnt lgkmcnt(9)
	v_mfma_f32_16x16x32_bf16 v[192:195], v[72:75], v[96:99], v[192:195]
	s_waitcnt lgkmcnt(9)
	v_mfma_f32_16x16x32_bf16 v[196:199], v[72:75], v[100:103], v[196:199]
	s_waitcnt lgkmcnt(9)
	v_mfma_f32_16x16x32_bf16 v[200:203], v[72:75], v[104:107], v[200:203]
	s_waitcnt lgkmcnt(9)
	v_mfma_f32_16x16x32_bf16 v[204:207], v[72:75], v[108:111], v[204:207]
	s_waitcnt vmcnt(0) lgkmcnt(0)
	s_barrier
	s_add_u32 m0, s38, 16384
	s_nop 0
	global_load_lds_dwordx4 v226, s[100:101]
	s_waitcnt lgkmcnt(8)
	v_mfma_f32_16x16x32_bf16 v[208:211], v[76:79], v[96:99], v[208:211]
	s_add_u32 m0, s38, 20480
	s_nop 0
	global_load_lds_dwordx4 v228, s[100:101]
	s_waitcnt lgkmcnt(8)
	v_mfma_f32_16x16x32_bf16 v[212:215], v[76:79], v[100:103], v[212:215]
	s_add_u32 m0, s38, 24576
	s_nop 0
	global_load_lds_dwordx4 v244, s[100:101]
	s_waitcnt lgkmcnt(8)
	v_mfma_f32_16x16x32_bf16 v[216:219], v[76:79], v[104:107], v[216:219]
	s_add_u32 m0, s38, 28672
	s_nop 0
	global_load_lds_dwordx4 v245, s[100:101]
	s_add_u32 s100, s100, 128
	s_addc_u32 s101, s101, 0
	s_waitcnt lgkmcnt(8)
	v_mfma_f32_16x16x32_bf16 v[230:233], v[76:79], v[108:111], v[230:233]
	s_add_u32 m0, s38, 32768
	s_nop 0
	global_load_lds_dwordx4 v226, s[4:5]
	s_waitcnt lgkmcnt(6)
	v_mfma_f32_16x16x32_bf16 v[160:163], v[80:83], v[112:115], v[160:163]
	ds_read_b128 v[64:67], v151 offset:0
	s_add_u32 m0, s38, 36864
	s_nop 0
	global_load_lds_dwordx4 v228, s[4:5]
	s_waitcnt lgkmcnt(6)
	v_mfma_f32_16x16x32_bf16 v[164:167], v[80:83], v[116:119], v[164:167]
	ds_read_b128 v[96:99], v222 offset:49152
	s_add_u32 m0, s38, 40960
	s_nop 0
	global_load_lds_dwordx4 v244, s[4:5]
	s_waitcnt lgkmcnt(6)
	v_mfma_f32_16x16x32_bf16 v[168:171], v[80:83], v[120:123], v[168:171]
	ds_read_b128 v[100:103], v222 offset:51200
	s_add_u32 m0, s38, 45056
	s_nop 0
	global_load_lds_dwordx4 v245, s[4:5]
	s_add_u32 s4, s4, 128
	s_addc_u32 s5, s5, 0
	s_waitcnt lgkmcnt(6)
	v_mfma_f32_16x16x32_bf16 v[172:175], v[80:83], v[124:127], v[172:175]
	ds_read_b128 v[104:107], v222 offset:53248
	s_waitcnt lgkmcnt(6)
	v_mfma_f32_16x16x32_bf16 v[176:179], v[84:87], v[112:115], v[176:179]
	ds_read_b128 v[108:111], v222 offset:55296
	s_waitcnt lgkmcnt(7)
	v_mfma_f32_16x16x32_bf16 v[180:183], v[84:87], v[116:119], v[180:183]
	ds_read_b128 v[68:71], v151 offset:2048
	s_waitcnt lgkmcnt(8)
	v_mfma_f32_16x16x32_bf16 v[184:187], v[84:87], v[120:123], v[184:187]
	ds_read_b128 v[72:75], v151 offset:4096
	s_waitcnt lgkmcnt(9)
	v_mfma_f32_16x16x32_bf16 v[188:191], v[84:87], v[124:127], v[188:191]
	ds_read_b128 v[76:79], v151 offset:6144
	s_waitcnt lgkmcnt(9)
	v_mfma_f32_16x16x32_bf16 v[192:195], v[88:91], v[112:115], v[192:195]
	s_waitcnt lgkmcnt(9)
	v_mfma_f32_16x16x32_bf16 v[196:199], v[88:91], v[116:119], v[196:199]
	s_waitcnt lgkmcnt(9)
	v_mfma_f32_16x16x32_bf16 v[200:203], v[88:91], v[120:123], v[200:203]
	s_waitcnt lgkmcnt(9)
	v_mfma_f32_16x16x32_bf16 v[204:207], v[88:91], v[124:127], v[204:207]
	s_waitcnt lgkmcnt(8)
	v_mfma_f32_16x16x32_bf16 v[208:211], v[92:95], v[112:115], v[208:211]
	s_waitcnt lgkmcnt(8)
	v_mfma_f32_16x16x32_bf16 v[212:215], v[92:95], v[116:119], v[212:215]
	s_waitcnt lgkmcnt(8)
	v_mfma_f32_16x16x32_bf16 v[216:219], v[92:95], v[120:123], v[216:219]
	s_waitcnt lgkmcnt(8)
	v_mfma_f32_16x16x32_bf16 v[230:233], v[92:95], v[124:127], v[230:233]
	s_waitcnt lgkmcnt(6)
	v_mfma_f32_16x16x32_bf16 v[0:3], v[64:67], v[96:99], v[0:3]
	ds_read_b128 v[80:83], v220 offset:0
	s_waitcnt lgkmcnt(6)
	v_mfma_f32_16x16x32_bf16 v[4:7], v[64:67], v[100:103], v[4:7]
	ds_read_b128 v[112:115], v224 offset:49152
	s_waitcnt lgkmcnt(6)
	v_mfma_f32_16x16x32_bf16 v[8:11], v[64:67], v[104:107], v[8:11]
	ds_read_b128 v[116:119], v224 offset:51200
	s_waitcnt lgkmcnt(6)
	v_mfma_f32_16x16x32_bf16 v[12:15], v[64:67], v[108:111], v[12:15]
	ds_read_b128 v[120:123], v224 offset:53248
	s_waitcnt lgkmcnt(6)
	v_mfma_f32_16x16x32_bf16 v[16:19], v[68:71], v[96:99], v[16:19]
	ds_read_b128 v[124:127], v224 offset:55296
	s_waitcnt lgkmcnt(7)
	v_mfma_f32_16x16x32_bf16 v[20:23], v[68:71], v[100:103], v[20:23]
	ds_read_b128 v[84:87], v220 offset:2048
	s_waitcnt lgkmcnt(8)
	v_mfma_f32_16x16x32_bf16 v[24:27], v[68:71], v[104:107], v[24:27]
	ds_read_b128 v[88:91], v220 offset:4096
	s_waitcnt lgkmcnt(9)
	v_mfma_f32_16x16x32_bf16 v[28:31], v[68:71], v[108:111], v[28:31]
	ds_read_b128 v[92:95], v220 offset:6144
	s_waitcnt lgkmcnt(9)
	v_mfma_f32_16x16x32_bf16 v[32:35], v[72:75], v[96:99], v[32:35]
	s_waitcnt lgkmcnt(9)
	v_mfma_f32_16x16x32_bf16 v[36:39], v[72:75], v[100:103], v[36:39]
	s_waitcnt lgkmcnt(9)
	v_mfma_f32_16x16x32_bf16 v[40:43], v[72:75], v[104:107], v[40:43]
	s_waitcnt lgkmcnt(9)
	v_mfma_f32_16x16x32_bf16 v[44:47], v[72:75], v[108:111], v[44:47]
	s_waitcnt vmcnt(4) lgkmcnt(0)
	s_barrier
	s_add_u32 m0, s38, 0
	s_nop 0
	global_load_lds_dwordx4 v226, s[98:99]
	s_waitcnt lgkmcnt(8)
	v_mfma_f32_16x16x32_bf16 v[48:51], v[76:79], v[96:99], v[48:51]
	s_add_u32 m0, s38, 4096
	s_nop 0
	global_load_lds_dwordx4 v228, s[98:99]
	s_waitcnt lgkmcnt(8)
	v_mfma_f32_16x16x32_bf16 v[52:55], v[76:79], v[100:103], v[52:55]
	s_add_u32 m0, s38, 8192
	s_nop 0
	global_load_lds_dwordx4 v244, s[98:99]
	s_waitcnt lgkmcnt(8)
	v_mfma_f32_16x16x32_bf16 v[56:59], v[76:79], v[104:107], v[56:59]
	s_add_u32 m0, s38, 12288
	s_nop 0
	global_load_lds_dwordx4 v245, s[98:99]
	s_add_u32 s98, s98, 128
	s_addc_u32 s99, s99, 0
	s_waitcnt lgkmcnt(8)
	v_mfma_f32_16x16x32_bf16 v[60:63], v[76:79], v[108:111], v[60:63]
	s_waitcnt lgkmcnt(6)
	v_mfma_f32_16x16x32_bf16 v[0:3], v[80:83], v[112:115], v[0:3]
	ds_read_b128 v[64:67], v151 offset:16384
	s_waitcnt lgkmcnt(6)
	v_mfma_f32_16x16x32_bf16 v[4:7], v[80:83], v[116:119], v[4:7]
	ds_read_b128 v[96:99], v222 offset:49152
	s_waitcnt lgkmcnt(6)
	v_mfma_f32_16x16x32_bf16 v[8:11], v[80:83], v[120:123], v[8:11]
	ds_read_b128 v[100:103], v222 offset:51200
	s_waitcnt lgkmcnt(6)
	v_mfma_f32_16x16x32_bf16 v[12:15], v[80:83], v[124:127], v[12:15]
	ds_read_b128 v[104:107], v222 offset:53248
	s_waitcnt lgkmcnt(6)
	v_mfma_f32_16x16x32_bf16 v[16:19], v[84:87], v[112:115], v[16:19]
	ds_read_b128 v[108:111], v222 offset:55296
	s_waitcnt lgkmcnt(7)
	v_mfma_f32_16x16x32_bf16 v[20:23], v[84:87], v[116:119], v[20:23]
	ds_read_b128 v[68:71], v151 offset:18432
	s_waitcnt lgkmcnt(8)
	v_mfma_f32_16x16x32_bf16 v[24:27], v[84:87], v[120:123], v[24:27]
	ds_read_b128 v[72:75], v151 offset:20480
	s_waitcnt lgkmcnt(9)
	v_mfma_f32_16x16x32_bf16 v[28:31], v[84:87], v[124:127], v[28:31]
	ds_read_b128 v[76:79], v151 offset:22528
	s_waitcnt lgkmcnt(9)
	v_mfma_f32_16x16x32_bf16 v[32:35], v[88:91], v[112:115], v[32:35]
	s_waitcnt lgkmcnt(9)
	v_mfma_f32_16x16x32_bf16 v[36:39], v[88:91], v[116:119], v[36:39]
	s_waitcnt lgkmcnt(9)
	v_mfma_f32_16x16x32_bf16 v[40:43], v[88:91], v[120:123], v[40:43]
	s_waitcnt lgkmcnt(9)
	v_mfma_f32_16x16x32_bf16 v[44:47], v[88:91], v[124:127], v[44:47]
	s_waitcnt lgkmcnt(8)
	v_mfma_f32_16x16x32_bf16 v[48:51], v[92:95], v[112:115], v[48:51]
	s_waitcnt lgkmcnt(8)
	v_mfma_f32_16x16x32_bf16 v[52:55], v[92:95], v[116:119], v[52:55]
	s_waitcnt lgkmcnt(8)
	v_mfma_f32_16x16x32_bf16 v[56:59], v[92:95], v[120:123], v[56:59]
	s_waitcnt lgkmcnt(8)
	v_mfma_f32_16x16x32_bf16 v[60:63], v[92:95], v[124:127], v[60:63]
	s_waitcnt lgkmcnt(6)
	v_mfma_f32_16x16x32_bf16 v[160:163], v[64:67], v[96:99], v[160:163]
	ds_read_b128 v[80:83], v220 offset:16384
	s_waitcnt lgkmcnt(6)
	v_mfma_f32_16x16x32_bf16 v[164:167], v[64:67], v[100:103], v[164:167]
	ds_read_b128 v[112:115], v224 offset:49152
	s_waitcnt lgkmcnt(6)
	v_mfma_f32_16x16x32_bf16 v[168:171], v[64:67], v[104:107], v[168:171]
	ds_read_b128 v[116:119], v224 offset:51200
	s_waitcnt lgkmcnt(6)
	v_mfma_f32_16x16x32_bf16 v[172:175], v[64:67], v[108:111], v[172:175]
	ds_read_b128 v[120:123], v224 offset:53248
	s_waitcnt lgkmcnt(6)
	v_mfma_f32_16x16x32_bf16 v[176:179], v[68:71], v[96:99], v[176:179]
	ds_read_b128 v[124:127], v224 offset:55296
	s_waitcnt lgkmcnt(7)
	v_mfma_f32_16x16x32_bf16 v[180:183], v[68:71], v[100:103], v[180:183]
	ds_read_b128 v[84:87], v220 offset:18432
	s_waitcnt lgkmcnt(8)
	v_mfma_f32_16x16x32_bf16 v[184:187], v[68:71], v[104:107], v[184:187]
	ds_read_b128 v[88:91], v220 offset:20480
	s_waitcnt lgkmcnt(9)
	v_mfma_f32_16x16x32_bf16 v[188:191], v[68:71], v[108:111], v[188:191]
	ds_read_b128 v[92:95], v220 offset:22528
	s_waitcnt lgkmcnt(9)
	v_mfma_f32_16x16x32_bf16 v[192:195], v[72:75], v[96:99], v[192:195]
	s_waitcnt lgkmcnt(9)
	v_mfma_f32_16x16x32_bf16 v[196:199], v[72:75], v[100:103], v[196:199]
	s_waitcnt lgkmcnt(9)
	v_mfma_f32_16x16x32_bf16 v[200:203], v[72:75], v[104:107], v[200:203]
	s_waitcnt lgkmcnt(9)
	v_mfma_f32_16x16x32_bf16 v[204:207], v[72:75], v[108:111], v[204:207]
	s_waitcnt vmcnt(0) lgkmcnt(0)
	s_barrier
	s_add_u32 m0, s38, 16384
	s_nop 0
	global_load_lds_dwordx4 v226, s[100:101]
	s_waitcnt lgkmcnt(8)
	v_mfma_f32_16x16x32_bf16 v[208:211], v[76:79], v[96:99], v[208:211]
	s_add_u32 m0, s38, 20480
	s_nop 0
	global_load_lds_dwordx4 v228, s[100:101]
	s_waitcnt lgkmcnt(8)
	v_mfma_f32_16x16x32_bf16 v[212:215], v[76:79], v[100:103], v[212:215]
	s_add_u32 m0, s38, 24576
	s_nop 0
	global_load_lds_dwordx4 v244, s[100:101]
	s_waitcnt lgkmcnt(8)
	v_mfma_f32_16x16x32_bf16 v[216:219], v[76:79], v[104:107], v[216:219]
	s_add_u32 m0, s38, 28672
	s_nop 0
	global_load_lds_dwordx4 v245, s[100:101]
	s_add_u32 s100, s100, 128
	s_addc_u32 s101, s101, 0
	s_waitcnt lgkmcnt(8)
	v_mfma_f32_16x16x32_bf16 v[230:233], v[76:79], v[108:111], v[230:233]
	s_add_u32 m0, s38, 49152
	s_nop 0
	global_load_lds_dwordx4 v226, s[4:5]
	s_waitcnt lgkmcnt(6)
	v_mfma_f32_16x16x32_bf16 v[160:163], v[80:83], v[112:115], v[160:163]
	ds_read_b128 v[64:67], v151 offset:0
	s_add_u32 m0, s38, 53248
	s_nop 0
	global_load_lds_dwordx4 v228, s[4:5]
	s_waitcnt lgkmcnt(6)
	v_mfma_f32_16x16x32_bf16 v[164:167], v[80:83], v[116:119], v[164:167]
	ds_read_b128 v[96:99], v222 offset:32768
	s_add_u32 m0, s38, 57344
	s_nop 0
	global_load_lds_dwordx4 v244, s[4:5]
	s_waitcnt lgkmcnt(6)
	v_mfma_f32_16x16x32_bf16 v[168:171], v[80:83], v[120:123], v[168:171]
	ds_read_b128 v[100:103], v222 offset:34816
	s_add_u32 m0, s38, 61440
	s_nop 0
	global_load_lds_dwordx4 v245, s[4:5]
	s_add_u32 s4, s4, 128
	s_addc_u32 s5, s5, 0
	s_waitcnt lgkmcnt(6)
	v_mfma_f32_16x16x32_bf16 v[172:175], v[80:83], v[124:127], v[172:175]
	ds_read_b128 v[104:107], v222 offset:36864
	s_waitcnt lgkmcnt(6)
	v_mfma_f32_16x16x32_bf16 v[176:179], v[84:87], v[112:115], v[176:179]
	ds_read_b128 v[108:111], v222 offset:38912
	s_waitcnt lgkmcnt(7)
	v_mfma_f32_16x16x32_bf16 v[180:183], v[84:87], v[116:119], v[180:183]
	ds_read_b128 v[68:71], v151 offset:2048
	s_waitcnt lgkmcnt(8)
	v_mfma_f32_16x16x32_bf16 v[184:187], v[84:87], v[120:123], v[184:187]
	ds_read_b128 v[72:75], v151 offset:4096
	s_waitcnt lgkmcnt(9)
	v_mfma_f32_16x16x32_bf16 v[188:191], v[84:87], v[124:127], v[188:191]
	ds_read_b128 v[76:79], v151 offset:6144
	s_waitcnt lgkmcnt(9)
	v_mfma_f32_16x16x32_bf16 v[192:195], v[88:91], v[112:115], v[192:195]
	s_waitcnt lgkmcnt(9)
	v_mfma_f32_16x16x32_bf16 v[196:199], v[88:91], v[116:119], v[196:199]
	s_waitcnt lgkmcnt(9)
	v_mfma_f32_16x16x32_bf16 v[200:203], v[88:91], v[120:123], v[200:203]
	s_waitcnt lgkmcnt(9)
	v_mfma_f32_16x16x32_bf16 v[204:207], v[88:91], v[124:127], v[204:207]
	s_waitcnt lgkmcnt(8)
	v_mfma_f32_16x16x32_bf16 v[208:211], v[92:95], v[112:115], v[208:211]
	s_waitcnt lgkmcnt(8)
	v_mfma_f32_16x16x32_bf16 v[212:215], v[92:95], v[116:119], v[212:215]
	s_waitcnt lgkmcnt(8)
	v_mfma_f32_16x16x32_bf16 v[216:219], v[92:95], v[120:123], v[216:219]
	s_waitcnt lgkmcnt(8)
	v_mfma_f32_16x16x32_bf16 v[230:233], v[92:95], v[124:127], v[230:233]
	s_waitcnt lgkmcnt(6)
	v_mfma_f32_16x16x32_bf16 v[0:3], v[64:67], v[96:99], v[0:3]
	ds_read_b128 v[80:83], v220 offset:0
	s_waitcnt lgkmcnt(6)
	v_mfma_f32_16x16x32_bf16 v[4:7], v[64:67], v[100:103], v[4:7]
	ds_read_b128 v[112:115], v224 offset:32768
	s_waitcnt lgkmcnt(6)
	v_mfma_f32_16x16x32_bf16 v[8:11], v[64:67], v[104:107], v[8:11]
	ds_read_b128 v[116:119], v224 offset:34816
	s_waitcnt lgkmcnt(6)
	v_mfma_f32_16x16x32_bf16 v[12:15], v[64:67], v[108:111], v[12:15]
	ds_read_b128 v[120:123], v224 offset:36864
	s_waitcnt lgkmcnt(6)
	v_mfma_f32_16x16x32_bf16 v[16:19], v[68:71], v[96:99], v[16:19]
	ds_read_b128 v[124:127], v224 offset:38912
	s_waitcnt lgkmcnt(7)
	v_mfma_f32_16x16x32_bf16 v[20:23], v[68:71], v[100:103], v[20:23]
	ds_read_b128 v[84:87], v220 offset:2048
	s_waitcnt lgkmcnt(8)
	v_mfma_f32_16x16x32_bf16 v[24:27], v[68:71], v[104:107], v[24:27]
	ds_read_b128 v[88:91], v220 offset:4096
	s_waitcnt lgkmcnt(9)
	v_mfma_f32_16x16x32_bf16 v[28:31], v[68:71], v[108:111], v[28:31]
	ds_read_b128 v[92:95], v220 offset:6144
	s_waitcnt lgkmcnt(9)
	v_mfma_f32_16x16x32_bf16 v[32:35], v[72:75], v[96:99], v[32:35]
	s_waitcnt lgkmcnt(9)
	v_mfma_f32_16x16x32_bf16 v[36:39], v[72:75], v[100:103], v[36:39]
	s_waitcnt lgkmcnt(9)
	v_mfma_f32_16x16x32_bf16 v[40:43], v[72:75], v[104:107], v[40:43]
	s_waitcnt lgkmcnt(9)
	v_mfma_f32_16x16x32_bf16 v[44:47], v[72:75], v[108:111], v[44:47]
	s_waitcnt vmcnt(4) lgkmcnt(0)
	s_barrier
	s_add_u32 m0, s38, 0
	s_nop 0
	global_load_lds_dwordx4 v226, s[98:99]
	s_waitcnt lgkmcnt(8)
	v_mfma_f32_16x16x32_bf16 v[48:51], v[76:79], v[96:99], v[48:51]
	s_add_u32 m0, s38, 4096
	s_nop 0
	global_load_lds_dwordx4 v228, s[98:99]
	s_waitcnt lgkmcnt(8)
	v_mfma_f32_16x16x32_bf16 v[52:55], v[76:79], v[100:103], v[52:55]
	s_add_u32 m0, s38, 8192
	s_nop 0
	global_load_lds_dwordx4 v244, s[98:99]
	s_waitcnt lgkmcnt(8)
	v_mfma_f32_16x16x32_bf16 v[56:59], v[76:79], v[104:107], v[56:59]
	s_add_u32 m0, s38, 12288
	s_nop 0
	global_load_lds_dwordx4 v245, s[98:99]
	s_add_u32 s98, s98, 128
	s_addc_u32 s99, s99, 0
	s_waitcnt lgkmcnt(8)
	v_mfma_f32_16x16x32_bf16 v[60:63], v[76:79], v[108:111], v[60:63]
	s_waitcnt lgkmcnt(6)
	v_mfma_f32_16x16x32_bf16 v[0:3], v[80:83], v[112:115], v[0:3]
	ds_read_b128 v[64:67], v151 offset:16384
	s_waitcnt lgkmcnt(6)
	v_mfma_f32_16x16x32_bf16 v[4:7], v[80:83], v[116:119], v[4:7]
	ds_read_b128 v[96:99], v222 offset:32768
	s_waitcnt lgkmcnt(6)
	v_mfma_f32_16x16x32_bf16 v[8:11], v[80:83], v[120:123], v[8:11]
	ds_read_b128 v[100:103], v222 offset:34816
	s_waitcnt lgkmcnt(6)
	v_mfma_f32_16x16x32_bf16 v[12:15], v[80:83], v[124:127], v[12:15]
	ds_read_b128 v[104:107], v222 offset:36864
	s_waitcnt lgkmcnt(6)
	v_mfma_f32_16x16x32_bf16 v[16:19], v[84:87], v[112:115], v[16:19]
	ds_read_b128 v[108:111], v222 offset:38912
	s_waitcnt lgkmcnt(7)
	v_mfma_f32_16x16x32_bf16 v[20:23], v[84:87], v[116:119], v[20:23]
	ds_read_b128 v[68:71], v151 offset:18432
	s_waitcnt lgkmcnt(8)
	v_mfma_f32_16x16x32_bf16 v[24:27], v[84:87], v[120:123], v[24:27]
	ds_read_b128 v[72:75], v151 offset:20480
	s_waitcnt lgkmcnt(9)
	v_mfma_f32_16x16x32_bf16 v[28:31], v[84:87], v[124:127], v[28:31]
	ds_read_b128 v[76:79], v151 offset:22528
	s_waitcnt lgkmcnt(9)
	v_mfma_f32_16x16x32_bf16 v[32:35], v[88:91], v[112:115], v[32:35]
	s_waitcnt lgkmcnt(9)
	v_mfma_f32_16x16x32_bf16 v[36:39], v[88:91], v[116:119], v[36:39]
	s_waitcnt lgkmcnt(9)
	v_mfma_f32_16x16x32_bf16 v[40:43], v[88:91], v[120:123], v[40:43]
	s_waitcnt lgkmcnt(9)
	v_mfma_f32_16x16x32_bf16 v[44:47], v[88:91], v[124:127], v[44:47]
	s_waitcnt lgkmcnt(8)
	v_mfma_f32_16x16x32_bf16 v[48:51], v[92:95], v[112:115], v[48:51]
	s_waitcnt lgkmcnt(8)
	v_mfma_f32_16x16x32_bf16 v[52:55], v[92:95], v[116:119], v[52:55]
	s_waitcnt lgkmcnt(8)
	v_mfma_f32_16x16x32_bf16 v[56:59], v[92:95], v[120:123], v[56:59]
	s_waitcnt lgkmcnt(8)
	v_mfma_f32_16x16x32_bf16 v[60:63], v[92:95], v[124:127], v[60:63]
	s_waitcnt lgkmcnt(6)
	v_mfma_f32_16x16x32_bf16 v[160:163], v[64:67], v[96:99], v[160:163]
	ds_read_b128 v[80:83], v220 offset:16384
	s_waitcnt lgkmcnt(6)
	v_mfma_f32_16x16x32_bf16 v[164:167], v[64:67], v[100:103], v[164:167]
	ds_read_b128 v[112:115], v224 offset:32768
	s_waitcnt lgkmcnt(6)
	v_mfma_f32_16x16x32_bf16 v[168:171], v[64:67], v[104:107], v[168:171]
	ds_read_b128 v[116:119], v224 offset:34816
	s_waitcnt lgkmcnt(6)
	v_mfma_f32_16x16x32_bf16 v[172:175], v[64:67], v[108:111], v[172:175]
	ds_read_b128 v[120:123], v224 offset:36864
	s_waitcnt lgkmcnt(6)
	v_mfma_f32_16x16x32_bf16 v[176:179], v[68:71], v[96:99], v[176:179]
	ds_read_b128 v[124:127], v224 offset:38912
	s_waitcnt lgkmcnt(7)
	v_mfma_f32_16x16x32_bf16 v[180:183], v[68:71], v[100:103], v[180:183]
	ds_read_b128 v[84:87], v220 offset:18432
	s_waitcnt lgkmcnt(8)
	v_mfma_f32_16x16x32_bf16 v[184:187], v[68:71], v[104:107], v[184:187]
	ds_read_b128 v[88:91], v220 offset:20480
	s_waitcnt lgkmcnt(9)
	v_mfma_f32_16x16x32_bf16 v[188:191], v[68:71], v[108:111], v[188:191]
	ds_read_b128 v[92:95], v220 offset:22528
	s_waitcnt lgkmcnt(9)
	v_mfma_f32_16x16x32_bf16 v[192:195], v[72:75], v[96:99], v[192:195]
	s_waitcnt lgkmcnt(9)
	v_mfma_f32_16x16x32_bf16 v[196:199], v[72:75], v[100:103], v[196:199]
	s_waitcnt lgkmcnt(9)
	v_mfma_f32_16x16x32_bf16 v[200:203], v[72:75], v[104:107], v[200:203]
	s_waitcnt lgkmcnt(9)
	v_mfma_f32_16x16x32_bf16 v[204:207], v[72:75], v[108:111], v[204:207]
	s_waitcnt vmcnt(0) lgkmcnt(0)
	s_barrier
	s_add_u32 m0, s38, 16384
	s_nop 0
	global_load_lds_dwordx4 v226, s[100:101]
	s_waitcnt lgkmcnt(8)
	v_mfma_f32_16x16x32_bf16 v[208:211], v[76:79], v[96:99], v[208:211]
	s_add_u32 m0, s38, 20480
	s_nop 0
	global_load_lds_dwordx4 v228, s[100:101]
	s_waitcnt lgkmcnt(8)
	v_mfma_f32_16x16x32_bf16 v[212:215], v[76:79], v[100:103], v[212:215]
	s_add_u32 m0, s38, 24576
	s_nop 0
	global_load_lds_dwordx4 v244, s[100:101]
	s_waitcnt lgkmcnt(8)
	v_mfma_f32_16x16x32_bf16 v[216:219], v[76:79], v[104:107], v[216:219]
	s_add_u32 m0, s38, 28672
	s_nop 0
	global_load_lds_dwordx4 v245, s[100:101]
	s_add_u32 s100, s100, 128
	s_addc_u32 s101, s101, 0
	s_waitcnt lgkmcnt(8)
	v_mfma_f32_16x16x32_bf16 v[230:233], v[76:79], v[108:111], v[230:233]
	s_add_u32 m0, s38, 32768
	s_nop 0
	global_load_lds_dwordx4 v226, s[4:5]
	s_waitcnt lgkmcnt(6)
	v_mfma_f32_16x16x32_bf16 v[160:163], v[80:83], v[112:115], v[160:163]
	ds_read_b128 v[64:67], v151 offset:0
	s_add_u32 m0, s38, 36864
	s_nop 0
	global_load_lds_dwordx4 v228, s[4:5]
	s_waitcnt lgkmcnt(6)
	v_mfma_f32_16x16x32_bf16 v[164:167], v[80:83], v[116:119], v[164:167]
	ds_read_b128 v[96:99], v222 offset:49152
	s_add_u32 m0, s38, 40960
	s_nop 0
	global_load_lds_dwordx4 v244, s[4:5]
	s_waitcnt lgkmcnt(6)
	v_mfma_f32_16x16x32_bf16 v[168:171], v[80:83], v[120:123], v[168:171]
	ds_read_b128 v[100:103], v222 offset:51200
	s_add_u32 m0, s38, 45056
	s_nop 0
	global_load_lds_dwordx4 v245, s[4:5]
	s_add_u32 s4, s4, 128
	s_addc_u32 s5, s5, 0
	s_waitcnt lgkmcnt(6)
	v_mfma_f32_16x16x32_bf16 v[172:175], v[80:83], v[124:127], v[172:175]
	ds_read_b128 v[104:107], v222 offset:53248
	s_waitcnt lgkmcnt(6)
	v_mfma_f32_16x16x32_bf16 v[176:179], v[84:87], v[112:115], v[176:179]
	ds_read_b128 v[108:111], v222 offset:55296
	s_waitcnt lgkmcnt(7)
	v_mfma_f32_16x16x32_bf16 v[180:183], v[84:87], v[116:119], v[180:183]
	ds_read_b128 v[68:71], v151 offset:2048
	s_waitcnt lgkmcnt(8)
	v_mfma_f32_16x16x32_bf16 v[184:187], v[84:87], v[120:123], v[184:187]
	ds_read_b128 v[72:75], v151 offset:4096
	s_waitcnt lgkmcnt(9)
	v_mfma_f32_16x16x32_bf16 v[188:191], v[84:87], v[124:127], v[188:191]
	ds_read_b128 v[76:79], v151 offset:6144
	s_waitcnt lgkmcnt(9)
	v_mfma_f32_16x16x32_bf16 v[192:195], v[88:91], v[112:115], v[192:195]
	s_waitcnt lgkmcnt(9)
	v_mfma_f32_16x16x32_bf16 v[196:199], v[88:91], v[116:119], v[196:199]
	s_waitcnt lgkmcnt(9)
	v_mfma_f32_16x16x32_bf16 v[200:203], v[88:91], v[120:123], v[200:203]
	s_waitcnt lgkmcnt(9)
	v_mfma_f32_16x16x32_bf16 v[204:207], v[88:91], v[124:127], v[204:207]
	s_waitcnt lgkmcnt(8)
	v_mfma_f32_16x16x32_bf16 v[208:211], v[92:95], v[112:115], v[208:211]
	s_waitcnt lgkmcnt(8)
	v_mfma_f32_16x16x32_bf16 v[212:215], v[92:95], v[116:119], v[212:215]
	s_waitcnt lgkmcnt(8)
	v_mfma_f32_16x16x32_bf16 v[216:219], v[92:95], v[120:123], v[216:219]
	s_waitcnt lgkmcnt(8)
	v_mfma_f32_16x16x32_bf16 v[230:233], v[92:95], v[124:127], v[230:233]
	s_waitcnt lgkmcnt(6)
	v_mfma_f32_16x16x32_bf16 v[0:3], v[64:67], v[96:99], v[0:3]
	ds_read_b128 v[80:83], v220 offset:0
	s_waitcnt lgkmcnt(6)
	v_mfma_f32_16x16x32_bf16 v[4:7], v[64:67], v[100:103], v[4:7]
	ds_read_b128 v[112:115], v224 offset:49152
	s_waitcnt lgkmcnt(6)
	v_mfma_f32_16x16x32_bf16 v[8:11], v[64:67], v[104:107], v[8:11]
	ds_read_b128 v[116:119], v224 offset:51200
	s_waitcnt lgkmcnt(6)
	v_mfma_f32_16x16x32_bf16 v[12:15], v[64:67], v[108:111], v[12:15]
	ds_read_b128 v[120:123], v224 offset:53248
	s_waitcnt lgkmcnt(6)
	v_mfma_f32_16x16x32_bf16 v[16:19], v[68:71], v[96:99], v[16:19]
	ds_read_b128 v[124:127], v224 offset:55296
	s_waitcnt lgkmcnt(7)
	v_mfma_f32_16x16x32_bf16 v[20:23], v[68:71], v[100:103], v[20:23]
	ds_read_b128 v[84:87], v220 offset:2048
	s_waitcnt lgkmcnt(8)
	v_mfma_f32_16x16x32_bf16 v[24:27], v[68:71], v[104:107], v[24:27]
	ds_read_b128 v[88:91], v220 offset:4096
	s_waitcnt lgkmcnt(9)
	v_mfma_f32_16x16x32_bf16 v[28:31], v[68:71], v[108:111], v[28:31]
	ds_read_b128 v[92:95], v220 offset:6144
	s_waitcnt lgkmcnt(9)
	v_mfma_f32_16x16x32_bf16 v[32:35], v[72:75], v[96:99], v[32:35]
	s_waitcnt lgkmcnt(9)
	v_mfma_f32_16x16x32_bf16 v[36:39], v[72:75], v[100:103], v[36:39]
	s_waitcnt lgkmcnt(9)
	v_mfma_f32_16x16x32_bf16 v[40:43], v[72:75], v[104:107], v[40:43]
	s_waitcnt lgkmcnt(9)
	v_mfma_f32_16x16x32_bf16 v[44:47], v[72:75], v[108:111], v[44:47]
	s_waitcnt vmcnt(4) lgkmcnt(0)
	s_barrier
	s_add_u32 m0, s38, 0
	s_nop 0
	global_load_lds_dwordx4 v226, s[98:99]
	s_waitcnt lgkmcnt(8)
	v_mfma_f32_16x16x32_bf16 v[48:51], v[76:79], v[96:99], v[48:51]
	s_add_u32 m0, s38, 4096
	s_nop 0
	global_load_lds_dwordx4 v228, s[98:99]
	s_waitcnt lgkmcnt(8)
	v_mfma_f32_16x16x32_bf16 v[52:55], v[76:79], v[100:103], v[52:55]
	s_add_u32 m0, s38, 8192
	s_nop 0
	global_load_lds_dwordx4 v244, s[98:99]
	s_waitcnt lgkmcnt(8)
	v_mfma_f32_16x16x32_bf16 v[56:59], v[76:79], v[104:107], v[56:59]
	s_add_u32 m0, s38, 12288
	s_nop 0
	global_load_lds_dwordx4 v245, s[98:99]
	s_add_u32 s98, s98, 128
	s_addc_u32 s99, s99, 0
	s_waitcnt lgkmcnt(8)
	v_mfma_f32_16x16x32_bf16 v[60:63], v[76:79], v[108:111], v[60:63]
	s_waitcnt lgkmcnt(6)
	v_mfma_f32_16x16x32_bf16 v[0:3], v[80:83], v[112:115], v[0:3]
	ds_read_b128 v[64:67], v151 offset:16384
	s_waitcnt lgkmcnt(6)
	v_mfma_f32_16x16x32_bf16 v[4:7], v[80:83], v[116:119], v[4:7]
	ds_read_b128 v[96:99], v222 offset:49152
	s_waitcnt lgkmcnt(6)
	v_mfma_f32_16x16x32_bf16 v[8:11], v[80:83], v[120:123], v[8:11]
	ds_read_b128 v[100:103], v222 offset:51200
	s_waitcnt lgkmcnt(6)
	v_mfma_f32_16x16x32_bf16 v[12:15], v[80:83], v[124:127], v[12:15]
	ds_read_b128 v[104:107], v222 offset:53248
	s_waitcnt lgkmcnt(6)
	v_mfma_f32_16x16x32_bf16 v[16:19], v[84:87], v[112:115], v[16:19]
	ds_read_b128 v[108:111], v222 offset:55296
	s_waitcnt lgkmcnt(7)
	v_mfma_f32_16x16x32_bf16 v[20:23], v[84:87], v[116:119], v[20:23]
	ds_read_b128 v[68:71], v151 offset:18432
	s_waitcnt lgkmcnt(8)
	v_mfma_f32_16x16x32_bf16 v[24:27], v[84:87], v[120:123], v[24:27]
	ds_read_b128 v[72:75], v151 offset:20480
	s_waitcnt lgkmcnt(9)
	v_mfma_f32_16x16x32_bf16 v[28:31], v[84:87], v[124:127], v[28:31]
	ds_read_b128 v[76:79], v151 offset:22528
	s_waitcnt lgkmcnt(9)
	v_mfma_f32_16x16x32_bf16 v[32:35], v[88:91], v[112:115], v[32:35]
	s_waitcnt lgkmcnt(9)
	v_mfma_f32_16x16x32_bf16 v[36:39], v[88:91], v[116:119], v[36:39]
	s_waitcnt lgkmcnt(9)
	v_mfma_f32_16x16x32_bf16 v[40:43], v[88:91], v[120:123], v[40:43]
	s_waitcnt lgkmcnt(9)
	v_mfma_f32_16x16x32_bf16 v[44:47], v[88:91], v[124:127], v[44:47]
	s_waitcnt lgkmcnt(8)
	v_mfma_f32_16x16x32_bf16 v[48:51], v[92:95], v[112:115], v[48:51]
	s_waitcnt lgkmcnt(8)
	v_mfma_f32_16x16x32_bf16 v[52:55], v[92:95], v[116:119], v[52:55]
	s_waitcnt lgkmcnt(8)
	v_mfma_f32_16x16x32_bf16 v[56:59], v[92:95], v[120:123], v[56:59]
	s_waitcnt lgkmcnt(8)
	v_mfma_f32_16x16x32_bf16 v[60:63], v[92:95], v[124:127], v[60:63]
	s_waitcnt lgkmcnt(6)
	v_mfma_f32_16x16x32_bf16 v[160:163], v[64:67], v[96:99], v[160:163]
	ds_read_b128 v[80:83], v220 offset:16384
	s_waitcnt lgkmcnt(6)
	v_mfma_f32_16x16x32_bf16 v[164:167], v[64:67], v[100:103], v[164:167]
	ds_read_b128 v[112:115], v224 offset:49152
	s_waitcnt lgkmcnt(6)
	v_mfma_f32_16x16x32_bf16 v[168:171], v[64:67], v[104:107], v[168:171]
	ds_read_b128 v[116:119], v224 offset:51200
	s_waitcnt lgkmcnt(6)
	v_mfma_f32_16x16x32_bf16 v[172:175], v[64:67], v[108:111], v[172:175]
	ds_read_b128 v[120:123], v224 offset:53248
	s_waitcnt lgkmcnt(6)
	v_mfma_f32_16x16x32_bf16 v[176:179], v[68:71], v[96:99], v[176:179]
	ds_read_b128 v[124:127], v224 offset:55296
	s_waitcnt lgkmcnt(7)
	v_mfma_f32_16x16x32_bf16 v[180:183], v[68:71], v[100:103], v[180:183]
	ds_read_b128 v[84:87], v220 offset:18432
	s_waitcnt lgkmcnt(8)
	v_mfma_f32_16x16x32_bf16 v[184:187], v[68:71], v[104:107], v[184:187]
	ds_read_b128 v[88:91], v220 offset:20480
	s_waitcnt lgkmcnt(9)
	v_mfma_f32_16x16x32_bf16 v[188:191], v[68:71], v[108:111], v[188:191]
	ds_read_b128 v[92:95], v220 offset:22528
	s_waitcnt lgkmcnt(9)
	v_mfma_f32_16x16x32_bf16 v[192:195], v[72:75], v[96:99], v[192:195]
	s_waitcnt lgkmcnt(9)
	v_mfma_f32_16x16x32_bf16 v[196:199], v[72:75], v[100:103], v[196:199]
	s_waitcnt lgkmcnt(9)
	v_mfma_f32_16x16x32_bf16 v[200:203], v[72:75], v[104:107], v[200:203]
	s_waitcnt lgkmcnt(9)
	v_mfma_f32_16x16x32_bf16 v[204:207], v[72:75], v[108:111], v[204:207]
	s_waitcnt vmcnt(0) lgkmcnt(0)
	s_barrier
	s_add_u32 m0, s38, 16384
	s_nop 0
	global_load_lds_dwordx4 v226, s[100:101]
	s_waitcnt lgkmcnt(8)
	v_mfma_f32_16x16x32_bf16 v[208:211], v[76:79], v[96:99], v[208:211]
	s_add_u32 m0, s38, 20480
	s_nop 0
	global_load_lds_dwordx4 v228, s[100:101]
	s_waitcnt lgkmcnt(8)
	v_mfma_f32_16x16x32_bf16 v[212:215], v[76:79], v[100:103], v[212:215]
	s_add_u32 m0, s38, 24576
	s_nop 0
	global_load_lds_dwordx4 v244, s[100:101]
	s_waitcnt lgkmcnt(8)
	v_mfma_f32_16x16x32_bf16 v[216:219], v[76:79], v[104:107], v[216:219]
	s_add_u32 m0, s38, 28672
	s_nop 0
	global_load_lds_dwordx4 v245, s[100:101]
	s_add_u32 s100, s100, 128
	s_addc_u32 s101, s101, 0
	s_waitcnt lgkmcnt(8)
	v_mfma_f32_16x16x32_bf16 v[230:233], v[76:79], v[108:111], v[230:233]
	s_add_u32 m0, s38, 49152
	s_nop 0
	global_load_lds_dwordx4 v226, s[4:5]
	s_waitcnt lgkmcnt(6)
	v_mfma_f32_16x16x32_bf16 v[160:163], v[80:83], v[112:115], v[160:163]
	ds_read_b128 v[64:67], v151 offset:0
	s_add_u32 m0, s38, 53248
	s_nop 0
	global_load_lds_dwordx4 v228, s[4:5]
	s_waitcnt lgkmcnt(6)
	v_mfma_f32_16x16x32_bf16 v[164:167], v[80:83], v[116:119], v[164:167]
	ds_read_b128 v[96:99], v222 offset:32768
	s_add_u32 m0, s38, 57344
	s_nop 0
	global_load_lds_dwordx4 v244, s[4:5]
	s_waitcnt lgkmcnt(6)
	v_mfma_f32_16x16x32_bf16 v[168:171], v[80:83], v[120:123], v[168:171]
	ds_read_b128 v[100:103], v222 offset:34816
	s_add_u32 m0, s38, 61440
	s_nop 0
	global_load_lds_dwordx4 v245, s[4:5]
	s_add_u32 s4, s4, 128
	s_addc_u32 s5, s5, 0
	s_waitcnt lgkmcnt(6)
	v_mfma_f32_16x16x32_bf16 v[172:175], v[80:83], v[124:127], v[172:175]
	ds_read_b128 v[104:107], v222 offset:36864
	s_waitcnt lgkmcnt(6)
	v_mfma_f32_16x16x32_bf16 v[176:179], v[84:87], v[112:115], v[176:179]
	ds_read_b128 v[108:111], v222 offset:38912
	s_waitcnt lgkmcnt(7)
	v_mfma_f32_16x16x32_bf16 v[180:183], v[84:87], v[116:119], v[180:183]
	ds_read_b128 v[68:71], v151 offset:2048
	s_waitcnt lgkmcnt(8)
	v_mfma_f32_16x16x32_bf16 v[184:187], v[84:87], v[120:123], v[184:187]
	ds_read_b128 v[72:75], v151 offset:4096
	s_waitcnt lgkmcnt(9)
	v_mfma_f32_16x16x32_bf16 v[188:191], v[84:87], v[124:127], v[188:191]
	ds_read_b128 v[76:79], v151 offset:6144
	s_waitcnt lgkmcnt(9)
	v_mfma_f32_16x16x32_bf16 v[192:195], v[88:91], v[112:115], v[192:195]
	s_waitcnt lgkmcnt(9)
	v_mfma_f32_16x16x32_bf16 v[196:199], v[88:91], v[116:119], v[196:199]
	s_waitcnt lgkmcnt(9)
	v_mfma_f32_16x16x32_bf16 v[200:203], v[88:91], v[120:123], v[200:203]
	s_waitcnt lgkmcnt(9)
	v_mfma_f32_16x16x32_bf16 v[204:207], v[88:91], v[124:127], v[204:207]
	s_waitcnt lgkmcnt(8)
	v_mfma_f32_16x16x32_bf16 v[208:211], v[92:95], v[112:115], v[208:211]
	s_waitcnt lgkmcnt(8)
	v_mfma_f32_16x16x32_bf16 v[212:215], v[92:95], v[116:119], v[212:215]
	s_waitcnt lgkmcnt(8)
	v_mfma_f32_16x16x32_bf16 v[216:219], v[92:95], v[120:123], v[216:219]
	s_waitcnt lgkmcnt(8)
	v_mfma_f32_16x16x32_bf16 v[230:233], v[92:95], v[124:127], v[230:233]
	s_waitcnt lgkmcnt(6)
	v_mfma_f32_16x16x32_bf16 v[0:3], v[64:67], v[96:99], v[0:3]
	ds_read_b128 v[80:83], v220 offset:0
	s_waitcnt lgkmcnt(6)
	v_mfma_f32_16x16x32_bf16 v[4:7], v[64:67], v[100:103], v[4:7]
	ds_read_b128 v[112:115], v224 offset:32768
	s_waitcnt lgkmcnt(6)
	v_mfma_f32_16x16x32_bf16 v[8:11], v[64:67], v[104:107], v[8:11]
	ds_read_b128 v[116:119], v224 offset:34816
	s_waitcnt lgkmcnt(6)
	v_mfma_f32_16x16x32_bf16 v[12:15], v[64:67], v[108:111], v[12:15]
	ds_read_b128 v[120:123], v224 offset:36864
	s_waitcnt lgkmcnt(6)
	v_mfma_f32_16x16x32_bf16 v[16:19], v[68:71], v[96:99], v[16:19]
	ds_read_b128 v[124:127], v224 offset:38912
	s_waitcnt lgkmcnt(7)
	v_mfma_f32_16x16x32_bf16 v[20:23], v[68:71], v[100:103], v[20:23]
	ds_read_b128 v[84:87], v220 offset:2048
	s_waitcnt lgkmcnt(8)
	v_mfma_f32_16x16x32_bf16 v[24:27], v[68:71], v[104:107], v[24:27]
	ds_read_b128 v[88:91], v220 offset:4096
	s_waitcnt lgkmcnt(9)
	v_mfma_f32_16x16x32_bf16 v[28:31], v[68:71], v[108:111], v[28:31]
	ds_read_b128 v[92:95], v220 offset:6144
	s_waitcnt lgkmcnt(9)
	v_mfma_f32_16x16x32_bf16 v[32:35], v[72:75], v[96:99], v[32:35]
	s_waitcnt lgkmcnt(9)
	v_mfma_f32_16x16x32_bf16 v[36:39], v[72:75], v[100:103], v[36:39]
	s_waitcnt lgkmcnt(9)
	v_mfma_f32_16x16x32_bf16 v[40:43], v[72:75], v[104:107], v[40:43]
	s_waitcnt lgkmcnt(9)
	v_mfma_f32_16x16x32_bf16 v[44:47], v[72:75], v[108:111], v[44:47]
	s_waitcnt vmcnt(4) lgkmcnt(0)
	s_barrier
	s_add_u32 m0, s38, 0
	s_nop 0
	global_load_lds_dwordx4 v226, s[98:99]
	s_waitcnt lgkmcnt(8)
	v_mfma_f32_16x16x32_bf16 v[48:51], v[76:79], v[96:99], v[48:51]
	s_add_u32 m0, s38, 4096
	s_nop 0
	global_load_lds_dwordx4 v228, s[98:99]
	s_waitcnt lgkmcnt(8)
	v_mfma_f32_16x16x32_bf16 v[52:55], v[76:79], v[100:103], v[52:55]
	s_add_u32 m0, s38, 8192
	s_nop 0
	global_load_lds_dwordx4 v244, s[98:99]
	s_waitcnt lgkmcnt(8)
	v_mfma_f32_16x16x32_bf16 v[56:59], v[76:79], v[104:107], v[56:59]
	s_add_u32 m0, s38, 12288
	s_nop 0
	global_load_lds_dwordx4 v245, s[98:99]
	s_add_u32 s98, s98, 128
	s_addc_u32 s99, s99, 0
	s_waitcnt lgkmcnt(8)
	v_mfma_f32_16x16x32_bf16 v[60:63], v[76:79], v[108:111], v[60:63]
	s_waitcnt lgkmcnt(6)
	v_mfma_f32_16x16x32_bf16 v[0:3], v[80:83], v[112:115], v[0:3]
	ds_read_b128 v[64:67], v151 offset:16384
	s_waitcnt lgkmcnt(6)
	v_mfma_f32_16x16x32_bf16 v[4:7], v[80:83], v[116:119], v[4:7]
	ds_read_b128 v[96:99], v222 offset:32768
	s_waitcnt lgkmcnt(6)
	v_mfma_f32_16x16x32_bf16 v[8:11], v[80:83], v[120:123], v[8:11]
	ds_read_b128 v[100:103], v222 offset:34816
	s_waitcnt lgkmcnt(6)
	v_mfma_f32_16x16x32_bf16 v[12:15], v[80:83], v[124:127], v[12:15]
	ds_read_b128 v[104:107], v222 offset:36864
	s_waitcnt lgkmcnt(6)
	v_mfma_f32_16x16x32_bf16 v[16:19], v[84:87], v[112:115], v[16:19]
	ds_read_b128 v[108:111], v222 offset:38912
	s_waitcnt lgkmcnt(7)
	v_mfma_f32_16x16x32_bf16 v[20:23], v[84:87], v[116:119], v[20:23]
	ds_read_b128 v[68:71], v151 offset:18432
	s_waitcnt lgkmcnt(8)
	v_mfma_f32_16x16x32_bf16 v[24:27], v[84:87], v[120:123], v[24:27]
	ds_read_b128 v[72:75], v151 offset:20480
	s_waitcnt lgkmcnt(9)
	v_mfma_f32_16x16x32_bf16 v[28:31], v[84:87], v[124:127], v[28:31]
	ds_read_b128 v[76:79], v151 offset:22528
	s_waitcnt lgkmcnt(9)
	v_mfma_f32_16x16x32_bf16 v[32:35], v[88:91], v[112:115], v[32:35]
	s_waitcnt lgkmcnt(9)
	v_mfma_f32_16x16x32_bf16 v[36:39], v[88:91], v[116:119], v[36:39]
	s_waitcnt lgkmcnt(9)
	v_mfma_f32_16x16x32_bf16 v[40:43], v[88:91], v[120:123], v[40:43]
	s_waitcnt lgkmcnt(9)
	v_mfma_f32_16x16x32_bf16 v[44:47], v[88:91], v[124:127], v[44:47]
	s_waitcnt lgkmcnt(8)
	v_mfma_f32_16x16x32_bf16 v[48:51], v[92:95], v[112:115], v[48:51]
	s_waitcnt lgkmcnt(8)
	v_mfma_f32_16x16x32_bf16 v[52:55], v[92:95], v[116:119], v[52:55]
	s_waitcnt lgkmcnt(8)
	v_mfma_f32_16x16x32_bf16 v[56:59], v[92:95], v[120:123], v[56:59]
	s_waitcnt lgkmcnt(8)
	v_mfma_f32_16x16x32_bf16 v[60:63], v[92:95], v[124:127], v[60:63]
	s_waitcnt lgkmcnt(6)
	v_mfma_f32_16x16x32_bf16 v[160:163], v[64:67], v[96:99], v[160:163]
	ds_read_b128 v[80:83], v220 offset:16384
	s_waitcnt lgkmcnt(6)
	v_mfma_f32_16x16x32_bf16 v[164:167], v[64:67], v[100:103], v[164:167]
	ds_read_b128 v[112:115], v224 offset:32768
	s_waitcnt lgkmcnt(6)
	v_mfma_f32_16x16x32_bf16 v[168:171], v[64:67], v[104:107], v[168:171]
	ds_read_b128 v[116:119], v224 offset:34816
	s_waitcnt lgkmcnt(6)
	v_mfma_f32_16x16x32_bf16 v[172:175], v[64:67], v[108:111], v[172:175]
	ds_read_b128 v[120:123], v224 offset:36864
	s_waitcnt lgkmcnt(6)
	v_mfma_f32_16x16x32_bf16 v[176:179], v[68:71], v[96:99], v[176:179]
	ds_read_b128 v[124:127], v224 offset:38912
	s_waitcnt lgkmcnt(7)
	v_mfma_f32_16x16x32_bf16 v[180:183], v[68:71], v[100:103], v[180:183]
	ds_read_b128 v[84:87], v220 offset:18432
	s_waitcnt lgkmcnt(8)
	v_mfma_f32_16x16x32_bf16 v[184:187], v[68:71], v[104:107], v[184:187]
	ds_read_b128 v[88:91], v220 offset:20480
	s_waitcnt lgkmcnt(9)
	v_mfma_f32_16x16x32_bf16 v[188:191], v[68:71], v[108:111], v[188:191]
	ds_read_b128 v[92:95], v220 offset:22528
	s_waitcnt lgkmcnt(9)
	v_mfma_f32_16x16x32_bf16 v[192:195], v[72:75], v[96:99], v[192:195]
	s_waitcnt lgkmcnt(9)
	v_mfma_f32_16x16x32_bf16 v[196:199], v[72:75], v[100:103], v[196:199]
	s_waitcnt lgkmcnt(9)
	v_mfma_f32_16x16x32_bf16 v[200:203], v[72:75], v[104:107], v[200:203]
	s_waitcnt lgkmcnt(9)
	v_mfma_f32_16x16x32_bf16 v[204:207], v[72:75], v[108:111], v[204:207]
	s_waitcnt vmcnt(0) lgkmcnt(0)
	s_barrier
	s_add_u32 m0, s38, 16384
	s_nop 0
	global_load_lds_dwordx4 v226, s[100:101]
	s_waitcnt lgkmcnt(8)
	v_mfma_f32_16x16x32_bf16 v[208:211], v[76:79], v[96:99], v[208:211]
	s_add_u32 m0, s38, 20480
	s_nop 0
	global_load_lds_dwordx4 v228, s[100:101]
	s_waitcnt lgkmcnt(8)
	v_mfma_f32_16x16x32_bf16 v[212:215], v[76:79], v[100:103], v[212:215]
	s_add_u32 m0, s38, 24576
	s_nop 0
	global_load_lds_dwordx4 v244, s[100:101]
	s_waitcnt lgkmcnt(8)
	v_mfma_f32_16x16x32_bf16 v[216:219], v[76:79], v[104:107], v[216:219]
	s_add_u32 m0, s38, 28672
	s_nop 0
	global_load_lds_dwordx4 v245, s[100:101]
	s_add_u32 s100, s100, 128
	s_addc_u32 s101, s101, 0
	s_waitcnt lgkmcnt(8)
	v_mfma_f32_16x16x32_bf16 v[230:233], v[76:79], v[108:111], v[230:233]
	s_add_u32 m0, s38, 32768
	s_nop 0
	global_load_lds_dwordx4 v226, s[4:5]
	s_waitcnt lgkmcnt(6)
	v_mfma_f32_16x16x32_bf16 v[160:163], v[80:83], v[112:115], v[160:163]
	ds_read_b128 v[64:67], v151 offset:0
	s_add_u32 m0, s38, 36864
	s_nop 0
	global_load_lds_dwordx4 v228, s[4:5]
	s_waitcnt lgkmcnt(6)
	v_mfma_f32_16x16x32_bf16 v[164:167], v[80:83], v[116:119], v[164:167]
	ds_read_b128 v[96:99], v222 offset:49152
	s_add_u32 m0, s38, 40960
	s_nop 0
	global_load_lds_dwordx4 v244, s[4:5]
	s_waitcnt lgkmcnt(6)
	v_mfma_f32_16x16x32_bf16 v[168:171], v[80:83], v[120:123], v[168:171]
	ds_read_b128 v[100:103], v222 offset:51200
	s_add_u32 m0, s38, 45056
	s_nop 0
	global_load_lds_dwordx4 v245, s[4:5]
	s_add_u32 s4, s4, 128
	s_addc_u32 s5, s5, 0
	s_waitcnt lgkmcnt(6)
	v_mfma_f32_16x16x32_bf16 v[172:175], v[80:83], v[124:127], v[172:175]
	ds_read_b128 v[104:107], v222 offset:53248
	s_waitcnt lgkmcnt(6)
	v_mfma_f32_16x16x32_bf16 v[176:179], v[84:87], v[112:115], v[176:179]
	ds_read_b128 v[108:111], v222 offset:55296
	s_waitcnt lgkmcnt(7)
	v_mfma_f32_16x16x32_bf16 v[180:183], v[84:87], v[116:119], v[180:183]
	ds_read_b128 v[68:71], v151 offset:2048
	s_waitcnt lgkmcnt(8)
	v_mfma_f32_16x16x32_bf16 v[184:187], v[84:87], v[120:123], v[184:187]
	ds_read_b128 v[72:75], v151 offset:4096
	s_waitcnt lgkmcnt(9)
	v_mfma_f32_16x16x32_bf16 v[188:191], v[84:87], v[124:127], v[188:191]
	ds_read_b128 v[76:79], v151 offset:6144
	s_waitcnt lgkmcnt(9)
	v_mfma_f32_16x16x32_bf16 v[192:195], v[88:91], v[112:115], v[192:195]
	s_waitcnt lgkmcnt(9)
	v_mfma_f32_16x16x32_bf16 v[196:199], v[88:91], v[116:119], v[196:199]
	s_waitcnt lgkmcnt(9)
	v_mfma_f32_16x16x32_bf16 v[200:203], v[88:91], v[120:123], v[200:203]
	s_waitcnt lgkmcnt(9)
	v_mfma_f32_16x16x32_bf16 v[204:207], v[88:91], v[124:127], v[204:207]
	s_waitcnt lgkmcnt(8)
	v_mfma_f32_16x16x32_bf16 v[208:211], v[92:95], v[112:115], v[208:211]
	s_waitcnt lgkmcnt(8)
	v_mfma_f32_16x16x32_bf16 v[212:215], v[92:95], v[116:119], v[212:215]
	s_waitcnt lgkmcnt(8)
	v_mfma_f32_16x16x32_bf16 v[216:219], v[92:95], v[120:123], v[216:219]
	s_waitcnt lgkmcnt(8)
	v_mfma_f32_16x16x32_bf16 v[230:233], v[92:95], v[124:127], v[230:233]
	s_waitcnt lgkmcnt(6)
	v_mfma_f32_16x16x32_bf16 v[0:3], v[64:67], v[96:99], v[0:3]
	ds_read_b128 v[80:83], v220 offset:0
	s_waitcnt lgkmcnt(6)
	v_mfma_f32_16x16x32_bf16 v[4:7], v[64:67], v[100:103], v[4:7]
	ds_read_b128 v[112:115], v224 offset:49152
	s_waitcnt lgkmcnt(6)
	v_mfma_f32_16x16x32_bf16 v[8:11], v[64:67], v[104:107], v[8:11]
	ds_read_b128 v[116:119], v224 offset:51200
	s_waitcnt lgkmcnt(6)
	v_mfma_f32_16x16x32_bf16 v[12:15], v[64:67], v[108:111], v[12:15]
	ds_read_b128 v[120:123], v224 offset:53248
	s_waitcnt lgkmcnt(6)
	v_mfma_f32_16x16x32_bf16 v[16:19], v[68:71], v[96:99], v[16:19]
	ds_read_b128 v[124:127], v224 offset:55296
	s_waitcnt lgkmcnt(7)
	v_mfma_f32_16x16x32_bf16 v[20:23], v[68:71], v[100:103], v[20:23]
	ds_read_b128 v[84:87], v220 offset:2048
	s_waitcnt lgkmcnt(8)
	v_mfma_f32_16x16x32_bf16 v[24:27], v[68:71], v[104:107], v[24:27]
	ds_read_b128 v[88:91], v220 offset:4096
	s_waitcnt lgkmcnt(9)
	v_mfma_f32_16x16x32_bf16 v[28:31], v[68:71], v[108:111], v[28:31]
	ds_read_b128 v[92:95], v220 offset:6144
	s_waitcnt lgkmcnt(9)
	v_mfma_f32_16x16x32_bf16 v[32:35], v[72:75], v[96:99], v[32:35]
	s_waitcnt lgkmcnt(9)
	v_mfma_f32_16x16x32_bf16 v[36:39], v[72:75], v[100:103], v[36:39]
	s_waitcnt lgkmcnt(9)
	v_mfma_f32_16x16x32_bf16 v[40:43], v[72:75], v[104:107], v[40:43]
	s_waitcnt lgkmcnt(9)
	v_mfma_f32_16x16x32_bf16 v[44:47], v[72:75], v[108:111], v[44:47]
	s_waitcnt vmcnt(4) lgkmcnt(0)
	s_barrier
	s_add_u32 m0, s38, 0
	s_nop 0
	global_load_lds_dwordx4 v226, s[98:99]
	s_waitcnt lgkmcnt(8)
	v_mfma_f32_16x16x32_bf16 v[48:51], v[76:79], v[96:99], v[48:51]
	s_add_u32 m0, s38, 4096
	s_nop 0
	global_load_lds_dwordx4 v228, s[98:99]
	s_waitcnt lgkmcnt(8)
	v_mfma_f32_16x16x32_bf16 v[52:55], v[76:79], v[100:103], v[52:55]
	s_add_u32 m0, s38, 8192
	s_nop 0
	global_load_lds_dwordx4 v244, s[98:99]
	s_waitcnt lgkmcnt(8)
	v_mfma_f32_16x16x32_bf16 v[56:59], v[76:79], v[104:107], v[56:59]
	s_add_u32 m0, s38, 12288
	s_nop 0
	global_load_lds_dwordx4 v245, s[98:99]
	s_add_u32 s98, s98, 128
	s_addc_u32 s99, s99, 0
	s_waitcnt lgkmcnt(8)
	v_mfma_f32_16x16x32_bf16 v[60:63], v[76:79], v[108:111], v[60:63]
	s_waitcnt lgkmcnt(6)
	v_mfma_f32_16x16x32_bf16 v[0:3], v[80:83], v[112:115], v[0:3]
	ds_read_b128 v[64:67], v151 offset:16384
	s_waitcnt lgkmcnt(6)
	v_mfma_f32_16x16x32_bf16 v[4:7], v[80:83], v[116:119], v[4:7]
	ds_read_b128 v[96:99], v222 offset:49152
	s_waitcnt lgkmcnt(6)
	v_mfma_f32_16x16x32_bf16 v[8:11], v[80:83], v[120:123], v[8:11]
	ds_read_b128 v[100:103], v222 offset:51200
	s_waitcnt lgkmcnt(6)
	v_mfma_f32_16x16x32_bf16 v[12:15], v[80:83], v[124:127], v[12:15]
	ds_read_b128 v[104:107], v222 offset:53248
	s_waitcnt lgkmcnt(6)
	v_mfma_f32_16x16x32_bf16 v[16:19], v[84:87], v[112:115], v[16:19]
	ds_read_b128 v[108:111], v222 offset:55296
	s_waitcnt lgkmcnt(7)
	v_mfma_f32_16x16x32_bf16 v[20:23], v[84:87], v[116:119], v[20:23]
	ds_read_b128 v[68:71], v151 offset:18432
	s_waitcnt lgkmcnt(8)
	v_mfma_f32_16x16x32_bf16 v[24:27], v[84:87], v[120:123], v[24:27]
	ds_read_b128 v[72:75], v151 offset:20480
	s_waitcnt lgkmcnt(9)
	v_mfma_f32_16x16x32_bf16 v[28:31], v[84:87], v[124:127], v[28:31]
	ds_read_b128 v[76:79], v151 offset:22528
	s_waitcnt lgkmcnt(9)
	v_mfma_f32_16x16x32_bf16 v[32:35], v[88:91], v[112:115], v[32:35]
	s_waitcnt lgkmcnt(9)
	v_mfma_f32_16x16x32_bf16 v[36:39], v[88:91], v[116:119], v[36:39]
	s_waitcnt lgkmcnt(9)
	v_mfma_f32_16x16x32_bf16 v[40:43], v[88:91], v[120:123], v[40:43]
	s_waitcnt lgkmcnt(9)
	v_mfma_f32_16x16x32_bf16 v[44:47], v[88:91], v[124:127], v[44:47]
	s_waitcnt lgkmcnt(8)
	v_mfma_f32_16x16x32_bf16 v[48:51], v[92:95], v[112:115], v[48:51]
	s_waitcnt lgkmcnt(8)
	v_mfma_f32_16x16x32_bf16 v[52:55], v[92:95], v[116:119], v[52:55]
	s_waitcnt lgkmcnt(8)
	v_mfma_f32_16x16x32_bf16 v[56:59], v[92:95], v[120:123], v[56:59]
	s_waitcnt lgkmcnt(8)
	v_mfma_f32_16x16x32_bf16 v[60:63], v[92:95], v[124:127], v[60:63]
	s_waitcnt lgkmcnt(6)
	v_mfma_f32_16x16x32_bf16 v[160:163], v[64:67], v[96:99], v[160:163]
	ds_read_b128 v[80:83], v220 offset:16384
	s_waitcnt lgkmcnt(6)
	v_mfma_f32_16x16x32_bf16 v[164:167], v[64:67], v[100:103], v[164:167]
	ds_read_b128 v[112:115], v224 offset:49152
	s_waitcnt lgkmcnt(6)
	v_mfma_f32_16x16x32_bf16 v[168:171], v[64:67], v[104:107], v[168:171]
	ds_read_b128 v[116:119], v224 offset:51200
	s_waitcnt lgkmcnt(6)
	v_mfma_f32_16x16x32_bf16 v[172:175], v[64:67], v[108:111], v[172:175]
	ds_read_b128 v[120:123], v224 offset:53248
	s_waitcnt lgkmcnt(6)
	v_mfma_f32_16x16x32_bf16 v[176:179], v[68:71], v[96:99], v[176:179]
	ds_read_b128 v[124:127], v224 offset:55296
	s_waitcnt lgkmcnt(7)
	v_mfma_f32_16x16x32_bf16 v[180:183], v[68:71], v[100:103], v[180:183]
	ds_read_b128 v[84:87], v220 offset:18432
	s_waitcnt lgkmcnt(8)
	v_mfma_f32_16x16x32_bf16 v[184:187], v[68:71], v[104:107], v[184:187]
	ds_read_b128 v[88:91], v220 offset:20480
	s_waitcnt lgkmcnt(9)
	v_mfma_f32_16x16x32_bf16 v[188:191], v[68:71], v[108:111], v[188:191]
	ds_read_b128 v[92:95], v220 offset:22528
	s_waitcnt lgkmcnt(9)
	v_mfma_f32_16x16x32_bf16 v[192:195], v[72:75], v[96:99], v[192:195]
	s_waitcnt lgkmcnt(9)
	v_mfma_f32_16x16x32_bf16 v[196:199], v[72:75], v[100:103], v[196:199]
	s_waitcnt lgkmcnt(9)
	v_mfma_f32_16x16x32_bf16 v[200:203], v[72:75], v[104:107], v[200:203]
	s_waitcnt lgkmcnt(9)
	v_mfma_f32_16x16x32_bf16 v[204:207], v[72:75], v[108:111], v[204:207]
	s_waitcnt vmcnt(0) lgkmcnt(0)
	s_barrier
	s_add_u32 m0, s38, 16384
	s_nop 0
	global_load_lds_dwordx4 v226, s[100:101]
	s_waitcnt lgkmcnt(8)
	v_mfma_f32_16x16x32_bf16 v[208:211], v[76:79], v[96:99], v[208:211]
	s_add_u32 m0, s38, 20480
	s_nop 0
	global_load_lds_dwordx4 v228, s[100:101]
	s_waitcnt lgkmcnt(8)
	v_mfma_f32_16x16x32_bf16 v[212:215], v[76:79], v[100:103], v[212:215]
	s_add_u32 m0, s38, 24576
	s_nop 0
	global_load_lds_dwordx4 v244, s[100:101]
	s_waitcnt lgkmcnt(8)
	v_mfma_f32_16x16x32_bf16 v[216:219], v[76:79], v[104:107], v[216:219]
	s_add_u32 m0, s38, 28672
	s_nop 0
	global_load_lds_dwordx4 v245, s[100:101]
	s_add_u32 s100, s100, 128
	s_addc_u32 s101, s101, 0
	s_waitcnt lgkmcnt(8)
	v_mfma_f32_16x16x32_bf16 v[230:233], v[76:79], v[108:111], v[230:233]
	s_add_u32 m0, s38, 49152
	s_nop 0
	global_load_lds_dwordx4 v226, s[4:5]
	s_waitcnt lgkmcnt(6)
	v_mfma_f32_16x16x32_bf16 v[160:163], v[80:83], v[112:115], v[160:163]
	ds_read_b128 v[64:67], v151 offset:0
	s_add_u32 m0, s38, 53248
	s_nop 0
	global_load_lds_dwordx4 v228, s[4:5]
	s_waitcnt lgkmcnt(6)
	v_mfma_f32_16x16x32_bf16 v[164:167], v[80:83], v[116:119], v[164:167]
	ds_read_b128 v[96:99], v222 offset:32768
	s_add_u32 m0, s38, 57344
	s_nop 0
	global_load_lds_dwordx4 v244, s[4:5]
	s_waitcnt lgkmcnt(6)
	v_mfma_f32_16x16x32_bf16 v[168:171], v[80:83], v[120:123], v[168:171]
	ds_read_b128 v[100:103], v222 offset:34816
	s_add_u32 m0, s38, 61440
	s_nop 0
	global_load_lds_dwordx4 v245, s[4:5]
	s_add_u32 s4, s4, 128
	s_addc_u32 s5, s5, 0
	s_waitcnt lgkmcnt(6)
	v_mfma_f32_16x16x32_bf16 v[172:175], v[80:83], v[124:127], v[172:175]
	ds_read_b128 v[104:107], v222 offset:36864
	s_waitcnt lgkmcnt(6)
	v_mfma_f32_16x16x32_bf16 v[176:179], v[84:87], v[112:115], v[176:179]
	ds_read_b128 v[108:111], v222 offset:38912
	s_waitcnt lgkmcnt(7)
	v_mfma_f32_16x16x32_bf16 v[180:183], v[84:87], v[116:119], v[180:183]
	ds_read_b128 v[68:71], v151 offset:2048
	s_waitcnt lgkmcnt(8)
	v_mfma_f32_16x16x32_bf16 v[184:187], v[84:87], v[120:123], v[184:187]
	ds_read_b128 v[72:75], v151 offset:4096
	s_waitcnt lgkmcnt(9)
	v_mfma_f32_16x16x32_bf16 v[188:191], v[84:87], v[124:127], v[188:191]
	ds_read_b128 v[76:79], v151 offset:6144
	s_waitcnt lgkmcnt(9)
	v_mfma_f32_16x16x32_bf16 v[192:195], v[88:91], v[112:115], v[192:195]
	s_waitcnt lgkmcnt(9)
	v_mfma_f32_16x16x32_bf16 v[196:199], v[88:91], v[116:119], v[196:199]
	s_waitcnt lgkmcnt(9)
	v_mfma_f32_16x16x32_bf16 v[200:203], v[88:91], v[120:123], v[200:203]
	s_waitcnt lgkmcnt(9)
	v_mfma_f32_16x16x32_bf16 v[204:207], v[88:91], v[124:127], v[204:207]
	s_waitcnt lgkmcnt(8)
	v_mfma_f32_16x16x32_bf16 v[208:211], v[92:95], v[112:115], v[208:211]
	s_waitcnt lgkmcnt(8)
	v_mfma_f32_16x16x32_bf16 v[212:215], v[92:95], v[116:119], v[212:215]
	s_waitcnt lgkmcnt(8)
	v_mfma_f32_16x16x32_bf16 v[216:219], v[92:95], v[120:123], v[216:219]
	s_waitcnt lgkmcnt(8)
	v_mfma_f32_16x16x32_bf16 v[230:233], v[92:95], v[124:127], v[230:233]
	s_waitcnt lgkmcnt(6)
	v_mfma_f32_16x16x32_bf16 v[0:3], v[64:67], v[96:99], v[0:3]
	ds_read_b128 v[80:83], v220 offset:0
	s_waitcnt lgkmcnt(6)
	v_mfma_f32_16x16x32_bf16 v[4:7], v[64:67], v[100:103], v[4:7]
	ds_read_b128 v[112:115], v224 offset:32768
	s_waitcnt lgkmcnt(6)
	v_mfma_f32_16x16x32_bf16 v[8:11], v[64:67], v[104:107], v[8:11]
	ds_read_b128 v[116:119], v224 offset:34816
	s_waitcnt lgkmcnt(6)
	v_mfma_f32_16x16x32_bf16 v[12:15], v[64:67], v[108:111], v[12:15]
	ds_read_b128 v[120:123], v224 offset:36864
	s_waitcnt lgkmcnt(6)
	v_mfma_f32_16x16x32_bf16 v[16:19], v[68:71], v[96:99], v[16:19]
	ds_read_b128 v[124:127], v224 offset:38912
	s_waitcnt lgkmcnt(7)
	v_mfma_f32_16x16x32_bf16 v[20:23], v[68:71], v[100:103], v[20:23]
	ds_read_b128 v[84:87], v220 offset:2048
	s_waitcnt lgkmcnt(8)
	v_mfma_f32_16x16x32_bf16 v[24:27], v[68:71], v[104:107], v[24:27]
	ds_read_b128 v[88:91], v220 offset:4096
	s_waitcnt lgkmcnt(9)
	v_mfma_f32_16x16x32_bf16 v[28:31], v[68:71], v[108:111], v[28:31]
	ds_read_b128 v[92:95], v220 offset:6144
	s_waitcnt lgkmcnt(9)
	v_mfma_f32_16x16x32_bf16 v[32:35], v[72:75], v[96:99], v[32:35]
	s_waitcnt lgkmcnt(9)
	v_mfma_f32_16x16x32_bf16 v[36:39], v[72:75], v[100:103], v[36:39]
	s_waitcnt lgkmcnt(9)
	v_mfma_f32_16x16x32_bf16 v[40:43], v[72:75], v[104:107], v[40:43]
	s_waitcnt lgkmcnt(9)
	v_mfma_f32_16x16x32_bf16 v[44:47], v[72:75], v[108:111], v[44:47]
	s_waitcnt vmcnt(4) lgkmcnt(0)
	s_barrier
	s_add_u32 m0, s38, 0
	s_nop 0
	global_load_lds_dwordx4 v226, s[98:99]
	s_waitcnt lgkmcnt(8)
	v_mfma_f32_16x16x32_bf16 v[48:51], v[76:79], v[96:99], v[48:51]
	s_add_u32 m0, s38, 4096
	s_nop 0
	global_load_lds_dwordx4 v228, s[98:99]
	s_waitcnt lgkmcnt(8)
	v_mfma_f32_16x16x32_bf16 v[52:55], v[76:79], v[100:103], v[52:55]
	s_add_u32 m0, s38, 8192
	s_nop 0
	global_load_lds_dwordx4 v244, s[98:99]
	s_waitcnt lgkmcnt(8)
	v_mfma_f32_16x16x32_bf16 v[56:59], v[76:79], v[104:107], v[56:59]
	s_add_u32 m0, s38, 12288
	s_nop 0
	global_load_lds_dwordx4 v245, s[98:99]
	s_add_u32 s98, s98, 128
	s_addc_u32 s99, s99, 0
	s_waitcnt lgkmcnt(8)
	v_mfma_f32_16x16x32_bf16 v[60:63], v[76:79], v[108:111], v[60:63]
	s_waitcnt lgkmcnt(6)
	v_mfma_f32_16x16x32_bf16 v[0:3], v[80:83], v[112:115], v[0:3]
	ds_read_b128 v[64:67], v151 offset:16384
	s_waitcnt lgkmcnt(6)
	v_mfma_f32_16x16x32_bf16 v[4:7], v[80:83], v[116:119], v[4:7]
	ds_read_b128 v[96:99], v222 offset:32768
	s_waitcnt lgkmcnt(6)
	v_mfma_f32_16x16x32_bf16 v[8:11], v[80:83], v[120:123], v[8:11]
	ds_read_b128 v[100:103], v222 offset:34816
	s_waitcnt lgkmcnt(6)
	v_mfma_f32_16x16x32_bf16 v[12:15], v[80:83], v[124:127], v[12:15]
	ds_read_b128 v[104:107], v222 offset:36864
	s_waitcnt lgkmcnt(6)
	v_mfma_f32_16x16x32_bf16 v[16:19], v[84:87], v[112:115], v[16:19]
	ds_read_b128 v[108:111], v222 offset:38912
	s_waitcnt lgkmcnt(7)
	v_mfma_f32_16x16x32_bf16 v[20:23], v[84:87], v[116:119], v[20:23]
	ds_read_b128 v[68:71], v151 offset:18432
	s_waitcnt lgkmcnt(8)
	v_mfma_f32_16x16x32_bf16 v[24:27], v[84:87], v[120:123], v[24:27]
	ds_read_b128 v[72:75], v151 offset:20480
	s_waitcnt lgkmcnt(9)
	v_mfma_f32_16x16x32_bf16 v[28:31], v[84:87], v[124:127], v[28:31]
	ds_read_b128 v[76:79], v151 offset:22528
	s_waitcnt lgkmcnt(9)
	v_mfma_f32_16x16x32_bf16 v[32:35], v[88:91], v[112:115], v[32:35]
	s_waitcnt lgkmcnt(9)
	v_mfma_f32_16x16x32_bf16 v[36:39], v[88:91], v[116:119], v[36:39]
	s_waitcnt lgkmcnt(9)
	v_mfma_f32_16x16x32_bf16 v[40:43], v[88:91], v[120:123], v[40:43]
	s_waitcnt lgkmcnt(9)
	v_mfma_f32_16x16x32_bf16 v[44:47], v[88:91], v[124:127], v[44:47]
	s_waitcnt lgkmcnt(8)
	v_mfma_f32_16x16x32_bf16 v[48:51], v[92:95], v[112:115], v[48:51]
	s_waitcnt lgkmcnt(8)
	v_mfma_f32_16x16x32_bf16 v[52:55], v[92:95], v[116:119], v[52:55]
	s_waitcnt lgkmcnt(8)
	v_mfma_f32_16x16x32_bf16 v[56:59], v[92:95], v[120:123], v[56:59]
	s_waitcnt lgkmcnt(8)
	v_mfma_f32_16x16x32_bf16 v[60:63], v[92:95], v[124:127], v[60:63]
	s_waitcnt lgkmcnt(6)
	v_mfma_f32_16x16x32_bf16 v[160:163], v[64:67], v[96:99], v[160:163]
	ds_read_b128 v[80:83], v220 offset:16384
	s_waitcnt lgkmcnt(6)
	v_mfma_f32_16x16x32_bf16 v[164:167], v[64:67], v[100:103], v[164:167]
	ds_read_b128 v[112:115], v224 offset:32768
	s_waitcnt lgkmcnt(6)
	v_mfma_f32_16x16x32_bf16 v[168:171], v[64:67], v[104:107], v[168:171]
	ds_read_b128 v[116:119], v224 offset:34816
	s_waitcnt lgkmcnt(6)
	v_mfma_f32_16x16x32_bf16 v[172:175], v[64:67], v[108:111], v[172:175]
	ds_read_b128 v[120:123], v224 offset:36864
	s_waitcnt lgkmcnt(6)
	v_mfma_f32_16x16x32_bf16 v[176:179], v[68:71], v[96:99], v[176:179]
	ds_read_b128 v[124:127], v224 offset:38912
	s_waitcnt lgkmcnt(7)
	v_mfma_f32_16x16x32_bf16 v[180:183], v[68:71], v[100:103], v[180:183]
	ds_read_b128 v[84:87], v220 offset:18432
	s_waitcnt lgkmcnt(8)
	v_mfma_f32_16x16x32_bf16 v[184:187], v[68:71], v[104:107], v[184:187]
	ds_read_b128 v[88:91], v220 offset:20480
	s_waitcnt lgkmcnt(9)
	v_mfma_f32_16x16x32_bf16 v[188:191], v[68:71], v[108:111], v[188:191]
	ds_read_b128 v[92:95], v220 offset:22528
	s_waitcnt lgkmcnt(9)
	v_mfma_f32_16x16x32_bf16 v[192:195], v[72:75], v[96:99], v[192:195]
	s_waitcnt lgkmcnt(9)
	v_mfma_f32_16x16x32_bf16 v[196:199], v[72:75], v[100:103], v[196:199]
	s_waitcnt lgkmcnt(9)
	v_mfma_f32_16x16x32_bf16 v[200:203], v[72:75], v[104:107], v[200:203]
	s_waitcnt lgkmcnt(9)
	v_mfma_f32_16x16x32_bf16 v[204:207], v[72:75], v[108:111], v[204:207]
	s_waitcnt vmcnt(0) lgkmcnt(0)
	s_barrier
	s_add_u32 m0, s38, 16384
	s_nop 0
	global_load_lds_dwordx4 v226, s[100:101]
	s_waitcnt lgkmcnt(8)
	v_mfma_f32_16x16x32_bf16 v[208:211], v[76:79], v[96:99], v[208:211]
	s_add_u32 m0, s38, 20480
	s_nop 0
	global_load_lds_dwordx4 v228, s[100:101]
	s_waitcnt lgkmcnt(8)
	v_mfma_f32_16x16x32_bf16 v[212:215], v[76:79], v[100:103], v[212:215]
	s_add_u32 m0, s38, 24576
	s_nop 0
	global_load_lds_dwordx4 v244, s[100:101]
	s_waitcnt lgkmcnt(8)
	v_mfma_f32_16x16x32_bf16 v[216:219], v[76:79], v[104:107], v[216:219]
	s_add_u32 m0, s38, 28672
	s_nop 0
	global_load_lds_dwordx4 v245, s[100:101]
	s_add_u32 s100, s100, 128
	s_addc_u32 s101, s101, 0
	s_waitcnt lgkmcnt(8)
	v_mfma_f32_16x16x32_bf16 v[230:233], v[76:79], v[108:111], v[230:233]
	s_add_u32 m0, s38, 32768
	s_nop 0
	global_load_lds_dwordx4 v226, s[4:5]
	s_waitcnt lgkmcnt(6)
	v_mfma_f32_16x16x32_bf16 v[160:163], v[80:83], v[112:115], v[160:163]
	ds_read_b128 v[64:67], v151 offset:0
	s_add_u32 m0, s38, 36864
	s_nop 0
	global_load_lds_dwordx4 v228, s[4:5]
	s_waitcnt lgkmcnt(6)
	v_mfma_f32_16x16x32_bf16 v[164:167], v[80:83], v[116:119], v[164:167]
	ds_read_b128 v[96:99], v222 offset:49152
	s_add_u32 m0, s38, 40960
	s_nop 0
	global_load_lds_dwordx4 v244, s[4:5]
	s_waitcnt lgkmcnt(6)
	v_mfma_f32_16x16x32_bf16 v[168:171], v[80:83], v[120:123], v[168:171]
	ds_read_b128 v[100:103], v222 offset:51200
	s_add_u32 m0, s38, 45056
	s_nop 0
	global_load_lds_dwordx4 v245, s[4:5]
	s_add_u32 s4, s4, 128
	s_addc_u32 s5, s5, 0
	s_waitcnt lgkmcnt(6)
	v_mfma_f32_16x16x32_bf16 v[172:175], v[80:83], v[124:127], v[172:175]
	ds_read_b128 v[104:107], v222 offset:53248
	s_waitcnt lgkmcnt(6)
	v_mfma_f32_16x16x32_bf16 v[176:179], v[84:87], v[112:115], v[176:179]
	ds_read_b128 v[108:111], v222 offset:55296
	s_waitcnt lgkmcnt(7)
	v_mfma_f32_16x16x32_bf16 v[180:183], v[84:87], v[116:119], v[180:183]
	ds_read_b128 v[68:71], v151 offset:2048
	s_waitcnt lgkmcnt(8)
	v_mfma_f32_16x16x32_bf16 v[184:187], v[84:87], v[120:123], v[184:187]
	ds_read_b128 v[72:75], v151 offset:4096
	s_waitcnt lgkmcnt(9)
	v_mfma_f32_16x16x32_bf16 v[188:191], v[84:87], v[124:127], v[188:191]
	ds_read_b128 v[76:79], v151 offset:6144
	s_waitcnt lgkmcnt(9)
	v_mfma_f32_16x16x32_bf16 v[192:195], v[88:91], v[112:115], v[192:195]
	s_waitcnt lgkmcnt(9)
	v_mfma_f32_16x16x32_bf16 v[196:199], v[88:91], v[116:119], v[196:199]
	s_waitcnt lgkmcnt(9)
	v_mfma_f32_16x16x32_bf16 v[200:203], v[88:91], v[120:123], v[200:203]
	s_waitcnt lgkmcnt(9)
	v_mfma_f32_16x16x32_bf16 v[204:207], v[88:91], v[124:127], v[204:207]
	s_waitcnt lgkmcnt(8)
	v_mfma_f32_16x16x32_bf16 v[208:211], v[92:95], v[112:115], v[208:211]
	s_waitcnt lgkmcnt(8)
	v_mfma_f32_16x16x32_bf16 v[212:215], v[92:95], v[116:119], v[212:215]
	s_waitcnt lgkmcnt(8)
	v_mfma_f32_16x16x32_bf16 v[216:219], v[92:95], v[120:123], v[216:219]
	s_waitcnt lgkmcnt(8)
	v_mfma_f32_16x16x32_bf16 v[230:233], v[92:95], v[124:127], v[230:233]
	s_waitcnt lgkmcnt(6)
	v_mfma_f32_16x16x32_bf16 v[0:3], v[64:67], v[96:99], v[0:3]
	ds_read_b128 v[80:83], v220 offset:0
	s_waitcnt lgkmcnt(6)
	v_mfma_f32_16x16x32_bf16 v[4:7], v[64:67], v[100:103], v[4:7]
	ds_read_b128 v[112:115], v224 offset:49152
	s_waitcnt lgkmcnt(6)
	v_mfma_f32_16x16x32_bf16 v[8:11], v[64:67], v[104:107], v[8:11]
	ds_read_b128 v[116:119], v224 offset:51200
	s_waitcnt lgkmcnt(6)
	v_mfma_f32_16x16x32_bf16 v[12:15], v[64:67], v[108:111], v[12:15]
	ds_read_b128 v[120:123], v224 offset:53248
	s_waitcnt lgkmcnt(6)
	v_mfma_f32_16x16x32_bf16 v[16:19], v[68:71], v[96:99], v[16:19]
	ds_read_b128 v[124:127], v224 offset:55296
	s_waitcnt lgkmcnt(7)
	v_mfma_f32_16x16x32_bf16 v[20:23], v[68:71], v[100:103], v[20:23]
	ds_read_b128 v[84:87], v220 offset:2048
	s_waitcnt lgkmcnt(8)
	v_mfma_f32_16x16x32_bf16 v[24:27], v[68:71], v[104:107], v[24:27]
	ds_read_b128 v[88:91], v220 offset:4096
	s_waitcnt lgkmcnt(9)
	v_mfma_f32_16x16x32_bf16 v[28:31], v[68:71], v[108:111], v[28:31]
	ds_read_b128 v[92:95], v220 offset:6144
	s_waitcnt lgkmcnt(9)
	v_mfma_f32_16x16x32_bf16 v[32:35], v[72:75], v[96:99], v[32:35]
	s_waitcnt lgkmcnt(9)
	v_mfma_f32_16x16x32_bf16 v[36:39], v[72:75], v[100:103], v[36:39]
	s_waitcnt lgkmcnt(9)
	v_mfma_f32_16x16x32_bf16 v[40:43], v[72:75], v[104:107], v[40:43]
	s_waitcnt lgkmcnt(9)
	v_mfma_f32_16x16x32_bf16 v[44:47], v[72:75], v[108:111], v[44:47]
	s_waitcnt vmcnt(4) lgkmcnt(0)
	s_barrier
	s_add_u32 m0, s38, 0
	s_nop 0
	global_load_lds_dwordx4 v226, s[98:99]
	s_waitcnt lgkmcnt(8)
	v_mfma_f32_16x16x32_bf16 v[48:51], v[76:79], v[96:99], v[48:51]
	s_add_u32 m0, s38, 4096
	s_nop 0
	global_load_lds_dwordx4 v228, s[98:99]
	s_waitcnt lgkmcnt(8)
	v_mfma_f32_16x16x32_bf16 v[52:55], v[76:79], v[100:103], v[52:55]
	s_add_u32 m0, s38, 8192
	s_nop 0
	global_load_lds_dwordx4 v244, s[98:99]
	s_waitcnt lgkmcnt(8)
	v_mfma_f32_16x16x32_bf16 v[56:59], v[76:79], v[104:107], v[56:59]
	s_add_u32 m0, s38, 12288
	s_nop 0
	global_load_lds_dwordx4 v245, s[98:99]
	s_add_u32 s98, s98, 128
	s_addc_u32 s99, s99, 0
	s_waitcnt lgkmcnt(8)
	v_mfma_f32_16x16x32_bf16 v[60:63], v[76:79], v[108:111], v[60:63]
	s_waitcnt lgkmcnt(6)
	v_mfma_f32_16x16x32_bf16 v[0:3], v[80:83], v[112:115], v[0:3]
	ds_read_b128 v[64:67], v151 offset:16384
	s_waitcnt lgkmcnt(6)
	v_mfma_f32_16x16x32_bf16 v[4:7], v[80:83], v[116:119], v[4:7]
	ds_read_b128 v[96:99], v222 offset:49152
	s_waitcnt lgkmcnt(6)
	v_mfma_f32_16x16x32_bf16 v[8:11], v[80:83], v[120:123], v[8:11]
	ds_read_b128 v[100:103], v222 offset:51200
	s_waitcnt lgkmcnt(6)
	v_mfma_f32_16x16x32_bf16 v[12:15], v[80:83], v[124:127], v[12:15]
	ds_read_b128 v[104:107], v222 offset:53248
	s_waitcnt lgkmcnt(6)
	v_mfma_f32_16x16x32_bf16 v[16:19], v[84:87], v[112:115], v[16:19]
	ds_read_b128 v[108:111], v222 offset:55296
	s_waitcnt lgkmcnt(7)
	v_mfma_f32_16x16x32_bf16 v[20:23], v[84:87], v[116:119], v[20:23]
	ds_read_b128 v[68:71], v151 offset:18432
	s_waitcnt lgkmcnt(8)
	v_mfma_f32_16x16x32_bf16 v[24:27], v[84:87], v[120:123], v[24:27]
	ds_read_b128 v[72:75], v151 offset:20480
	s_waitcnt lgkmcnt(9)
	v_mfma_f32_16x16x32_bf16 v[28:31], v[84:87], v[124:127], v[28:31]
	ds_read_b128 v[76:79], v151 offset:22528
	s_waitcnt lgkmcnt(9)
	v_mfma_f32_16x16x32_bf16 v[32:35], v[88:91], v[112:115], v[32:35]
	s_waitcnt lgkmcnt(9)
	v_mfma_f32_16x16x32_bf16 v[36:39], v[88:91], v[116:119], v[36:39]
	s_waitcnt lgkmcnt(9)
	v_mfma_f32_16x16x32_bf16 v[40:43], v[88:91], v[120:123], v[40:43]
	s_waitcnt lgkmcnt(9)
	v_mfma_f32_16x16x32_bf16 v[44:47], v[88:91], v[124:127], v[44:47]
	s_waitcnt lgkmcnt(8)
	v_mfma_f32_16x16x32_bf16 v[48:51], v[92:95], v[112:115], v[48:51]
	s_waitcnt lgkmcnt(8)
	v_mfma_f32_16x16x32_bf16 v[52:55], v[92:95], v[116:119], v[52:55]
	s_waitcnt lgkmcnt(8)
	v_mfma_f32_16x16x32_bf16 v[56:59], v[92:95], v[120:123], v[56:59]
	s_waitcnt lgkmcnt(8)
	v_mfma_f32_16x16x32_bf16 v[60:63], v[92:95], v[124:127], v[60:63]
	s_waitcnt lgkmcnt(6)
	v_mfma_f32_16x16x32_bf16 v[160:163], v[64:67], v[96:99], v[160:163]
	ds_read_b128 v[80:83], v220 offset:16384
	s_waitcnt lgkmcnt(6)
	v_mfma_f32_16x16x32_bf16 v[164:167], v[64:67], v[100:103], v[164:167]
	ds_read_b128 v[112:115], v224 offset:49152
	s_waitcnt lgkmcnt(6)
	v_mfma_f32_16x16x32_bf16 v[168:171], v[64:67], v[104:107], v[168:171]
	ds_read_b128 v[116:119], v224 offset:51200
	s_waitcnt lgkmcnt(6)
	v_mfma_f32_16x16x32_bf16 v[172:175], v[64:67], v[108:111], v[172:175]
	ds_read_b128 v[120:123], v224 offset:53248
	s_waitcnt lgkmcnt(6)
	v_mfma_f32_16x16x32_bf16 v[176:179], v[68:71], v[96:99], v[176:179]
	ds_read_b128 v[124:127], v224 offset:55296
	s_waitcnt lgkmcnt(7)
	v_mfma_f32_16x16x32_bf16 v[180:183], v[68:71], v[100:103], v[180:183]
	ds_read_b128 v[84:87], v220 offset:18432
	s_waitcnt lgkmcnt(8)
	v_mfma_f32_16x16x32_bf16 v[184:187], v[68:71], v[104:107], v[184:187]
	ds_read_b128 v[88:91], v220 offset:20480
	s_waitcnt lgkmcnt(9)
	v_mfma_f32_16x16x32_bf16 v[188:191], v[68:71], v[108:111], v[188:191]
	ds_read_b128 v[92:95], v220 offset:22528
	s_waitcnt lgkmcnt(9)
	v_mfma_f32_16x16x32_bf16 v[192:195], v[72:75], v[96:99], v[192:195]
	s_waitcnt lgkmcnt(9)
	v_mfma_f32_16x16x32_bf16 v[196:199], v[72:75], v[100:103], v[196:199]
	s_waitcnt lgkmcnt(9)
	v_mfma_f32_16x16x32_bf16 v[200:203], v[72:75], v[104:107], v[200:203]
	s_waitcnt lgkmcnt(9)
	v_mfma_f32_16x16x32_bf16 v[204:207], v[72:75], v[108:111], v[204:207]
	s_waitcnt vmcnt(0) lgkmcnt(0)
	s_barrier
	s_add_u32 m0, s38, 16384
	s_nop 0
	global_load_lds_dwordx4 v226, s[100:101]
	s_waitcnt lgkmcnt(8)
	v_mfma_f32_16x16x32_bf16 v[208:211], v[76:79], v[96:99], v[208:211]
	s_add_u32 m0, s38, 20480
	s_nop 0
	global_load_lds_dwordx4 v228, s[100:101]
	s_waitcnt lgkmcnt(8)
	v_mfma_f32_16x16x32_bf16 v[212:215], v[76:79], v[100:103], v[212:215]
	s_add_u32 m0, s38, 24576
	s_nop 0
	global_load_lds_dwordx4 v244, s[100:101]
	s_waitcnt lgkmcnt(8)
	v_mfma_f32_16x16x32_bf16 v[216:219], v[76:79], v[104:107], v[216:219]
	s_add_u32 m0, s38, 28672
	s_nop 0
	global_load_lds_dwordx4 v245, s[100:101]
	s_add_u32 s100, s100, 128
	s_addc_u32 s101, s101, 0
	s_waitcnt lgkmcnt(8)
	v_mfma_f32_16x16x32_bf16 v[230:233], v[76:79], v[108:111], v[230:233]
	s_add_u32 m0, s38, 49152
	s_nop 0
	global_load_lds_dwordx4 v226, s[4:5]
	s_waitcnt lgkmcnt(6)
	v_mfma_f32_16x16x32_bf16 v[160:163], v[80:83], v[112:115], v[160:163]
	ds_read_b128 v[64:67], v151 offset:0
	s_add_u32 m0, s38, 53248
	s_nop 0
	global_load_lds_dwordx4 v228, s[4:5]
	s_waitcnt lgkmcnt(6)
	v_mfma_f32_16x16x32_bf16 v[164:167], v[80:83], v[116:119], v[164:167]
	ds_read_b128 v[96:99], v222 offset:32768
	s_add_u32 m0, s38, 57344
	s_nop 0
	global_load_lds_dwordx4 v244, s[4:5]
	s_waitcnt lgkmcnt(6)
	v_mfma_f32_16x16x32_bf16 v[168:171], v[80:83], v[120:123], v[168:171]
	ds_read_b128 v[100:103], v222 offset:34816
	s_add_u32 m0, s38, 61440
	s_nop 0
	global_load_lds_dwordx4 v245, s[4:5]
	s_add_u32 s4, s4, 128
	s_addc_u32 s5, s5, 0
	s_waitcnt lgkmcnt(6)
	v_mfma_f32_16x16x32_bf16 v[172:175], v[80:83], v[124:127], v[172:175]
	ds_read_b128 v[104:107], v222 offset:36864
	s_waitcnt lgkmcnt(6)
	v_mfma_f32_16x16x32_bf16 v[176:179], v[84:87], v[112:115], v[176:179]
	ds_read_b128 v[108:111], v222 offset:38912
	s_waitcnt lgkmcnt(7)
	v_mfma_f32_16x16x32_bf16 v[180:183], v[84:87], v[116:119], v[180:183]
	ds_read_b128 v[68:71], v151 offset:2048
	s_waitcnt lgkmcnt(8)
	v_mfma_f32_16x16x32_bf16 v[184:187], v[84:87], v[120:123], v[184:187]
	ds_read_b128 v[72:75], v151 offset:4096
	s_waitcnt lgkmcnt(9)
	v_mfma_f32_16x16x32_bf16 v[188:191], v[84:87], v[124:127], v[188:191]
	ds_read_b128 v[76:79], v151 offset:6144
	s_waitcnt lgkmcnt(9)
	v_mfma_f32_16x16x32_bf16 v[192:195], v[88:91], v[112:115], v[192:195]
	s_waitcnt lgkmcnt(9)
	v_mfma_f32_16x16x32_bf16 v[196:199], v[88:91], v[116:119], v[196:199]
	s_waitcnt lgkmcnt(9)
	v_mfma_f32_16x16x32_bf16 v[200:203], v[88:91], v[120:123], v[200:203]
	s_waitcnt lgkmcnt(9)
	v_mfma_f32_16x16x32_bf16 v[204:207], v[88:91], v[124:127], v[204:207]
	s_waitcnt lgkmcnt(8)
	v_mfma_f32_16x16x32_bf16 v[208:211], v[92:95], v[112:115], v[208:211]
	s_waitcnt lgkmcnt(8)
	v_mfma_f32_16x16x32_bf16 v[212:215], v[92:95], v[116:119], v[212:215]
	s_waitcnt lgkmcnt(8)
	v_mfma_f32_16x16x32_bf16 v[216:219], v[92:95], v[120:123], v[216:219]
	s_waitcnt lgkmcnt(8)
	v_mfma_f32_16x16x32_bf16 v[230:233], v[92:95], v[124:127], v[230:233]
	s_waitcnt lgkmcnt(6)
	v_mfma_f32_16x16x32_bf16 v[0:3], v[64:67], v[96:99], v[0:3]
	ds_read_b128 v[80:83], v220 offset:0
	s_waitcnt lgkmcnt(6)
	v_mfma_f32_16x16x32_bf16 v[4:7], v[64:67], v[100:103], v[4:7]
	ds_read_b128 v[112:115], v224 offset:32768
	s_waitcnt lgkmcnt(6)
	v_mfma_f32_16x16x32_bf16 v[8:11], v[64:67], v[104:107], v[8:11]
	ds_read_b128 v[116:119], v224 offset:34816
	s_waitcnt lgkmcnt(6)
	v_mfma_f32_16x16x32_bf16 v[12:15], v[64:67], v[108:111], v[12:15]
	ds_read_b128 v[120:123], v224 offset:36864
	s_waitcnt lgkmcnt(6)
	v_mfma_f32_16x16x32_bf16 v[16:19], v[68:71], v[96:99], v[16:19]
	ds_read_b128 v[124:127], v224 offset:38912
	s_waitcnt lgkmcnt(7)
	v_mfma_f32_16x16x32_bf16 v[20:23], v[68:71], v[100:103], v[20:23]
	ds_read_b128 v[84:87], v220 offset:2048
	s_waitcnt lgkmcnt(8)
	v_mfma_f32_16x16x32_bf16 v[24:27], v[68:71], v[104:107], v[24:27]
	ds_read_b128 v[88:91], v220 offset:4096
	s_waitcnt lgkmcnt(9)
	v_mfma_f32_16x16x32_bf16 v[28:31], v[68:71], v[108:111], v[28:31]
	ds_read_b128 v[92:95], v220 offset:6144
	s_waitcnt lgkmcnt(9)
	v_mfma_f32_16x16x32_bf16 v[32:35], v[72:75], v[96:99], v[32:35]
	s_waitcnt lgkmcnt(9)
	v_mfma_f32_16x16x32_bf16 v[36:39], v[72:75], v[100:103], v[36:39]
	s_waitcnt lgkmcnt(9)
	v_mfma_f32_16x16x32_bf16 v[40:43], v[72:75], v[104:107], v[40:43]
	s_waitcnt lgkmcnt(9)
	v_mfma_f32_16x16x32_bf16 v[44:47], v[72:75], v[108:111], v[44:47]
	s_waitcnt vmcnt(4) lgkmcnt(0)
	s_barrier
	s_add_u32 m0, s38, 0
	s_nop 0
	global_load_lds_dwordx4 v226, s[98:99]
	s_waitcnt lgkmcnt(8)
	v_mfma_f32_16x16x32_bf16 v[48:51], v[76:79], v[96:99], v[48:51]
	s_add_u32 m0, s38, 4096
	s_nop 0
	global_load_lds_dwordx4 v228, s[98:99]
	s_waitcnt lgkmcnt(8)
	v_mfma_f32_16x16x32_bf16 v[52:55], v[76:79], v[100:103], v[52:55]
	s_add_u32 m0, s38, 8192
	s_nop 0
	global_load_lds_dwordx4 v244, s[98:99]
	s_waitcnt lgkmcnt(8)
	v_mfma_f32_16x16x32_bf16 v[56:59], v[76:79], v[104:107], v[56:59]
	s_add_u32 m0, s38, 12288
	s_nop 0
	global_load_lds_dwordx4 v245, s[98:99]
	s_add_u32 s98, s98, 128
	s_addc_u32 s99, s99, 0
	s_waitcnt lgkmcnt(8)
	v_mfma_f32_16x16x32_bf16 v[60:63], v[76:79], v[108:111], v[60:63]
	s_waitcnt lgkmcnt(6)
	v_mfma_f32_16x16x32_bf16 v[0:3], v[80:83], v[112:115], v[0:3]
	ds_read_b128 v[64:67], v151 offset:16384
	s_waitcnt lgkmcnt(6)
	v_mfma_f32_16x16x32_bf16 v[4:7], v[80:83], v[116:119], v[4:7]
	ds_read_b128 v[96:99], v222 offset:32768
	s_waitcnt lgkmcnt(6)
	v_mfma_f32_16x16x32_bf16 v[8:11], v[80:83], v[120:123], v[8:11]
	ds_read_b128 v[100:103], v222 offset:34816
	s_waitcnt lgkmcnt(6)
	v_mfma_f32_16x16x32_bf16 v[12:15], v[80:83], v[124:127], v[12:15]
	ds_read_b128 v[104:107], v222 offset:36864
	s_waitcnt lgkmcnt(6)
	v_mfma_f32_16x16x32_bf16 v[16:19], v[84:87], v[112:115], v[16:19]
	ds_read_b128 v[108:111], v222 offset:38912
	s_waitcnt lgkmcnt(7)
	v_mfma_f32_16x16x32_bf16 v[20:23], v[84:87], v[116:119], v[20:23]
	ds_read_b128 v[68:71], v151 offset:18432
	s_waitcnt lgkmcnt(8)
	v_mfma_f32_16x16x32_bf16 v[24:27], v[84:87], v[120:123], v[24:27]
	ds_read_b128 v[72:75], v151 offset:20480
	s_waitcnt lgkmcnt(9)
	v_mfma_f32_16x16x32_bf16 v[28:31], v[84:87], v[124:127], v[28:31]
	ds_read_b128 v[76:79], v151 offset:22528
	s_waitcnt lgkmcnt(9)
	v_mfma_f32_16x16x32_bf16 v[32:35], v[88:91], v[112:115], v[32:35]
	s_waitcnt lgkmcnt(9)
	v_mfma_f32_16x16x32_bf16 v[36:39], v[88:91], v[116:119], v[36:39]
	s_waitcnt lgkmcnt(9)
	v_mfma_f32_16x16x32_bf16 v[40:43], v[88:91], v[120:123], v[40:43]
	s_waitcnt lgkmcnt(9)
	v_mfma_f32_16x16x32_bf16 v[44:47], v[88:91], v[124:127], v[44:47]
	s_waitcnt lgkmcnt(8)
	v_mfma_f32_16x16x32_bf16 v[48:51], v[92:95], v[112:115], v[48:51]
	s_waitcnt lgkmcnt(8)
	v_mfma_f32_16x16x32_bf16 v[52:55], v[92:95], v[116:119], v[52:55]
	s_waitcnt lgkmcnt(8)
	v_mfma_f32_16x16x32_bf16 v[56:59], v[92:95], v[120:123], v[56:59]
	s_waitcnt lgkmcnt(8)
	v_mfma_f32_16x16x32_bf16 v[60:63], v[92:95], v[124:127], v[60:63]
	s_waitcnt lgkmcnt(6)
	v_mfma_f32_16x16x32_bf16 v[160:163], v[64:67], v[96:99], v[160:163]
	ds_read_b128 v[80:83], v220 offset:16384
	s_waitcnt lgkmcnt(6)
	v_mfma_f32_16x16x32_bf16 v[164:167], v[64:67], v[100:103], v[164:167]
	ds_read_b128 v[112:115], v224 offset:32768
	s_waitcnt lgkmcnt(6)
	v_mfma_f32_16x16x32_bf16 v[168:171], v[64:67], v[104:107], v[168:171]
	ds_read_b128 v[116:119], v224 offset:34816
	s_waitcnt lgkmcnt(6)
	v_mfma_f32_16x16x32_bf16 v[172:175], v[64:67], v[108:111], v[172:175]
	ds_read_b128 v[120:123], v224 offset:36864
	s_waitcnt lgkmcnt(6)
	v_mfma_f32_16x16x32_bf16 v[176:179], v[68:71], v[96:99], v[176:179]
	ds_read_b128 v[124:127], v224 offset:38912
	s_waitcnt lgkmcnt(7)
	v_mfma_f32_16x16x32_bf16 v[180:183], v[68:71], v[100:103], v[180:183]
	ds_read_b128 v[84:87], v220 offset:18432
	s_waitcnt lgkmcnt(8)
	v_mfma_f32_16x16x32_bf16 v[184:187], v[68:71], v[104:107], v[184:187]
	ds_read_b128 v[88:91], v220 offset:20480
	s_waitcnt lgkmcnt(9)
	v_mfma_f32_16x16x32_bf16 v[188:191], v[68:71], v[108:111], v[188:191]
	ds_read_b128 v[92:95], v220 offset:22528
	s_waitcnt lgkmcnt(9)
	v_mfma_f32_16x16x32_bf16 v[192:195], v[72:75], v[96:99], v[192:195]
	s_waitcnt lgkmcnt(9)
	v_mfma_f32_16x16x32_bf16 v[196:199], v[72:75], v[100:103], v[196:199]
	s_waitcnt lgkmcnt(9)
	v_mfma_f32_16x16x32_bf16 v[200:203], v[72:75], v[104:107], v[200:203]
	s_waitcnt lgkmcnt(9)
	v_mfma_f32_16x16x32_bf16 v[204:207], v[72:75], v[108:111], v[204:207]
	s_waitcnt vmcnt(0) lgkmcnt(0)
	s_barrier
	s_add_u32 m0, s38, 16384
	s_nop 0
	global_load_lds_dwordx4 v226, s[100:101]
	s_waitcnt lgkmcnt(8)
	v_mfma_f32_16x16x32_bf16 v[208:211], v[76:79], v[96:99], v[208:211]
	s_add_u32 m0, s38, 20480
	s_nop 0
	global_load_lds_dwordx4 v228, s[100:101]
	s_waitcnt lgkmcnt(8)
	v_mfma_f32_16x16x32_bf16 v[212:215], v[76:79], v[100:103], v[212:215]
	s_add_u32 m0, s38, 24576
	s_nop 0
	global_load_lds_dwordx4 v244, s[100:101]
	s_waitcnt lgkmcnt(8)
	v_mfma_f32_16x16x32_bf16 v[216:219], v[76:79], v[104:107], v[216:219]
	s_add_u32 m0, s38, 28672
	s_nop 0
	global_load_lds_dwordx4 v245, s[100:101]
	s_add_u32 s100, s100, 128
	s_addc_u32 s101, s101, 0
	s_waitcnt lgkmcnt(8)
	v_mfma_f32_16x16x32_bf16 v[230:233], v[76:79], v[108:111], v[230:233]
	s_waitcnt lgkmcnt(6)
	v_mfma_f32_16x16x32_bf16 v[160:163], v[80:83], v[112:115], v[160:163]
	ds_read_b128 v[64:67], v151 offset:0
	s_waitcnt lgkmcnt(6)
	v_mfma_f32_16x16x32_bf16 v[164:167], v[80:83], v[116:119], v[164:167]
	ds_read_b128 v[96:99], v222 offset:49152
	s_waitcnt lgkmcnt(6)
	v_mfma_f32_16x16x32_bf16 v[168:171], v[80:83], v[120:123], v[168:171]
	ds_read_b128 v[100:103], v222 offset:51200
	s_waitcnt lgkmcnt(6)
	v_mfma_f32_16x16x32_bf16 v[172:175], v[80:83], v[124:127], v[172:175]
	ds_read_b128 v[104:107], v222 offset:53248
	s_waitcnt lgkmcnt(6)
	v_mfma_f32_16x16x32_bf16 v[176:179], v[84:87], v[112:115], v[176:179]
	ds_read_b128 v[108:111], v222 offset:55296
	s_waitcnt lgkmcnt(7)
	v_mfma_f32_16x16x32_bf16 v[180:183], v[84:87], v[116:119], v[180:183]
	ds_read_b128 v[68:71], v151 offset:2048
	s_waitcnt lgkmcnt(8)
	v_mfma_f32_16x16x32_bf16 v[184:187], v[84:87], v[120:123], v[184:187]
	ds_read_b128 v[72:75], v151 offset:4096
	s_waitcnt lgkmcnt(9)
	v_mfma_f32_16x16x32_bf16 v[188:191], v[84:87], v[124:127], v[188:191]
	ds_read_b128 v[76:79], v151 offset:6144
	s_waitcnt lgkmcnt(9)
	v_mfma_f32_16x16x32_bf16 v[192:195], v[88:91], v[112:115], v[192:195]
	s_waitcnt lgkmcnt(9)
	v_mfma_f32_16x16x32_bf16 v[196:199], v[88:91], v[116:119], v[196:199]
	s_waitcnt lgkmcnt(9)
	v_mfma_f32_16x16x32_bf16 v[200:203], v[88:91], v[120:123], v[200:203]
	s_waitcnt lgkmcnt(9)
	v_mfma_f32_16x16x32_bf16 v[204:207], v[88:91], v[124:127], v[204:207]
	s_waitcnt lgkmcnt(8)
	v_mfma_f32_16x16x32_bf16 v[208:211], v[92:95], v[112:115], v[208:211]
	s_waitcnt lgkmcnt(8)
	v_mfma_f32_16x16x32_bf16 v[212:215], v[92:95], v[116:119], v[212:215]
	s_waitcnt lgkmcnt(8)
	v_mfma_f32_16x16x32_bf16 v[216:219], v[92:95], v[120:123], v[216:219]
	s_waitcnt lgkmcnt(8)
	v_mfma_f32_16x16x32_bf16 v[230:233], v[92:95], v[124:127], v[230:233]
	s_waitcnt lgkmcnt(6)
	v_mfma_f32_16x16x32_bf16 v[0:3], v[64:67], v[96:99], v[0:3]
	ds_read_b128 v[80:83], v220 offset:0
	s_waitcnt lgkmcnt(6)
	v_mfma_f32_16x16x32_bf16 v[4:7], v[64:67], v[100:103], v[4:7]
	ds_read_b128 v[112:115], v224 offset:49152
	s_waitcnt lgkmcnt(6)
	v_mfma_f32_16x16x32_bf16 v[8:11], v[64:67], v[104:107], v[8:11]
	ds_read_b128 v[116:119], v224 offset:51200
	s_waitcnt lgkmcnt(6)
	v_mfma_f32_16x16x32_bf16 v[12:15], v[64:67], v[108:111], v[12:15]
	ds_read_b128 v[120:123], v224 offset:53248
	s_waitcnt lgkmcnt(6)
	v_mfma_f32_16x16x32_bf16 v[16:19], v[68:71], v[96:99], v[16:19]
	ds_read_b128 v[124:127], v224 offset:55296
	s_waitcnt lgkmcnt(7)
	v_mfma_f32_16x16x32_bf16 v[20:23], v[68:71], v[100:103], v[20:23]
	ds_read_b128 v[84:87], v220 offset:2048
	s_waitcnt lgkmcnt(8)
	v_mfma_f32_16x16x32_bf16 v[24:27], v[68:71], v[104:107], v[24:27]
	ds_read_b128 v[88:91], v220 offset:4096
	s_waitcnt lgkmcnt(9)
	v_mfma_f32_16x16x32_bf16 v[28:31], v[68:71], v[108:111], v[28:31]
	ds_read_b128 v[92:95], v220 offset:6144
	s_waitcnt lgkmcnt(9)
	v_mfma_f32_16x16x32_bf16 v[32:35], v[72:75], v[96:99], v[32:35]
	s_waitcnt lgkmcnt(9)
	v_mfma_f32_16x16x32_bf16 v[36:39], v[72:75], v[100:103], v[36:39]
	s_waitcnt lgkmcnt(9)
	v_mfma_f32_16x16x32_bf16 v[40:43], v[72:75], v[104:107], v[40:43]
	s_waitcnt lgkmcnt(9)
	v_mfma_f32_16x16x32_bf16 v[44:47], v[72:75], v[108:111], v[44:47]
	s_waitcnt vmcnt(0) lgkmcnt(0)
	s_barrier
	s_waitcnt lgkmcnt(8)
	v_mfma_f32_16x16x32_bf16 v[48:51], v[76:79], v[96:99], v[48:51]
	s_waitcnt lgkmcnt(8)
	v_mfma_f32_16x16x32_bf16 v[52:55], v[76:79], v[100:103], v[52:55]
	s_waitcnt lgkmcnt(8)
	v_mfma_f32_16x16x32_bf16 v[56:59], v[76:79], v[104:107], v[56:59]
	s_waitcnt lgkmcnt(8)
	v_mfma_f32_16x16x32_bf16 v[60:63], v[76:79], v[108:111], v[60:63]
	s_waitcnt lgkmcnt(6)
	v_mfma_f32_16x16x32_bf16 v[0:3], v[80:83], v[112:115], v[0:3]
	ds_read_b128 v[64:67], v151 offset:16384
	s_waitcnt lgkmcnt(6)
	v_mfma_f32_16x16x32_bf16 v[4:7], v[80:83], v[116:119], v[4:7]
	ds_read_b128 v[96:99], v222 offset:49152
	s_waitcnt lgkmcnt(6)
	v_mfma_f32_16x16x32_bf16 v[8:11], v[80:83], v[120:123], v[8:11]
	ds_read_b128 v[100:103], v222 offset:51200
	s_waitcnt lgkmcnt(6)
	v_mfma_f32_16x16x32_bf16 v[12:15], v[80:83], v[124:127], v[12:15]
	ds_read_b128 v[104:107], v222 offset:53248
	s_waitcnt lgkmcnt(6)
	v_mfma_f32_16x16x32_bf16 v[16:19], v[84:87], v[112:115], v[16:19]
	ds_read_b128 v[108:111], v222 offset:55296
	s_waitcnt lgkmcnt(7)
	v_mfma_f32_16x16x32_bf16 v[20:23], v[84:87], v[116:119], v[20:23]
	ds_read_b128 v[68:71], v151 offset:18432
	s_waitcnt lgkmcnt(8)
	v_mfma_f32_16x16x32_bf16 v[24:27], v[84:87], v[120:123], v[24:27]
	ds_read_b128 v[72:75], v151 offset:20480
	s_waitcnt lgkmcnt(9)
	v_mfma_f32_16x16x32_bf16 v[28:31], v[84:87], v[124:127], v[28:31]
	ds_read_b128 v[76:79], v151 offset:22528
	s_waitcnt lgkmcnt(9)
	v_mfma_f32_16x16x32_bf16 v[32:35], v[88:91], v[112:115], v[32:35]
	s_waitcnt lgkmcnt(9)
	v_mfma_f32_16x16x32_bf16 v[36:39], v[88:91], v[116:119], v[36:39]
	s_waitcnt lgkmcnt(9)
	v_mfma_f32_16x16x32_bf16 v[40:43], v[88:91], v[120:123], v[40:43]
	s_waitcnt lgkmcnt(9)
	v_mfma_f32_16x16x32_bf16 v[44:47], v[88:91], v[124:127], v[44:47]
	s_waitcnt lgkmcnt(8)
	v_mfma_f32_16x16x32_bf16 v[48:51], v[92:95], v[112:115], v[48:51]
	s_waitcnt lgkmcnt(8)
	v_mfma_f32_16x16x32_bf16 v[52:55], v[92:95], v[116:119], v[52:55]
	s_waitcnt lgkmcnt(8)
	v_mfma_f32_16x16x32_bf16 v[56:59], v[92:95], v[120:123], v[56:59]
	s_waitcnt lgkmcnt(8)
	v_mfma_f32_16x16x32_bf16 v[60:63], v[92:95], v[124:127], v[60:63]
	s_waitcnt lgkmcnt(6)
	v_mfma_f32_16x16x32_bf16 v[160:163], v[64:67], v[96:99], v[160:163]
	ds_read_b128 v[80:83], v220 offset:16384
	s_waitcnt lgkmcnt(6)
	v_mfma_f32_16x16x32_bf16 v[164:167], v[64:67], v[100:103], v[164:167]
	ds_read_b128 v[112:115], v224 offset:49152
	s_waitcnt lgkmcnt(6)
	v_mfma_f32_16x16x32_bf16 v[168:171], v[64:67], v[104:107], v[168:171]
	ds_read_b128 v[116:119], v224 offset:51200
	s_waitcnt lgkmcnt(6)
	v_mfma_f32_16x16x32_bf16 v[172:175], v[64:67], v[108:111], v[172:175]
	ds_read_b128 v[120:123], v224 offset:53248
	s_waitcnt lgkmcnt(6)
	v_mfma_f32_16x16x32_bf16 v[176:179], v[68:71], v[96:99], v[176:179]
	ds_read_b128 v[124:127], v224 offset:55296
	s_waitcnt lgkmcnt(7)
	v_mfma_f32_16x16x32_bf16 v[180:183], v[68:71], v[100:103], v[180:183]
	ds_read_b128 v[84:87], v220 offset:18432
	s_waitcnt lgkmcnt(8)
	v_mfma_f32_16x16x32_bf16 v[184:187], v[68:71], v[104:107], v[184:187]
	ds_read_b128 v[88:91], v220 offset:20480
	s_waitcnt lgkmcnt(9)
	v_mfma_f32_16x16x32_bf16 v[188:191], v[68:71], v[108:111], v[188:191]
	ds_read_b128 v[92:95], v220 offset:22528
	s_waitcnt lgkmcnt(9)
	v_mfma_f32_16x16x32_bf16 v[192:195], v[72:75], v[96:99], v[192:195]
	s_waitcnt lgkmcnt(9)
	v_mfma_f32_16x16x32_bf16 v[196:199], v[72:75], v[100:103], v[196:199]
	s_waitcnt lgkmcnt(9)
	v_mfma_f32_16x16x32_bf16 v[200:203], v[72:75], v[104:107], v[200:203]
	s_waitcnt lgkmcnt(9)
	v_mfma_f32_16x16x32_bf16 v[204:207], v[72:75], v[108:111], v[204:207]
	s_waitcnt lgkmcnt(8)
	v_mfma_f32_16x16x32_bf16 v[208:211], v[76:79], v[96:99], v[208:211]
	s_waitcnt lgkmcnt(8)
	v_mfma_f32_16x16x32_bf16 v[212:215], v[76:79], v[100:103], v[212:215]
	s_waitcnt lgkmcnt(8)
	v_mfma_f32_16x16x32_bf16 v[216:219], v[76:79], v[104:107], v[216:219]
	s_waitcnt lgkmcnt(8)
	v_mfma_f32_16x16x32_bf16 v[230:233], v[76:79], v[108:111], v[230:233]
	s_waitcnt lgkmcnt(6)
	v_mfma_f32_16x16x32_bf16 v[160:163], v[80:83], v[112:115], v[160:163]
	s_waitcnt lgkmcnt(5)
	v_mfma_f32_16x16x32_bf16 v[164:167], v[80:83], v[116:119], v[164:167]
	s_waitcnt lgkmcnt(4)
	v_mfma_f32_16x16x32_bf16 v[168:171], v[80:83], v[120:123], v[168:171]
	s_waitcnt lgkmcnt(3)
	v_mfma_f32_16x16x32_bf16 v[172:175], v[80:83], v[124:127], v[172:175]
	s_waitcnt lgkmcnt(2)
	v_mfma_f32_16x16x32_bf16 v[176:179], v[84:87], v[112:115], v[176:179]
	s_waitcnt lgkmcnt(2)
	v_mfma_f32_16x16x32_bf16 v[180:183], v[84:87], v[116:119], v[180:183]
	s_waitcnt lgkmcnt(2)
	v_mfma_f32_16x16x32_bf16 v[184:187], v[84:87], v[120:123], v[184:187]
	s_waitcnt lgkmcnt(2)
	v_mfma_f32_16x16x32_bf16 v[188:191], v[84:87], v[124:127], v[188:191]
	s_waitcnt lgkmcnt(1)
	v_mfma_f32_16x16x32_bf16 v[192:195], v[88:91], v[112:115], v[192:195]
	s_waitcnt lgkmcnt(1)
	v_mfma_f32_16x16x32_bf16 v[196:199], v[88:91], v[116:119], v[196:199]
	s_waitcnt lgkmcnt(1)
	v_mfma_f32_16x16x32_bf16 v[200:203], v[88:91], v[120:123], v[200:203]
	s_waitcnt lgkmcnt(1)
	v_mfma_f32_16x16x32_bf16 v[204:207], v[88:91], v[124:127], v[204:207]
	s_waitcnt lgkmcnt(0)
	v_mfma_f32_16x16x32_bf16 v[208:211], v[92:95], v[112:115], v[208:211]
	s_waitcnt lgkmcnt(0)
	v_mfma_f32_16x16x32_bf16 v[212:215], v[92:95], v[116:119], v[212:215]
	s_waitcnt lgkmcnt(0)
	v_mfma_f32_16x16x32_bf16 v[216:219], v[92:95], v[120:123], v[216:219]
	s_waitcnt lgkmcnt(0)
	v_mfma_f32_16x16x32_bf16 v[230:233], v[92:95], v[124:127], v[230:233]
	s_add_u32 s14, s10, 0x0
	s_addc_u32 s15, s11, 0
	global_load_dwordx4 v[64:67], v150, s[14:15] nt
	global_load_dwordx4 v[68:71], v150, s[14:15] offset:16 nt
	s_add_u32 s14, s14, 0x8000
	s_addc_u32 s15, s15, 0
	global_load_dwordx4 v[72:75], v150, s[14:15] nt
	global_load_dwordx4 v[76:79], v150, s[14:15] offset:16 nt
	s_add_u32 s14, s14, 0x8000
	s_addc_u32 s15, s15, 0
	global_load_dwordx4 v[80:83], v150, s[14:15] nt
	global_load_dwordx4 v[84:87], v150, s[14:15] offset:16 nt
	s_add_u32 s14, s14, 0x8000
	s_addc_u32 s15, s15, 0
	global_load_dwordx4 v[88:91], v150, s[14:15] nt
	global_load_dwordx4 v[92:95], v150, s[14:15] offset:16 nt
	s_add_u32 s14, s10, 0x20000
	s_addc_u32 s15, s11, 0
	global_load_dwordx4 v[96:99], v150, s[14:15] nt
	global_load_dwordx4 v[100:103], v150, s[14:15] offset:16 nt
	s_add_u32 s14, s14, 0x8000
	s_addc_u32 s15, s15, 0
	global_load_dwordx4 v[104:107], v150, s[14:15] nt
	global_load_dwordx4 v[108:111], v150, s[14:15] offset:16 nt
	s_add_u32 s14, s14, 0x8000
	s_addc_u32 s15, s15, 0
	global_load_dwordx4 v[112:115], v150, s[14:15] nt
	global_load_dwordx4 v[116:119], v150, s[14:15] offset:16 nt
	s_add_u32 s14, s14, 0x8000
	s_addc_u32 s15, s15, 0
	global_load_dwordx4 v[120:123], v150, s[14:15] nt
	global_load_dwordx4 v[124:127], v150, s[14:15] offset:16 nt
	s_nop 7
	s_waitcnt lgkmcnt(0)
	s_barrier
	s_add_u32 s18, s12, 0x0
	s_addc_u32 s19, s13, 0
	ds_write_b32 v248, v0 offset:0
	ds_write_b32 v248, v1 offset:256
	ds_write_b32 v248, v2 offset:512
	ds_write_b32 v248, v3 offset:768
	ds_write_b32 v249, v4 offset:0
	ds_write_b32 v249, v5 offset:256
	ds_write_b32 v249, v6 offset:512
	ds_write_b32 v249, v7 offset:768
	ds_write_b32 v250, v8 offset:0
	ds_write_b32 v250, v9 offset:256
	ds_write_b32 v250, v10 offset:512
	ds_write_b32 v250, v11 offset:768
	ds_write_b32 v251, v12 offset:0
	ds_write_b32 v251, v13 offset:256
	ds_write_b32 v251, v14 offset:512
	ds_write_b32 v251, v15 offset:768
	ds_write_b32 v248, v16 offset:4096
	ds_write_b32 v248, v17 offset:4352
	ds_write_b32 v248, v18 offset:4608
	ds_write_b32 v248, v19 offset:4864
	ds_write_b32 v249, v20 offset:4096
	ds_write_b32 v249, v21 offset:4352
	ds_write_b32 v249, v22 offset:4608
	ds_write_b32 v249, v23 offset:4864
	ds_write_b32 v250, v24 offset:4096
	ds_write_b32 v250, v25 offset:4352
	ds_write_b32 v250, v26 offset:4608
	ds_write_b32 v250, v27 offset:4864
	ds_write_b32 v251, v28 offset:4096
	ds_write_b32 v251, v29 offset:4352
	ds_write_b32 v251, v30 offset:4608
	ds_write_b32 v251, v31 offset:4864
	s_waitcnt lgkmcnt(0)
	ds_read_b128 v[0:3], v252
	ds_read_b128 v[4:7], v252 offset:16
	ds_read_b128 v[8:11], v253
	ds_read_b128 v[12:15], v253 offset:16
	ds_read_b128 v[16:19], v254
	ds_read_b128 v[20:23], v254 offset:16
	ds_read_b128 v[24:27], v255
	ds_read_b128 v[28:31], v255 offset:16
	s_waitcnt vmcnt(14) lgkmcnt(6)
	v_pk_fma_f32 v[0:1], v[142:143], v[0:1], v[64:65]
	v_pk_fma_f32 v[2:3], v[144:145], v[2:3], v[66:67]
	v_pk_fma_f32 v[4:5], v[146:147], v[4:5], v[68:69]
	v_pk_fma_f32 v[6:7], v[234:235], v[6:7], v[70:71]
	global_store_dwordx4 v150, v[0:3], s[18:19]
	global_store_dwordx4 v150, v[4:7], s[18:19] offset:16
	s_add_u32 s18, s18, 0x8000
	s_addc_u32 s19, s19, 0
	s_waitcnt vmcnt(14) lgkmcnt(4)
	v_pk_fma_f32 v[8:9], v[142:143], v[8:9], v[72:73]
	v_pk_fma_f32 v[10:11], v[144:145], v[10:11], v[74:75]
	v_pk_fma_f32 v[12:13], v[146:147], v[12:13], v[76:77]
	v_pk_fma_f32 v[14:15], v[234:235], v[14:15], v[78:79]
	global_store_dwordx4 v150, v[8:11], s[18:19]
	global_store_dwordx4 v150, v[12:15], s[18:19] offset:16
	s_add_u32 s18, s18, 0x8000
	s_addc_u32 s19, s19, 0
	s_waitcnt vmcnt(14) lgkmcnt(2)
	v_pk_fma_f32 v[16:17], v[142:143], v[16:17], v[80:81]
	v_pk_fma_f32 v[18:19], v[144:145], v[18:19], v[82:83]
	v_pk_fma_f32 v[20:21], v[146:147], v[20:21], v[84:85]
	v_pk_fma_f32 v[22:23], v[234:235], v[22:23], v[86:87]
	global_store_dwordx4 v150, v[16:19], s[18:19]
	global_store_dwordx4 v150, v[20:23], s[18:19] offset:16
	s_add_u32 s18, s18, 0x8000
	s_addc_u32 s19, s19, 0
	s_waitcnt vmcnt(14) lgkmcnt(0)
	v_pk_fma_f32 v[24:25], v[142:143], v[24:25], v[88:89]
	v_pk_fma_f32 v[26:27], v[144:145], v[26:27], v[90:91]
	v_pk_fma_f32 v[28:29], v[146:147], v[28:29], v[92:93]
	v_pk_fma_f32 v[30:31], v[234:235], v[30:31], v[94:95]
	global_store_dwordx4 v150, v[24:27], s[18:19]
	global_store_dwordx4 v150, v[28:31], s[18:19] offset:16
	s_add_u32 s18, s18, 0x8000
	s_addc_u32 s19, s19, 0
	s_add_u32 s14, s10, 0x2000000
	s_addc_u32 s15, s11, 0
	global_load_dwordx4 v[64:67], v150, s[14:15] nt
	global_load_dwordx4 v[68:71], v150, s[14:15] offset:16 nt
	s_add_u32 s14, s14, 0x8000
	s_addc_u32 s15, s15, 0
	global_load_dwordx4 v[72:75], v150, s[14:15] nt
	global_load_dwordx4 v[76:79], v150, s[14:15] offset:16 nt
	s_add_u32 s14, s14, 0x8000
	s_addc_u32 s15, s15, 0
	global_load_dwordx4 v[80:83], v150, s[14:15] nt
	global_load_dwordx4 v[84:87], v150, s[14:15] offset:16 nt
	s_add_u32 s14, s14, 0x8000
	s_addc_u32 s15, s15, 0
	global_load_dwordx4 v[88:91], v150, s[14:15] nt
	global_load_dwordx4 v[92:95], v150, s[14:15] offset:16 nt
	ds_write_b32 v248, v32 offset:0
	ds_write_b32 v248, v33 offset:256
	ds_write_b32 v248, v34 offset:512
	ds_write_b32 v248, v35 offset:768
	ds_write_b32 v249, v36 offset:0
	ds_write_b32 v249, v37 offset:256
	ds_write_b32 v249, v38 offset:512
	ds_write_b32 v249, v39 offset:768
	ds_write_b32 v250, v40 offset:0
	ds_write_b32 v250, v41 offset:256
	ds_write_b32 v250, v42 offset:512
	ds_write_b32 v250, v43 offset:768
	ds_write_b32 v251, v44 offset:0
	ds_write_b32 v251, v45 offset:256
	ds_write_b32 v251, v46 offset:512
	ds_write_b32 v251, v47 offset:768
	ds_write_b32 v248, v48 offset:4096
	ds_write_b32 v248, v49 offset:4352
	ds_write_b32 v248, v50 offset:4608
	ds_write_b32 v248, v51 offset:4864
	ds_write_b32 v249, v52 offset:4096
	ds_write_b32 v249, v53 offset:4352
	ds_write_b32 v249, v54 offset:4608
	ds_write_b32 v249, v55 offset:4864
	ds_write_b32 v250, v56 offset:4096
	ds_write_b32 v250, v57 offset:4352
	ds_write_b32 v250, v58 offset:4608
	ds_write_b32 v250, v59 offset:4864
	ds_write_b32 v251, v60 offset:4096
	ds_write_b32 v251, v61 offset:4352
	ds_write_b32 v251, v62 offset:4608
	ds_write_b32 v251, v63 offset:4864
	s_waitcnt lgkmcnt(0)
	ds_read_b128 v[32:35], v252
	ds_read_b128 v[36:39], v252 offset:16
	ds_read_b128 v[40:43], v253
	ds_read_b128 v[44:47], v253 offset:16
	ds_read_b128 v[48:51], v254
	ds_read_b128 v[52:55], v254 offset:16
	ds_read_b128 v[56:59], v255
	ds_read_b128 v[60:63], v255 offset:16
	s_waitcnt vmcnt(22) lgkmcnt(6)
	v_pk_fma_f32 v[32:33], v[142:143], v[32:33], v[96:97]
	v_pk_fma_f32 v[34:35], v[144:145], v[34:35], v[98:99]
	v_pk_fma_f32 v[36:37], v[146:147], v[36:37], v[100:101]
	v_pk_fma_f32 v[38:39], v[234:235], v[38:39], v[102:103]
	global_store_dwordx4 v150, v[32:35], s[18:19]
	global_store_dwordx4 v150, v[36:39], s[18:19] offset:16
	s_add_u32 s18, s18, 0x8000
	s_addc_u32 s19, s19, 0
	s_waitcnt vmcnt(22) lgkmcnt(4)
	v_pk_fma_f32 v[40:41], v[142:143], v[40:41], v[104:105]
	v_pk_fma_f32 v[42:43], v[144:145], v[42:43], v[106:107]
	v_pk_fma_f32 v[44:45], v[146:147], v[44:45], v[108:109]
	v_pk_fma_f32 v[46:47], v[234:235], v[46:47], v[110:111]
	global_store_dwordx4 v150, v[40:43], s[18:19]
	global_store_dwordx4 v150, v[44:47], s[18:19] offset:16
	s_add_u32 s18, s18, 0x8000
	s_addc_u32 s19, s19, 0
	s_waitcnt vmcnt(22) lgkmcnt(2)
	v_pk_fma_f32 v[48:49], v[142:143], v[48:49], v[112:113]
	v_pk_fma_f32 v[50:51], v[144:145], v[50:51], v[114:115]
	v_pk_fma_f32 v[52:53], v[146:147], v[52:53], v[116:117]
	v_pk_fma_f32 v[54:55], v[234:235], v[54:55], v[118:119]
	global_store_dwordx4 v150, v[48:51], s[18:19]
	global_store_dwordx4 v150, v[52:55], s[18:19] offset:16
	s_add_u32 s18, s18, 0x8000
	s_addc_u32 s19, s19, 0
	s_waitcnt vmcnt(22) lgkmcnt(0)
	v_pk_fma_f32 v[56:57], v[142:143], v[56:57], v[120:121]
	v_pk_fma_f32 v[58:59], v[144:145], v[58:59], v[122:123]
	v_pk_fma_f32 v[60:61], v[146:147], v[60:61], v[124:125]
	v_pk_fma_f32 v[62:63], v[234:235], v[62:63], v[126:127]
	global_store_dwordx4 v150, v[56:59], s[18:19]
	global_store_dwordx4 v150, v[60:63], s[18:19] offset:16
	s_add_u32 s18, s18, 0x8000
	s_addc_u32 s19, s19, 0
	s_add_u32 s14, s10, 0x2020000
	s_addc_u32 s15, s11, 0
	global_load_dwordx4 v[96:99], v150, s[14:15] nt
	global_load_dwordx4 v[100:103], v150, s[14:15] offset:16 nt
	s_add_u32 s14, s14, 0x8000
	s_addc_u32 s15, s15, 0
	global_load_dwordx4 v[104:107], v150, s[14:15] nt
	global_load_dwordx4 v[108:111], v150, s[14:15] offset:16 nt
	s_add_u32 s14, s14, 0x8000
	s_addc_u32 s15, s15, 0
	global_load_dwordx4 v[112:115], v150, s[14:15] nt
	global_load_dwordx4 v[116:119], v150, s[14:15] offset:16 nt
	s_add_u32 s14, s14, 0x8000
	s_addc_u32 s15, s15, 0
	global_load_dwordx4 v[120:123], v150, s[14:15] nt
	global_load_dwordx4 v[124:127], v150, s[14:15] offset:16 nt
	s_add_u32 s18, s12, 0x2000000
	s_addc_u32 s19, s13, 0
	ds_write_b32 v248, v160 offset:0
	ds_write_b32 v248, v161 offset:256
	ds_write_b32 v248, v162 offset:512
	ds_write_b32 v248, v163 offset:768
	ds_write_b32 v249, v164 offset:0
	ds_write_b32 v249, v165 offset:256
	ds_write_b32 v249, v166 offset:512
	ds_write_b32 v249, v167 offset:768
	ds_write_b32 v250, v168 offset:0
	ds_write_b32 v250, v169 offset:256
	ds_write_b32 v250, v170 offset:512
	ds_write_b32 v250, v171 offset:768
	ds_write_b32 v251, v172 offset:0
	ds_write_b32 v251, v173 offset:256
	ds_write_b32 v251, v174 offset:512
	ds_write_b32 v251, v175 offset:768
	ds_write_b32 v248, v176 offset:4096
	ds_write_b32 v248, v177 offset:4352
	ds_write_b32 v248, v178 offset:4608
	ds_write_b32 v248, v179 offset:4864
	ds_write_b32 v249, v180 offset:4096
	ds_write_b32 v249, v181 offset:4352
	ds_write_b32 v249, v182 offset:4608
	ds_write_b32 v249, v183 offset:4864
	ds_write_b32 v250, v184 offset:4096
	ds_write_b32 v250, v185 offset:4352
	ds_write_b32 v250, v186 offset:4608
	ds_write_b32 v250, v187 offset:4864
	ds_write_b32 v251, v188 offset:4096
	ds_write_b32 v251, v189 offset:4352
	ds_write_b32 v251, v190 offset:4608
	ds_write_b32 v251, v191 offset:4864
	s_waitcnt lgkmcnt(0)
	ds_read_b128 v[160:163], v252
	ds_read_b128 v[164:167], v252 offset:16
	ds_read_b128 v[168:171], v253
	ds_read_b128 v[172:175], v253 offset:16
	ds_read_b128 v[176:179], v254
	ds_read_b128 v[180:183], v254 offset:16
	ds_read_b128 v[184:187], v255
	ds_read_b128 v[188:191], v255 offset:16
	s_waitcnt vmcnt(22) lgkmcnt(6)
	v_pk_fma_f32 v[160:161], v[236:237], v[160:161], v[64:65]
	v_pk_fma_f32 v[162:163], v[238:239], v[162:163], v[66:67]
	v_pk_fma_f32 v[164:165], v[240:241], v[164:165], v[68:69]
	v_pk_fma_f32 v[166:167], v[242:243], v[166:167], v[70:71]
	global_store_dwordx4 v150, v[160:163], s[18:19]
	global_store_dwordx4 v150, v[164:167], s[18:19] offset:16
	s_add_u32 s18, s18, 0x8000
	s_addc_u32 s19, s19, 0
	s_waitcnt vmcnt(22) lgkmcnt(4)
	v_pk_fma_f32 v[168:169], v[236:237], v[168:169], v[72:73]
	v_pk_fma_f32 v[170:171], v[238:239], v[170:171], v[74:75]
	v_pk_fma_f32 v[172:173], v[240:241], v[172:173], v[76:77]
	v_pk_fma_f32 v[174:175], v[242:243], v[174:175], v[78:79]
	global_store_dwordx4 v150, v[168:171], s[18:19]
	global_store_dwordx4 v150, v[172:175], s[18:19] offset:16
	s_add_u32 s18, s18, 0x8000
	s_addc_u32 s19, s19, 0
	s_waitcnt vmcnt(22) lgkmcnt(2)
	v_pk_fma_f32 v[176:177], v[236:237], v[176:177], v[80:81]
	v_pk_fma_f32 v[178:179], v[238:239], v[178:179], v[82:83]
	v_pk_fma_f32 v[180:181], v[240:241], v[180:181], v[84:85]
	v_pk_fma_f32 v[182:183], v[242:243], v[182:183], v[86:87]
	global_store_dwordx4 v150, v[176:179], s[18:19]
	global_store_dwordx4 v150, v[180:183], s[18:19] offset:16
	s_add_u32 s18, s18, 0x8000
	s_addc_u32 s19, s19, 0
	s_waitcnt vmcnt(22) lgkmcnt(0)
	v_pk_fma_f32 v[184:185], v[236:237], v[184:185], v[88:89]
	v_pk_fma_f32 v[186:187], v[238:239], v[186:187], v[90:91]
	v_pk_fma_f32 v[188:189], v[240:241], v[188:189], v[92:93]
	v_pk_fma_f32 v[190:191], v[242:243], v[190:191], v[94:95]
	global_store_dwordx4 v150, v[184:187], s[18:19]
	global_store_dwordx4 v150, v[188:191], s[18:19] offset:16
	s_add_u32 s18, s18, 0x8000
	s_addc_u32 s19, s19, 0
	ds_write_b32 v248, v192 offset:0
	ds_write_b32 v248, v193 offset:256
	ds_write_b32 v248, v194 offset:512
	ds_write_b32 v248, v195 offset:768
	ds_write_b32 v249, v196 offset:0
	ds_write_b32 v249, v197 offset:256
	ds_write_b32 v249, v198 offset:512
	ds_write_b32 v249, v199 offset:768
	ds_write_b32 v250, v200 offset:0
	ds_write_b32 v250, v201 offset:256
	ds_write_b32 v250, v202 offset:512
	ds_write_b32 v250, v203 offset:768
	ds_write_b32 v251, v204 offset:0
	ds_write_b32 v251, v205 offset:256
	ds_write_b32 v251, v206 offset:512
	ds_write_b32 v251, v207 offset:768
	ds_write_b32 v248, v208 offset:4096
	ds_write_b32 v248, v209 offset:4352
	ds_write_b32 v248, v210 offset:4608
	ds_write_b32 v248, v211 offset:4864
	ds_write_b32 v249, v212 offset:4096
	ds_write_b32 v249, v213 offset:4352
	ds_write_b32 v249, v214 offset:4608
	ds_write_b32 v249, v215 offset:4864
	ds_write_b32 v250, v216 offset:4096
	ds_write_b32 v250, v217 offset:4352
	ds_write_b32 v250, v218 offset:4608
	ds_write_b32 v250, v219 offset:4864
	ds_write_b32 v251, v230 offset:4096
	ds_write_b32 v251, v231 offset:4352
	ds_write_b32 v251, v232 offset:4608
	ds_write_b32 v251, v233 offset:4864
	s_waitcnt lgkmcnt(0)
	ds_read_b128 v[192:195], v252
	ds_read_b128 v[196:199], v252 offset:16
	ds_read_b128 v[200:203], v253
	ds_read_b128 v[204:207], v253 offset:16
	ds_read_b128 v[208:211], v254
	ds_read_b128 v[212:215], v254 offset:16
	ds_read_b128 v[216:219], v255
	ds_read_b128 v[230:233], v255 offset:16
	s_waitcnt vmcnt(14) lgkmcnt(6)
	v_pk_fma_f32 v[192:193], v[236:237], v[192:193], v[96:97]
	v_pk_fma_f32 v[194:195], v[238:239], v[194:195], v[98:99]
	v_pk_fma_f32 v[196:197], v[240:241], v[196:197], v[100:101]
	v_pk_fma_f32 v[198:199], v[242:243], v[198:199], v[102:103]
	global_store_dwordx4 v150, v[192:195], s[18:19]
	global_store_dwordx4 v150, v[196:199], s[18:19] offset:16
	s_add_u32 s18, s18, 0x8000
	s_addc_u32 s19, s19, 0
	s_waitcnt vmcnt(14) lgkmcnt(4)
	v_pk_fma_f32 v[200:201], v[236:237], v[200:201], v[104:105]
	v_pk_fma_f32 v[202:203], v[238:239], v[202:203], v[106:107]
	v_pk_fma_f32 v[204:205], v[240:241], v[204:205], v[108:109]
	v_pk_fma_f32 v[206:207], v[242:243], v[206:207], v[110:111]
	global_store_dwordx4 v150, v[200:203], s[18:19]
	global_store_dwordx4 v150, v[204:207], s[18:19] offset:16
	s_add_u32 s18, s18, 0x8000
	s_addc_u32 s19, s19, 0
	s_waitcnt vmcnt(14) lgkmcnt(2)
	v_pk_fma_f32 v[208:209], v[236:237], v[208:209], v[112:113]
	v_pk_fma_f32 v[210:211], v[238:239], v[210:211], v[114:115]
	v_pk_fma_f32 v[212:213], v[240:241], v[212:213], v[116:117]
	v_pk_fma_f32 v[214:215], v[242:243], v[214:215], v[118:119]
	global_store_dwordx4 v150, v[208:211], s[18:19]
	global_store_dwordx4 v150, v[212:215], s[18:19] offset:16
	s_add_u32 s18, s18, 0x8000
	s_addc_u32 s19, s19, 0
	s_waitcnt vmcnt(14) lgkmcnt(0)
	v_pk_fma_f32 v[216:217], v[236:237], v[216:217], v[120:121]
	v_pk_fma_f32 v[218:219], v[238:239], v[218:219], v[122:123]
	v_pk_fma_f32 v[230:231], v[240:241], v[230:231], v[124:125]
	v_pk_fma_f32 v[232:233], v[242:243], v[232:233], v[126:127]
	global_store_dwordx4 v150, v[216:219], s[18:19]
	global_store_dwordx4 v150, v[230:233], s[18:19] offset:16
	s_add_u32 s18, s18, 0x8000
	s_addc_u32 s19, s19, 0
	s_add_i32 s52, s52, s3
	s_cmpk_lt_i32 s52, 0x200
	s_cbranch_scc1 .Lmy_op0_tile
.Lmy_op0_end:
.LBB0_318:
	s_waitcnt vmcnt(0)
	s_barrier
	s_mov_b64 s[0:1], exec
	v_readlane_b32 s4, v247, 1
	v_readlane_b32 s5, v247, 2
	s_and_b64 s[4:5], s[0:1], s[4:5]
	s_mov_b64 exec, s[4:5]
	s_cbranch_execz .LBB0_370
	s_mov_b64 s[4:5], src_shared_base
	v_mov_b32_e32 v0, 0x10010
	v_mov_b32_e32 v1, s5
	s_waitcnt vmcnt(0) expcnt(0) lgkmcnt(0)
	flat_load_dword v2, v[0:1] sc0 sc1
	s_waitcnt vmcnt(0)
	v_mov_b32_e32 v0, 0x10014
	flat_load_dword v0, v[0:1] sc0 sc1
	s_waitcnt vmcnt(0) lgkmcnt(0)
	v_cmp_eq_u32_e32 vcc, 0, v2
	s_and_saveexec_b64 s[4:5], vcc
	s_cbranch_execz .LBB0_334
	s_add_u32 s6, s50, 0x1180200
	s_addc_u32 s7, s51, 0
	s_add_u32 s8, s50, 0x1180400
	s_addc_u32 s9, s51, 0
	s_add_u32 s10, s50, 0x1180500
	s_addc_u32 s11, s51, 0
	s_add_u32 s12, s50, 0x1180600
	s_addc_u32 s13, s51, 0
	s_add_u32 s14, s50, 0x1180700
	s_addc_u32 s15, s51, 0
	s_add_u32 s18, s50, 0x1180800
	s_addc_u32 s19, s51, 0
	s_add_u32 s20, s50, 0x1180900
	s_addc_u32 s21, s51, 0
	s_add_u32 s22, s50, 0x1180a00
	s_addc_u32 s23, s51, 0
	s_add_u32 s24, s50, 0x1180b00
	s_addc_u32 s25, s51, 0
	s_add_u32 s28, s50, 0x1180c00
	s_addc_u32 s29, s51, 0
	s_add_u32 s30, s50, 0x1180d00
	s_addc_u32 s31, s51, 0
	s_add_u32 s34, s50, 0x1180e00
	s_addc_u32 s35, s51, 0
	s_add_u32 s38, s50, 0x1180f00
	s_addc_u32 s39, s51, 0
	s_add_u32 s46, s50, 0x1181000
	s_addc_u32 s47, s51, 0
	s_add_u32 s52, s50, 0x1181100
	s_addc_u32 s53, s51, 0
	s_add_u32 s54, s50, 0x1181200
	s_addc_u32 s55, s51, 0
	s_add_u32 s56, s50, 0x1181300
	s_addc_u32 s57, s51, 0
	s_mov_b32 s33, 1
	v_mov_b32_e32 v16, 0
	s_branch .LBB0_322

.LBB0_684:
	s_or_b64 exec, exec, s[0:1]
	s_and_b64 vcc, exec, s[54:55]
	s_waitcnt lgkmcnt(0)
	s_barrier
	s_cbranch_vccnz .LBB0_689
	v_lshrrev_b32_e32 v141, 4, v129
	v_and_b32_e32 v64, 15, v141
	v_bfe_u32 v65, v141, 4, 2
	v_bfe_u32 v66, v141, 1, 3
	v_xor_b32_e32 v66, v65, v66
	v_lshlrev_b32_e32 v66, 4, v66
	v_lshl_or_b32 v67, v64, 7, v66
	v_bfe_u32 v68, v141, 7, 1
	v_bfe_u32 v69, v141, 6, 1
	v_lshl_add_u32 v151, v68, 13, v67
	v_xor_b32_e32 v220, 64, v151
	v_lshl_add_u32 v222, v69, 13, v67
	v_xor_b32_e32 v224, 64, v222
	v_bfe_u32 v70, v141, 4, 3
	v_and_b32_e32 v71, 7, v141
	v_xor_b32_e32 v70, v70, v71
	v_lshlrev_b32_e32 v70, 4, v70
	v_lshrrev_b32_e32 v72, 3, v141
	v_lshl_or_b32 v226, v72, 12, v70
	v_add_u32_e32 v228, 131072, v226
	v_add_u32_e32 v244, 262144, v226
	v_add_u32_e32 v245, 393216, v226
	v_bfe_u32 v73, v141, 3, 3
	v_lshlrev_b32_e32 v74, 8, v69
	v_lshl_add_u32 v148, v71, 5, v74
	v_lshl_add_u32 v74, v68, 6, v73
	v_lshl_add_u32 v150, v74, 12, v148
	v_lshrrev_b32_e32 v74, 6, v141
	v_lshlrev_b32_e32 v74, 13, v74
	v_lshl_add_u32 v75, v65, 10, v74
	v_add_u32_e32 v76, 0, v65
	v_and_b32_e32 v76, 3, v76
	v_lshl_add_u32 v76, v76, 4, v64
	v_lshl_add_u32 v248, v76, 2, v75
	v_add_u32_e32 v76, 1, v65
	v_and_b32_e32 v76, 3, v76
	v_lshl_add_u32 v76, v76, 4, v64
	v_lshl_add_u32 v249, v76, 2, v75
	v_add_u32_e32 v76, 2, v65
	v_and_b32_e32 v76, 3, v76
	v_lshl_add_u32 v76, v76, 4, v64
	v_lshl_add_u32 v250, v76, 2, v75
	v_add_u32_e32 v76, 3, v65
	v_and_b32_e32 v76, 3, v76
	v_lshl_add_u32 v76, v76, 4, v64
	v_lshl_add_u32 v251, v76, 2, v75
	v_lshl_add_u32 v75, v73, 8, v74
	v_lshrrev_b32_e32 v77, 2, v73
	v_lshlrev_b32_e32 v78, 3, v71
	v_add_u32_e32 v76, 0, v77
	v_and_b32_e32 v76, 3, v76
	v_lshl_add_u32 v76, v76, 4, v78
	v_and_b32_e32 v76, 63, v76
	v_lshl_add_u32 v252, v76, 2, v75
	v_add_u32_e32 v76, 2, v77
	v_and_b32_e32 v76, 3, v76
	v_lshl_add_u32 v76, v76, 4, v78
	v_and_b32_e32 v76, 63, v76
	v_lshl_add_u32 v253, v76, 2, v75
	v_add_u32_e32 v253, 2048, v253
	v_add_u32_e32 v76, 4, v77
	v_and_b32_e32 v76, 3, v76
	v_lshl_add_u32 v76, v76, 4, v78
	v_and_b32_e32 v76, 63, v76
	v_lshl_add_u32 v254, v76, 2, v75
	v_add_u32_e32 v254, 4096, v254
	v_add_u32_e32 v76, 6, v77
	v_and_b32_e32 v76, 3, v76
	v_lshl_add_u32 v76, v76, 4, v78
	v_and_b32_e32 v76, 63, v76
	v_lshl_add_u32 v255, v76, 2, v75
	v_add_u32_e32 v255, 6144, v255
	v_readfirstlane_b32 s38, v129
	s_mov_b32 s52, s2
	s_cmpk_ge_i32 s52, 0x200
	s_cbranch_scc1 .Lmy_op1_end
.Lmy_op1_tile:
	s_and_b32 s20, s52, 7
	s_lshl_b32 s20, s20, 3
	s_bfe_u32 s21, s52, 0x30003
	s_or_b32 s22, s20, s21
	s_bfe_u32 s23, s52, 0x30006
	s_lshl_b32 s20, s22, 19
	s_add_u32 s98, s50, s20
	s_addc_u32 s99, s51, 0
	s_add_u32 s98, s98, 0x5a00000
	s_addc_u32 s99, s99, 0
	s_add_u32 s100, s98, 0x2000000
	s_addc_u32 s101, s99, 0
	s_lshl_b32 s21, s23, 19
	s_add_u32 s4, s50, s21
	s_addc_u32 s5, s51, 0
	s_add_u32 s4, s4, 0xc00000
	s_addc_u32 s5, s5, 0
	s_lshr_b32 s21, s22, 5
	s_mul_i32 s21, s21, 0x3000
	s_lshl_b32 s24, s23, 9
	s_add_i32 s21, s21, s24
	s_add_i32 s21, s21, 0x1122000
	s_add_u32 s6, s50, s21
	s_addc_u32 s7, s51, 0
	s_add_u32 s8, s6, 0x6000
	s_addc_u32 s9, s7, 0
	s_add_i32 s20, s20, s24
	s_add_u32 s10, s48, s20
	s_addc_u32 s11, s49, 0
	s_add_u32 s12, s48, s20
	s_addc_u32 s13, s49, 0
	global_load_dwordx4 v[0:3], v148, s[6:7]
	global_load_dwordx4 v[4:7], v148, s[6:7] offset:16
	s_add_u32 s6, s6, 0xc000
	s_addc_u32 s7, s7, 0
	global_load_dwordx4 v[8:11], v148, s[6:7]
	global_load_dwordx4 v[12:15], v148, s[6:7] offset:16
	s_add_u32 s6, s6, 0xc000
	s_addc_u32 s7, s7, 0
	global_load_dwordx4 v[16:19], v148, s[6:7]
	global_load_dwordx4 v[20:23], v148, s[6:7] offset:16
	s_add_u32 s6, s6, 0xc000
	s_addc_u32 s7, s7, 0
	global_load_dwordx4 v[24:27], v148, s[6:7]
	global_load_dwordx4 v[28:31], v148, s[6:7] offset:16
	s_add_u32 s6, s6, 0xc000
	s_addc_u32 s7, s7, 0
	global_load_dwordx4 v[32:35], v148, s[6:7]
	global_load_dwordx4 v[36:39], v148, s[6:7] offset:16
	s_add_u32 s6, s6, 0xc000
	s_addc_u32 s7, s7, 0
	global_load_dwordx4 v[40:43], v148, s[6:7]
	global_load_dwordx4 v[44:47], v148, s[6:7] offset:16
	s_add_u32 s6, s6, 0xc000
	s_addc_u32 s7, s7, 0
	global_load_dwordx4 v[48:51], v148, s[6:7]
	global_load_dwordx4 v[52:55], v148, s[6:7] offset:16
	s_add_u32 s6, s6, 0xc000
	s_addc_u32 s7, s7, 0
	global_load_dwordx4 v[56:59], v148, s[6:7]
	global_load_dwordx4 v[60:63], v148, s[6:7] offset:16
	global_load_dwordx4 v[160:163], v148, s[8:9]
	global_load_dwordx4 v[164:167], v148, s[8:9] offset:16
	s_add_u32 s8, s8, 0xc000
	s_addc_u32 s9, s9, 0
	global_load_dwordx4 v[168:171], v148, s[8:9]
	global_load_dwordx4 v[172:175], v148, s[8:9] offset:16
	s_add_u32 s8, s8, 0xc000
	s_addc_u32 s9, s9, 0
	global_load_dwordx4 v[176:179], v148, s[8:9]
	global_load_dwordx4 v[180:183], v148, s[8:9] offset:16
	s_add_u32 s8, s8, 0xc000
	s_addc_u32 s9, s9, 0
	global_load_dwordx4 v[184:187], v148, s[8:9]
	global_load_dwordx4 v[188:191], v148, s[8:9] offset:16
	s_add_u32 s8, s8, 0xc000
	s_addc_u32 s9, s9, 0
	global_load_dwordx4 v[192:195], v148, s[8:9]
	global_load_dwordx4 v[196:199], v148, s[8:9] offset:16
	s_add_u32 s8, s8, 0xc000
	s_addc_u32 s9, s9, 0
	global_load_dwordx4 v[200:203], v148, s[8:9]
	global_load_dwordx4 v[204:207], v148, s[8:9] offset:16
	s_add_u32 s8, s8, 0xc000
	s_addc_u32 s9, s9, 0
	global_load_dwordx4 v[208:211], v148, s[8:9]
	global_load_dwordx4 v[212:215], v148, s[8:9] offset:16
	s_add_u32 s8, s8, 0xc000
	s_addc_u32 s9, s9, 0
	global_load_dwordx4 v[216:219], v148, s[8:9]
	global_load_dwordx4 v[230:233], v148, s[8:9] offset:16
	s_barrier
	s_add_u32 m0, s38, 32768
	s_nop 0
	global_load_lds_dwordx4 v226, s[4:5]
	s_add_u32 m0, s38, 36864
	s_nop 0
	global_load_lds_dwordx4 v228, s[4:5]
	s_add_u32 m0, s38, 40960
	s_nop 0
	global_load_lds_dwordx4 v244, s[4:5]
	s_add_u32 m0, s38, 45056
	s_nop 0
	global_load_lds_dwordx4 v245, s[4:5]
	s_add_u32 s4, s4, 128
	s_addc_u32 s5, s5, 0
	s_add_u32 m0, s38, 0
	s_nop 0
	global_load_lds_dwordx4 v226, s[98:99]
	s_add_u32 m0, s38, 4096
	s_nop 0
	global_load_lds_dwordx4 v228, s[98:99]
	s_add_u32 m0, s38, 8192
	s_nop 0
	global_load_lds_dwordx4 v244, s[98:99]
	s_add_u32 m0, s38, 12288
	s_nop 0
	global_load_lds_dwordx4 v245, s[98:99]
	s_add_u32 s98, s98, 128
	s_addc_u32 s99, s99, 0
	s_add_u32 m0, s38, 16384
	s_nop 0
	global_load_lds_dwordx4 v226, s[100:101]
	s_add_u32 m0, s38, 20480
	s_nop 0
	global_load_lds_dwordx4 v228, s[100:101]
	s_add_u32 m0, s38, 24576
	s_nop 0
	global_load_lds_dwordx4 v244, s[100:101]
	s_add_u32 m0, s38, 28672
	s_nop 0
	global_load_lds_dwordx4 v245, s[100:101]
	s_add_u32 s100, s100, 128
	s_addc_u32 s101, s101, 0
	s_add_u32 m0, s38, 49152
	s_nop 0
	global_load_lds_dwordx4 v226, s[4:5]
	s_add_u32 m0, s38, 53248
	s_nop 0
	global_load_lds_dwordx4 v228, s[4:5]
	s_add_u32 m0, s38, 57344
	s_nop 0
	global_load_lds_dwordx4 v244, s[4:5]
	s_add_u32 m0, s38, 61440
	s_nop 0
	global_load_lds_dwordx4 v245, s[4:5]
	s_add_u32 s4, s4, 128
	s_addc_u32 s5, s5, 0
	s_waitcnt vmcnt(16)
	v_add_f32_e32 v142, 0, v0
	v_add_f32_e32 v143, 0, v1
	v_add_f32_e32 v144, 0, v2
	v_add_f32_e32 v145, 0, v3
	v_add_f32_e32 v146, 0, v4
	v_add_f32_e32 v147, 0, v5
	v_add_f32_e32 v234, 0, v6
	v_add_f32_e32 v235, 0, v7
	v_add_f32_e32 v142, v142, v8
	v_add_f32_e32 v143, v143, v9
	v_add_f32_e32 v144, v144, v10
	v_add_f32_e32 v145, v145, v11
	v_add_f32_e32 v146, v146, v12
	v_add_f32_e32 v147, v147, v13
	v_add_f32_e32 v234, v234, v14
	v_add_f32_e32 v235, v235, v15
	v_add_f32_e32 v142, v142, v16
	v_add_f32_e32 v143, v143, v17
	v_add_f32_e32 v144, v144, v18
	v_add_f32_e32 v145, v145, v19
	v_add_f32_e32 v146, v146, v20
	v_add_f32_e32 v147, v147, v21
	v_add_f32_e32 v234, v234, v22
	v_add_f32_e32 v235, v235, v23
	v_add_f32_e32 v142, v142, v24
	v_add_f32_e32 v143, v143, v25
	v_add_f32_e32 v144, v144, v26
	v_add_f32_e32 v145, v145, v27
	v_add_f32_e32 v146, v146, v28
	v_add_f32_e32 v147, v147, v29
	v_add_f32_e32 v234, v234, v30
	v_add_f32_e32 v235, v235, v31
	v_add_f32_e32 v142, v142, v32
	v_add_f32_e32 v143, v143, v33
	v_add_f32_e32 v144, v144, v34
	v_add_f32_e32 v145, v145, v35
	v_add_f32_e32 v146, v146, v36
	v_add_f32_e32 v147, v147, v37
	v_add_f32_e32 v234, v234, v38
	v_add_f32_e32 v235, v235, v39
	v_add_f32_e32 v142, v142, v40
	v_add_f32_e32 v143, v143, v41
	v_add_f32_e32 v144, v144, v42
	v_add_f32_e32 v145, v145, v43
	v_add_f32_e32 v146, v146, v44
	v_add_f32_e32 v147, v147, v45
	v_add_f32_e32 v234, v234, v46
	v_add_f32_e32 v235, v235, v47
	v_add_f32_e32 v142, v142, v48
	v_add_f32_e32 v143, v143, v49
	v_add_f32_e32 v144, v144, v50
	v_add_f32_e32 v145, v145, v51
	v_add_f32_e32 v146, v146, v52
	v_add_f32_e32 v147, v147, v53
	v_add_f32_e32 v234, v234, v54
	v_add_f32_e32 v235, v235, v55
	v_add_f32_e32 v142, v142, v56
	v_add_f32_e32 v143, v143, v57
	v_add_f32_e32 v144, v144, v58
	v_add_f32_e32 v145, v145, v59
	v_add_f32_e32 v146, v146, v60
	v_add_f32_e32 v147, v147, v61
	v_add_f32_e32 v234, v234, v62
	v_add_f32_e32 v235, v235, v63
	v_add_f32_e32 v236, 0, v160
	v_add_f32_e32 v237, 0, v161
	v_add_f32_e32 v238, 0, v162
	v_add_f32_e32 v239, 0, v163
	v_add_f32_e32 v240, 0, v164
	v_add_f32_e32 v241, 0, v165
	v_add_f32_e32 v242, 0, v166
	v_add_f32_e32 v243, 0, v167
	v_add_f32_e32 v236, v236, v168
	v_add_f32_e32 v237, v237, v169
	v_add_f32_e32 v238, v238, v170
	v_add_f32_e32 v239, v239, v171
	v_add_f32_e32 v240, v240, v172
	v_add_f32_e32 v241, v241, v173
	v_add_f32_e32 v242, v242, v174
	v_add_f32_e32 v243, v243, v175
	v_add_f32_e32 v236, v236, v176
	v_add_f32_e32 v237, v237, v177
	v_add_f32_e32 v238, v238, v178
	v_add_f32_e32 v239, v239, v179
	v_add_f32_e32 v240, v240, v180
	v_add_f32_e32 v241, v241, v181
	v_add_f32_e32 v242, v242, v182
	v_add_f32_e32 v243, v243, v183
	v_add_f32_e32 v236, v236, v184
	v_add_f32_e32 v237, v237, v185
	v_add_f32_e32 v238, v238, v186
	v_add_f32_e32 v239, v239, v187
	v_add_f32_e32 v240, v240, v188
	v_add_f32_e32 v241, v241, v189
	v_add_f32_e32 v242, v242, v190
	v_add_f32_e32 v243, v243, v191
	v_add_f32_e32 v236, v236, v192
	v_add_f32_e32 v237, v237, v193
	v_add_f32_e32 v238, v238, v194
	v_add_f32_e32 v239, v239, v195
	v_add_f32_e32 v240, v240, v196
	v_add_f32_e32 v241, v241, v197
	v_add_f32_e32 v242, v242, v198
	v_add_f32_e32 v243, v243, v199
	v_add_f32_e32 v236, v236, v200
	v_add_f32_e32 v237, v237, v201
	v_add_f32_e32 v238, v238, v202
	v_add_f32_e32 v239, v239, v203
	v_add_f32_e32 v240, v240, v204
	v_add_f32_e32 v241, v241, v205
	v_add_f32_e32 v242, v242, v206
	v_add_f32_e32 v243, v243, v207
	v_add_f32_e32 v236, v236, v208
	v_add_f32_e32 v237, v237, v209
	v_add_f32_e32 v238, v238, v210
	v_add_f32_e32 v239, v239, v211
	v_add_f32_e32 v240, v240, v212
	v_add_f32_e32 v241, v241, v213
	v_add_f32_e32 v242, v242, v214
	v_add_f32_e32 v243, v243, v215
	v_add_f32_e32 v236, v236, v216
	v_add_f32_e32 v237, v237, v217
	v_add_f32_e32 v238, v238, v218
	v_add_f32_e32 v239, v239, v219
	v_add_f32_e32 v240, v240, v230
	v_add_f32_e32 v241, v241, v231
	v_add_f32_e32 v242, v242, v232
	v_add_f32_e32 v243, v243, v233
	s_waitcnt vmcnt(8)
	s_barrier
	ds_read_b128 v[64:67], v151 offset:0
	ds_read_b128 v[96:99], v222 offset:32768
	ds_read_b128 v[100:103], v222 offset:34816
	ds_read_b128 v[104:107], v222 offset:36864
	ds_read_b128 v[108:111], v222 offset:38912
	ds_read_b128 v[68:71], v151 offset:2048
	ds_read_b128 v[72:75], v151 offset:4096
	ds_read_b128 v[76:79], v151 offset:6144
	s_waitcnt lgkmcnt(6)
	v_mfma_f32_16x16x32_bf16 v[0:3], v[64:67], v[96:99], 0
	ds_read_b128 v[80:83], v220 offset:0
	s_waitcnt lgkmcnt(6)
	v_mfma_f32_16x16x32_bf16 v[4:7], v[64:67], v[100:103], 0
	ds_read_b128 v[112:115], v224 offset:32768
	s_waitcnt lgkmcnt(6)
	v_mfma_f32_16x16x32_bf16 v[8:11], v[64:67], v[104:107], 0
	ds_read_b128 v[116:119], v224 offset:34816
	s_waitcnt lgkmcnt(6)
	v_mfma_f32_16x16x32_bf16 v[12:15], v[64:67], v[108:111], 0
	ds_read_b128 v[120:123], v224 offset:36864
	s_waitcnt lgkmcnt(6)
	v_mfma_f32_16x16x32_bf16 v[16:19], v[68:71], v[96:99], 0
	ds_read_b128 v[124:127], v224 offset:38912
	s_waitcnt lgkmcnt(7)
	v_mfma_f32_16x16x32_bf16 v[20:23], v[68:71], v[100:103], 0
	ds_read_b128 v[84:87], v220 offset:2048
	s_waitcnt lgkmcnt(8)
	v_mfma_f32_16x16x32_bf16 v[24:27], v[68:71], v[104:107], 0
	ds_read_b128 v[88:91], v220 offset:4096
	s_waitcnt lgkmcnt(9)
	v_mfma_f32_16x16x32_bf16 v[28:31], v[68:71], v[108:111], 0
	ds_read_b128 v[92:95], v220 offset:6144
	s_waitcnt lgkmcnt(9)
	v_mfma_f32_16x16x32_bf16 v[32:35], v[72:75], v[96:99], 0
	s_waitcnt lgkmcnt(9)
	v_mfma_f32_16x16x32_bf16 v[36:39], v[72:75], v[100:103], 0
	s_waitcnt lgkmcnt(9)
	v_mfma_f32_16x16x32_bf16 v[40:43], v[72:75], v[104:107], 0
	s_waitcnt lgkmcnt(9)
	v_mfma_f32_16x16x32_bf16 v[44:47], v[72:75], v[108:111], 0
	s_waitcnt vmcnt(4) lgkmcnt(0)
	s_barrier
	s_add_u32 m0, s38, 0
	s_nop 0
	global_load_lds_dwordx4 v226, s[98:99]
	s_waitcnt lgkmcnt(8)
	v_mfma_f32_16x16x32_bf16 v[48:51], v[76:79], v[96:99], 0
	s_add_u32 m0, s38, 4096
	s_nop 0
	global_load_lds_dwordx4 v228, s[98:99]
	s_waitcnt lgkmcnt(8)
	v_mfma_f32_16x16x32_bf16 v[52:55], v[76:79], v[100:103], 0
	s_add_u32 m0, s38, 8192
	s_nop 0
	global_load_lds_dwordx4 v244, s[98:99]
	s_waitcnt lgkmcnt(8)
	v_mfma_f32_16x16x32_bf16 v[56:59], v[76:79], v[104:107], 0
	s_add_u32 m0, s38, 12288
	s_nop 0
	global_load_lds_dwordx4 v245, s[98:99]
	s_add_u32 s98, s98, 128
	s_addc_u32 s99, s99, 0
	s_waitcnt lgkmcnt(8)
	v_mfma_f32_16x16x32_bf16 v[60:63], v[76:79], v[108:111], 0
	s_waitcnt lgkmcnt(6)
	v_mfma_f32_16x16x32_bf16 v[0:3], v[80:83], v[112:115], v[0:3]
	ds_read_b128 v[64:67], v151 offset:16384
	s_waitcnt lgkmcnt(6)
	v_mfma_f32_16x16x32_bf16 v[4:7], v[80:83], v[116:119], v[4:7]
	ds_read_b128 v[96:99], v222 offset:32768
	s_waitcnt lgkmcnt(6)
	v_mfma_f32_16x16x32_bf16 v[8:11], v[80:83], v[120:123], v[8:11]
	ds_read_b128 v[100:103], v222 offset:34816
	s_waitcnt lgkmcnt(6)
	v_mfma_f32_16x16x32_bf16 v[12:15], v[80:83], v[124:127], v[12:15]
	ds_read_b128 v[104:107], v222 offset:36864
	s_waitcnt lgkmcnt(6)
	v_mfma_f32_16x16x32_bf16 v[16:19], v[84:87], v[112:115], v[16:19]
	ds_read_b128 v[108:111], v222 offset:38912
	s_waitcnt lgkmcnt(7)
	v_mfma_f32_16x16x32_bf16 v[20:23], v[84:87], v[116:119], v[20:23]
	ds_read_b128 v[68:71], v151 offset:18432
	s_waitcnt lgkmcnt(8)
	v_mfma_f32_16x16x32_bf16 v[24:27], v[84:87], v[120:123], v[24:27]
	ds_read_b128 v[72:75], v151 offset:20480
	s_waitcnt lgkmcnt(9)
	v_mfma_f32_16x16x32_bf16 v[28:31], v[84:87], v[124:127], v[28:31]
	ds_read_b128 v[76:79], v151 offset:22528
	s_waitcnt lgkmcnt(9)
	v_mfma_f32_16x16x32_bf16 v[32:35], v[88:91], v[112:115], v[32:35]
	s_waitcnt lgkmcnt(9)
	v_mfma_f32_16x16x32_bf16 v[36:39], v[88:91], v[116:119], v[36:39]
	s_waitcnt lgkmcnt(9)
	v_mfma_f32_16x16x32_bf16 v[40:43], v[88:91], v[120:123], v[40:43]
	s_waitcnt lgkmcnt(9)
	v_mfma_f32_16x16x32_bf16 v[44:47], v[88:91], v[124:127], v[44:47]
	s_waitcnt lgkmcnt(8)
	v_mfma_f32_16x16x32_bf16 v[48:51], v[92:95], v[112:115], v[48:51]
	s_waitcnt lgkmcnt(8)
	v_mfma_f32_16x16x32_bf16 v[52:55], v[92:95], v[116:119], v[52:55]
	s_waitcnt lgkmcnt(8)
	v_mfma_f32_16x16x32_bf16 v[56:59], v[92:95], v[120:123], v[56:59]
	s_waitcnt lgkmcnt(8)
	v_mfma_f32_16x16x32_bf16 v[60:63], v[92:95], v[124:127], v[60:63]
	s_waitcnt lgkmcnt(6)
	v_mfma_f32_16x16x32_bf16 v[160:163], v[64:67], v[96:99], 0
	ds_read_b128 v[80:83], v220 offset:16384
	s_waitcnt lgkmcnt(6)
	v_mfma_f32_16x16x32_bf16 v[164:167], v[64:67], v[100:103], 0
	ds_read_b128 v[112:115], v224 offset:32768
	s_waitcnt lgkmcnt(6)
	v_mfma_f32_16x16x32_bf16 v[168:171], v[64:67], v[104:107], 0
	ds_read_b128 v[116:119], v224 offset:34816
	s_waitcnt lgkmcnt(6)
	v_mfma_f32_16x16x32_bf16 v[172:175], v[64:67], v[108:111], 0
	ds_read_b128 v[120:123], v224 offset:36864
	s_waitcnt lgkmcnt(6)
	v_mfma_f32_16x16x32_bf16 v[176:179], v[68:71], v[96:99], 0
	ds_read_b128 v[124:127], v224 offset:38912
	s_waitcnt lgkmcnt(7)
	v_mfma_f32_16x16x32_bf16 v[180:183], v[68:71], v[100:103], 0
	ds_read_b128 v[84:87], v220 offset:18432
	s_waitcnt lgkmcnt(8)
	v_mfma_f32_16x16x32_bf16 v[184:187], v[68:71], v[104:107], 0
	ds_read_b128 v[88:91], v220 offset:20480
	s_waitcnt lgkmcnt(9)
	v_mfma_f32_16x16x32_bf16 v[188:191], v[68:71], v[108:111], 0
	ds_read_b128 v[92:95], v220 offset:22528
	s_waitcnt lgkmcnt(9)
	v_mfma_f32_16x16x32_bf16 v[192:195], v[72:75], v[96:99], 0
	s_waitcnt lgkmcnt(9)
	v_mfma_f32_16x16x32_bf16 v[196:199], v[72:75], v[100:103], 0
	s_waitcnt lgkmcnt(9)
	v_mfma_f32_16x16x32_bf16 v[200:203], v[72:75], v[104:107], 0
	s_waitcnt lgkmcnt(9)
	v_mfma_f32_16x16x32_bf16 v[204:207], v[72:75], v[108:111], 0
	s_waitcnt vmcnt(0) lgkmcnt(0)
	s_barrier
	s_add_u32 m0, s38, 16384
	s_nop 0
	global_load_lds_dwordx4 v226, s[100:101]
	s_waitcnt lgkmcnt(8)
	v_mfma_f32_16x16x32_bf16 v[208:211], v[76:79], v[96:99], 0
	s_add_u32 m0, s38, 20480
	s_nop 0
	global_load_lds_dwordx4 v228, s[100:101]
	s_waitcnt lgkmcnt(8)
	v_mfma_f32_16x16x32_bf16 v[212:215], v[76:79], v[100:103], 0
	s_add_u32 m0, s38, 24576
	s_nop 0
	global_load_lds_dwordx4 v244, s[100:101]
	s_waitcnt lgkmcnt(8)
	v_mfma_f32_16x16x32_bf16 v[216:219], v[76:79], v[104:107], 0
	s_add_u32 m0, s38, 28672
	s_nop 0
	global_load_lds_dwordx4 v245, s[100:101]
	s_add_u32 s100, s100, 128
	s_addc_u32 s101, s101, 0
	s_waitcnt lgkmcnt(8)
	v_mfma_f32_16x16x32_bf16 v[230:233], v[76:79], v[108:111], 0
	s_add_u32 m0, s38, 32768
	s_nop 0
	global_load_lds_dwordx4 v226, s[4:5]
	s_waitcnt lgkmcnt(6)
	v_mfma_f32_16x16x32_bf16 v[160:163], v[80:83], v[112:115], v[160:163]
	ds_read_b128 v[64:67], v151 offset:0
	s_add_u32 m0, s38, 36864
	s_nop 0
	global_load_lds_dwordx4 v228, s[4:5]
	s_waitcnt lgkmcnt(6)
	v_mfma_f32_16x16x32_bf16 v[164:167], v[80:83], v[116:119], v[164:167]
	ds_read_b128 v[96:99], v222 offset:49152
	s_add_u32 m0, s38, 40960
	s_nop 0
	global_load_lds_dwordx4 v244, s[4:5]
	s_waitcnt lgkmcnt(6)
	v_mfma_f32_16x16x32_bf16 v[168:171], v[80:83], v[120:123], v[168:171]
	ds_read_b128 v[100:103], v222 offset:51200
	s_add_u32 m0, s38, 45056
	s_nop 0
	global_load_lds_dwordx4 v245, s[4:5]
	s_add_u32 s4, s4, 128
	s_addc_u32 s5, s5, 0
	s_waitcnt lgkmcnt(6)
	v_mfma_f32_16x16x32_bf16 v[172:175], v[80:83], v[124:127], v[172:175]
	ds_read_b128 v[104:107], v222 offset:53248
	s_waitcnt lgkmcnt(6)
	v_mfma_f32_16x16x32_bf16 v[176:179], v[84:87], v[112:115], v[176:179]
	ds_read_b128 v[108:111], v222 offset:55296
	s_waitcnt lgkmcnt(7)
	v_mfma_f32_16x16x32_bf16 v[180:183], v[84:87], v[116:119], v[180:183]
	ds_read_b128 v[68:71], v151 offset:2048
	s_waitcnt lgkmcnt(8)
	v_mfma_f32_16x16x32_bf16 v[184:187], v[84:87], v[120:123], v[184:187]
	ds_read_b128 v[72:75], v151 offset:4096
	s_waitcnt lgkmcnt(9)
	v_mfma_f32_16x16x32_bf16 v[188:191], v[84:87], v[124:127], v[188:191]
	ds_read_b128 v[76:79], v151 offset:6144
	s_waitcnt lgkmcnt(9)
	v_mfma_f32_16x16x32_bf16 v[192:195], v[88:91], v[112:115], v[192:195]
	s_waitcnt lgkmcnt(9)
	v_mfma_f32_16x16x32_bf16 v[196:199], v[88:91], v[116:119], v[196:199]
	s_waitcnt lgkmcnt(9)
	v_mfma_f32_16x16x32_bf16 v[200:203], v[88:91], v[120:123], v[200:203]
	s_waitcnt lgkmcnt(9)
	v_mfma_f32_16x16x32_bf16 v[204:207], v[88:91], v[124:127], v[204:207]
	s_waitcnt lgkmcnt(8)
	v_mfma_f32_16x16x32_bf16 v[208:211], v[92:95], v[112:115], v[208:211]
	s_waitcnt lgkmcnt(8)
	v_mfma_f32_16x16x32_bf16 v[212:215], v[92:95], v[116:119], v[212:215]
	s_waitcnt lgkmcnt(8)
	v_mfma_f32_16x16x32_bf16 v[216:219], v[92:95], v[120:123], v[216:219]
	s_waitcnt lgkmcnt(8)
	v_mfma_f32_16x16x32_bf16 v[230:233], v[92:95], v[124:127], v[230:233]
	s_waitcnt lgkmcnt(6)
	v_mfma_f32_16x16x32_bf16 v[0:3], v[64:67], v[96:99], v[0:3]
	ds_read_b128 v[80:83], v220 offset:0
	s_waitcnt lgkmcnt(6)
	v_mfma_f32_16x16x32_bf16 v[4:7], v[64:67], v[100:103], v[4:7]
	ds_read_b128 v[112:115], v224 offset:49152
	s_waitcnt lgkmcnt(6)
	v_mfma_f32_16x16x32_bf16 v[8:11], v[64:67], v[104:107], v[8:11]
	ds_read_b128 v[116:119], v224 offset:51200
	s_waitcnt lgkmcnt(6)
	v_mfma_f32_16x16x32_bf16 v[12:15], v[64:67], v[108:111], v[12:15]
	ds_read_b128 v[120:123], v224 offset:53248
	s_waitcnt lgkmcnt(6)
	v_mfma_f32_16x16x32_bf16 v[16:19], v[68:71], v[96:99], v[16:19]
	ds_read_b128 v[124:127], v224 offset:55296
	s_waitcnt lgkmcnt(7)
	v_mfma_f32_16x16x32_bf16 v[20:23], v[68:71], v[100:103], v[20:23]
	ds_read_b128 v[84:87], v220 offset:2048
	s_waitcnt lgkmcnt(8)
	v_mfma_f32_16x16x32_bf16 v[24:27], v[68:71], v[104:107], v[24:27]
	ds_read_b128 v[88:91], v220 offset:4096
	s_waitcnt lgkmcnt(9)
	v_mfma_f32_16x16x32_bf16 v[28:31], v[68:71], v[108:111], v[28:31]
	ds_read_b128 v[92:95], v220 offset:6144
	s_waitcnt lgkmcnt(9)
	v_mfma_f32_16x16x32_bf16 v[32:35], v[72:75], v[96:99], v[32:35]
	s_waitcnt lgkmcnt(9)
	v_mfma_f32_16x16x32_bf16 v[36:39], v[72:75], v[100:103], v[36:39]
	s_waitcnt lgkmcnt(9)
	v_mfma_f32_16x16x32_bf16 v[40:43], v[72:75], v[104:107], v[40:43]
	s_waitcnt lgkmcnt(9)
	v_mfma_f32_16x16x32_bf16 v[44:47], v[72:75], v[108:111], v[44:47]
	s_waitcnt vmcnt(4) lgkmcnt(0)
	s_barrier
	s_add_u32 m0, s38, 0
	s_nop 0
	global_load_lds_dwordx4 v226, s[98:99]
	s_waitcnt lgkmcnt(8)
	v_mfma_f32_16x16x32_bf16 v[48:51], v[76:79], v[96:99], v[48:51]
	s_add_u32 m0, s38, 4096
	s_nop 0
	global_load_lds_dwordx4 v228, s[98:99]
	s_waitcnt lgkmcnt(8)
	v_mfma_f32_16x16x32_bf16 v[52:55], v[76:79], v[100:103], v[52:55]
	s_add_u32 m0, s38, 8192
	s_nop 0
	global_load_lds_dwordx4 v244, s[98:99]
	s_waitcnt lgkmcnt(8)
	v_mfma_f32_16x16x32_bf16 v[56:59], v[76:79], v[104:107], v[56:59]
	s_add_u32 m0, s38, 12288
	s_nop 0
	global_load_lds_dwordx4 v245, s[98:99]
	s_add_u32 s98, s98, 128
	s_addc_u32 s99, s99, 0
	s_waitcnt lgkmcnt(8)
	v_mfma_f32_16x16x32_bf16 v[60:63], v[76:79], v[108:111], v[60:63]
	s_waitcnt lgkmcnt(6)
	v_mfma_f32_16x16x32_bf16 v[0:3], v[80:83], v[112:115], v[0:3]
	ds_read_b128 v[64:67], v151 offset:16384
	s_waitcnt lgkmcnt(6)
	v_mfma_f32_16x16x32_bf16 v[4:7], v[80:83], v[116:119], v[4:7]
	ds_read_b128 v[96:99], v222 offset:49152
	s_waitcnt lgkmcnt(6)
	v_mfma_f32_16x16x32_bf16 v[8:11], v[80:83], v[120:123], v[8:11]
	ds_read_b128 v[100:103], v222 offset:51200
	s_waitcnt lgkmcnt(6)
	v_mfma_f32_16x16x32_bf16 v[12:15], v[80:83], v[124:127], v[12:15]
	ds_read_b128 v[104:107], v222 offset:53248
	s_waitcnt lgkmcnt(6)
	v_mfma_f32_16x16x32_bf16 v[16:19], v[84:87], v[112:115], v[16:19]
	ds_read_b128 v[108:111], v222 offset:55296
	s_waitcnt lgkmcnt(7)
	v_mfma_f32_16x16x32_bf16 v[20:23], v[84:87], v[116:119], v[20:23]
	ds_read_b128 v[68:71], v151 offset:18432
	s_waitcnt lgkmcnt(8)
	v_mfma_f32_16x16x32_bf16 v[24:27], v[84:87], v[120:123], v[24:27]
	ds_read_b128 v[72:75], v151 offset:20480
	s_waitcnt lgkmcnt(9)
	v_mfma_f32_16x16x32_bf16 v[28:31], v[84:87], v[124:127], v[28:31]
	ds_read_b128 v[76:79], v151 offset:22528
	s_waitcnt lgkmcnt(9)
	v_mfma_f32_16x16x32_bf16 v[32:35], v[88:91], v[112:115], v[32:35]
	s_waitcnt lgkmcnt(9)
	v_mfma_f32_16x16x32_bf16 v[36:39], v[88:91], v[116:119], v[36:39]
	s_waitcnt lgkmcnt(9)
	v_mfma_f32_16x16x32_bf16 v[40:43], v[88:91], v[120:123], v[40:43]
	s_waitcnt lgkmcnt(9)
	v_mfma_f32_16x16x32_bf16 v[44:47], v[88:91], v[124:127], v[44:47]
	s_waitcnt lgkmcnt(8)
	v_mfma_f32_16x16x32_bf16 v[48:51], v[92:95], v[112:115], v[48:51]
	s_waitcnt lgkmcnt(8)
	v_mfma_f32_16x16x32_bf16 v[52:55], v[92:95], v[116:119], v[52:55]
	s_waitcnt lgkmcnt(8)
	v_mfma_f32_16x16x32_bf16 v[56:59], v[92:95], v[120:123], v[56:59]
	s_waitcnt lgkmcnt(8)
	v_mfma_f32_16x16x32_bf16 v[60:63], v[92:95], v[124:127], v[60:63]
	s_waitcnt lgkmcnt(6)
	v_mfma_f32_16x16x32_bf16 v[160:163], v[64:67], v[96:99], v[160:163]
	ds_read_b128 v[80:83], v220 offset:16384
	s_waitcnt lgkmcnt(6)
	v_mfma_f32_16x16x32_bf16 v[164:167], v[64:67], v[100:103], v[164:167]
	ds_read_b128 v[112:115], v224 offset:49152
	s_waitcnt lgkmcnt(6)
	v_mfma_f32_16x16x32_bf16 v[168:171], v[64:67], v[104:107], v[168:171]
	ds_read_b128 v[116:119], v224 offset:51200
	s_waitcnt lgkmcnt(6)
	v_mfma_f32_16x16x32_bf16 v[172:175], v[64:67], v[108:111], v[172:175]
	ds_read_b128 v[120:123], v224 offset:53248
	s_waitcnt lgkmcnt(6)
	v_mfma_f32_16x16x32_bf16 v[176:179], v[68:71], v[96:99], v[176:179]
	ds_read_b128 v[124:127], v224 offset:55296
	s_waitcnt lgkmcnt(7)
	v_mfma_f32_16x16x32_bf16 v[180:183], v[68:71], v[100:103], v[180:183]
	ds_read_b128 v[84:87], v220 offset:18432
	s_waitcnt lgkmcnt(8)
	v_mfma_f32_16x16x32_bf16 v[184:187], v[68:71], v[104:107], v[184:187]
	ds_read_b128 v[88:91], v220 offset:20480
	s_waitcnt lgkmcnt(9)
	v_mfma_f32_16x16x32_bf16 v[188:191], v[68:71], v[108:111], v[188:191]
	ds_read_b128 v[92:95], v220 offset:22528
	s_waitcnt lgkmcnt(9)
	v_mfma_f32_16x16x32_bf16 v[192:195], v[72:75], v[96:99], v[192:195]
	s_waitcnt lgkmcnt(9)
	v_mfma_f32_16x16x32_bf16 v[196:199], v[72:75], v[100:103], v[196:199]
	s_waitcnt lgkmcnt(9)
	v_mfma_f32_16x16x32_bf16 v[200:203], v[72:75], v[104:107], v[200:203]
	s_waitcnt lgkmcnt(9)
	v_mfma_f32_16x16x32_bf16 v[204:207], v[72:75], v[108:111], v[204:207]
	s_waitcnt vmcnt(0) lgkmcnt(0)
	s_barrier
	s_add_u32 m0, s38, 16384
	s_nop 0
	global_load_lds_dwordx4 v226, s[100:101]
	s_waitcnt lgkmcnt(8)
	v_mfma_f32_16x16x32_bf16 v[208:211], v[76:79], v[96:99], v[208:211]
	s_add_u32 m0, s38, 20480
	s_nop 0
	global_load_lds_dwordx4 v228, s[100:101]
	s_waitcnt lgkmcnt(8)
	v_mfma_f32_16x16x32_bf16 v[212:215], v[76:79], v[100:103], v[212:215]
	s_add_u32 m0, s38, 24576
	s_nop 0
	global_load_lds_dwordx4 v244, s[100:101]
	s_waitcnt lgkmcnt(8)
	v_mfma_f32_16x16x32_bf16 v[216:219], v[76:79], v[104:107], v[216:219]
	s_add_u32 m0, s38, 28672
	s_nop 0
	global_load_lds_dwordx4 v245, s[100:101]
	s_add_u32 s100, s100, 128
	s_addc_u32 s101, s101, 0
	s_waitcnt lgkmcnt(8)
	v_mfma_f32_16x16x32_bf16 v[230:233], v[76:79], v[108:111], v[230:233]
	s_add_u32 m0, s38, 49152
	s_nop 0
	global_load_lds_dwordx4 v226, s[4:5]
	s_waitcnt lgkmcnt(6)
	v_mfma_f32_16x16x32_bf16 v[160:163], v[80:83], v[112:115], v[160:163]
	ds_read_b128 v[64:67], v151 offset:0
	s_add_u32 m0, s38, 53248
	s_nop 0
	global_load_lds_dwordx4 v228, s[4:5]
	s_waitcnt lgkmcnt(6)
	v_mfma_f32_16x16x32_bf16 v[164:167], v[80:83], v[116:119], v[164:167]
	ds_read_b128 v[96:99], v222 offset:32768
	s_add_u32 m0, s38, 57344
	s_nop 0
	global_load_lds_dwordx4 v244, s[4:5]
	s_waitcnt lgkmcnt(6)
	v_mfma_f32_16x16x32_bf16 v[168:171], v[80:83], v[120:123], v[168:171]
	ds_read_b128 v[100:103], v222 offset:34816
	s_add_u32 m0, s38, 61440
	s_nop 0
	global_load_lds_dwordx4 v245, s[4:5]
	s_add_u32 s4, s4, 128
	s_addc_u32 s5, s5, 0
	s_waitcnt lgkmcnt(6)
	v_mfma_f32_16x16x32_bf16 v[172:175], v[80:83], v[124:127], v[172:175]
	ds_read_b128 v[104:107], v222 offset:36864
	s_waitcnt lgkmcnt(6)
	v_mfma_f32_16x16x32_bf16 v[176:179], v[84:87], v[112:115], v[176:179]
	ds_read_b128 v[108:111], v222 offset:38912
	s_waitcnt lgkmcnt(7)
	v_mfma_f32_16x16x32_bf16 v[180:183], v[84:87], v[116:119], v[180:183]
	ds_read_b128 v[68:71], v151 offset:2048
	s_waitcnt lgkmcnt(8)
	v_mfma_f32_16x16x32_bf16 v[184:187], v[84:87], v[120:123], v[184:187]
	ds_read_b128 v[72:75], v151 offset:4096
	s_waitcnt lgkmcnt(9)
	v_mfma_f32_16x16x32_bf16 v[188:191], v[84:87], v[124:127], v[188:191]
	ds_read_b128 v[76:79], v151 offset:6144
	s_waitcnt lgkmcnt(9)
	v_mfma_f32_16x16x32_bf16 v[192:195], v[88:91], v[112:115], v[192:195]
	s_waitcnt lgkmcnt(9)
	v_mfma_f32_16x16x32_bf16 v[196:199], v[88:91], v[116:119], v[196:199]
	s_waitcnt lgkmcnt(9)
	v_mfma_f32_16x16x32_bf16 v[200:203], v[88:91], v[120:123], v[200:203]
	s_waitcnt lgkmcnt(9)
	v_mfma_f32_16x16x32_bf16 v[204:207], v[88:91], v[124:127], v[204:207]
	s_waitcnt lgkmcnt(8)
	v_mfma_f32_16x16x32_bf16 v[208:211], v[92:95], v[112:115], v[208:211]
	s_waitcnt lgkmcnt(8)
	v_mfma_f32_16x16x32_bf16 v[212:215], v[92:95], v[116:119], v[212:215]
	s_waitcnt lgkmcnt(8)
	v_mfma_f32_16x16x32_bf16 v[216:219], v[92:95], v[120:123], v[216:219]
	s_waitcnt lgkmcnt(8)
	v_mfma_f32_16x16x32_bf16 v[230:233], v[92:95], v[124:127], v[230:233]
	s_waitcnt lgkmcnt(6)
	v_mfma_f32_16x16x32_bf16 v[0:3], v[64:67], v[96:99], v[0:3]
	ds_read_b128 v[80:83], v220 offset:0
	s_waitcnt lgkmcnt(6)
	v_mfma_f32_16x16x32_bf16 v[4:7], v[64:67], v[100:103], v[4:7]
	ds_read_b128 v[112:115], v224 offset:32768
	s_waitcnt lgkmcnt(6)
	v_mfma_f32_16x16x32_bf16 v[8:11], v[64:67], v[104:107], v[8:11]
	ds_read_b128 v[116:119], v224 offset:34816
	s_waitcnt lgkmcnt(6)
	v_mfma_f32_16x16x32_bf16 v[12:15], v[64:67], v[108:111], v[12:15]
	ds_read_b128 v[120:123], v224 offset:36864
	s_waitcnt lgkmcnt(6)
	v_mfma_f32_16x16x32_bf16 v[16:19], v[68:71], v[96:99], v[16:19]
	ds_read_b128 v[124:127], v224 offset:38912
	s_waitcnt lgkmcnt(7)
	v_mfma_f32_16x16x32_bf16 v[20:23], v[68:71], v[100:103], v[20:23]
	ds_read_b128 v[84:87], v220 offset:2048
	s_waitcnt lgkmcnt(8)
	v_mfma_f32_16x16x32_bf16 v[24:27], v[68:71], v[104:107], v[24:27]
	ds_read_b128 v[88:91], v220 offset:4096
	s_waitcnt lgkmcnt(9)
	v_mfma_f32_16x16x32_bf16 v[28:31], v[68:71], v[108:111], v[28:31]
	ds_read_b128 v[92:95], v220 offset:6144
	s_waitcnt lgkmcnt(9)
	v_mfma_f32_16x16x32_bf16 v[32:35], v[72:75], v[96:99], v[32:35]
	s_waitcnt lgkmcnt(9)
	v_mfma_f32_16x16x32_bf16 v[36:39], v[72:75], v[100:103], v[36:39]
	s_waitcnt lgkmcnt(9)
	v_mfma_f32_16x16x32_bf16 v[40:43], v[72:75], v[104:107], v[40:43]
	s_waitcnt lgkmcnt(9)
	v_mfma_f32_16x16x32_bf16 v[44:47], v[72:75], v[108:111], v[44:47]
	s_waitcnt vmcnt(4) lgkmcnt(0)
	s_barrier
	s_add_u32 m0, s38, 0
	s_nop 0
	global_load_lds_dwordx4 v226, s[98:99]
	s_waitcnt lgkmcnt(8)
	v_mfma_f32_16x16x32_bf16 v[48:51], v[76:79], v[96:99], v[48:51]
	s_add_u32 m0, s38, 4096
	s_nop 0
	global_load_lds_dwordx4 v228, s[98:99]
	s_waitcnt lgkmcnt(8)
	v_mfma_f32_16x16x32_bf16 v[52:55], v[76:79], v[100:103], v[52:55]
	s_add_u32 m0, s38, 8192
	s_nop 0
	global_load_lds_dwordx4 v244, s[98:99]
	s_waitcnt lgkmcnt(8)
	v_mfma_f32_16x16x32_bf16 v[56:59], v[76:79], v[104:107], v[56:59]
	s_add_u32 m0, s38, 12288
	s_nop 0
	global_load_lds_dwordx4 v245, s[98:99]
	s_add_u32 s98, s98, 128
	s_addc_u32 s99, s99, 0
	s_waitcnt lgkmcnt(8)
	v_mfma_f32_16x16x32_bf16 v[60:63], v[76:79], v[108:111], v[60:63]
	s_waitcnt lgkmcnt(6)
	v_mfma_f32_16x16x32_bf16 v[0:3], v[80:83], v[112:115], v[0:3]
	ds_read_b128 v[64:67], v151 offset:16384
	s_waitcnt lgkmcnt(6)
	v_mfma_f32_16x16x32_bf16 v[4:7], v[80:83], v[116:119], v[4:7]
	ds_read_b128 v[96:99], v222 offset:32768
	s_waitcnt lgkmcnt(6)
	v_mfma_f32_16x16x32_bf16 v[8:11], v[80:83], v[120:123], v[8:11]
	ds_read_b128 v[100:103], v222 offset:34816
	s_waitcnt lgkmcnt(6)
	v_mfma_f32_16x16x32_bf16 v[12:15], v[80:83], v[124:127], v[12:15]
	ds_read_b128 v[104:107], v222 offset:36864
	s_waitcnt lgkmcnt(6)
	v_mfma_f32_16x16x32_bf16 v[16:19], v[84:87], v[112:115], v[16:19]
	ds_read_b128 v[108:111], v222 offset:38912
	s_waitcnt lgkmcnt(7)
	v_mfma_f32_16x16x32_bf16 v[20:23], v[84:87], v[116:119], v[20:23]
	ds_read_b128 v[68:71], v151 offset:18432
	s_waitcnt lgkmcnt(8)
	v_mfma_f32_16x16x32_bf16 v[24:27], v[84:87], v[120:123], v[24:27]
	ds_read_b128 v[72:75], v151 offset:20480
	s_waitcnt lgkmcnt(9)
	v_mfma_f32_16x16x32_bf16 v[28:31], v[84:87], v[124:127], v[28:31]
	ds_read_b128 v[76:79], v151 offset:22528
	s_waitcnt lgkmcnt(9)
	v_mfma_f32_16x16x32_bf16 v[32:35], v[88:91], v[112:115], v[32:35]
	s_waitcnt lgkmcnt(9)
	v_mfma_f32_16x16x32_bf16 v[36:39], v[88:91], v[116:119], v[36:39]
	s_waitcnt lgkmcnt(9)
	v_mfma_f32_16x16x32_bf16 v[40:43], v[88:91], v[120:123], v[40:43]
	s_waitcnt lgkmcnt(9)
	v_mfma_f32_16x16x32_bf16 v[44:47], v[88:91], v[124:127], v[44:47]
	s_waitcnt lgkmcnt(8)
	v_mfma_f32_16x16x32_bf16 v[48:51], v[92:95], v[112:115], v[48:51]
	s_waitcnt lgkmcnt(8)
	v_mfma_f32_16x16x32_bf16 v[52:55], v[92:95], v[116:119], v[52:55]
	s_waitcnt lgkmcnt(8)
	v_mfma_f32_16x16x32_bf16 v[56:59], v[92:95], v[120:123], v[56:59]
	s_waitcnt lgkmcnt(8)
	v_mfma_f32_16x16x32_bf16 v[60:63], v[92:95], v[124:127], v[60:63]
	s_waitcnt lgkmcnt(6)
	v_mfma_f32_16x16x32_bf16 v[160:163], v[64:67], v[96:99], v[160:163]
	ds_read_b128 v[80:83], v220 offset:16384
	s_waitcnt lgkmcnt(6)
	v_mfma_f32_16x16x32_bf16 v[164:167], v[64:67], v[100:103], v[164:167]
	ds_read_b128 v[112:115], v224 offset:32768
	s_waitcnt lgkmcnt(6)
	v_mfma_f32_16x16x32_bf16 v[168:171], v[64:67], v[104:107], v[168:171]
	ds_read_b128 v[116:119], v224 offset:34816
	s_waitcnt lgkmcnt(6)
	v_mfma_f32_16x16x32_bf16 v[172:175], v[64:67], v[108:111], v[172:175]
	ds_read_b128 v[120:123], v224 offset:36864
	s_waitcnt lgkmcnt(6)
	v_mfma_f32_16x16x32_bf16 v[176:179], v[68:71], v[96:99], v[176:179]
	ds_read_b128 v[124:127], v224 offset:38912
	s_waitcnt lgkmcnt(7)
	v_mfma_f32_16x16x32_bf16 v[180:183], v[68:71], v[100:103], v[180:183]
	ds_read_b128 v[84:87], v220 offset:18432
	s_waitcnt lgkmcnt(8)
	v_mfma_f32_16x16x32_bf16 v[184:187], v[68:71], v[104:107], v[184:187]
	ds_read_b128 v[88:91], v220 offset:20480
	s_waitcnt lgkmcnt(9)
	v_mfma_f32_16x16x32_bf16 v[188:191], v[68:71], v[108:111], v[188:191]
	ds_read_b128 v[92:95], v220 offset:22528
	s_waitcnt lgkmcnt(9)
	v_mfma_f32_16x16x32_bf16 v[192:195], v[72:75], v[96:99], v[192:195]
	s_waitcnt lgkmcnt(9)
	v_mfma_f32_16x16x32_bf16 v[196:199], v[72:75], v[100:103], v[196:199]
	s_waitcnt lgkmcnt(9)
	v_mfma_f32_16x16x32_bf16 v[200:203], v[72:75], v[104:107], v[200:203]
	s_waitcnt lgkmcnt(9)
	v_mfma_f32_16x16x32_bf16 v[204:207], v[72:75], v[108:111], v[204:207]
	s_waitcnt vmcnt(0) lgkmcnt(0)
	s_barrier
	s_add_u32 m0, s38, 16384
	s_nop 0
	global_load_lds_dwordx4 v226, s[100:101]
	s_waitcnt lgkmcnt(8)
	v_mfma_f32_16x16x32_bf16 v[208:211], v[76:79], v[96:99], v[208:211]
	s_add_u32 m0, s38, 20480
	s_nop 0
	global_load_lds_dwordx4 v228, s[100:101]
	s_waitcnt lgkmcnt(8)
	v_mfma_f32_16x16x32_bf16 v[212:215], v[76:79], v[100:103], v[212:215]
	s_add_u32 m0, s38, 24576
	s_nop 0
	global_load_lds_dwordx4 v244, s[100:101]
	s_waitcnt lgkmcnt(8)
	v_mfma_f32_16x16x32_bf16 v[216:219], v[76:79], v[104:107], v[216:219]
	s_add_u32 m0, s38, 28672
	s_nop 0
	global_load_lds_dwordx4 v245, s[100:101]
	s_add_u32 s100, s100, 128
	s_addc_u32 s101, s101, 0
	s_waitcnt lgkmcnt(8)
	v_mfma_f32_16x16x32_bf16 v[230:233], v[76:79], v[108:111], v[230:233]
	s_add_u32 m0, s38, 32768
	s_nop 0
	global_load_lds_dwordx4 v226, s[4:5]
	s_waitcnt lgkmcnt(6)
	v_mfma_f32_16x16x32_bf16 v[160:163], v[80:83], v[112:115], v[160:163]
	ds_read_b128 v[64:67], v151 offset:0
	s_add_u32 m0, s38, 36864
	s_nop 0
	global_load_lds_dwordx4 v228, s[4:5]
	s_waitcnt lgkmcnt(6)
	v_mfma_f32_16x16x32_bf16 v[164:167], v[80:83], v[116:119], v[164:167]
	ds_read_b128 v[96:99], v222 offset:49152
	s_add_u32 m0, s38, 40960
	s_nop 0
	global_load_lds_dwordx4 v244, s[4:5]
	s_waitcnt lgkmcnt(6)
	v_mfma_f32_16x16x32_bf16 v[168:171], v[80:83], v[120:123], v[168:171]
	ds_read_b128 v[100:103], v222 offset:51200
	s_add_u32 m0, s38, 45056
	s_nop 0
	global_load_lds_dwordx4 v245, s[4:5]
	s_add_u32 s4, s4, 128
	s_addc_u32 s5, s5, 0
	s_waitcnt lgkmcnt(6)
	v_mfma_f32_16x16x32_bf16 v[172:175], v[80:83], v[124:127], v[172:175]
	ds_read_b128 v[104:107], v222 offset:53248
	s_waitcnt lgkmcnt(6)
	v_mfma_f32_16x16x32_bf16 v[176:179], v[84:87], v[112:115], v[176:179]
	ds_read_b128 v[108:111], v222 offset:55296
	s_waitcnt lgkmcnt(7)
	v_mfma_f32_16x16x32_bf16 v[180:183], v[84:87], v[116:119], v[180:183]
	ds_read_b128 v[68:71], v151 offset:2048
	s_waitcnt lgkmcnt(8)
	v_mfma_f32_16x16x32_bf16 v[184:187], v[84:87], v[120:123], v[184:187]
	ds_read_b128 v[72:75], v151 offset:4096
	s_waitcnt lgkmcnt(9)
	v_mfma_f32_16x16x32_bf16 v[188:191], v[84:87], v[124:127], v[188:191]
	ds_read_b128 v[76:79], v151 offset:6144
	s_waitcnt lgkmcnt(9)
	v_mfma_f32_16x16x32_bf16 v[192:195], v[88:91], v[112:115], v[192:195]
	s_waitcnt lgkmcnt(9)
	v_mfma_f32_16x16x32_bf16 v[196:199], v[88:91], v[116:119], v[196:199]
	s_waitcnt lgkmcnt(9)
	v_mfma_f32_16x16x32_bf16 v[200:203], v[88:91], v[120:123], v[200:203]
	s_waitcnt lgkmcnt(9)
	v_mfma_f32_16x16x32_bf16 v[204:207], v[88:91], v[124:127], v[204:207]
	s_waitcnt lgkmcnt(8)
	v_mfma_f32_16x16x32_bf16 v[208:211], v[92:95], v[112:115], v[208:211]
	s_waitcnt lgkmcnt(8)
	v_mfma_f32_16x16x32_bf16 v[212:215], v[92:95], v[116:119], v[212:215]
	s_waitcnt lgkmcnt(8)
	v_mfma_f32_16x16x32_bf16 v[216:219], v[92:95], v[120:123], v[216:219]
	s_waitcnt lgkmcnt(8)
	v_mfma_f32_16x16x32_bf16 v[230:233], v[92:95], v[124:127], v[230:233]
	s_waitcnt lgkmcnt(6)
	v_mfma_f32_16x16x32_bf16 v[0:3], v[64:67], v[96:99], v[0:3]
	ds_read_b128 v[80:83], v220 offset:0
	s_waitcnt lgkmcnt(6)
	v_mfma_f32_16x16x32_bf16 v[4:7], v[64:67], v[100:103], v[4:7]
	ds_read_b128 v[112:115], v224 offset:49152
	s_waitcnt lgkmcnt(6)
	v_mfma_f32_16x16x32_bf16 v[8:11], v[64:67], v[104:107], v[8:11]
	ds_read_b128 v[116:119], v224 offset:51200
	s_waitcnt lgkmcnt(6)
	v_mfma_f32_16x16x32_bf16 v[12:15], v[64:67], v[108:111], v[12:15]
	ds_read_b128 v[120:123], v224 offset:53248
	s_waitcnt lgkmcnt(6)
	v_mfma_f32_16x16x32_bf16 v[16:19], v[68:71], v[96:99], v[16:19]
	ds_read_b128 v[124:127], v224 offset:55296
	s_waitcnt lgkmcnt(7)
	v_mfma_f32_16x16x32_bf16 v[20:23], v[68:71], v[100:103], v[20:23]
	ds_read_b128 v[84:87], v220 offset:2048
	s_waitcnt lgkmcnt(8)
	v_mfma_f32_16x16x32_bf16 v[24:27], v[68:71], v[104:107], v[24:27]
	ds_read_b128 v[88:91], v220 offset:4096
	s_waitcnt lgkmcnt(9)
	v_mfma_f32_16x16x32_bf16 v[28:31], v[68:71], v[108:111], v[28:31]
	ds_read_b128 v[92:95], v220 offset:6144
	s_waitcnt lgkmcnt(9)
	v_mfma_f32_16x16x32_bf16 v[32:35], v[72:75], v[96:99], v[32:35]
	s_waitcnt lgkmcnt(9)
	v_mfma_f32_16x16x32_bf16 v[36:39], v[72:75], v[100:103], v[36:39]
	s_waitcnt lgkmcnt(9)
	v_mfma_f32_16x16x32_bf16 v[40:43], v[72:75], v[104:107], v[40:43]
	s_waitcnt lgkmcnt(9)
	v_mfma_f32_16x16x32_bf16 v[44:47], v[72:75], v[108:111], v[44:47]
	s_waitcnt vmcnt(4) lgkmcnt(0)
	s_barrier
	s_add_u32 m0, s38, 0
	s_nop 0
	global_load_lds_dwordx4 v226, s[98:99]
	s_waitcnt lgkmcnt(8)
	v_mfma_f32_16x16x32_bf16 v[48:51], v[76:79], v[96:99], v[48:51]
	s_add_u32 m0, s38, 4096
	s_nop 0
	global_load_lds_dwordx4 v228, s[98:99]
	s_waitcnt lgkmcnt(8)
	v_mfma_f32_16x16x32_bf16 v[52:55], v[76:79], v[100:103], v[52:55]
	s_add_u32 m0, s38, 8192
	s_nop 0
	global_load_lds_dwordx4 v244, s[98:99]
	s_waitcnt lgkmcnt(8)
	v_mfma_f32_16x16x32_bf16 v[56:59], v[76:79], v[104:107], v[56:59]
	s_add_u32 m0, s38, 12288
	s_nop 0
	global_load_lds_dwordx4 v245, s[98:99]
	s_add_u32 s98, s98, 128
	s_addc_u32 s99, s99, 0
	s_waitcnt lgkmcnt(8)
	v_mfma_f32_16x16x32_bf16 v[60:63], v[76:79], v[108:111], v[60:63]
	s_waitcnt lgkmcnt(6)
	v_mfma_f32_16x16x32_bf16 v[0:3], v[80:83], v[112:115], v[0:3]
	ds_read_b128 v[64:67], v151 offset:16384
	s_waitcnt lgkmcnt(6)
	v_mfma_f32_16x16x32_bf16 v[4:7], v[80:83], v[116:119], v[4:7]
	ds_read_b128 v[96:99], v222 offset:49152
	s_waitcnt lgkmcnt(6)
	v_mfma_f32_16x16x32_bf16 v[8:11], v[80:83], v[120:123], v[8:11]
	ds_read_b128 v[100:103], v222 offset:51200
	s_waitcnt lgkmcnt(6)
	v_mfma_f32_16x16x32_bf16 v[12:15], v[80:83], v[124:127], v[12:15]
	ds_read_b128 v[104:107], v222 offset:53248
	s_waitcnt lgkmcnt(6)
	v_mfma_f32_16x16x32_bf16 v[16:19], v[84:87], v[112:115], v[16:19]
	ds_read_b128 v[108:111], v222 offset:55296
	s_waitcnt lgkmcnt(7)
	v_mfma_f32_16x16x32_bf16 v[20:23], v[84:87], v[116:119], v[20:23]
	ds_read_b128 v[68:71], v151 offset:18432
	s_waitcnt lgkmcnt(8)
	v_mfma_f32_16x16x32_bf16 v[24:27], v[84:87], v[120:123], v[24:27]
	ds_read_b128 v[72:75], v151 offset:20480
	s_waitcnt lgkmcnt(9)
	v_mfma_f32_16x16x32_bf16 v[28:31], v[84:87], v[124:127], v[28:31]
	ds_read_b128 v[76:79], v151 offset:22528
	s_waitcnt lgkmcnt(9)
	v_mfma_f32_16x16x32_bf16 v[32:35], v[88:91], v[112:115], v[32:35]
	s_waitcnt lgkmcnt(9)
	v_mfma_f32_16x16x32_bf16 v[36:39], v[88:91], v[116:119], v[36:39]
	s_waitcnt lgkmcnt(9)
	v_mfma_f32_16x16x32_bf16 v[40:43], v[88:91], v[120:123], v[40:43]
	s_waitcnt lgkmcnt(9)
	v_mfma_f32_16x16x32_bf16 v[44:47], v[88:91], v[124:127], v[44:47]
	s_waitcnt lgkmcnt(8)
	v_mfma_f32_16x16x32_bf16 v[48:51], v[92:95], v[112:115], v[48:51]
	s_waitcnt lgkmcnt(8)
	v_mfma_f32_16x16x32_bf16 v[52:55], v[92:95], v[116:119], v[52:55]
	s_waitcnt lgkmcnt(8)
	v_mfma_f32_16x16x32_bf16 v[56:59], v[92:95], v[120:123], v[56:59]
	s_waitcnt lgkmcnt(8)
	v_mfma_f32_16x16x32_bf16 v[60:63], v[92:95], v[124:127], v[60:63]
	s_waitcnt lgkmcnt(6)
	v_mfma_f32_16x16x32_bf16 v[160:163], v[64:67], v[96:99], v[160:163]
	ds_read_b128 v[80:83], v220 offset:16384
	s_waitcnt lgkmcnt(6)
	v_mfma_f32_16x16x32_bf16 v[164:167], v[64:67], v[100:103], v[164:167]
	ds_read_b128 v[112:115], v224 offset:49152
	s_waitcnt lgkmcnt(6)
	v_mfma_f32_16x16x32_bf16 v[168:171], v[64:67], v[104:107], v[168:171]
	ds_read_b128 v[116:119], v224 offset:51200
	s_waitcnt lgkmcnt(6)
	v_mfma_f32_16x16x32_bf16 v[172:175], v[64:67], v[108:111], v[172:175]
	ds_read_b128 v[120:123], v224 offset:53248
	s_waitcnt lgkmcnt(6)
	v_mfma_f32_16x16x32_bf16 v[176:179], v[68:71], v[96:99], v[176:179]
	ds_read_b128 v[124:127], v224 offset:55296
	s_waitcnt lgkmcnt(7)
	v_mfma_f32_16x16x32_bf16 v[180:183], v[68:71], v[100:103], v[180:183]
	ds_read_b128 v[84:87], v220 offset:18432
	s_waitcnt lgkmcnt(8)
	v_mfma_f32_16x16x32_bf16 v[184:187], v[68:71], v[104:107], v[184:187]
	ds_read_b128 v[88:91], v220 offset:20480
	s_waitcnt lgkmcnt(9)
	v_mfma_f32_16x16x32_bf16 v[188:191], v[68:71], v[108:111], v[188:191]
	ds_read_b128 v[92:95], v220 offset:22528
	s_waitcnt lgkmcnt(9)
	v_mfma_f32_16x16x32_bf16 v[192:195], v[72:75], v[96:99], v[192:195]
	s_waitcnt lgkmcnt(9)
	v_mfma_f32_16x16x32_bf16 v[196:199], v[72:75], v[100:103], v[196:199]
	s_waitcnt lgkmcnt(9)
	v_mfma_f32_16x16x32_bf16 v[200:203], v[72:75], v[104:107], v[200:203]
	s_waitcnt lgkmcnt(9)
	v_mfma_f32_16x16x32_bf16 v[204:207], v[72:75], v[108:111], v[204:207]
	s_waitcnt vmcnt(0) lgkmcnt(0)
	s_barrier
	s_add_u32 m0, s38, 16384
	s_nop 0
	global_load_lds_dwordx4 v226, s[100:101]
	s_waitcnt lgkmcnt(8)
	v_mfma_f32_16x16x32_bf16 v[208:211], v[76:79], v[96:99], v[208:211]
	s_add_u32 m0, s38, 20480
	s_nop 0
	global_load_lds_dwordx4 v228, s[100:101]
	s_waitcnt lgkmcnt(8)
	v_mfma_f32_16x16x32_bf16 v[212:215], v[76:79], v[100:103], v[212:215]
	s_add_u32 m0, s38, 24576
	s_nop 0
	global_load_lds_dwordx4 v244, s[100:101]
	s_waitcnt lgkmcnt(8)
	v_mfma_f32_16x16x32_bf16 v[216:219], v[76:79], v[104:107], v[216:219]
	s_add_u32 m0, s38, 28672
	s_nop 0
	global_load_lds_dwordx4 v245, s[100:101]
	s_add_u32 s100, s100, 128
	s_addc_u32 s101, s101, 0
	s_waitcnt lgkmcnt(8)
	v_mfma_f32_16x16x32_bf16 v[230:233], v[76:79], v[108:111], v[230:233]
	s_add_u32 m0, s38, 49152
	s_nop 0
	global_load_lds_dwordx4 v226, s[4:5]
	s_waitcnt lgkmcnt(6)
	v_mfma_f32_16x16x32_bf16 v[160:163], v[80:83], v[112:115], v[160:163]
	ds_read_b128 v[64:67], v151 offset:0
	s_add_u32 m0, s38, 53248
	s_nop 0
	global_load_lds_dwordx4 v228, s[4:5]
	s_waitcnt lgkmcnt(6)
	v_mfma_f32_16x16x32_bf16 v[164:167], v[80:83], v[116:119], v[164:167]
	ds_read_b128 v[96:99], v222 offset:32768
	s_add_u32 m0, s38, 57344
	s_nop 0
	global_load_lds_dwordx4 v244, s[4:5]
	s_waitcnt lgkmcnt(6)
	v_mfma_f32_16x16x32_bf16 v[168:171], v[80:83], v[120:123], v[168:171]
	ds_read_b128 v[100:103], v222 offset:34816
	s_add_u32 m0, s38, 61440
	s_nop 0
	global_load_lds_dwordx4 v245, s[4:5]
	s_add_u32 s4, s4, 128
	s_addc_u32 s5, s5, 0
	s_waitcnt lgkmcnt(6)
	v_mfma_f32_16x16x32_bf16 v[172:175], v[80:83], v[124:127], v[172:175]
	ds_read_b128 v[104:107], v222 offset:36864
	s_waitcnt lgkmcnt(6)
	v_mfma_f32_16x16x32_bf16 v[176:179], v[84:87], v[112:115], v[176:179]
	ds_read_b128 v[108:111], v222 offset:38912
	s_waitcnt lgkmcnt(7)
	v_mfma_f32_16x16x32_bf16 v[180:183], v[84:87], v[116:119], v[180:183]
	ds_read_b128 v[68:71], v151 offset:2048
	s_waitcnt lgkmcnt(8)
	v_mfma_f32_16x16x32_bf16 v[184:187], v[84:87], v[120:123], v[184:187]
	ds_read_b128 v[72:75], v151 offset:4096
	s_waitcnt lgkmcnt(9)
	v_mfma_f32_16x16x32_bf16 v[188:191], v[84:87], v[124:127], v[188:191]
	ds_read_b128 v[76:79], v151 offset:6144
	s_waitcnt lgkmcnt(9)
	v_mfma_f32_16x16x32_bf16 v[192:195], v[88:91], v[112:115], v[192:195]
	s_waitcnt lgkmcnt(9)
	v_mfma_f32_16x16x32_bf16 v[196:199], v[88:91], v[116:119], v[196:199]
	s_waitcnt lgkmcnt(9)
	v_mfma_f32_16x16x32_bf16 v[200:203], v[88:91], v[120:123], v[200:203]
	s_waitcnt lgkmcnt(9)
	v_mfma_f32_16x16x32_bf16 v[204:207], v[88:91], v[124:127], v[204:207]
	s_waitcnt lgkmcnt(8)
	v_mfma_f32_16x16x32_bf16 v[208:211], v[92:95], v[112:115], v[208:211]
	s_waitcnt lgkmcnt(8)
	v_mfma_f32_16x16x32_bf16 v[212:215], v[92:95], v[116:119], v[212:215]
	s_waitcnt lgkmcnt(8)
	v_mfma_f32_16x16x32_bf16 v[216:219], v[92:95], v[120:123], v[216:219]
	s_waitcnt lgkmcnt(8)
	v_mfma_f32_16x16x32_bf16 v[230:233], v[92:95], v[124:127], v[230:233]
	s_waitcnt lgkmcnt(6)
	v_mfma_f32_16x16x32_bf16 v[0:3], v[64:67], v[96:99], v[0:3]
	ds_read_b128 v[80:83], v220 offset:0
	s_waitcnt lgkmcnt(6)
	v_mfma_f32_16x16x32_bf16 v[4:7], v[64:67], v[100:103], v[4:7]
	ds_read_b128 v[112:115], v224 offset:32768
	s_waitcnt lgkmcnt(6)
	v_mfma_f32_16x16x32_bf16 v[8:11], v[64:67], v[104:107], v[8:11]
	ds_read_b128 v[116:119], v224 offset:34816
	s_waitcnt lgkmcnt(6)
	v_mfma_f32_16x16x32_bf16 v[12:15], v[64:67], v[108:111], v[12:15]
	ds_read_b128 v[120:123], v224 offset:36864
	s_waitcnt lgkmcnt(6)
	v_mfma_f32_16x16x32_bf16 v[16:19], v[68:71], v[96:99], v[16:19]
	ds_read_b128 v[124:127], v224 offset:38912
	s_waitcnt lgkmcnt(7)
	v_mfma_f32_16x16x32_bf16 v[20:23], v[68:71], v[100:103], v[20:23]
	ds_read_b128 v[84:87], v220 offset:2048
	s_waitcnt lgkmcnt(8)
	v_mfma_f32_16x16x32_bf16 v[24:27], v[68:71], v[104:107], v[24:27]
	ds_read_b128 v[88:91], v220 offset:4096
	s_waitcnt lgkmcnt(9)
	v_mfma_f32_16x16x32_bf16 v[28:31], v[68:71], v[108:111], v[28:31]
	ds_read_b128 v[92:95], v220 offset:6144
	s_waitcnt lgkmcnt(9)
	v_mfma_f32_16x16x32_bf16 v[32:35], v[72:75], v[96:99], v[32:35]
	s_waitcnt lgkmcnt(9)
	v_mfma_f32_16x16x32_bf16 v[36:39], v[72:75], v[100:103], v[36:39]
	s_waitcnt lgkmcnt(9)
	v_mfma_f32_16x16x32_bf16 v[40:43], v[72:75], v[104:107], v[40:43]
	s_waitcnt lgkmcnt(9)
	v_mfma_f32_16x16x32_bf16 v[44:47], v[72:75], v[108:111], v[44:47]
	s_waitcnt vmcnt(4) lgkmcnt(0)
	s_barrier
	s_add_u32 m0, s38, 0
	s_nop 0
	global_load_lds_dwordx4 v226, s[98:99]
	s_waitcnt lgkmcnt(8)
	v_mfma_f32_16x16x32_bf16 v[48:51], v[76:79], v[96:99], v[48:51]
	s_add_u32 m0, s38, 4096
	s_nop 0
	global_load_lds_dwordx4 v228, s[98:99]
	s_waitcnt lgkmcnt(8)
	v_mfma_f32_16x16x32_bf16 v[52:55], v[76:79], v[100:103], v[52:55]
	s_add_u32 m0, s38, 8192
	s_nop 0
	global_load_lds_dwordx4 v244, s[98:99]
	s_waitcnt lgkmcnt(8)
	v_mfma_f32_16x16x32_bf16 v[56:59], v[76:79], v[104:107], v[56:59]
	s_add_u32 m0, s38, 12288
	s_nop 0
	global_load_lds_dwordx4 v245, s[98:99]
	s_add_u32 s98, s98, 128
	s_addc_u32 s99, s99, 0
	s_waitcnt lgkmcnt(8)
	v_mfma_f32_16x16x32_bf16 v[60:63], v[76:79], v[108:111], v[60:63]
	s_waitcnt lgkmcnt(6)
	v_mfma_f32_16x16x32_bf16 v[0:3], v[80:83], v[112:115], v[0:3]
	ds_read_b128 v[64:67], v151 offset:16384
	s_waitcnt lgkmcnt(6)
	v_mfma_f32_16x16x32_bf16 v[4:7], v[80:83], v[116:119], v[4:7]
	ds_read_b128 v[96:99], v222 offset:32768
	s_waitcnt lgkmcnt(6)
	v_mfma_f32_16x16x32_bf16 v[8:11], v[80:83], v[120:123], v[8:11]
	ds_read_b128 v[100:103], v222 offset:34816
	s_waitcnt lgkmcnt(6)
	v_mfma_f32_16x16x32_bf16 v[12:15], v[80:83], v[124:127], v[12:15]
	ds_read_b128 v[104:107], v222 offset:36864
	s_waitcnt lgkmcnt(6)
	v_mfma_f32_16x16x32_bf16 v[16:19], v[84:87], v[112:115], v[16:19]
	ds_read_b128 v[108:111], v222 offset:38912
	s_waitcnt lgkmcnt(7)
	v_mfma_f32_16x16x32_bf16 v[20:23], v[84:87], v[116:119], v[20:23]
	ds_read_b128 v[68:71], v151 offset:18432
	s_waitcnt lgkmcnt(8)
	v_mfma_f32_16x16x32_bf16 v[24:27], v[84:87], v[120:123], v[24:27]
	ds_read_b128 v[72:75], v151 offset:20480
	s_waitcnt lgkmcnt(9)
	v_mfma_f32_16x16x32_bf16 v[28:31], v[84:87], v[124:127], v[28:31]
	ds_read_b128 v[76:79], v151 offset:22528
	s_waitcnt lgkmcnt(9)
	v_mfma_f32_16x16x32_bf16 v[32:35], v[88:91], v[112:115], v[32:35]
	s_waitcnt lgkmcnt(9)
	v_mfma_f32_16x16x32_bf16 v[36:39], v[88:91], v[116:119], v[36:39]
	s_waitcnt lgkmcnt(9)
	v_mfma_f32_16x16x32_bf16 v[40:43], v[88:91], v[120:123], v[40:43]
	s_waitcnt lgkmcnt(9)
	v_mfma_f32_16x16x32_bf16 v[44:47], v[88:91], v[124:127], v[44:47]
	s_waitcnt lgkmcnt(8)
	v_mfma_f32_16x16x32_bf16 v[48:51], v[92:95], v[112:115], v[48:51]
	s_waitcnt lgkmcnt(8)
	v_mfma_f32_16x16x32_bf16 v[52:55], v[92:95], v[116:119], v[52:55]
	s_waitcnt lgkmcnt(8)
	v_mfma_f32_16x16x32_bf16 v[56:59], v[92:95], v[120:123], v[56:59]
	s_waitcnt lgkmcnt(8)
	v_mfma_f32_16x16x32_bf16 v[60:63], v[92:95], v[124:127], v[60:63]
	s_waitcnt lgkmcnt(6)
	v_mfma_f32_16x16x32_bf16 v[160:163], v[64:67], v[96:99], v[160:163]
	ds_read_b128 v[80:83], v220 offset:16384
	s_waitcnt lgkmcnt(6)
	v_mfma_f32_16x16x32_bf16 v[164:167], v[64:67], v[100:103], v[164:167]
	ds_read_b128 v[112:115], v224 offset:32768
	s_waitcnt lgkmcnt(6)
	v_mfma_f32_16x16x32_bf16 v[168:171], v[64:67], v[104:107], v[168:171]
	ds_read_b128 v[116:119], v224 offset:34816
	s_waitcnt lgkmcnt(6)
	v_mfma_f32_16x16x32_bf16 v[172:175], v[64:67], v[108:111], v[172:175]
	ds_read_b128 v[120:123], v224 offset:36864
	s_waitcnt lgkmcnt(6)
	v_mfma_f32_16x16x32_bf16 v[176:179], v[68:71], v[96:99], v[176:179]
	ds_read_b128 v[124:127], v224 offset:38912
	s_waitcnt lgkmcnt(7)
	v_mfma_f32_16x16x32_bf16 v[180:183], v[68:71], v[100:103], v[180:183]
	ds_read_b128 v[84:87], v220 offset:18432
	s_waitcnt lgkmcnt(8)
	v_mfma_f32_16x16x32_bf16 v[184:187], v[68:71], v[104:107], v[184:187]
	ds_read_b128 v[88:91], v220 offset:20480
	s_waitcnt lgkmcnt(9)
	v_mfma_f32_16x16x32_bf16 v[188:191], v[68:71], v[108:111], v[188:191]
	ds_read_b128 v[92:95], v220 offset:22528
	s_waitcnt lgkmcnt(9)
	v_mfma_f32_16x16x32_bf16 v[192:195], v[72:75], v[96:99], v[192:195]
	s_waitcnt lgkmcnt(9)
	v_mfma_f32_16x16x32_bf16 v[196:199], v[72:75], v[100:103], v[196:199]
	s_waitcnt lgkmcnt(9)
	v_mfma_f32_16x16x32_bf16 v[200:203], v[72:75], v[104:107], v[200:203]
	s_waitcnt lgkmcnt(9)
	v_mfma_f32_16x16x32_bf16 v[204:207], v[72:75], v[108:111], v[204:207]
	s_waitcnt vmcnt(0) lgkmcnt(0)
	s_barrier
	s_add_u32 m0, s38, 16384
	s_nop 0
	global_load_lds_dwordx4 v226, s[100:101]
	s_waitcnt lgkmcnt(8)
	v_mfma_f32_16x16x32_bf16 v[208:211], v[76:79], v[96:99], v[208:211]
	s_add_u32 m0, s38, 20480
	s_nop 0
	global_load_lds_dwordx4 v228, s[100:101]
	s_waitcnt lgkmcnt(8)
	v_mfma_f32_16x16x32_bf16 v[212:215], v[76:79], v[100:103], v[212:215]
	s_add_u32 m0, s38, 24576
	s_nop 0
	global_load_lds_dwordx4 v244, s[100:101]
	s_waitcnt lgkmcnt(8)
	v_mfma_f32_16x16x32_bf16 v[216:219], v[76:79], v[104:107], v[216:219]
	s_add_u32 m0, s38, 28672
	s_nop 0
	global_load_lds_dwordx4 v245, s[100:101]
	s_add_u32 s100, s100, 128
	s_addc_u32 s101, s101, 0
	s_waitcnt lgkmcnt(8)
	v_mfma_f32_16x16x32_bf16 v[230:233], v[76:79], v[108:111], v[230:233]
	s_add_u32 m0, s38, 32768
	s_nop 0
	global_load_lds_dwordx4 v226, s[4:5]
	s_waitcnt lgkmcnt(6)
	v_mfma_f32_16x16x32_bf16 v[160:163], v[80:83], v[112:115], v[160:163]
	ds_read_b128 v[64:67], v151 offset:0
	s_add_u32 m0, s38, 36864
	s_nop 0
	global_load_lds_dwordx4 v228, s[4:5]
	s_waitcnt lgkmcnt(6)
	v_mfma_f32_16x16x32_bf16 v[164:167], v[80:83], v[116:119], v[164:167]
	ds_read_b128 v[96:99], v222 offset:49152
	s_add_u32 m0, s38, 40960
	s_nop 0
	global_load_lds_dwordx4 v244, s[4:5]
	s_waitcnt lgkmcnt(6)
	v_mfma_f32_16x16x32_bf16 v[168:171], v[80:83], v[120:123], v[168:171]
	ds_read_b128 v[100:103], v222 offset:51200
	s_add_u32 m0, s38, 45056
	s_nop 0
	global_load_lds_dwordx4 v245, s[4:5]
	s_add_u32 s4, s4, 128
	s_addc_u32 s5, s5, 0
	s_waitcnt lgkmcnt(6)
	v_mfma_f32_16x16x32_bf16 v[172:175], v[80:83], v[124:127], v[172:175]
	ds_read_b128 v[104:107], v222 offset:53248
	s_waitcnt lgkmcnt(6)
	v_mfma_f32_16x16x32_bf16 v[176:179], v[84:87], v[112:115], v[176:179]
	ds_read_b128 v[108:111], v222 offset:55296
	s_waitcnt lgkmcnt(7)
	v_mfma_f32_16x16x32_bf16 v[180:183], v[84:87], v[116:119], v[180:183]
	ds_read_b128 v[68:71], v151 offset:2048
	s_waitcnt lgkmcnt(8)
	v_mfma_f32_16x16x32_bf16 v[184:187], v[84:87], v[120:123], v[184:187]
	ds_read_b128 v[72:75], v151 offset:4096
	s_waitcnt lgkmcnt(9)
	v_mfma_f32_16x16x32_bf16 v[188:191], v[84:87], v[124:127], v[188:191]
	ds_read_b128 v[76:79], v151 offset:6144
	s_waitcnt lgkmcnt(9)
	v_mfma_f32_16x16x32_bf16 v[192:195], v[88:91], v[112:115], v[192:195]
	s_waitcnt lgkmcnt(9)
	v_mfma_f32_16x16x32_bf16 v[196:199], v[88:91], v[116:119], v[196:199]
	s_waitcnt lgkmcnt(9)
	v_mfma_f32_16x16x32_bf16 v[200:203], v[88:91], v[120:123], v[200:203]
	s_waitcnt lgkmcnt(9)
	v_mfma_f32_16x16x32_bf16 v[204:207], v[88:91], v[124:127], v[204:207]
	s_waitcnt lgkmcnt(8)
	v_mfma_f32_16x16x32_bf16 v[208:211], v[92:95], v[112:115], v[208:211]
	s_waitcnt lgkmcnt(8)
	v_mfma_f32_16x16x32_bf16 v[212:215], v[92:95], v[116:119], v[212:215]
	s_waitcnt lgkmcnt(8)
	v_mfma_f32_16x16x32_bf16 v[216:219], v[92:95], v[120:123], v[216:219]
	s_waitcnt lgkmcnt(8)
	v_mfma_f32_16x16x32_bf16 v[230:233], v[92:95], v[124:127], v[230:233]
	s_waitcnt lgkmcnt(6)
	v_mfma_f32_16x16x32_bf16 v[0:3], v[64:67], v[96:99], v[0:3]
	ds_read_b128 v[80:83], v220 offset:0
	s_waitcnt lgkmcnt(6)
	v_mfma_f32_16x16x32_bf16 v[4:7], v[64:67], v[100:103], v[4:7]
	ds_read_b128 v[112:115], v224 offset:49152
	s_waitcnt lgkmcnt(6)
	v_mfma_f32_16x16x32_bf16 v[8:11], v[64:67], v[104:107], v[8:11]
	ds_read_b128 v[116:119], v224 offset:51200
	s_waitcnt lgkmcnt(6)
	v_mfma_f32_16x16x32_bf16 v[12:15], v[64:67], v[108:111], v[12:15]
	ds_read_b128 v[120:123], v224 offset:53248
	s_waitcnt lgkmcnt(6)
	v_mfma_f32_16x16x32_bf16 v[16:19], v[68:71], v[96:99], v[16:19]
	ds_read_b128 v[124:127], v224 offset:55296
	s_waitcnt lgkmcnt(7)
	v_mfma_f32_16x16x32_bf16 v[20:23], v[68:71], v[100:103], v[20:23]
	ds_read_b128 v[84:87], v220 offset:2048
	s_waitcnt lgkmcnt(8)
	v_mfma_f32_16x16x32_bf16 v[24:27], v[68:71], v[104:107], v[24:27]
	ds_read_b128 v[88:91], v220 offset:4096
	s_waitcnt lgkmcnt(9)
	v_mfma_f32_16x16x32_bf16 v[28:31], v[68:71], v[108:111], v[28:31]
	ds_read_b128 v[92:95], v220 offset:6144
	s_waitcnt lgkmcnt(9)
	v_mfma_f32_16x16x32_bf16 v[32:35], v[72:75], v[96:99], v[32:35]
	s_waitcnt lgkmcnt(9)
	v_mfma_f32_16x16x32_bf16 v[36:39], v[72:75], v[100:103], v[36:39]
	s_waitcnt lgkmcnt(9)
	v_mfma_f32_16x16x32_bf16 v[40:43], v[72:75], v[104:107], v[40:43]
	s_waitcnt lgkmcnt(9)
	v_mfma_f32_16x16x32_bf16 v[44:47], v[72:75], v[108:111], v[44:47]
	s_waitcnt vmcnt(4) lgkmcnt(0)
	s_barrier
	s_add_u32 m0, s38, 0
	s_nop 0
	global_load_lds_dwordx4 v226, s[98:99]
	s_waitcnt lgkmcnt(8)
	v_mfma_f32_16x16x32_bf16 v[48:51], v[76:79], v[96:99], v[48:51]
	s_add_u32 m0, s38, 4096
	s_nop 0
	global_load_lds_dwordx4 v228, s[98:99]
	s_waitcnt lgkmcnt(8)
	v_mfma_f32_16x16x32_bf16 v[52:55], v[76:79], v[100:103], v[52:55]
	s_add_u32 m0, s38, 8192
	s_nop 0
	global_load_lds_dwordx4 v244, s[98:99]
	s_waitcnt lgkmcnt(8)
	v_mfma_f32_16x16x32_bf16 v[56:59], v[76:79], v[104:107], v[56:59]
	s_add_u32 m0, s38, 12288
	s_nop 0
	global_load_lds_dwordx4 v245, s[98:99]
	s_add_u32 s98, s98, 128
	s_addc_u32 s99, s99, 0
	s_waitcnt lgkmcnt(8)
	v_mfma_f32_16x16x32_bf16 v[60:63], v[76:79], v[108:111], v[60:63]
	s_waitcnt lgkmcnt(6)
	v_mfma_f32_16x16x32_bf16 v[0:3], v[80:83], v[112:115], v[0:3]
	ds_read_b128 v[64:67], v151 offset:16384
	s_waitcnt lgkmcnt(6)
	v_mfma_f32_16x16x32_bf16 v[4:7], v[80:83], v[116:119], v[4:7]
	ds_read_b128 v[96:99], v222 offset:49152
	s_waitcnt lgkmcnt(6)
	v_mfma_f32_16x16x32_bf16 v[8:11], v[80:83], v[120:123], v[8:11]
	ds_read_b128 v[100:103], v222 offset:51200
	s_waitcnt lgkmcnt(6)
	v_mfma_f32_16x16x32_bf16 v[12:15], v[80:83], v[124:127], v[12:15]
	ds_read_b128 v[104:107], v222 offset:53248
	s_waitcnt lgkmcnt(6)
	v_mfma_f32_16x16x32_bf16 v[16:19], v[84:87], v[112:115], v[16:19]
	ds_read_b128 v[108:111], v222 offset:55296
	s_waitcnt lgkmcnt(7)
	v_mfma_f32_16x16x32_bf16 v[20:23], v[84:87], v[116:119], v[20:23]
	ds_read_b128 v[68:71], v151 offset:18432
	s_waitcnt lgkmcnt(8)
	v_mfma_f32_16x16x32_bf16 v[24:27], v[84:87], v[120:123], v[24:27]
	ds_read_b128 v[72:75], v151 offset:20480
	s_waitcnt lgkmcnt(9)
	v_mfma_f32_16x16x32_bf16 v[28:31], v[84:87], v[124:127], v[28:31]
	ds_read_b128 v[76:79], v151 offset:22528
	s_waitcnt lgkmcnt(9)
	v_mfma_f32_16x16x32_bf16 v[32:35], v[88:91], v[112:115], v[32:35]
	s_waitcnt lgkmcnt(9)
	v_mfma_f32_16x16x32_bf16 v[36:39], v[88:91], v[116:119], v[36:39]
	s_waitcnt lgkmcnt(9)
	v_mfma_f32_16x16x32_bf16 v[40:43], v[88:91], v[120:123], v[40:43]
	s_waitcnt lgkmcnt(9)
	v_mfma_f32_16x16x32_bf16 v[44:47], v[88:91], v[124:127], v[44:47]
	s_waitcnt lgkmcnt(8)
	v_mfma_f32_16x16x32_bf16 v[48:51], v[92:95], v[112:115], v[48:51]
	s_waitcnt lgkmcnt(8)
	v_mfma_f32_16x16x32_bf16 v[52:55], v[92:95], v[116:119], v[52:55]
	s_waitcnt lgkmcnt(8)
	v_mfma_f32_16x16x32_bf16 v[56:59], v[92:95], v[120:123], v[56:59]
	s_waitcnt lgkmcnt(8)
	v_mfma_f32_16x16x32_bf16 v[60:63], v[92:95], v[124:127], v[60:63]
	s_waitcnt lgkmcnt(6)
	v_mfma_f32_16x16x32_bf16 v[160:163], v[64:67], v[96:99], v[160:163]
	ds_read_b128 v[80:83], v220 offset:16384
	s_waitcnt lgkmcnt(6)
	v_mfma_f32_16x16x32_bf16 v[164:167], v[64:67], v[100:103], v[164:167]
	ds_read_b128 v[112:115], v224 offset:49152
	s_waitcnt lgkmcnt(6)
	v_mfma_f32_16x16x32_bf16 v[168:171], v[64:67], v[104:107], v[168:171]
	ds_read_b128 v[116:119], v224 offset:51200
	s_waitcnt lgkmcnt(6)
	v_mfma_f32_16x16x32_bf16 v[172:175], v[64:67], v[108:111], v[172:175]
	ds_read_b128 v[120:123], v224 offset:53248
	s_waitcnt lgkmcnt(6)
	v_mfma_f32_16x16x32_bf16 v[176:179], v[68:71], v[96:99], v[176:179]
	ds_read_b128 v[124:127], v224 offset:55296
	s_waitcnt lgkmcnt(7)
	v_mfma_f32_16x16x32_bf16 v[180:183], v[68:71], v[100:103], v[180:183]
	ds_read_b128 v[84:87], v220 offset:18432
	s_waitcnt lgkmcnt(8)
	v_mfma_f32_16x16x32_bf16 v[184:187], v[68:71], v[104:107], v[184:187]
	ds_read_b128 v[88:91], v220 offset:20480
	s_waitcnt lgkmcnt(9)
	v_mfma_f32_16x16x32_bf16 v[188:191], v[68:71], v[108:111], v[188:191]
	ds_read_b128 v[92:95], v220 offset:22528
	s_waitcnt lgkmcnt(9)
	v_mfma_f32_16x16x32_bf16 v[192:195], v[72:75], v[96:99], v[192:195]
	s_waitcnt lgkmcnt(9)
	v_mfma_f32_16x16x32_bf16 v[196:199], v[72:75], v[100:103], v[196:199]
	s_waitcnt lgkmcnt(9)
	v_mfma_f32_16x16x32_bf16 v[200:203], v[72:75], v[104:107], v[200:203]
	s_waitcnt lgkmcnt(9)
	v_mfma_f32_16x16x32_bf16 v[204:207], v[72:75], v[108:111], v[204:207]
	s_waitcnt vmcnt(0) lgkmcnt(0)
	s_barrier
	s_add_u32 m0, s38, 16384
	s_nop 0
	global_load_lds_dwordx4 v226, s[100:101]
	s_waitcnt lgkmcnt(8)
	v_mfma_f32_16x16x32_bf16 v[208:211], v[76:79], v[96:99], v[208:211]
	s_add_u32 m0, s38, 20480
	s_nop 0
	global_load_lds_dwordx4 v228, s[100:101]
	s_waitcnt lgkmcnt(8)
	v_mfma_f32_16x16x32_bf16 v[212:215], v[76:79], v[100:103], v[212:215]
	s_add_u32 m0, s38, 24576
	s_nop 0
	global_load_lds_dwordx4 v244, s[100:101]
	s_waitcnt lgkmcnt(8)
	v_mfma_f32_16x16x32_bf16 v[216:219], v[76:79], v[104:107], v[216:219]
	s_add_u32 m0, s38, 28672
	s_nop 0
	global_load_lds_dwordx4 v245, s[100:101]
	s_add_u32 s100, s100, 128
	s_addc_u32 s101, s101, 0
	s_waitcnt lgkmcnt(8)
	v_mfma_f32_16x16x32_bf16 v[230:233], v[76:79], v[108:111], v[230:233]
	s_add_u32 m0, s38, 49152
	s_nop 0
	global_load_lds_dwordx4 v226, s[4:5]
	s_waitcnt lgkmcnt(6)
	v_mfma_f32_16x16x32_bf16 v[160:163], v[80:83], v[112:115], v[160:163]
	ds_read_b128 v[64:67], v151 offset:0
	s_add_u32 m0, s38, 53248
	s_nop 0
	global_load_lds_dwordx4 v228, s[4:5]
	s_waitcnt lgkmcnt(6)
	v_mfma_f32_16x16x32_bf16 v[164:167], v[80:83], v[116:119], v[164:167]
	ds_read_b128 v[96:99], v222 offset:32768
	s_add_u32 m0, s38, 57344
	s_nop 0
	global_load_lds_dwordx4 v244, s[4:5]
	s_waitcnt lgkmcnt(6)
	v_mfma_f32_16x16x32_bf16 v[168:171], v[80:83], v[120:123], v[168:171]
	ds_read_b128 v[100:103], v222 offset:34816
	s_add_u32 m0, s38, 61440
	s_nop 0
	global_load_lds_dwordx4 v245, s[4:5]
	s_add_u32 s4, s4, 128
	s_addc_u32 s5, s5, 0
	s_waitcnt lgkmcnt(6)
	v_mfma_f32_16x16x32_bf16 v[172:175], v[80:83], v[124:127], v[172:175]
	ds_read_b128 v[104:107], v222 offset:36864
	s_waitcnt lgkmcnt(6)
	v_mfma_f32_16x16x32_bf16 v[176:179], v[84:87], v[112:115], v[176:179]
	ds_read_b128 v[108:111], v222 offset:38912
	s_waitcnt lgkmcnt(7)
	v_mfma_f32_16x16x32_bf16 v[180:183], v[84:87], v[116:119], v[180:183]
	ds_read_b128 v[68:71], v151 offset:2048
	s_waitcnt lgkmcnt(8)
	v_mfma_f32_16x16x32_bf16 v[184:187], v[84:87], v[120:123], v[184:187]
	ds_read_b128 v[72:75], v151 offset:4096
	s_waitcnt lgkmcnt(9)
	v_mfma_f32_16x16x32_bf16 v[188:191], v[84:87], v[124:127], v[188:191]
	ds_read_b128 v[76:79], v151 offset:6144
	s_waitcnt lgkmcnt(9)
	v_mfma_f32_16x16x32_bf16 v[192:195], v[88:91], v[112:115], v[192:195]
	s_waitcnt lgkmcnt(9)
	v_mfma_f32_16x16x32_bf16 v[196:199], v[88:91], v[116:119], v[196:199]
	s_waitcnt lgkmcnt(9)
	v_mfma_f32_16x16x32_bf16 v[200:203], v[88:91], v[120:123], v[200:203]
	s_waitcnt lgkmcnt(9)
	v_mfma_f32_16x16x32_bf16 v[204:207], v[88:91], v[124:127], v[204:207]
	s_waitcnt lgkmcnt(8)
	v_mfma_f32_16x16x32_bf16 v[208:211], v[92:95], v[112:115], v[208:211]
	s_waitcnt lgkmcnt(8)
	v_mfma_f32_16x16x32_bf16 v[212:215], v[92:95], v[116:119], v[212:215]
	s_waitcnt lgkmcnt(8)
	v_mfma_f32_16x16x32_bf16 v[216:219], v[92:95], v[120:123], v[216:219]
	s_waitcnt lgkmcnt(8)
	v_mfma_f32_16x16x32_bf16 v[230:233], v[92:95], v[124:127], v[230:233]
	s_waitcnt lgkmcnt(6)
	v_mfma_f32_16x16x32_bf16 v[0:3], v[64:67], v[96:99], v[0:3]
	ds_read_b128 v[80:83], v220 offset:0
	s_waitcnt lgkmcnt(6)
	v_mfma_f32_16x16x32_bf16 v[4:7], v[64:67], v[100:103], v[4:7]
	ds_read_b128 v[112:115], v224 offset:32768
	s_waitcnt lgkmcnt(6)
	v_mfma_f32_16x16x32_bf16 v[8:11], v[64:67], v[104:107], v[8:11]
	ds_read_b128 v[116:119], v224 offset:34816
	s_waitcnt lgkmcnt(6)
	v_mfma_f32_16x16x32_bf16 v[12:15], v[64:67], v[108:111], v[12:15]
	ds_read_b128 v[120:123], v224 offset:36864
	s_waitcnt lgkmcnt(6)
	v_mfma_f32_16x16x32_bf16 v[16:19], v[68:71], v[96:99], v[16:19]
	ds_read_b128 v[124:127], v224 offset:38912
	s_waitcnt lgkmcnt(7)
	v_mfma_f32_16x16x32_bf16 v[20:23], v[68:71], v[100:103], v[20:23]
	ds_read_b128 v[84:87], v220 offset:2048
	s_waitcnt lgkmcnt(8)
	v_mfma_f32_16x16x32_bf16 v[24:27], v[68:71], v[104:107], v[24:27]
	ds_read_b128 v[88:91], v220 offset:4096
	s_waitcnt lgkmcnt(9)
	v_mfma_f32_16x16x32_bf16 v[28:31], v[68:71], v[108:111], v[28:31]
	ds_read_b128 v[92:95], v220 offset:6144
	s_waitcnt lgkmcnt(9)
	v_mfma_f32_16x16x32_bf16 v[32:35], v[72:75], v[96:99], v[32:35]
	s_waitcnt lgkmcnt(9)
	v_mfma_f32_16x16x32_bf16 v[36:39], v[72:75], v[100:103], v[36:39]
	s_waitcnt lgkmcnt(9)
	v_mfma_f32_16x16x32_bf16 v[40:43], v[72:75], v[104:107], v[40:43]
	s_waitcnt lgkmcnt(9)
	v_mfma_f32_16x16x32_bf16 v[44:47], v[72:75], v[108:111], v[44:47]
	s_waitcnt vmcnt(4) lgkmcnt(0)
	s_barrier
	s_add_u32 m0, s38, 0
	s_nop 0
	global_load_lds_dwordx4 v226, s[98:99]
	s_waitcnt lgkmcnt(8)
	v_mfma_f32_16x16x32_bf16 v[48:51], v[76:79], v[96:99], v[48:51]
	s_add_u32 m0, s38, 4096
	s_nop 0
	global_load_lds_dwordx4 v228, s[98:99]
	s_waitcnt lgkmcnt(8)
	v_mfma_f32_16x16x32_bf16 v[52:55], v[76:79], v[100:103], v[52:55]
	s_add_u32 m0, s38, 8192
	s_nop 0
	global_load_lds_dwordx4 v244, s[98:99]
	s_waitcnt lgkmcnt(8)
	v_mfma_f32_16x16x32_bf16 v[56:59], v[76:79], v[104:107], v[56:59]
	s_add_u32 m0, s38, 12288
	s_nop 0
	global_load_lds_dwordx4 v245, s[98:99]
	s_add_u32 s98, s98, 128
	s_addc_u32 s99, s99, 0
	s_waitcnt lgkmcnt(8)
	v_mfma_f32_16x16x32_bf16 v[60:63], v[76:79], v[108:111], v[60:63]
	s_waitcnt lgkmcnt(6)
	v_mfma_f32_16x16x32_bf16 v[0:3], v[80:83], v[112:115], v[0:3]
	ds_read_b128 v[64:67], v151 offset:16384
	s_waitcnt lgkmcnt(6)
	v_mfma_f32_16x16x32_bf16 v[4:7], v[80:83], v[116:119], v[4:7]
	ds_read_b128 v[96:99], v222 offset:32768
	s_waitcnt lgkmcnt(6)
	v_mfma_f32_16x16x32_bf16 v[8:11], v[80:83], v[120:123], v[8:11]
	ds_read_b128 v[100:103], v222 offset:34816
	s_waitcnt lgkmcnt(6)
	v_mfma_f32_16x16x32_bf16 v[12:15], v[80:83], v[124:127], v[12:15]
	ds_read_b128 v[104:107], v222 offset:36864
	s_waitcnt lgkmcnt(6)
	v_mfma_f32_16x16x32_bf16 v[16:19], v[84:87], v[112:115], v[16:19]
	ds_read_b128 v[108:111], v222 offset:38912
	s_waitcnt lgkmcnt(7)
	v_mfma_f32_16x16x32_bf16 v[20:23], v[84:87], v[116:119], v[20:23]
	ds_read_b128 v[68:71], v151 offset:18432
	s_waitcnt lgkmcnt(8)
	v_mfma_f32_16x16x32_bf16 v[24:27], v[84:87], v[120:123], v[24:27]
	ds_read_b128 v[72:75], v151 offset:20480
	s_waitcnt lgkmcnt(9)
	v_mfma_f32_16x16x32_bf16 v[28:31], v[84:87], v[124:127], v[28:31]
	ds_read_b128 v[76:79], v151 offset:22528
	s_waitcnt lgkmcnt(9)
	v_mfma_f32_16x16x32_bf16 v[32:35], v[88:91], v[112:115], v[32:35]
	s_waitcnt lgkmcnt(9)
	v_mfma_f32_16x16x32_bf16 v[36:39], v[88:91], v[116:119], v[36:39]
	s_waitcnt lgkmcnt(9)
	v_mfma_f32_16x16x32_bf16 v[40:43], v[88:91], v[120:123], v[40:43]
	s_waitcnt lgkmcnt(9)
	v_mfma_f32_16x16x32_bf16 v[44:47], v[88:91], v[124:127], v[44:47]
	s_waitcnt lgkmcnt(8)
	v_mfma_f32_16x16x32_bf16 v[48:51], v[92:95], v[112:115], v[48:51]
	s_waitcnt lgkmcnt(8)
	v_mfma_f32_16x16x32_bf16 v[52:55], v[92:95], v[116:119], v[52:55]
	s_waitcnt lgkmcnt(8)
	v_mfma_f32_16x16x32_bf16 v[56:59], v[92:95], v[120:123], v[56:59]
	s_waitcnt lgkmcnt(8)
	v_mfma_f32_16x16x32_bf16 v[60:63], v[92:95], v[124:127], v[60:63]
	s_waitcnt lgkmcnt(6)
	v_mfma_f32_16x16x32_bf16 v[160:163], v[64:67], v[96:99], v[160:163]
	ds_read_b128 v[80:83], v220 offset:16384
	s_waitcnt lgkmcnt(6)
	v_mfma_f32_16x16x32_bf16 v[164:167], v[64:67], v[100:103], v[164:167]
	ds_read_b128 v[112:115], v224 offset:32768
	s_waitcnt lgkmcnt(6)
	v_mfma_f32_16x16x32_bf16 v[168:171], v[64:67], v[104:107], v[168:171]
	ds_read_b128 v[116:119], v224 offset:34816
	s_waitcnt lgkmcnt(6)
	v_mfma_f32_16x16x32_bf16 v[172:175], v[64:67], v[108:111], v[172:175]
	ds_read_b128 v[120:123], v224 offset:36864
	s_waitcnt lgkmcnt(6)
	v_mfma_f32_16x16x32_bf16 v[176:179], v[68:71], v[96:99], v[176:179]
	ds_read_b128 v[124:127], v224 offset:38912
	s_waitcnt lgkmcnt(7)
	v_mfma_f32_16x16x32_bf16 v[180:183], v[68:71], v[100:103], v[180:183]
	ds_read_b128 v[84:87], v220 offset:18432
	s_waitcnt lgkmcnt(8)
	v_mfma_f32_16x16x32_bf16 v[184:187], v[68:71], v[104:107], v[184:187]
	ds_read_b128 v[88:91], v220 offset:20480
	s_waitcnt lgkmcnt(9)
	v_mfma_f32_16x16x32_bf16 v[188:191], v[68:71], v[108:111], v[188:191]
	ds_read_b128 v[92:95], v220 offset:22528
	s_waitcnt lgkmcnt(9)
	v_mfma_f32_16x16x32_bf16 v[192:195], v[72:75], v[96:99], v[192:195]
	s_waitcnt lgkmcnt(9)
	v_mfma_f32_16x16x32_bf16 v[196:199], v[72:75], v[100:103], v[196:199]
	s_waitcnt lgkmcnt(9)
	v_mfma_f32_16x16x32_bf16 v[200:203], v[72:75], v[104:107], v[200:203]
	s_waitcnt lgkmcnt(9)
	v_mfma_f32_16x16x32_bf16 v[204:207], v[72:75], v[108:111], v[204:207]
	s_waitcnt vmcnt(0) lgkmcnt(0)
	s_barrier
	s_add_u32 m0, s38, 16384
	s_nop 0
	global_load_lds_dwordx4 v226, s[100:101]
	s_waitcnt lgkmcnt(8)
	v_mfma_f32_16x16x32_bf16 v[208:211], v[76:79], v[96:99], v[208:211]
	s_add_u32 m0, s38, 20480
	s_nop 0
	global_load_lds_dwordx4 v228, s[100:101]
	s_waitcnt lgkmcnt(8)
	v_mfma_f32_16x16x32_bf16 v[212:215], v[76:79], v[100:103], v[212:215]
	s_add_u32 m0, s38, 24576
	s_nop 0
	global_load_lds_dwordx4 v244, s[100:101]
	s_waitcnt lgkmcnt(8)
	v_mfma_f32_16x16x32_bf16 v[216:219], v[76:79], v[104:107], v[216:219]
	s_add_u32 m0, s38, 28672
	s_nop 0
	global_load_lds_dwordx4 v245, s[100:101]
	s_add_u32 s100, s100, 128
	s_addc_u32 s101, s101, 0
	s_waitcnt lgkmcnt(8)
	v_mfma_f32_16x16x32_bf16 v[230:233], v[76:79], v[108:111], v[230:233]
	s_add_u32 m0, s38, 32768
	s_nop 0
	global_load_lds_dwordx4 v226, s[4:5]
	s_waitcnt lgkmcnt(6)
	v_mfma_f32_16x16x32_bf16 v[160:163], v[80:83], v[112:115], v[160:163]
	ds_read_b128 v[64:67], v151 offset:0
	s_add_u32 m0, s38, 36864
	s_nop 0
	global_load_lds_dwordx4 v228, s[4:5]
	s_waitcnt lgkmcnt(6)
	v_mfma_f32_16x16x32_bf16 v[164:167], v[80:83], v[116:119], v[164:167]
	ds_read_b128 v[96:99], v222 offset:49152
	s_add_u32 m0, s38, 40960
	s_nop 0
	global_load_lds_dwordx4 v244, s[4:5]
	s_waitcnt lgkmcnt(6)
	v_mfma_f32_16x16x32_bf16 v[168:171], v[80:83], v[120:123], v[168:171]
	ds_read_b128 v[100:103], v222 offset:51200
	s_add_u32 m0, s38, 45056
	s_nop 0
	global_load_lds_dwordx4 v245, s[4:5]
	s_add_u32 s4, s4, 128
	s_addc_u32 s5, s5, 0
	s_waitcnt lgkmcnt(6)
	v_mfma_f32_16x16x32_bf16 v[172:175], v[80:83], v[124:127], v[172:175]
	ds_read_b128 v[104:107], v222 offset:53248
	s_waitcnt lgkmcnt(6)
	v_mfma_f32_16x16x32_bf16 v[176:179], v[84:87], v[112:115], v[176:179]
	ds_read_b128 v[108:111], v222 offset:55296
	s_waitcnt lgkmcnt(7)
	v_mfma_f32_16x16x32_bf16 v[180:183], v[84:87], v[116:119], v[180:183]
	ds_read_b128 v[68:71], v151 offset:2048
	s_waitcnt lgkmcnt(8)
	v_mfma_f32_16x16x32_bf16 v[184:187], v[84:87], v[120:123], v[184:187]
	ds_read_b128 v[72:75], v151 offset:4096
	s_waitcnt lgkmcnt(9)
	v_mfma_f32_16x16x32_bf16 v[188:191], v[84:87], v[124:127], v[188:191]
	ds_read_b128 v[76:79], v151 offset:6144
	s_waitcnt lgkmcnt(9)
	v_mfma_f32_16x16x32_bf16 v[192:195], v[88:91], v[112:115], v[192:195]
	s_waitcnt lgkmcnt(9)
	v_mfma_f32_16x16x32_bf16 v[196:199], v[88:91], v[116:119], v[196:199]
	s_waitcnt lgkmcnt(9)
	v_mfma_f32_16x16x32_bf16 v[200:203], v[88:91], v[120:123], v[200:203]
	s_waitcnt lgkmcnt(9)
	v_mfma_f32_16x16x32_bf16 v[204:207], v[88:91], v[124:127], v[204:207]
	s_waitcnt lgkmcnt(8)
	v_mfma_f32_16x16x32_bf16 v[208:211], v[92:95], v[112:115], v[208:211]
	s_waitcnt lgkmcnt(8)
	v_mfma_f32_16x16x32_bf16 v[212:215], v[92:95], v[116:119], v[212:215]
	s_waitcnt lgkmcnt(8)
	v_mfma_f32_16x16x32_bf16 v[216:219], v[92:95], v[120:123], v[216:219]
	s_waitcnt lgkmcnt(8)
	v_mfma_f32_16x16x32_bf16 v[230:233], v[92:95], v[124:127], v[230:233]
	s_waitcnt lgkmcnt(6)
	v_mfma_f32_16x16x32_bf16 v[0:3], v[64:67], v[96:99], v[0:3]
	ds_read_b128 v[80:83], v220 offset:0
	s_waitcnt lgkmcnt(6)
	v_mfma_f32_16x16x32_bf16 v[4:7], v[64:67], v[100:103], v[4:7]
	ds_read_b128 v[112:115], v224 offset:49152
	s_waitcnt lgkmcnt(6)
	v_mfma_f32_16x16x32_bf16 v[8:11], v[64:67], v[104:107], v[8:11]
	ds_read_b128 v[116:119], v224 offset:51200
	s_waitcnt lgkmcnt(6)
	v_mfma_f32_16x16x32_bf16 v[12:15], v[64:67], v[108:111], v[12:15]
	ds_read_b128 v[120:123], v224 offset:53248
	s_waitcnt lgkmcnt(6)
	v_mfma_f32_16x16x32_bf16 v[16:19], v[68:71], v[96:99], v[16:19]
	ds_read_b128 v[124:127], v224 offset:55296
	s_waitcnt lgkmcnt(7)
	v_mfma_f32_16x16x32_bf16 v[20:23], v[68:71], v[100:103], v[20:23]
	ds_read_b128 v[84:87], v220 offset:2048
	s_waitcnt lgkmcnt(8)
	v_mfma_f32_16x16x32_bf16 v[24:27], v[68:71], v[104:107], v[24:27]
	ds_read_b128 v[88:91], v220 offset:4096
	s_waitcnt lgkmcnt(9)
	v_mfma_f32_16x16x32_bf16 v[28:31], v[68:71], v[108:111], v[28:31]
	ds_read_b128 v[92:95], v220 offset:6144
	s_waitcnt lgkmcnt(9)
	v_mfma_f32_16x16x32_bf16 v[32:35], v[72:75], v[96:99], v[32:35]
	s_waitcnt lgkmcnt(9)
	v_mfma_f32_16x16x32_bf16 v[36:39], v[72:75], v[100:103], v[36:39]
	s_waitcnt lgkmcnt(9)
	v_mfma_f32_16x16x32_bf16 v[40:43], v[72:75], v[104:107], v[40:43]
	s_waitcnt lgkmcnt(9)
	v_mfma_f32_16x16x32_bf16 v[44:47], v[72:75], v[108:111], v[44:47]
	s_waitcnt vmcnt(4) lgkmcnt(0)
	s_barrier
	s_add_u32 m0, s38, 0
	s_nop 0
	global_load_lds_dwordx4 v226, s[98:99]
	s_waitcnt lgkmcnt(8)
	v_mfma_f32_16x16x32_bf16 v[48:51], v[76:79], v[96:99], v[48:51]
	s_add_u32 m0, s38, 4096
	s_nop 0
	global_load_lds_dwordx4 v228, s[98:99]
	s_waitcnt lgkmcnt(8)
	v_mfma_f32_16x16x32_bf16 v[52:55], v[76:79], v[100:103], v[52:55]
	s_add_u32 m0, s38, 8192
	s_nop 0
	global_load_lds_dwordx4 v244, s[98:99]
	s_waitcnt lgkmcnt(8)
	v_mfma_f32_16x16x32_bf16 v[56:59], v[76:79], v[104:107], v[56:59]
	s_add_u32 m0, s38, 12288
	s_nop 0
	global_load_lds_dwordx4 v245, s[98:99]
	s_add_u32 s98, s98, 128
	s_addc_u32 s99, s99, 0
	s_waitcnt lgkmcnt(8)
	v_mfma_f32_16x16x32_bf16 v[60:63], v[76:79], v[108:111], v[60:63]
	s_waitcnt lgkmcnt(6)
	v_mfma_f32_16x16x32_bf16 v[0:3], v[80:83], v[112:115], v[0:3]
	ds_read_b128 v[64:67], v151 offset:16384
	s_waitcnt lgkmcnt(6)
	v_mfma_f32_16x16x32_bf16 v[4:7], v[80:83], v[116:119], v[4:7]
	ds_read_b128 v[96:99], v222 offset:49152
	s_waitcnt lgkmcnt(6)
	v_mfma_f32_16x16x32_bf16 v[8:11], v[80:83], v[120:123], v[8:11]
	ds_read_b128 v[100:103], v222 offset:51200
	s_waitcnt lgkmcnt(6)
	v_mfma_f32_16x16x32_bf16 v[12:15], v[80:83], v[124:127], v[12:15]
	ds_read_b128 v[104:107], v222 offset:53248
	s_waitcnt lgkmcnt(6)
	v_mfma_f32_16x16x32_bf16 v[16:19], v[84:87], v[112:115], v[16:19]
	ds_read_b128 v[108:111], v222 offset:55296
	s_waitcnt lgkmcnt(7)
	v_mfma_f32_16x16x32_bf16 v[20:23], v[84:87], v[116:119], v[20:23]
	ds_read_b128 v[68:71], v151 offset:18432
	s_waitcnt lgkmcnt(8)
	v_mfma_f32_16x16x32_bf16 v[24:27], v[84:87], v[120:123], v[24:27]
	ds_read_b128 v[72:75], v151 offset:20480
	s_waitcnt lgkmcnt(9)
	v_mfma_f32_16x16x32_bf16 v[28:31], v[84:87], v[124:127], v[28:31]
	ds_read_b128 v[76:79], v151 offset:22528
	s_waitcnt lgkmcnt(9)
	v_mfma_f32_16x16x32_bf16 v[32:35], v[88:91], v[112:115], v[32:35]
	s_waitcnt lgkmcnt(9)
	v_mfma_f32_16x16x32_bf16 v[36:39], v[88:91], v[116:119], v[36:39]
	s_waitcnt lgkmcnt(9)
	v_mfma_f32_16x16x32_bf16 v[40:43], v[88:91], v[120:123], v[40:43]
	s_waitcnt lgkmcnt(9)
	v_mfma_f32_16x16x32_bf16 v[44:47], v[88:91], v[124:127], v[44:47]
	s_waitcnt lgkmcnt(8)
	v_mfma_f32_16x16x32_bf16 v[48:51], v[92:95], v[112:115], v[48:51]
	s_waitcnt lgkmcnt(8)
	v_mfma_f32_16x16x32_bf16 v[52:55], v[92:95], v[116:119], v[52:55]
	s_waitcnt lgkmcnt(8)
	v_mfma_f32_16x16x32_bf16 v[56:59], v[92:95], v[120:123], v[56:59]
	s_waitcnt lgkmcnt(8)
	v_mfma_f32_16x16x32_bf16 v[60:63], v[92:95], v[124:127], v[60:63]
	s_waitcnt lgkmcnt(6)
	v_mfma_f32_16x16x32_bf16 v[160:163], v[64:67], v[96:99], v[160:163]
	ds_read_b128 v[80:83], v220 offset:16384
	s_waitcnt lgkmcnt(6)
	v_mfma_f32_16x16x32_bf16 v[164:167], v[64:67], v[100:103], v[164:167]
	ds_read_b128 v[112:115], v224 offset:49152
	s_waitcnt lgkmcnt(6)
	v_mfma_f32_16x16x32_bf16 v[168:171], v[64:67], v[104:107], v[168:171]
	ds_read_b128 v[116:119], v224 offset:51200
	s_waitcnt lgkmcnt(6)
	v_mfma_f32_16x16x32_bf16 v[172:175], v[64:67], v[108:111], v[172:175]
	ds_read_b128 v[120:123], v224 offset:53248
	s_waitcnt lgkmcnt(6)
	v_mfma_f32_16x16x32_bf16 v[176:179], v[68:71], v[96:99], v[176:179]
	ds_read_b128 v[124:127], v224 offset:55296
	s_waitcnt lgkmcnt(7)
	v_mfma_f32_16x16x32_bf16 v[180:183], v[68:71], v[100:103], v[180:183]
	ds_read_b128 v[84:87], v220 offset:18432
	s_waitcnt lgkmcnt(8)
	v_mfma_f32_16x16x32_bf16 v[184:187], v[68:71], v[104:107], v[184:187]
	ds_read_b128 v[88:91], v220 offset:20480
	s_waitcnt lgkmcnt(9)
	v_mfma_f32_16x16x32_bf16 v[188:191], v[68:71], v[108:111], v[188:191]
	ds_read_b128 v[92:95], v220 offset:22528
	s_waitcnt lgkmcnt(9)
	v_mfma_f32_16x16x32_bf16 v[192:195], v[72:75], v[96:99], v[192:195]
	s_waitcnt lgkmcnt(9)
	v_mfma_f32_16x16x32_bf16 v[196:199], v[72:75], v[100:103], v[196:199]
	s_waitcnt lgkmcnt(9)
	v_mfma_f32_16x16x32_bf16 v[200:203], v[72:75], v[104:107], v[200:203]
	s_waitcnt lgkmcnt(9)
	v_mfma_f32_16x16x32_bf16 v[204:207], v[72:75], v[108:111], v[204:207]
	s_waitcnt vmcnt(0) lgkmcnt(0)
	s_barrier
	s_add_u32 m0, s38, 16384
	s_nop 0
	global_load_lds_dwordx4 v226, s[100:101]
	s_waitcnt lgkmcnt(8)
	v_mfma_f32_16x16x32_bf16 v[208:211], v[76:79], v[96:99], v[208:211]
	s_add_u32 m0, s38, 20480
	s_nop 0
	global_load_lds_dwordx4 v228, s[100:101]
	s_waitcnt lgkmcnt(8)
	v_mfma_f32_16x16x32_bf16 v[212:215], v[76:79], v[100:103], v[212:215]
	s_add_u32 m0, s38, 24576
	s_nop 0
	global_load_lds_dwordx4 v244, s[100:101]
	s_waitcnt lgkmcnt(8)
	v_mfma_f32_16x16x32_bf16 v[216:219], v[76:79], v[104:107], v[216:219]
	s_add_u32 m0, s38, 28672
	s_nop 0
	global_load_lds_dwordx4 v245, s[100:101]
	s_add_u32 s100, s100, 128
	s_addc_u32 s101, s101, 0
	s_waitcnt lgkmcnt(8)
	v_mfma_f32_16x16x32_bf16 v[230:233], v[76:79], v[108:111], v[230:233]
	s_add_u32 m0, s38, 49152
	s_nop 0
	global_load_lds_dwordx4 v226, s[4:5]
	s_waitcnt lgkmcnt(6)
	v_mfma_f32_16x16x32_bf16 v[160:163], v[80:83], v[112:115], v[160:163]
	ds_read_b128 v[64:67], v151 offset:0
	s_add_u32 m0, s38, 53248
	s_nop 0
	global_load_lds_dwordx4 v228, s[4:5]
	s_waitcnt lgkmcnt(6)
	v_mfma_f32_16x16x32_bf16 v[164:167], v[80:83], v[116:119], v[164:167]
	ds_read_b128 v[96:99], v222 offset:32768
	s_add_u32 m0, s38, 57344
	s_nop 0
	global_load_lds_dwordx4 v244, s[4:5]
	s_waitcnt lgkmcnt(6)
	v_mfma_f32_16x16x32_bf16 v[168:171], v[80:83], v[120:123], v[168:171]
	ds_read_b128 v[100:103], v222 offset:34816
	s_add_u32 m0, s38, 61440
	s_nop 0
	global_load_lds_dwordx4 v245, s[4:5]
	s_add_u32 s4, s4, 128
	s_addc_u32 s5, s5, 0
	s_waitcnt lgkmcnt(6)
	v_mfma_f32_16x16x32_bf16 v[172:175], v[80:83], v[124:127], v[172:175]
	ds_read_b128 v[104:107], v222 offset:36864
	s_waitcnt lgkmcnt(6)
	v_mfma_f32_16x16x32_bf16 v[176:179], v[84:87], v[112:115], v[176:179]
	ds_read_b128 v[108:111], v222 offset:38912
	s_waitcnt lgkmcnt(7)
	v_mfma_f32_16x16x32_bf16 v[180:183], v[84:87], v[116:119], v[180:183]
	ds_read_b128 v[68:71], v151 offset:2048
	s_waitcnt lgkmcnt(8)
	v_mfma_f32_16x16x32_bf16 v[184:187], v[84:87], v[120:123], v[184:187]
	ds_read_b128 v[72:75], v151 offset:4096
	s_waitcnt lgkmcnt(9)
	v_mfma_f32_16x16x32_bf16 v[188:191], v[84:87], v[124:127], v[188:191]
	ds_read_b128 v[76:79], v151 offset:6144
	s_waitcnt lgkmcnt(9)
	v_mfma_f32_16x16x32_bf16 v[192:195], v[88:91], v[112:115], v[192:195]
	s_waitcnt lgkmcnt(9)
	v_mfma_f32_16x16x32_bf16 v[196:199], v[88:91], v[116:119], v[196:199]
	s_waitcnt lgkmcnt(9)
	v_mfma_f32_16x16x32_bf16 v[200:203], v[88:91], v[120:123], v[200:203]
	s_waitcnt lgkmcnt(9)
	v_mfma_f32_16x16x32_bf16 v[204:207], v[88:91], v[124:127], v[204:207]
	s_waitcnt lgkmcnt(8)
	v_mfma_f32_16x16x32_bf16 v[208:211], v[92:95], v[112:115], v[208:211]
	s_waitcnt lgkmcnt(8)
	v_mfma_f32_16x16x32_bf16 v[212:215], v[92:95], v[116:119], v[212:215]
	s_waitcnt lgkmcnt(8)
	v_mfma_f32_16x16x32_bf16 v[216:219], v[92:95], v[120:123], v[216:219]
	s_waitcnt lgkmcnt(8)
	v_mfma_f32_16x16x32_bf16 v[230:233], v[92:95], v[124:127], v[230:233]
	s_waitcnt lgkmcnt(6)
	v_mfma_f32_16x16x32_bf16 v[0:3], v[64:67], v[96:99], v[0:3]
	ds_read_b128 v[80:83], v220 offset:0
	s_waitcnt lgkmcnt(6)
	v_mfma_f32_16x16x32_bf16 v[4:7], v[64:67], v[100:103], v[4:7]
	ds_read_b128 v[112:115], v224 offset:32768
	s_waitcnt lgkmcnt(6)
	v_mfma_f32_16x16x32_bf16 v[8:11], v[64:67], v[104:107], v[8:11]
	ds_read_b128 v[116:119], v224 offset:34816
	s_waitcnt lgkmcnt(6)
	v_mfma_f32_16x16x32_bf16 v[12:15], v[64:67], v[108:111], v[12:15]
	ds_read_b128 v[120:123], v224 offset:36864
	s_waitcnt lgkmcnt(6)
	v_mfma_f32_16x16x32_bf16 v[16:19], v[68:71], v[96:99], v[16:19]
	ds_read_b128 v[124:127], v224 offset:38912
	s_waitcnt lgkmcnt(7)
	v_mfma_f32_16x16x32_bf16 v[20:23], v[68:71], v[100:103], v[20:23]
	ds_read_b128 v[84:87], v220 offset:2048
	s_waitcnt lgkmcnt(8)
	v_mfma_f32_16x16x32_bf16 v[24:27], v[68:71], v[104:107], v[24:27]
	ds_read_b128 v[88:91], v220 offset:4096
	s_waitcnt lgkmcnt(9)
	v_mfma_f32_16x16x32_bf16 v[28:31], v[68:71], v[108:111], v[28:31]
	ds_read_b128 v[92:95], v220 offset:6144
	s_waitcnt lgkmcnt(9)
	v_mfma_f32_16x16x32_bf16 v[32:35], v[72:75], v[96:99], v[32:35]
	s_waitcnt lgkmcnt(9)
	v_mfma_f32_16x16x32_bf16 v[36:39], v[72:75], v[100:103], v[36:39]
	s_waitcnt lgkmcnt(9)
	v_mfma_f32_16x16x32_bf16 v[40:43], v[72:75], v[104:107], v[40:43]
	s_waitcnt lgkmcnt(9)
	v_mfma_f32_16x16x32_bf16 v[44:47], v[72:75], v[108:111], v[44:47]
	s_waitcnt vmcnt(4) lgkmcnt(0)
	s_barrier
	s_add_u32 m0, s38, 0
	s_nop 0
	global_load_lds_dwordx4 v226, s[98:99]
	s_waitcnt lgkmcnt(8)
	v_mfma_f32_16x16x32_bf16 v[48:51], v[76:79], v[96:99], v[48:51]
	s_add_u32 m0, s38, 4096
	s_nop 0
	global_load_lds_dwordx4 v228, s[98:99]
	s_waitcnt lgkmcnt(8)
	v_mfma_f32_16x16x32_bf16 v[52:55], v[76:79], v[100:103], v[52:55]
	s_add_u32 m0, s38, 8192
	s_nop 0
	global_load_lds_dwordx4 v244, s[98:99]
	s_waitcnt lgkmcnt(8)
	v_mfma_f32_16x16x32_bf16 v[56:59], v[76:79], v[104:107], v[56:59]
	s_add_u32 m0, s38, 12288
	s_nop 0
	global_load_lds_dwordx4 v245, s[98:99]
	s_add_u32 s98, s98, 128
	s_addc_u32 s99, s99, 0
	s_waitcnt lgkmcnt(8)
	v_mfma_f32_16x16x32_bf16 v[60:63], v[76:79], v[108:111], v[60:63]
	s_waitcnt lgkmcnt(6)
	v_mfma_f32_16x16x32_bf16 v[0:3], v[80:83], v[112:115], v[0:3]
	ds_read_b128 v[64:67], v151 offset:16384
	s_waitcnt lgkmcnt(6)
	v_mfma_f32_16x16x32_bf16 v[4:7], v[80:83], v[116:119], v[4:7]
	ds_read_b128 v[96:99], v222 offset:32768
	s_waitcnt lgkmcnt(6)
	v_mfma_f32_16x16x32_bf16 v[8:11], v[80:83], v[120:123], v[8:11]
	ds_read_b128 v[100:103], v222 offset:34816
	s_waitcnt lgkmcnt(6)
	v_mfma_f32_16x16x32_bf16 v[12:15], v[80:83], v[124:127], v[12:15]
	ds_read_b128 v[104:107], v222 offset:36864
	s_waitcnt lgkmcnt(6)
	v_mfma_f32_16x16x32_bf16 v[16:19], v[84:87], v[112:115], v[16:19]
	ds_read_b128 v[108:111], v222 offset:38912
	s_waitcnt lgkmcnt(7)
	v_mfma_f32_16x16x32_bf16 v[20:23], v[84:87], v[116:119], v[20:23]
	ds_read_b128 v[68:71], v151 offset:18432
	s_waitcnt lgkmcnt(8)
	v_mfma_f32_16x16x32_bf16 v[24:27], v[84:87], v[120:123], v[24:27]
	ds_read_b128 v[72:75], v151 offset:20480
	s_waitcnt lgkmcnt(9)
	v_mfma_f32_16x16x32_bf16 v[28:31], v[84:87], v[124:127], v[28:31]
	ds_read_b128 v[76:79], v151 offset:22528
	s_waitcnt lgkmcnt(9)
	v_mfma_f32_16x16x32_bf16 v[32:35], v[88:91], v[112:115], v[32:35]
	s_waitcnt lgkmcnt(9)
	v_mfma_f32_16x16x32_bf16 v[36:39], v[88:91], v[116:119], v[36:39]
	s_waitcnt lgkmcnt(9)
	v_mfma_f32_16x16x32_bf16 v[40:43], v[88:91], v[120:123], v[40:43]
	s_waitcnt lgkmcnt(9)
	v_mfma_f32_16x16x32_bf16 v[44:47], v[88:91], v[124:127], v[44:47]
	s_waitcnt lgkmcnt(8)
	v_mfma_f32_16x16x32_bf16 v[48:51], v[92:95], v[112:115], v[48:51]
	s_waitcnt lgkmcnt(8)
	v_mfma_f32_16x16x32_bf16 v[52:55], v[92:95], v[116:119], v[52:55]
	s_waitcnt lgkmcnt(8)
	v_mfma_f32_16x16x32_bf16 v[56:59], v[92:95], v[120:123], v[56:59]
	s_waitcnt lgkmcnt(8)
	v_mfma_f32_16x16x32_bf16 v[60:63], v[92:95], v[124:127], v[60:63]
	s_waitcnt lgkmcnt(6)
	v_mfma_f32_16x16x32_bf16 v[160:163], v[64:67], v[96:99], v[160:163]
	ds_read_b128 v[80:83], v220 offset:16384
	s_waitcnt lgkmcnt(6)
	v_mfma_f32_16x16x32_bf16 v[164:167], v[64:67], v[100:103], v[164:167]
	ds_read_b128 v[112:115], v224 offset:32768
	s_waitcnt lgkmcnt(6)
	v_mfma_f32_16x16x32_bf16 v[168:171], v[64:67], v[104:107], v[168:171]
	ds_read_b128 v[116:119], v224 offset:34816
	s_waitcnt lgkmcnt(6)
	v_mfma_f32_16x16x32_bf16 v[172:175], v[64:67], v[108:111], v[172:175]
	ds_read_b128 v[120:123], v224 offset:36864
	s_waitcnt lgkmcnt(6)
	v_mfma_f32_16x16x32_bf16 v[176:179], v[68:71], v[96:99], v[176:179]
	ds_read_b128 v[124:127], v224 offset:38912
	s_waitcnt lgkmcnt(7)
	v_mfma_f32_16x16x32_bf16 v[180:183], v[68:71], v[100:103], v[180:183]
	ds_read_b128 v[84:87], v220 offset:18432
	s_waitcnt lgkmcnt(8)
	v_mfma_f32_16x16x32_bf16 v[184:187], v[68:71], v[104:107], v[184:187]
	ds_read_b128 v[88:91], v220 offset:20480
	s_waitcnt lgkmcnt(9)
	v_mfma_f32_16x16x32_bf16 v[188:191], v[68:71], v[108:111], v[188:191]
	ds_read_b128 v[92:95], v220 offset:22528
	s_waitcnt lgkmcnt(9)
	v_mfma_f32_16x16x32_bf16 v[192:195], v[72:75], v[96:99], v[192:195]
	s_waitcnt lgkmcnt(9)
	v_mfma_f32_16x16x32_bf16 v[196:199], v[72:75], v[100:103], v[196:199]
	s_waitcnt lgkmcnt(9)
	v_mfma_f32_16x16x32_bf16 v[200:203], v[72:75], v[104:107], v[200:203]
	s_waitcnt lgkmcnt(9)
	v_mfma_f32_16x16x32_bf16 v[204:207], v[72:75], v[108:111], v[204:207]
	s_waitcnt vmcnt(0) lgkmcnt(0)
	s_barrier
	s_add_u32 m0, s38, 16384
	s_nop 0
	global_load_lds_dwordx4 v226, s[100:101]
	s_waitcnt lgkmcnt(8)
	v_mfma_f32_16x16x32_bf16 v[208:211], v[76:79], v[96:99], v[208:211]
	s_add_u32 m0, s38, 20480
	s_nop 0
	global_load_lds_dwordx4 v228, s[100:101]
	s_waitcnt lgkmcnt(8)
	v_mfma_f32_16x16x32_bf16 v[212:215], v[76:79], v[100:103], v[212:215]
	s_add_u32 m0, s38, 24576
	s_nop 0
	global_load_lds_dwordx4 v244, s[100:101]
	s_waitcnt lgkmcnt(8)
	v_mfma_f32_16x16x32_bf16 v[216:219], v[76:79], v[104:107], v[216:219]
	s_add_u32 m0, s38, 28672
	s_nop 0
	global_load_lds_dwordx4 v245, s[100:101]
	s_add_u32 s100, s100, 128
	s_addc_u32 s101, s101, 0
	s_waitcnt lgkmcnt(8)
	v_mfma_f32_16x16x32_bf16 v[230:233], v[76:79], v[108:111], v[230:233]
	s_add_u32 m0, s38, 32768
	s_nop 0
	global_load_lds_dwordx4 v226, s[4:5]
	s_waitcnt lgkmcnt(6)
	v_mfma_f32_16x16x32_bf16 v[160:163], v[80:83], v[112:115], v[160:163]
	ds_read_b128 v[64:67], v151 offset:0
	s_add_u32 m0, s38, 36864
	s_nop 0
	global_load_lds_dwordx4 v228, s[4:5]
	s_waitcnt lgkmcnt(6)
	v_mfma_f32_16x16x32_bf16 v[164:167], v[80:83], v[116:119], v[164:167]
	ds_read_b128 v[96:99], v222 offset:49152
	s_add_u32 m0, s38, 40960
	s_nop 0
	global_load_lds_dwordx4 v244, s[4:5]
	s_waitcnt lgkmcnt(6)
	v_mfma_f32_16x16x32_bf16 v[168:171], v[80:83], v[120:123], v[168:171]
	ds_read_b128 v[100:103], v222 offset:51200
	s_add_u32 m0, s38, 45056
	s_nop 0
	global_load_lds_dwordx4 v245, s[4:5]
	s_add_u32 s4, s4, 128
	s_addc_u32 s5, s5, 0
	s_waitcnt lgkmcnt(6)
	v_mfma_f32_16x16x32_bf16 v[172:175], v[80:83], v[124:127], v[172:175]
	ds_read_b128 v[104:107], v222 offset:53248
	s_waitcnt lgkmcnt(6)
	v_mfma_f32_16x16x32_bf16 v[176:179], v[84:87], v[112:115], v[176:179]
	ds_read_b128 v[108:111], v222 offset:55296
	s_waitcnt lgkmcnt(7)
	v_mfma_f32_16x16x32_bf16 v[180:183], v[84:87], v[116:119], v[180:183]
	ds_read_b128 v[68:71], v151 offset:2048
	s_waitcnt lgkmcnt(8)
	v_mfma_f32_16x16x32_bf16 v[184:187], v[84:87], v[120:123], v[184:187]
	ds_read_b128 v[72:75], v151 offset:4096
	s_waitcnt lgkmcnt(9)
	v_mfma_f32_16x16x32_bf16 v[188:191], v[84:87], v[124:127], v[188:191]
	ds_read_b128 v[76:79], v151 offset:6144
	s_waitcnt lgkmcnt(9)
	v_mfma_f32_16x16x32_bf16 v[192:195], v[88:91], v[112:115], v[192:195]
	s_waitcnt lgkmcnt(9)
	v_mfma_f32_16x16x32_bf16 v[196:199], v[88:91], v[116:119], v[196:199]
	s_waitcnt lgkmcnt(9)
	v_mfma_f32_16x16x32_bf16 v[200:203], v[88:91], v[120:123], v[200:203]
	s_waitcnt lgkmcnt(9)
	v_mfma_f32_16x16x32_bf16 v[204:207], v[88:91], v[124:127], v[204:207]
	s_waitcnt lgkmcnt(8)
	v_mfma_f32_16x16x32_bf16 v[208:211], v[92:95], v[112:115], v[208:211]
	s_waitcnt lgkmcnt(8)
	v_mfma_f32_16x16x32_bf16 v[212:215], v[92:95], v[116:119], v[212:215]
	s_waitcnt lgkmcnt(8)
	v_mfma_f32_16x16x32_bf16 v[216:219], v[92:95], v[120:123], v[216:219]
	s_waitcnt lgkmcnt(8)
	v_mfma_f32_16x16x32_bf16 v[230:233], v[92:95], v[124:127], v[230:233]
	s_waitcnt lgkmcnt(6)
	v_mfma_f32_16x16x32_bf16 v[0:3], v[64:67], v[96:99], v[0:3]
	ds_read_b128 v[80:83], v220 offset:0
	s_waitcnt lgkmcnt(6)
	v_mfma_f32_16x16x32_bf16 v[4:7], v[64:67], v[100:103], v[4:7]
	ds_read_b128 v[112:115], v224 offset:49152
	s_waitcnt lgkmcnt(6)
	v_mfma_f32_16x16x32_bf16 v[8:11], v[64:67], v[104:107], v[8:11]
	ds_read_b128 v[116:119], v224 offset:51200
	s_waitcnt lgkmcnt(6)
	v_mfma_f32_16x16x32_bf16 v[12:15], v[64:67], v[108:111], v[12:15]
	ds_read_b128 v[120:123], v224 offset:53248
	s_waitcnt lgkmcnt(6)
	v_mfma_f32_16x16x32_bf16 v[16:19], v[68:71], v[96:99], v[16:19]
	ds_read_b128 v[124:127], v224 offset:55296
	s_waitcnt lgkmcnt(7)
	v_mfma_f32_16x16x32_bf16 v[20:23], v[68:71], v[100:103], v[20:23]
	ds_read_b128 v[84:87], v220 offset:2048
	s_waitcnt lgkmcnt(8)
	v_mfma_f32_16x16x32_bf16 v[24:27], v[68:71], v[104:107], v[24:27]
	ds_read_b128 v[88:91], v220 offset:4096
	s_waitcnt lgkmcnt(9)
	v_mfma_f32_16x16x32_bf16 v[28:31], v[68:71], v[108:111], v[28:31]
	ds_read_b128 v[92:95], v220 offset:6144
	s_waitcnt lgkmcnt(9)
	v_mfma_f32_16x16x32_bf16 v[32:35], v[72:75], v[96:99], v[32:35]
	s_waitcnt lgkmcnt(9)
	v_mfma_f32_16x16x32_bf16 v[36:39], v[72:75], v[100:103], v[36:39]
	s_waitcnt lgkmcnt(9)
	v_mfma_f32_16x16x32_bf16 v[40:43], v[72:75], v[104:107], v[40:43]
	s_waitcnt lgkmcnt(9)
	v_mfma_f32_16x16x32_bf16 v[44:47], v[72:75], v[108:111], v[44:47]
	s_waitcnt vmcnt(4) lgkmcnt(0)
	s_barrier
	s_add_u32 m0, s38, 0
	s_nop 0
	global_load_lds_dwordx4 v226, s[98:99]
	s_waitcnt lgkmcnt(8)
	v_mfma_f32_16x16x32_bf16 v[48:51], v[76:79], v[96:99], v[48:51]
	s_add_u32 m0, s38, 4096
	s_nop 0
	global_load_lds_dwordx4 v228, s[98:99]
	s_waitcnt lgkmcnt(8)
	v_mfma_f32_16x16x32_bf16 v[52:55], v[76:79], v[100:103], v[52:55]
	s_add_u32 m0, s38, 8192
	s_nop 0
	global_load_lds_dwordx4 v244, s[98:99]
	s_waitcnt lgkmcnt(8)
	v_mfma_f32_16x16x32_bf16 v[56:59], v[76:79], v[104:107], v[56:59]
	s_add_u32 m0, s38, 12288
	s_nop 0
	global_load_lds_dwordx4 v245, s[98:99]
	s_add_u32 s98, s98, 128
	s_addc_u32 s99, s99, 0
	s_waitcnt lgkmcnt(8)
	v_mfma_f32_16x16x32_bf16 v[60:63], v[76:79], v[108:111], v[60:63]
	s_waitcnt lgkmcnt(6)
	v_mfma_f32_16x16x32_bf16 v[0:3], v[80:83], v[112:115], v[0:3]
	ds_read_b128 v[64:67], v151 offset:16384
	s_waitcnt lgkmcnt(6)
	v_mfma_f32_16x16x32_bf16 v[4:7], v[80:83], v[116:119], v[4:7]
	ds_read_b128 v[96:99], v222 offset:49152
	s_waitcnt lgkmcnt(6)
	v_mfma_f32_16x16x32_bf16 v[8:11], v[80:83], v[120:123], v[8:11]
	ds_read_b128 v[100:103], v222 offset:51200
	s_waitcnt lgkmcnt(6)
	v_mfma_f32_16x16x32_bf16 v[12:15], v[80:83], v[124:127], v[12:15]
	ds_read_b128 v[104:107], v222 offset:53248
	s_waitcnt lgkmcnt(6)
	v_mfma_f32_16x16x32_bf16 v[16:19], v[84:87], v[112:115], v[16:19]
	ds_read_b128 v[108:111], v222 offset:55296
	s_waitcnt lgkmcnt(7)
	v_mfma_f32_16x16x32_bf16 v[20:23], v[84:87], v[116:119], v[20:23]
	ds_read_b128 v[68:71], v151 offset:18432
	s_waitcnt lgkmcnt(8)
	v_mfma_f32_16x16x32_bf16 v[24:27], v[84:87], v[120:123], v[24:27]
	ds_read_b128 v[72:75], v151 offset:20480
	s_waitcnt lgkmcnt(9)
	v_mfma_f32_16x16x32_bf16 v[28:31], v[84:87], v[124:127], v[28:31]
	ds_read_b128 v[76:79], v151 offset:22528
	s_waitcnt lgkmcnt(9)
	v_mfma_f32_16x16x32_bf16 v[32:35], v[88:91], v[112:115], v[32:35]
	s_waitcnt lgkmcnt(9)
	v_mfma_f32_16x16x32_bf16 v[36:39], v[88:91], v[116:119], v[36:39]
	s_waitcnt lgkmcnt(9)
	v_mfma_f32_16x16x32_bf16 v[40:43], v[88:91], v[120:123], v[40:43]
	s_waitcnt lgkmcnt(9)
	v_mfma_f32_16x16x32_bf16 v[44:47], v[88:91], v[124:127], v[44:47]
	s_waitcnt lgkmcnt(8)
	v_mfma_f32_16x16x32_bf16 v[48:51], v[92:95], v[112:115], v[48:51]
	s_waitcnt lgkmcnt(8)
	v_mfma_f32_16x16x32_bf16 v[52:55], v[92:95], v[116:119], v[52:55]
	s_waitcnt lgkmcnt(8)
	v_mfma_f32_16x16x32_bf16 v[56:59], v[92:95], v[120:123], v[56:59]
	s_waitcnt lgkmcnt(8)
	v_mfma_f32_16x16x32_bf16 v[60:63], v[92:95], v[124:127], v[60:63]
	s_waitcnt lgkmcnt(6)
	v_mfma_f32_16x16x32_bf16 v[160:163], v[64:67], v[96:99], v[160:163]
	ds_read_b128 v[80:83], v220 offset:16384
	s_waitcnt lgkmcnt(6)
	v_mfma_f32_16x16x32_bf16 v[164:167], v[64:67], v[100:103], v[164:167]
	ds_read_b128 v[112:115], v224 offset:49152
	s_waitcnt lgkmcnt(6)
	v_mfma_f32_16x16x32_bf16 v[168:171], v[64:67], v[104:107], v[168:171]
	ds_read_b128 v[116:119], v224 offset:51200
	s_waitcnt lgkmcnt(6)
	v_mfma_f32_16x16x32_bf16 v[172:175], v[64:67], v[108:111], v[172:175]
	ds_read_b128 v[120:123], v224 offset:53248
	s_waitcnt lgkmcnt(6)
	v_mfma_f32_16x16x32_bf16 v[176:179], v[68:71], v[96:99], v[176:179]
	ds_read_b128 v[124:127], v224 offset:55296
	s_waitcnt lgkmcnt(7)
	v_mfma_f32_16x16x32_bf16 v[180:183], v[68:71], v[100:103], v[180:183]
	ds_read_b128 v[84:87], v220 offset:18432
	s_waitcnt lgkmcnt(8)
	v_mfma_f32_16x16x32_bf16 v[184:187], v[68:71], v[104:107], v[184:187]
	ds_read_b128 v[88:91], v220 offset:20480
	s_waitcnt lgkmcnt(9)
	v_mfma_f32_16x16x32_bf16 v[188:191], v[68:71], v[108:111], v[188:191]
	ds_read_b128 v[92:95], v220 offset:22528
	s_waitcnt lgkmcnt(9)
	v_mfma_f32_16x16x32_bf16 v[192:195], v[72:75], v[96:99], v[192:195]
	s_waitcnt lgkmcnt(9)
	v_mfma_f32_16x16x32_bf16 v[196:199], v[72:75], v[100:103], v[196:199]
	s_waitcnt lgkmcnt(9)
	v_mfma_f32_16x16x32_bf16 v[200:203], v[72:75], v[104:107], v[200:203]
	s_waitcnt lgkmcnt(9)
	v_mfma_f32_16x16x32_bf16 v[204:207], v[72:75], v[108:111], v[204:207]
	s_waitcnt vmcnt(0) lgkmcnt(0)
	s_barrier
	s_add_u32 m0, s38, 16384
	s_nop 0
	global_load_lds_dwordx4 v226, s[100:101]
	s_waitcnt lgkmcnt(8)
	v_mfma_f32_16x16x32_bf16 v[208:211], v[76:79], v[96:99], v[208:211]
	s_add_u32 m0, s38, 20480
	s_nop 0
	global_load_lds_dwordx4 v228, s[100:101]
	s_waitcnt lgkmcnt(8)
	v_mfma_f32_16x16x32_bf16 v[212:215], v[76:79], v[100:103], v[212:215]
	s_add_u32 m0, s38, 24576
	s_nop 0
	global_load_lds_dwordx4 v244, s[100:101]
	s_waitcnt lgkmcnt(8)
	v_mfma_f32_16x16x32_bf16 v[216:219], v[76:79], v[104:107], v[216:219]
	s_add_u32 m0, s38, 28672
	s_nop 0
	global_load_lds_dwordx4 v245, s[100:101]
	s_add_u32 s100, s100, 128
	s_addc_u32 s101, s101, 0
	s_waitcnt lgkmcnt(8)
	v_mfma_f32_16x16x32_bf16 v[230:233], v[76:79], v[108:111], v[230:233]
	s_add_u32 m0, s38, 49152
	s_nop 0
	global_load_lds_dwordx4 v226, s[4:5]
	s_waitcnt lgkmcnt(6)
	v_mfma_f32_16x16x32_bf16 v[160:163], v[80:83], v[112:115], v[160:163]
	ds_read_b128 v[64:67], v151 offset:0
	s_add_u32 m0, s38, 53248
	s_nop 0
	global_load_lds_dwordx4 v228, s[4:5]
	s_waitcnt lgkmcnt(6)
	v_mfma_f32_16x16x32_bf16 v[164:167], v[80:83], v[116:119], v[164:167]
	ds_read_b128 v[96:99], v222 offset:32768
	s_add_u32 m0, s38, 57344
	s_nop 0
	global_load_lds_dwordx4 v244, s[4:5]
	s_waitcnt lgkmcnt(6)
	v_mfma_f32_16x16x32_bf16 v[168:171], v[80:83], v[120:123], v[168:171]
	ds_read_b128 v[100:103], v222 offset:34816
	s_add_u32 m0, s38, 61440
	s_nop 0
	global_load_lds_dwordx4 v245, s[4:5]
	s_add_u32 s4, s4, 128
	s_addc_u32 s5, s5, 0
	s_waitcnt lgkmcnt(6)
	v_mfma_f32_16x16x32_bf16 v[172:175], v[80:83], v[124:127], v[172:175]
	ds_read_b128 v[104:107], v222 offset:36864
	s_waitcnt lgkmcnt(6)
	v_mfma_f32_16x16x32_bf16 v[176:179], v[84:87], v[112:115], v[176:179]
	ds_read_b128 v[108:111], v222 offset:38912
	s_waitcnt lgkmcnt(7)
	v_mfma_f32_16x16x32_bf16 v[180:183], v[84:87], v[116:119], v[180:183]
	ds_read_b128 v[68:71], v151 offset:2048
	s_waitcnt lgkmcnt(8)
	v_mfma_f32_16x16x32_bf16 v[184:187], v[84:87], v[120:123], v[184:187]
	ds_read_b128 v[72:75], v151 offset:4096
	s_waitcnt lgkmcnt(9)
	v_mfma_f32_16x16x32_bf16 v[188:191], v[84:87], v[124:127], v[188:191]
	ds_read_b128 v[76:79], v151 offset:6144
	s_waitcnt lgkmcnt(9)
	v_mfma_f32_16x16x32_bf16 v[192:195], v[88:91], v[112:115], v[192:195]
	s_waitcnt lgkmcnt(9)
	v_mfma_f32_16x16x32_bf16 v[196:199], v[88:91], v[116:119], v[196:199]
	s_waitcnt lgkmcnt(9)
	v_mfma_f32_16x16x32_bf16 v[200:203], v[88:91], v[120:123], v[200:203]
	s_waitcnt lgkmcnt(9)
	v_mfma_f32_16x16x32_bf16 v[204:207], v[88:91], v[124:127], v[204:207]
	s_waitcnt lgkmcnt(8)
	v_mfma_f32_16x16x32_bf16 v[208:211], v[92:95], v[112:115], v[208:211]
	s_waitcnt lgkmcnt(8)
	v_mfma_f32_16x16x32_bf16 v[212:215], v[92:95], v[116:119], v[212:215]
	s_waitcnt lgkmcnt(8)
	v_mfma_f32_16x16x32_bf16 v[216:219], v[92:95], v[120:123], v[216:219]
	s_waitcnt lgkmcnt(8)
	v_mfma_f32_16x16x32_bf16 v[230:233], v[92:95], v[124:127], v[230:233]
	s_waitcnt lgkmcnt(6)
	v_mfma_f32_16x16x32_bf16 v[0:3], v[64:67], v[96:99], v[0:3]
	ds_read_b128 v[80:83], v220 offset:0
	s_waitcnt lgkmcnt(6)
	v_mfma_f32_16x16x32_bf16 v[4:7], v[64:67], v[100:103], v[4:7]
	ds_read_b128 v[112:115], v224 offset:32768
	s_waitcnt lgkmcnt(6)
	v_mfma_f32_16x16x32_bf16 v[8:11], v[64:67], v[104:107], v[8:11]
	ds_read_b128 v[116:119], v224 offset:34816
	s_waitcnt lgkmcnt(6)
	v_mfma_f32_16x16x32_bf16 v[12:15], v[64:67], v[108:111], v[12:15]
	ds_read_b128 v[120:123], v224 offset:36864
	s_waitcnt lgkmcnt(6)
	v_mfma_f32_16x16x32_bf16 v[16:19], v[68:71], v[96:99], v[16:19]
	ds_read_b128 v[124:127], v224 offset:38912
	s_waitcnt lgkmcnt(7)
	v_mfma_f32_16x16x32_bf16 v[20:23], v[68:71], v[100:103], v[20:23]
	ds_read_b128 v[84:87], v220 offset:2048
	s_waitcnt lgkmcnt(8)
	v_mfma_f32_16x16x32_bf16 v[24:27], v[68:71], v[104:107], v[24:27]
	ds_read_b128 v[88:91], v220 offset:4096
	s_waitcnt lgkmcnt(9)
	v_mfma_f32_16x16x32_bf16 v[28:31], v[68:71], v[108:111], v[28:31]
	ds_read_b128 v[92:95], v220 offset:6144
	s_waitcnt lgkmcnt(9)
	v_mfma_f32_16x16x32_bf16 v[32:35], v[72:75], v[96:99], v[32:35]
	s_waitcnt lgkmcnt(9)
	v_mfma_f32_16x16x32_bf16 v[36:39], v[72:75], v[100:103], v[36:39]
	s_waitcnt lgkmcnt(9)
	v_mfma_f32_16x16x32_bf16 v[40:43], v[72:75], v[104:107], v[40:43]
	s_waitcnt lgkmcnt(9)
	v_mfma_f32_16x16x32_bf16 v[44:47], v[72:75], v[108:111], v[44:47]
	s_waitcnt vmcnt(4) lgkmcnt(0)
	s_barrier
	s_add_u32 m0, s38, 0
	s_nop 0
	global_load_lds_dwordx4 v226, s[98:99]
	s_waitcnt lgkmcnt(8)
	v_mfma_f32_16x16x32_bf16 v[48:51], v[76:79], v[96:99], v[48:51]
	s_add_u32 m0, s38, 4096
	s_nop 0
	global_load_lds_dwordx4 v228, s[98:99]
	s_waitcnt lgkmcnt(8)
	v_mfma_f32_16x16x32_bf16 v[52:55], v[76:79], v[100:103], v[52:55]
	s_add_u32 m0, s38, 8192
	s_nop 0
	global_load_lds_dwordx4 v244, s[98:99]
	s_waitcnt lgkmcnt(8)
	v_mfma_f32_16x16x32_bf16 v[56:59], v[76:79], v[104:107], v[56:59]
	s_add_u32 m0, s38, 12288
	s_nop 0
	global_load_lds_dwordx4 v245, s[98:99]
	s_add_u32 s98, s98, 128
	s_addc_u32 s99, s99, 0
	s_waitcnt lgkmcnt(8)
	v_mfma_f32_16x16x32_bf16 v[60:63], v[76:79], v[108:111], v[60:63]
	s_waitcnt lgkmcnt(6)
	v_mfma_f32_16x16x32_bf16 v[0:3], v[80:83], v[112:115], v[0:3]
	ds_read_b128 v[64:67], v151 offset:16384
	s_waitcnt lgkmcnt(6)
	v_mfma_f32_16x16x32_bf16 v[4:7], v[80:83], v[116:119], v[4:7]
	ds_read_b128 v[96:99], v222 offset:32768
	s_waitcnt lgkmcnt(6)
	v_mfma_f32_16x16x32_bf16 v[8:11], v[80:83], v[120:123], v[8:11]
	ds_read_b128 v[100:103], v222 offset:34816
	s_waitcnt lgkmcnt(6)
	v_mfma_f32_16x16x32_bf16 v[12:15], v[80:83], v[124:127], v[12:15]
	ds_read_b128 v[104:107], v222 offset:36864
	s_waitcnt lgkmcnt(6)
	v_mfma_f32_16x16x32_bf16 v[16:19], v[84:87], v[112:115], v[16:19]
	ds_read_b128 v[108:111], v222 offset:38912
	s_waitcnt lgkmcnt(7)
	v_mfma_f32_16x16x32_bf16 v[20:23], v[84:87], v[116:119], v[20:23]
	ds_read_b128 v[68:71], v151 offset:18432
	s_waitcnt lgkmcnt(8)
	v_mfma_f32_16x16x32_bf16 v[24:27], v[84:87], v[120:123], v[24:27]
	ds_read_b128 v[72:75], v151 offset:20480
	s_waitcnt lgkmcnt(9)
	v_mfma_f32_16x16x32_bf16 v[28:31], v[84:87], v[124:127], v[28:31]
	ds_read_b128 v[76:79], v151 offset:22528
	s_waitcnt lgkmcnt(9)
	v_mfma_f32_16x16x32_bf16 v[32:35], v[88:91], v[112:115], v[32:35]
	s_waitcnt lgkmcnt(9)
	v_mfma_f32_16x16x32_bf16 v[36:39], v[88:91], v[116:119], v[36:39]
	s_waitcnt lgkmcnt(9)
	v_mfma_f32_16x16x32_bf16 v[40:43], v[88:91], v[120:123], v[40:43]
	s_waitcnt lgkmcnt(9)
	v_mfma_f32_16x16x32_bf16 v[44:47], v[88:91], v[124:127], v[44:47]
	s_waitcnt lgkmcnt(8)
	v_mfma_f32_16x16x32_bf16 v[48:51], v[92:95], v[112:115], v[48:51]
	s_waitcnt lgkmcnt(8)
	v_mfma_f32_16x16x32_bf16 v[52:55], v[92:95], v[116:119], v[52:55]
	s_waitcnt lgkmcnt(8)
	v_mfma_f32_16x16x32_bf16 v[56:59], v[92:95], v[120:123], v[56:59]
	s_waitcnt lgkmcnt(8)
	v_mfma_f32_16x16x32_bf16 v[60:63], v[92:95], v[124:127], v[60:63]
	s_waitcnt lgkmcnt(6)
	v_mfma_f32_16x16x32_bf16 v[160:163], v[64:67], v[96:99], v[160:163]
	ds_read_b128 v[80:83], v220 offset:16384
	s_waitcnt lgkmcnt(6)
	v_mfma_f32_16x16x32_bf16 v[164:167], v[64:67], v[100:103], v[164:167]
	ds_read_b128 v[112:115], v224 offset:32768
	s_waitcnt lgkmcnt(6)
	v_mfma_f32_16x16x32_bf16 v[168:171], v[64:67], v[104:107], v[168:171]
	ds_read_b128 v[116:119], v224 offset:34816
	s_waitcnt lgkmcnt(6)
	v_mfma_f32_16x16x32_bf16 v[172:175], v[64:67], v[108:111], v[172:175]
	ds_read_b128 v[120:123], v224 offset:36864
	s_waitcnt lgkmcnt(6)
	v_mfma_f32_16x16x32_bf16 v[176:179], v[68:71], v[96:99], v[176:179]
	ds_read_b128 v[124:127], v224 offset:38912
	s_waitcnt lgkmcnt(7)
	v_mfma_f32_16x16x32_bf16 v[180:183], v[68:71], v[100:103], v[180:183]
	ds_read_b128 v[84:87], v220 offset:18432
	s_waitcnt lgkmcnt(8)
	v_mfma_f32_16x16x32_bf16 v[184:187], v[68:71], v[104:107], v[184:187]
	ds_read_b128 v[88:91], v220 offset:20480
	s_waitcnt lgkmcnt(9)
	v_mfma_f32_16x16x32_bf16 v[188:191], v[68:71], v[108:111], v[188:191]
	ds_read_b128 v[92:95], v220 offset:22528
	s_waitcnt lgkmcnt(9)
	v_mfma_f32_16x16x32_bf16 v[192:195], v[72:75], v[96:99], v[192:195]
	s_waitcnt lgkmcnt(9)
	v_mfma_f32_16x16x32_bf16 v[196:199], v[72:75], v[100:103], v[196:199]
	s_waitcnt lgkmcnt(9)
	v_mfma_f32_16x16x32_bf16 v[200:203], v[72:75], v[104:107], v[200:203]
	s_waitcnt lgkmcnt(9)
	v_mfma_f32_16x16x32_bf16 v[204:207], v[72:75], v[108:111], v[204:207]
	s_waitcnt vmcnt(0) lgkmcnt(0)
	s_barrier
	s_add_u32 m0, s38, 16384
	s_nop 0
	global_load_lds_dwordx4 v226, s[100:101]
	s_waitcnt lgkmcnt(8)
	v_mfma_f32_16x16x32_bf16 v[208:211], v[76:79], v[96:99], v[208:211]
	s_add_u32 m0, s38, 20480
	s_nop 0
	global_load_lds_dwordx4 v228, s[100:101]
	s_waitcnt lgkmcnt(8)
	v_mfma_f32_16x16x32_bf16 v[212:215], v[76:79], v[100:103], v[212:215]
	s_add_u32 m0, s38, 24576
	s_nop 0
	global_load_lds_dwordx4 v244, s[100:101]
	s_waitcnt lgkmcnt(8)
	v_mfma_f32_16x16x32_bf16 v[216:219], v[76:79], v[104:107], v[216:219]
	s_add_u32 m0, s38, 28672
	s_nop 0
	global_load_lds_dwordx4 v245, s[100:101]
	s_add_u32 s100, s100, 128
	s_addc_u32 s101, s101, 0
	s_waitcnt lgkmcnt(8)
	v_mfma_f32_16x16x32_bf16 v[230:233], v[76:79], v[108:111], v[230:233]
	s_add_u32 m0, s38, 32768
	s_nop 0
	global_load_lds_dwordx4 v226, s[4:5]
	s_waitcnt lgkmcnt(6)
	v_mfma_f32_16x16x32_bf16 v[160:163], v[80:83], v[112:115], v[160:163]
	ds_read_b128 v[64:67], v151 offset:0
	s_add_u32 m0, s38, 36864
	s_nop 0
	global_load_lds_dwordx4 v228, s[4:5]
	s_waitcnt lgkmcnt(6)
	v_mfma_f32_16x16x32_bf16 v[164:167], v[80:83], v[116:119], v[164:167]
	ds_read_b128 v[96:99], v222 offset:49152
	s_add_u32 m0, s38, 40960
	s_nop 0
	global_load_lds_dwordx4 v244, s[4:5]
	s_waitcnt lgkmcnt(6)
	v_mfma_f32_16x16x32_bf16 v[168:171], v[80:83], v[120:123], v[168:171]
	ds_read_b128 v[100:103], v222 offset:51200
	s_add_u32 m0, s38, 45056
	s_nop 0
	global_load_lds_dwordx4 v245, s[4:5]
	s_add_u32 s4, s4, 128
	s_addc_u32 s5, s5, 0
	s_waitcnt lgkmcnt(6)
	v_mfma_f32_16x16x32_bf16 v[172:175], v[80:83], v[124:127], v[172:175]
	ds_read_b128 v[104:107], v222 offset:53248
	s_waitcnt lgkmcnt(6)
	v_mfma_f32_16x16x32_bf16 v[176:179], v[84:87], v[112:115], v[176:179]
	ds_read_b128 v[108:111], v222 offset:55296
	s_waitcnt lgkmcnt(7)
	v_mfma_f32_16x16x32_bf16 v[180:183], v[84:87], v[116:119], v[180:183]
	ds_read_b128 v[68:71], v151 offset:2048
	s_waitcnt lgkmcnt(8)
	v_mfma_f32_16x16x32_bf16 v[184:187], v[84:87], v[120:123], v[184:187]
	ds_read_b128 v[72:75], v151 offset:4096
	s_waitcnt lgkmcnt(9)
	v_mfma_f32_16x16x32_bf16 v[188:191], v[84:87], v[124:127], v[188:191]
	ds_read_b128 v[76:79], v151 offset:6144
	s_waitcnt lgkmcnt(9)
	v_mfma_f32_16x16x32_bf16 v[192:195], v[88:91], v[112:115], v[192:195]
	s_waitcnt lgkmcnt(9)
	v_mfma_f32_16x16x32_bf16 v[196:199], v[88:91], v[116:119], v[196:199]
	s_waitcnt lgkmcnt(9)
	v_mfma_f32_16x16x32_bf16 v[200:203], v[88:91], v[120:123], v[200:203]
	s_waitcnt lgkmcnt(9)
	v_mfma_f32_16x16x32_bf16 v[204:207], v[88:91], v[124:127], v[204:207]
	s_waitcnt lgkmcnt(8)
	v_mfma_f32_16x16x32_bf16 v[208:211], v[92:95], v[112:115], v[208:211]
	s_waitcnt lgkmcnt(8)
	v_mfma_f32_16x16x32_bf16 v[212:215], v[92:95], v[116:119], v[212:215]
	s_waitcnt lgkmcnt(8)
	v_mfma_f32_16x16x32_bf16 v[216:219], v[92:95], v[120:123], v[216:219]
	s_waitcnt lgkmcnt(8)
	v_mfma_f32_16x16x32_bf16 v[230:233], v[92:95], v[124:127], v[230:233]
	s_waitcnt lgkmcnt(6)
	v_mfma_f32_16x16x32_bf16 v[0:3], v[64:67], v[96:99], v[0:3]
	ds_read_b128 v[80:83], v220 offset:0
	s_waitcnt lgkmcnt(6)
	v_mfma_f32_16x16x32_bf16 v[4:7], v[64:67], v[100:103], v[4:7]
	ds_read_b128 v[112:115], v224 offset:49152
	s_waitcnt lgkmcnt(6)
	v_mfma_f32_16x16x32_bf16 v[8:11], v[64:67], v[104:107], v[8:11]
	ds_read_b128 v[116:119], v224 offset:51200
	s_waitcnt lgkmcnt(6)
	v_mfma_f32_16x16x32_bf16 v[12:15], v[64:67], v[108:111], v[12:15]
	ds_read_b128 v[120:123], v224 offset:53248
	s_waitcnt lgkmcnt(6)
	v_mfma_f32_16x16x32_bf16 v[16:19], v[68:71], v[96:99], v[16:19]
	ds_read_b128 v[124:127], v224 offset:55296
	s_waitcnt lgkmcnt(7)
	v_mfma_f32_16x16x32_bf16 v[20:23], v[68:71], v[100:103], v[20:23]
	ds_read_b128 v[84:87], v220 offset:2048
	s_waitcnt lgkmcnt(8)
	v_mfma_f32_16x16x32_bf16 v[24:27], v[68:71], v[104:107], v[24:27]
	ds_read_b128 v[88:91], v220 offset:4096
	s_waitcnt lgkmcnt(9)
	v_mfma_f32_16x16x32_bf16 v[28:31], v[68:71], v[108:111], v[28:31]
	ds_read_b128 v[92:95], v220 offset:6144
	s_waitcnt lgkmcnt(9)
	v_mfma_f32_16x16x32_bf16 v[32:35], v[72:75], v[96:99], v[32:35]
	s_waitcnt lgkmcnt(9)
	v_mfma_f32_16x16x32_bf16 v[36:39], v[72:75], v[100:103], v[36:39]
	s_waitcnt lgkmcnt(9)
	v_mfma_f32_16x16x32_bf16 v[40:43], v[72:75], v[104:107], v[40:43]
	s_waitcnt lgkmcnt(9)
	v_mfma_f32_16x16x32_bf16 v[44:47], v[72:75], v[108:111], v[44:47]
	s_waitcnt vmcnt(4) lgkmcnt(0)
	s_barrier
	s_add_u32 m0, s38, 0
	s_nop 0
	global_load_lds_dwordx4 v226, s[98:99]
	s_waitcnt lgkmcnt(8)
	v_mfma_f32_16x16x32_bf16 v[48:51], v[76:79], v[96:99], v[48:51]
	s_add_u32 m0, s38, 4096
	s_nop 0
	global_load_lds_dwordx4 v228, s[98:99]
	s_waitcnt lgkmcnt(8)
	v_mfma_f32_16x16x32_bf16 v[52:55], v[76:79], v[100:103], v[52:55]
	s_add_u32 m0, s38, 8192
	s_nop 0
	global_load_lds_dwordx4 v244, s[98:99]
	s_waitcnt lgkmcnt(8)
	v_mfma_f32_16x16x32_bf16 v[56:59], v[76:79], v[104:107], v[56:59]
	s_add_u32 m0, s38, 12288
	s_nop 0
	global_load_lds_dwordx4 v245, s[98:99]
	s_add_u32 s98, s98, 128
	s_addc_u32 s99, s99, 0
	s_waitcnt lgkmcnt(8)
	v_mfma_f32_16x16x32_bf16 v[60:63], v[76:79], v[108:111], v[60:63]
	s_waitcnt lgkmcnt(6)
	v_mfma_f32_16x16x32_bf16 v[0:3], v[80:83], v[112:115], v[0:3]
	ds_read_b128 v[64:67], v151 offset:16384
	s_waitcnt lgkmcnt(6)
	v_mfma_f32_16x16x32_bf16 v[4:7], v[80:83], v[116:119], v[4:7]
	ds_read_b128 v[96:99], v222 offset:49152
	s_waitcnt lgkmcnt(6)
	v_mfma_f32_16x16x32_bf16 v[8:11], v[80:83], v[120:123], v[8:11]
	ds_read_b128 v[100:103], v222 offset:51200
	s_waitcnt lgkmcnt(6)
	v_mfma_f32_16x16x32_bf16 v[12:15], v[80:83], v[124:127], v[12:15]
	ds_read_b128 v[104:107], v222 offset:53248
	s_waitcnt lgkmcnt(6)
	v_mfma_f32_16x16x32_bf16 v[16:19], v[84:87], v[112:115], v[16:19]
	ds_read_b128 v[108:111], v222 offset:55296
	s_waitcnt lgkmcnt(7)
	v_mfma_f32_16x16x32_bf16 v[20:23], v[84:87], v[116:119], v[20:23]
	ds_read_b128 v[68:71], v151 offset:18432
	s_waitcnt lgkmcnt(8)
	v_mfma_f32_16x16x32_bf16 v[24:27], v[84:87], v[120:123], v[24:27]
	ds_read_b128 v[72:75], v151 offset:20480
	s_waitcnt lgkmcnt(9)
	v_mfma_f32_16x16x32_bf16 v[28:31], v[84:87], v[124:127], v[28:31]
	ds_read_b128 v[76:79], v151 offset:22528
	s_waitcnt lgkmcnt(9)
	v_mfma_f32_16x16x32_bf16 v[32:35], v[88:91], v[112:115], v[32:35]
	s_waitcnt lgkmcnt(9)
	v_mfma_f32_16x16x32_bf16 v[36:39], v[88:91], v[116:119], v[36:39]
	s_waitcnt lgkmcnt(9)
	v_mfma_f32_16x16x32_bf16 v[40:43], v[88:91], v[120:123], v[40:43]
	s_waitcnt lgkmcnt(9)
	v_mfma_f32_16x16x32_bf16 v[44:47], v[88:91], v[124:127], v[44:47]
	s_waitcnt lgkmcnt(8)
	v_mfma_f32_16x16x32_bf16 v[48:51], v[92:95], v[112:115], v[48:51]
	s_waitcnt lgkmcnt(8)
	v_mfma_f32_16x16x32_bf16 v[52:55], v[92:95], v[116:119], v[52:55]
	s_waitcnt lgkmcnt(8)
	v_mfma_f32_16x16x32_bf16 v[56:59], v[92:95], v[120:123], v[56:59]
	s_waitcnt lgkmcnt(8)
	v_mfma_f32_16x16x32_bf16 v[60:63], v[92:95], v[124:127], v[60:63]
	s_waitcnt lgkmcnt(6)
	v_mfma_f32_16x16x32_bf16 v[160:163], v[64:67], v[96:99], v[160:163]
	ds_read_b128 v[80:83], v220 offset:16384
	s_waitcnt lgkmcnt(6)
	v_mfma_f32_16x16x32_bf16 v[164:167], v[64:67], v[100:103], v[164:167]
	ds_read_b128 v[112:115], v224 offset:49152
	s_waitcnt lgkmcnt(6)
	v_mfma_f32_16x16x32_bf16 v[168:171], v[64:67], v[104:107], v[168:171]
	ds_read_b128 v[116:119], v224 offset:51200
	s_waitcnt lgkmcnt(6)
	v_mfma_f32_16x16x32_bf16 v[172:175], v[64:67], v[108:111], v[172:175]
	ds_read_b128 v[120:123], v224 offset:53248
	s_waitcnt lgkmcnt(6)
	v_mfma_f32_16x16x32_bf16 v[176:179], v[68:71], v[96:99], v[176:179]
	ds_read_b128 v[124:127], v224 offset:55296
	s_waitcnt lgkmcnt(7)
	v_mfma_f32_16x16x32_bf16 v[180:183], v[68:71], v[100:103], v[180:183]
	ds_read_b128 v[84:87], v220 offset:18432
	s_waitcnt lgkmcnt(8)
	v_mfma_f32_16x16x32_bf16 v[184:187], v[68:71], v[104:107], v[184:187]
	ds_read_b128 v[88:91], v220 offset:20480
	s_waitcnt lgkmcnt(9)
	v_mfma_f32_16x16x32_bf16 v[188:191], v[68:71], v[108:111], v[188:191]
	ds_read_b128 v[92:95], v220 offset:22528
	s_waitcnt lgkmcnt(9)
	v_mfma_f32_16x16x32_bf16 v[192:195], v[72:75], v[96:99], v[192:195]
	s_waitcnt lgkmcnt(9)
	v_mfma_f32_16x16x32_bf16 v[196:199], v[72:75], v[100:103], v[196:199]
	s_waitcnt lgkmcnt(9)
	v_mfma_f32_16x16x32_bf16 v[200:203], v[72:75], v[104:107], v[200:203]
	s_waitcnt lgkmcnt(9)
	v_mfma_f32_16x16x32_bf16 v[204:207], v[72:75], v[108:111], v[204:207]
	s_waitcnt vmcnt(0) lgkmcnt(0)
	s_barrier
	s_add_u32 m0, s38, 16384
	s_nop 0
	global_load_lds_dwordx4 v226, s[100:101]
	s_waitcnt lgkmcnt(8)
	v_mfma_f32_16x16x32_bf16 v[208:211], v[76:79], v[96:99], v[208:211]
	s_add_u32 m0, s38, 20480
	s_nop 0
	global_load_lds_dwordx4 v228, s[100:101]
	s_waitcnt lgkmcnt(8)
	v_mfma_f32_16x16x32_bf16 v[212:215], v[76:79], v[100:103], v[212:215]
	s_add_u32 m0, s38, 24576
	s_nop 0
	global_load_lds_dwordx4 v244, s[100:101]
	s_waitcnt lgkmcnt(8)
	v_mfma_f32_16x16x32_bf16 v[216:219], v[76:79], v[104:107], v[216:219]
	s_add_u32 m0, s38, 28672
	s_nop 0
	global_load_lds_dwordx4 v245, s[100:101]
	s_add_u32 s100, s100, 128
	s_addc_u32 s101, s101, 0
	s_waitcnt lgkmcnt(8)
	v_mfma_f32_16x16x32_bf16 v[230:233], v[76:79], v[108:111], v[230:233]
	s_add_u32 m0, s38, 49152
	s_nop 0
	global_load_lds_dwordx4 v226, s[4:5]
	s_waitcnt lgkmcnt(6)
	v_mfma_f32_16x16x32_bf16 v[160:163], v[80:83], v[112:115], v[160:163]
	ds_read_b128 v[64:67], v151 offset:0
	s_add_u32 m0, s38, 53248
	s_nop 0
	global_load_lds_dwordx4 v228, s[4:5]
	s_waitcnt lgkmcnt(6)
	v_mfma_f32_16x16x32_bf16 v[164:167], v[80:83], v[116:119], v[164:167]
	ds_read_b128 v[96:99], v222 offset:32768
	s_add_u32 m0, s38, 57344
	s_nop 0
	global_load_lds_dwordx4 v244, s[4:5]
	s_waitcnt lgkmcnt(6)
	v_mfma_f32_16x16x32_bf16 v[168:171], v[80:83], v[120:123], v[168:171]
	ds_read_b128 v[100:103], v222 offset:34816
	s_add_u32 m0, s38, 61440
	s_nop 0
	global_load_lds_dwordx4 v245, s[4:5]
	s_add_u32 s4, s4, 128
	s_addc_u32 s5, s5, 0
	s_waitcnt lgkmcnt(6)
	v_mfma_f32_16x16x32_bf16 v[172:175], v[80:83], v[124:127], v[172:175]
	ds_read_b128 v[104:107], v222 offset:36864
	s_waitcnt lgkmcnt(6)
	v_mfma_f32_16x16x32_bf16 v[176:179], v[84:87], v[112:115], v[176:179]
	ds_read_b128 v[108:111], v222 offset:38912
	s_waitcnt lgkmcnt(7)
	v_mfma_f32_16x16x32_bf16 v[180:183], v[84:87], v[116:119], v[180:183]
	ds_read_b128 v[68:71], v151 offset:2048
	s_waitcnt lgkmcnt(8)
	v_mfma_f32_16x16x32_bf16 v[184:187], v[84:87], v[120:123], v[184:187]
	ds_read_b128 v[72:75], v151 offset:4096
	s_waitcnt lgkmcnt(9)
	v_mfma_f32_16x16x32_bf16 v[188:191], v[84:87], v[124:127], v[188:191]
	ds_read_b128 v[76:79], v151 offset:6144
	s_waitcnt lgkmcnt(9)
	v_mfma_f32_16x16x32_bf16 v[192:195], v[88:91], v[112:115], v[192:195]
	s_waitcnt lgkmcnt(9)
	v_mfma_f32_16x16x32_bf16 v[196:199], v[88:91], v[116:119], v[196:199]
	s_waitcnt lgkmcnt(9)
	v_mfma_f32_16x16x32_bf16 v[200:203], v[88:91], v[120:123], v[200:203]
	s_waitcnt lgkmcnt(9)
	v_mfma_f32_16x16x32_bf16 v[204:207], v[88:91], v[124:127], v[204:207]
	s_waitcnt lgkmcnt(8)
	v_mfma_f32_16x16x32_bf16 v[208:211], v[92:95], v[112:115], v[208:211]
	s_waitcnt lgkmcnt(8)
	v_mfma_f32_16x16x32_bf16 v[212:215], v[92:95], v[116:119], v[212:215]
	s_waitcnt lgkmcnt(8)
	v_mfma_f32_16x16x32_bf16 v[216:219], v[92:95], v[120:123], v[216:219]
	s_waitcnt lgkmcnt(8)
	v_mfma_f32_16x16x32_bf16 v[230:233], v[92:95], v[124:127], v[230:233]
	s_waitcnt lgkmcnt(6)
	v_mfma_f32_16x16x32_bf16 v[0:3], v[64:67], v[96:99], v[0:3]
	ds_read_b128 v[80:83], v220 offset:0
	s_waitcnt lgkmcnt(6)
	v_mfma_f32_16x16x32_bf16 v[4:7], v[64:67], v[100:103], v[4:7]
	ds_read_b128 v[112:115], v224 offset:32768
	s_waitcnt lgkmcnt(6)
	v_mfma_f32_16x16x32_bf16 v[8:11], v[64:67], v[104:107], v[8:11]
	ds_read_b128 v[116:119], v224 offset:34816
	s_waitcnt lgkmcnt(6)
	v_mfma_f32_16x16x32_bf16 v[12:15], v[64:67], v[108:111], v[12:15]
	ds_read_b128 v[120:123], v224 offset:36864
	s_waitcnt lgkmcnt(6)
	v_mfma_f32_16x16x32_bf16 v[16:19], v[68:71], v[96:99], v[16:19]
	ds_read_b128 v[124:127], v224 offset:38912
	s_waitcnt lgkmcnt(7)
	v_mfma_f32_16x16x32_bf16 v[20:23], v[68:71], v[100:103], v[20:23]
	ds_read_b128 v[84:87], v220 offset:2048
	s_waitcnt lgkmcnt(8)
	v_mfma_f32_16x16x32_bf16 v[24:27], v[68:71], v[104:107], v[24:27]
	ds_read_b128 v[88:91], v220 offset:4096
	s_waitcnt lgkmcnt(9)
	v_mfma_f32_16x16x32_bf16 v[28:31], v[68:71], v[108:111], v[28:31]
	ds_read_b128 v[92:95], v220 offset:6144
	s_waitcnt lgkmcnt(9)
	v_mfma_f32_16x16x32_bf16 v[32:35], v[72:75], v[96:99], v[32:35]
	s_waitcnt lgkmcnt(9)
	v_mfma_f32_16x16x32_bf16 v[36:39], v[72:75], v[100:103], v[36:39]
	s_waitcnt lgkmcnt(9)
	v_mfma_f32_16x16x32_bf16 v[40:43], v[72:75], v[104:107], v[40:43]
	s_waitcnt lgkmcnt(9)
	v_mfma_f32_16x16x32_bf16 v[44:47], v[72:75], v[108:111], v[44:47]
	s_waitcnt vmcnt(4) lgkmcnt(0)
	s_barrier
	s_add_u32 m0, s38, 0
	s_nop 0
	global_load_lds_dwordx4 v226, s[98:99]
	s_waitcnt lgkmcnt(8)
	v_mfma_f32_16x16x32_bf16 v[48:51], v[76:79], v[96:99], v[48:51]
	s_add_u32 m0, s38, 4096
	s_nop 0
	global_load_lds_dwordx4 v228, s[98:99]
	s_waitcnt lgkmcnt(8)
	v_mfma_f32_16x16x32_bf16 v[52:55], v[76:79], v[100:103], v[52:55]
	s_add_u32 m0, s38, 8192
	s_nop 0
	global_load_lds_dwordx4 v244, s[98:99]
	s_waitcnt lgkmcnt(8)
	v_mfma_f32_16x16x32_bf16 v[56:59], v[76:79], v[104:107], v[56:59]
	s_add_u32 m0, s38, 12288
	s_nop 0
	global_load_lds_dwordx4 v245, s[98:99]
	s_add_u32 s98, s98, 128
	s_addc_u32 s99, s99, 0
	s_waitcnt lgkmcnt(8)
	v_mfma_f32_16x16x32_bf16 v[60:63], v[76:79], v[108:111], v[60:63]
	s_waitcnt lgkmcnt(6)
	v_mfma_f32_16x16x32_bf16 v[0:3], v[80:83], v[112:115], v[0:3]
	ds_read_b128 v[64:67], v151 offset:16384
	s_waitcnt lgkmcnt(6)
	v_mfma_f32_16x16x32_bf16 v[4:7], v[80:83], v[116:119], v[4:7]
	ds_read_b128 v[96:99], v222 offset:32768
	s_waitcnt lgkmcnt(6)
	v_mfma_f32_16x16x32_bf16 v[8:11], v[80:83], v[120:123], v[8:11]
	ds_read_b128 v[100:103], v222 offset:34816
	s_waitcnt lgkmcnt(6)
	v_mfma_f32_16x16x32_bf16 v[12:15], v[80:83], v[124:127], v[12:15]
	ds_read_b128 v[104:107], v222 offset:36864
	s_waitcnt lgkmcnt(6)
	v_mfma_f32_16x16x32_bf16 v[16:19], v[84:87], v[112:115], v[16:19]
	ds_read_b128 v[108:111], v222 offset:38912
	s_waitcnt lgkmcnt(7)
	v_mfma_f32_16x16x32_bf16 v[20:23], v[84:87], v[116:119], v[20:23]
	ds_read_b128 v[68:71], v151 offset:18432
	s_waitcnt lgkmcnt(8)
	v_mfma_f32_16x16x32_bf16 v[24:27], v[84:87], v[120:123], v[24:27]
	ds_read_b128 v[72:75], v151 offset:20480
	s_waitcnt lgkmcnt(9)
	v_mfma_f32_16x16x32_bf16 v[28:31], v[84:87], v[124:127], v[28:31]
	ds_read_b128 v[76:79], v151 offset:22528
	s_waitcnt lgkmcnt(9)
	v_mfma_f32_16x16x32_bf16 v[32:35], v[88:91], v[112:115], v[32:35]
	s_waitcnt lgkmcnt(9)
	v_mfma_f32_16x16x32_bf16 v[36:39], v[88:91], v[116:119], v[36:39]
	s_waitcnt lgkmcnt(9)
	v_mfma_f32_16x16x32_bf16 v[40:43], v[88:91], v[120:123], v[40:43]
	s_waitcnt lgkmcnt(9)
	v_mfma_f32_16x16x32_bf16 v[44:47], v[88:91], v[124:127], v[44:47]
	s_waitcnt lgkmcnt(8)
	v_mfma_f32_16x16x32_bf16 v[48:51], v[92:95], v[112:115], v[48:51]
	s_waitcnt lgkmcnt(8)
	v_mfma_f32_16x16x32_bf16 v[52:55], v[92:95], v[116:119], v[52:55]
	s_waitcnt lgkmcnt(8)
	v_mfma_f32_16x16x32_bf16 v[56:59], v[92:95], v[120:123], v[56:59]
	s_waitcnt lgkmcnt(8)
	v_mfma_f32_16x16x32_bf16 v[60:63], v[92:95], v[124:127], v[60:63]
	s_waitcnt lgkmcnt(6)
	v_mfma_f32_16x16x32_bf16 v[160:163], v[64:67], v[96:99], v[160:163]
	ds_read_b128 v[80:83], v220 offset:16384
	s_waitcnt lgkmcnt(6)
	v_mfma_f32_16x16x32_bf16 v[164:167], v[64:67], v[100:103], v[164:167]
	ds_read_b128 v[112:115], v224 offset:32768
	s_waitcnt lgkmcnt(6)
	v_mfma_f32_16x16x32_bf16 v[168:171], v[64:67], v[104:107], v[168:171]
	ds_read_b128 v[116:119], v224 offset:34816
	s_waitcnt lgkmcnt(6)
	v_mfma_f32_16x16x32_bf16 v[172:175], v[64:67], v[108:111], v[172:175]
	ds_read_b128 v[120:123], v224 offset:36864
	s_waitcnt lgkmcnt(6)
	v_mfma_f32_16x16x32_bf16 v[176:179], v[68:71], v[96:99], v[176:179]
	ds_read_b128 v[124:127], v224 offset:38912
	s_waitcnt lgkmcnt(7)
	v_mfma_f32_16x16x32_bf16 v[180:183], v[68:71], v[100:103], v[180:183]
	ds_read_b128 v[84:87], v220 offset:18432
	s_waitcnt lgkmcnt(8)
	v_mfma_f32_16x16x32_bf16 v[184:187], v[68:71], v[104:107], v[184:187]
	ds_read_b128 v[88:91], v220 offset:20480
	s_waitcnt lgkmcnt(9)
	v_mfma_f32_16x16x32_bf16 v[188:191], v[68:71], v[108:111], v[188:191]
	ds_read_b128 v[92:95], v220 offset:22528
	s_waitcnt lgkmcnt(9)
	v_mfma_f32_16x16x32_bf16 v[192:195], v[72:75], v[96:99], v[192:195]
	s_waitcnt lgkmcnt(9)
	v_mfma_f32_16x16x32_bf16 v[196:199], v[72:75], v[100:103], v[196:199]
	s_waitcnt lgkmcnt(9)
	v_mfma_f32_16x16x32_bf16 v[200:203], v[72:75], v[104:107], v[200:203]
	s_waitcnt lgkmcnt(9)
	v_mfma_f32_16x16x32_bf16 v[204:207], v[72:75], v[108:111], v[204:207]
	s_waitcnt vmcnt(0) lgkmcnt(0)
	s_barrier
	s_add_u32 m0, s38, 16384
	s_nop 0
	global_load_lds_dwordx4 v226, s[100:101]
	s_waitcnt lgkmcnt(8)
	v_mfma_f32_16x16x32_bf16 v[208:211], v[76:79], v[96:99], v[208:211]
	s_add_u32 m0, s38, 20480
	s_nop 0
	global_load_lds_dwordx4 v228, s[100:101]
	s_waitcnt lgkmcnt(8)
	v_mfma_f32_16x16x32_bf16 v[212:215], v[76:79], v[100:103], v[212:215]
	s_add_u32 m0, s38, 24576
	s_nop 0
	global_load_lds_dwordx4 v244, s[100:101]
	s_waitcnt lgkmcnt(8)
	v_mfma_f32_16x16x32_bf16 v[216:219], v[76:79], v[104:107], v[216:219]
	s_add_u32 m0, s38, 28672
	s_nop 0
	global_load_lds_dwordx4 v245, s[100:101]
	s_add_u32 s100, s100, 128
	s_addc_u32 s101, s101, 0
	s_waitcnt lgkmcnt(8)
	v_mfma_f32_16x16x32_bf16 v[230:233], v[76:79], v[108:111], v[230:233]
	s_add_u32 m0, s38, 32768
	s_nop 0
	global_load_lds_dwordx4 v226, s[4:5]
	s_waitcnt lgkmcnt(6)
	v_mfma_f32_16x16x32_bf16 v[160:163], v[80:83], v[112:115], v[160:163]
	ds_read_b128 v[64:67], v151 offset:0
	s_add_u32 m0, s38, 36864
	s_nop 0
	global_load_lds_dwordx4 v228, s[4:5]
	s_waitcnt lgkmcnt(6)
	v_mfma_f32_16x16x32_bf16 v[164:167], v[80:83], v[116:119], v[164:167]
	ds_read_b128 v[96:99], v222 offset:49152
	s_add_u32 m0, s38, 40960
	s_nop 0
	global_load_lds_dwordx4 v244, s[4:5]
	s_waitcnt lgkmcnt(6)
	v_mfma_f32_16x16x32_bf16 v[168:171], v[80:83], v[120:123], v[168:171]
	ds_read_b128 v[100:103], v222 offset:51200
	s_add_u32 m0, s38, 45056
	s_nop 0
	global_load_lds_dwordx4 v245, s[4:5]
	s_add_u32 s4, s4, 128
	s_addc_u32 s5, s5, 0
	s_waitcnt lgkmcnt(6)
	v_mfma_f32_16x16x32_bf16 v[172:175], v[80:83], v[124:127], v[172:175]
	ds_read_b128 v[104:107], v222 offset:53248
	s_waitcnt lgkmcnt(6)
	v_mfma_f32_16x16x32_bf16 v[176:179], v[84:87], v[112:115], v[176:179]
	ds_read_b128 v[108:111], v222 offset:55296
	s_waitcnt lgkmcnt(7)
	v_mfma_f32_16x16x32_bf16 v[180:183], v[84:87], v[116:119], v[180:183]
	ds_read_b128 v[68:71], v151 offset:2048
	s_waitcnt lgkmcnt(8)
	v_mfma_f32_16x16x32_bf16 v[184:187], v[84:87], v[120:123], v[184:187]
	ds_read_b128 v[72:75], v151 offset:4096
	s_waitcnt lgkmcnt(9)
	v_mfma_f32_16x16x32_bf16 v[188:191], v[84:87], v[124:127], v[188:191]
	ds_read_b128 v[76:79], v151 offset:6144
	s_waitcnt lgkmcnt(9)
	v_mfma_f32_16x16x32_bf16 v[192:195], v[88:91], v[112:115], v[192:195]
	s_waitcnt lgkmcnt(9)
	v_mfma_f32_16x16x32_bf16 v[196:199], v[88:91], v[116:119], v[196:199]
	s_waitcnt lgkmcnt(9)
	v_mfma_f32_16x16x32_bf16 v[200:203], v[88:91], v[120:123], v[200:203]
	s_waitcnt lgkmcnt(9)
	v_mfma_f32_16x16x32_bf16 v[204:207], v[88:91], v[124:127], v[204:207]
	s_waitcnt lgkmcnt(8)
	v_mfma_f32_16x16x32_bf16 v[208:211], v[92:95], v[112:115], v[208:211]
	s_waitcnt lgkmcnt(8)
	v_mfma_f32_16x16x32_bf16 v[212:215], v[92:95], v[116:119], v[212:215]
	s_waitcnt lgkmcnt(8)
	v_mfma_f32_16x16x32_bf16 v[216:219], v[92:95], v[120:123], v[216:219]
	s_waitcnt lgkmcnt(8)
	v_mfma_f32_16x16x32_bf16 v[230:233], v[92:95], v[124:127], v[230:233]
	s_waitcnt lgkmcnt(6)
	v_mfma_f32_16x16x32_bf16 v[0:3], v[64:67], v[96:99], v[0:3]
	ds_read_b128 v[80:83], v220 offset:0
	s_waitcnt lgkmcnt(6)
	v_mfma_f32_16x16x32_bf16 v[4:7], v[64:67], v[100:103], v[4:7]
	ds_read_b128 v[112:115], v224 offset:49152
	s_waitcnt lgkmcnt(6)
	v_mfma_f32_16x16x32_bf16 v[8:11], v[64:67], v[104:107], v[8:11]
	ds_read_b128 v[116:119], v224 offset:51200
	s_waitcnt lgkmcnt(6)
	v_mfma_f32_16x16x32_bf16 v[12:15], v[64:67], v[108:111], v[12:15]
	ds_read_b128 v[120:123], v224 offset:53248
	s_waitcnt lgkmcnt(6)
	v_mfma_f32_16x16x32_bf16 v[16:19], v[68:71], v[96:99], v[16:19]
	ds_read_b128 v[124:127], v224 offset:55296
	s_waitcnt lgkmcnt(7)
	v_mfma_f32_16x16x32_bf16 v[20:23], v[68:71], v[100:103], v[20:23]
	ds_read_b128 v[84:87], v220 offset:2048
	s_waitcnt lgkmcnt(8)
	v_mfma_f32_16x16x32_bf16 v[24:27], v[68:71], v[104:107], v[24:27]
	ds_read_b128 v[88:91], v220 offset:4096
	s_waitcnt lgkmcnt(9)
	v_mfma_f32_16x16x32_bf16 v[28:31], v[68:71], v[108:111], v[28:31]
	ds_read_b128 v[92:95], v220 offset:6144
	s_waitcnt lgkmcnt(9)
	v_mfma_f32_16x16x32_bf16 v[32:35], v[72:75], v[96:99], v[32:35]
	s_waitcnt lgkmcnt(9)
	v_mfma_f32_16x16x32_bf16 v[36:39], v[72:75], v[100:103], v[36:39]
	s_waitcnt lgkmcnt(9)
	v_mfma_f32_16x16x32_bf16 v[40:43], v[72:75], v[104:107], v[40:43]
	s_waitcnt lgkmcnt(9)
	v_mfma_f32_16x16x32_bf16 v[44:47], v[72:75], v[108:111], v[44:47]
	s_waitcnt vmcnt(4) lgkmcnt(0)
	s_barrier
	s_add_u32 m0, s38, 0
	s_nop 0
	global_load_lds_dwordx4 v226, s[98:99]
	s_waitcnt lgkmcnt(8)
	v_mfma_f32_16x16x32_bf16 v[48:51], v[76:79], v[96:99], v[48:51]
	s_add_u32 m0, s38, 4096
	s_nop 0
	global_load_lds_dwordx4 v228, s[98:99]
	s_waitcnt lgkmcnt(8)
	v_mfma_f32_16x16x32_bf16 v[52:55], v[76:79], v[100:103], v[52:55]
	s_add_u32 m0, s38, 8192
	s_nop 0
	global_load_lds_dwordx4 v244, s[98:99]
	s_waitcnt lgkmcnt(8)
	v_mfma_f32_16x16x32_bf16 v[56:59], v[76:79], v[104:107], v[56:59]
	s_add_u32 m0, s38, 12288
	s_nop 0
	global_load_lds_dwordx4 v245, s[98:99]
	s_add_u32 s98, s98, 128
	s_addc_u32 s99, s99, 0
	s_waitcnt lgkmcnt(8)
	v_mfma_f32_16x16x32_bf16 v[60:63], v[76:79], v[108:111], v[60:63]
	s_waitcnt lgkmcnt(6)
	v_mfma_f32_16x16x32_bf16 v[0:3], v[80:83], v[112:115], v[0:3]
	ds_read_b128 v[64:67], v151 offset:16384
	s_waitcnt lgkmcnt(6)
	v_mfma_f32_16x16x32_bf16 v[4:7], v[80:83], v[116:119], v[4:7]
	ds_read_b128 v[96:99], v222 offset:49152
	s_waitcnt lgkmcnt(6)
	v_mfma_f32_16x16x32_bf16 v[8:11], v[80:83], v[120:123], v[8:11]
	ds_read_b128 v[100:103], v222 offset:51200
	s_waitcnt lgkmcnt(6)
	v_mfma_f32_16x16x32_bf16 v[12:15], v[80:83], v[124:127], v[12:15]
	ds_read_b128 v[104:107], v222 offset:53248
	s_waitcnt lgkmcnt(6)
	v_mfma_f32_16x16x32_bf16 v[16:19], v[84:87], v[112:115], v[16:19]
	ds_read_b128 v[108:111], v222 offset:55296
	s_waitcnt lgkmcnt(7)
	v_mfma_f32_16x16x32_bf16 v[20:23], v[84:87], v[116:119], v[20:23]
	ds_read_b128 v[68:71], v151 offset:18432
	s_waitcnt lgkmcnt(8)
	v_mfma_f32_16x16x32_bf16 v[24:27], v[84:87], v[120:123], v[24:27]
	ds_read_b128 v[72:75], v151 offset:20480
	s_waitcnt lgkmcnt(9)
	v_mfma_f32_16x16x32_bf16 v[28:31], v[84:87], v[124:127], v[28:31]
	ds_read_b128 v[76:79], v151 offset:22528
	s_waitcnt lgkmcnt(9)
	v_mfma_f32_16x16x32_bf16 v[32:35], v[88:91], v[112:115], v[32:35]
	s_waitcnt lgkmcnt(9)
	v_mfma_f32_16x16x32_bf16 v[36:39], v[88:91], v[116:119], v[36:39]
	s_waitcnt lgkmcnt(9)
	v_mfma_f32_16x16x32_bf16 v[40:43], v[88:91], v[120:123], v[40:43]
	s_waitcnt lgkmcnt(9)
	v_mfma_f32_16x16x32_bf16 v[44:47], v[88:91], v[124:127], v[44:47]
	s_waitcnt lgkmcnt(8)
	v_mfma_f32_16x16x32_bf16 v[48:51], v[92:95], v[112:115], v[48:51]
	s_waitcnt lgkmcnt(8)
	v_mfma_f32_16x16x32_bf16 v[52:55], v[92:95], v[116:119], v[52:55]
	s_waitcnt lgkmcnt(8)
	v_mfma_f32_16x16x32_bf16 v[56:59], v[92:95], v[120:123], v[56:59]
	s_waitcnt lgkmcnt(8)
	v_mfma_f32_16x16x32_bf16 v[60:63], v[92:95], v[124:127], v[60:63]
	s_waitcnt lgkmcnt(6)
	v_mfma_f32_16x16x32_bf16 v[160:163], v[64:67], v[96:99], v[160:163]
	ds_read_b128 v[80:83], v220 offset:16384
	s_waitcnt lgkmcnt(6)
	v_mfma_f32_16x16x32_bf16 v[164:167], v[64:67], v[100:103], v[164:167]
	ds_read_b128 v[112:115], v224 offset:49152
	s_waitcnt lgkmcnt(6)
	v_mfma_f32_16x16x32_bf16 v[168:171], v[64:67], v[104:107], v[168:171]
	ds_read_b128 v[116:119], v224 offset:51200
	s_waitcnt lgkmcnt(6)
	v_mfma_f32_16x16x32_bf16 v[172:175], v[64:67], v[108:111], v[172:175]
	ds_read_b128 v[120:123], v224 offset:53248
	s_waitcnt lgkmcnt(6)
	v_mfma_f32_16x16x32_bf16 v[176:179], v[68:71], v[96:99], v[176:179]
	ds_read_b128 v[124:127], v224 offset:55296
	s_waitcnt lgkmcnt(7)
	v_mfma_f32_16x16x32_bf16 v[180:183], v[68:71], v[100:103], v[180:183]
	ds_read_b128 v[84:87], v220 offset:18432
	s_waitcnt lgkmcnt(8)
	v_mfma_f32_16x16x32_bf16 v[184:187], v[68:71], v[104:107], v[184:187]
	ds_read_b128 v[88:91], v220 offset:20480
	s_waitcnt lgkmcnt(9)
	v_mfma_f32_16x16x32_bf16 v[188:191], v[68:71], v[108:111], v[188:191]
	ds_read_b128 v[92:95], v220 offset:22528
	s_waitcnt lgkmcnt(9)
	v_mfma_f32_16x16x32_bf16 v[192:195], v[72:75], v[96:99], v[192:195]
	s_waitcnt lgkmcnt(9)
	v_mfma_f32_16x16x32_bf16 v[196:199], v[72:75], v[100:103], v[196:199]
	s_waitcnt lgkmcnt(9)
	v_mfma_f32_16x16x32_bf16 v[200:203], v[72:75], v[104:107], v[200:203]
	s_waitcnt lgkmcnt(9)
	v_mfma_f32_16x16x32_bf16 v[204:207], v[72:75], v[108:111], v[204:207]
	s_waitcnt vmcnt(0) lgkmcnt(0)
	s_barrier
	s_add_u32 m0, s38, 16384
	s_nop 0
	global_load_lds_dwordx4 v226, s[100:101]
	s_waitcnt lgkmcnt(8)
	v_mfma_f32_16x16x32_bf16 v[208:211], v[76:79], v[96:99], v[208:211]
	s_add_u32 m0, s38, 20480
	s_nop 0
	global_load_lds_dwordx4 v228, s[100:101]
	s_waitcnt lgkmcnt(8)
	v_mfma_f32_16x16x32_bf16 v[212:215], v[76:79], v[100:103], v[212:215]
	s_add_u32 m0, s38, 24576
	s_nop 0
	global_load_lds_dwordx4 v244, s[100:101]
	s_waitcnt lgkmcnt(8)
	v_mfma_f32_16x16x32_bf16 v[216:219], v[76:79], v[104:107], v[216:219]
	s_add_u32 m0, s38, 28672
	s_nop 0
	global_load_lds_dwordx4 v245, s[100:101]
	s_add_u32 s100, s100, 128
	s_addc_u32 s101, s101, 0
	s_waitcnt lgkmcnt(8)
	v_mfma_f32_16x16x32_bf16 v[230:233], v[76:79], v[108:111], v[230:233]
	s_add_u32 m0, s38, 49152
	s_nop 0
	global_load_lds_dwordx4 v226, s[4:5]
	s_waitcnt lgkmcnt(6)
	v_mfma_f32_16x16x32_bf16 v[160:163], v[80:83], v[112:115], v[160:163]
	ds_read_b128 v[64:67], v151 offset:0
	s_add_u32 m0, s38, 53248
	s_nop 0
	global_load_lds_dwordx4 v228, s[4:5]
	s_waitcnt lgkmcnt(6)
	v_mfma_f32_16x16x32_bf16 v[164:167], v[80:83], v[116:119], v[164:167]
	ds_read_b128 v[96:99], v222 offset:32768
	s_add_u32 m0, s38, 57344
	s_nop 0
	global_load_lds_dwordx4 v244, s[4:5]
	s_waitcnt lgkmcnt(6)
	v_mfma_f32_16x16x32_bf16 v[168:171], v[80:83], v[120:123], v[168:171]
	ds_read_b128 v[100:103], v222 offset:34816
	s_add_u32 m0, s38, 61440
	s_nop 0
	global_load_lds_dwordx4 v245, s[4:5]
	s_add_u32 s4, s4, 128
	s_addc_u32 s5, s5, 0
	s_waitcnt lgkmcnt(6)
	v_mfma_f32_16x16x32_bf16 v[172:175], v[80:83], v[124:127], v[172:175]
	ds_read_b128 v[104:107], v222 offset:36864
	s_waitcnt lgkmcnt(6)
	v_mfma_f32_16x16x32_bf16 v[176:179], v[84:87], v[112:115], v[176:179]
	ds_read_b128 v[108:111], v222 offset:38912
	s_waitcnt lgkmcnt(7)
	v_mfma_f32_16x16x32_bf16 v[180:183], v[84:87], v[116:119], v[180:183]
	ds_read_b128 v[68:71], v151 offset:2048
	s_waitcnt lgkmcnt(8)
	v_mfma_f32_16x16x32_bf16 v[184:187], v[84:87], v[120:123], v[184:187]
	ds_read_b128 v[72:75], v151 offset:4096
	s_waitcnt lgkmcnt(9)
	v_mfma_f32_16x16x32_bf16 v[188:191], v[84:87], v[124:127], v[188:191]
	ds_read_b128 v[76:79], v151 offset:6144
	s_waitcnt lgkmcnt(9)
	v_mfma_f32_16x16x32_bf16 v[192:195], v[88:91], v[112:115], v[192:195]
	s_waitcnt lgkmcnt(9)
	v_mfma_f32_16x16x32_bf16 v[196:199], v[88:91], v[116:119], v[196:199]
	s_waitcnt lgkmcnt(9)
	v_mfma_f32_16x16x32_bf16 v[200:203], v[88:91], v[120:123], v[200:203]
	s_waitcnt lgkmcnt(9)
	v_mfma_f32_16x16x32_bf16 v[204:207], v[88:91], v[124:127], v[204:207]
	s_waitcnt lgkmcnt(8)
	v_mfma_f32_16x16x32_bf16 v[208:211], v[92:95], v[112:115], v[208:211]
	s_waitcnt lgkmcnt(8)
	v_mfma_f32_16x16x32_bf16 v[212:215], v[92:95], v[116:119], v[212:215]
	s_waitcnt lgkmcnt(8)
	v_mfma_f32_16x16x32_bf16 v[216:219], v[92:95], v[120:123], v[216:219]
	s_waitcnt lgkmcnt(8)
	v_mfma_f32_16x16x32_bf16 v[230:233], v[92:95], v[124:127], v[230:233]
	s_waitcnt lgkmcnt(6)
	v_mfma_f32_16x16x32_bf16 v[0:3], v[64:67], v[96:99], v[0:3]
	ds_read_b128 v[80:83], v220 offset:0
	s_waitcnt lgkmcnt(6)
	v_mfma_f32_16x16x32_bf16 v[4:7], v[64:67], v[100:103], v[4:7]
	ds_read_b128 v[112:115], v224 offset:32768
	s_waitcnt lgkmcnt(6)
	v_mfma_f32_16x16x32_bf16 v[8:11], v[64:67], v[104:107], v[8:11]
	ds_read_b128 v[116:119], v224 offset:34816
	s_waitcnt lgkmcnt(6)
	v_mfma_f32_16x16x32_bf16 v[12:15], v[64:67], v[108:111], v[12:15]
	ds_read_b128 v[120:123], v224 offset:36864
	s_waitcnt lgkmcnt(6)
	v_mfma_f32_16x16x32_bf16 v[16:19], v[68:71], v[96:99], v[16:19]
	ds_read_b128 v[124:127], v224 offset:38912
	s_waitcnt lgkmcnt(7)
	v_mfma_f32_16x16x32_bf16 v[20:23], v[68:71], v[100:103], v[20:23]
	ds_read_b128 v[84:87], v220 offset:2048
	s_waitcnt lgkmcnt(8)
	v_mfma_f32_16x16x32_bf16 v[24:27], v[68:71], v[104:107], v[24:27]
	ds_read_b128 v[88:91], v220 offset:4096
	s_waitcnt lgkmcnt(9)
	v_mfma_f32_16x16x32_bf16 v[28:31], v[68:71], v[108:111], v[28:31]
	ds_read_b128 v[92:95], v220 offset:6144
	s_waitcnt lgkmcnt(9)
	v_mfma_f32_16x16x32_bf16 v[32:35], v[72:75], v[96:99], v[32:35]
	s_waitcnt lgkmcnt(9)
	v_mfma_f32_16x16x32_bf16 v[36:39], v[72:75], v[100:103], v[36:39]
	s_waitcnt lgkmcnt(9)
	v_mfma_f32_16x16x32_bf16 v[40:43], v[72:75], v[104:107], v[40:43]
	s_waitcnt lgkmcnt(9)
	v_mfma_f32_16x16x32_bf16 v[44:47], v[72:75], v[108:111], v[44:47]
	s_waitcnt vmcnt(4) lgkmcnt(0)
	s_barrier
	s_add_u32 m0, s38, 0
	s_nop 0
	global_load_lds_dwordx4 v226, s[98:99]
	s_waitcnt lgkmcnt(8)
	v_mfma_f32_16x16x32_bf16 v[48:51], v[76:79], v[96:99], v[48:51]
	s_add_u32 m0, s38, 4096
	s_nop 0
	global_load_lds_dwordx4 v228, s[98:99]
	s_waitcnt lgkmcnt(8)
	v_mfma_f32_16x16x32_bf16 v[52:55], v[76:79], v[100:103], v[52:55]
	s_add_u32 m0, s38, 8192
	s_nop 0
	global_load_lds_dwordx4 v244, s[98:99]
	s_waitcnt lgkmcnt(8)
	v_mfma_f32_16x16x32_bf16 v[56:59], v[76:79], v[104:107], v[56:59]
	s_add_u32 m0, s38, 12288
	s_nop 0
	global_load_lds_dwordx4 v245, s[98:99]
	s_add_u32 s98, s98, 128
	s_addc_u32 s99, s99, 0
	s_waitcnt lgkmcnt(8)
	v_mfma_f32_16x16x32_bf16 v[60:63], v[76:79], v[108:111], v[60:63]
	s_waitcnt lgkmcnt(6)
	v_mfma_f32_16x16x32_bf16 v[0:3], v[80:83], v[112:115], v[0:3]
	ds_read_b128 v[64:67], v151 offset:16384
	s_waitcnt lgkmcnt(6)
	v_mfma_f32_16x16x32_bf16 v[4:7], v[80:83], v[116:119], v[4:7]
	ds_read_b128 v[96:99], v222 offset:32768
	s_waitcnt lgkmcnt(6)
	v_mfma_f32_16x16x32_bf16 v[8:11], v[80:83], v[120:123], v[8:11]
	ds_read_b128 v[100:103], v222 offset:34816
	s_waitcnt lgkmcnt(6)
	v_mfma_f32_16x16x32_bf16 v[12:15], v[80:83], v[124:127], v[12:15]
	ds_read_b128 v[104:107], v222 offset:36864
	s_waitcnt lgkmcnt(6)
	v_mfma_f32_16x16x32_bf16 v[16:19], v[84:87], v[112:115], v[16:19]
	ds_read_b128 v[108:111], v222 offset:38912
	s_waitcnt lgkmcnt(7)
	v_mfma_f32_16x16x32_bf16 v[20:23], v[84:87], v[116:119], v[20:23]
	ds_read_b128 v[68:71], v151 offset:18432
	s_waitcnt lgkmcnt(8)
	v_mfma_f32_16x16x32_bf16 v[24:27], v[84:87], v[120:123], v[24:27]
	ds_read_b128 v[72:75], v151 offset:20480
	s_waitcnt lgkmcnt(9)
	v_mfma_f32_16x16x32_bf16 v[28:31], v[84:87], v[124:127], v[28:31]
	ds_read_b128 v[76:79], v151 offset:22528
	s_waitcnt lgkmcnt(9)
	v_mfma_f32_16x16x32_bf16 v[32:35], v[88:91], v[112:115], v[32:35]
	s_waitcnt lgkmcnt(9)
	v_mfma_f32_16x16x32_bf16 v[36:39], v[88:91], v[116:119], v[36:39]
	s_waitcnt lgkmcnt(9)
	v_mfma_f32_16x16x32_bf16 v[40:43], v[88:91], v[120:123], v[40:43]
	s_waitcnt lgkmcnt(9)
	v_mfma_f32_16x16x32_bf16 v[44:47], v[88:91], v[124:127], v[44:47]
	s_waitcnt lgkmcnt(8)
	v_mfma_f32_16x16x32_bf16 v[48:51], v[92:95], v[112:115], v[48:51]
	s_waitcnt lgkmcnt(8)
	v_mfma_f32_16x16x32_bf16 v[52:55], v[92:95], v[116:119], v[52:55]
	s_waitcnt lgkmcnt(8)
	v_mfma_f32_16x16x32_bf16 v[56:59], v[92:95], v[120:123], v[56:59]
	s_waitcnt lgkmcnt(8)
	v_mfma_f32_16x16x32_bf16 v[60:63], v[92:95], v[124:127], v[60:63]
	s_waitcnt lgkmcnt(6)
	v_mfma_f32_16x16x32_bf16 v[160:163], v[64:67], v[96:99], v[160:163]
	ds_read_b128 v[80:83], v220 offset:16384
	s_waitcnt lgkmcnt(6)
	v_mfma_f32_16x16x32_bf16 v[164:167], v[64:67], v[100:103], v[164:167]
	ds_read_b128 v[112:115], v224 offset:32768
	s_waitcnt lgkmcnt(6)
	v_mfma_f32_16x16x32_bf16 v[168:171], v[64:67], v[104:107], v[168:171]
	ds_read_b128 v[116:119], v224 offset:34816
	s_waitcnt lgkmcnt(6)
	v_mfma_f32_16x16x32_bf16 v[172:175], v[64:67], v[108:111], v[172:175]
	ds_read_b128 v[120:123], v224 offset:36864
	s_waitcnt lgkmcnt(6)
	v_mfma_f32_16x16x32_bf16 v[176:179], v[68:71], v[96:99], v[176:179]
	ds_read_b128 v[124:127], v224 offset:38912
	s_waitcnt lgkmcnt(7)
	v_mfma_f32_16x16x32_bf16 v[180:183], v[68:71], v[100:103], v[180:183]
	ds_read_b128 v[84:87], v220 offset:18432
	s_waitcnt lgkmcnt(8)
	v_mfma_f32_16x16x32_bf16 v[184:187], v[68:71], v[104:107], v[184:187]
	ds_read_b128 v[88:91], v220 offset:20480
	s_waitcnt lgkmcnt(9)
	v_mfma_f32_16x16x32_bf16 v[188:191], v[68:71], v[108:111], v[188:191]
	ds_read_b128 v[92:95], v220 offset:22528
	s_waitcnt lgkmcnt(9)
	v_mfma_f32_16x16x32_bf16 v[192:195], v[72:75], v[96:99], v[192:195]
	s_waitcnt lgkmcnt(9)
	v_mfma_f32_16x16x32_bf16 v[196:199], v[72:75], v[100:103], v[196:199]
	s_waitcnt lgkmcnt(9)
	v_mfma_f32_16x16x32_bf16 v[200:203], v[72:75], v[104:107], v[200:203]
	s_waitcnt lgkmcnt(9)
	v_mfma_f32_16x16x32_bf16 v[204:207], v[72:75], v[108:111], v[204:207]
	s_waitcnt vmcnt(0) lgkmcnt(0)
	s_barrier
	s_add_u32 m0, s38, 16384
	s_nop 0
	global_load_lds_dwordx4 v226, s[100:101]
	s_waitcnt lgkmcnt(8)
	v_mfma_f32_16x16x32_bf16 v[208:211], v[76:79], v[96:99], v[208:211]
	s_add_u32 m0, s38, 20480
	s_nop 0
	global_load_lds_dwordx4 v228, s[100:101]
	s_waitcnt lgkmcnt(8)
	v_mfma_f32_16x16x32_bf16 v[212:215], v[76:79], v[100:103], v[212:215]
	s_add_u32 m0, s38, 24576
	s_nop 0
	global_load_lds_dwordx4 v244, s[100:101]
	s_waitcnt lgkmcnt(8)
	v_mfma_f32_16x16x32_bf16 v[216:219], v[76:79], v[104:107], v[216:219]
	s_add_u32 m0, s38, 28672
	s_nop 0
	global_load_lds_dwordx4 v245, s[100:101]
	s_add_u32 s100, s100, 128
	s_addc_u32 s101, s101, 0
	s_waitcnt lgkmcnt(8)
	v_mfma_f32_16x16x32_bf16 v[230:233], v[76:79], v[108:111], v[230:233]
	s_add_u32 m0, s38, 32768
	s_nop 0
	global_load_lds_dwordx4 v226, s[4:5]
	s_waitcnt lgkmcnt(6)
	v_mfma_f32_16x16x32_bf16 v[160:163], v[80:83], v[112:115], v[160:163]
	ds_read_b128 v[64:67], v151 offset:0
	s_add_u32 m0, s38, 36864
	s_nop 0
	global_load_lds_dwordx4 v228, s[4:5]
	s_waitcnt lgkmcnt(6)
	v_mfma_f32_16x16x32_bf16 v[164:167], v[80:83], v[116:119], v[164:167]
	ds_read_b128 v[96:99], v222 offset:49152
	s_add_u32 m0, s38, 40960
	s_nop 0
	global_load_lds_dwordx4 v244, s[4:5]
	s_waitcnt lgkmcnt(6)
	v_mfma_f32_16x16x32_bf16 v[168:171], v[80:83], v[120:123], v[168:171]
	ds_read_b128 v[100:103], v222 offset:51200
	s_add_u32 m0, s38, 45056
	s_nop 0
	global_load_lds_dwordx4 v245, s[4:5]
	s_add_u32 s4, s4, 128
	s_addc_u32 s5, s5, 0
	s_waitcnt lgkmcnt(6)
	v_mfma_f32_16x16x32_bf16 v[172:175], v[80:83], v[124:127], v[172:175]
	ds_read_b128 v[104:107], v222 offset:53248
	s_waitcnt lgkmcnt(6)
	v_mfma_f32_16x16x32_bf16 v[176:179], v[84:87], v[112:115], v[176:179]
	ds_read_b128 v[108:111], v222 offset:55296
	s_waitcnt lgkmcnt(7)
	v_mfma_f32_16x16x32_bf16 v[180:183], v[84:87], v[116:119], v[180:183]
	ds_read_b128 v[68:71], v151 offset:2048
	s_waitcnt lgkmcnt(8)
	v_mfma_f32_16x16x32_bf16 v[184:187], v[84:87], v[120:123], v[184:187]
	ds_read_b128 v[72:75], v151 offset:4096
	s_waitcnt lgkmcnt(9)
	v_mfma_f32_16x16x32_bf16 v[188:191], v[84:87], v[124:127], v[188:191]
	ds_read_b128 v[76:79], v151 offset:6144
	s_waitcnt lgkmcnt(9)
	v_mfma_f32_16x16x32_bf16 v[192:195], v[88:91], v[112:115], v[192:195]
	s_waitcnt lgkmcnt(9)
	v_mfma_f32_16x16x32_bf16 v[196:199], v[88:91], v[116:119], v[196:199]
	s_waitcnt lgkmcnt(9)
	v_mfma_f32_16x16x32_bf16 v[200:203], v[88:91], v[120:123], v[200:203]
	s_waitcnt lgkmcnt(9)
	v_mfma_f32_16x16x32_bf16 v[204:207], v[88:91], v[124:127], v[204:207]
	s_waitcnt lgkmcnt(8)
	v_mfma_f32_16x16x32_bf16 v[208:211], v[92:95], v[112:115], v[208:211]
	s_waitcnt lgkmcnt(8)
	v_mfma_f32_16x16x32_bf16 v[212:215], v[92:95], v[116:119], v[212:215]
	s_waitcnt lgkmcnt(8)
	v_mfma_f32_16x16x32_bf16 v[216:219], v[92:95], v[120:123], v[216:219]
	s_waitcnt lgkmcnt(8)
	v_mfma_f32_16x16x32_bf16 v[230:233], v[92:95], v[124:127], v[230:233]
	s_waitcnt lgkmcnt(6)
	v_mfma_f32_16x16x32_bf16 v[0:3], v[64:67], v[96:99], v[0:3]
	ds_read_b128 v[80:83], v220 offset:0
	s_waitcnt lgkmcnt(6)
	v_mfma_f32_16x16x32_bf16 v[4:7], v[64:67], v[100:103], v[4:7]
	ds_read_b128 v[112:115], v224 offset:49152
	s_waitcnt lgkmcnt(6)
	v_mfma_f32_16x16x32_bf16 v[8:11], v[64:67], v[104:107], v[8:11]
	ds_read_b128 v[116:119], v224 offset:51200
	s_waitcnt lgkmcnt(6)
	v_mfma_f32_16x16x32_bf16 v[12:15], v[64:67], v[108:111], v[12:15]
	ds_read_b128 v[120:123], v224 offset:53248
	s_waitcnt lgkmcnt(6)
	v_mfma_f32_16x16x32_bf16 v[16:19], v[68:71], v[96:99], v[16:19]
	ds_read_b128 v[124:127], v224 offset:55296
	s_waitcnt lgkmcnt(7)
	v_mfma_f32_16x16x32_bf16 v[20:23], v[68:71], v[100:103], v[20:23]
	ds_read_b128 v[84:87], v220 offset:2048
	s_waitcnt lgkmcnt(8)
	v_mfma_f32_16x16x32_bf16 v[24:27], v[68:71], v[104:107], v[24:27]
	ds_read_b128 v[88:91], v220 offset:4096
	s_waitcnt lgkmcnt(9)
	v_mfma_f32_16x16x32_bf16 v[28:31], v[68:71], v[108:111], v[28:31]
	ds_read_b128 v[92:95], v220 offset:6144
	s_waitcnt lgkmcnt(9)
	v_mfma_f32_16x16x32_bf16 v[32:35], v[72:75], v[96:99], v[32:35]
	s_waitcnt lgkmcnt(9)
	v_mfma_f32_16x16x32_bf16 v[36:39], v[72:75], v[100:103], v[36:39]
	s_waitcnt lgkmcnt(9)
	v_mfma_f32_16x16x32_bf16 v[40:43], v[72:75], v[104:107], v[40:43]
	s_waitcnt lgkmcnt(9)
	v_mfma_f32_16x16x32_bf16 v[44:47], v[72:75], v[108:111], v[44:47]
	s_waitcnt vmcnt(4) lgkmcnt(0)
	s_barrier
	s_add_u32 m0, s38, 0
	s_nop 0
	global_load_lds_dwordx4 v226, s[98:99]
	s_waitcnt lgkmcnt(8)
	v_mfma_f32_16x16x32_bf16 v[48:51], v[76:79], v[96:99], v[48:51]
	s_add_u32 m0, s38, 4096
	s_nop 0
	global_load_lds_dwordx4 v228, s[98:99]
	s_waitcnt lgkmcnt(8)
	v_mfma_f32_16x16x32_bf16 v[52:55], v[76:79], v[100:103], v[52:55]
	s_add_u32 m0, s38, 8192
	s_nop 0
	global_load_lds_dwordx4 v244, s[98:99]
	s_waitcnt lgkmcnt(8)
	v_mfma_f32_16x16x32_bf16 v[56:59], v[76:79], v[104:107], v[56:59]
	s_add_u32 m0, s38, 12288
	s_nop 0
	global_load_lds_dwordx4 v245, s[98:99]
	s_add_u32 s98, s98, 128
	s_addc_u32 s99, s99, 0
	s_waitcnt lgkmcnt(8)
	v_mfma_f32_16x16x32_bf16 v[60:63], v[76:79], v[108:111], v[60:63]
	s_waitcnt lgkmcnt(6)
	v_mfma_f32_16x16x32_bf16 v[0:3], v[80:83], v[112:115], v[0:3]
	ds_read_b128 v[64:67], v151 offset:16384
	s_waitcnt lgkmcnt(6)
	v_mfma_f32_16x16x32_bf16 v[4:7], v[80:83], v[116:119], v[4:7]
	ds_read_b128 v[96:99], v222 offset:49152
	s_waitcnt lgkmcnt(6)
	v_mfma_f32_16x16x32_bf16 v[8:11], v[80:83], v[120:123], v[8:11]
	ds_read_b128 v[100:103], v222 offset:51200
	s_waitcnt lgkmcnt(6)
	v_mfma_f32_16x16x32_bf16 v[12:15], v[80:83], v[124:127], v[12:15]
	ds_read_b128 v[104:107], v222 offset:53248
	s_waitcnt lgkmcnt(6)
	v_mfma_f32_16x16x32_bf16 v[16:19], v[84:87], v[112:115], v[16:19]
	ds_read_b128 v[108:111], v222 offset:55296
	s_waitcnt lgkmcnt(7)
	v_mfma_f32_16x16x32_bf16 v[20:23], v[84:87], v[116:119], v[20:23]
	ds_read_b128 v[68:71], v151 offset:18432
	s_waitcnt lgkmcnt(8)
	v_mfma_f32_16x16x32_bf16 v[24:27], v[84:87], v[120:123], v[24:27]
	ds_read_b128 v[72:75], v151 offset:20480
	s_waitcnt lgkmcnt(9)
	v_mfma_f32_16x16x32_bf16 v[28:31], v[84:87], v[124:127], v[28:31]
	ds_read_b128 v[76:79], v151 offset:22528
	s_waitcnt lgkmcnt(9)
	v_mfma_f32_16x16x32_bf16 v[32:35], v[88:91], v[112:115], v[32:35]
	s_waitcnt lgkmcnt(9)
	v_mfma_f32_16x16x32_bf16 v[36:39], v[88:91], v[116:119], v[36:39]
	s_waitcnt lgkmcnt(9)
	v_mfma_f32_16x16x32_bf16 v[40:43], v[88:91], v[120:123], v[40:43]
	s_waitcnt lgkmcnt(9)
	v_mfma_f32_16x16x32_bf16 v[44:47], v[88:91], v[124:127], v[44:47]
	s_waitcnt lgkmcnt(8)
	v_mfma_f32_16x16x32_bf16 v[48:51], v[92:95], v[112:115], v[48:51]
	s_waitcnt lgkmcnt(8)
	v_mfma_f32_16x16x32_bf16 v[52:55], v[92:95], v[116:119], v[52:55]
	s_waitcnt lgkmcnt(8)
	v_mfma_f32_16x16x32_bf16 v[56:59], v[92:95], v[120:123], v[56:59]
	s_waitcnt lgkmcnt(8)
	v_mfma_f32_16x16x32_bf16 v[60:63], v[92:95], v[124:127], v[60:63]
	s_waitcnt lgkmcnt(6)
	v_mfma_f32_16x16x32_bf16 v[160:163], v[64:67], v[96:99], v[160:163]
	ds_read_b128 v[80:83], v220 offset:16384
	s_waitcnt lgkmcnt(6)
	v_mfma_f32_16x16x32_bf16 v[164:167], v[64:67], v[100:103], v[164:167]
	ds_read_b128 v[112:115], v224 offset:49152
	s_waitcnt lgkmcnt(6)
	v_mfma_f32_16x16x32_bf16 v[168:171], v[64:67], v[104:107], v[168:171]
	ds_read_b128 v[116:119], v224 offset:51200
	s_waitcnt lgkmcnt(6)
	v_mfma_f32_16x16x32_bf16 v[172:175], v[64:67], v[108:111], v[172:175]
	ds_read_b128 v[120:123], v224 offset:53248
	s_waitcnt lgkmcnt(6)
	v_mfma_f32_16x16x32_bf16 v[176:179], v[68:71], v[96:99], v[176:179]
	ds_read_b128 v[124:127], v224 offset:55296
	s_waitcnt lgkmcnt(7)
	v_mfma_f32_16x16x32_bf16 v[180:183], v[68:71], v[100:103], v[180:183]
	ds_read_b128 v[84:87], v220 offset:18432
	s_waitcnt lgkmcnt(8)
	v_mfma_f32_16x16x32_bf16 v[184:187], v[68:71], v[104:107], v[184:187]
	ds_read_b128 v[88:91], v220 offset:20480
	s_waitcnt lgkmcnt(9)
	v_mfma_f32_16x16x32_bf16 v[188:191], v[68:71], v[108:111], v[188:191]
	ds_read_b128 v[92:95], v220 offset:22528
	s_waitcnt lgkmcnt(9)
	v_mfma_f32_16x16x32_bf16 v[192:195], v[72:75], v[96:99], v[192:195]
	s_waitcnt lgkmcnt(9)
	v_mfma_f32_16x16x32_bf16 v[196:199], v[72:75], v[100:103], v[196:199]
	s_waitcnt lgkmcnt(9)
	v_mfma_f32_16x16x32_bf16 v[200:203], v[72:75], v[104:107], v[200:203]
	s_waitcnt lgkmcnt(9)
	v_mfma_f32_16x16x32_bf16 v[204:207], v[72:75], v[108:111], v[204:207]
	s_waitcnt vmcnt(0) lgkmcnt(0)
	s_barrier
	s_add_u32 m0, s38, 16384
	s_nop 0
	global_load_lds_dwordx4 v226, s[100:101]
	s_waitcnt lgkmcnt(8)
	v_mfma_f32_16x16x32_bf16 v[208:211], v[76:79], v[96:99], v[208:211]
	s_add_u32 m0, s38, 20480
	s_nop 0
	global_load_lds_dwordx4 v228, s[100:101]
	s_waitcnt lgkmcnt(8)
	v_mfma_f32_16x16x32_bf16 v[212:215], v[76:79], v[100:103], v[212:215]
	s_add_u32 m0, s38, 24576
	s_nop 0
	global_load_lds_dwordx4 v244, s[100:101]
	s_waitcnt lgkmcnt(8)
	v_mfma_f32_16x16x32_bf16 v[216:219], v[76:79], v[104:107], v[216:219]
	s_add_u32 m0, s38, 28672
	s_nop 0
	global_load_lds_dwordx4 v245, s[100:101]
	s_add_u32 s100, s100, 128
	s_addc_u32 s101, s101, 0
	s_waitcnt lgkmcnt(8)
	v_mfma_f32_16x16x32_bf16 v[230:233], v[76:79], v[108:111], v[230:233]
	s_add_u32 m0, s38, 49152
	s_nop 0
	global_load_lds_dwordx4 v226, s[4:5]
	s_waitcnt lgkmcnt(6)
	v_mfma_f32_16x16x32_bf16 v[160:163], v[80:83], v[112:115], v[160:163]
	ds_read_b128 v[64:67], v151 offset:0
	s_add_u32 m0, s38, 53248
	s_nop 0
	global_load_lds_dwordx4 v228, s[4:5]
	s_waitcnt lgkmcnt(6)
	v_mfma_f32_16x16x32_bf16 v[164:167], v[80:83], v[116:119], v[164:167]
	ds_read_b128 v[96:99], v222 offset:32768
	s_add_u32 m0, s38, 57344
	s_nop 0
	global_load_lds_dwordx4 v244, s[4:5]
	s_waitcnt lgkmcnt(6)
	v_mfma_f32_16x16x32_bf16 v[168:171], v[80:83], v[120:123], v[168:171]
	ds_read_b128 v[100:103], v222 offset:34816
	s_add_u32 m0, s38, 61440
	s_nop 0
	global_load_lds_dwordx4 v245, s[4:5]
	s_add_u32 s4, s4, 128
	s_addc_u32 s5, s5, 0
	s_waitcnt lgkmcnt(6)
	v_mfma_f32_16x16x32_bf16 v[172:175], v[80:83], v[124:127], v[172:175]
	ds_read_b128 v[104:107], v222 offset:36864
	s_waitcnt lgkmcnt(6)
	v_mfma_f32_16x16x32_bf16 v[176:179], v[84:87], v[112:115], v[176:179]
	ds_read_b128 v[108:111], v222 offset:38912
	s_waitcnt lgkmcnt(7)
	v_mfma_f32_16x16x32_bf16 v[180:183], v[84:87], v[116:119], v[180:183]
	ds_read_b128 v[68:71], v151 offset:2048
	s_waitcnt lgkmcnt(8)
	v_mfma_f32_16x16x32_bf16 v[184:187], v[84:87], v[120:123], v[184:187]
	ds_read_b128 v[72:75], v151 offset:4096
	s_waitcnt lgkmcnt(9)
	v_mfma_f32_16x16x32_bf16 v[188:191], v[84:87], v[124:127], v[188:191]
	ds_read_b128 v[76:79], v151 offset:6144
	s_waitcnt lgkmcnt(9)
	v_mfma_f32_16x16x32_bf16 v[192:195], v[88:91], v[112:115], v[192:195]
	s_waitcnt lgkmcnt(9)
	v_mfma_f32_16x16x32_bf16 v[196:199], v[88:91], v[116:119], v[196:199]
	s_waitcnt lgkmcnt(9)
	v_mfma_f32_16x16x32_bf16 v[200:203], v[88:91], v[120:123], v[200:203]
	s_waitcnt lgkmcnt(9)
	v_mfma_f32_16x16x32_bf16 v[204:207], v[88:91], v[124:127], v[204:207]
	s_waitcnt lgkmcnt(8)
	v_mfma_f32_16x16x32_bf16 v[208:211], v[92:95], v[112:115], v[208:211]
	s_waitcnt lgkmcnt(8)
	v_mfma_f32_16x16x32_bf16 v[212:215], v[92:95], v[116:119], v[212:215]
	s_waitcnt lgkmcnt(8)
	v_mfma_f32_16x16x32_bf16 v[216:219], v[92:95], v[120:123], v[216:219]
	s_waitcnt lgkmcnt(8)
	v_mfma_f32_16x16x32_bf16 v[230:233], v[92:95], v[124:127], v[230:233]
	s_waitcnt lgkmcnt(6)
	v_mfma_f32_16x16x32_bf16 v[0:3], v[64:67], v[96:99], v[0:3]
	ds_read_b128 v[80:83], v220 offset:0
	s_waitcnt lgkmcnt(6)
	v_mfma_f32_16x16x32_bf16 v[4:7], v[64:67], v[100:103], v[4:7]
	ds_read_b128 v[112:115], v224 offset:32768
	s_waitcnt lgkmcnt(6)
	v_mfma_f32_16x16x32_bf16 v[8:11], v[64:67], v[104:107], v[8:11]
	ds_read_b128 v[116:119], v224 offset:34816
	s_waitcnt lgkmcnt(6)
	v_mfma_f32_16x16x32_bf16 v[12:15], v[64:67], v[108:111], v[12:15]
	ds_read_b128 v[120:123], v224 offset:36864
	s_waitcnt lgkmcnt(6)
	v_mfma_f32_16x16x32_bf16 v[16:19], v[68:71], v[96:99], v[16:19]
	ds_read_b128 v[124:127], v224 offset:38912
	s_waitcnt lgkmcnt(7)
	v_mfma_f32_16x16x32_bf16 v[20:23], v[68:71], v[100:103], v[20:23]
	ds_read_b128 v[84:87], v220 offset:2048
	s_waitcnt lgkmcnt(8)
	v_mfma_f32_16x16x32_bf16 v[24:27], v[68:71], v[104:107], v[24:27]
	ds_read_b128 v[88:91], v220 offset:4096
	s_waitcnt lgkmcnt(9)
	v_mfma_f32_16x16x32_bf16 v[28:31], v[68:71], v[108:111], v[28:31]
	ds_read_b128 v[92:95], v220 offset:6144
	s_waitcnt lgkmcnt(9)
	v_mfma_f32_16x16x32_bf16 v[32:35], v[72:75], v[96:99], v[32:35]
	s_waitcnt lgkmcnt(9)
	v_mfma_f32_16x16x32_bf16 v[36:39], v[72:75], v[100:103], v[36:39]
	s_waitcnt lgkmcnt(9)
	v_mfma_f32_16x16x32_bf16 v[40:43], v[72:75], v[104:107], v[40:43]
	s_waitcnt lgkmcnt(9)
	v_mfma_f32_16x16x32_bf16 v[44:47], v[72:75], v[108:111], v[44:47]
	s_waitcnt vmcnt(4) lgkmcnt(0)
	s_barrier
	s_add_u32 m0, s38, 0
	s_nop 0
	global_load_lds_dwordx4 v226, s[98:99]
	s_waitcnt lgkmcnt(8)
	v_mfma_f32_16x16x32_bf16 v[48:51], v[76:79], v[96:99], v[48:51]
	s_add_u32 m0, s38, 4096
	s_nop 0
	global_load_lds_dwordx4 v228, s[98:99]
	s_waitcnt lgkmcnt(8)
	v_mfma_f32_16x16x32_bf16 v[52:55], v[76:79], v[100:103], v[52:55]
	s_add_u32 m0, s38, 8192
	s_nop 0
	global_load_lds_dwordx4 v244, s[98:99]
	s_waitcnt lgkmcnt(8)
	v_mfma_f32_16x16x32_bf16 v[56:59], v[76:79], v[104:107], v[56:59]
	s_add_u32 m0, s38, 12288
	s_nop 0
	global_load_lds_dwordx4 v245, s[98:99]
	s_add_u32 s98, s98, 128
	s_addc_u32 s99, s99, 0
	s_waitcnt lgkmcnt(8)
	v_mfma_f32_16x16x32_bf16 v[60:63], v[76:79], v[108:111], v[60:63]
	s_waitcnt lgkmcnt(6)
	v_mfma_f32_16x16x32_bf16 v[0:3], v[80:83], v[112:115], v[0:3]
	ds_read_b128 v[64:67], v151 offset:16384
	s_waitcnt lgkmcnt(6)
	v_mfma_f32_16x16x32_bf16 v[4:7], v[80:83], v[116:119], v[4:7]
	ds_read_b128 v[96:99], v222 offset:32768
	s_waitcnt lgkmcnt(6)
	v_mfma_f32_16x16x32_bf16 v[8:11], v[80:83], v[120:123], v[8:11]
	ds_read_b128 v[100:103], v222 offset:34816
	s_waitcnt lgkmcnt(6)
	v_mfma_f32_16x16x32_bf16 v[12:15], v[80:83], v[124:127], v[12:15]
	ds_read_b128 v[104:107], v222 offset:36864
	s_waitcnt lgkmcnt(6)
	v_mfma_f32_16x16x32_bf16 v[16:19], v[84:87], v[112:115], v[16:19]
	ds_read_b128 v[108:111], v222 offset:38912
	s_waitcnt lgkmcnt(7)
	v_mfma_f32_16x16x32_bf16 v[20:23], v[84:87], v[116:119], v[20:23]
	ds_read_b128 v[68:71], v151 offset:18432
	s_waitcnt lgkmcnt(8)
	v_mfma_f32_16x16x32_bf16 v[24:27], v[84:87], v[120:123], v[24:27]
	ds_read_b128 v[72:75], v151 offset:20480
	s_waitcnt lgkmcnt(9)
	v_mfma_f32_16x16x32_bf16 v[28:31], v[84:87], v[124:127], v[28:31]
	ds_read_b128 v[76:79], v151 offset:22528
	s_waitcnt lgkmcnt(9)
	v_mfma_f32_16x16x32_bf16 v[32:35], v[88:91], v[112:115], v[32:35]
	s_waitcnt lgkmcnt(9)
	v_mfma_f32_16x16x32_bf16 v[36:39], v[88:91], v[116:119], v[36:39]
	s_waitcnt lgkmcnt(9)
	v_mfma_f32_16x16x32_bf16 v[40:43], v[88:91], v[120:123], v[40:43]
	s_waitcnt lgkmcnt(9)
	v_mfma_f32_16x16x32_bf16 v[44:47], v[88:91], v[124:127], v[44:47]
	s_waitcnt lgkmcnt(8)
	v_mfma_f32_16x16x32_bf16 v[48:51], v[92:95], v[112:115], v[48:51]
	s_waitcnt lgkmcnt(8)
	v_mfma_f32_16x16x32_bf16 v[52:55], v[92:95], v[116:119], v[52:55]
	s_waitcnt lgkmcnt(8)
	v_mfma_f32_16x16x32_bf16 v[56:59], v[92:95], v[120:123], v[56:59]
	s_waitcnt lgkmcnt(8)
	v_mfma_f32_16x16x32_bf16 v[60:63], v[92:95], v[124:127], v[60:63]
	s_waitcnt lgkmcnt(6)
	v_mfma_f32_16x16x32_bf16 v[160:163], v[64:67], v[96:99], v[160:163]
	ds_read_b128 v[80:83], v220 offset:16384
	s_waitcnt lgkmcnt(6)
	v_mfma_f32_16x16x32_bf16 v[164:167], v[64:67], v[100:103], v[164:167]
	ds_read_b128 v[112:115], v224 offset:32768
	s_waitcnt lgkmcnt(6)
	v_mfma_f32_16x16x32_bf16 v[168:171], v[64:67], v[104:107], v[168:171]
	ds_read_b128 v[116:119], v224 offset:34816
	s_waitcnt lgkmcnt(6)
	v_mfma_f32_16x16x32_bf16 v[172:175], v[64:67], v[108:111], v[172:175]
	ds_read_b128 v[120:123], v224 offset:36864
	s_waitcnt lgkmcnt(6)
	v_mfma_f32_16x16x32_bf16 v[176:179], v[68:71], v[96:99], v[176:179]
	ds_read_b128 v[124:127], v224 offset:38912
	s_waitcnt lgkmcnt(7)
	v_mfma_f32_16x16x32_bf16 v[180:183], v[68:71], v[100:103], v[180:183]
	ds_read_b128 v[84:87], v220 offset:18432
	s_waitcnt lgkmcnt(8)
	v_mfma_f32_16x16x32_bf16 v[184:187], v[68:71], v[104:107], v[184:187]
	ds_read_b128 v[88:91], v220 offset:20480
	s_waitcnt lgkmcnt(9)
	v_mfma_f32_16x16x32_bf16 v[188:191], v[68:71], v[108:111], v[188:191]
	ds_read_b128 v[92:95], v220 offset:22528
	s_waitcnt lgkmcnt(9)
	v_mfma_f32_16x16x32_bf16 v[192:195], v[72:75], v[96:99], v[192:195]
	s_waitcnt lgkmcnt(9)
	v_mfma_f32_16x16x32_bf16 v[196:199], v[72:75], v[100:103], v[196:199]
	s_waitcnt lgkmcnt(9)
	v_mfma_f32_16x16x32_bf16 v[200:203], v[72:75], v[104:107], v[200:203]
	s_waitcnt lgkmcnt(9)
	v_mfma_f32_16x16x32_bf16 v[204:207], v[72:75], v[108:111], v[204:207]
	s_waitcnt vmcnt(0) lgkmcnt(0)
	s_barrier
	s_add_u32 m0, s38, 16384
	s_nop 0
	global_load_lds_dwordx4 v226, s[100:101]
	s_waitcnt lgkmcnt(8)
	v_mfma_f32_16x16x32_bf16 v[208:211], v[76:79], v[96:99], v[208:211]
	s_add_u32 m0, s38, 20480
	s_nop 0
	global_load_lds_dwordx4 v228, s[100:101]
	s_waitcnt lgkmcnt(8)
	v_mfma_f32_16x16x32_bf16 v[212:215], v[76:79], v[100:103], v[212:215]
	s_add_u32 m0, s38, 24576
	s_nop 0
	global_load_lds_dwordx4 v244, s[100:101]
	s_waitcnt lgkmcnt(8)
	v_mfma_f32_16x16x32_bf16 v[216:219], v[76:79], v[104:107], v[216:219]
	s_add_u32 m0, s38, 28672
	s_nop 0
	global_load_lds_dwordx4 v245, s[100:101]
	s_add_u32 s100, s100, 128
	s_addc_u32 s101, s101, 0
	s_waitcnt lgkmcnt(8)
	v_mfma_f32_16x16x32_bf16 v[230:233], v[76:79], v[108:111], v[230:233]
	s_add_u32 m0, s38, 32768
	s_nop 0
	global_load_lds_dwordx4 v226, s[4:5]
	s_waitcnt lgkmcnt(6)
	v_mfma_f32_16x16x32_bf16 v[160:163], v[80:83], v[112:115], v[160:163]
	ds_read_b128 v[64:67], v151 offset:0
	s_add_u32 m0, s38, 36864
	s_nop 0
	global_load_lds_dwordx4 v228, s[4:5]
	s_waitcnt lgkmcnt(6)
	v_mfma_f32_16x16x32_bf16 v[164:167], v[80:83], v[116:119], v[164:167]
	ds_read_b128 v[96:99], v222 offset:49152
	s_add_u32 m0, s38, 40960
	s_nop 0
	global_load_lds_dwordx4 v244, s[4:5]
	s_waitcnt lgkmcnt(6)
	v_mfma_f32_16x16x32_bf16 v[168:171], v[80:83], v[120:123], v[168:171]
	ds_read_b128 v[100:103], v222 offset:51200
	s_add_u32 m0, s38, 45056
	s_nop 0
	global_load_lds_dwordx4 v245, s[4:5]
	s_add_u32 s4, s4, 128
	s_addc_u32 s5, s5, 0
	s_waitcnt lgkmcnt(6)
	v_mfma_f32_16x16x32_bf16 v[172:175], v[80:83], v[124:127], v[172:175]
	ds_read_b128 v[104:107], v222 offset:53248
	s_waitcnt lgkmcnt(6)
	v_mfma_f32_16x16x32_bf16 v[176:179], v[84:87], v[112:115], v[176:179]
	ds_read_b128 v[108:111], v222 offset:55296
	s_waitcnt lgkmcnt(7)
	v_mfma_f32_16x16x32_bf16 v[180:183], v[84:87], v[116:119], v[180:183]
	ds_read_b128 v[68:71], v151 offset:2048
	s_waitcnt lgkmcnt(8)
	v_mfma_f32_16x16x32_bf16 v[184:187], v[84:87], v[120:123], v[184:187]
	ds_read_b128 v[72:75], v151 offset:4096
	s_waitcnt lgkmcnt(9)
	v_mfma_f32_16x16x32_bf16 v[188:191], v[84:87], v[124:127], v[188:191]
	ds_read_b128 v[76:79], v151 offset:6144
	s_waitcnt lgkmcnt(9)
	v_mfma_f32_16x16x32_bf16 v[192:195], v[88:91], v[112:115], v[192:195]
	s_waitcnt lgkmcnt(9)
	v_mfma_f32_16x16x32_bf16 v[196:199], v[88:91], v[116:119], v[196:199]
	s_waitcnt lgkmcnt(9)
	v_mfma_f32_16x16x32_bf16 v[200:203], v[88:91], v[120:123], v[200:203]
	s_waitcnt lgkmcnt(9)
	v_mfma_f32_16x16x32_bf16 v[204:207], v[88:91], v[124:127], v[204:207]
	s_waitcnt lgkmcnt(8)
	v_mfma_f32_16x16x32_bf16 v[208:211], v[92:95], v[112:115], v[208:211]
	s_waitcnt lgkmcnt(8)
	v_mfma_f32_16x16x32_bf16 v[212:215], v[92:95], v[116:119], v[212:215]
	s_waitcnt lgkmcnt(8)
	v_mfma_f32_16x16x32_bf16 v[216:219], v[92:95], v[120:123], v[216:219]
	s_waitcnt lgkmcnt(8)
	v_mfma_f32_16x16x32_bf16 v[230:233], v[92:95], v[124:127], v[230:233]
	s_waitcnt lgkmcnt(6)
	v_mfma_f32_16x16x32_bf16 v[0:3], v[64:67], v[96:99], v[0:3]
	ds_read_b128 v[80:83], v220 offset:0
	s_waitcnt lgkmcnt(6)
	v_mfma_f32_16x16x32_bf16 v[4:7], v[64:67], v[100:103], v[4:7]
	ds_read_b128 v[112:115], v224 offset:49152
	s_waitcnt lgkmcnt(6)
	v_mfma_f32_16x16x32_bf16 v[8:11], v[64:67], v[104:107], v[8:11]
	ds_read_b128 v[116:119], v224 offset:51200
	s_waitcnt lgkmcnt(6)
	v_mfma_f32_16x16x32_bf16 v[12:15], v[64:67], v[108:111], v[12:15]
	ds_read_b128 v[120:123], v224 offset:53248
	s_waitcnt lgkmcnt(6)
	v_mfma_f32_16x16x32_bf16 v[16:19], v[68:71], v[96:99], v[16:19]
	ds_read_b128 v[124:127], v224 offset:55296
	s_waitcnt lgkmcnt(7)
	v_mfma_f32_16x16x32_bf16 v[20:23], v[68:71], v[100:103], v[20:23]
	ds_read_b128 v[84:87], v220 offset:2048
	s_waitcnt lgkmcnt(8)
	v_mfma_f32_16x16x32_bf16 v[24:27], v[68:71], v[104:107], v[24:27]
	ds_read_b128 v[88:91], v220 offset:4096
	s_waitcnt lgkmcnt(9)
	v_mfma_f32_16x16x32_bf16 v[28:31], v[68:71], v[108:111], v[28:31]
	ds_read_b128 v[92:95], v220 offset:6144
	s_waitcnt lgkmcnt(9)
	v_mfma_f32_16x16x32_bf16 v[32:35], v[72:75], v[96:99], v[32:35]
	s_waitcnt lgkmcnt(9)
	v_mfma_f32_16x16x32_bf16 v[36:39], v[72:75], v[100:103], v[36:39]
	s_waitcnt lgkmcnt(9)
	v_mfma_f32_16x16x32_bf16 v[40:43], v[72:75], v[104:107], v[40:43]
	s_waitcnt lgkmcnt(9)
	v_mfma_f32_16x16x32_bf16 v[44:47], v[72:75], v[108:111], v[44:47]
	s_waitcnt vmcnt(4) lgkmcnt(0)
	s_barrier
	s_add_u32 m0, s38, 0
	s_nop 0
	global_load_lds_dwordx4 v226, s[98:99]
	s_waitcnt lgkmcnt(8)
	v_mfma_f32_16x16x32_bf16 v[48:51], v[76:79], v[96:99], v[48:51]
	s_add_u32 m0, s38, 4096
	s_nop 0
	global_load_lds_dwordx4 v228, s[98:99]
	s_waitcnt lgkmcnt(8)
	v_mfma_f32_16x16x32_bf16 v[52:55], v[76:79], v[100:103], v[52:55]
	s_add_u32 m0, s38, 8192
	s_nop 0
	global_load_lds_dwordx4 v244, s[98:99]
	s_waitcnt lgkmcnt(8)
	v_mfma_f32_16x16x32_bf16 v[56:59], v[76:79], v[104:107], v[56:59]
	s_add_u32 m0, s38, 12288
	s_nop 0
	global_load_lds_dwordx4 v245, s[98:99]
	s_add_u32 s98, s98, 128
	s_addc_u32 s99, s99, 0
	s_waitcnt lgkmcnt(8)
	v_mfma_f32_16x16x32_bf16 v[60:63], v[76:79], v[108:111], v[60:63]
	s_waitcnt lgkmcnt(6)
	v_mfma_f32_16x16x32_bf16 v[0:3], v[80:83], v[112:115], v[0:3]
	ds_read_b128 v[64:67], v151 offset:16384
	s_waitcnt lgkmcnt(6)
	v_mfma_f32_16x16x32_bf16 v[4:7], v[80:83], v[116:119], v[4:7]
	ds_read_b128 v[96:99], v222 offset:49152
	s_waitcnt lgkmcnt(6)
	v_mfma_f32_16x16x32_bf16 v[8:11], v[80:83], v[120:123], v[8:11]
	ds_read_b128 v[100:103], v222 offset:51200
	s_waitcnt lgkmcnt(6)
	v_mfma_f32_16x16x32_bf16 v[12:15], v[80:83], v[124:127], v[12:15]
	ds_read_b128 v[104:107], v222 offset:53248
	s_waitcnt lgkmcnt(6)
	v_mfma_f32_16x16x32_bf16 v[16:19], v[84:87], v[112:115], v[16:19]
	ds_read_b128 v[108:111], v222 offset:55296
	s_waitcnt lgkmcnt(7)
	v_mfma_f32_16x16x32_bf16 v[20:23], v[84:87], v[116:119], v[20:23]
	ds_read_b128 v[68:71], v151 offset:18432
	s_waitcnt lgkmcnt(8)
	v_mfma_f32_16x16x32_bf16 v[24:27], v[84:87], v[120:123], v[24:27]
	ds_read_b128 v[72:75], v151 offset:20480
	s_waitcnt lgkmcnt(9)
	v_mfma_f32_16x16x32_bf16 v[28:31], v[84:87], v[124:127], v[28:31]
	ds_read_b128 v[76:79], v151 offset:22528
	s_waitcnt lgkmcnt(9)
	v_mfma_f32_16x16x32_bf16 v[32:35], v[88:91], v[112:115], v[32:35]
	s_waitcnt lgkmcnt(9)
	v_mfma_f32_16x16x32_bf16 v[36:39], v[88:91], v[116:119], v[36:39]
	s_waitcnt lgkmcnt(9)
	v_mfma_f32_16x16x32_bf16 v[40:43], v[88:91], v[120:123], v[40:43]
	s_waitcnt lgkmcnt(9)
	v_mfma_f32_16x16x32_bf16 v[44:47], v[88:91], v[124:127], v[44:47]
	s_waitcnt lgkmcnt(8)
	v_mfma_f32_16x16x32_bf16 v[48:51], v[92:95], v[112:115], v[48:51]
	s_waitcnt lgkmcnt(8)
	v_mfma_f32_16x16x32_bf16 v[52:55], v[92:95], v[116:119], v[52:55]
	s_waitcnt lgkmcnt(8)
	v_mfma_f32_16x16x32_bf16 v[56:59], v[92:95], v[120:123], v[56:59]
	s_waitcnt lgkmcnt(8)
	v_mfma_f32_16x16x32_bf16 v[60:63], v[92:95], v[124:127], v[60:63]
	s_waitcnt lgkmcnt(6)
	v_mfma_f32_16x16x32_bf16 v[160:163], v[64:67], v[96:99], v[160:163]
	ds_read_b128 v[80:83], v220 offset:16384
	s_waitcnt lgkmcnt(6)
	v_mfma_f32_16x16x32_bf16 v[164:167], v[64:67], v[100:103], v[164:167]
	ds_read_b128 v[112:115], v224 offset:49152
	s_waitcnt lgkmcnt(6)
	v_mfma_f32_16x16x32_bf16 v[168:171], v[64:67], v[104:107], v[168:171]
	ds_read_b128 v[116:119], v224 offset:51200
	s_waitcnt lgkmcnt(6)
	v_mfma_f32_16x16x32_bf16 v[172:175], v[64:67], v[108:111], v[172:175]
	ds_read_b128 v[120:123], v224 offset:53248
	s_waitcnt lgkmcnt(6)
	v_mfma_f32_16x16x32_bf16 v[176:179], v[68:71], v[96:99], v[176:179]
	ds_read_b128 v[124:127], v224 offset:55296
	s_waitcnt lgkmcnt(7)
	v_mfma_f32_16x16x32_bf16 v[180:183], v[68:71], v[100:103], v[180:183]
	ds_read_b128 v[84:87], v220 offset:18432
	s_waitcnt lgkmcnt(8)
	v_mfma_f32_16x16x32_bf16 v[184:187], v[68:71], v[104:107], v[184:187]
	ds_read_b128 v[88:91], v220 offset:20480
	s_waitcnt lgkmcnt(9)
	v_mfma_f32_16x16x32_bf16 v[188:191], v[68:71], v[108:111], v[188:191]
	ds_read_b128 v[92:95], v220 offset:22528
	s_waitcnt lgkmcnt(9)
	v_mfma_f32_16x16x32_bf16 v[192:195], v[72:75], v[96:99], v[192:195]
	s_waitcnt lgkmcnt(9)
	v_mfma_f32_16x16x32_bf16 v[196:199], v[72:75], v[100:103], v[196:199]
	s_waitcnt lgkmcnt(9)
	v_mfma_f32_16x16x32_bf16 v[200:203], v[72:75], v[104:107], v[200:203]
	s_waitcnt lgkmcnt(9)
	v_mfma_f32_16x16x32_bf16 v[204:207], v[72:75], v[108:111], v[204:207]
	s_waitcnt vmcnt(0) lgkmcnt(0)
	s_barrier
	s_add_u32 m0, s38, 16384
	s_nop 0
	global_load_lds_dwordx4 v226, s[100:101]
	s_waitcnt lgkmcnt(8)
	v_mfma_f32_16x16x32_bf16 v[208:211], v[76:79], v[96:99], v[208:211]
	s_add_u32 m0, s38, 20480
	s_nop 0
	global_load_lds_dwordx4 v228, s[100:101]
	s_waitcnt lgkmcnt(8)
	v_mfma_f32_16x16x32_bf16 v[212:215], v[76:79], v[100:103], v[212:215]
	s_add_u32 m0, s38, 24576
	s_nop 0
	global_load_lds_dwordx4 v244, s[100:101]
	s_waitcnt lgkmcnt(8)
	v_mfma_f32_16x16x32_bf16 v[216:219], v[76:79], v[104:107], v[216:219]
	s_add_u32 m0, s38, 28672
	s_nop 0
	global_load_lds_dwordx4 v245, s[100:101]
	s_add_u32 s100, s100, 128
	s_addc_u32 s101, s101, 0
	s_waitcnt lgkmcnt(8)
	v_mfma_f32_16x16x32_bf16 v[230:233], v[76:79], v[108:111], v[230:233]
	s_add_u32 m0, s38, 49152
	s_nop 0
	global_load_lds_dwordx4 v226, s[4:5]
	s_waitcnt lgkmcnt(6)
	v_mfma_f32_16x16x32_bf16 v[160:163], v[80:83], v[112:115], v[160:163]
	ds_read_b128 v[64:67], v151 offset:0
	s_add_u32 m0, s38, 53248
	s_nop 0
	global_load_lds_dwordx4 v228, s[4:5]
	s_waitcnt lgkmcnt(6)
	v_mfma_f32_16x16x32_bf16 v[164:167], v[80:83], v[116:119], v[164:167]
	ds_read_b128 v[96:99], v222 offset:32768
	s_add_u32 m0, s38, 57344
	s_nop 0
	global_load_lds_dwordx4 v244, s[4:5]
	s_waitcnt lgkmcnt(6)
	v_mfma_f32_16x16x32_bf16 v[168:171], v[80:83], v[120:123], v[168:171]
	ds_read_b128 v[100:103], v222 offset:34816
	s_add_u32 m0, s38, 61440
	s_nop 0
	global_load_lds_dwordx4 v245, s[4:5]
	s_add_u32 s4, s4, 128
	s_addc_u32 s5, s5, 0
	s_waitcnt lgkmcnt(6)
	v_mfma_f32_16x16x32_bf16 v[172:175], v[80:83], v[124:127], v[172:175]
	ds_read_b128 v[104:107], v222 offset:36864
	s_waitcnt lgkmcnt(6)
	v_mfma_f32_16x16x32_bf16 v[176:179], v[84:87], v[112:115], v[176:179]
	ds_read_b128 v[108:111], v222 offset:38912
	s_waitcnt lgkmcnt(7)
	v_mfma_f32_16x16x32_bf16 v[180:183], v[84:87], v[116:119], v[180:183]
	ds_read_b128 v[68:71], v151 offset:2048
	s_waitcnt lgkmcnt(8)
	v_mfma_f32_16x16x32_bf16 v[184:187], v[84:87], v[120:123], v[184:187]
	ds_read_b128 v[72:75], v151 offset:4096
	s_waitcnt lgkmcnt(9)
	v_mfma_f32_16x16x32_bf16 v[188:191], v[84:87], v[124:127], v[188:191]
	ds_read_b128 v[76:79], v151 offset:6144
	s_waitcnt lgkmcnt(9)
	v_mfma_f32_16x16x32_bf16 v[192:195], v[88:91], v[112:115], v[192:195]
	s_waitcnt lgkmcnt(9)
	v_mfma_f32_16x16x32_bf16 v[196:199], v[88:91], v[116:119], v[196:199]
	s_waitcnt lgkmcnt(9)
	v_mfma_f32_16x16x32_bf16 v[200:203], v[88:91], v[120:123], v[200:203]
	s_waitcnt lgkmcnt(9)
	v_mfma_f32_16x16x32_bf16 v[204:207], v[88:91], v[124:127], v[204:207]
	s_waitcnt lgkmcnt(8)
	v_mfma_f32_16x16x32_bf16 v[208:211], v[92:95], v[112:115], v[208:211]
	s_waitcnt lgkmcnt(8)
	v_mfma_f32_16x16x32_bf16 v[212:215], v[92:95], v[116:119], v[212:215]
	s_waitcnt lgkmcnt(8)
	v_mfma_f32_16x16x32_bf16 v[216:219], v[92:95], v[120:123], v[216:219]
	s_waitcnt lgkmcnt(8)
	v_mfma_f32_16x16x32_bf16 v[230:233], v[92:95], v[124:127], v[230:233]
	s_waitcnt lgkmcnt(6)
	v_mfma_f32_16x16x32_bf16 v[0:3], v[64:67], v[96:99], v[0:3]
	ds_read_b128 v[80:83], v220 offset:0
	s_waitcnt lgkmcnt(6)
	v_mfma_f32_16x16x32_bf16 v[4:7], v[64:67], v[100:103], v[4:7]
	ds_read_b128 v[112:115], v224 offset:32768
	s_waitcnt lgkmcnt(6)
	v_mfma_f32_16x16x32_bf16 v[8:11], v[64:67], v[104:107], v[8:11]
	ds_read_b128 v[116:119], v224 offset:34816
	s_waitcnt lgkmcnt(6)
	v_mfma_f32_16x16x32_bf16 v[12:15], v[64:67], v[108:111], v[12:15]
	ds_read_b128 v[120:123], v224 offset:36864
	s_waitcnt lgkmcnt(6)
	v_mfma_f32_16x16x32_bf16 v[16:19], v[68:71], v[96:99], v[16:19]
	ds_read_b128 v[124:127], v224 offset:38912
	s_waitcnt lgkmcnt(7)
	v_mfma_f32_16x16x32_bf16 v[20:23], v[68:71], v[100:103], v[20:23]
	ds_read_b128 v[84:87], v220 offset:2048
	s_waitcnt lgkmcnt(8)
	v_mfma_f32_16x16x32_bf16 v[24:27], v[68:71], v[104:107], v[24:27]
	ds_read_b128 v[88:91], v220 offset:4096
	s_waitcnt lgkmcnt(9)
	v_mfma_f32_16x16x32_bf16 v[28:31], v[68:71], v[108:111], v[28:31]
	ds_read_b128 v[92:95], v220 offset:6144
	s_waitcnt lgkmcnt(9)
	v_mfma_f32_16x16x32_bf16 v[32:35], v[72:75], v[96:99], v[32:35]
	s_waitcnt lgkmcnt(9)
	v_mfma_f32_16x16x32_bf16 v[36:39], v[72:75], v[100:103], v[36:39]
	s_waitcnt lgkmcnt(9)
	v_mfma_f32_16x16x32_bf16 v[40:43], v[72:75], v[104:107], v[40:43]
	s_waitcnt lgkmcnt(9)
	v_mfma_f32_16x16x32_bf16 v[44:47], v[72:75], v[108:111], v[44:47]
	s_waitcnt vmcnt(4) lgkmcnt(0)
	s_barrier
	s_add_u32 m0, s38, 0
	s_nop 0
	global_load_lds_dwordx4 v226, s[98:99]
	s_waitcnt lgkmcnt(8)
	v_mfma_f32_16x16x32_bf16 v[48:51], v[76:79], v[96:99], v[48:51]
	s_add_u32 m0, s38, 4096
	s_nop 0
	global_load_lds_dwordx4 v228, s[98:99]
	s_waitcnt lgkmcnt(8)
	v_mfma_f32_16x16x32_bf16 v[52:55], v[76:79], v[100:103], v[52:55]
	s_add_u32 m0, s38, 8192
	s_nop 0
	global_load_lds_dwordx4 v244, s[98:99]
	s_waitcnt lgkmcnt(8)
	v_mfma_f32_16x16x32_bf16 v[56:59], v[76:79], v[104:107], v[56:59]
	s_add_u32 m0, s38, 12288
	s_nop 0
	global_load_lds_dwordx4 v245, s[98:99]
	s_add_u32 s98, s98, 128
	s_addc_u32 s99, s99, 0
	s_waitcnt lgkmcnt(8)
	v_mfma_f32_16x16x32_bf16 v[60:63], v[76:79], v[108:111], v[60:63]
	s_waitcnt lgkmcnt(6)
	v_mfma_f32_16x16x32_bf16 v[0:3], v[80:83], v[112:115], v[0:3]
	ds_read_b128 v[64:67], v151 offset:16384
	s_waitcnt lgkmcnt(6)
	v_mfma_f32_16x16x32_bf16 v[4:7], v[80:83], v[116:119], v[4:7]
	ds_read_b128 v[96:99], v222 offset:32768
	s_waitcnt lgkmcnt(6)
	v_mfma_f32_16x16x32_bf16 v[8:11], v[80:83], v[120:123], v[8:11]
	ds_read_b128 v[100:103], v222 offset:34816
	s_waitcnt lgkmcnt(6)
	v_mfma_f32_16x16x32_bf16 v[12:15], v[80:83], v[124:127], v[12:15]
	ds_read_b128 v[104:107], v222 offset:36864
	s_waitcnt lgkmcnt(6)
	v_mfma_f32_16x16x32_bf16 v[16:19], v[84:87], v[112:115], v[16:19]
	ds_read_b128 v[108:111], v222 offset:38912
	s_waitcnt lgkmcnt(7)
	v_mfma_f32_16x16x32_bf16 v[20:23], v[84:87], v[116:119], v[20:23]
	ds_read_b128 v[68:71], v151 offset:18432
	s_waitcnt lgkmcnt(8)
	v_mfma_f32_16x16x32_bf16 v[24:27], v[84:87], v[120:123], v[24:27]
	ds_read_b128 v[72:75], v151 offset:20480
	s_waitcnt lgkmcnt(9)
	v_mfma_f32_16x16x32_bf16 v[28:31], v[84:87], v[124:127], v[28:31]
	ds_read_b128 v[76:79], v151 offset:22528
	s_waitcnt lgkmcnt(9)
	v_mfma_f32_16x16x32_bf16 v[32:35], v[88:91], v[112:115], v[32:35]
	s_waitcnt lgkmcnt(9)
	v_mfma_f32_16x16x32_bf16 v[36:39], v[88:91], v[116:119], v[36:39]
	s_waitcnt lgkmcnt(9)
	v_mfma_f32_16x16x32_bf16 v[40:43], v[88:91], v[120:123], v[40:43]
	s_waitcnt lgkmcnt(9)
	v_mfma_f32_16x16x32_bf16 v[44:47], v[88:91], v[124:127], v[44:47]
	s_waitcnt lgkmcnt(8)
	v_mfma_f32_16x16x32_bf16 v[48:51], v[92:95], v[112:115], v[48:51]
	s_waitcnt lgkmcnt(8)
	v_mfma_f32_16x16x32_bf16 v[52:55], v[92:95], v[116:119], v[52:55]
	s_waitcnt lgkmcnt(8)
	v_mfma_f32_16x16x32_bf16 v[56:59], v[92:95], v[120:123], v[56:59]
	s_waitcnt lgkmcnt(8)
	v_mfma_f32_16x16x32_bf16 v[60:63], v[92:95], v[124:127], v[60:63]
	s_waitcnt lgkmcnt(6)
	v_mfma_f32_16x16x32_bf16 v[160:163], v[64:67], v[96:99], v[160:163]
	ds_read_b128 v[80:83], v220 offset:16384
	s_waitcnt lgkmcnt(6)
	v_mfma_f32_16x16x32_bf16 v[164:167], v[64:67], v[100:103], v[164:167]
	ds_read_b128 v[112:115], v224 offset:32768
	s_waitcnt lgkmcnt(6)
	v_mfma_f32_16x16x32_bf16 v[168:171], v[64:67], v[104:107], v[168:171]
	ds_read_b128 v[116:119], v224 offset:34816
	s_waitcnt lgkmcnt(6)
	v_mfma_f32_16x16x32_bf16 v[172:175], v[64:67], v[108:111], v[172:175]
	ds_read_b128 v[120:123], v224 offset:36864
	s_waitcnt lgkmcnt(6)
	v_mfma_f32_16x16x32_bf16 v[176:179], v[68:71], v[96:99], v[176:179]
	ds_read_b128 v[124:127], v224 offset:38912
	s_waitcnt lgkmcnt(7)
	v_mfma_f32_16x16x32_bf16 v[180:183], v[68:71], v[100:103], v[180:183]
	ds_read_b128 v[84:87], v220 offset:18432
	s_waitcnt lgkmcnt(8)
	v_mfma_f32_16x16x32_bf16 v[184:187], v[68:71], v[104:107], v[184:187]
	ds_read_b128 v[88:91], v220 offset:20480
	s_waitcnt lgkmcnt(9)
	v_mfma_f32_16x16x32_bf16 v[188:191], v[68:71], v[108:111], v[188:191]
	ds_read_b128 v[92:95], v220 offset:22528
	s_waitcnt lgkmcnt(9)
	v_mfma_f32_16x16x32_bf16 v[192:195], v[72:75], v[96:99], v[192:195]
	s_waitcnt lgkmcnt(9)
	v_mfma_f32_16x16x32_bf16 v[196:199], v[72:75], v[100:103], v[196:199]
	s_waitcnt lgkmcnt(9)
	v_mfma_f32_16x16x32_bf16 v[200:203], v[72:75], v[104:107], v[200:203]
	s_waitcnt lgkmcnt(9)
	v_mfma_f32_16x16x32_bf16 v[204:207], v[72:75], v[108:111], v[204:207]
	s_waitcnt vmcnt(0) lgkmcnt(0)
	s_barrier
	s_add_u32 m0, s38, 16384
	s_nop 0
	global_load_lds_dwordx4 v226, s[100:101]
	s_waitcnt lgkmcnt(8)
	v_mfma_f32_16x16x32_bf16 v[208:211], v[76:79], v[96:99], v[208:211]
	s_add_u32 m0, s38, 20480
	s_nop 0
	global_load_lds_dwordx4 v228, s[100:101]
	s_waitcnt lgkmcnt(8)
	v_mfma_f32_16x16x32_bf16 v[212:215], v[76:79], v[100:103], v[212:215]
	s_add_u32 m0, s38, 24576
	s_nop 0
	global_load_lds_dwordx4 v244, s[100:101]
	s_waitcnt lgkmcnt(8)
	v_mfma_f32_16x16x32_bf16 v[216:219], v[76:79], v[104:107], v[216:219]
	s_add_u32 m0, s38, 28672
	s_nop 0
	global_load_lds_dwordx4 v245, s[100:101]
	s_add_u32 s100, s100, 128
	s_addc_u32 s101, s101, 0
	s_waitcnt lgkmcnt(8)
	v_mfma_f32_16x16x32_bf16 v[230:233], v[76:79], v[108:111], v[230:233]
	s_add_u32 m0, s38, 32768
	s_nop 0
	global_load_lds_dwordx4 v226, s[4:5]
	s_waitcnt lgkmcnt(6)
	v_mfma_f32_16x16x32_bf16 v[160:163], v[80:83], v[112:115], v[160:163]
	ds_read_b128 v[64:67], v151 offset:0
	s_add_u32 m0, s38, 36864
	s_nop 0
	global_load_lds_dwordx4 v228, s[4:5]
	s_waitcnt lgkmcnt(6)
	v_mfma_f32_16x16x32_bf16 v[164:167], v[80:83], v[116:119], v[164:167]
	ds_read_b128 v[96:99], v222 offset:49152
	s_add_u32 m0, s38, 40960
	s_nop 0
	global_load_lds_dwordx4 v244, s[4:5]
	s_waitcnt lgkmcnt(6)
	v_mfma_f32_16x16x32_bf16 v[168:171], v[80:83], v[120:123], v[168:171]
	ds_read_b128 v[100:103], v222 offset:51200
	s_add_u32 m0, s38, 45056
	s_nop 0
	global_load_lds_dwordx4 v245, s[4:5]
	s_add_u32 s4, s4, 128
	s_addc_u32 s5, s5, 0
	s_waitcnt lgkmcnt(6)
	v_mfma_f32_16x16x32_bf16 v[172:175], v[80:83], v[124:127], v[172:175]
	ds_read_b128 v[104:107], v222 offset:53248
	s_waitcnt lgkmcnt(6)
	v_mfma_f32_16x16x32_bf16 v[176:179], v[84:87], v[112:115], v[176:179]
	ds_read_b128 v[108:111], v222 offset:55296
	s_waitcnt lgkmcnt(7)
	v_mfma_f32_16x16x32_bf16 v[180:183], v[84:87], v[116:119], v[180:183]
	ds_read_b128 v[68:71], v151 offset:2048
	s_waitcnt lgkmcnt(8)
	v_mfma_f32_16x16x32_bf16 v[184:187], v[84:87], v[120:123], v[184:187]
	ds_read_b128 v[72:75], v151 offset:4096
	s_waitcnt lgkmcnt(9)
	v_mfma_f32_16x16x32_bf16 v[188:191], v[84:87], v[124:127], v[188:191]
	ds_read_b128 v[76:79], v151 offset:6144
	s_waitcnt lgkmcnt(9)
	v_mfma_f32_16x16x32_bf16 v[192:195], v[88:91], v[112:115], v[192:195]
	s_waitcnt lgkmcnt(9)
	v_mfma_f32_16x16x32_bf16 v[196:199], v[88:91], v[116:119], v[196:199]
	s_waitcnt lgkmcnt(9)
	v_mfma_f32_16x16x32_bf16 v[200:203], v[88:91], v[120:123], v[200:203]
	s_waitcnt lgkmcnt(9)
	v_mfma_f32_16x16x32_bf16 v[204:207], v[88:91], v[124:127], v[204:207]
	s_waitcnt lgkmcnt(8)
	v_mfma_f32_16x16x32_bf16 v[208:211], v[92:95], v[112:115], v[208:211]
	s_waitcnt lgkmcnt(8)
	v_mfma_f32_16x16x32_bf16 v[212:215], v[92:95], v[116:119], v[212:215]
	s_waitcnt lgkmcnt(8)
	v_mfma_f32_16x16x32_bf16 v[216:219], v[92:95], v[120:123], v[216:219]
	s_waitcnt lgkmcnt(8)
	v_mfma_f32_16x16x32_bf16 v[230:233], v[92:95], v[124:127], v[230:233]
	s_waitcnt lgkmcnt(6)
	v_mfma_f32_16x16x32_bf16 v[0:3], v[64:67], v[96:99], v[0:3]
	ds_read_b128 v[80:83], v220 offset:0
	s_waitcnt lgkmcnt(6)
	v_mfma_f32_16x16x32_bf16 v[4:7], v[64:67], v[100:103], v[4:7]
	ds_read_b128 v[112:115], v224 offset:49152
	s_waitcnt lgkmcnt(6)
	v_mfma_f32_16x16x32_bf16 v[8:11], v[64:67], v[104:107], v[8:11]
	ds_read_b128 v[116:119], v224 offset:51200
	s_waitcnt lgkmcnt(6)
	v_mfma_f32_16x16x32_bf16 v[12:15], v[64:67], v[108:111], v[12:15]
	ds_read_b128 v[120:123], v224 offset:53248
	s_waitcnt lgkmcnt(6)
	v_mfma_f32_16x16x32_bf16 v[16:19], v[68:71], v[96:99], v[16:19]
	ds_read_b128 v[124:127], v224 offset:55296
	s_waitcnt lgkmcnt(7)
	v_mfma_f32_16x16x32_bf16 v[20:23], v[68:71], v[100:103], v[20:23]
	ds_read_b128 v[84:87], v220 offset:2048
	s_waitcnt lgkmcnt(8)
	v_mfma_f32_16x16x32_bf16 v[24:27], v[68:71], v[104:107], v[24:27]
	ds_read_b128 v[88:91], v220 offset:4096
	s_waitcnt lgkmcnt(9)
	v_mfma_f32_16x16x32_bf16 v[28:31], v[68:71], v[108:111], v[28:31]
	ds_read_b128 v[92:95], v220 offset:6144
	s_waitcnt lgkmcnt(9)
	v_mfma_f32_16x16x32_bf16 v[32:35], v[72:75], v[96:99], v[32:35]
	s_waitcnt lgkmcnt(9)
	v_mfma_f32_16x16x32_bf16 v[36:39], v[72:75], v[100:103], v[36:39]
	s_waitcnt lgkmcnt(9)
	v_mfma_f32_16x16x32_bf16 v[40:43], v[72:75], v[104:107], v[40:43]
	s_waitcnt lgkmcnt(9)
	v_mfma_f32_16x16x32_bf16 v[44:47], v[72:75], v[108:111], v[44:47]
	s_waitcnt vmcnt(4) lgkmcnt(0)
	s_barrier
	s_add_u32 m0, s38, 0
	s_nop 0
	global_load_lds_dwordx4 v226, s[98:99]
	s_waitcnt lgkmcnt(8)
	v_mfma_f32_16x16x32_bf16 v[48:51], v[76:79], v[96:99], v[48:51]
	s_add_u32 m0, s38, 4096
	s_nop 0
	global_load_lds_dwordx4 v228, s[98:99]
	s_waitcnt lgkmcnt(8)
	v_mfma_f32_16x16x32_bf16 v[52:55], v[76:79], v[100:103], v[52:55]
	s_add_u32 m0, s38, 8192
	s_nop 0
	global_load_lds_dwordx4 v244, s[98:99]
	s_waitcnt lgkmcnt(8)
	v_mfma_f32_16x16x32_bf16 v[56:59], v[76:79], v[104:107], v[56:59]
	s_add_u32 m0, s38, 12288
	s_nop 0
	global_load_lds_dwordx4 v245, s[98:99]
	s_add_u32 s98, s98, 128
	s_addc_u32 s99, s99, 0
	s_waitcnt lgkmcnt(8)
	v_mfma_f32_16x16x32_bf16 v[60:63], v[76:79], v[108:111], v[60:63]
	s_waitcnt lgkmcnt(6)
	v_mfma_f32_16x16x32_bf16 v[0:3], v[80:83], v[112:115], v[0:3]
	ds_read_b128 v[64:67], v151 offset:16384
	s_waitcnt lgkmcnt(6)
	v_mfma_f32_16x16x32_bf16 v[4:7], v[80:83], v[116:119], v[4:7]
	ds_read_b128 v[96:99], v222 offset:49152
	s_waitcnt lgkmcnt(6)
	v_mfma_f32_16x16x32_bf16 v[8:11], v[80:83], v[120:123], v[8:11]
	ds_read_b128 v[100:103], v222 offset:51200
	s_waitcnt lgkmcnt(6)
	v_mfma_f32_16x16x32_bf16 v[12:15], v[80:83], v[124:127], v[12:15]
	ds_read_b128 v[104:107], v222 offset:53248
	s_waitcnt lgkmcnt(6)
	v_mfma_f32_16x16x32_bf16 v[16:19], v[84:87], v[112:115], v[16:19]
	ds_read_b128 v[108:111], v222 offset:55296
	s_waitcnt lgkmcnt(7)
	v_mfma_f32_16x16x32_bf16 v[20:23], v[84:87], v[116:119], v[20:23]
	ds_read_b128 v[68:71], v151 offset:18432
	s_waitcnt lgkmcnt(8)
	v_mfma_f32_16x16x32_bf16 v[24:27], v[84:87], v[120:123], v[24:27]
	ds_read_b128 v[72:75], v151 offset:20480
	s_waitcnt lgkmcnt(9)
	v_mfma_f32_16x16x32_bf16 v[28:31], v[84:87], v[124:127], v[28:31]
	ds_read_b128 v[76:79], v151 offset:22528
	s_waitcnt lgkmcnt(9)
	v_mfma_f32_16x16x32_bf16 v[32:35], v[88:91], v[112:115], v[32:35]
	s_waitcnt lgkmcnt(9)
	v_mfma_f32_16x16x32_bf16 v[36:39], v[88:91], v[116:119], v[36:39]
	s_waitcnt lgkmcnt(9)
	v_mfma_f32_16x16x32_bf16 v[40:43], v[88:91], v[120:123], v[40:43]
	s_waitcnt lgkmcnt(9)
	v_mfma_f32_16x16x32_bf16 v[44:47], v[88:91], v[124:127], v[44:47]
	s_waitcnt lgkmcnt(8)
	v_mfma_f32_16x16x32_bf16 v[48:51], v[92:95], v[112:115], v[48:51]
	s_waitcnt lgkmcnt(8)
	v_mfma_f32_16x16x32_bf16 v[52:55], v[92:95], v[116:119], v[52:55]
	s_waitcnt lgkmcnt(8)
	v_mfma_f32_16x16x32_bf16 v[56:59], v[92:95], v[120:123], v[56:59]
	s_waitcnt lgkmcnt(8)
	v_mfma_f32_16x16x32_bf16 v[60:63], v[92:95], v[124:127], v[60:63]
	s_waitcnt lgkmcnt(6)
	v_mfma_f32_16x16x32_bf16 v[160:163], v[64:67], v[96:99], v[160:163]
	ds_read_b128 v[80:83], v220 offset:16384
	s_waitcnt lgkmcnt(6)
	v_mfma_f32_16x16x32_bf16 v[164:167], v[64:67], v[100:103], v[164:167]
	ds_read_b128 v[112:115], v224 offset:49152
	s_waitcnt lgkmcnt(6)
	v_mfma_f32_16x16x32_bf16 v[168:171], v[64:67], v[104:107], v[168:171]
	ds_read_b128 v[116:119], v224 offset:51200
	s_waitcnt lgkmcnt(6)
	v_mfma_f32_16x16x32_bf16 v[172:175], v[64:67], v[108:111], v[172:175]
	ds_read_b128 v[120:123], v224 offset:53248
	s_waitcnt lgkmcnt(6)
	v_mfma_f32_16x16x32_bf16 v[176:179], v[68:71], v[96:99], v[176:179]
	ds_read_b128 v[124:127], v224 offset:55296
	s_waitcnt lgkmcnt(7)
	v_mfma_f32_16x16x32_bf16 v[180:183], v[68:71], v[100:103], v[180:183]
	ds_read_b128 v[84:87], v220 offset:18432
	s_waitcnt lgkmcnt(8)
	v_mfma_f32_16x16x32_bf16 v[184:187], v[68:71], v[104:107], v[184:187]
	ds_read_b128 v[88:91], v220 offset:20480
	s_waitcnt lgkmcnt(9)
	v_mfma_f32_16x16x32_bf16 v[188:191], v[68:71], v[108:111], v[188:191]
	ds_read_b128 v[92:95], v220 offset:22528
	s_waitcnt lgkmcnt(9)
	v_mfma_f32_16x16x32_bf16 v[192:195], v[72:75], v[96:99], v[192:195]
	s_waitcnt lgkmcnt(9)
	v_mfma_f32_16x16x32_bf16 v[196:199], v[72:75], v[100:103], v[196:199]
	s_waitcnt lgkmcnt(9)
	v_mfma_f32_16x16x32_bf16 v[200:203], v[72:75], v[104:107], v[200:203]
	s_waitcnt lgkmcnt(9)
	v_mfma_f32_16x16x32_bf16 v[204:207], v[72:75], v[108:111], v[204:207]
	s_waitcnt vmcnt(0) lgkmcnt(0)
	s_barrier
	s_add_u32 m0, s38, 16384
	s_nop 0
	global_load_lds_dwordx4 v226, s[100:101]
	s_waitcnt lgkmcnt(8)
	v_mfma_f32_16x16x32_bf16 v[208:211], v[76:79], v[96:99], v[208:211]
	s_add_u32 m0, s38, 20480
	s_nop 0
	global_load_lds_dwordx4 v228, s[100:101]
	s_waitcnt lgkmcnt(8)
	v_mfma_f32_16x16x32_bf16 v[212:215], v[76:79], v[100:103], v[212:215]
	s_add_u32 m0, s38, 24576
	s_nop 0
	global_load_lds_dwordx4 v244, s[100:101]
	s_waitcnt lgkmcnt(8)
	v_mfma_f32_16x16x32_bf16 v[216:219], v[76:79], v[104:107], v[216:219]
	s_add_u32 m0, s38, 28672
	s_nop 0
	global_load_lds_dwordx4 v245, s[100:101]
	s_add_u32 s100, s100, 128
	s_addc_u32 s101, s101, 0
	s_waitcnt lgkmcnt(8)
	v_mfma_f32_16x16x32_bf16 v[230:233], v[76:79], v[108:111], v[230:233]
	s_add_u32 m0, s38, 49152
	s_nop 0
	global_load_lds_dwordx4 v226, s[4:5]
	s_waitcnt lgkmcnt(6)
	v_mfma_f32_16x16x32_bf16 v[160:163], v[80:83], v[112:115], v[160:163]
	ds_read_b128 v[64:67], v151 offset:0
	s_add_u32 m0, s38, 53248
	s_nop 0
	global_load_lds_dwordx4 v228, s[4:5]
	s_waitcnt lgkmcnt(6)
	v_mfma_f32_16x16x32_bf16 v[164:167], v[80:83], v[116:119], v[164:167]
	ds_read_b128 v[96:99], v222 offset:32768
	s_add_u32 m0, s38, 57344
	s_nop 0
	global_load_lds_dwordx4 v244, s[4:5]
	s_waitcnt lgkmcnt(6)
	v_mfma_f32_16x16x32_bf16 v[168:171], v[80:83], v[120:123], v[168:171]
	ds_read_b128 v[100:103], v222 offset:34816
	s_add_u32 m0, s38, 61440
	s_nop 0
	global_load_lds_dwordx4 v245, s[4:5]
	s_add_u32 s4, s4, 128
	s_addc_u32 s5, s5, 0
	s_waitcnt lgkmcnt(6)
	v_mfma_f32_16x16x32_bf16 v[172:175], v[80:83], v[124:127], v[172:175]
	ds_read_b128 v[104:107], v222 offset:36864
	s_waitcnt lgkmcnt(6)
	v_mfma_f32_16x16x32_bf16 v[176:179], v[84:87], v[112:115], v[176:179]
	ds_read_b128 v[108:111], v222 offset:38912
	s_waitcnt lgkmcnt(7)
	v_mfma_f32_16x16x32_bf16 v[180:183], v[84:87], v[116:119], v[180:183]
	ds_read_b128 v[68:71], v151 offset:2048
	s_waitcnt lgkmcnt(8)
	v_mfma_f32_16x16x32_bf16 v[184:187], v[84:87], v[120:123], v[184:187]
	ds_read_b128 v[72:75], v151 offset:4096
	s_waitcnt lgkmcnt(9)
	v_mfma_f32_16x16x32_bf16 v[188:191], v[84:87], v[124:127], v[188:191]
	ds_read_b128 v[76:79], v151 offset:6144
	s_waitcnt lgkmcnt(9)
	v_mfma_f32_16x16x32_bf16 v[192:195], v[88:91], v[112:115], v[192:195]
	s_waitcnt lgkmcnt(9)
	v_mfma_f32_16x16x32_bf16 v[196:199], v[88:91], v[116:119], v[196:199]
	s_waitcnt lgkmcnt(9)
	v_mfma_f32_16x16x32_bf16 v[200:203], v[88:91], v[120:123], v[200:203]
	s_waitcnt lgkmcnt(9)
	v_mfma_f32_16x16x32_bf16 v[204:207], v[88:91], v[124:127], v[204:207]
	s_waitcnt lgkmcnt(8)
	v_mfma_f32_16x16x32_bf16 v[208:211], v[92:95], v[112:115], v[208:211]
	s_waitcnt lgkmcnt(8)
	v_mfma_f32_16x16x32_bf16 v[212:215], v[92:95], v[116:119], v[212:215]
	s_waitcnt lgkmcnt(8)
	v_mfma_f32_16x16x32_bf16 v[216:219], v[92:95], v[120:123], v[216:219]
	s_waitcnt lgkmcnt(8)
	v_mfma_f32_16x16x32_bf16 v[230:233], v[92:95], v[124:127], v[230:233]
	s_waitcnt lgkmcnt(6)
	v_mfma_f32_16x16x32_bf16 v[0:3], v[64:67], v[96:99], v[0:3]
	ds_read_b128 v[80:83], v220 offset:0
	s_waitcnt lgkmcnt(6)
	v_mfma_f32_16x16x32_bf16 v[4:7], v[64:67], v[100:103], v[4:7]
	ds_read_b128 v[112:115], v224 offset:32768
	s_waitcnt lgkmcnt(6)
	v_mfma_f32_16x16x32_bf16 v[8:11], v[64:67], v[104:107], v[8:11]
	ds_read_b128 v[116:119], v224 offset:34816
	s_waitcnt lgkmcnt(6)
	v_mfma_f32_16x16x32_bf16 v[12:15], v[64:67], v[108:111], v[12:15]
	ds_read_b128 v[120:123], v224 offset:36864
	s_waitcnt lgkmcnt(6)
	v_mfma_f32_16x16x32_bf16 v[16:19], v[68:71], v[96:99], v[16:19]
	ds_read_b128 v[124:127], v224 offset:38912
	s_waitcnt lgkmcnt(7)
	v_mfma_f32_16x16x32_bf16 v[20:23], v[68:71], v[100:103], v[20:23]
	ds_read_b128 v[84:87], v220 offset:2048
	s_waitcnt lgkmcnt(8)
	v_mfma_f32_16x16x32_bf16 v[24:27], v[68:71], v[104:107], v[24:27]
	ds_read_b128 v[88:91], v220 offset:4096
	s_waitcnt lgkmcnt(9)
	v_mfma_f32_16x16x32_bf16 v[28:31], v[68:71], v[108:111], v[28:31]
	ds_read_b128 v[92:95], v220 offset:6144
	s_waitcnt lgkmcnt(9)
	v_mfma_f32_16x16x32_bf16 v[32:35], v[72:75], v[96:99], v[32:35]
	s_waitcnt lgkmcnt(9)
	v_mfma_f32_16x16x32_bf16 v[36:39], v[72:75], v[100:103], v[36:39]
	s_waitcnt lgkmcnt(9)
	v_mfma_f32_16x16x32_bf16 v[40:43], v[72:75], v[104:107], v[40:43]
	s_waitcnt lgkmcnt(9)
	v_mfma_f32_16x16x32_bf16 v[44:47], v[72:75], v[108:111], v[44:47]
	s_waitcnt vmcnt(4) lgkmcnt(0)
	s_barrier
	s_add_u32 m0, s38, 0
	s_nop 0
	global_load_lds_dwordx4 v226, s[98:99]
	s_waitcnt lgkmcnt(8)
	v_mfma_f32_16x16x32_bf16 v[48:51], v[76:79], v[96:99], v[48:51]
	s_add_u32 m0, s38, 4096
	s_nop 0
	global_load_lds_dwordx4 v228, s[98:99]
	s_waitcnt lgkmcnt(8)
	v_mfma_f32_16x16x32_bf16 v[52:55], v[76:79], v[100:103], v[52:55]
	s_add_u32 m0, s38, 8192
	s_nop 0
	global_load_lds_dwordx4 v244, s[98:99]
	s_waitcnt lgkmcnt(8)
	v_mfma_f32_16x16x32_bf16 v[56:59], v[76:79], v[104:107], v[56:59]
	s_add_u32 m0, s38, 12288
	s_nop 0
	global_load_lds_dwordx4 v245, s[98:99]
	s_add_u32 s98, s98, 128
	s_addc_u32 s99, s99, 0
	s_waitcnt lgkmcnt(8)
	v_mfma_f32_16x16x32_bf16 v[60:63], v[76:79], v[108:111], v[60:63]
	s_waitcnt lgkmcnt(6)
	v_mfma_f32_16x16x32_bf16 v[0:3], v[80:83], v[112:115], v[0:3]
	ds_read_b128 v[64:67], v151 offset:16384
	s_waitcnt lgkmcnt(6)
	v_mfma_f32_16x16x32_bf16 v[4:7], v[80:83], v[116:119], v[4:7]
	ds_read_b128 v[96:99], v222 offset:32768
	s_waitcnt lgkmcnt(6)
	v_mfma_f32_16x16x32_bf16 v[8:11], v[80:83], v[120:123], v[8:11]
	ds_read_b128 v[100:103], v222 offset:34816
	s_waitcnt lgkmcnt(6)
	v_mfma_f32_16x16x32_bf16 v[12:15], v[80:83], v[124:127], v[12:15]
	ds_read_b128 v[104:107], v222 offset:36864
	s_waitcnt lgkmcnt(6)
	v_mfma_f32_16x16x32_bf16 v[16:19], v[84:87], v[112:115], v[16:19]
	ds_read_b128 v[108:111], v222 offset:38912
	s_waitcnt lgkmcnt(7)
	v_mfma_f32_16x16x32_bf16 v[20:23], v[84:87], v[116:119], v[20:23]
	ds_read_b128 v[68:71], v151 offset:18432
	s_waitcnt lgkmcnt(8)
	v_mfma_f32_16x16x32_bf16 v[24:27], v[84:87], v[120:123], v[24:27]
	ds_read_b128 v[72:75], v151 offset:20480
	s_waitcnt lgkmcnt(9)
	v_mfma_f32_16x16x32_bf16 v[28:31], v[84:87], v[124:127], v[28:31]
	ds_read_b128 v[76:79], v151 offset:22528
	s_waitcnt lgkmcnt(9)
	v_mfma_f32_16x16x32_bf16 v[32:35], v[88:91], v[112:115], v[32:35]
	s_waitcnt lgkmcnt(9)
	v_mfma_f32_16x16x32_bf16 v[36:39], v[88:91], v[116:119], v[36:39]
	s_waitcnt lgkmcnt(9)
	v_mfma_f32_16x16x32_bf16 v[40:43], v[88:91], v[120:123], v[40:43]
	s_waitcnt lgkmcnt(9)
	v_mfma_f32_16x16x32_bf16 v[44:47], v[88:91], v[124:127], v[44:47]
	s_waitcnt lgkmcnt(8)
	v_mfma_f32_16x16x32_bf16 v[48:51], v[92:95], v[112:115], v[48:51]
	s_waitcnt lgkmcnt(8)
	v_mfma_f32_16x16x32_bf16 v[52:55], v[92:95], v[116:119], v[52:55]
	s_waitcnt lgkmcnt(8)
	v_mfma_f32_16x16x32_bf16 v[56:59], v[92:95], v[120:123], v[56:59]
	s_waitcnt lgkmcnt(8)
	v_mfma_f32_16x16x32_bf16 v[60:63], v[92:95], v[124:127], v[60:63]
	s_waitcnt lgkmcnt(6)
	v_mfma_f32_16x16x32_bf16 v[160:163], v[64:67], v[96:99], v[160:163]
	ds_read_b128 v[80:83], v220 offset:16384
	s_waitcnt lgkmcnt(6)
	v_mfma_f32_16x16x32_bf16 v[164:167], v[64:67], v[100:103], v[164:167]
	ds_read_b128 v[112:115], v224 offset:32768
	s_waitcnt lgkmcnt(6)
	v_mfma_f32_16x16x32_bf16 v[168:171], v[64:67], v[104:107], v[168:171]
	ds_read_b128 v[116:119], v224 offset:34816
	s_waitcnt lgkmcnt(6)
	v_mfma_f32_16x16x32_bf16 v[172:175], v[64:67], v[108:111], v[172:175]
	ds_read_b128 v[120:123], v224 offset:36864
	s_waitcnt lgkmcnt(6)
	v_mfma_f32_16x16x32_bf16 v[176:179], v[68:71], v[96:99], v[176:179]
	ds_read_b128 v[124:127], v224 offset:38912
	s_waitcnt lgkmcnt(7)
	v_mfma_f32_16x16x32_bf16 v[180:183], v[68:71], v[100:103], v[180:183]
	ds_read_b128 v[84:87], v220 offset:18432
	s_waitcnt lgkmcnt(8)
	v_mfma_f32_16x16x32_bf16 v[184:187], v[68:71], v[104:107], v[184:187]
	ds_read_b128 v[88:91], v220 offset:20480
	s_waitcnt lgkmcnt(9)
	v_mfma_f32_16x16x32_bf16 v[188:191], v[68:71], v[108:111], v[188:191]
	ds_read_b128 v[92:95], v220 offset:22528
	s_waitcnt lgkmcnt(9)
	v_mfma_f32_16x16x32_bf16 v[192:195], v[72:75], v[96:99], v[192:195]
	s_waitcnt lgkmcnt(9)
	v_mfma_f32_16x16x32_bf16 v[196:199], v[72:75], v[100:103], v[196:199]
	s_waitcnt lgkmcnt(9)
	v_mfma_f32_16x16x32_bf16 v[200:203], v[72:75], v[104:107], v[200:203]
	s_waitcnt lgkmcnt(9)
	v_mfma_f32_16x16x32_bf16 v[204:207], v[72:75], v[108:111], v[204:207]
	s_waitcnt vmcnt(0) lgkmcnt(0)
	s_barrier
	s_add_u32 m0, s38, 16384
	s_nop 0
	global_load_lds_dwordx4 v226, s[100:101]
	s_waitcnt lgkmcnt(8)
	v_mfma_f32_16x16x32_bf16 v[208:211], v[76:79], v[96:99], v[208:211]
	s_add_u32 m0, s38, 20480
	s_nop 0
	global_load_lds_dwordx4 v228, s[100:101]
	s_waitcnt lgkmcnt(8)
	v_mfma_f32_16x16x32_bf16 v[212:215], v[76:79], v[100:103], v[212:215]
	s_add_u32 m0, s38, 24576
	s_nop 0
	global_load_lds_dwordx4 v244, s[100:101]
	s_waitcnt lgkmcnt(8)
	v_mfma_f32_16x16x32_bf16 v[216:219], v[76:79], v[104:107], v[216:219]
	s_add_u32 m0, s38, 28672
	s_nop 0
	global_load_lds_dwordx4 v245, s[100:101]
	s_add_u32 s100, s100, 128
	s_addc_u32 s101, s101, 0
	s_waitcnt lgkmcnt(8)
	v_mfma_f32_16x16x32_bf16 v[230:233], v[76:79], v[108:111], v[230:233]
	s_add_u32 m0, s38, 32768
	s_nop 0
	global_load_lds_dwordx4 v226, s[4:5]
	s_waitcnt lgkmcnt(6)
	v_mfma_f32_16x16x32_bf16 v[160:163], v[80:83], v[112:115], v[160:163]
	ds_read_b128 v[64:67], v151 offset:0
	s_add_u32 m0, s38, 36864
	s_nop 0
	global_load_lds_dwordx4 v228, s[4:5]
	s_waitcnt lgkmcnt(6)
	v_mfma_f32_16x16x32_bf16 v[164:167], v[80:83], v[116:119], v[164:167]
	ds_read_b128 v[96:99], v222 offset:49152
	s_add_u32 m0, s38, 40960
	s_nop 0
	global_load_lds_dwordx4 v244, s[4:5]
	s_waitcnt lgkmcnt(6)
	v_mfma_f32_16x16x32_bf16 v[168:171], v[80:83], v[120:123], v[168:171]
	ds_read_b128 v[100:103], v222 offset:51200
	s_add_u32 m0, s38, 45056
	s_nop 0
	global_load_lds_dwordx4 v245, s[4:5]
	s_add_u32 s4, s4, 128
	s_addc_u32 s5, s5, 0
	s_waitcnt lgkmcnt(6)
	v_mfma_f32_16x16x32_bf16 v[172:175], v[80:83], v[124:127], v[172:175]
	ds_read_b128 v[104:107], v222 offset:53248
	s_waitcnt lgkmcnt(6)
	v_mfma_f32_16x16x32_bf16 v[176:179], v[84:87], v[112:115], v[176:179]
	ds_read_b128 v[108:111], v222 offset:55296
	s_waitcnt lgkmcnt(7)
	v_mfma_f32_16x16x32_bf16 v[180:183], v[84:87], v[116:119], v[180:183]
	ds_read_b128 v[68:71], v151 offset:2048
	s_waitcnt lgkmcnt(8)
	v_mfma_f32_16x16x32_bf16 v[184:187], v[84:87], v[120:123], v[184:187]
	ds_read_b128 v[72:75], v151 offset:4096
	s_waitcnt lgkmcnt(9)
	v_mfma_f32_16x16x32_bf16 v[188:191], v[84:87], v[124:127], v[188:191]
	ds_read_b128 v[76:79], v151 offset:6144
	s_waitcnt lgkmcnt(9)
	v_mfma_f32_16x16x32_bf16 v[192:195], v[88:91], v[112:115], v[192:195]
	s_waitcnt lgkmcnt(9)
	v_mfma_f32_16x16x32_bf16 v[196:199], v[88:91], v[116:119], v[196:199]
	s_waitcnt lgkmcnt(9)
	v_mfma_f32_16x16x32_bf16 v[200:203], v[88:91], v[120:123], v[200:203]
	s_waitcnt lgkmcnt(9)
	v_mfma_f32_16x16x32_bf16 v[204:207], v[88:91], v[124:127], v[204:207]
	s_waitcnt lgkmcnt(8)
	v_mfma_f32_16x16x32_bf16 v[208:211], v[92:95], v[112:115], v[208:211]
	s_waitcnt lgkmcnt(8)
	v_mfma_f32_16x16x32_bf16 v[212:215], v[92:95], v[116:119], v[212:215]
	s_waitcnt lgkmcnt(8)
	v_mfma_f32_16x16x32_bf16 v[216:219], v[92:95], v[120:123], v[216:219]
	s_waitcnt lgkmcnt(8)
	v_mfma_f32_16x16x32_bf16 v[230:233], v[92:95], v[124:127], v[230:233]
	s_waitcnt lgkmcnt(6)
	v_mfma_f32_16x16x32_bf16 v[0:3], v[64:67], v[96:99], v[0:3]
	ds_read_b128 v[80:83], v220 offset:0
	s_waitcnt lgkmcnt(6)
	v_mfma_f32_16x16x32_bf16 v[4:7], v[64:67], v[100:103], v[4:7]
	ds_read_b128 v[112:115], v224 offset:49152
	s_waitcnt lgkmcnt(6)
	v_mfma_f32_16x16x32_bf16 v[8:11], v[64:67], v[104:107], v[8:11]
	ds_read_b128 v[116:119], v224 offset:51200
	s_waitcnt lgkmcnt(6)
	v_mfma_f32_16x16x32_bf16 v[12:15], v[64:67], v[108:111], v[12:15]
	ds_read_b128 v[120:123], v224 offset:53248
	s_waitcnt lgkmcnt(6)
	v_mfma_f32_16x16x32_bf16 v[16:19], v[68:71], v[96:99], v[16:19]
	ds_read_b128 v[124:127], v224 offset:55296
	s_waitcnt lgkmcnt(7)
	v_mfma_f32_16x16x32_bf16 v[20:23], v[68:71], v[100:103], v[20:23]
	ds_read_b128 v[84:87], v220 offset:2048
	s_waitcnt lgkmcnt(8)
	v_mfma_f32_16x16x32_bf16 v[24:27], v[68:71], v[104:107], v[24:27]
	ds_read_b128 v[88:91], v220 offset:4096
	s_waitcnt lgkmcnt(9)
	v_mfma_f32_16x16x32_bf16 v[28:31], v[68:71], v[108:111], v[28:31]
	ds_read_b128 v[92:95], v220 offset:6144
	s_waitcnt lgkmcnt(9)
	v_mfma_f32_16x16x32_bf16 v[32:35], v[72:75], v[96:99], v[32:35]
	s_waitcnt lgkmcnt(9)
	v_mfma_f32_16x16x32_bf16 v[36:39], v[72:75], v[100:103], v[36:39]
	s_waitcnt lgkmcnt(9)
	v_mfma_f32_16x16x32_bf16 v[40:43], v[72:75], v[104:107], v[40:43]
	s_waitcnt lgkmcnt(9)
	v_mfma_f32_16x16x32_bf16 v[44:47], v[72:75], v[108:111], v[44:47]
	s_waitcnt vmcnt(4) lgkmcnt(0)
	s_barrier
	s_add_u32 m0, s38, 0
	s_nop 0
	global_load_lds_dwordx4 v226, s[98:99]
	s_waitcnt lgkmcnt(8)
	v_mfma_f32_16x16x32_bf16 v[48:51], v[76:79], v[96:99], v[48:51]
	s_add_u32 m0, s38, 4096
	s_nop 0
	global_load_lds_dwordx4 v228, s[98:99]
	s_waitcnt lgkmcnt(8)
	v_mfma_f32_16x16x32_bf16 v[52:55], v[76:79], v[100:103], v[52:55]
	s_add_u32 m0, s38, 8192
	s_nop 0
	global_load_lds_dwordx4 v244, s[98:99]
	s_waitcnt lgkmcnt(8)
	v_mfma_f32_16x16x32_bf16 v[56:59], v[76:79], v[104:107], v[56:59]
	s_add_u32 m0, s38, 12288
	s_nop 0
	global_load_lds_dwordx4 v245, s[98:99]
	s_add_u32 s98, s98, 128
	s_addc_u32 s99, s99, 0
	s_waitcnt lgkmcnt(8)
	v_mfma_f32_16x16x32_bf16 v[60:63], v[76:79], v[108:111], v[60:63]
	s_waitcnt lgkmcnt(6)
	v_mfma_f32_16x16x32_bf16 v[0:3], v[80:83], v[112:115], v[0:3]
	ds_read_b128 v[64:67], v151 offset:16384
	s_waitcnt lgkmcnt(6)
	v_mfma_f32_16x16x32_bf16 v[4:7], v[80:83], v[116:119], v[4:7]
	ds_read_b128 v[96:99], v222 offset:49152
	s_waitcnt lgkmcnt(6)
	v_mfma_f32_16x16x32_bf16 v[8:11], v[80:83], v[120:123], v[8:11]
	ds_read_b128 v[100:103], v222 offset:51200
	s_waitcnt lgkmcnt(6)
	v_mfma_f32_16x16x32_bf16 v[12:15], v[80:83], v[124:127], v[12:15]
	ds_read_b128 v[104:107], v222 offset:53248
	s_waitcnt lgkmcnt(6)
	v_mfma_f32_16x16x32_bf16 v[16:19], v[84:87], v[112:115], v[16:19]
	ds_read_b128 v[108:111], v222 offset:55296
	s_waitcnt lgkmcnt(7)
	v_mfma_f32_16x16x32_bf16 v[20:23], v[84:87], v[116:119], v[20:23]
	ds_read_b128 v[68:71], v151 offset:18432
	s_waitcnt lgkmcnt(8)
	v_mfma_f32_16x16x32_bf16 v[24:27], v[84:87], v[120:123], v[24:27]
	ds_read_b128 v[72:75], v151 offset:20480
	s_waitcnt lgkmcnt(9)
	v_mfma_f32_16x16x32_bf16 v[28:31], v[84:87], v[124:127], v[28:31]
	ds_read_b128 v[76:79], v151 offset:22528
	s_waitcnt lgkmcnt(9)
	v_mfma_f32_16x16x32_bf16 v[32:35], v[88:91], v[112:115], v[32:35]
	s_waitcnt lgkmcnt(9)
	v_mfma_f32_16x16x32_bf16 v[36:39], v[88:91], v[116:119], v[36:39]
	s_waitcnt lgkmcnt(9)
	v_mfma_f32_16x16x32_bf16 v[40:43], v[88:91], v[120:123], v[40:43]
	s_waitcnt lgkmcnt(9)
	v_mfma_f32_16x16x32_bf16 v[44:47], v[88:91], v[124:127], v[44:47]
	s_waitcnt lgkmcnt(8)
	v_mfma_f32_16x16x32_bf16 v[48:51], v[92:95], v[112:115], v[48:51]
	s_waitcnt lgkmcnt(8)
	v_mfma_f32_16x16x32_bf16 v[52:55], v[92:95], v[116:119], v[52:55]
	s_waitcnt lgkmcnt(8)
	v_mfma_f32_16x16x32_bf16 v[56:59], v[92:95], v[120:123], v[56:59]
	s_waitcnt lgkmcnt(8)
	v_mfma_f32_16x16x32_bf16 v[60:63], v[92:95], v[124:127], v[60:63]
	s_waitcnt lgkmcnt(6)
	v_mfma_f32_16x16x32_bf16 v[160:163], v[64:67], v[96:99], v[160:163]
	ds_read_b128 v[80:83], v220 offset:16384
	s_waitcnt lgkmcnt(6)
	v_mfma_f32_16x16x32_bf16 v[164:167], v[64:67], v[100:103], v[164:167]
	ds_read_b128 v[112:115], v224 offset:49152
	s_waitcnt lgkmcnt(6)
	v_mfma_f32_16x16x32_bf16 v[168:171], v[64:67], v[104:107], v[168:171]
	ds_read_b128 v[116:119], v224 offset:51200
	s_waitcnt lgkmcnt(6)
	v_mfma_f32_16x16x32_bf16 v[172:175], v[64:67], v[108:111], v[172:175]
	ds_read_b128 v[120:123], v224 offset:53248
	s_waitcnt lgkmcnt(6)
	v_mfma_f32_16x16x32_bf16 v[176:179], v[68:71], v[96:99], v[176:179]
	ds_read_b128 v[124:127], v224 offset:55296
	s_waitcnt lgkmcnt(7)
	v_mfma_f32_16x16x32_bf16 v[180:183], v[68:71], v[100:103], v[180:183]
	ds_read_b128 v[84:87], v220 offset:18432
	s_waitcnt lgkmcnt(8)
	v_mfma_f32_16x16x32_bf16 v[184:187], v[68:71], v[104:107], v[184:187]
	ds_read_b128 v[88:91], v220 offset:20480
	s_waitcnt lgkmcnt(9)
	v_mfma_f32_16x16x32_bf16 v[188:191], v[68:71], v[108:111], v[188:191]
	ds_read_b128 v[92:95], v220 offset:22528
	s_waitcnt lgkmcnt(9)
	v_mfma_f32_16x16x32_bf16 v[192:195], v[72:75], v[96:99], v[192:195]
	s_waitcnt lgkmcnt(9)
	v_mfma_f32_16x16x32_bf16 v[196:199], v[72:75], v[100:103], v[196:199]
	s_waitcnt lgkmcnt(9)
	v_mfma_f32_16x16x32_bf16 v[200:203], v[72:75], v[104:107], v[200:203]
	s_waitcnt lgkmcnt(9)
	v_mfma_f32_16x16x32_bf16 v[204:207], v[72:75], v[108:111], v[204:207]
	s_waitcnt vmcnt(0) lgkmcnt(0)
	s_barrier
	s_add_u32 m0, s38, 16384
	s_nop 0
	global_load_lds_dwordx4 v226, s[100:101]
	s_waitcnt lgkmcnt(8)
	v_mfma_f32_16x16x32_bf16 v[208:211], v[76:79], v[96:99], v[208:211]
	s_add_u32 m0, s38, 20480
	s_nop 0
	global_load_lds_dwordx4 v228, s[100:101]
	s_waitcnt lgkmcnt(8)
	v_mfma_f32_16x16x32_bf16 v[212:215], v[76:79], v[100:103], v[212:215]
	s_add_u32 m0, s38, 24576
	s_nop 0
	global_load_lds_dwordx4 v244, s[100:101]
	s_waitcnt lgkmcnt(8)
	v_mfma_f32_16x16x32_bf16 v[216:219], v[76:79], v[104:107], v[216:219]
	s_add_u32 m0, s38, 28672
	s_nop 0
	global_load_lds_dwordx4 v245, s[100:101]
	s_add_u32 s100, s100, 128
	s_addc_u32 s101, s101, 0
	s_waitcnt lgkmcnt(8)
	v_mfma_f32_16x16x32_bf16 v[230:233], v[76:79], v[108:111], v[230:233]
	s_add_u32 m0, s38, 49152
	s_nop 0
	global_load_lds_dwordx4 v226, s[4:5]
	s_waitcnt lgkmcnt(6)
	v_mfma_f32_16x16x32_bf16 v[160:163], v[80:83], v[112:115], v[160:163]
	ds_read_b128 v[64:67], v151 offset:0
	s_add_u32 m0, s38, 53248
	s_nop 0
	global_load_lds_dwordx4 v228, s[4:5]
	s_waitcnt lgkmcnt(6)
	v_mfma_f32_16x16x32_bf16 v[164:167], v[80:83], v[116:119], v[164:167]
	ds_read_b128 v[96:99], v222 offset:32768
	s_add_u32 m0, s38, 57344
	s_nop 0
	global_load_lds_dwordx4 v244, s[4:5]
	s_waitcnt lgkmcnt(6)
	v_mfma_f32_16x16x32_bf16 v[168:171], v[80:83], v[120:123], v[168:171]
	ds_read_b128 v[100:103], v222 offset:34816
	s_add_u32 m0, s38, 61440
	s_nop 0
	global_load_lds_dwordx4 v245, s[4:5]
	s_add_u32 s4, s4, 128
	s_addc_u32 s5, s5, 0
	s_waitcnt lgkmcnt(6)
	v_mfma_f32_16x16x32_bf16 v[172:175], v[80:83], v[124:127], v[172:175]
	ds_read_b128 v[104:107], v222 offset:36864
	s_waitcnt lgkmcnt(6)
	v_mfma_f32_16x16x32_bf16 v[176:179], v[84:87], v[112:115], v[176:179]
	ds_read_b128 v[108:111], v222 offset:38912
	s_waitcnt lgkmcnt(7)
	v_mfma_f32_16x16x32_bf16 v[180:183], v[84:87], v[116:119], v[180:183]
	ds_read_b128 v[68:71], v151 offset:2048
	s_waitcnt lgkmcnt(8)
	v_mfma_f32_16x16x32_bf16 v[184:187], v[84:87], v[120:123], v[184:187]
	ds_read_b128 v[72:75], v151 offset:4096
	s_waitcnt lgkmcnt(9)
	v_mfma_f32_16x16x32_bf16 v[188:191], v[84:87], v[124:127], v[188:191]
	ds_read_b128 v[76:79], v151 offset:6144
	s_waitcnt lgkmcnt(9)
	v_mfma_f32_16x16x32_bf16 v[192:195], v[88:91], v[112:115], v[192:195]
	s_waitcnt lgkmcnt(9)
	v_mfma_f32_16x16x32_bf16 v[196:199], v[88:91], v[116:119], v[196:199]
	s_waitcnt lgkmcnt(9)
	v_mfma_f32_16x16x32_bf16 v[200:203], v[88:91], v[120:123], v[200:203]
	s_waitcnt lgkmcnt(9)
	v_mfma_f32_16x16x32_bf16 v[204:207], v[88:91], v[124:127], v[204:207]
	s_waitcnt lgkmcnt(8)
	v_mfma_f32_16x16x32_bf16 v[208:211], v[92:95], v[112:115], v[208:211]
	s_waitcnt lgkmcnt(8)
	v_mfma_f32_16x16x32_bf16 v[212:215], v[92:95], v[116:119], v[212:215]
	s_waitcnt lgkmcnt(8)
	v_mfma_f32_16x16x32_bf16 v[216:219], v[92:95], v[120:123], v[216:219]
	s_waitcnt lgkmcnt(8)
	v_mfma_f32_16x16x32_bf16 v[230:233], v[92:95], v[124:127], v[230:233]
	s_waitcnt lgkmcnt(6)
	v_mfma_f32_16x16x32_bf16 v[0:3], v[64:67], v[96:99], v[0:3]
	ds_read_b128 v[80:83], v220 offset:0
	s_waitcnt lgkmcnt(6)
	v_mfma_f32_16x16x32_bf16 v[4:7], v[64:67], v[100:103], v[4:7]
	ds_read_b128 v[112:115], v224 offset:32768
	s_waitcnt lgkmcnt(6)
	v_mfma_f32_16x16x32_bf16 v[8:11], v[64:67], v[104:107], v[8:11]
	ds_read_b128 v[116:119], v224 offset:34816
	s_waitcnt lgkmcnt(6)
	v_mfma_f32_16x16x32_bf16 v[12:15], v[64:67], v[108:111], v[12:15]
	ds_read_b128 v[120:123], v224 offset:36864
	s_waitcnt lgkmcnt(6)
	v_mfma_f32_16x16x32_bf16 v[16:19], v[68:71], v[96:99], v[16:19]
	ds_read_b128 v[124:127], v224 offset:38912
	s_waitcnt lgkmcnt(7)
	v_mfma_f32_16x16x32_bf16 v[20:23], v[68:71], v[100:103], v[20:23]
	ds_read_b128 v[84:87], v220 offset:2048
	s_waitcnt lgkmcnt(8)
	v_mfma_f32_16x16x32_bf16 v[24:27], v[68:71], v[104:107], v[24:27]
	ds_read_b128 v[88:91], v220 offset:4096
	s_waitcnt lgkmcnt(9)
	v_mfma_f32_16x16x32_bf16 v[28:31], v[68:71], v[108:111], v[28:31]
	ds_read_b128 v[92:95], v220 offset:6144
	s_waitcnt lgkmcnt(9)
	v_mfma_f32_16x16x32_bf16 v[32:35], v[72:75], v[96:99], v[32:35]
	s_waitcnt lgkmcnt(9)
	v_mfma_f32_16x16x32_bf16 v[36:39], v[72:75], v[100:103], v[36:39]
	s_waitcnt lgkmcnt(9)
	v_mfma_f32_16x16x32_bf16 v[40:43], v[72:75], v[104:107], v[40:43]
	s_waitcnt lgkmcnt(9)
	v_mfma_f32_16x16x32_bf16 v[44:47], v[72:75], v[108:111], v[44:47]
	s_waitcnt vmcnt(4) lgkmcnt(0)
	s_barrier
	s_add_u32 m0, s38, 0
	s_nop 0
	global_load_lds_dwordx4 v226, s[98:99]
	s_waitcnt lgkmcnt(8)
	v_mfma_f32_16x16x32_bf16 v[48:51], v[76:79], v[96:99], v[48:51]
	s_add_u32 m0, s38, 4096
	s_nop 0
	global_load_lds_dwordx4 v228, s[98:99]
	s_waitcnt lgkmcnt(8)
	v_mfma_f32_16x16x32_bf16 v[52:55], v[76:79], v[100:103], v[52:55]
	s_add_u32 m0, s38, 8192
	s_nop 0
	global_load_lds_dwordx4 v244, s[98:99]
	s_waitcnt lgkmcnt(8)
	v_mfma_f32_16x16x32_bf16 v[56:59], v[76:79], v[104:107], v[56:59]
	s_add_u32 m0, s38, 12288
	s_nop 0
	global_load_lds_dwordx4 v245, s[98:99]
	s_add_u32 s98, s98, 128
	s_addc_u32 s99, s99, 0
	s_waitcnt lgkmcnt(8)
	v_mfma_f32_16x16x32_bf16 v[60:63], v[76:79], v[108:111], v[60:63]
	s_waitcnt lgkmcnt(6)
	v_mfma_f32_16x16x32_bf16 v[0:3], v[80:83], v[112:115], v[0:3]
	ds_read_b128 v[64:67], v151 offset:16384
	s_waitcnt lgkmcnt(6)
	v_mfma_f32_16x16x32_bf16 v[4:7], v[80:83], v[116:119], v[4:7]
	ds_read_b128 v[96:99], v222 offset:32768
	s_waitcnt lgkmcnt(6)
	v_mfma_f32_16x16x32_bf16 v[8:11], v[80:83], v[120:123], v[8:11]
	ds_read_b128 v[100:103], v222 offset:34816
	s_waitcnt lgkmcnt(6)
	v_mfma_f32_16x16x32_bf16 v[12:15], v[80:83], v[124:127], v[12:15]
	ds_read_b128 v[104:107], v222 offset:36864
	s_waitcnt lgkmcnt(6)
	v_mfma_f32_16x16x32_bf16 v[16:19], v[84:87], v[112:115], v[16:19]
	ds_read_b128 v[108:111], v222 offset:38912
	s_waitcnt lgkmcnt(7)
	v_mfma_f32_16x16x32_bf16 v[20:23], v[84:87], v[116:119], v[20:23]
	ds_read_b128 v[68:71], v151 offset:18432
	s_waitcnt lgkmcnt(8)
	v_mfma_f32_16x16x32_bf16 v[24:27], v[84:87], v[120:123], v[24:27]
	ds_read_b128 v[72:75], v151 offset:20480
	s_waitcnt lgkmcnt(9)
	v_mfma_f32_16x16x32_bf16 v[28:31], v[84:87], v[124:127], v[28:31]
	ds_read_b128 v[76:79], v151 offset:22528
	s_waitcnt lgkmcnt(9)
	v_mfma_f32_16x16x32_bf16 v[32:35], v[88:91], v[112:115], v[32:35]
	s_waitcnt lgkmcnt(9)
	v_mfma_f32_16x16x32_bf16 v[36:39], v[88:91], v[116:119], v[36:39]
	s_waitcnt lgkmcnt(9)
	v_mfma_f32_16x16x32_bf16 v[40:43], v[88:91], v[120:123], v[40:43]
	s_waitcnt lgkmcnt(9)
	v_mfma_f32_16x16x32_bf16 v[44:47], v[88:91], v[124:127], v[44:47]
	s_waitcnt lgkmcnt(8)
	v_mfma_f32_16x16x32_bf16 v[48:51], v[92:95], v[112:115], v[48:51]
	s_waitcnt lgkmcnt(8)
	v_mfma_f32_16x16x32_bf16 v[52:55], v[92:95], v[116:119], v[52:55]
	s_waitcnt lgkmcnt(8)
	v_mfma_f32_16x16x32_bf16 v[56:59], v[92:95], v[120:123], v[56:59]
	s_waitcnt lgkmcnt(8)
	v_mfma_f32_16x16x32_bf16 v[60:63], v[92:95], v[124:127], v[60:63]
	s_waitcnt lgkmcnt(6)
	v_mfma_f32_16x16x32_bf16 v[160:163], v[64:67], v[96:99], v[160:163]
	ds_read_b128 v[80:83], v220 offset:16384
	s_waitcnt lgkmcnt(6)
	v_mfma_f32_16x16x32_bf16 v[164:167], v[64:67], v[100:103], v[164:167]
	ds_read_b128 v[112:115], v224 offset:32768
	s_waitcnt lgkmcnt(6)
	v_mfma_f32_16x16x32_bf16 v[168:171], v[64:67], v[104:107], v[168:171]
	ds_read_b128 v[116:119], v224 offset:34816
	s_waitcnt lgkmcnt(6)
	v_mfma_f32_16x16x32_bf16 v[172:175], v[64:67], v[108:111], v[172:175]
	ds_read_b128 v[120:123], v224 offset:36864
	s_waitcnt lgkmcnt(6)
	v_mfma_f32_16x16x32_bf16 v[176:179], v[68:71], v[96:99], v[176:179]
	ds_read_b128 v[124:127], v224 offset:38912
	s_waitcnt lgkmcnt(7)
	v_mfma_f32_16x16x32_bf16 v[180:183], v[68:71], v[100:103], v[180:183]
	ds_read_b128 v[84:87], v220 offset:18432
	s_waitcnt lgkmcnt(8)
	v_mfma_f32_16x16x32_bf16 v[184:187], v[68:71], v[104:107], v[184:187]
	ds_read_b128 v[88:91], v220 offset:20480
	s_waitcnt lgkmcnt(9)
	v_mfma_f32_16x16x32_bf16 v[188:191], v[68:71], v[108:111], v[188:191]
	ds_read_b128 v[92:95], v220 offset:22528
	s_waitcnt lgkmcnt(9)
	v_mfma_f32_16x16x32_bf16 v[192:195], v[72:75], v[96:99], v[192:195]
	s_waitcnt lgkmcnt(9)
	v_mfma_f32_16x16x32_bf16 v[196:199], v[72:75], v[100:103], v[196:199]
	s_waitcnt lgkmcnt(9)
	v_mfma_f32_16x16x32_bf16 v[200:203], v[72:75], v[104:107], v[200:203]
	s_waitcnt lgkmcnt(9)
	v_mfma_f32_16x16x32_bf16 v[204:207], v[72:75], v[108:111], v[204:207]
	s_waitcnt vmcnt(0) lgkmcnt(0)
	s_barrier
	s_add_u32 m0, s38, 16384
	s_nop 0
	global_load_lds_dwordx4 v226, s[100:101]
	s_waitcnt lgkmcnt(8)
	v_mfma_f32_16x16x32_bf16 v[208:211], v[76:79], v[96:99], v[208:211]
	s_add_u32 m0, s38, 20480
	s_nop 0
	global_load_lds_dwordx4 v228, s[100:101]
	s_waitcnt lgkmcnt(8)
	v_mfma_f32_16x16x32_bf16 v[212:215], v[76:79], v[100:103], v[212:215]
	s_add_u32 m0, s38, 24576
	s_nop 0
	global_load_lds_dwordx4 v244, s[100:101]
	s_waitcnt lgkmcnt(8)
	v_mfma_f32_16x16x32_bf16 v[216:219], v[76:79], v[104:107], v[216:219]
	s_add_u32 m0, s38, 28672
	s_nop 0
	global_load_lds_dwordx4 v245, s[100:101]
	s_add_u32 s100, s100, 128
	s_addc_u32 s101, s101, 0
	s_waitcnt lgkmcnt(8)
	v_mfma_f32_16x16x32_bf16 v[230:233], v[76:79], v[108:111], v[230:233]
	s_add_u32 m0, s38, 32768
	s_nop 0
	global_load_lds_dwordx4 v226, s[4:5]
	s_waitcnt lgkmcnt(6)
	v_mfma_f32_16x16x32_bf16 v[160:163], v[80:83], v[112:115], v[160:163]
	ds_read_b128 v[64:67], v151 offset:0
	s_add_u32 m0, s38, 36864
	s_nop 0
	global_load_lds_dwordx4 v228, s[4:5]
	s_waitcnt lgkmcnt(6)
	v_mfma_f32_16x16x32_bf16 v[164:167], v[80:83], v[116:119], v[164:167]
	ds_read_b128 v[96:99], v222 offset:49152
	s_add_u32 m0, s38, 40960
	s_nop 0
	global_load_lds_dwordx4 v244, s[4:5]
	s_waitcnt lgkmcnt(6)
	v_mfma_f32_16x16x32_bf16 v[168:171], v[80:83], v[120:123], v[168:171]
	ds_read_b128 v[100:103], v222 offset:51200
	s_add_u32 m0, s38, 45056
	s_nop 0
	global_load_lds_dwordx4 v245, s[4:5]
	s_add_u32 s4, s4, 128
	s_addc_u32 s5, s5, 0
	s_waitcnt lgkmcnt(6)
	v_mfma_f32_16x16x32_bf16 v[172:175], v[80:83], v[124:127], v[172:175]
	ds_read_b128 v[104:107], v222 offset:53248
	s_waitcnt lgkmcnt(6)
	v_mfma_f32_16x16x32_bf16 v[176:179], v[84:87], v[112:115], v[176:179]
	ds_read_b128 v[108:111], v222 offset:55296
	s_waitcnt lgkmcnt(7)
	v_mfma_f32_16x16x32_bf16 v[180:183], v[84:87], v[116:119], v[180:183]
	ds_read_b128 v[68:71], v151 offset:2048
	s_waitcnt lgkmcnt(8)
	v_mfma_f32_16x16x32_bf16 v[184:187], v[84:87], v[120:123], v[184:187]
	ds_read_b128 v[72:75], v151 offset:4096
	s_waitcnt lgkmcnt(9)
	v_mfma_f32_16x16x32_bf16 v[188:191], v[84:87], v[124:127], v[188:191]
	ds_read_b128 v[76:79], v151 offset:6144
	s_waitcnt lgkmcnt(9)
	v_mfma_f32_16x16x32_bf16 v[192:195], v[88:91], v[112:115], v[192:195]
	s_waitcnt lgkmcnt(9)
	v_mfma_f32_16x16x32_bf16 v[196:199], v[88:91], v[116:119], v[196:199]
	s_waitcnt lgkmcnt(9)
	v_mfma_f32_16x16x32_bf16 v[200:203], v[88:91], v[120:123], v[200:203]
	s_waitcnt lgkmcnt(9)
	v_mfma_f32_16x16x32_bf16 v[204:207], v[88:91], v[124:127], v[204:207]
	s_waitcnt lgkmcnt(8)
	v_mfma_f32_16x16x32_bf16 v[208:211], v[92:95], v[112:115], v[208:211]
	s_waitcnt lgkmcnt(8)
	v_mfma_f32_16x16x32_bf16 v[212:215], v[92:95], v[116:119], v[212:215]
	s_waitcnt lgkmcnt(8)
	v_mfma_f32_16x16x32_bf16 v[216:219], v[92:95], v[120:123], v[216:219]
	s_waitcnt lgkmcnt(8)
	v_mfma_f32_16x16x32_bf16 v[230:233], v[92:95], v[124:127], v[230:233]
	s_waitcnt lgkmcnt(6)
	v_mfma_f32_16x16x32_bf16 v[0:3], v[64:67], v[96:99], v[0:3]
	ds_read_b128 v[80:83], v220 offset:0
	s_waitcnt lgkmcnt(6)
	v_mfma_f32_16x16x32_bf16 v[4:7], v[64:67], v[100:103], v[4:7]
	ds_read_b128 v[112:115], v224 offset:49152
	s_waitcnt lgkmcnt(6)
	v_mfma_f32_16x16x32_bf16 v[8:11], v[64:67], v[104:107], v[8:11]
	ds_read_b128 v[116:119], v224 offset:51200
	s_waitcnt lgkmcnt(6)
	v_mfma_f32_16x16x32_bf16 v[12:15], v[64:67], v[108:111], v[12:15]
	ds_read_b128 v[120:123], v224 offset:53248
	s_waitcnt lgkmcnt(6)
	v_mfma_f32_16x16x32_bf16 v[16:19], v[68:71], v[96:99], v[16:19]
	ds_read_b128 v[124:127], v224 offset:55296
	s_waitcnt lgkmcnt(7)
	v_mfma_f32_16x16x32_bf16 v[20:23], v[68:71], v[100:103], v[20:23]
	ds_read_b128 v[84:87], v220 offset:2048
	s_waitcnt lgkmcnt(8)
	v_mfma_f32_16x16x32_bf16 v[24:27], v[68:71], v[104:107], v[24:27]
	ds_read_b128 v[88:91], v220 offset:4096
	s_waitcnt lgkmcnt(9)
	v_mfma_f32_16x16x32_bf16 v[28:31], v[68:71], v[108:111], v[28:31]
	ds_read_b128 v[92:95], v220 offset:6144
	s_waitcnt lgkmcnt(9)
	v_mfma_f32_16x16x32_bf16 v[32:35], v[72:75], v[96:99], v[32:35]
	s_waitcnt lgkmcnt(9)
	v_mfma_f32_16x16x32_bf16 v[36:39], v[72:75], v[100:103], v[36:39]
	s_waitcnt lgkmcnt(9)
	v_mfma_f32_16x16x32_bf16 v[40:43], v[72:75], v[104:107], v[40:43]
	s_waitcnt lgkmcnt(9)
	v_mfma_f32_16x16x32_bf16 v[44:47], v[72:75], v[108:111], v[44:47]
	s_waitcnt vmcnt(4) lgkmcnt(0)
	s_barrier
	s_add_u32 m0, s38, 0
	s_nop 0
	global_load_lds_dwordx4 v226, s[98:99]
	s_waitcnt lgkmcnt(8)
	v_mfma_f32_16x16x32_bf16 v[48:51], v[76:79], v[96:99], v[48:51]
	s_add_u32 m0, s38, 4096
	s_nop 0
	global_load_lds_dwordx4 v228, s[98:99]
	s_waitcnt lgkmcnt(8)
	v_mfma_f32_16x16x32_bf16 v[52:55], v[76:79], v[100:103], v[52:55]
	s_add_u32 m0, s38, 8192
	s_nop 0
	global_load_lds_dwordx4 v244, s[98:99]
	s_waitcnt lgkmcnt(8)
	v_mfma_f32_16x16x32_bf16 v[56:59], v[76:79], v[104:107], v[56:59]
	s_add_u32 m0, s38, 12288
	s_nop 0
	global_load_lds_dwordx4 v245, s[98:99]
	s_add_u32 s98, s98, 128
	s_addc_u32 s99, s99, 0
	s_waitcnt lgkmcnt(8)
	v_mfma_f32_16x16x32_bf16 v[60:63], v[76:79], v[108:111], v[60:63]
	s_waitcnt lgkmcnt(6)
	v_mfma_f32_16x16x32_bf16 v[0:3], v[80:83], v[112:115], v[0:3]
	ds_read_b128 v[64:67], v151 offset:16384
	s_waitcnt lgkmcnt(6)
	v_mfma_f32_16x16x32_bf16 v[4:7], v[80:83], v[116:119], v[4:7]
	ds_read_b128 v[96:99], v222 offset:49152
	s_waitcnt lgkmcnt(6)
	v_mfma_f32_16x16x32_bf16 v[8:11], v[80:83], v[120:123], v[8:11]
	ds_read_b128 v[100:103], v222 offset:51200
	s_waitcnt lgkmcnt(6)
	v_mfma_f32_16x16x32_bf16 v[12:15], v[80:83], v[124:127], v[12:15]
	ds_read_b128 v[104:107], v222 offset:53248
	s_waitcnt lgkmcnt(6)
	v_mfma_f32_16x16x32_bf16 v[16:19], v[84:87], v[112:115], v[16:19]
	ds_read_b128 v[108:111], v222 offset:55296
	s_waitcnt lgkmcnt(7)
	v_mfma_f32_16x16x32_bf16 v[20:23], v[84:87], v[116:119], v[20:23]
	ds_read_b128 v[68:71], v151 offset:18432
	s_waitcnt lgkmcnt(8)
	v_mfma_f32_16x16x32_bf16 v[24:27], v[84:87], v[120:123], v[24:27]
	ds_read_b128 v[72:75], v151 offset:20480
	s_waitcnt lgkmcnt(9)
	v_mfma_f32_16x16x32_bf16 v[28:31], v[84:87], v[124:127], v[28:31]
	ds_read_b128 v[76:79], v151 offset:22528
	s_waitcnt lgkmcnt(9)
	v_mfma_f32_16x16x32_bf16 v[32:35], v[88:91], v[112:115], v[32:35]
	s_waitcnt lgkmcnt(9)
	v_mfma_f32_16x16x32_bf16 v[36:39], v[88:91], v[116:119], v[36:39]
	s_waitcnt lgkmcnt(9)
	v_mfma_f32_16x16x32_bf16 v[40:43], v[88:91], v[120:123], v[40:43]
	s_waitcnt lgkmcnt(9)
	v_mfma_f32_16x16x32_bf16 v[44:47], v[88:91], v[124:127], v[44:47]
	s_waitcnt lgkmcnt(8)
	v_mfma_f32_16x16x32_bf16 v[48:51], v[92:95], v[112:115], v[48:51]
	s_waitcnt lgkmcnt(8)
	v_mfma_f32_16x16x32_bf16 v[52:55], v[92:95], v[116:119], v[52:55]
	s_waitcnt lgkmcnt(8)
	v_mfma_f32_16x16x32_bf16 v[56:59], v[92:95], v[120:123], v[56:59]
	s_waitcnt lgkmcnt(8)
	v_mfma_f32_16x16x32_bf16 v[60:63], v[92:95], v[124:127], v[60:63]
	s_waitcnt lgkmcnt(6)
	v_mfma_f32_16x16x32_bf16 v[160:163], v[64:67], v[96:99], v[160:163]
	ds_read_b128 v[80:83], v220 offset:16384
	s_waitcnt lgkmcnt(6)
	v_mfma_f32_16x16x32_bf16 v[164:167], v[64:67], v[100:103], v[164:167]
	ds_read_b128 v[112:115], v224 offset:49152
	s_waitcnt lgkmcnt(6)
	v_mfma_f32_16x16x32_bf16 v[168:171], v[64:67], v[104:107], v[168:171]
	ds_read_b128 v[116:119], v224 offset:51200
	s_waitcnt lgkmcnt(6)
	v_mfma_f32_16x16x32_bf16 v[172:175], v[64:67], v[108:111], v[172:175]
	ds_read_b128 v[120:123], v224 offset:53248
	s_waitcnt lgkmcnt(6)
	v_mfma_f32_16x16x32_bf16 v[176:179], v[68:71], v[96:99], v[176:179]
	ds_read_b128 v[124:127], v224 offset:55296
	s_waitcnt lgkmcnt(7)
	v_mfma_f32_16x16x32_bf16 v[180:183], v[68:71], v[100:103], v[180:183]
	ds_read_b128 v[84:87], v220 offset:18432
	s_waitcnt lgkmcnt(8)
	v_mfma_f32_16x16x32_bf16 v[184:187], v[68:71], v[104:107], v[184:187]
	ds_read_b128 v[88:91], v220 offset:20480
	s_waitcnt lgkmcnt(9)
	v_mfma_f32_16x16x32_bf16 v[188:191], v[68:71], v[108:111], v[188:191]
	ds_read_b128 v[92:95], v220 offset:22528
	s_waitcnt lgkmcnt(9)
	v_mfma_f32_16x16x32_bf16 v[192:195], v[72:75], v[96:99], v[192:195]
	s_waitcnt lgkmcnt(9)
	v_mfma_f32_16x16x32_bf16 v[196:199], v[72:75], v[100:103], v[196:199]
	s_waitcnt lgkmcnt(9)
	v_mfma_f32_16x16x32_bf16 v[200:203], v[72:75], v[104:107], v[200:203]
	s_waitcnt lgkmcnt(9)
	v_mfma_f32_16x16x32_bf16 v[204:207], v[72:75], v[108:111], v[204:207]
	s_waitcnt vmcnt(0) lgkmcnt(0)
	s_barrier
	s_add_u32 m0, s38, 16384
	s_nop 0
	global_load_lds_dwordx4 v226, s[100:101]
	s_waitcnt lgkmcnt(8)
	v_mfma_f32_16x16x32_bf16 v[208:211], v[76:79], v[96:99], v[208:211]
	s_add_u32 m0, s38, 20480
	s_nop 0
	global_load_lds_dwordx4 v228, s[100:101]
	s_waitcnt lgkmcnt(8)
	v_mfma_f32_16x16x32_bf16 v[212:215], v[76:79], v[100:103], v[212:215]
	s_add_u32 m0, s38, 24576
	s_nop 0
	global_load_lds_dwordx4 v244, s[100:101]
	s_waitcnt lgkmcnt(8)
	v_mfma_f32_16x16x32_bf16 v[216:219], v[76:79], v[104:107], v[216:219]
	s_add_u32 m0, s38, 28672
	s_nop 0
	global_load_lds_dwordx4 v245, s[100:101]
	s_add_u32 s100, s100, 128
	s_addc_u32 s101, s101, 0
	s_waitcnt lgkmcnt(8)
	v_mfma_f32_16x16x32_bf16 v[230:233], v[76:79], v[108:111], v[230:233]
	s_add_u32 m0, s38, 49152
	s_nop 0
	global_load_lds_dwordx4 v226, s[4:5]
	s_waitcnt lgkmcnt(6)
	v_mfma_f32_16x16x32_bf16 v[160:163], v[80:83], v[112:115], v[160:163]
	ds_read_b128 v[64:67], v151 offset:0
	s_add_u32 m0, s38, 53248
	s_nop 0
	global_load_lds_dwordx4 v228, s[4:5]
	s_waitcnt lgkmcnt(6)
	v_mfma_f32_16x16x32_bf16 v[164:167], v[80:83], v[116:119], v[164:167]
	ds_read_b128 v[96:99], v222 offset:32768
	s_add_u32 m0, s38, 57344
	s_nop 0
	global_load_lds_dwordx4 v244, s[4:5]
	s_waitcnt lgkmcnt(6)
	v_mfma_f32_16x16x32_bf16 v[168:171], v[80:83], v[120:123], v[168:171]
	ds_read_b128 v[100:103], v222 offset:34816
	s_add_u32 m0, s38, 61440
	s_nop 0
	global_load_lds_dwordx4 v245, s[4:5]
	s_add_u32 s4, s4, 128
	s_addc_u32 s5, s5, 0
	s_waitcnt lgkmcnt(6)
	v_mfma_f32_16x16x32_bf16 v[172:175], v[80:83], v[124:127], v[172:175]
	ds_read_b128 v[104:107], v222 offset:36864
	s_waitcnt lgkmcnt(6)
	v_mfma_f32_16x16x32_bf16 v[176:179], v[84:87], v[112:115], v[176:179]
	ds_read_b128 v[108:111], v222 offset:38912
	s_waitcnt lgkmcnt(7)
	v_mfma_f32_16x16x32_bf16 v[180:183], v[84:87], v[116:119], v[180:183]
	ds_read_b128 v[68:71], v151 offset:2048
	s_waitcnt lgkmcnt(8)
	v_mfma_f32_16x16x32_bf16 v[184:187], v[84:87], v[120:123], v[184:187]
	ds_read_b128 v[72:75], v151 offset:4096
	s_waitcnt lgkmcnt(9)
	v_mfma_f32_16x16x32_bf16 v[188:191], v[84:87], v[124:127], v[188:191]
	ds_read_b128 v[76:79], v151 offset:6144
	s_waitcnt lgkmcnt(9)
	v_mfma_f32_16x16x32_bf16 v[192:195], v[88:91], v[112:115], v[192:195]
	s_waitcnt lgkmcnt(9)
	v_mfma_f32_16x16x32_bf16 v[196:199], v[88:91], v[116:119], v[196:199]
	s_waitcnt lgkmcnt(9)
	v_mfma_f32_16x16x32_bf16 v[200:203], v[88:91], v[120:123], v[200:203]
	s_waitcnt lgkmcnt(9)
	v_mfma_f32_16x16x32_bf16 v[204:207], v[88:91], v[124:127], v[204:207]
	s_waitcnt lgkmcnt(8)
	v_mfma_f32_16x16x32_bf16 v[208:211], v[92:95], v[112:115], v[208:211]
	s_waitcnt lgkmcnt(8)
	v_mfma_f32_16x16x32_bf16 v[212:215], v[92:95], v[116:119], v[212:215]
	s_waitcnt lgkmcnt(8)
	v_mfma_f32_16x16x32_bf16 v[216:219], v[92:95], v[120:123], v[216:219]
	s_waitcnt lgkmcnt(8)
	v_mfma_f32_16x16x32_bf16 v[230:233], v[92:95], v[124:127], v[230:233]
	s_waitcnt lgkmcnt(6)
	v_mfma_f32_16x16x32_bf16 v[0:3], v[64:67], v[96:99], v[0:3]
	ds_read_b128 v[80:83], v220 offset:0
	s_waitcnt lgkmcnt(6)
	v_mfma_f32_16x16x32_bf16 v[4:7], v[64:67], v[100:103], v[4:7]
	ds_read_b128 v[112:115], v224 offset:32768
	s_waitcnt lgkmcnt(6)
	v_mfma_f32_16x16x32_bf16 v[8:11], v[64:67], v[104:107], v[8:11]
	ds_read_b128 v[116:119], v224 offset:34816
	s_waitcnt lgkmcnt(6)
	v_mfma_f32_16x16x32_bf16 v[12:15], v[64:67], v[108:111], v[12:15]
	ds_read_b128 v[120:123], v224 offset:36864
	s_waitcnt lgkmcnt(6)
	v_mfma_f32_16x16x32_bf16 v[16:19], v[68:71], v[96:99], v[16:19]
	ds_read_b128 v[124:127], v224 offset:38912
	s_waitcnt lgkmcnt(7)
	v_mfma_f32_16x16x32_bf16 v[20:23], v[68:71], v[100:103], v[20:23]
	ds_read_b128 v[84:87], v220 offset:2048
	s_waitcnt lgkmcnt(8)
	v_mfma_f32_16x16x32_bf16 v[24:27], v[68:71], v[104:107], v[24:27]
	ds_read_b128 v[88:91], v220 offset:4096
	s_waitcnt lgkmcnt(9)
	v_mfma_f32_16x16x32_bf16 v[28:31], v[68:71], v[108:111], v[28:31]
	ds_read_b128 v[92:95], v220 offset:6144
	s_waitcnt lgkmcnt(9)
	v_mfma_f32_16x16x32_bf16 v[32:35], v[72:75], v[96:99], v[32:35]
	s_waitcnt lgkmcnt(9)
	v_mfma_f32_16x16x32_bf16 v[36:39], v[72:75], v[100:103], v[36:39]
	s_waitcnt lgkmcnt(9)
	v_mfma_f32_16x16x32_bf16 v[40:43], v[72:75], v[104:107], v[40:43]
	s_waitcnt lgkmcnt(9)
	v_mfma_f32_16x16x32_bf16 v[44:47], v[72:75], v[108:111], v[44:47]
	s_waitcnt vmcnt(4) lgkmcnt(0)
	s_barrier
	s_add_u32 m0, s38, 0
	s_nop 0
	global_load_lds_dwordx4 v226, s[98:99]
	s_waitcnt lgkmcnt(8)
	v_mfma_f32_16x16x32_bf16 v[48:51], v[76:79], v[96:99], v[48:51]
	s_add_u32 m0, s38, 4096
	s_nop 0
	global_load_lds_dwordx4 v228, s[98:99]
	s_waitcnt lgkmcnt(8)
	v_mfma_f32_16x16x32_bf16 v[52:55], v[76:79], v[100:103], v[52:55]
	s_add_u32 m0, s38, 8192
	s_nop 0
	global_load_lds_dwordx4 v244, s[98:99]
	s_waitcnt lgkmcnt(8)
	v_mfma_f32_16x16x32_bf16 v[56:59], v[76:79], v[104:107], v[56:59]
	s_add_u32 m0, s38, 12288
	s_nop 0
	global_load_lds_dwordx4 v245, s[98:99]
	s_add_u32 s98, s98, 128
	s_addc_u32 s99, s99, 0
	s_waitcnt lgkmcnt(8)
	v_mfma_f32_16x16x32_bf16 v[60:63], v[76:79], v[108:111], v[60:63]
	s_waitcnt lgkmcnt(6)
	v_mfma_f32_16x16x32_bf16 v[0:3], v[80:83], v[112:115], v[0:3]
	ds_read_b128 v[64:67], v151 offset:16384
	s_waitcnt lgkmcnt(6)
	v_mfma_f32_16x16x32_bf16 v[4:7], v[80:83], v[116:119], v[4:7]
	ds_read_b128 v[96:99], v222 offset:32768
	s_waitcnt lgkmcnt(6)
	v_mfma_f32_16x16x32_bf16 v[8:11], v[80:83], v[120:123], v[8:11]
	ds_read_b128 v[100:103], v222 offset:34816
	s_waitcnt lgkmcnt(6)
	v_mfma_f32_16x16x32_bf16 v[12:15], v[80:83], v[124:127], v[12:15]
	ds_read_b128 v[104:107], v222 offset:36864
	s_waitcnt lgkmcnt(6)
	v_mfma_f32_16x16x32_bf16 v[16:19], v[84:87], v[112:115], v[16:19]
	ds_read_b128 v[108:111], v222 offset:38912
	s_waitcnt lgkmcnt(7)
	v_mfma_f32_16x16x32_bf16 v[20:23], v[84:87], v[116:119], v[20:23]
	ds_read_b128 v[68:71], v151 offset:18432
	s_waitcnt lgkmcnt(8)
	v_mfma_f32_16x16x32_bf16 v[24:27], v[84:87], v[120:123], v[24:27]
	ds_read_b128 v[72:75], v151 offset:20480
	s_waitcnt lgkmcnt(9)
	v_mfma_f32_16x16x32_bf16 v[28:31], v[84:87], v[124:127], v[28:31]
	ds_read_b128 v[76:79], v151 offset:22528
	s_waitcnt lgkmcnt(9)
	v_mfma_f32_16x16x32_bf16 v[32:35], v[88:91], v[112:115], v[32:35]
	s_waitcnt lgkmcnt(9)
	v_mfma_f32_16x16x32_bf16 v[36:39], v[88:91], v[116:119], v[36:39]
	s_waitcnt lgkmcnt(9)
	v_mfma_f32_16x16x32_bf16 v[40:43], v[88:91], v[120:123], v[40:43]
	s_waitcnt lgkmcnt(9)
	v_mfma_f32_16x16x32_bf16 v[44:47], v[88:91], v[124:127], v[44:47]
	s_waitcnt lgkmcnt(8)
	v_mfma_f32_16x16x32_bf16 v[48:51], v[92:95], v[112:115], v[48:51]
	s_waitcnt lgkmcnt(8)
	v_mfma_f32_16x16x32_bf16 v[52:55], v[92:95], v[116:119], v[52:55]
	s_waitcnt lgkmcnt(8)
	v_mfma_f32_16x16x32_bf16 v[56:59], v[92:95], v[120:123], v[56:59]
	s_waitcnt lgkmcnt(8)
	v_mfma_f32_16x16x32_bf16 v[60:63], v[92:95], v[124:127], v[60:63]
	s_waitcnt lgkmcnt(6)
	v_mfma_f32_16x16x32_bf16 v[160:163], v[64:67], v[96:99], v[160:163]
	ds_read_b128 v[80:83], v220 offset:16384
	s_waitcnt lgkmcnt(6)
	v_mfma_f32_16x16x32_bf16 v[164:167], v[64:67], v[100:103], v[164:167]
	ds_read_b128 v[112:115], v224 offset:32768
	s_waitcnt lgkmcnt(6)
	v_mfma_f32_16x16x32_bf16 v[168:171], v[64:67], v[104:107], v[168:171]
	ds_read_b128 v[116:119], v224 offset:34816
	s_waitcnt lgkmcnt(6)
	v_mfma_f32_16x16x32_bf16 v[172:175], v[64:67], v[108:111], v[172:175]
	ds_read_b128 v[120:123], v224 offset:36864
	s_waitcnt lgkmcnt(6)
	v_mfma_f32_16x16x32_bf16 v[176:179], v[68:71], v[96:99], v[176:179]
	ds_read_b128 v[124:127], v224 offset:38912
	s_waitcnt lgkmcnt(7)
	v_mfma_f32_16x16x32_bf16 v[180:183], v[68:71], v[100:103], v[180:183]
	ds_read_b128 v[84:87], v220 offset:18432
	s_waitcnt lgkmcnt(8)
	v_mfma_f32_16x16x32_bf16 v[184:187], v[68:71], v[104:107], v[184:187]
	ds_read_b128 v[88:91], v220 offset:20480
	s_waitcnt lgkmcnt(9)
	v_mfma_f32_16x16x32_bf16 v[188:191], v[68:71], v[108:111], v[188:191]
	ds_read_b128 v[92:95], v220 offset:22528
	s_waitcnt lgkmcnt(9)
	v_mfma_f32_16x16x32_bf16 v[192:195], v[72:75], v[96:99], v[192:195]
	s_waitcnt lgkmcnt(9)
	v_mfma_f32_16x16x32_bf16 v[196:199], v[72:75], v[100:103], v[196:199]
	s_waitcnt lgkmcnt(9)
	v_mfma_f32_16x16x32_bf16 v[200:203], v[72:75], v[104:107], v[200:203]
	s_waitcnt lgkmcnt(9)
	v_mfma_f32_16x16x32_bf16 v[204:207], v[72:75], v[108:111], v[204:207]
	s_waitcnt vmcnt(0) lgkmcnt(0)
	s_barrier
	s_add_u32 m0, s38, 16384
	s_nop 0
	global_load_lds_dwordx4 v226, s[100:101]
	s_waitcnt lgkmcnt(8)
	v_mfma_f32_16x16x32_bf16 v[208:211], v[76:79], v[96:99], v[208:211]
	s_add_u32 m0, s38, 20480
	s_nop 0
	global_load_lds_dwordx4 v228, s[100:101]
	s_waitcnt lgkmcnt(8)
	v_mfma_f32_16x16x32_bf16 v[212:215], v[76:79], v[100:103], v[212:215]
	s_add_u32 m0, s38, 24576
	s_nop 0
	global_load_lds_dwordx4 v244, s[100:101]
	s_waitcnt lgkmcnt(8)
	v_mfma_f32_16x16x32_bf16 v[216:219], v[76:79], v[104:107], v[216:219]
	s_add_u32 m0, s38, 28672
	s_nop 0
	global_load_lds_dwordx4 v245, s[100:101]
	s_add_u32 s100, s100, 128
	s_addc_u32 s101, s101, 0
	s_waitcnt lgkmcnt(8)
	v_mfma_f32_16x16x32_bf16 v[230:233], v[76:79], v[108:111], v[230:233]
	s_add_u32 m0, s38, 32768
	s_nop 0
	global_load_lds_dwordx4 v226, s[4:5]
	s_waitcnt lgkmcnt(6)
	v_mfma_f32_16x16x32_bf16 v[160:163], v[80:83], v[112:115], v[160:163]
	ds_read_b128 v[64:67], v151 offset:0
	s_add_u32 m0, s38, 36864
	s_nop 0
	global_load_lds_dwordx4 v228, s[4:5]
	s_waitcnt lgkmcnt(6)
	v_mfma_f32_16x16x32_bf16 v[164:167], v[80:83], v[116:119], v[164:167]
	ds_read_b128 v[96:99], v222 offset:49152
	s_add_u32 m0, s38, 40960
	s_nop 0
	global_load_lds_dwordx4 v244, s[4:5]
	s_waitcnt lgkmcnt(6)
	v_mfma_f32_16x16x32_bf16 v[168:171], v[80:83], v[120:123], v[168:171]
	ds_read_b128 v[100:103], v222 offset:51200
	s_add_u32 m0, s38, 45056
	s_nop 0
	global_load_lds_dwordx4 v245, s[4:5]
	s_add_u32 s4, s4, 128
	s_addc_u32 s5, s5, 0
	s_waitcnt lgkmcnt(6)
	v_mfma_f32_16x16x32_bf16 v[172:175], v[80:83], v[124:127], v[172:175]
	ds_read_b128 v[104:107], v222 offset:53248
	s_waitcnt lgkmcnt(6)
	v_mfma_f32_16x16x32_bf16 v[176:179], v[84:87], v[112:115], v[176:179]
	ds_read_b128 v[108:111], v222 offset:55296
	s_waitcnt lgkmcnt(7)
	v_mfma_f32_16x16x32_bf16 v[180:183], v[84:87], v[116:119], v[180:183]
	ds_read_b128 v[68:71], v151 offset:2048
	s_waitcnt lgkmcnt(8)
	v_mfma_f32_16x16x32_bf16 v[184:187], v[84:87], v[120:123], v[184:187]
	ds_read_b128 v[72:75], v151 offset:4096
	s_waitcnt lgkmcnt(9)
	v_mfma_f32_16x16x32_bf16 v[188:191], v[84:87], v[124:127], v[188:191]
	ds_read_b128 v[76:79], v151 offset:6144
	s_waitcnt lgkmcnt(9)
	v_mfma_f32_16x16x32_bf16 v[192:195], v[88:91], v[112:115], v[192:195]
	s_waitcnt lgkmcnt(9)
	v_mfma_f32_16x16x32_bf16 v[196:199], v[88:91], v[116:119], v[196:199]
	s_waitcnt lgkmcnt(9)
	v_mfma_f32_16x16x32_bf16 v[200:203], v[88:91], v[120:123], v[200:203]
	s_waitcnt lgkmcnt(9)
	v_mfma_f32_16x16x32_bf16 v[204:207], v[88:91], v[124:127], v[204:207]
	s_waitcnt lgkmcnt(8)
	v_mfma_f32_16x16x32_bf16 v[208:211], v[92:95], v[112:115], v[208:211]
	s_waitcnt lgkmcnt(8)
	v_mfma_f32_16x16x32_bf16 v[212:215], v[92:95], v[116:119], v[212:215]
	s_waitcnt lgkmcnt(8)
	v_mfma_f32_16x16x32_bf16 v[216:219], v[92:95], v[120:123], v[216:219]
	s_waitcnt lgkmcnt(8)
	v_mfma_f32_16x16x32_bf16 v[230:233], v[92:95], v[124:127], v[230:233]
	s_waitcnt lgkmcnt(6)
	v_mfma_f32_16x16x32_bf16 v[0:3], v[64:67], v[96:99], v[0:3]
	ds_read_b128 v[80:83], v220 offset:0
	s_waitcnt lgkmcnt(6)
	v_mfma_f32_16x16x32_bf16 v[4:7], v[64:67], v[100:103], v[4:7]
	ds_read_b128 v[112:115], v224 offset:49152
	s_waitcnt lgkmcnt(6)
	v_mfma_f32_16x16x32_bf16 v[8:11], v[64:67], v[104:107], v[8:11]
	ds_read_b128 v[116:119], v224 offset:51200
	s_waitcnt lgkmcnt(6)
	v_mfma_f32_16x16x32_bf16 v[12:15], v[64:67], v[108:111], v[12:15]
	ds_read_b128 v[120:123], v224 offset:53248
	s_waitcnt lgkmcnt(6)
	v_mfma_f32_16x16x32_bf16 v[16:19], v[68:71], v[96:99], v[16:19]
	ds_read_b128 v[124:127], v224 offset:55296
	s_waitcnt lgkmcnt(7)
	v_mfma_f32_16x16x32_bf16 v[20:23], v[68:71], v[100:103], v[20:23]
	ds_read_b128 v[84:87], v220 offset:2048
	s_waitcnt lgkmcnt(8)
	v_mfma_f32_16x16x32_bf16 v[24:27], v[68:71], v[104:107], v[24:27]
	ds_read_b128 v[88:91], v220 offset:4096
	s_waitcnt lgkmcnt(9)
	v_mfma_f32_16x16x32_bf16 v[28:31], v[68:71], v[108:111], v[28:31]
	ds_read_b128 v[92:95], v220 offset:6144
	s_waitcnt lgkmcnt(9)
	v_mfma_f32_16x16x32_bf16 v[32:35], v[72:75], v[96:99], v[32:35]
	s_waitcnt lgkmcnt(9)
	v_mfma_f32_16x16x32_bf16 v[36:39], v[72:75], v[100:103], v[36:39]
	s_waitcnt lgkmcnt(9)
	v_mfma_f32_16x16x32_bf16 v[40:43], v[72:75], v[104:107], v[40:43]
	s_waitcnt lgkmcnt(9)
	v_mfma_f32_16x16x32_bf16 v[44:47], v[72:75], v[108:111], v[44:47]
	s_waitcnt vmcnt(4) lgkmcnt(0)
	s_barrier
	s_add_u32 m0, s38, 0
	s_nop 0
	global_load_lds_dwordx4 v226, s[98:99]
	s_waitcnt lgkmcnt(8)
	v_mfma_f32_16x16x32_bf16 v[48:51], v[76:79], v[96:99], v[48:51]
	s_add_u32 m0, s38, 4096
	s_nop 0
	global_load_lds_dwordx4 v228, s[98:99]
	s_waitcnt lgkmcnt(8)
	v_mfma_f32_16x16x32_bf16 v[52:55], v[76:79], v[100:103], v[52:55]
	s_add_u32 m0, s38, 8192
	s_nop 0
	global_load_lds_dwordx4 v244, s[98:99]
	s_waitcnt lgkmcnt(8)
	v_mfma_f32_16x16x32_bf16 v[56:59], v[76:79], v[104:107], v[56:59]
	s_add_u32 m0, s38, 12288
	s_nop 0
	global_load_lds_dwordx4 v245, s[98:99]
	s_add_u32 s98, s98, 128
	s_addc_u32 s99, s99, 0
	s_waitcnt lgkmcnt(8)
	v_mfma_f32_16x16x32_bf16 v[60:63], v[76:79], v[108:111], v[60:63]
	s_waitcnt lgkmcnt(6)
	v_mfma_f32_16x16x32_bf16 v[0:3], v[80:83], v[112:115], v[0:3]
	ds_read_b128 v[64:67], v151 offset:16384
	s_waitcnt lgkmcnt(6)
	v_mfma_f32_16x16x32_bf16 v[4:7], v[80:83], v[116:119], v[4:7]
	ds_read_b128 v[96:99], v222 offset:49152
	s_waitcnt lgkmcnt(6)
	v_mfma_f32_16x16x32_bf16 v[8:11], v[80:83], v[120:123], v[8:11]
	ds_read_b128 v[100:103], v222 offset:51200
	s_waitcnt lgkmcnt(6)
	v_mfma_f32_16x16x32_bf16 v[12:15], v[80:83], v[124:127], v[12:15]
	ds_read_b128 v[104:107], v222 offset:53248
	s_waitcnt lgkmcnt(6)
	v_mfma_f32_16x16x32_bf16 v[16:19], v[84:87], v[112:115], v[16:19]
	ds_read_b128 v[108:111], v222 offset:55296
	s_waitcnt lgkmcnt(7)
	v_mfma_f32_16x16x32_bf16 v[20:23], v[84:87], v[116:119], v[20:23]
	ds_read_b128 v[68:71], v151 offset:18432
	s_waitcnt lgkmcnt(8)
	v_mfma_f32_16x16x32_bf16 v[24:27], v[84:87], v[120:123], v[24:27]
	ds_read_b128 v[72:75], v151 offset:20480
	s_waitcnt lgkmcnt(9)
	v_mfma_f32_16x16x32_bf16 v[28:31], v[84:87], v[124:127], v[28:31]
	ds_read_b128 v[76:79], v151 offset:22528
	s_waitcnt lgkmcnt(9)
	v_mfma_f32_16x16x32_bf16 v[32:35], v[88:91], v[112:115], v[32:35]
	s_waitcnt lgkmcnt(9)
	v_mfma_f32_16x16x32_bf16 v[36:39], v[88:91], v[116:119], v[36:39]
	s_waitcnt lgkmcnt(9)
	v_mfma_f32_16x16x32_bf16 v[40:43], v[88:91], v[120:123], v[40:43]
	s_waitcnt lgkmcnt(9)
	v_mfma_f32_16x16x32_bf16 v[44:47], v[88:91], v[124:127], v[44:47]
	s_waitcnt lgkmcnt(8)
	v_mfma_f32_16x16x32_bf16 v[48:51], v[92:95], v[112:115], v[48:51]
	s_waitcnt lgkmcnt(8)
	v_mfma_f32_16x16x32_bf16 v[52:55], v[92:95], v[116:119], v[52:55]
	s_waitcnt lgkmcnt(8)
	v_mfma_f32_16x16x32_bf16 v[56:59], v[92:95], v[120:123], v[56:59]
	s_waitcnt lgkmcnt(8)
	v_mfma_f32_16x16x32_bf16 v[60:63], v[92:95], v[124:127], v[60:63]
	s_waitcnt lgkmcnt(6)
	v_mfma_f32_16x16x32_bf16 v[160:163], v[64:67], v[96:99], v[160:163]
	ds_read_b128 v[80:83], v220 offset:16384
	s_waitcnt lgkmcnt(6)
	v_mfma_f32_16x16x32_bf16 v[164:167], v[64:67], v[100:103], v[164:167]
	ds_read_b128 v[112:115], v224 offset:49152
	s_waitcnt lgkmcnt(6)
	v_mfma_f32_16x16x32_bf16 v[168:171], v[64:67], v[104:107], v[168:171]
	ds_read_b128 v[116:119], v224 offset:51200
	s_waitcnt lgkmcnt(6)
	v_mfma_f32_16x16x32_bf16 v[172:175], v[64:67], v[108:111], v[172:175]
	ds_read_b128 v[120:123], v224 offset:53248
	s_waitcnt lgkmcnt(6)
	v_mfma_f32_16x16x32_bf16 v[176:179], v[68:71], v[96:99], v[176:179]
	ds_read_b128 v[124:127], v224 offset:55296
	s_waitcnt lgkmcnt(7)
	v_mfma_f32_16x16x32_bf16 v[180:183], v[68:71], v[100:103], v[180:183]
	ds_read_b128 v[84:87], v220 offset:18432
	s_waitcnt lgkmcnt(8)
	v_mfma_f32_16x16x32_bf16 v[184:187], v[68:71], v[104:107], v[184:187]
	ds_read_b128 v[88:91], v220 offset:20480
	s_waitcnt lgkmcnt(9)
	v_mfma_f32_16x16x32_bf16 v[188:191], v[68:71], v[108:111], v[188:191]
	ds_read_b128 v[92:95], v220 offset:22528
	s_waitcnt lgkmcnt(9)
	v_mfma_f32_16x16x32_bf16 v[192:195], v[72:75], v[96:99], v[192:195]
	s_waitcnt lgkmcnt(9)
	v_mfma_f32_16x16x32_bf16 v[196:199], v[72:75], v[100:103], v[196:199]
	s_waitcnt lgkmcnt(9)
	v_mfma_f32_16x16x32_bf16 v[200:203], v[72:75], v[104:107], v[200:203]
	s_waitcnt lgkmcnt(9)
	v_mfma_f32_16x16x32_bf16 v[204:207], v[72:75], v[108:111], v[204:207]
	s_waitcnt vmcnt(0) lgkmcnt(0)
	s_barrier
	s_add_u32 m0, s38, 16384
	s_nop 0
	global_load_lds_dwordx4 v226, s[100:101]
	s_waitcnt lgkmcnt(8)
	v_mfma_f32_16x16x32_bf16 v[208:211], v[76:79], v[96:99], v[208:211]
	s_add_u32 m0, s38, 20480
	s_nop 0
	global_load_lds_dwordx4 v228, s[100:101]
	s_waitcnt lgkmcnt(8)
	v_mfma_f32_16x16x32_bf16 v[212:215], v[76:79], v[100:103], v[212:215]
	s_add_u32 m0, s38, 24576
	s_nop 0
	global_load_lds_dwordx4 v244, s[100:101]
	s_waitcnt lgkmcnt(8)
	v_mfma_f32_16x16x32_bf16 v[216:219], v[76:79], v[104:107], v[216:219]
	s_add_u32 m0, s38, 28672
	s_nop 0
	global_load_lds_dwordx4 v245, s[100:101]
	s_add_u32 s100, s100, 128
	s_addc_u32 s101, s101, 0
	s_waitcnt lgkmcnt(8)
	v_mfma_f32_16x16x32_bf16 v[230:233], v[76:79], v[108:111], v[230:233]
	s_add_u32 m0, s38, 49152
	s_nop 0
	global_load_lds_dwordx4 v226, s[4:5]
	s_waitcnt lgkmcnt(6)
	v_mfma_f32_16x16x32_bf16 v[160:163], v[80:83], v[112:115], v[160:163]
	ds_read_b128 v[64:67], v151 offset:0
	s_add_u32 m0, s38, 53248
	s_nop 0
	global_load_lds_dwordx4 v228, s[4:5]
	s_waitcnt lgkmcnt(6)
	v_mfma_f32_16x16x32_bf16 v[164:167], v[80:83], v[116:119], v[164:167]
	ds_read_b128 v[96:99], v222 offset:32768
	s_add_u32 m0, s38, 57344
	s_nop 0
	global_load_lds_dwordx4 v244, s[4:5]
	s_waitcnt lgkmcnt(6)
	v_mfma_f32_16x16x32_bf16 v[168:171], v[80:83], v[120:123], v[168:171]
	ds_read_b128 v[100:103], v222 offset:34816
	s_add_u32 m0, s38, 61440
	s_nop 0
	global_load_lds_dwordx4 v245, s[4:5]
	s_add_u32 s4, s4, 128
	s_addc_u32 s5, s5, 0
	s_waitcnt lgkmcnt(6)
	v_mfma_f32_16x16x32_bf16 v[172:175], v[80:83], v[124:127], v[172:175]
	ds_read_b128 v[104:107], v222 offset:36864
	s_waitcnt lgkmcnt(6)
	v_mfma_f32_16x16x32_bf16 v[176:179], v[84:87], v[112:115], v[176:179]
	ds_read_b128 v[108:111], v222 offset:38912
	s_waitcnt lgkmcnt(7)
	v_mfma_f32_16x16x32_bf16 v[180:183], v[84:87], v[116:119], v[180:183]
	ds_read_b128 v[68:71], v151 offset:2048
	s_waitcnt lgkmcnt(8)
	v_mfma_f32_16x16x32_bf16 v[184:187], v[84:87], v[120:123], v[184:187]
	ds_read_b128 v[72:75], v151 offset:4096
	s_waitcnt lgkmcnt(9)
	v_mfma_f32_16x16x32_bf16 v[188:191], v[84:87], v[124:127], v[188:191]
	ds_read_b128 v[76:79], v151 offset:6144
	s_waitcnt lgkmcnt(9)
	v_mfma_f32_16x16x32_bf16 v[192:195], v[88:91], v[112:115], v[192:195]
	s_waitcnt lgkmcnt(9)
	v_mfma_f32_16x16x32_bf16 v[196:199], v[88:91], v[116:119], v[196:199]
	s_waitcnt lgkmcnt(9)
	v_mfma_f32_16x16x32_bf16 v[200:203], v[88:91], v[120:123], v[200:203]
	s_waitcnt lgkmcnt(9)
	v_mfma_f32_16x16x32_bf16 v[204:207], v[88:91], v[124:127], v[204:207]
	s_waitcnt lgkmcnt(8)
	v_mfma_f32_16x16x32_bf16 v[208:211], v[92:95], v[112:115], v[208:211]
	s_waitcnt lgkmcnt(8)
	v_mfma_f32_16x16x32_bf16 v[212:215], v[92:95], v[116:119], v[212:215]
	s_waitcnt lgkmcnt(8)
	v_mfma_f32_16x16x32_bf16 v[216:219], v[92:95], v[120:123], v[216:219]
	s_waitcnt lgkmcnt(8)
	v_mfma_f32_16x16x32_bf16 v[230:233], v[92:95], v[124:127], v[230:233]
	s_waitcnt lgkmcnt(6)
	v_mfma_f32_16x16x32_bf16 v[0:3], v[64:67], v[96:99], v[0:3]
	ds_read_b128 v[80:83], v220 offset:0
	s_waitcnt lgkmcnt(6)
	v_mfma_f32_16x16x32_bf16 v[4:7], v[64:67], v[100:103], v[4:7]
	ds_read_b128 v[112:115], v224 offset:32768
	s_waitcnt lgkmcnt(6)
	v_mfma_f32_16x16x32_bf16 v[8:11], v[64:67], v[104:107], v[8:11]
	ds_read_b128 v[116:119], v224 offset:34816
	s_waitcnt lgkmcnt(6)
	v_mfma_f32_16x16x32_bf16 v[12:15], v[64:67], v[108:111], v[12:15]
	ds_read_b128 v[120:123], v224 offset:36864
	s_waitcnt lgkmcnt(6)
	v_mfma_f32_16x16x32_bf16 v[16:19], v[68:71], v[96:99], v[16:19]
	ds_read_b128 v[124:127], v224 offset:38912
	s_waitcnt lgkmcnt(7)
	v_mfma_f32_16x16x32_bf16 v[20:23], v[68:71], v[100:103], v[20:23]
	ds_read_b128 v[84:87], v220 offset:2048
	s_waitcnt lgkmcnt(8)
	v_mfma_f32_16x16x32_bf16 v[24:27], v[68:71], v[104:107], v[24:27]
	ds_read_b128 v[88:91], v220 offset:4096
	s_waitcnt lgkmcnt(9)
	v_mfma_f32_16x16x32_bf16 v[28:31], v[68:71], v[108:111], v[28:31]
	ds_read_b128 v[92:95], v220 offset:6144
	s_waitcnt lgkmcnt(9)
	v_mfma_f32_16x16x32_bf16 v[32:35], v[72:75], v[96:99], v[32:35]
	s_waitcnt lgkmcnt(9)
	v_mfma_f32_16x16x32_bf16 v[36:39], v[72:75], v[100:103], v[36:39]
	s_waitcnt lgkmcnt(9)
	v_mfma_f32_16x16x32_bf16 v[40:43], v[72:75], v[104:107], v[40:43]
	s_waitcnt lgkmcnt(9)
	v_mfma_f32_16x16x32_bf16 v[44:47], v[72:75], v[108:111], v[44:47]
	s_waitcnt vmcnt(4) lgkmcnt(0)
	s_barrier
	s_add_u32 m0, s38, 0
	s_nop 0
	global_load_lds_dwordx4 v226, s[98:99]
	s_waitcnt lgkmcnt(8)
	v_mfma_f32_16x16x32_bf16 v[48:51], v[76:79], v[96:99], v[48:51]
	s_add_u32 m0, s38, 4096
	s_nop 0
	global_load_lds_dwordx4 v228, s[98:99]
	s_waitcnt lgkmcnt(8)
	v_mfma_f32_16x16x32_bf16 v[52:55], v[76:79], v[100:103], v[52:55]
	s_add_u32 m0, s38, 8192
	s_nop 0
	global_load_lds_dwordx4 v244, s[98:99]
	s_waitcnt lgkmcnt(8)
	v_mfma_f32_16x16x32_bf16 v[56:59], v[76:79], v[104:107], v[56:59]
	s_add_u32 m0, s38, 12288
	s_nop 0
	global_load_lds_dwordx4 v245, s[98:99]
	s_add_u32 s98, s98, 128
	s_addc_u32 s99, s99, 0
	s_waitcnt lgkmcnt(8)
	v_mfma_f32_16x16x32_bf16 v[60:63], v[76:79], v[108:111], v[60:63]
	s_waitcnt lgkmcnt(6)
	v_mfma_f32_16x16x32_bf16 v[0:3], v[80:83], v[112:115], v[0:3]
	ds_read_b128 v[64:67], v151 offset:16384
	s_waitcnt lgkmcnt(6)
	v_mfma_f32_16x16x32_bf16 v[4:7], v[80:83], v[116:119], v[4:7]
	ds_read_b128 v[96:99], v222 offset:32768
	s_waitcnt lgkmcnt(6)
	v_mfma_f32_16x16x32_bf16 v[8:11], v[80:83], v[120:123], v[8:11]
	ds_read_b128 v[100:103], v222 offset:34816
	s_waitcnt lgkmcnt(6)
	v_mfma_f32_16x16x32_bf16 v[12:15], v[80:83], v[124:127], v[12:15]
	ds_read_b128 v[104:107], v222 offset:36864
	s_waitcnt lgkmcnt(6)
	v_mfma_f32_16x16x32_bf16 v[16:19], v[84:87], v[112:115], v[16:19]
	ds_read_b128 v[108:111], v222 offset:38912
	s_waitcnt lgkmcnt(7)
	v_mfma_f32_16x16x32_bf16 v[20:23], v[84:87], v[116:119], v[20:23]
	ds_read_b128 v[68:71], v151 offset:18432
	s_waitcnt lgkmcnt(8)
	v_mfma_f32_16x16x32_bf16 v[24:27], v[84:87], v[120:123], v[24:27]
	ds_read_b128 v[72:75], v151 offset:20480
	s_waitcnt lgkmcnt(9)
	v_mfma_f32_16x16x32_bf16 v[28:31], v[84:87], v[124:127], v[28:31]
	ds_read_b128 v[76:79], v151 offset:22528
	s_waitcnt lgkmcnt(9)
	v_mfma_f32_16x16x32_bf16 v[32:35], v[88:91], v[112:115], v[32:35]
	s_waitcnt lgkmcnt(9)
	v_mfma_f32_16x16x32_bf16 v[36:39], v[88:91], v[116:119], v[36:39]
	s_waitcnt lgkmcnt(9)
	v_mfma_f32_16x16x32_bf16 v[40:43], v[88:91], v[120:123], v[40:43]
	s_waitcnt lgkmcnt(9)
	v_mfma_f32_16x16x32_bf16 v[44:47], v[88:91], v[124:127], v[44:47]
	s_waitcnt lgkmcnt(8)
	v_mfma_f32_16x16x32_bf16 v[48:51], v[92:95], v[112:115], v[48:51]
	s_waitcnt lgkmcnt(8)
	v_mfma_f32_16x16x32_bf16 v[52:55], v[92:95], v[116:119], v[52:55]
	s_waitcnt lgkmcnt(8)
	v_mfma_f32_16x16x32_bf16 v[56:59], v[92:95], v[120:123], v[56:59]
	s_waitcnt lgkmcnt(8)
	v_mfma_f32_16x16x32_bf16 v[60:63], v[92:95], v[124:127], v[60:63]
	s_waitcnt lgkmcnt(6)
	v_mfma_f32_16x16x32_bf16 v[160:163], v[64:67], v[96:99], v[160:163]
	ds_read_b128 v[80:83], v220 offset:16384
	s_waitcnt lgkmcnt(6)
	v_mfma_f32_16x16x32_bf16 v[164:167], v[64:67], v[100:103], v[164:167]
	ds_read_b128 v[112:115], v224 offset:32768
	s_waitcnt lgkmcnt(6)
	v_mfma_f32_16x16x32_bf16 v[168:171], v[64:67], v[104:107], v[168:171]
	ds_read_b128 v[116:119], v224 offset:34816
	s_waitcnt lgkmcnt(6)
	v_mfma_f32_16x16x32_bf16 v[172:175], v[64:67], v[108:111], v[172:175]
	ds_read_b128 v[120:123], v224 offset:36864
	s_waitcnt lgkmcnt(6)
	v_mfma_f32_16x16x32_bf16 v[176:179], v[68:71], v[96:99], v[176:179]
	ds_read_b128 v[124:127], v224 offset:38912
	s_waitcnt lgkmcnt(7)
	v_mfma_f32_16x16x32_bf16 v[180:183], v[68:71], v[100:103], v[180:183]
	ds_read_b128 v[84:87], v220 offset:18432
	s_waitcnt lgkmcnt(8)
	v_mfma_f32_16x16x32_bf16 v[184:187], v[68:71], v[104:107], v[184:187]
	ds_read_b128 v[88:91], v220 offset:20480
	s_waitcnt lgkmcnt(9)
	v_mfma_f32_16x16x32_bf16 v[188:191], v[68:71], v[108:111], v[188:191]
	ds_read_b128 v[92:95], v220 offset:22528
	s_waitcnt lgkmcnt(9)
	v_mfma_f32_16x16x32_bf16 v[192:195], v[72:75], v[96:99], v[192:195]
	s_waitcnt lgkmcnt(9)
	v_mfma_f32_16x16x32_bf16 v[196:199], v[72:75], v[100:103], v[196:199]
	s_waitcnt lgkmcnt(9)
	v_mfma_f32_16x16x32_bf16 v[200:203], v[72:75], v[104:107], v[200:203]
	s_waitcnt lgkmcnt(9)
	v_mfma_f32_16x16x32_bf16 v[204:207], v[72:75], v[108:111], v[204:207]
	s_waitcnt vmcnt(0) lgkmcnt(0)
	s_barrier
	s_add_u32 m0, s38, 16384
	s_nop 0
	global_load_lds_dwordx4 v226, s[100:101]
	s_waitcnt lgkmcnt(8)
	v_mfma_f32_16x16x32_bf16 v[208:211], v[76:79], v[96:99], v[208:211]
	s_add_u32 m0, s38, 20480
	s_nop 0
	global_load_lds_dwordx4 v228, s[100:101]
	s_waitcnt lgkmcnt(8)
	v_mfma_f32_16x16x32_bf16 v[212:215], v[76:79], v[100:103], v[212:215]
	s_add_u32 m0, s38, 24576
	s_nop 0
	global_load_lds_dwordx4 v244, s[100:101]
	s_waitcnt lgkmcnt(8)
	v_mfma_f32_16x16x32_bf16 v[216:219], v[76:79], v[104:107], v[216:219]
	s_add_u32 m0, s38, 28672
	s_nop 0
	global_load_lds_dwordx4 v245, s[100:101]
	s_add_u32 s100, s100, 128
	s_addc_u32 s101, s101, 0
	s_waitcnt lgkmcnt(8)
	v_mfma_f32_16x16x32_bf16 v[230:233], v[76:79], v[108:111], v[230:233]
	s_add_u32 m0, s38, 32768
	s_nop 0
	global_load_lds_dwordx4 v226, s[4:5]
	s_waitcnt lgkmcnt(6)
	v_mfma_f32_16x16x32_bf16 v[160:163], v[80:83], v[112:115], v[160:163]
	ds_read_b128 v[64:67], v151 offset:0
	s_add_u32 m0, s38, 36864
	s_nop 0
	global_load_lds_dwordx4 v228, s[4:5]
	s_waitcnt lgkmcnt(6)
	v_mfma_f32_16x16x32_bf16 v[164:167], v[80:83], v[116:119], v[164:167]
	ds_read_b128 v[96:99], v222 offset:49152
	s_add_u32 m0, s38, 40960
	s_nop 0
	global_load_lds_dwordx4 v244, s[4:5]
	s_waitcnt lgkmcnt(6)
	v_mfma_f32_16x16x32_bf16 v[168:171], v[80:83], v[120:123], v[168:171]
	ds_read_b128 v[100:103], v222 offset:51200
	s_add_u32 m0, s38, 45056
	s_nop 0
	global_load_lds_dwordx4 v245, s[4:5]
	s_add_u32 s4, s4, 128
	s_addc_u32 s5, s5, 0
	s_waitcnt lgkmcnt(6)
	v_mfma_f32_16x16x32_bf16 v[172:175], v[80:83], v[124:127], v[172:175]
	ds_read_b128 v[104:107], v222 offset:53248
	s_waitcnt lgkmcnt(6)
	v_mfma_f32_16x16x32_bf16 v[176:179], v[84:87], v[112:115], v[176:179]
	ds_read_b128 v[108:111], v222 offset:55296
	s_waitcnt lgkmcnt(7)
	v_mfma_f32_16x16x32_bf16 v[180:183], v[84:87], v[116:119], v[180:183]
	ds_read_b128 v[68:71], v151 offset:2048
	s_waitcnt lgkmcnt(8)
	v_mfma_f32_16x16x32_bf16 v[184:187], v[84:87], v[120:123], v[184:187]
	ds_read_b128 v[72:75], v151 offset:4096
	s_waitcnt lgkmcnt(9)
	v_mfma_f32_16x16x32_bf16 v[188:191], v[84:87], v[124:127], v[188:191]
	ds_read_b128 v[76:79], v151 offset:6144
	s_waitcnt lgkmcnt(9)
	v_mfma_f32_16x16x32_bf16 v[192:195], v[88:91], v[112:115], v[192:195]
	s_waitcnt lgkmcnt(9)
	v_mfma_f32_16x16x32_bf16 v[196:199], v[88:91], v[116:119], v[196:199]
	s_waitcnt lgkmcnt(9)
	v_mfma_f32_16x16x32_bf16 v[200:203], v[88:91], v[120:123], v[200:203]
	s_waitcnt lgkmcnt(9)
	v_mfma_f32_16x16x32_bf16 v[204:207], v[88:91], v[124:127], v[204:207]
	s_waitcnt lgkmcnt(8)
	v_mfma_f32_16x16x32_bf16 v[208:211], v[92:95], v[112:115], v[208:211]
	s_waitcnt lgkmcnt(8)
	v_mfma_f32_16x16x32_bf16 v[212:215], v[92:95], v[116:119], v[212:215]
	s_waitcnt lgkmcnt(8)
	v_mfma_f32_16x16x32_bf16 v[216:219], v[92:95], v[120:123], v[216:219]
	s_waitcnt lgkmcnt(8)
	v_mfma_f32_16x16x32_bf16 v[230:233], v[92:95], v[124:127], v[230:233]
	s_waitcnt lgkmcnt(6)
	v_mfma_f32_16x16x32_bf16 v[0:3], v[64:67], v[96:99], v[0:3]
	ds_read_b128 v[80:83], v220 offset:0
	s_waitcnt lgkmcnt(6)
	v_mfma_f32_16x16x32_bf16 v[4:7], v[64:67], v[100:103], v[4:7]
	ds_read_b128 v[112:115], v224 offset:49152
	s_waitcnt lgkmcnt(6)
	v_mfma_f32_16x16x32_bf16 v[8:11], v[64:67], v[104:107], v[8:11]
	ds_read_b128 v[116:119], v224 offset:51200
	s_waitcnt lgkmcnt(6)
	v_mfma_f32_16x16x32_bf16 v[12:15], v[64:67], v[108:111], v[12:15]
	ds_read_b128 v[120:123], v224 offset:53248
	s_waitcnt lgkmcnt(6)
	v_mfma_f32_16x16x32_bf16 v[16:19], v[68:71], v[96:99], v[16:19]
	ds_read_b128 v[124:127], v224 offset:55296
	s_waitcnt lgkmcnt(7)
	v_mfma_f32_16x16x32_bf16 v[20:23], v[68:71], v[100:103], v[20:23]
	ds_read_b128 v[84:87], v220 offset:2048
	s_waitcnt lgkmcnt(8)
	v_mfma_f32_16x16x32_bf16 v[24:27], v[68:71], v[104:107], v[24:27]
	ds_read_b128 v[88:91], v220 offset:4096
	s_waitcnt lgkmcnt(9)
	v_mfma_f32_16x16x32_bf16 v[28:31], v[68:71], v[108:111], v[28:31]
	ds_read_b128 v[92:95], v220 offset:6144
	s_waitcnt lgkmcnt(9)
	v_mfma_f32_16x16x32_bf16 v[32:35], v[72:75], v[96:99], v[32:35]
	s_waitcnt lgkmcnt(9)
	v_mfma_f32_16x16x32_bf16 v[36:39], v[72:75], v[100:103], v[36:39]
	s_waitcnt lgkmcnt(9)
	v_mfma_f32_16x16x32_bf16 v[40:43], v[72:75], v[104:107], v[40:43]
	s_waitcnt lgkmcnt(9)
	v_mfma_f32_16x16x32_bf16 v[44:47], v[72:75], v[108:111], v[44:47]
	s_waitcnt vmcnt(4) lgkmcnt(0)
	s_barrier
	s_add_u32 m0, s38, 0
	s_nop 0
	global_load_lds_dwordx4 v226, s[98:99]
	s_waitcnt lgkmcnt(8)
	v_mfma_f32_16x16x32_bf16 v[48:51], v[76:79], v[96:99], v[48:51]
	s_add_u32 m0, s38, 4096
	s_nop 0
	global_load_lds_dwordx4 v228, s[98:99]
	s_waitcnt lgkmcnt(8)
	v_mfma_f32_16x16x32_bf16 v[52:55], v[76:79], v[100:103], v[52:55]
	s_add_u32 m0, s38, 8192
	s_nop 0
	global_load_lds_dwordx4 v244, s[98:99]
	s_waitcnt lgkmcnt(8)
	v_mfma_f32_16x16x32_bf16 v[56:59], v[76:79], v[104:107], v[56:59]
	s_add_u32 m0, s38, 12288
	s_nop 0
	global_load_lds_dwordx4 v245, s[98:99]
	s_add_u32 s98, s98, 128
	s_addc_u32 s99, s99, 0
	s_waitcnt lgkmcnt(8)
	v_mfma_f32_16x16x32_bf16 v[60:63], v[76:79], v[108:111], v[60:63]
	s_waitcnt lgkmcnt(6)
	v_mfma_f32_16x16x32_bf16 v[0:3], v[80:83], v[112:115], v[0:3]
	ds_read_b128 v[64:67], v151 offset:16384
	s_waitcnt lgkmcnt(6)
	v_mfma_f32_16x16x32_bf16 v[4:7], v[80:83], v[116:119], v[4:7]
	ds_read_b128 v[96:99], v222 offset:49152
	s_waitcnt lgkmcnt(6)
	v_mfma_f32_16x16x32_bf16 v[8:11], v[80:83], v[120:123], v[8:11]
	ds_read_b128 v[100:103], v222 offset:51200
	s_waitcnt lgkmcnt(6)
	v_mfma_f32_16x16x32_bf16 v[12:15], v[80:83], v[124:127], v[12:15]
	ds_read_b128 v[104:107], v222 offset:53248
	s_waitcnt lgkmcnt(6)
	v_mfma_f32_16x16x32_bf16 v[16:19], v[84:87], v[112:115], v[16:19]
	ds_read_b128 v[108:111], v222 offset:55296
	s_waitcnt lgkmcnt(7)
	v_mfma_f32_16x16x32_bf16 v[20:23], v[84:87], v[116:119], v[20:23]
	ds_read_b128 v[68:71], v151 offset:18432
	s_waitcnt lgkmcnt(8)
	v_mfma_f32_16x16x32_bf16 v[24:27], v[84:87], v[120:123], v[24:27]
	ds_read_b128 v[72:75], v151 offset:20480
	s_waitcnt lgkmcnt(9)
	v_mfma_f32_16x16x32_bf16 v[28:31], v[84:87], v[124:127], v[28:31]
	ds_read_b128 v[76:79], v151 offset:22528
	s_waitcnt lgkmcnt(9)
	v_mfma_f32_16x16x32_bf16 v[32:35], v[88:91], v[112:115], v[32:35]
	s_waitcnt lgkmcnt(9)
	v_mfma_f32_16x16x32_bf16 v[36:39], v[88:91], v[116:119], v[36:39]
	s_waitcnt lgkmcnt(9)
	v_mfma_f32_16x16x32_bf16 v[40:43], v[88:91], v[120:123], v[40:43]
	s_waitcnt lgkmcnt(9)
	v_mfma_f32_16x16x32_bf16 v[44:47], v[88:91], v[124:127], v[44:47]
	s_waitcnt lgkmcnt(8)
	v_mfma_f32_16x16x32_bf16 v[48:51], v[92:95], v[112:115], v[48:51]
	s_waitcnt lgkmcnt(8)
	v_mfma_f32_16x16x32_bf16 v[52:55], v[92:95], v[116:119], v[52:55]
	s_waitcnt lgkmcnt(8)
	v_mfma_f32_16x16x32_bf16 v[56:59], v[92:95], v[120:123], v[56:59]
	s_waitcnt lgkmcnt(8)
	v_mfma_f32_16x16x32_bf16 v[60:63], v[92:95], v[124:127], v[60:63]
	s_waitcnt lgkmcnt(6)
	v_mfma_f32_16x16x32_bf16 v[160:163], v[64:67], v[96:99], v[160:163]
	ds_read_b128 v[80:83], v220 offset:16384
	s_waitcnt lgkmcnt(6)
	v_mfma_f32_16x16x32_bf16 v[164:167], v[64:67], v[100:103], v[164:167]
	ds_read_b128 v[112:115], v224 offset:49152
	s_waitcnt lgkmcnt(6)
	v_mfma_f32_16x16x32_bf16 v[168:171], v[64:67], v[104:107], v[168:171]
	ds_read_b128 v[116:119], v224 offset:51200
	s_waitcnt lgkmcnt(6)
	v_mfma_f32_16x16x32_bf16 v[172:175], v[64:67], v[108:111], v[172:175]
	ds_read_b128 v[120:123], v224 offset:53248
	s_waitcnt lgkmcnt(6)
	v_mfma_f32_16x16x32_bf16 v[176:179], v[68:71], v[96:99], v[176:179]
	ds_read_b128 v[124:127], v224 offset:55296
	s_waitcnt lgkmcnt(7)
	v_mfma_f32_16x16x32_bf16 v[180:183], v[68:71], v[100:103], v[180:183]
	ds_read_b128 v[84:87], v220 offset:18432
	s_waitcnt lgkmcnt(8)
	v_mfma_f32_16x16x32_bf16 v[184:187], v[68:71], v[104:107], v[184:187]
	ds_read_b128 v[88:91], v220 offset:20480
	s_waitcnt lgkmcnt(9)
	v_mfma_f32_16x16x32_bf16 v[188:191], v[68:71], v[108:111], v[188:191]
	ds_read_b128 v[92:95], v220 offset:22528
	s_waitcnt lgkmcnt(9)
	v_mfma_f32_16x16x32_bf16 v[192:195], v[72:75], v[96:99], v[192:195]
	s_waitcnt lgkmcnt(9)
	v_mfma_f32_16x16x32_bf16 v[196:199], v[72:75], v[100:103], v[196:199]
	s_waitcnt lgkmcnt(9)
	v_mfma_f32_16x16x32_bf16 v[200:203], v[72:75], v[104:107], v[200:203]
	s_waitcnt lgkmcnt(9)
	v_mfma_f32_16x16x32_bf16 v[204:207], v[72:75], v[108:111], v[204:207]
	s_waitcnt vmcnt(0) lgkmcnt(0)
	s_barrier
	s_add_u32 m0, s38, 16384
	s_nop 0
	global_load_lds_dwordx4 v226, s[100:101]
	s_waitcnt lgkmcnt(8)
	v_mfma_f32_16x16x32_bf16 v[208:211], v[76:79], v[96:99], v[208:211]
	s_add_u32 m0, s38, 20480
	s_nop 0
	global_load_lds_dwordx4 v228, s[100:101]
	s_waitcnt lgkmcnt(8)
	v_mfma_f32_16x16x32_bf16 v[212:215], v[76:79], v[100:103], v[212:215]
	s_add_u32 m0, s38, 24576
	s_nop 0
	global_load_lds_dwordx4 v244, s[100:101]
	s_waitcnt lgkmcnt(8)
	v_mfma_f32_16x16x32_bf16 v[216:219], v[76:79], v[104:107], v[216:219]
	s_add_u32 m0, s38, 28672
	s_nop 0
	global_load_lds_dwordx4 v245, s[100:101]
	s_add_u32 s100, s100, 128
	s_addc_u32 s101, s101, 0
	s_waitcnt lgkmcnt(8)
	v_mfma_f32_16x16x32_bf16 v[230:233], v[76:79], v[108:111], v[230:233]
	s_add_u32 m0, s38, 49152
	s_nop 0
	global_load_lds_dwordx4 v226, s[4:5]
	s_waitcnt lgkmcnt(6)
	v_mfma_f32_16x16x32_bf16 v[160:163], v[80:83], v[112:115], v[160:163]
	ds_read_b128 v[64:67], v151 offset:0
	s_add_u32 m0, s38, 53248
	s_nop 0
	global_load_lds_dwordx4 v228, s[4:5]
	s_waitcnt lgkmcnt(6)
	v_mfma_f32_16x16x32_bf16 v[164:167], v[80:83], v[116:119], v[164:167]
	ds_read_b128 v[96:99], v222 offset:32768
	s_add_u32 m0, s38, 57344
	s_nop 0
	global_load_lds_dwordx4 v244, s[4:5]
	s_waitcnt lgkmcnt(6)
	v_mfma_f32_16x16x32_bf16 v[168:171], v[80:83], v[120:123], v[168:171]
	ds_read_b128 v[100:103], v222 offset:34816
	s_add_u32 m0, s38, 61440
	s_nop 0
	global_load_lds_dwordx4 v245, s[4:5]
	s_add_u32 s4, s4, 128
	s_addc_u32 s5, s5, 0
	s_waitcnt lgkmcnt(6)
	v_mfma_f32_16x16x32_bf16 v[172:175], v[80:83], v[124:127], v[172:175]
	ds_read_b128 v[104:107], v222 offset:36864
	s_waitcnt lgkmcnt(6)
	v_mfma_f32_16x16x32_bf16 v[176:179], v[84:87], v[112:115], v[176:179]
	ds_read_b128 v[108:111], v222 offset:38912
	s_waitcnt lgkmcnt(7)
	v_mfma_f32_16x16x32_bf16 v[180:183], v[84:87], v[116:119], v[180:183]
	ds_read_b128 v[68:71], v151 offset:2048
	s_waitcnt lgkmcnt(8)
	v_mfma_f32_16x16x32_bf16 v[184:187], v[84:87], v[120:123], v[184:187]
	ds_read_b128 v[72:75], v151 offset:4096
	s_waitcnt lgkmcnt(9)
	v_mfma_f32_16x16x32_bf16 v[188:191], v[84:87], v[124:127], v[188:191]
	ds_read_b128 v[76:79], v151 offset:6144
	s_waitcnt lgkmcnt(9)
	v_mfma_f32_16x16x32_bf16 v[192:195], v[88:91], v[112:115], v[192:195]
	s_waitcnt lgkmcnt(9)
	v_mfma_f32_16x16x32_bf16 v[196:199], v[88:91], v[116:119], v[196:199]
	s_waitcnt lgkmcnt(9)
	v_mfma_f32_16x16x32_bf16 v[200:203], v[88:91], v[120:123], v[200:203]
	s_waitcnt lgkmcnt(9)
	v_mfma_f32_16x16x32_bf16 v[204:207], v[88:91], v[124:127], v[204:207]
	s_waitcnt lgkmcnt(8)
	v_mfma_f32_16x16x32_bf16 v[208:211], v[92:95], v[112:115], v[208:211]
	s_waitcnt lgkmcnt(8)
	v_mfma_f32_16x16x32_bf16 v[212:215], v[92:95], v[116:119], v[212:215]
	s_waitcnt lgkmcnt(8)
	v_mfma_f32_16x16x32_bf16 v[216:219], v[92:95], v[120:123], v[216:219]
	s_waitcnt lgkmcnt(8)
	v_mfma_f32_16x16x32_bf16 v[230:233], v[92:95], v[124:127], v[230:233]
	s_waitcnt lgkmcnt(6)
	v_mfma_f32_16x16x32_bf16 v[0:3], v[64:67], v[96:99], v[0:3]
	ds_read_b128 v[80:83], v220 offset:0
	s_waitcnt lgkmcnt(6)
	v_mfma_f32_16x16x32_bf16 v[4:7], v[64:67], v[100:103], v[4:7]
	ds_read_b128 v[112:115], v224 offset:32768
	s_waitcnt lgkmcnt(6)
	v_mfma_f32_16x16x32_bf16 v[8:11], v[64:67], v[104:107], v[8:11]
	ds_read_b128 v[116:119], v224 offset:34816
	s_waitcnt lgkmcnt(6)
	v_mfma_f32_16x16x32_bf16 v[12:15], v[64:67], v[108:111], v[12:15]
	ds_read_b128 v[120:123], v224 offset:36864
	s_waitcnt lgkmcnt(6)
	v_mfma_f32_16x16x32_bf16 v[16:19], v[68:71], v[96:99], v[16:19]
	ds_read_b128 v[124:127], v224 offset:38912
	s_waitcnt lgkmcnt(7)
	v_mfma_f32_16x16x32_bf16 v[20:23], v[68:71], v[100:103], v[20:23]
	ds_read_b128 v[84:87], v220 offset:2048
	s_waitcnt lgkmcnt(8)
	v_mfma_f32_16x16x32_bf16 v[24:27], v[68:71], v[104:107], v[24:27]
	ds_read_b128 v[88:91], v220 offset:4096
	s_waitcnt lgkmcnt(9)
	v_mfma_f32_16x16x32_bf16 v[28:31], v[68:71], v[108:111], v[28:31]
	ds_read_b128 v[92:95], v220 offset:6144
	s_waitcnt lgkmcnt(9)
	v_mfma_f32_16x16x32_bf16 v[32:35], v[72:75], v[96:99], v[32:35]
	s_waitcnt lgkmcnt(9)
	v_mfma_f32_16x16x32_bf16 v[36:39], v[72:75], v[100:103], v[36:39]
	s_waitcnt lgkmcnt(9)
	v_mfma_f32_16x16x32_bf16 v[40:43], v[72:75], v[104:107], v[40:43]
	s_waitcnt lgkmcnt(9)
	v_mfma_f32_16x16x32_bf16 v[44:47], v[72:75], v[108:111], v[44:47]
	s_waitcnt vmcnt(4) lgkmcnt(0)
	s_barrier
	s_add_u32 m0, s38, 0
	s_nop 0
	global_load_lds_dwordx4 v226, s[98:99]
	s_waitcnt lgkmcnt(8)
	v_mfma_f32_16x16x32_bf16 v[48:51], v[76:79], v[96:99], v[48:51]
	s_add_u32 m0, s38, 4096
	s_nop 0
	global_load_lds_dwordx4 v228, s[98:99]
	s_waitcnt lgkmcnt(8)
	v_mfma_f32_16x16x32_bf16 v[52:55], v[76:79], v[100:103], v[52:55]
	s_add_u32 m0, s38, 8192
	s_nop 0
	global_load_lds_dwordx4 v244, s[98:99]
	s_waitcnt lgkmcnt(8)
	v_mfma_f32_16x16x32_bf16 v[56:59], v[76:79], v[104:107], v[56:59]
	s_add_u32 m0, s38, 12288
	s_nop 0
	global_load_lds_dwordx4 v245, s[98:99]
	s_add_u32 s98, s98, 128
	s_addc_u32 s99, s99, 0
	s_waitcnt lgkmcnt(8)
	v_mfma_f32_16x16x32_bf16 v[60:63], v[76:79], v[108:111], v[60:63]
	s_waitcnt lgkmcnt(6)
	v_mfma_f32_16x16x32_bf16 v[0:3], v[80:83], v[112:115], v[0:3]
	ds_read_b128 v[64:67], v151 offset:16384
	s_waitcnt lgkmcnt(6)
	v_mfma_f32_16x16x32_bf16 v[4:7], v[80:83], v[116:119], v[4:7]
	ds_read_b128 v[96:99], v222 offset:32768
	s_waitcnt lgkmcnt(6)
	v_mfma_f32_16x16x32_bf16 v[8:11], v[80:83], v[120:123], v[8:11]
	ds_read_b128 v[100:103], v222 offset:34816
	s_waitcnt lgkmcnt(6)
	v_mfma_f32_16x16x32_bf16 v[12:15], v[80:83], v[124:127], v[12:15]
	ds_read_b128 v[104:107], v222 offset:36864
	s_waitcnt lgkmcnt(6)
	v_mfma_f32_16x16x32_bf16 v[16:19], v[84:87], v[112:115], v[16:19]
	ds_read_b128 v[108:111], v222 offset:38912
	s_waitcnt lgkmcnt(7)
	v_mfma_f32_16x16x32_bf16 v[20:23], v[84:87], v[116:119], v[20:23]
	ds_read_b128 v[68:71], v151 offset:18432
	s_waitcnt lgkmcnt(8)
	v_mfma_f32_16x16x32_bf16 v[24:27], v[84:87], v[120:123], v[24:27]
	ds_read_b128 v[72:75], v151 offset:20480
	s_waitcnt lgkmcnt(9)
	v_mfma_f32_16x16x32_bf16 v[28:31], v[84:87], v[124:127], v[28:31]
	ds_read_b128 v[76:79], v151 offset:22528
	s_waitcnt lgkmcnt(9)
	v_mfma_f32_16x16x32_bf16 v[32:35], v[88:91], v[112:115], v[32:35]
	s_waitcnt lgkmcnt(9)
	v_mfma_f32_16x16x32_bf16 v[36:39], v[88:91], v[116:119], v[36:39]
	s_waitcnt lgkmcnt(9)
	v_mfma_f32_16x16x32_bf16 v[40:43], v[88:91], v[120:123], v[40:43]
	s_waitcnt lgkmcnt(9)
	v_mfma_f32_16x16x32_bf16 v[44:47], v[88:91], v[124:127], v[44:47]
	s_waitcnt lgkmcnt(8)
	v_mfma_f32_16x16x32_bf16 v[48:51], v[92:95], v[112:115], v[48:51]
	s_waitcnt lgkmcnt(8)
	v_mfma_f32_16x16x32_bf16 v[52:55], v[92:95], v[116:119], v[52:55]
	s_waitcnt lgkmcnt(8)
	v_mfma_f32_16x16x32_bf16 v[56:59], v[92:95], v[120:123], v[56:59]
	s_waitcnt lgkmcnt(8)
	v_mfma_f32_16x16x32_bf16 v[60:63], v[92:95], v[124:127], v[60:63]
	s_waitcnt lgkmcnt(6)
	v_mfma_f32_16x16x32_bf16 v[160:163], v[64:67], v[96:99], v[160:163]
	ds_read_b128 v[80:83], v220 offset:16384
	s_waitcnt lgkmcnt(6)
	v_mfma_f32_16x16x32_bf16 v[164:167], v[64:67], v[100:103], v[164:167]
	ds_read_b128 v[112:115], v224 offset:32768
	s_waitcnt lgkmcnt(6)
	v_mfma_f32_16x16x32_bf16 v[168:171], v[64:67], v[104:107], v[168:171]
	ds_read_b128 v[116:119], v224 offset:34816
	s_waitcnt lgkmcnt(6)
	v_mfma_f32_16x16x32_bf16 v[172:175], v[64:67], v[108:111], v[172:175]
	ds_read_b128 v[120:123], v224 offset:36864
	s_waitcnt lgkmcnt(6)
	v_mfma_f32_16x16x32_bf16 v[176:179], v[68:71], v[96:99], v[176:179]
	ds_read_b128 v[124:127], v224 offset:38912
	s_waitcnt lgkmcnt(7)
	v_mfma_f32_16x16x32_bf16 v[180:183], v[68:71], v[100:103], v[180:183]
	ds_read_b128 v[84:87], v220 offset:18432
	s_waitcnt lgkmcnt(8)
	v_mfma_f32_16x16x32_bf16 v[184:187], v[68:71], v[104:107], v[184:187]
	ds_read_b128 v[88:91], v220 offset:20480
	s_waitcnt lgkmcnt(9)
	v_mfma_f32_16x16x32_bf16 v[188:191], v[68:71], v[108:111], v[188:191]
	ds_read_b128 v[92:95], v220 offset:22528
	s_waitcnt lgkmcnt(9)
	v_mfma_f32_16x16x32_bf16 v[192:195], v[72:75], v[96:99], v[192:195]
	s_waitcnt lgkmcnt(9)
	v_mfma_f32_16x16x32_bf16 v[196:199], v[72:75], v[100:103], v[196:199]
	s_waitcnt lgkmcnt(9)
	v_mfma_f32_16x16x32_bf16 v[200:203], v[72:75], v[104:107], v[200:203]
	s_waitcnt lgkmcnt(9)
	v_mfma_f32_16x16x32_bf16 v[204:207], v[72:75], v[108:111], v[204:207]
	s_waitcnt vmcnt(0) lgkmcnt(0)
	s_barrier
	s_add_u32 m0, s38, 16384
	s_nop 0
	global_load_lds_dwordx4 v226, s[100:101]
	s_waitcnt lgkmcnt(8)
	v_mfma_f32_16x16x32_bf16 v[208:211], v[76:79], v[96:99], v[208:211]
	s_add_u32 m0, s38, 20480
	s_nop 0
	global_load_lds_dwordx4 v228, s[100:101]
	s_waitcnt lgkmcnt(8)
	v_mfma_f32_16x16x32_bf16 v[212:215], v[76:79], v[100:103], v[212:215]
	s_add_u32 m0, s38, 24576
	s_nop 0
	global_load_lds_dwordx4 v244, s[100:101]
	s_waitcnt lgkmcnt(8)
	v_mfma_f32_16x16x32_bf16 v[216:219], v[76:79], v[104:107], v[216:219]
	s_add_u32 m0, s38, 28672
	s_nop 0
	global_load_lds_dwordx4 v245, s[100:101]
	s_add_u32 s100, s100, 128
	s_addc_u32 s101, s101, 0
	s_waitcnt lgkmcnt(8)
	v_mfma_f32_16x16x32_bf16 v[230:233], v[76:79], v[108:111], v[230:233]
	s_add_u32 m0, s38, 32768
	s_nop 0
	global_load_lds_dwordx4 v226, s[4:5]
	s_waitcnt lgkmcnt(6)
	v_mfma_f32_16x16x32_bf16 v[160:163], v[80:83], v[112:115], v[160:163]
	ds_read_b128 v[64:67], v151 offset:0
	s_add_u32 m0, s38, 36864
	s_nop 0
	global_load_lds_dwordx4 v228, s[4:5]
	s_waitcnt lgkmcnt(6)
	v_mfma_f32_16x16x32_bf16 v[164:167], v[80:83], v[116:119], v[164:167]
	ds_read_b128 v[96:99], v222 offset:49152
	s_add_u32 m0, s38, 40960
	s_nop 0
	global_load_lds_dwordx4 v244, s[4:5]
	s_waitcnt lgkmcnt(6)
	v_mfma_f32_16x16x32_bf16 v[168:171], v[80:83], v[120:123], v[168:171]
	ds_read_b128 v[100:103], v222 offset:51200
	s_add_u32 m0, s38, 45056
	s_nop 0
	global_load_lds_dwordx4 v245, s[4:5]
	s_add_u32 s4, s4, 128
	s_addc_u32 s5, s5, 0
	s_waitcnt lgkmcnt(6)
	v_mfma_f32_16x16x32_bf16 v[172:175], v[80:83], v[124:127], v[172:175]
	ds_read_b128 v[104:107], v222 offset:53248
	s_waitcnt lgkmcnt(6)
	v_mfma_f32_16x16x32_bf16 v[176:179], v[84:87], v[112:115], v[176:179]
	ds_read_b128 v[108:111], v222 offset:55296
	s_waitcnt lgkmcnt(7)
	v_mfma_f32_16x16x32_bf16 v[180:183], v[84:87], v[116:119], v[180:183]
	ds_read_b128 v[68:71], v151 offset:2048
	s_waitcnt lgkmcnt(8)
	v_mfma_f32_16x16x32_bf16 v[184:187], v[84:87], v[120:123], v[184:187]
	ds_read_b128 v[72:75], v151 offset:4096
	s_waitcnt lgkmcnt(9)
	v_mfma_f32_16x16x32_bf16 v[188:191], v[84:87], v[124:127], v[188:191]
	ds_read_b128 v[76:79], v151 offset:6144
	s_waitcnt lgkmcnt(9)
	v_mfma_f32_16x16x32_bf16 v[192:195], v[88:91], v[112:115], v[192:195]
	s_waitcnt lgkmcnt(9)
	v_mfma_f32_16x16x32_bf16 v[196:199], v[88:91], v[116:119], v[196:199]
	s_waitcnt lgkmcnt(9)
	v_mfma_f32_16x16x32_bf16 v[200:203], v[88:91], v[120:123], v[200:203]
	s_waitcnt lgkmcnt(9)
	v_mfma_f32_16x16x32_bf16 v[204:207], v[88:91], v[124:127], v[204:207]
	s_waitcnt lgkmcnt(8)
	v_mfma_f32_16x16x32_bf16 v[208:211], v[92:95], v[112:115], v[208:211]
	s_waitcnt lgkmcnt(8)
	v_mfma_f32_16x16x32_bf16 v[212:215], v[92:95], v[116:119], v[212:215]
	s_waitcnt lgkmcnt(8)
	v_mfma_f32_16x16x32_bf16 v[216:219], v[92:95], v[120:123], v[216:219]
	s_waitcnt lgkmcnt(8)
	v_mfma_f32_16x16x32_bf16 v[230:233], v[92:95], v[124:127], v[230:233]
	s_waitcnt lgkmcnt(6)
	v_mfma_f32_16x16x32_bf16 v[0:3], v[64:67], v[96:99], v[0:3]
	ds_read_b128 v[80:83], v220 offset:0
	s_waitcnt lgkmcnt(6)
	v_mfma_f32_16x16x32_bf16 v[4:7], v[64:67], v[100:103], v[4:7]
	ds_read_b128 v[112:115], v224 offset:49152
	s_waitcnt lgkmcnt(6)
	v_mfma_f32_16x16x32_bf16 v[8:11], v[64:67], v[104:107], v[8:11]
	ds_read_b128 v[116:119], v224 offset:51200
	s_waitcnt lgkmcnt(6)
	v_mfma_f32_16x16x32_bf16 v[12:15], v[64:67], v[108:111], v[12:15]
	ds_read_b128 v[120:123], v224 offset:53248
	s_waitcnt lgkmcnt(6)
	v_mfma_f32_16x16x32_bf16 v[16:19], v[68:71], v[96:99], v[16:19]
	ds_read_b128 v[124:127], v224 offset:55296
	s_waitcnt lgkmcnt(7)
	v_mfma_f32_16x16x32_bf16 v[20:23], v[68:71], v[100:103], v[20:23]
	ds_read_b128 v[84:87], v220 offset:2048
	s_waitcnt lgkmcnt(8)
	v_mfma_f32_16x16x32_bf16 v[24:27], v[68:71], v[104:107], v[24:27]
	ds_read_b128 v[88:91], v220 offset:4096
	s_waitcnt lgkmcnt(9)
	v_mfma_f32_16x16x32_bf16 v[28:31], v[68:71], v[108:111], v[28:31]
	ds_read_b128 v[92:95], v220 offset:6144
	s_waitcnt lgkmcnt(9)
	v_mfma_f32_16x16x32_bf16 v[32:35], v[72:75], v[96:99], v[32:35]
	s_waitcnt lgkmcnt(9)
	v_mfma_f32_16x16x32_bf16 v[36:39], v[72:75], v[100:103], v[36:39]
	s_waitcnt lgkmcnt(9)
	v_mfma_f32_16x16x32_bf16 v[40:43], v[72:75], v[104:107], v[40:43]
	s_waitcnt lgkmcnt(9)
	v_mfma_f32_16x16x32_bf16 v[44:47], v[72:75], v[108:111], v[44:47]
	s_waitcnt vmcnt(4) lgkmcnt(0)
	s_barrier
	s_add_u32 m0, s38, 0
	s_nop 0
	global_load_lds_dwordx4 v226, s[98:99]
	s_waitcnt lgkmcnt(8)
	v_mfma_f32_16x16x32_bf16 v[48:51], v[76:79], v[96:99], v[48:51]
	s_add_u32 m0, s38, 4096
	s_nop 0
	global_load_lds_dwordx4 v228, s[98:99]
	s_waitcnt lgkmcnt(8)
	v_mfma_f32_16x16x32_bf16 v[52:55], v[76:79], v[100:103], v[52:55]
	s_add_u32 m0, s38, 8192
	s_nop 0
	global_load_lds_dwordx4 v244, s[98:99]
	s_waitcnt lgkmcnt(8)
	v_mfma_f32_16x16x32_bf16 v[56:59], v[76:79], v[104:107], v[56:59]
	s_add_u32 m0, s38, 12288
	s_nop 0
	global_load_lds_dwordx4 v245, s[98:99]
	s_add_u32 s98, s98, 128
	s_addc_u32 s99, s99, 0
	s_waitcnt lgkmcnt(8)
	v_mfma_f32_16x16x32_bf16 v[60:63], v[76:79], v[108:111], v[60:63]
	s_waitcnt lgkmcnt(6)
	v_mfma_f32_16x16x32_bf16 v[0:3], v[80:83], v[112:115], v[0:3]
	ds_read_b128 v[64:67], v151 offset:16384
	s_waitcnt lgkmcnt(6)
	v_mfma_f32_16x16x32_bf16 v[4:7], v[80:83], v[116:119], v[4:7]
	ds_read_b128 v[96:99], v222 offset:49152
	s_waitcnt lgkmcnt(6)
	v_mfma_f32_16x16x32_bf16 v[8:11], v[80:83], v[120:123], v[8:11]
	ds_read_b128 v[100:103], v222 offset:51200
	s_waitcnt lgkmcnt(6)
	v_mfma_f32_16x16x32_bf16 v[12:15], v[80:83], v[124:127], v[12:15]
	ds_read_b128 v[104:107], v222 offset:53248
	s_waitcnt lgkmcnt(6)
	v_mfma_f32_16x16x32_bf16 v[16:19], v[84:87], v[112:115], v[16:19]
	ds_read_b128 v[108:111], v222 offset:55296
	s_waitcnt lgkmcnt(7)
	v_mfma_f32_16x16x32_bf16 v[20:23], v[84:87], v[116:119], v[20:23]
	ds_read_b128 v[68:71], v151 offset:18432
	s_waitcnt lgkmcnt(8)
	v_mfma_f32_16x16x32_bf16 v[24:27], v[84:87], v[120:123], v[24:27]
	ds_read_b128 v[72:75], v151 offset:20480
	s_waitcnt lgkmcnt(9)
	v_mfma_f32_16x16x32_bf16 v[28:31], v[84:87], v[124:127], v[28:31]
	ds_read_b128 v[76:79], v151 offset:22528
	s_waitcnt lgkmcnt(9)
	v_mfma_f32_16x16x32_bf16 v[32:35], v[88:91], v[112:115], v[32:35]
	s_waitcnt lgkmcnt(9)
	v_mfma_f32_16x16x32_bf16 v[36:39], v[88:91], v[116:119], v[36:39]
	s_waitcnt lgkmcnt(9)
	v_mfma_f32_16x16x32_bf16 v[40:43], v[88:91], v[120:123], v[40:43]
	s_waitcnt lgkmcnt(9)
	v_mfma_f32_16x16x32_bf16 v[44:47], v[88:91], v[124:127], v[44:47]
	s_waitcnt lgkmcnt(8)
	v_mfma_f32_16x16x32_bf16 v[48:51], v[92:95], v[112:115], v[48:51]
	s_waitcnt lgkmcnt(8)
	v_mfma_f32_16x16x32_bf16 v[52:55], v[92:95], v[116:119], v[52:55]
	s_waitcnt lgkmcnt(8)
	v_mfma_f32_16x16x32_bf16 v[56:59], v[92:95], v[120:123], v[56:59]
	s_waitcnt lgkmcnt(8)
	v_mfma_f32_16x16x32_bf16 v[60:63], v[92:95], v[124:127], v[60:63]
	s_waitcnt lgkmcnt(6)
	v_mfma_f32_16x16x32_bf16 v[160:163], v[64:67], v[96:99], v[160:163]
	ds_read_b128 v[80:83], v220 offset:16384
	s_waitcnt lgkmcnt(6)
	v_mfma_f32_16x16x32_bf16 v[164:167], v[64:67], v[100:103], v[164:167]
	ds_read_b128 v[112:115], v224 offset:49152
	s_waitcnt lgkmcnt(6)
	v_mfma_f32_16x16x32_bf16 v[168:171], v[64:67], v[104:107], v[168:171]
	ds_read_b128 v[116:119], v224 offset:51200
	s_waitcnt lgkmcnt(6)
	v_mfma_f32_16x16x32_bf16 v[172:175], v[64:67], v[108:111], v[172:175]
	ds_read_b128 v[120:123], v224 offset:53248
	s_waitcnt lgkmcnt(6)
	v_mfma_f32_16x16x32_bf16 v[176:179], v[68:71], v[96:99], v[176:179]
	ds_read_b128 v[124:127], v224 offset:55296
	s_waitcnt lgkmcnt(7)
	v_mfma_f32_16x16x32_bf16 v[180:183], v[68:71], v[100:103], v[180:183]
	ds_read_b128 v[84:87], v220 offset:18432
	s_waitcnt lgkmcnt(8)
	v_mfma_f32_16x16x32_bf16 v[184:187], v[68:71], v[104:107], v[184:187]
	ds_read_b128 v[88:91], v220 offset:20480
	s_waitcnt lgkmcnt(9)
	v_mfma_f32_16x16x32_bf16 v[188:191], v[68:71], v[108:111], v[188:191]
	ds_read_b128 v[92:95], v220 offset:22528
	s_waitcnt lgkmcnt(9)
	v_mfma_f32_16x16x32_bf16 v[192:195], v[72:75], v[96:99], v[192:195]
	s_waitcnt lgkmcnt(9)
	v_mfma_f32_16x16x32_bf16 v[196:199], v[72:75], v[100:103], v[196:199]
	s_waitcnt lgkmcnt(9)
	v_mfma_f32_16x16x32_bf16 v[200:203], v[72:75], v[104:107], v[200:203]
	s_waitcnt lgkmcnt(9)
	v_mfma_f32_16x16x32_bf16 v[204:207], v[72:75], v[108:111], v[204:207]
	s_waitcnt vmcnt(0) lgkmcnt(0)
	s_barrier
	s_add_u32 m0, s38, 16384
	s_nop 0
	global_load_lds_dwordx4 v226, s[100:101]
	s_waitcnt lgkmcnt(8)
	v_mfma_f32_16x16x32_bf16 v[208:211], v[76:79], v[96:99], v[208:211]
	s_add_u32 m0, s38, 20480
	s_nop 0
	global_load_lds_dwordx4 v228, s[100:101]
	s_waitcnt lgkmcnt(8)
	v_mfma_f32_16x16x32_bf16 v[212:215], v[76:79], v[100:103], v[212:215]
	s_add_u32 m0, s38, 24576
	s_nop 0
	global_load_lds_dwordx4 v244, s[100:101]
	s_waitcnt lgkmcnt(8)
	v_mfma_f32_16x16x32_bf16 v[216:219], v[76:79], v[104:107], v[216:219]
	s_add_u32 m0, s38, 28672
	s_nop 0
	global_load_lds_dwordx4 v245, s[100:101]
	s_add_u32 s100, s100, 128
	s_addc_u32 s101, s101, 0
	s_waitcnt lgkmcnt(8)
	v_mfma_f32_16x16x32_bf16 v[230:233], v[76:79], v[108:111], v[230:233]
	s_add_u32 m0, s38, 49152
	s_nop 0
	global_load_lds_dwordx4 v226, s[4:5]
	s_waitcnt lgkmcnt(6)
	v_mfma_f32_16x16x32_bf16 v[160:163], v[80:83], v[112:115], v[160:163]
	ds_read_b128 v[64:67], v151 offset:0
	s_add_u32 m0, s38, 53248
	s_nop 0
	global_load_lds_dwordx4 v228, s[4:5]
	s_waitcnt lgkmcnt(6)
	v_mfma_f32_16x16x32_bf16 v[164:167], v[80:83], v[116:119], v[164:167]
	ds_read_b128 v[96:99], v222 offset:32768
	s_add_u32 m0, s38, 57344
	s_nop 0
	global_load_lds_dwordx4 v244, s[4:5]
	s_waitcnt lgkmcnt(6)
	v_mfma_f32_16x16x32_bf16 v[168:171], v[80:83], v[120:123], v[168:171]
	ds_read_b128 v[100:103], v222 offset:34816
	s_add_u32 m0, s38, 61440
	s_nop 0
	global_load_lds_dwordx4 v245, s[4:5]
	s_add_u32 s4, s4, 128
	s_addc_u32 s5, s5, 0
	s_waitcnt lgkmcnt(6)
	v_mfma_f32_16x16x32_bf16 v[172:175], v[80:83], v[124:127], v[172:175]
	ds_read_b128 v[104:107], v222 offset:36864
	s_waitcnt lgkmcnt(6)
	v_mfma_f32_16x16x32_bf16 v[176:179], v[84:87], v[112:115], v[176:179]
	ds_read_b128 v[108:111], v222 offset:38912
	s_waitcnt lgkmcnt(7)
	v_mfma_f32_16x16x32_bf16 v[180:183], v[84:87], v[116:119], v[180:183]
	ds_read_b128 v[68:71], v151 offset:2048
	s_waitcnt lgkmcnt(8)
	v_mfma_f32_16x16x32_bf16 v[184:187], v[84:87], v[120:123], v[184:187]
	ds_read_b128 v[72:75], v151 offset:4096
	s_waitcnt lgkmcnt(9)
	v_mfma_f32_16x16x32_bf16 v[188:191], v[84:87], v[124:127], v[188:191]
	ds_read_b128 v[76:79], v151 offset:6144
	s_waitcnt lgkmcnt(9)
	v_mfma_f32_16x16x32_bf16 v[192:195], v[88:91], v[112:115], v[192:195]
	s_waitcnt lgkmcnt(9)
	v_mfma_f32_16x16x32_bf16 v[196:199], v[88:91], v[116:119], v[196:199]
	s_waitcnt lgkmcnt(9)
	v_mfma_f32_16x16x32_bf16 v[200:203], v[88:91], v[120:123], v[200:203]
	s_waitcnt lgkmcnt(9)
	v_mfma_f32_16x16x32_bf16 v[204:207], v[88:91], v[124:127], v[204:207]
	s_waitcnt lgkmcnt(8)
	v_mfma_f32_16x16x32_bf16 v[208:211], v[92:95], v[112:115], v[208:211]
	s_waitcnt lgkmcnt(8)
	v_mfma_f32_16x16x32_bf16 v[212:215], v[92:95], v[116:119], v[212:215]
	s_waitcnt lgkmcnt(8)
	v_mfma_f32_16x16x32_bf16 v[216:219], v[92:95], v[120:123], v[216:219]
	s_waitcnt lgkmcnt(8)
	v_mfma_f32_16x16x32_bf16 v[230:233], v[92:95], v[124:127], v[230:233]
	s_waitcnt lgkmcnt(6)
	v_mfma_f32_16x16x32_bf16 v[0:3], v[64:67], v[96:99], v[0:3]
	ds_read_b128 v[80:83], v220 offset:0
	s_waitcnt lgkmcnt(6)
	v_mfma_f32_16x16x32_bf16 v[4:7], v[64:67], v[100:103], v[4:7]
	ds_read_b128 v[112:115], v224 offset:32768
	s_waitcnt lgkmcnt(6)
	v_mfma_f32_16x16x32_bf16 v[8:11], v[64:67], v[104:107], v[8:11]
	ds_read_b128 v[116:119], v224 offset:34816
	s_waitcnt lgkmcnt(6)
	v_mfma_f32_16x16x32_bf16 v[12:15], v[64:67], v[108:111], v[12:15]
	ds_read_b128 v[120:123], v224 offset:36864
	s_waitcnt lgkmcnt(6)
	v_mfma_f32_16x16x32_bf16 v[16:19], v[68:71], v[96:99], v[16:19]
	ds_read_b128 v[124:127], v224 offset:38912
	s_waitcnt lgkmcnt(7)
	v_mfma_f32_16x16x32_bf16 v[20:23], v[68:71], v[100:103], v[20:23]
	ds_read_b128 v[84:87], v220 offset:2048
	s_waitcnt lgkmcnt(8)
	v_mfma_f32_16x16x32_bf16 v[24:27], v[68:71], v[104:107], v[24:27]
	ds_read_b128 v[88:91], v220 offset:4096
	s_waitcnt lgkmcnt(9)
	v_mfma_f32_16x16x32_bf16 v[28:31], v[68:71], v[108:111], v[28:31]
	ds_read_b128 v[92:95], v220 offset:6144
	s_waitcnt lgkmcnt(9)
	v_mfma_f32_16x16x32_bf16 v[32:35], v[72:75], v[96:99], v[32:35]
	s_waitcnt lgkmcnt(9)
	v_mfma_f32_16x16x32_bf16 v[36:39], v[72:75], v[100:103], v[36:39]
	s_waitcnt lgkmcnt(9)
	v_mfma_f32_16x16x32_bf16 v[40:43], v[72:75], v[104:107], v[40:43]
	s_waitcnt lgkmcnt(9)
	v_mfma_f32_16x16x32_bf16 v[44:47], v[72:75], v[108:111], v[44:47]
	s_waitcnt vmcnt(4) lgkmcnt(0)
	s_barrier
	s_add_u32 m0, s38, 0
	s_nop 0
	global_load_lds_dwordx4 v226, s[98:99]
	s_waitcnt lgkmcnt(8)
	v_mfma_f32_16x16x32_bf16 v[48:51], v[76:79], v[96:99], v[48:51]
	s_add_u32 m0, s38, 4096
	s_nop 0
	global_load_lds_dwordx4 v228, s[98:99]
	s_waitcnt lgkmcnt(8)
	v_mfma_f32_16x16x32_bf16 v[52:55], v[76:79], v[100:103], v[52:55]
	s_add_u32 m0, s38, 8192
	s_nop 0
	global_load_lds_dwordx4 v244, s[98:99]
	s_waitcnt lgkmcnt(8)
	v_mfma_f32_16x16x32_bf16 v[56:59], v[76:79], v[104:107], v[56:59]
	s_add_u32 m0, s38, 12288
	s_nop 0
	global_load_lds_dwordx4 v245, s[98:99]
	s_add_u32 s98, s98, 128
	s_addc_u32 s99, s99, 0
	s_waitcnt lgkmcnt(8)
	v_mfma_f32_16x16x32_bf16 v[60:63], v[76:79], v[108:111], v[60:63]
	s_waitcnt lgkmcnt(6)
	v_mfma_f32_16x16x32_bf16 v[0:3], v[80:83], v[112:115], v[0:3]
	ds_read_b128 v[64:67], v151 offset:16384
	s_waitcnt lgkmcnt(6)
	v_mfma_f32_16x16x32_bf16 v[4:7], v[80:83], v[116:119], v[4:7]
	ds_read_b128 v[96:99], v222 offset:32768
	s_waitcnt lgkmcnt(6)
	v_mfma_f32_16x16x32_bf16 v[8:11], v[80:83], v[120:123], v[8:11]
	ds_read_b128 v[100:103], v222 offset:34816
	s_waitcnt lgkmcnt(6)
	v_mfma_f32_16x16x32_bf16 v[12:15], v[80:83], v[124:127], v[12:15]
	ds_read_b128 v[104:107], v222 offset:36864
	s_waitcnt lgkmcnt(6)
	v_mfma_f32_16x16x32_bf16 v[16:19], v[84:87], v[112:115], v[16:19]
	ds_read_b128 v[108:111], v222 offset:38912
	s_waitcnt lgkmcnt(7)
	v_mfma_f32_16x16x32_bf16 v[20:23], v[84:87], v[116:119], v[20:23]
	ds_read_b128 v[68:71], v151 offset:18432
	s_waitcnt lgkmcnt(8)
	v_mfma_f32_16x16x32_bf16 v[24:27], v[84:87], v[120:123], v[24:27]
	ds_read_b128 v[72:75], v151 offset:20480
	s_waitcnt lgkmcnt(9)
	v_mfma_f32_16x16x32_bf16 v[28:31], v[84:87], v[124:127], v[28:31]
	ds_read_b128 v[76:79], v151 offset:22528
	s_waitcnt lgkmcnt(9)
	v_mfma_f32_16x16x32_bf16 v[32:35], v[88:91], v[112:115], v[32:35]
	s_waitcnt lgkmcnt(9)
	v_mfma_f32_16x16x32_bf16 v[36:39], v[88:91], v[116:119], v[36:39]
	s_waitcnt lgkmcnt(9)
	v_mfma_f32_16x16x32_bf16 v[40:43], v[88:91], v[120:123], v[40:43]
	s_waitcnt lgkmcnt(9)
	v_mfma_f32_16x16x32_bf16 v[44:47], v[88:91], v[124:127], v[44:47]
	s_waitcnt lgkmcnt(8)
	v_mfma_f32_16x16x32_bf16 v[48:51], v[92:95], v[112:115], v[48:51]
	s_waitcnt lgkmcnt(8)
	v_mfma_f32_16x16x32_bf16 v[52:55], v[92:95], v[116:119], v[52:55]
	s_waitcnt lgkmcnt(8)
	v_mfma_f32_16x16x32_bf16 v[56:59], v[92:95], v[120:123], v[56:59]
	s_waitcnt lgkmcnt(8)
	v_mfma_f32_16x16x32_bf16 v[60:63], v[92:95], v[124:127], v[60:63]
	s_waitcnt lgkmcnt(6)
	v_mfma_f32_16x16x32_bf16 v[160:163], v[64:67], v[96:99], v[160:163]
	ds_read_b128 v[80:83], v220 offset:16384
	s_waitcnt lgkmcnt(6)
	v_mfma_f32_16x16x32_bf16 v[164:167], v[64:67], v[100:103], v[164:167]
	ds_read_b128 v[112:115], v224 offset:32768
	s_waitcnt lgkmcnt(6)
	v_mfma_f32_16x16x32_bf16 v[168:171], v[64:67], v[104:107], v[168:171]
	ds_read_b128 v[116:119], v224 offset:34816
	s_waitcnt lgkmcnt(6)
	v_mfma_f32_16x16x32_bf16 v[172:175], v[64:67], v[108:111], v[172:175]
	ds_read_b128 v[120:123], v224 offset:36864
	s_waitcnt lgkmcnt(6)
	v_mfma_f32_16x16x32_bf16 v[176:179], v[68:71], v[96:99], v[176:179]
	ds_read_b128 v[124:127], v224 offset:38912
	s_waitcnt lgkmcnt(7)
	v_mfma_f32_16x16x32_bf16 v[180:183], v[68:71], v[100:103], v[180:183]
	ds_read_b128 v[84:87], v220 offset:18432
	s_waitcnt lgkmcnt(8)
	v_mfma_f32_16x16x32_bf16 v[184:187], v[68:71], v[104:107], v[184:187]
	ds_read_b128 v[88:91], v220 offset:20480
	s_waitcnt lgkmcnt(9)
	v_mfma_f32_16x16x32_bf16 v[188:191], v[68:71], v[108:111], v[188:191]
	ds_read_b128 v[92:95], v220 offset:22528
	s_waitcnt lgkmcnt(9)
	v_mfma_f32_16x16x32_bf16 v[192:195], v[72:75], v[96:99], v[192:195]
	s_waitcnt lgkmcnt(9)
	v_mfma_f32_16x16x32_bf16 v[196:199], v[72:75], v[100:103], v[196:199]
	s_waitcnt lgkmcnt(9)
	v_mfma_f32_16x16x32_bf16 v[200:203], v[72:75], v[104:107], v[200:203]
	s_waitcnt lgkmcnt(9)
	v_mfma_f32_16x16x32_bf16 v[204:207], v[72:75], v[108:111], v[204:207]
	s_waitcnt vmcnt(0) lgkmcnt(0)
	s_barrier
	s_add_u32 m0, s38, 16384
	s_nop 0
	global_load_lds_dwordx4 v226, s[100:101]
	s_waitcnt lgkmcnt(8)
	v_mfma_f32_16x16x32_bf16 v[208:211], v[76:79], v[96:99], v[208:211]
	s_add_u32 m0, s38, 20480
	s_nop 0
	global_load_lds_dwordx4 v228, s[100:101]
	s_waitcnt lgkmcnt(8)
	v_mfma_f32_16x16x32_bf16 v[212:215], v[76:79], v[100:103], v[212:215]
	s_add_u32 m0, s38, 24576
	s_nop 0
	global_load_lds_dwordx4 v244, s[100:101]
	s_waitcnt lgkmcnt(8)
	v_mfma_f32_16x16x32_bf16 v[216:219], v[76:79], v[104:107], v[216:219]
	s_add_u32 m0, s38, 28672
	s_nop 0
	global_load_lds_dwordx4 v245, s[100:101]
	s_add_u32 s100, s100, 128
	s_addc_u32 s101, s101, 0
	s_waitcnt lgkmcnt(8)
	v_mfma_f32_16x16x32_bf16 v[230:233], v[76:79], v[108:111], v[230:233]
	s_waitcnt lgkmcnt(6)
	v_mfma_f32_16x16x32_bf16 v[160:163], v[80:83], v[112:115], v[160:163]
	ds_read_b128 v[64:67], v151 offset:0
	s_waitcnt lgkmcnt(6)
	v_mfma_f32_16x16x32_bf16 v[164:167], v[80:83], v[116:119], v[164:167]
	ds_read_b128 v[96:99], v222 offset:49152
	s_waitcnt lgkmcnt(6)
	v_mfma_f32_16x16x32_bf16 v[168:171], v[80:83], v[120:123], v[168:171]
	ds_read_b128 v[100:103], v222 offset:51200
	s_waitcnt lgkmcnt(6)
	v_mfma_f32_16x16x32_bf16 v[172:175], v[80:83], v[124:127], v[172:175]
	ds_read_b128 v[104:107], v222 offset:53248
	s_waitcnt lgkmcnt(6)
	v_mfma_f32_16x16x32_bf16 v[176:179], v[84:87], v[112:115], v[176:179]
	ds_read_b128 v[108:111], v222 offset:55296
	s_waitcnt lgkmcnt(7)
	v_mfma_f32_16x16x32_bf16 v[180:183], v[84:87], v[116:119], v[180:183]
	ds_read_b128 v[68:71], v151 offset:2048
	s_waitcnt lgkmcnt(8)
	v_mfma_f32_16x16x32_bf16 v[184:187], v[84:87], v[120:123], v[184:187]
	ds_read_b128 v[72:75], v151 offset:4096
	s_waitcnt lgkmcnt(9)
	v_mfma_f32_16x16x32_bf16 v[188:191], v[84:87], v[124:127], v[188:191]
	ds_read_b128 v[76:79], v151 offset:6144
	s_waitcnt lgkmcnt(9)
	v_mfma_f32_16x16x32_bf16 v[192:195], v[88:91], v[112:115], v[192:195]
	s_waitcnt lgkmcnt(9)
	v_mfma_f32_16x16x32_bf16 v[196:199], v[88:91], v[116:119], v[196:199]
	s_waitcnt lgkmcnt(9)
	v_mfma_f32_16x16x32_bf16 v[200:203], v[88:91], v[120:123], v[200:203]
	s_waitcnt lgkmcnt(9)
	v_mfma_f32_16x16x32_bf16 v[204:207], v[88:91], v[124:127], v[204:207]
	s_waitcnt lgkmcnt(8)
	v_mfma_f32_16x16x32_bf16 v[208:211], v[92:95], v[112:115], v[208:211]
	s_waitcnt lgkmcnt(8)
	v_mfma_f32_16x16x32_bf16 v[212:215], v[92:95], v[116:119], v[212:215]
	s_waitcnt lgkmcnt(8)
	v_mfma_f32_16x16x32_bf16 v[216:219], v[92:95], v[120:123], v[216:219]
	s_waitcnt lgkmcnt(8)
	v_mfma_f32_16x16x32_bf16 v[230:233], v[92:95], v[124:127], v[230:233]
	s_waitcnt lgkmcnt(6)
	v_mfma_f32_16x16x32_bf16 v[0:3], v[64:67], v[96:99], v[0:3]
	ds_read_b128 v[80:83], v220 offset:0
	s_waitcnt lgkmcnt(6)
	v_mfma_f32_16x16x32_bf16 v[4:7], v[64:67], v[100:103], v[4:7]
	ds_read_b128 v[112:115], v224 offset:49152
	s_waitcnt lgkmcnt(6)
	v_mfma_f32_16x16x32_bf16 v[8:11], v[64:67], v[104:107], v[8:11]
	ds_read_b128 v[116:119], v224 offset:51200
	s_waitcnt lgkmcnt(6)
	v_mfma_f32_16x16x32_bf16 v[12:15], v[64:67], v[108:111], v[12:15]
	ds_read_b128 v[120:123], v224 offset:53248
	s_waitcnt lgkmcnt(6)
	v_mfma_f32_16x16x32_bf16 v[16:19], v[68:71], v[96:99], v[16:19]
	ds_read_b128 v[124:127], v224 offset:55296
	s_waitcnt lgkmcnt(7)
	v_mfma_f32_16x16x32_bf16 v[20:23], v[68:71], v[100:103], v[20:23]
	ds_read_b128 v[84:87], v220 offset:2048
	s_waitcnt lgkmcnt(8)
	v_mfma_f32_16x16x32_bf16 v[24:27], v[68:71], v[104:107], v[24:27]
	ds_read_b128 v[88:91], v220 offset:4096
	s_waitcnt lgkmcnt(9)
	v_mfma_f32_16x16x32_bf16 v[28:31], v[68:71], v[108:111], v[28:31]
	ds_read_b128 v[92:95], v220 offset:6144
	s_waitcnt lgkmcnt(9)
	v_mfma_f32_16x16x32_bf16 v[32:35], v[72:75], v[96:99], v[32:35]
	s_waitcnt lgkmcnt(9)
	v_mfma_f32_16x16x32_bf16 v[36:39], v[72:75], v[100:103], v[36:39]
	s_waitcnt lgkmcnt(9)
	v_mfma_f32_16x16x32_bf16 v[40:43], v[72:75], v[104:107], v[40:43]
	s_waitcnt lgkmcnt(9)
	v_mfma_f32_16x16x32_bf16 v[44:47], v[72:75], v[108:111], v[44:47]
	s_waitcnt vmcnt(0) lgkmcnt(0)
	s_barrier
	s_waitcnt lgkmcnt(8)
	v_mfma_f32_16x16x32_bf16 v[48:51], v[76:79], v[96:99], v[48:51]
	s_waitcnt lgkmcnt(8)
	v_mfma_f32_16x16x32_bf16 v[52:55], v[76:79], v[100:103], v[52:55]
	s_waitcnt lgkmcnt(8)
	v_mfma_f32_16x16x32_bf16 v[56:59], v[76:79], v[104:107], v[56:59]
	s_waitcnt lgkmcnt(8)
	v_mfma_f32_16x16x32_bf16 v[60:63], v[76:79], v[108:111], v[60:63]
	s_waitcnt lgkmcnt(6)
	v_mfma_f32_16x16x32_bf16 v[0:3], v[80:83], v[112:115], v[0:3]
	ds_read_b128 v[64:67], v151 offset:16384
	s_waitcnt lgkmcnt(6)
	v_mfma_f32_16x16x32_bf16 v[4:7], v[80:83], v[116:119], v[4:7]
	ds_read_b128 v[96:99], v222 offset:49152
	s_waitcnt lgkmcnt(6)
	v_mfma_f32_16x16x32_bf16 v[8:11], v[80:83], v[120:123], v[8:11]
	ds_read_b128 v[100:103], v222 offset:51200
	s_waitcnt lgkmcnt(6)
	v_mfma_f32_16x16x32_bf16 v[12:15], v[80:83], v[124:127], v[12:15]
	ds_read_b128 v[104:107], v222 offset:53248
	s_waitcnt lgkmcnt(6)
	v_mfma_f32_16x16x32_bf16 v[16:19], v[84:87], v[112:115], v[16:19]
	ds_read_b128 v[108:111], v222 offset:55296
	s_waitcnt lgkmcnt(7)
	v_mfma_f32_16x16x32_bf16 v[20:23], v[84:87], v[116:119], v[20:23]
	ds_read_b128 v[68:71], v151 offset:18432
	s_waitcnt lgkmcnt(8)
	v_mfma_f32_16x16x32_bf16 v[24:27], v[84:87], v[120:123], v[24:27]
	ds_read_b128 v[72:75], v151 offset:20480
	s_waitcnt lgkmcnt(9)
	v_mfma_f32_16x16x32_bf16 v[28:31], v[84:87], v[124:127], v[28:31]
	ds_read_b128 v[76:79], v151 offset:22528
	s_waitcnt lgkmcnt(9)
	v_mfma_f32_16x16x32_bf16 v[32:35], v[88:91], v[112:115], v[32:35]
	s_waitcnt lgkmcnt(9)
	v_mfma_f32_16x16x32_bf16 v[36:39], v[88:91], v[116:119], v[36:39]
	s_waitcnt lgkmcnt(9)
	v_mfma_f32_16x16x32_bf16 v[40:43], v[88:91], v[120:123], v[40:43]
	s_waitcnt lgkmcnt(9)
	v_mfma_f32_16x16x32_bf16 v[44:47], v[88:91], v[124:127], v[44:47]
	s_waitcnt lgkmcnt(8)
	v_mfma_f32_16x16x32_bf16 v[48:51], v[92:95], v[112:115], v[48:51]
	s_waitcnt lgkmcnt(8)
	v_mfma_f32_16x16x32_bf16 v[52:55], v[92:95], v[116:119], v[52:55]
	s_waitcnt lgkmcnt(8)
	v_mfma_f32_16x16x32_bf16 v[56:59], v[92:95], v[120:123], v[56:59]
	s_waitcnt lgkmcnt(8)
	v_mfma_f32_16x16x32_bf16 v[60:63], v[92:95], v[124:127], v[60:63]
	s_waitcnt lgkmcnt(6)
	v_mfma_f32_16x16x32_bf16 v[160:163], v[64:67], v[96:99], v[160:163]
	ds_read_b128 v[80:83], v220 offset:16384
	s_waitcnt lgkmcnt(6)
	v_mfma_f32_16x16x32_bf16 v[164:167], v[64:67], v[100:103], v[164:167]
	ds_read_b128 v[112:115], v224 offset:49152
	s_waitcnt lgkmcnt(6)
	v_mfma_f32_16x16x32_bf16 v[168:171], v[64:67], v[104:107], v[168:171]
	ds_read_b128 v[116:119], v224 offset:51200
	s_waitcnt lgkmcnt(6)
	v_mfma_f32_16x16x32_bf16 v[172:175], v[64:67], v[108:111], v[172:175]
	ds_read_b128 v[120:123], v224 offset:53248
	s_waitcnt lgkmcnt(6)
	v_mfma_f32_16x16x32_bf16 v[176:179], v[68:71], v[96:99], v[176:179]
	ds_read_b128 v[124:127], v224 offset:55296
	s_waitcnt lgkmcnt(7)
	v_mfma_f32_16x16x32_bf16 v[180:183], v[68:71], v[100:103], v[180:183]
	ds_read_b128 v[84:87], v220 offset:18432
	s_waitcnt lgkmcnt(8)
	v_mfma_f32_16x16x32_bf16 v[184:187], v[68:71], v[104:107], v[184:187]
	ds_read_b128 v[88:91], v220 offset:20480
	s_waitcnt lgkmcnt(9)
	v_mfma_f32_16x16x32_bf16 v[188:191], v[68:71], v[108:111], v[188:191]
	ds_read_b128 v[92:95], v220 offset:22528
	s_waitcnt lgkmcnt(9)
	v_mfma_f32_16x16x32_bf16 v[192:195], v[72:75], v[96:99], v[192:195]
	s_waitcnt lgkmcnt(9)
	v_mfma_f32_16x16x32_bf16 v[196:199], v[72:75], v[100:103], v[196:199]
	s_waitcnt lgkmcnt(9)
	v_mfma_f32_16x16x32_bf16 v[200:203], v[72:75], v[104:107], v[200:203]
	s_waitcnt lgkmcnt(9)
	v_mfma_f32_16x16x32_bf16 v[204:207], v[72:75], v[108:111], v[204:207]
	s_waitcnt lgkmcnt(8)
	v_mfma_f32_16x16x32_bf16 v[208:211], v[76:79], v[96:99], v[208:211]
	s_waitcnt lgkmcnt(8)
	v_mfma_f32_16x16x32_bf16 v[212:215], v[76:79], v[100:103], v[212:215]
	s_waitcnt lgkmcnt(8)
	v_mfma_f32_16x16x32_bf16 v[216:219], v[76:79], v[104:107], v[216:219]
	s_waitcnt lgkmcnt(8)
	v_mfma_f32_16x16x32_bf16 v[230:233], v[76:79], v[108:111], v[230:233]
	s_waitcnt lgkmcnt(6)
	v_mfma_f32_16x16x32_bf16 v[160:163], v[80:83], v[112:115], v[160:163]
	s_waitcnt lgkmcnt(5)
	v_mfma_f32_16x16x32_bf16 v[164:167], v[80:83], v[116:119], v[164:167]
	s_waitcnt lgkmcnt(4)
	v_mfma_f32_16x16x32_bf16 v[168:171], v[80:83], v[120:123], v[168:171]
	s_waitcnt lgkmcnt(3)
	v_mfma_f32_16x16x32_bf16 v[172:175], v[80:83], v[124:127], v[172:175]
	s_waitcnt lgkmcnt(2)
	v_mfma_f32_16x16x32_bf16 v[176:179], v[84:87], v[112:115], v[176:179]
	s_waitcnt lgkmcnt(2)
	v_mfma_f32_16x16x32_bf16 v[180:183], v[84:87], v[116:119], v[180:183]
	s_waitcnt lgkmcnt(2)
	v_mfma_f32_16x16x32_bf16 v[184:187], v[84:87], v[120:123], v[184:187]
	s_waitcnt lgkmcnt(2)
	v_mfma_f32_16x16x32_bf16 v[188:191], v[84:87], v[124:127], v[188:191]
	s_waitcnt lgkmcnt(1)
	v_mfma_f32_16x16x32_bf16 v[192:195], v[88:91], v[112:115], v[192:195]
	s_waitcnt lgkmcnt(1)
	v_mfma_f32_16x16x32_bf16 v[196:199], v[88:91], v[116:119], v[196:199]
	s_waitcnt lgkmcnt(1)
	v_mfma_f32_16x16x32_bf16 v[200:203], v[88:91], v[120:123], v[200:203]
	s_waitcnt lgkmcnt(1)
	v_mfma_f32_16x16x32_bf16 v[204:207], v[88:91], v[124:127], v[204:207]
	s_waitcnt lgkmcnt(0)
	v_mfma_f32_16x16x32_bf16 v[208:211], v[92:95], v[112:115], v[208:211]
	s_waitcnt lgkmcnt(0)
	v_mfma_f32_16x16x32_bf16 v[212:215], v[92:95], v[116:119], v[212:215]
	s_waitcnt lgkmcnt(0)
	v_mfma_f32_16x16x32_bf16 v[216:219], v[92:95], v[120:123], v[216:219]
	s_waitcnt lgkmcnt(0)
	v_mfma_f32_16x16x32_bf16 v[230:233], v[92:95], v[124:127], v[230:233]
	s_add_u32 s14, s10, 0x0
	s_addc_u32 s15, s11, 0
	global_load_dwordx4 v[64:67], v150, s[14:15] nt
	global_load_dwordx4 v[68:71], v150, s[14:15] offset:16 nt
	s_add_u32 s14, s14, 0x8000
	s_addc_u32 s15, s15, 0
	global_load_dwordx4 v[72:75], v150, s[14:15] nt
	global_load_dwordx4 v[76:79], v150, s[14:15] offset:16 nt
	s_add_u32 s14, s14, 0x8000
	s_addc_u32 s15, s15, 0
	global_load_dwordx4 v[80:83], v150, s[14:15] nt
	global_load_dwordx4 v[84:87], v150, s[14:15] offset:16 nt
	s_add_u32 s14, s14, 0x8000
	s_addc_u32 s15, s15, 0
	global_load_dwordx4 v[88:91], v150, s[14:15] nt
	global_load_dwordx4 v[92:95], v150, s[14:15] offset:16 nt
	s_add_u32 s14, s10, 0x20000
	s_addc_u32 s15, s11, 0
	global_load_dwordx4 v[96:99], v150, s[14:15] nt
	global_load_dwordx4 v[100:103], v150, s[14:15] offset:16 nt
	s_add_u32 s14, s14, 0x8000
	s_addc_u32 s15, s15, 0
	global_load_dwordx4 v[104:107], v150, s[14:15] nt
	global_load_dwordx4 v[108:111], v150, s[14:15] offset:16 nt
	s_add_u32 s14, s14, 0x8000
	s_addc_u32 s15, s15, 0
	global_load_dwordx4 v[112:115], v150, s[14:15] nt
	global_load_dwordx4 v[116:119], v150, s[14:15] offset:16 nt
	s_add_u32 s14, s14, 0x8000
	s_addc_u32 s15, s15, 0
	global_load_dwordx4 v[120:123], v150, s[14:15] nt
	global_load_dwordx4 v[124:127], v150, s[14:15] offset:16 nt
	s_nop 7
	s_waitcnt lgkmcnt(0)
	s_barrier
	s_add_u32 s18, s12, 0x0
	s_addc_u32 s19, s13, 0
	ds_write_b32 v248, v0 offset:0
	ds_write_b32 v248, v1 offset:256
	ds_write_b32 v248, v2 offset:512
	ds_write_b32 v248, v3 offset:768
	ds_write_b32 v249, v4 offset:0
	ds_write_b32 v249, v5 offset:256
	ds_write_b32 v249, v6 offset:512
	ds_write_b32 v249, v7 offset:768
	ds_write_b32 v250, v8 offset:0
	ds_write_b32 v250, v9 offset:256
	ds_write_b32 v250, v10 offset:512
	ds_write_b32 v250, v11 offset:768
	ds_write_b32 v251, v12 offset:0
	ds_write_b32 v251, v13 offset:256
	ds_write_b32 v251, v14 offset:512
	ds_write_b32 v251, v15 offset:768
	ds_write_b32 v248, v16 offset:4096
	ds_write_b32 v248, v17 offset:4352
	ds_write_b32 v248, v18 offset:4608
	ds_write_b32 v248, v19 offset:4864
	ds_write_b32 v249, v20 offset:4096
	ds_write_b32 v249, v21 offset:4352
	ds_write_b32 v249, v22 offset:4608
	ds_write_b32 v249, v23 offset:4864
	ds_write_b32 v250, v24 offset:4096
	ds_write_b32 v250, v25 offset:4352
	ds_write_b32 v250, v26 offset:4608
	ds_write_b32 v250, v27 offset:4864
	ds_write_b32 v251, v28 offset:4096
	ds_write_b32 v251, v29 offset:4352
	ds_write_b32 v251, v30 offset:4608
	ds_write_b32 v251, v31 offset:4864
	s_waitcnt lgkmcnt(0)
	ds_read_b128 v[0:3], v252
	ds_read_b128 v[4:7], v252 offset:16
	ds_read_b128 v[8:11], v253
	ds_read_b128 v[12:15], v253 offset:16
	ds_read_b128 v[16:19], v254
	ds_read_b128 v[20:23], v254 offset:16
	ds_read_b128 v[24:27], v255
	ds_read_b128 v[28:31], v255 offset:16
	s_waitcnt vmcnt(14) lgkmcnt(6)
	v_pk_fma_f32 v[0:1], v[142:143], v[0:1], v[64:65]
	v_pk_fma_f32 v[2:3], v[144:145], v[2:3], v[66:67]
	v_pk_fma_f32 v[4:5], v[146:147], v[4:5], v[68:69]
	v_pk_fma_f32 v[6:7], v[234:235], v[6:7], v[70:71]
	global_store_dwordx4 v150, v[0:3], s[18:19]
	global_store_dwordx4 v150, v[4:7], s[18:19] offset:16
	s_add_u32 s18, s18, 0x8000
	s_addc_u32 s19, s19, 0
	s_waitcnt vmcnt(14) lgkmcnt(4)
	v_pk_fma_f32 v[8:9], v[142:143], v[8:9], v[72:73]
	v_pk_fma_f32 v[10:11], v[144:145], v[10:11], v[74:75]
	v_pk_fma_f32 v[12:13], v[146:147], v[12:13], v[76:77]
	v_pk_fma_f32 v[14:15], v[234:235], v[14:15], v[78:79]
	global_store_dwordx4 v150, v[8:11], s[18:19]
	global_store_dwordx4 v150, v[12:15], s[18:19] offset:16
	s_add_u32 s18, s18, 0x8000
	s_addc_u32 s19, s19, 0
	s_waitcnt vmcnt(14) lgkmcnt(2)
	v_pk_fma_f32 v[16:17], v[142:143], v[16:17], v[80:81]
	v_pk_fma_f32 v[18:19], v[144:145], v[18:19], v[82:83]
	v_pk_fma_f32 v[20:21], v[146:147], v[20:21], v[84:85]
	v_pk_fma_f32 v[22:23], v[234:235], v[22:23], v[86:87]
	global_store_dwordx4 v150, v[16:19], s[18:19]
	global_store_dwordx4 v150, v[20:23], s[18:19] offset:16
	s_add_u32 s18, s18, 0x8000
	s_addc_u32 s19, s19, 0
	s_waitcnt vmcnt(14) lgkmcnt(0)
	v_pk_fma_f32 v[24:25], v[142:143], v[24:25], v[88:89]
	v_pk_fma_f32 v[26:27], v[144:145], v[26:27], v[90:91]
	v_pk_fma_f32 v[28:29], v[146:147], v[28:29], v[92:93]
	v_pk_fma_f32 v[30:31], v[234:235], v[30:31], v[94:95]
	global_store_dwordx4 v150, v[24:27], s[18:19]
	global_store_dwordx4 v150, v[28:31], s[18:19] offset:16
	s_add_u32 s18, s18, 0x8000
	s_addc_u32 s19, s19, 0
	s_add_u32 s14, s10, 0x2000000
	s_addc_u32 s15, s11, 0
	global_load_dwordx4 v[64:67], v150, s[14:15] nt
	global_load_dwordx4 v[68:71], v150, s[14:15] offset:16 nt
	s_add_u32 s14, s14, 0x8000
	s_addc_u32 s15, s15, 0
	global_load_dwordx4 v[72:75], v150, s[14:15] nt
	global_load_dwordx4 v[76:79], v150, s[14:15] offset:16 nt
	s_add_u32 s14, s14, 0x8000
	s_addc_u32 s15, s15, 0
	global_load_dwordx4 v[80:83], v150, s[14:15] nt
	global_load_dwordx4 v[84:87], v150, s[14:15] offset:16 nt
	s_add_u32 s14, s14, 0x8000
	s_addc_u32 s15, s15, 0
	global_load_dwordx4 v[88:91], v150, s[14:15] nt
	global_load_dwordx4 v[92:95], v150, s[14:15] offset:16 nt
	ds_write_b32 v248, v32 offset:0
	ds_write_b32 v248, v33 offset:256
	ds_write_b32 v248, v34 offset:512
	ds_write_b32 v248, v35 offset:768
	ds_write_b32 v249, v36 offset:0
	ds_write_b32 v249, v37 offset:256
	ds_write_b32 v249, v38 offset:512
	ds_write_b32 v249, v39 offset:768
	ds_write_b32 v250, v40 offset:0
	ds_write_b32 v250, v41 offset:256
	ds_write_b32 v250, v42 offset:512
	ds_write_b32 v250, v43 offset:768
	ds_write_b32 v251, v44 offset:0
	ds_write_b32 v251, v45 offset:256
	ds_write_b32 v251, v46 offset:512
	ds_write_b32 v251, v47 offset:768
	ds_write_b32 v248, v48 offset:4096
	ds_write_b32 v248, v49 offset:4352
	ds_write_b32 v248, v50 offset:4608
	ds_write_b32 v248, v51 offset:4864
	ds_write_b32 v249, v52 offset:4096
	ds_write_b32 v249, v53 offset:4352
	ds_write_b32 v249, v54 offset:4608
	ds_write_b32 v249, v55 offset:4864
	ds_write_b32 v250, v56 offset:4096
	ds_write_b32 v250, v57 offset:4352
	ds_write_b32 v250, v58 offset:4608
	ds_write_b32 v250, v59 offset:4864
	ds_write_b32 v251, v60 offset:4096
	ds_write_b32 v251, v61 offset:4352
	ds_write_b32 v251, v62 offset:4608
	ds_write_b32 v251, v63 offset:4864
	s_waitcnt lgkmcnt(0)
	ds_read_b128 v[32:35], v252
	ds_read_b128 v[36:39], v252 offset:16
	ds_read_b128 v[40:43], v253
	ds_read_b128 v[44:47], v253 offset:16
	ds_read_b128 v[48:51], v254
	ds_read_b128 v[52:55], v254 offset:16
	ds_read_b128 v[56:59], v255
	ds_read_b128 v[60:63], v255 offset:16
	s_waitcnt vmcnt(22) lgkmcnt(6)
	v_pk_fma_f32 v[32:33], v[142:143], v[32:33], v[96:97]
	v_pk_fma_f32 v[34:35], v[144:145], v[34:35], v[98:99]
	v_pk_fma_f32 v[36:37], v[146:147], v[36:37], v[100:101]
	v_pk_fma_f32 v[38:39], v[234:235], v[38:39], v[102:103]
	global_store_dwordx4 v150, v[32:35], s[18:19]
	global_store_dwordx4 v150, v[36:39], s[18:19] offset:16
	s_add_u32 s18, s18, 0x8000
	s_addc_u32 s19, s19, 0
	s_waitcnt vmcnt(22) lgkmcnt(4)
	v_pk_fma_f32 v[40:41], v[142:143], v[40:41], v[104:105]
	v_pk_fma_f32 v[42:43], v[144:145], v[42:43], v[106:107]
	v_pk_fma_f32 v[44:45], v[146:147], v[44:45], v[108:109]
	v_pk_fma_f32 v[46:47], v[234:235], v[46:47], v[110:111]
	global_store_dwordx4 v150, v[40:43], s[18:19]
	global_store_dwordx4 v150, v[44:47], s[18:19] offset:16
	s_add_u32 s18, s18, 0x8000
	s_addc_u32 s19, s19, 0
	s_waitcnt vmcnt(22) lgkmcnt(2)
	v_pk_fma_f32 v[48:49], v[142:143], v[48:49], v[112:113]
	v_pk_fma_f32 v[50:51], v[144:145], v[50:51], v[114:115]
	v_pk_fma_f32 v[52:53], v[146:147], v[52:53], v[116:117]
	v_pk_fma_f32 v[54:55], v[234:235], v[54:55], v[118:119]
	global_store_dwordx4 v150, v[48:51], s[18:19]
	global_store_dwordx4 v150, v[52:55], s[18:19] offset:16
	s_add_u32 s18, s18, 0x8000
	s_addc_u32 s19, s19, 0
	s_waitcnt vmcnt(22) lgkmcnt(0)
	v_pk_fma_f32 v[56:57], v[142:143], v[56:57], v[120:121]
	v_pk_fma_f32 v[58:59], v[144:145], v[58:59], v[122:123]
	v_pk_fma_f32 v[60:61], v[146:147], v[60:61], v[124:125]
	v_pk_fma_f32 v[62:63], v[234:235], v[62:63], v[126:127]
	global_store_dwordx4 v150, v[56:59], s[18:19]
	global_store_dwordx4 v150, v[60:63], s[18:19] offset:16
	s_add_u32 s18, s18, 0x8000
	s_addc_u32 s19, s19, 0
	s_add_u32 s14, s10, 0x2020000
	s_addc_u32 s15, s11, 0
	global_load_dwordx4 v[96:99], v150, s[14:15] nt
	global_load_dwordx4 v[100:103], v150, s[14:15] offset:16 nt
	s_add_u32 s14, s14, 0x8000
	s_addc_u32 s15, s15, 0
	global_load_dwordx4 v[104:107], v150, s[14:15] nt
	global_load_dwordx4 v[108:111], v150, s[14:15] offset:16 nt
	s_add_u32 s14, s14, 0x8000
	s_addc_u32 s15, s15, 0
	global_load_dwordx4 v[112:115], v150, s[14:15] nt
	global_load_dwordx4 v[116:119], v150, s[14:15] offset:16 nt
	s_add_u32 s14, s14, 0x8000
	s_addc_u32 s15, s15, 0
	global_load_dwordx4 v[120:123], v150, s[14:15] nt
	global_load_dwordx4 v[124:127], v150, s[14:15] offset:16 nt
	s_add_u32 s18, s12, 0x2000000
	s_addc_u32 s19, s13, 0
	ds_write_b32 v248, v160 offset:0
	ds_write_b32 v248, v161 offset:256
	ds_write_b32 v248, v162 offset:512
	ds_write_b32 v248, v163 offset:768
	ds_write_b32 v249, v164 offset:0
	ds_write_b32 v249, v165 offset:256
	ds_write_b32 v249, v166 offset:512
	ds_write_b32 v249, v167 offset:768
	ds_write_b32 v250, v168 offset:0
	ds_write_b32 v250, v169 offset:256
	ds_write_b32 v250, v170 offset:512
	ds_write_b32 v250, v171 offset:768
	ds_write_b32 v251, v172 offset:0
	ds_write_b32 v251, v173 offset:256
	ds_write_b32 v251, v174 offset:512
	ds_write_b32 v251, v175 offset:768
	ds_write_b32 v248, v176 offset:4096
	ds_write_b32 v248, v177 offset:4352
	ds_write_b32 v248, v178 offset:4608
	ds_write_b32 v248, v179 offset:4864
	ds_write_b32 v249, v180 offset:4096
	ds_write_b32 v249, v181 offset:4352
	ds_write_b32 v249, v182 offset:4608
	ds_write_b32 v249, v183 offset:4864
	ds_write_b32 v250, v184 offset:4096
	ds_write_b32 v250, v185 offset:4352
	ds_write_b32 v250, v186 offset:4608
	ds_write_b32 v250, v187 offset:4864
	ds_write_b32 v251, v188 offset:4096
	ds_write_b32 v251, v189 offset:4352
	ds_write_b32 v251, v190 offset:4608
	ds_write_b32 v251, v191 offset:4864
	s_waitcnt lgkmcnt(0)
	ds_read_b128 v[160:163], v252
	ds_read_b128 v[164:167], v252 offset:16
	ds_read_b128 v[168:171], v253
	ds_read_b128 v[172:175], v253 offset:16
	ds_read_b128 v[176:179], v254
	ds_read_b128 v[180:183], v254 offset:16
	ds_read_b128 v[184:187], v255
	ds_read_b128 v[188:191], v255 offset:16
	s_waitcnt vmcnt(22) lgkmcnt(6)
	v_pk_fma_f32 v[160:161], v[236:237], v[160:161], v[64:65]
	v_pk_fma_f32 v[162:163], v[238:239], v[162:163], v[66:67]
	v_pk_fma_f32 v[164:165], v[240:241], v[164:165], v[68:69]
	v_pk_fma_f32 v[166:167], v[242:243], v[166:167], v[70:71]
	global_store_dwordx4 v150, v[160:163], s[18:19]
	global_store_dwordx4 v150, v[164:167], s[18:19] offset:16
	s_add_u32 s18, s18, 0x8000
	s_addc_u32 s19, s19, 0
	s_waitcnt vmcnt(22) lgkmcnt(4)
	v_pk_fma_f32 v[168:169], v[236:237], v[168:169], v[72:73]
	v_pk_fma_f32 v[170:171], v[238:239], v[170:171], v[74:75]
	v_pk_fma_f32 v[172:173], v[240:241], v[172:173], v[76:77]
	v_pk_fma_f32 v[174:175], v[242:243], v[174:175], v[78:79]
	global_store_dwordx4 v150, v[168:171], s[18:19]
	global_store_dwordx4 v150, v[172:175], s[18:19] offset:16
	s_add_u32 s18, s18, 0x8000
	s_addc_u32 s19, s19, 0
	s_waitcnt vmcnt(22) lgkmcnt(2)
	v_pk_fma_f32 v[176:177], v[236:237], v[176:177], v[80:81]
	v_pk_fma_f32 v[178:179], v[238:239], v[178:179], v[82:83]
	v_pk_fma_f32 v[180:181], v[240:241], v[180:181], v[84:85]
	v_pk_fma_f32 v[182:183], v[242:243], v[182:183], v[86:87]
	global_store_dwordx4 v150, v[176:179], s[18:19]
	global_store_dwordx4 v150, v[180:183], s[18:19] offset:16
	s_add_u32 s18, s18, 0x8000
	s_addc_u32 s19, s19, 0
	s_waitcnt vmcnt(22) lgkmcnt(0)
	v_pk_fma_f32 v[184:185], v[236:237], v[184:185], v[88:89]
	v_pk_fma_f32 v[186:187], v[238:239], v[186:187], v[90:91]
	v_pk_fma_f32 v[188:189], v[240:241], v[188:189], v[92:93]
	v_pk_fma_f32 v[190:191], v[242:243], v[190:191], v[94:95]
	global_store_dwordx4 v150, v[184:187], s[18:19]
	global_store_dwordx4 v150, v[188:191], s[18:19] offset:16
	s_add_u32 s18, s18, 0x8000
	s_addc_u32 s19, s19, 0
	ds_write_b32 v248, v192 offset:0
	ds_write_b32 v248, v193 offset:256
	ds_write_b32 v248, v194 offset:512
	ds_write_b32 v248, v195 offset:768
	ds_write_b32 v249, v196 offset:0
	ds_write_b32 v249, v197 offset:256
	ds_write_b32 v249, v198 offset:512
	ds_write_b32 v249, v199 offset:768
	ds_write_b32 v250, v200 offset:0
	ds_write_b32 v250, v201 offset:256
	ds_write_b32 v250, v202 offset:512
	ds_write_b32 v250, v203 offset:768
	ds_write_b32 v251, v204 offset:0
	ds_write_b32 v251, v205 offset:256
	ds_write_b32 v251, v206 offset:512
	ds_write_b32 v251, v207 offset:768
	ds_write_b32 v248, v208 offset:4096
	ds_write_b32 v248, v209 offset:4352
	ds_write_b32 v248, v210 offset:4608
	ds_write_b32 v248, v211 offset:4864
	ds_write_b32 v249, v212 offset:4096
	ds_write_b32 v249, v213 offset:4352
	ds_write_b32 v249, v214 offset:4608
	ds_write_b32 v249, v215 offset:4864
	ds_write_b32 v250, v216 offset:4096
	ds_write_b32 v250, v217 offset:4352
	ds_write_b32 v250, v218 offset:4608
	ds_write_b32 v250, v219 offset:4864
	ds_write_b32 v251, v230 offset:4096
	ds_write_b32 v251, v231 offset:4352
	ds_write_b32 v251, v232 offset:4608
	ds_write_b32 v251, v233 offset:4864
	s_waitcnt lgkmcnt(0)
	ds_read_b128 v[192:195], v252
	ds_read_b128 v[196:199], v252 offset:16
	ds_read_b128 v[200:203], v253
	ds_read_b128 v[204:207], v253 offset:16
	ds_read_b128 v[208:211], v254
	ds_read_b128 v[212:215], v254 offset:16
	ds_read_b128 v[216:219], v255
	ds_read_b128 v[230:233], v255 offset:16
	s_waitcnt vmcnt(14) lgkmcnt(6)
	v_pk_fma_f32 v[192:193], v[236:237], v[192:193], v[96:97]
	v_pk_fma_f32 v[194:195], v[238:239], v[194:195], v[98:99]
	v_pk_fma_f32 v[196:197], v[240:241], v[196:197], v[100:101]
	v_pk_fma_f32 v[198:199], v[242:243], v[198:199], v[102:103]
	global_store_dwordx4 v150, v[192:195], s[18:19]
	global_store_dwordx4 v150, v[196:199], s[18:19] offset:16
	s_add_u32 s18, s18, 0x8000
	s_addc_u32 s19, s19, 0
	s_waitcnt vmcnt(14) lgkmcnt(4)
	v_pk_fma_f32 v[200:201], v[236:237], v[200:201], v[104:105]
	v_pk_fma_f32 v[202:203], v[238:239], v[202:203], v[106:107]
	v_pk_fma_f32 v[204:205], v[240:241], v[204:205], v[108:109]
	v_pk_fma_f32 v[206:207], v[242:243], v[206:207], v[110:111]
	global_store_dwordx4 v150, v[200:203], s[18:19]
	global_store_dwordx4 v150, v[204:207], s[18:19] offset:16
	s_add_u32 s18, s18, 0x8000
	s_addc_u32 s19, s19, 0
	s_waitcnt vmcnt(14) lgkmcnt(2)
	v_pk_fma_f32 v[208:209], v[236:237], v[208:209], v[112:113]
	v_pk_fma_f32 v[210:211], v[238:239], v[210:211], v[114:115]
	v_pk_fma_f32 v[212:213], v[240:241], v[212:213], v[116:117]
	v_pk_fma_f32 v[214:215], v[242:243], v[214:215], v[118:119]
	global_store_dwordx4 v150, v[208:211], s[18:19]
	global_store_dwordx4 v150, v[212:215], s[18:19] offset:16
	s_add_u32 s18, s18, 0x8000
	s_addc_u32 s19, s19, 0
	s_waitcnt vmcnt(14) lgkmcnt(0)
	v_pk_fma_f32 v[216:217], v[236:237], v[216:217], v[120:121]
	v_pk_fma_f32 v[218:219], v[238:239], v[218:219], v[122:123]
	v_pk_fma_f32 v[230:231], v[240:241], v[230:231], v[124:125]
	v_pk_fma_f32 v[232:233], v[242:243], v[232:233], v[126:127]
	global_store_dwordx4 v150, v[216:219], s[18:19]
	global_store_dwordx4 v150, v[230:233], s[18:19] offset:16
	s_add_u32 s18, s18, 0x8000
	s_addc_u32 s19, s19, 0
	s_add_i32 s52, s52, s3
	s_cmpk_lt_i32 s52, 0x200
	s_cbranch_scc1 .Lmy_op1_tile
.Lmy_op1_end:
.LBB0_689:
	s_endpgm
